# v17_all_nont
# speedup vs baseline: 1.0260x; 1.0080x over previous
; template <int EPI, int TS, bool VT>
; DEVI void gemm_epilogue(const Params& p, char* smem, f32x4 (&acc)[2][2][4][2], int m0, int n0, float scale, const float* ssin,
;                         float* ssout, u16* xbout, int wid, int lane, int wr, int wc, int fr, int fq) {
;     ...
;       float* tw = T + (wr * 64 + fq * 4) * TS + wc * 32 + fr;
; #pragma unroll
;       for (int m = 0; m < 4; ++m)
; #pragma unroll
;         for (int j = 0; j < 4; ++j)
; #pragma unroll
;           for (int v = 0; v < 4; ++v) tw[(m * 16 + j) * TS + (v >> 1) * 128 + (v & 1) * 16] = acc[ai][v >> 1][m][v & 1][j];
;     }
;     __syncthreads();
;     const int r0 = wid * 16;
;     const int g0 = m0 + ai * 128 + r0;
;     if constexpr (!VT) {
;       float rsv = 1.f;
;       if constexpr (EPI == E_PLEGATE || EPI == E_F32 || EPI == E_SWIGLU || EPI == E_GLAIN)
;         rsv = rsqrtf(ssin[g0 + (lane & 15)] * (1.f / 1024.f) + EPS);
;       if constexpr (EPI == E_QROPE) rsv = rsqrtf(ssin[g0 + (lane & 15)] * (1.f / 384.f) + EPS);
;       if constexpr (EPI == E_KV) rsv = rsqrtf(ssin[g0 + (lane & 15)] * (1.f / 256.f) + EPS);
;       for (int i0 = 0; i0 < 16; i0 += 8) {
;         float4 xo[8];
;         uint2 pv[8];
;         if constexpr (EPI == E_RESID || EPI == E_PLEGATE) {
; #pragma unroll
;           for (int u = 0; u < 8; ++u) {
;             const size_t ro = (size_t)(g0 + i0 + u) * 1024 + n0 + 4 * lane;
;             const int gr = g0 + i0 + u;
;             const float* xs = p.x + ro;
;             if (scale < 0.f)
;               xs = (gr < MP ? p.x_prompt + ro : p.x_sample + (ro - (size_t)MP * 1024));
;             { const f32x4 t_ = __builtin_nontemporal_load((const f32x4*)xs); xo[u] = make_float4(t_[0], t_[1], t_[2], t_[3]); }
;             if constexpr (EPI == E_PLEGATE) {
;               const unsigned long long t2_ = __builtin_nontemporal_load((const unsigned long long*)((const u16*)(wsb + OFF_PP) + ro));
;               pv[u] = make_uint2((unsigned)t2_, (unsigned)(t2_ >> 32));
;             }
;           }
;         }
; #pragma unroll
;         for (int u = 0; u < 8; ++u) {
;           const int i = i0 + u;
;           const int grow = g0 + i;
;           const float* Tr = T + (r0 + i) * TS;
;           const float rs = __int_as_float(__builtin_amdgcn_readlane(__float_as_int(rsv), i));
;     ...
;           } else if constexpr (EPI == E_SWIGLU) {
.LBB0_135:
	v_readlane_b32 s14, v254, 22
	v_readlane_b32 s15, v254, 23
	s_lshl_b32 s10, s7, 4
	s_add_i32 s10, s10, s6
	v_or_b32_e32 v176, s10, v132
	v_lshlrev_b32_e32 v176, 2, v176
	s_nop 2
	global_load_dword v178, v176, s[14:15]
	global_load_dword v179, v176, s[14:15] offset:512
	v_lshrrev_b32_e32 v128, 2, v134
	v_and_or_b32 v128, v128, 12, s44
	s_movk_i32 s10, 0x410
	v_readlane_b32 s8, v254, 13
	v_mul_lo_u32 v128, v128, s10
	s_lshl_b32 s10, s35, 7
	v_lshlrev_b32_e32 v129, 2, v132
	v_readlane_b32 s9, v254, 14
	v_add3_u32 v128, s10, v128, v129
	ds_write2_b32 v128, v92, v100 offset1:16
	ds_write2_b32 v128, v120, v124 offset0:128 offset1:144
	v_add_u32_e32 v92, 0x400, v128
	ds_write2_b32 v92, v93, v101 offset0:4 offset1:20
	ds_write2_b32 v92, v121, v125 offset0:132 offset1:148
	v_add_u32_e32 v93, 0x800, v128
	ds_write2_b32 v93, v94, v102 offset0:8 offset1:24
	ds_write2_b32 v93, v122, v126 offset0:136 offset1:152
	v_add_u32_e32 v94, 0xc00, v128
	ds_write2_b32 v94, v95, v103 offset0:12 offset1:28
	ds_write2_b32 v94, v123, v127 offset0:140 offset1:156
	v_add_u32_e32 v95, 0x4000, v128
	ds_write2_b32 v95, v80, v84 offset0:64 offset1:80
	ds_write2_b32 v95, v112, v116 offset0:192 offset1:208
	v_add_u32_e32 v80, 0x4400, v128
	ds_write2_b32 v80, v81, v85 offset0:68 offset1:84
	ds_write2_b32 v80, v113, v117 offset0:196 offset1:212
	v_add_u32_e32 v81, 0x4800, v128
	ds_write2_b32 v81, v82, v86 offset0:72 offset1:88
	ds_write2_b32 v81, v114, v118 offset0:200 offset1:216
	v_add_u32_e32 v82, 0x4c00, v128
	ds_write2_b32 v82, v83, v87 offset0:76 offset1:92
	ds_write2_b32 v82, v115, v119 offset0:204 offset1:220
	v_add_u32_e32 v83, 0x8000, v128
	ds_write2_b32 v83, v72, v76 offset0:128 offset1:144
	v_add_u32_e32 v72, 0x8400, v128
	s_lshl_b32 s10, s7, 4
	ds_write2_b32 v72, v104, v108 offset1:16
	ds_write2_b32 v72, v73, v77 offset0:132 offset1:148
	v_add_u32_e32 v73, 0x8800, v128
	s_add_i32 s6, s10, s6
	ds_write2_b32 v73, v105, v109 offset0:4 offset1:20
	ds_write2_b32 v73, v74, v78 offset0:136 offset1:152
	v_add_u32_e32 v74, 0x8c00, v128
	v_add_u32_e32 v76, 0xc000, v128
	ds_write2_b32 v74, v106, v110 offset0:8 offset1:24
	ds_write2_b32 v74, v75, v79 offset0:140 offset1:156
	v_add_u32_e32 v75, 0x9000, v128
	ds_write2_b32 v76, v64, v68 offset0:192 offset1:208
	v_add_u32_e32 v77, 0xc400, v128
	v_add_u32_e32 v78, 0xc800, v128
	v_or_b32_e32 v64, s6, v132
	v_readlane_b32 s14, v254, 22
	ds_write2_b32 v75, v107, v111 offset0:12 offset1:28
	ds_write2_b32 v77, v88, v96 offset0:64 offset1:80
	ds_write2_b32 v77, v65, v69 offset0:196 offset1:212
	ds_write2_b32 v78, v89, v97 offset0:68 offset1:84
	ds_write2_b32 v78, v66, v70 offset0:200 offset1:216
	v_add_u32_e32 v70, 0xcc00, v128
	v_ashrrev_i32_e32 v65, 31, v64
	v_readlane_b32 s15, v254, 23
	ds_write2_b32 v70, v90, v98 offset0:72 offset1:88
	ds_write2_b32 v70, v67, v71 offset0:204 offset1:220
	v_add_u32_e32 v71, 0xd000, v128
	v_lshl_add_u64 v[64:65], v[64:65], 2, s[14:15]
	ds_write2_b32 v71, v91, v99 offset0:76 offset1:92
	s_waitcnt vmcnt(0) lgkmcnt(0)
	s_barrier
	v_readlane_b32 s8, v254, 13
	v_readlane_b32 s9, v254, 14
	s_add_u32 s12, s8, 0x1e95ee00
	s_addc_u32 s13, s9, 0
	s_lshl_b32 s10, s31, 8
	s_add_u32 s12, s12, s10
	s_addc_u32 s13, s13, 0
	s_mov_b32 s31, s23
	v_lshlrev_b32_e32 v204, 3, v134
	v_and_b32_e32 v204, 56, v204
	s_movk_i32 s10, 0x380
	v_and_or_b32 v250, v133, s10, v204
	s_mul_i32 s10, s7, 0x4100
	v_add_u32_e32 v250, s10, v250
	v_and_b32_e32 v204, 63, v134
	v_lshlrev_b32_e32 v204, 2, v204
	s_mul_i32 s10, s6, 0x1600
	v_add_u32_e32 v251, s10, v204
	v_add_u32_e32 v253, 0x1600, v251
	v_mov_b32_e32 v246, 0xbfb8aa3b
	v_mov_b32_e32 v247, 0xbfb8aa3b
	v_mov_b32_e32 v248, 1.0
	v_mov_b32_e32 v249, 1.0
	v_fmamk_f32 v204, v178, 0x3a800000, v150
	v_mul_f32_e32 v205, 0x4b800000, v204
	v_cmp_gt_f32_e32 vcc, s29, v204
	s_nop 1
	v_cndmask_b32_e32 v204, v204, v205, vcc
	v_rsq_f32_e32 v204, v204
	s_nop 0
	v_mul_f32_e32 v205, 0x45800000, v204
	v_cndmask_b32_e32 v252, v204, v205, vcc
	ds_read_b64 v[180:181], v250
	ds_read_b64 v[182:183], v250 offset:64
	ds_read_b64 v[184:185], v250 offset:1040
	ds_read_b64 v[186:187], v250 offset:1104
	ds_read_b64 v[188:189], v250 offset:2080
	ds_read_b64 v[190:191], v250 offset:2144
	ds_read_b64 v[192:193], v250 offset:3120
	ds_read_b64 v[194:195], v250 offset:3184
	v_readlane_b32 s8, v252, 0
	v_readlane_b32 s10, v252, 1
	ds_read_b64 v[196:197], v250 offset:4160
	ds_read_b64 v[198:199], v250 offset:4224
	ds_read_b64 v[200:201], v250 offset:5200
	ds_read_b64 v[202:203], v250 offset:5264
	s_waitcnt lgkmcnt(11)
	v_pk_mul_f32 v[180:181], s[8:9], v[180:181] op_sel_hi:[0,1]
	s_waitcnt lgkmcnt(9)
	v_pk_mul_f32 v[184:185], s[10:11], v[184:185] op_sel_hi:[0,1]
	v_pk_mul_f32 v[182:183], s[8:9], v[182:183] op_sel_hi:[0,1]
	s_waitcnt lgkmcnt(8)
	v_pk_mul_f32 v[186:187], s[10:11], v[186:187] op_sel_hi:[0,1]
	v_pk_mul_f32 v[204:205], v[180:181], v[246:247]
	v_pk_mul_f32 v[206:207], v[184:185], v[246:247]
	v_exp_f32_e32 v204, v204
	v_exp_f32_e32 v205, v205
	v_exp_f32_e32 v206, v206
	v_exp_f32_e32 v207, v207
	v_pk_add_f32 v[204:205], v[204:205], v[248:249]
	v_pk_add_f32 v[206:207], v[206:207], v[248:249]
	v_rcp_f32_e32 v204, v204
	v_rcp_f32_e32 v205, v205
	v_rcp_f32_e32 v206, v206
	v_rcp_f32_e32 v207, v207
	v_pk_mul_f32 v[180:181], v[180:181], v[204:205]
	v_pk_mul_f32 v[184:185], v[184:185], v[206:207]
	v_pk_mul_f32 v[180:181], v[182:183], v[180:181]
	v_pk_mul_f32 v[184:185], v[186:187], v[184:185]
	v_cvt_pk_bf16_f32 v212, v180, v181
	v_cvt_pk_bf16_f32 v213, v184, v185
	global_store_dword v251, v212, s[12:13]
	global_store_dword v253, v213, s[12:13]
	v_add_u32_e32 v251, 0x2c00, v251
	v_add_u32_e32 v253, 0x2c00, v253
	v_readlane_b32 s8, v252, 2
	v_readlane_b32 s10, v252, 3
	ds_read_b64 v[180:181], v250 offset:6240
	ds_read_b64 v[182:183], v250 offset:6304
	ds_read_b64 v[184:185], v250 offset:7280
	ds_read_b64 v[186:187], v250 offset:7344
	s_waitcnt lgkmcnt(11)
; DEVI float fsig(float x) { return __builtin_amdgcn_rcpf(1.f + __expf(-x)); }
; template <int EPI, int TS, bool VT>
; DEVI void gemm_epilogue(const Params& p, char* smem, f32x4 (&acc)[2][2][4][2], int m0, int n0, float scale, const float* ssin,
;                         float* ssout, u16* xbout, int wid, int lane, int wr, int wc, int fr, int fq) {
;     ...
;         for (int u = 0; u < 8; ++u) {
;           const int i = i0 + u;
;           const int grow = g0 + i;
;           const float* Tr = T + (r0 + i) * TS;
;           const float rs = __int_as_float(__builtin_amdgcn_readlane(__float_as_int(rsv), i));
;     ...
;           } else if constexpr (EPI == E_SWIGLU) {
;             const int gc = (lane >> 3) * 32 + 2 * (lane & 7);
;             const float2 g2 = *(const float2*)(Tr + gc), u2 = *(const float2*)(Tr + gc + 16);
;             const float ga = g2.x * rs, gb = g2.y * rs;
;             const float ha = ga * fsig(ga) * (u2.x * rs), hb = gb * fsig(gb) * (u2.y * rs);
;             __builtin_nontemporal_store(pack2(ha, hb), (unsigned*)((u16*)(wsb + OFF_HID) + (size_t)grow * 2816 + (n0 >> 1) + 2 * lane));
	v_pk_mul_f32 v[188:189], s[8:9], v[188:189] op_sel_hi:[0,1]
	s_waitcnt lgkmcnt(9)
	v_pk_mul_f32 v[192:193], s[10:11], v[192:193] op_sel_hi:[0,1]
	v_pk_mul_f32 v[190:191], s[8:9], v[190:191] op_sel_hi:[0,1]
	s_waitcnt lgkmcnt(8)
	v_pk_mul_f32 v[194:195], s[10:11], v[194:195] op_sel_hi:[0,1]
	v_pk_mul_f32 v[204:205], v[188:189], v[246:247]
	v_pk_mul_f32 v[206:207], v[192:193], v[246:247]
	v_exp_f32_e32 v204, v204
	v_exp_f32_e32 v205, v205
	v_exp_f32_e32 v206, v206
	v_exp_f32_e32 v207, v207
	v_pk_add_f32 v[204:205], v[204:205], v[248:249]
	v_pk_add_f32 v[206:207], v[206:207], v[248:249]
	v_rcp_f32_e32 v204, v204
	v_rcp_f32_e32 v205, v205
	v_rcp_f32_e32 v206, v206
	v_rcp_f32_e32 v207, v207
	v_pk_mul_f32 v[188:189], v[188:189], v[204:205]
	v_pk_mul_f32 v[192:193], v[192:193], v[206:207]
	v_pk_mul_f32 v[188:189], v[190:191], v[188:189]
	v_pk_mul_f32 v[192:193], v[194:195], v[192:193]
	v_cvt_pk_bf16_f32 v214, v188, v189
	v_cvt_pk_bf16_f32 v215, v192, v193
	global_store_dword v251, v214, s[12:13]
	global_store_dword v253, v215, s[12:13]
	v_add_u32_e32 v251, 0x2c00, v251
	v_add_u32_e32 v253, 0x2c00, v253
	v_readlane_b32 s8, v252, 4
	v_readlane_b32 s10, v252, 5
	ds_read_b64 v[188:189], v250 offset:8320
	ds_read_b64 v[190:191], v250 offset:8384
	ds_read_b64 v[192:193], v250 offset:9360
	ds_read_b64 v[194:195], v250 offset:9424
	s_waitcnt lgkmcnt(11)
	v_pk_mul_f32 v[196:197], s[8:9], v[196:197] op_sel_hi:[0,1]
	s_waitcnt lgkmcnt(9)
	v_pk_mul_f32 v[200:201], s[10:11], v[200:201] op_sel_hi:[0,1]
	v_pk_mul_f32 v[198:199], s[8:9], v[198:199] op_sel_hi:[0,1]
	s_waitcnt lgkmcnt(8)
	v_pk_mul_f32 v[202:203], s[10:11], v[202:203] op_sel_hi:[0,1]
	v_pk_mul_f32 v[204:205], v[196:197], v[246:247]
	v_pk_mul_f32 v[206:207], v[200:201], v[246:247]
	v_exp_f32_e32 v204, v204
	v_exp_f32_e32 v205, v205
	v_exp_f32_e32 v206, v206
	v_exp_f32_e32 v207, v207
	v_pk_add_f32 v[204:205], v[204:205], v[248:249]
	v_pk_add_f32 v[206:207], v[206:207], v[248:249]
	v_rcp_f32_e32 v204, v204
	v_rcp_f32_e32 v205, v205
	v_rcp_f32_e32 v206, v206
	v_rcp_f32_e32 v207, v207
	v_pk_mul_f32 v[196:197], v[196:197], v[204:205]
	v_pk_mul_f32 v[200:201], v[200:201], v[206:207]
	v_pk_mul_f32 v[196:197], v[198:199], v[196:197]
	v_pk_mul_f32 v[200:201], v[202:203], v[200:201]
	v_cvt_pk_bf16_f32 v212, v196, v197
	v_cvt_pk_bf16_f32 v213, v200, v201
	global_store_dword v251, v212, s[12:13]
	global_store_dword v253, v213, s[12:13]
	v_add_u32_e32 v251, 0x2c00, v251
	v_add_u32_e32 v253, 0x2c00, v253
	v_readlane_b32 s8, v252, 6
	v_readlane_b32 s10, v252, 7
	ds_read_b64 v[196:197], v250 offset:10400
	ds_read_b64 v[198:199], v250 offset:10464
	ds_read_b64 v[200:201], v250 offset:11440
	ds_read_b64 v[202:203], v250 offset:11504
	s_waitcnt lgkmcnt(11)
	v_pk_mul_f32 v[180:181], s[8:9], v[180:181] op_sel_hi:[0,1]
	s_waitcnt lgkmcnt(9)
	v_pk_mul_f32 v[184:185], s[10:11], v[184:185] op_sel_hi:[0,1]
	v_pk_mul_f32 v[182:183], s[8:9], v[182:183] op_sel_hi:[0,1]
	s_waitcnt lgkmcnt(8)
	v_pk_mul_f32 v[186:187], s[10:11], v[186:187] op_sel_hi:[0,1]
	v_pk_mul_f32 v[204:205], v[180:181], v[246:247]
	v_pk_mul_f32 v[206:207], v[184:185], v[246:247]
	v_exp_f32_e32 v204, v204
	v_exp_f32_e32 v205, v205
	v_exp_f32_e32 v206, v206
	v_exp_f32_e32 v207, v207
	v_pk_add_f32 v[204:205], v[204:205], v[248:249]
	v_pk_add_f32 v[206:207], v[206:207], v[248:249]
	v_rcp_f32_e32 v204, v204
	v_rcp_f32_e32 v205, v205
	v_rcp_f32_e32 v206, v206
	v_rcp_f32_e32 v207, v207
	v_pk_mul_f32 v[180:181], v[180:181], v[204:205]
	v_pk_mul_f32 v[184:185], v[184:185], v[206:207]
	v_pk_mul_f32 v[180:181], v[182:183], v[180:181]
	v_pk_mul_f32 v[184:185], v[186:187], v[184:185]
	v_cvt_pk_bf16_f32 v214, v180, v181
	v_cvt_pk_bf16_f32 v215, v184, v185
	global_store_dword v251, v214, s[12:13]
	global_store_dword v253, v215, s[12:13]
	v_add_u32_e32 v251, 0x2c00, v251
	v_add_u32_e32 v253, 0x2c00, v253
	v_readlane_b32 s8, v252, 8
	v_readlane_b32 s10, v252, 9
	ds_read_b64 v[180:181], v250 offset:12480
	ds_read_b64 v[182:183], v250 offset:12544
	ds_read_b64 v[184:185], v250 offset:13520
	ds_read_b64 v[186:187], v250 offset:13584
	s_waitcnt lgkmcnt(11)
	v_pk_mul_f32 v[188:189], s[8:9], v[188:189] op_sel_hi:[0,1]
	s_waitcnt lgkmcnt(9)
	v_pk_mul_f32 v[192:193], s[10:11], v[192:193] op_sel_hi:[0,1]
	v_pk_mul_f32 v[190:191], s[8:9], v[190:191] op_sel_hi:[0,1]
	s_waitcnt lgkmcnt(8)
	v_pk_mul_f32 v[194:195], s[10:11], v[194:195] op_sel_hi:[0,1]
	v_pk_mul_f32 v[204:205], v[188:189], v[246:247]
	v_pk_mul_f32 v[206:207], v[192:193], v[246:247]
	v_exp_f32_e32 v204, v204
	v_exp_f32_e32 v205, v205
	v_exp_f32_e32 v206, v206
	v_exp_f32_e32 v207, v207
	v_pk_add_f32 v[204:205], v[204:205], v[248:249]
	v_pk_add_f32 v[206:207], v[206:207], v[248:249]
	v_rcp_f32_e32 v204, v204
	v_rcp_f32_e32 v205, v205
	v_rcp_f32_e32 v206, v206
	v_rcp_f32_e32 v207, v207
	v_pk_mul_f32 v[188:189], v[188:189], v[204:205]
	v_pk_mul_f32 v[192:193], v[192:193], v[206:207]
	v_pk_mul_f32 v[188:189], v[190:191], v[188:189]
	v_pk_mul_f32 v[192:193], v[194:195], v[192:193]
	v_cvt_pk_bf16_f32 v212, v188, v189
	v_cvt_pk_bf16_f32 v213, v192, v193
	global_store_dword v251, v212, s[12:13]
	global_store_dword v253, v213, s[12:13]
	v_add_u32_e32 v251, 0x2c00, v251
	v_add_u32_e32 v253, 0x2c00, v253
	v_readlane_b32 s8, v252, 10
	v_readlane_b32 s10, v252, 11
	ds_read_b64 v[188:189], v250 offset:14560
	ds_read_b64 v[190:191], v250 offset:14624
	ds_read_b64 v[192:193], v250 offset:15600
	ds_read_b64 v[194:195], v250 offset:15664
	s_waitcnt lgkmcnt(11)
	v_pk_mul_f32 v[196:197], s[8:9], v[196:197] op_sel_hi:[0,1]
	s_waitcnt lgkmcnt(9)
	v_pk_mul_f32 v[200:201], s[10:11], v[200:201] op_sel_hi:[0,1]
	v_pk_mul_f32 v[198:199], s[8:9], v[198:199] op_sel_hi:[0,1]
	s_waitcnt lgkmcnt(8)
; DEVI float fsig(float x) { return __builtin_amdgcn_rcpf(1.f + __expf(-x)); }
; template <int EPI, int TS, bool VT>
; DEVI void gemm_epilogue(const Params& p, char* smem, f32x4 (&acc)[2][2][4][2], int m0, int n0, float scale, const float* ssin,
;                         float* ssout, u16* xbout, int wid, int lane, int wr, int wc, int fr, int fq) {
;     ...
;   for (int ai = 0; ai < 2; ++ai) {
;     {
;       float* tw = T + (wr * 64 + fq * 4) * TS + wc * 32 + fr;
; #pragma unroll
;       for (int m = 0; m < 4; ++m)
; #pragma unroll
;         for (int j = 0; j < 4; ++j)
; #pragma unroll
;           for (int v = 0; v < 4; ++v) tw[(m * 16 + j) * TS + (v >> 1) * 128 + (v & 1) * 16] = acc[ai][v >> 1][m][v & 1][j];
;     }
;     __syncthreads();
;     ...
;           } else if constexpr (EPI == E_SWIGLU) {
;             const int gc = (lane >> 3) * 32 + 2 * (lane & 7);
;             const float2 g2 = *(const float2*)(Tr + gc), u2 = *(const float2*)(Tr + gc + 16);
;             const float ga = g2.x * rs, gb = g2.y * rs;
;             const float ha = ga * fsig(ga) * (u2.x * rs), hb = gb * fsig(gb) * (u2.y * rs);
;             __builtin_nontemporal_store(pack2(ha, hb), (unsigned*)((u16*)(wsb + OFF_HID) + (size_t)grow * 2816 + (n0 >> 1) + 2 * lane));
	v_pk_mul_f32 v[202:203], s[10:11], v[202:203] op_sel_hi:[0,1]
	v_pk_mul_f32 v[204:205], v[196:197], v[246:247]
	v_pk_mul_f32 v[206:207], v[200:201], v[246:247]
	v_exp_f32_e32 v204, v204
	v_exp_f32_e32 v205, v205
	v_exp_f32_e32 v206, v206
	v_exp_f32_e32 v207, v207
	v_pk_add_f32 v[204:205], v[204:205], v[248:249]
	v_pk_add_f32 v[206:207], v[206:207], v[248:249]
	v_rcp_f32_e32 v204, v204
	v_rcp_f32_e32 v205, v205
	v_rcp_f32_e32 v206, v206
	v_rcp_f32_e32 v207, v207
	v_pk_mul_f32 v[196:197], v[196:197], v[204:205]
	v_pk_mul_f32 v[200:201], v[200:201], v[206:207]
	v_pk_mul_f32 v[196:197], v[198:199], v[196:197]
	v_pk_mul_f32 v[200:201], v[202:203], v[200:201]
	v_cvt_pk_bf16_f32 v214, v196, v197
	v_cvt_pk_bf16_f32 v215, v200, v201
	global_store_dword v251, v214, s[12:13]
	global_store_dword v253, v215, s[12:13]
	v_add_u32_e32 v251, 0x2c00, v251
	v_add_u32_e32 v253, 0x2c00, v253
	v_readlane_b32 s8, v252, 12
	v_readlane_b32 s10, v252, 13
	s_waitcnt lgkmcnt(7)
	v_pk_mul_f32 v[180:181], s[8:9], v[180:181] op_sel_hi:[0,1]
	s_waitcnt lgkmcnt(5)
	v_pk_mul_f32 v[184:185], s[10:11], v[184:185] op_sel_hi:[0,1]
	v_pk_mul_f32 v[182:183], s[8:9], v[182:183] op_sel_hi:[0,1]
	s_waitcnt lgkmcnt(4)
	v_pk_mul_f32 v[186:187], s[10:11], v[186:187] op_sel_hi:[0,1]
	v_pk_mul_f32 v[204:205], v[180:181], v[246:247]
	v_pk_mul_f32 v[206:207], v[184:185], v[246:247]
	v_exp_f32_e32 v204, v204
	v_exp_f32_e32 v205, v205
	v_exp_f32_e32 v206, v206
	v_exp_f32_e32 v207, v207
	v_pk_add_f32 v[204:205], v[204:205], v[248:249]
	v_pk_add_f32 v[206:207], v[206:207], v[248:249]
	v_rcp_f32_e32 v204, v204
	v_rcp_f32_e32 v205, v205
	v_rcp_f32_e32 v206, v206
	v_rcp_f32_e32 v207, v207
	v_pk_mul_f32 v[180:181], v[180:181], v[204:205]
	v_pk_mul_f32 v[184:185], v[184:185], v[206:207]
	v_pk_mul_f32 v[180:181], v[182:183], v[180:181]
	v_pk_mul_f32 v[184:185], v[186:187], v[184:185]
	v_cvt_pk_bf16_f32 v212, v180, v181
	v_cvt_pk_bf16_f32 v213, v184, v185
	global_store_dword v251, v212, s[12:13]
	global_store_dword v253, v213, s[12:13]
	v_add_u32_e32 v251, 0x2c00, v251
	v_add_u32_e32 v253, 0x2c00, v253
	v_readlane_b32 s8, v252, 14
	v_readlane_b32 s10, v252, 15
	s_waitcnt lgkmcnt(3)
	v_pk_mul_f32 v[188:189], s[8:9], v[188:189] op_sel_hi:[0,1]
	s_waitcnt lgkmcnt(1)
	v_pk_mul_f32 v[192:193], s[10:11], v[192:193] op_sel_hi:[0,1]
	v_pk_mul_f32 v[190:191], s[8:9], v[190:191] op_sel_hi:[0,1]
	s_waitcnt lgkmcnt(0)
	v_pk_mul_f32 v[194:195], s[10:11], v[194:195] op_sel_hi:[0,1]
	v_pk_mul_f32 v[204:205], v[188:189], v[246:247]
	v_pk_mul_f32 v[206:207], v[192:193], v[246:247]
	v_exp_f32_e32 v204, v204
	v_exp_f32_e32 v205, v205
	v_exp_f32_e32 v206, v206
	v_exp_f32_e32 v207, v207
	v_pk_add_f32 v[204:205], v[204:205], v[248:249]
	v_pk_add_f32 v[206:207], v[206:207], v[248:249]
	v_rcp_f32_e32 v204, v204
	v_rcp_f32_e32 v205, v205
	v_rcp_f32_e32 v206, v206
	v_rcp_f32_e32 v207, v207
	v_pk_mul_f32 v[188:189], v[188:189], v[204:205]
	v_pk_mul_f32 v[192:193], v[192:193], v[206:207]
	v_pk_mul_f32 v[188:189], v[190:191], v[188:189]
	v_pk_mul_f32 v[192:193], v[194:195], v[192:193]
	v_cvt_pk_bf16_f32 v214, v188, v189
	v_cvt_pk_bf16_f32 v215, v192, v193
	global_store_dword v251, v214, s[12:13]
	global_store_dword v253, v215, s[12:13]
	v_add_u32_e32 v251, 0x2c00, v251
	v_add_u32_e32 v253, 0x2c00, v253
	s_waitcnt lgkmcnt(0)
	s_barrier
	ds_write2_b32 v128, v24, v28 offset1:16
	ds_write2_b32 v128, v56, v60 offset0:128 offset1:144
	ds_write2_b32 v92, v25, v29 offset0:4 offset1:20
	ds_write2_b32 v92, v57, v61 offset0:132 offset1:148
	ds_write2_b32 v93, v26, v30 offset0:8 offset1:24
	ds_write2_b32 v93, v58, v62 offset0:136 offset1:152
	ds_write2_b32 v94, v27, v31 offset0:12 offset1:28
	ds_write2_b32 v94, v59, v63 offset0:140 offset1:156
	ds_write2_b32 v95, v16, v20 offset0:64 offset1:80
	ds_write2_b32 v95, v48, v52 offset0:192 offset1:208
	ds_write2_b32 v80, v17, v21 offset0:68 offset1:84
	ds_write2_b32 v80, v49, v53 offset0:196 offset1:212
	ds_write2_b32 v81, v18, v22 offset0:72 offset1:88
	ds_write2_b32 v81, v50, v54 offset0:200 offset1:216
	ds_write2_b32 v82, v19, v23 offset0:76 offset1:92
	ds_write2_b32 v82, v51, v55 offset0:204 offset1:220
	ds_write2_b32 v83, v8, v12 offset0:128 offset1:144
	ds_write2_b32 v72, v40, v44 offset1:16
	ds_write2_b32 v72, v9, v13 offset0:132 offset1:148
	ds_write2_b32 v73, v41, v45 offset0:4 offset1:20
	ds_write2_b32 v73, v10, v14 offset0:136 offset1:152
	ds_write2_b32 v74, v42, v46 offset0:8 offset1:24
	ds_write2_b32 v74, v11, v15 offset0:140 offset1:156
	ds_write2_b32 v75, v43, v47 offset0:12 offset1:28
	ds_write2_b32 v76, v0, v4 offset0:192 offset1:208
	ds_write2_b32 v77, v32, v36 offset0:64 offset1:80
	ds_write2_b32 v77, v1, v5 offset0:196 offset1:212
	ds_write2_b32 v78, v33, v37 offset0:68 offset1:84
	ds_write2_b32 v78, v2, v6 offset0:200 offset1:216
	ds_write2_b32 v70, v34, v38 offset0:72 offset1:88
	ds_write2_b32 v70, v3, v7 offset0:204 offset1:220
	ds_write2_b32 v71, v35, v39 offset0:76 offset1:92
	s_waitcnt lgkmcnt(0)
	s_barrier
; DEVI float fsig(float x) { return __builtin_amdgcn_rcpf(1.f + __expf(-x)); }
; template <int EPI, int TS, bool VT>
; DEVI void gemm_epilogue(const Params& p, char* smem, f32x4 (&acc)[2][2][4][2], int m0, int n0, float scale, const float* ssin,
;                         float* ssout, u16* xbout, int wid, int lane, int wr, int wc, int fr, int fq) {
;     ...
;       if constexpr (EPI == E_PLEGATE || EPI == E_F32 || EPI == E_SWIGLU || EPI == E_GLAIN)
;         rsv = rsqrtf(ssin[g0 + (lane & 15)] * (1.f / 1024.f) + EPS);
;       if constexpr (EPI == E_QROPE) rsv = rsqrtf(ssin[g0 + (lane & 15)] * (1.f / 384.f) + EPS);
;       if constexpr (EPI == E_KV) rsv = rsqrtf(ssin[g0 + (lane & 15)] * (1.f / 256.f) + EPS);
;       for (int i0 = 0; i0 < 16; i0 += 8) {
;     ...
;           } else if constexpr (EPI == E_SWIGLU) {
;             const int gc = (lane >> 3) * 32 + 2 * (lane & 7);
;             const float2 g2 = *(const float2*)(Tr + gc), u2 = *(const float2*)(Tr + gc + 16);
;             const float ga = g2.x * rs, gb = g2.y * rs;
;             const float ha = ga * fsig(ga) * (u2.x * rs), hb = gb * fsig(gb) * (u2.y * rs);
;             __builtin_nontemporal_store(pack2(ha, hb), (unsigned*)((u16*)(wsb + OFF_HID) + (size_t)grow * 2816 + (n0 >> 1) + 2 * lane));
	v_add_u32_e32 v251, 0x9a000, v251
	v_add_u32_e32 v253, 0x9a000, v253
	v_fmamk_f32 v204, v179, 0x3a800000, v150
	v_mul_f32_e32 v205, 0x4b800000, v204
	v_cmp_gt_f32_e32 vcc, s29, v204
	s_nop 1
	v_cndmask_b32_e32 v204, v204, v205, vcc
	v_rsq_f32_e32 v204, v204
	s_nop 0
	v_mul_f32_e32 v205, 0x45800000, v204
	v_cndmask_b32_e32 v252, v204, v205, vcc
	ds_read_b64 v[180:181], v250
	ds_read_b64 v[182:183], v250 offset:64
	ds_read_b64 v[184:185], v250 offset:1040
	ds_read_b64 v[186:187], v250 offset:1104
	ds_read_b64 v[188:189], v250 offset:2080
	ds_read_b64 v[190:191], v250 offset:2144
	ds_read_b64 v[192:193], v250 offset:3120
	ds_read_b64 v[194:195], v250 offset:3184
	v_readlane_b32 s8, v252, 0
	v_readlane_b32 s10, v252, 1
	ds_read_b64 v[196:197], v250 offset:4160
	ds_read_b64 v[198:199], v250 offset:4224
	ds_read_b64 v[200:201], v250 offset:5200
	ds_read_b64 v[202:203], v250 offset:5264
	s_waitcnt lgkmcnt(11)
	v_pk_mul_f32 v[180:181], s[8:9], v[180:181] op_sel_hi:[0,1]
	s_waitcnt lgkmcnt(9)
	v_pk_mul_f32 v[184:185], s[10:11], v[184:185] op_sel_hi:[0,1]
	v_pk_mul_f32 v[182:183], s[8:9], v[182:183] op_sel_hi:[0,1]
	s_waitcnt lgkmcnt(8)
	v_pk_mul_f32 v[186:187], s[10:11], v[186:187] op_sel_hi:[0,1]
	v_pk_mul_f32 v[204:205], v[180:181], v[246:247]
	v_pk_mul_f32 v[206:207], v[184:185], v[246:247]
	v_exp_f32_e32 v204, v204
	v_exp_f32_e32 v205, v205
	v_exp_f32_e32 v206, v206
	v_exp_f32_e32 v207, v207
	v_pk_add_f32 v[204:205], v[204:205], v[248:249]
	v_pk_add_f32 v[206:207], v[206:207], v[248:249]
	v_rcp_f32_e32 v204, v204
	v_rcp_f32_e32 v205, v205
	v_rcp_f32_e32 v206, v206
	v_rcp_f32_e32 v207, v207
	v_pk_mul_f32 v[180:181], v[180:181], v[204:205]
	v_pk_mul_f32 v[184:185], v[184:185], v[206:207]
	v_pk_mul_f32 v[180:181], v[182:183], v[180:181]
	v_pk_mul_f32 v[184:185], v[186:187], v[184:185]
	v_cvt_pk_bf16_f32 v212, v180, v181
	v_cvt_pk_bf16_f32 v213, v184, v185
	global_store_dword v251, v212, s[12:13]
	global_store_dword v253, v213, s[12:13]
	v_add_u32_e32 v251, 0x2c00, v251
	v_add_u32_e32 v253, 0x2c00, v253
	v_readlane_b32 s8, v252, 2
	v_readlane_b32 s10, v252, 3
	ds_read_b64 v[180:181], v250 offset:6240
	ds_read_b64 v[182:183], v250 offset:6304
	ds_read_b64 v[184:185], v250 offset:7280
	ds_read_b64 v[186:187], v250 offset:7344
	s_waitcnt lgkmcnt(11)
	v_pk_mul_f32 v[188:189], s[8:9], v[188:189] op_sel_hi:[0,1]
	s_waitcnt lgkmcnt(9)
	v_pk_mul_f32 v[192:193], s[10:11], v[192:193] op_sel_hi:[0,1]
	v_pk_mul_f32 v[190:191], s[8:9], v[190:191] op_sel_hi:[0,1]
	s_waitcnt lgkmcnt(8)
	v_pk_mul_f32 v[194:195], s[10:11], v[194:195] op_sel_hi:[0,1]
	v_pk_mul_f32 v[204:205], v[188:189], v[246:247]
	v_pk_mul_f32 v[206:207], v[192:193], v[246:247]
	v_exp_f32_e32 v204, v204
	v_exp_f32_e32 v205, v205
	v_exp_f32_e32 v206, v206
	v_exp_f32_e32 v207, v207
	v_pk_add_f32 v[204:205], v[204:205], v[248:249]
	v_pk_add_f32 v[206:207], v[206:207], v[248:249]
	v_rcp_f32_e32 v204, v204
	v_rcp_f32_e32 v205, v205
	v_rcp_f32_e32 v206, v206
	v_rcp_f32_e32 v207, v207
	v_pk_mul_f32 v[188:189], v[188:189], v[204:205]
	v_pk_mul_f32 v[192:193], v[192:193], v[206:207]
	v_pk_mul_f32 v[188:189], v[190:191], v[188:189]
	v_pk_mul_f32 v[192:193], v[194:195], v[192:193]
	v_cvt_pk_bf16_f32 v214, v188, v189
	v_cvt_pk_bf16_f32 v215, v192, v193
	global_store_dword v251, v214, s[12:13]
	global_store_dword v253, v215, s[12:13]
	v_add_u32_e32 v251, 0x2c00, v251
	v_add_u32_e32 v253, 0x2c00, v253
	v_readlane_b32 s8, v252, 4
	v_readlane_b32 s10, v252, 5
	ds_read_b64 v[188:189], v250 offset:8320
	ds_read_b64 v[190:191], v250 offset:8384
	ds_read_b64 v[192:193], v250 offset:9360
	ds_read_b64 v[194:195], v250 offset:9424
	s_waitcnt lgkmcnt(11)
	v_pk_mul_f32 v[196:197], s[8:9], v[196:197] op_sel_hi:[0,1]
	s_waitcnt lgkmcnt(9)
	v_pk_mul_f32 v[200:201], s[10:11], v[200:201] op_sel_hi:[0,1]
	v_pk_mul_f32 v[198:199], s[8:9], v[198:199] op_sel_hi:[0,1]
	s_waitcnt lgkmcnt(8)
	v_pk_mul_f32 v[202:203], s[10:11], v[202:203] op_sel_hi:[0,1]
	v_pk_mul_f32 v[204:205], v[196:197], v[246:247]
	v_pk_mul_f32 v[206:207], v[200:201], v[246:247]
	v_exp_f32_e32 v204, v204
	v_exp_f32_e32 v205, v205
	v_exp_f32_e32 v206, v206
	v_exp_f32_e32 v207, v207
	v_pk_add_f32 v[204:205], v[204:205], v[248:249]
	v_pk_add_f32 v[206:207], v[206:207], v[248:249]
	v_rcp_f32_e32 v204, v204
	v_rcp_f32_e32 v205, v205
	v_rcp_f32_e32 v206, v206
	v_rcp_f32_e32 v207, v207
	v_pk_mul_f32 v[196:197], v[196:197], v[204:205]
	v_pk_mul_f32 v[200:201], v[200:201], v[206:207]
	v_pk_mul_f32 v[196:197], v[198:199], v[196:197]
	v_pk_mul_f32 v[200:201], v[202:203], v[200:201]
	v_cvt_pk_bf16_f32 v212, v196, v197
	v_cvt_pk_bf16_f32 v213, v200, v201
	global_store_dword v251, v212, s[12:13]
	global_store_dword v253, v213, s[12:13]
	v_add_u32_e32 v251, 0x2c00, v251
	v_add_u32_e32 v253, 0x2c00, v253
	v_readlane_b32 s8, v252, 6
	v_readlane_b32 s10, v252, 7
	ds_read_b64 v[196:197], v250 offset:10400
	ds_read_b64 v[198:199], v250 offset:10464
	ds_read_b64 v[200:201], v250 offset:11440
	ds_read_b64 v[202:203], v250 offset:11504
	s_waitcnt lgkmcnt(11)
	v_pk_mul_f32 v[180:181], s[8:9], v[180:181] op_sel_hi:[0,1]
	s_waitcnt lgkmcnt(9)
	v_pk_mul_f32 v[184:185], s[10:11], v[184:185] op_sel_hi:[0,1]
	v_pk_mul_f32 v[182:183], s[8:9], v[182:183] op_sel_hi:[0,1]
	s_waitcnt lgkmcnt(8)
; DEVI float fsig(float x) { return __builtin_amdgcn_rcpf(1.f + __expf(-x)); }
; template <int EPI, int TS, bool VT>
; DEVI void gemm_epilogue(const Params& p, char* smem, f32x4 (&acc)[2][2][4][2], int m0, int n0, float scale, const float* ssin,
;                         float* ssout, u16* xbout, int wid, int lane, int wr, int wc, int fr, int fq) {
;     ...
;         for (int u = 0; u < 8; ++u) {
;           const int i = i0 + u;
;           const int grow = g0 + i;
;           const float* Tr = T + (r0 + i) * TS;
;           const float rs = __int_as_float(__builtin_amdgcn_readlane(__float_as_int(rsv), i));
;     ...
;           } else if constexpr (EPI == E_SWIGLU) {
;             const int gc = (lane >> 3) * 32 + 2 * (lane & 7);
;             const float2 g2 = *(const float2*)(Tr + gc), u2 = *(const float2*)(Tr + gc + 16);
;             const float ga = g2.x * rs, gb = g2.y * rs;
;             const float ha = ga * fsig(ga) * (u2.x * rs), hb = gb * fsig(gb) * (u2.y * rs);
;             __builtin_nontemporal_store(pack2(ha, hb), (unsigned*)((u16*)(wsb + OFF_HID) + (size_t)grow * 2816 + (n0 >> 1) + 2 * lane));
	v_pk_mul_f32 v[186:187], s[10:11], v[186:187] op_sel_hi:[0,1]
	v_pk_mul_f32 v[204:205], v[180:181], v[246:247]
	v_pk_mul_f32 v[206:207], v[184:185], v[246:247]
	v_exp_f32_e32 v204, v204
	v_exp_f32_e32 v205, v205
	v_exp_f32_e32 v206, v206
	v_exp_f32_e32 v207, v207
	v_pk_add_f32 v[204:205], v[204:205], v[248:249]
	v_pk_add_f32 v[206:207], v[206:207], v[248:249]
	v_rcp_f32_e32 v204, v204
	v_rcp_f32_e32 v205, v205
	v_rcp_f32_e32 v206, v206
	v_rcp_f32_e32 v207, v207
	v_pk_mul_f32 v[180:181], v[180:181], v[204:205]
	v_pk_mul_f32 v[184:185], v[184:185], v[206:207]
	v_pk_mul_f32 v[180:181], v[182:183], v[180:181]
	v_pk_mul_f32 v[184:185], v[186:187], v[184:185]
	v_cvt_pk_bf16_f32 v214, v180, v181
	v_cvt_pk_bf16_f32 v215, v184, v185
	global_store_dword v251, v214, s[12:13]
	global_store_dword v253, v215, s[12:13]
	v_add_u32_e32 v251, 0x2c00, v251
	v_add_u32_e32 v253, 0x2c00, v253
	v_readlane_b32 s8, v252, 8
	v_readlane_b32 s10, v252, 9
	ds_read_b64 v[180:181], v250 offset:12480
	ds_read_b64 v[182:183], v250 offset:12544
	ds_read_b64 v[184:185], v250 offset:13520
	ds_read_b64 v[186:187], v250 offset:13584
	s_waitcnt lgkmcnt(11)
	v_pk_mul_f32 v[188:189], s[8:9], v[188:189] op_sel_hi:[0,1]
	s_waitcnt lgkmcnt(9)
	v_pk_mul_f32 v[192:193], s[10:11], v[192:193] op_sel_hi:[0,1]
	v_pk_mul_f32 v[190:191], s[8:9], v[190:191] op_sel_hi:[0,1]
	s_waitcnt lgkmcnt(8)
	v_pk_mul_f32 v[194:195], s[10:11], v[194:195] op_sel_hi:[0,1]
	v_pk_mul_f32 v[204:205], v[188:189], v[246:247]
	v_pk_mul_f32 v[206:207], v[192:193], v[246:247]
	v_exp_f32_e32 v204, v204
	v_exp_f32_e32 v205, v205
	v_exp_f32_e32 v206, v206
	v_exp_f32_e32 v207, v207
	v_pk_add_f32 v[204:205], v[204:205], v[248:249]
	v_pk_add_f32 v[206:207], v[206:207], v[248:249]
	v_rcp_f32_e32 v204, v204
	v_rcp_f32_e32 v205, v205
	v_rcp_f32_e32 v206, v206
	v_rcp_f32_e32 v207, v207
	v_pk_mul_f32 v[188:189], v[188:189], v[204:205]
	v_pk_mul_f32 v[192:193], v[192:193], v[206:207]
	v_pk_mul_f32 v[188:189], v[190:191], v[188:189]
	v_pk_mul_f32 v[192:193], v[194:195], v[192:193]
	v_cvt_pk_bf16_f32 v212, v188, v189
	v_cvt_pk_bf16_f32 v213, v192, v193
	global_store_dword v251, v212, s[12:13]
	global_store_dword v253, v213, s[12:13]
	v_add_u32_e32 v251, 0x2c00, v251
	v_add_u32_e32 v253, 0x2c00, v253
	v_readlane_b32 s8, v252, 10
	v_readlane_b32 s10, v252, 11
	ds_read_b64 v[188:189], v250 offset:14560
	ds_read_b64 v[190:191], v250 offset:14624
	ds_read_b64 v[192:193], v250 offset:15600
	ds_read_b64 v[194:195], v250 offset:15664
	s_waitcnt lgkmcnt(11)
	v_pk_mul_f32 v[196:197], s[8:9], v[196:197] op_sel_hi:[0,1]
	s_waitcnt lgkmcnt(9)
	v_pk_mul_f32 v[200:201], s[10:11], v[200:201] op_sel_hi:[0,1]
	v_pk_mul_f32 v[198:199], s[8:9], v[198:199] op_sel_hi:[0,1]
	s_waitcnt lgkmcnt(8)
	v_pk_mul_f32 v[202:203], s[10:11], v[202:203] op_sel_hi:[0,1]
	v_pk_mul_f32 v[204:205], v[196:197], v[246:247]
	v_pk_mul_f32 v[206:207], v[200:201], v[246:247]
	v_exp_f32_e32 v204, v204
	v_exp_f32_e32 v205, v205
	v_exp_f32_e32 v206, v206
	v_exp_f32_e32 v207, v207
	v_pk_add_f32 v[204:205], v[204:205], v[248:249]
	v_pk_add_f32 v[206:207], v[206:207], v[248:249]
	v_rcp_f32_e32 v204, v204
	v_rcp_f32_e32 v205, v205
	v_rcp_f32_e32 v206, v206
	v_rcp_f32_e32 v207, v207
	v_pk_mul_f32 v[196:197], v[196:197], v[204:205]
	v_pk_mul_f32 v[200:201], v[200:201], v[206:207]
	v_pk_mul_f32 v[196:197], v[198:199], v[196:197]
	v_pk_mul_f32 v[200:201], v[202:203], v[200:201]
	v_cvt_pk_bf16_f32 v214, v196, v197
	v_cvt_pk_bf16_f32 v215, v200, v201
	global_store_dword v251, v214, s[12:13]
	global_store_dword v253, v215, s[12:13]
	v_add_u32_e32 v251, 0x2c00, v251
	v_add_u32_e32 v253, 0x2c00, v253
	v_readlane_b32 s8, v252, 12
	v_readlane_b32 s10, v252, 13
	s_waitcnt lgkmcnt(7)
	v_pk_mul_f32 v[180:181], s[8:9], v[180:181] op_sel_hi:[0,1]
	s_waitcnt lgkmcnt(5)
	v_pk_mul_f32 v[184:185], s[10:11], v[184:185] op_sel_hi:[0,1]
	v_pk_mul_f32 v[182:183], s[8:9], v[182:183] op_sel_hi:[0,1]
	s_waitcnt lgkmcnt(4)
	v_pk_mul_f32 v[186:187], s[10:11], v[186:187] op_sel_hi:[0,1]
	v_pk_mul_f32 v[204:205], v[180:181], v[246:247]
	v_pk_mul_f32 v[206:207], v[184:185], v[246:247]
	v_exp_f32_e32 v204, v204
	v_exp_f32_e32 v205, v205
	v_exp_f32_e32 v206, v206
	v_exp_f32_e32 v207, v207
	v_pk_add_f32 v[204:205], v[204:205], v[248:249]
	v_pk_add_f32 v[206:207], v[206:207], v[248:249]
	v_rcp_f32_e32 v204, v204
	v_rcp_f32_e32 v205, v205
	v_rcp_f32_e32 v206, v206
	v_rcp_f32_e32 v207, v207
	v_pk_mul_f32 v[180:181], v[180:181], v[204:205]
	v_pk_mul_f32 v[184:185], v[184:185], v[206:207]
	v_pk_mul_f32 v[180:181], v[182:183], v[180:181]
	v_pk_mul_f32 v[184:185], v[186:187], v[184:185]
	v_cvt_pk_bf16_f32 v212, v180, v181
	v_cvt_pk_bf16_f32 v213, v184, v185
	global_store_dword v251, v212, s[12:13]
	global_store_dword v253, v213, s[12:13]
	v_add_u32_e32 v251, 0x2c00, v251
	v_add_u32_e32 v253, 0x2c00, v253
	v_readlane_b32 s8, v252, 14
	v_readlane_b32 s10, v252, 15
	s_waitcnt lgkmcnt(3)
	v_pk_mul_f32 v[188:189], s[8:9], v[188:189] op_sel_hi:[0,1]
	s_waitcnt lgkmcnt(1)
	v_pk_mul_f32 v[192:193], s[10:11], v[192:193] op_sel_hi:[0,1]
	v_pk_mul_f32 v[190:191], s[8:9], v[190:191] op_sel_hi:[0,1]
	s_waitcnt lgkmcnt(0)
	v_pk_mul_f32 v[194:195], s[10:11], v[194:195] op_sel_hi:[0,1]
	v_pk_mul_f32 v[204:205], v[188:189], v[246:247]
	v_pk_mul_f32 v[206:207], v[192:193], v[246:247]
	v_exp_f32_e32 v204, v204
	v_exp_f32_e32 v205, v205
	v_exp_f32_e32 v206, v206
	v_exp_f32_e32 v207, v207
	v_pk_add_f32 v[204:205], v[204:205], v[248:249]
	v_pk_add_f32 v[206:207], v[206:207], v[248:249]
	v_rcp_f32_e32 v204, v204
	v_rcp_f32_e32 v205, v205
	v_rcp_f32_e32 v206, v206
	v_rcp_f32_e32 v207, v207
	v_pk_mul_f32 v[188:189], v[188:189], v[204:205]
	v_pk_mul_f32 v[192:193], v[192:193], v[206:207]
	v_pk_mul_f32 v[188:189], v[190:191], v[188:189]
	v_pk_mul_f32 v[192:193], v[194:195], v[192:193]
	v_cvt_pk_bf16_f32 v214, v188, v189
	v_cvt_pk_bf16_f32 v215, v192, v193
	global_store_dword v251, v214, s[12:13]
	global_store_dword v253, v215, s[12:13]
	v_add_u32_e32 v251, 0x2c00, v251
	v_add_u32_e32 v253, 0x2c00, v253
	s_mov_b32 s7, s30
	s_andn2_b64 vcc, exec, s[4:5]
	s_waitcnt lgkmcnt(0)
	s_barrier
	s_cbranch_vccz .LBB0_144

; template <int EPI, int TS, bool VT>
; DEVI void gemm_epilogue(const Params& p, char* smem, f32x4 (&acc)[2][2][4][2], int m0, int n0, float scale, const float* ssin,
;                         float* ssout, u16* xbout, int wid, int lane, int wr, int wc, int fr, int fq) {
;     ...
;           for (int u = 0; u < 8; ++u) {
;             const size_t ro = (size_t)(g0 + i0 + u) * 1024 + n0 + 4 * lane;
;             const int gr = g0 + i0 + u;
;             const float* xs = p.x + ro;
;             if (scale < 0.f)
;               xs = (gr < MP ? p.x_prompt + ro : p.x_sample + (ro - (size_t)MP * 1024));
;             { const f32x4 t_ = __builtin_nontemporal_load((const f32x4*)xs); xo[u] = make_float4(t_[0], t_[1], t_[2], t_[3]); }
.LBB0_174:
	global_load_dwordx4 v[92:95], v[64:65], off
	s_or_b32 s66, s18, 1
	s_ashr_i32 s67, s66, 31
	s_lshl_b64 s[0:1], s[66:67], 10
	v_lshl_add_u64 v[126:127], s[0:1], 0, v[128:129]
	v_lshl_add_u64 v[124:125], v[126:127], 2, s[38:39]
	s_and_b64 vcc, exec, s[4:5]
	v_mov_b64_e32 v[64:65], v[124:125]
	s_cbranch_vccnz .LBB0_179
	s_cmp_lt_i32 s18, 0xffff
	s_mov_b64 s[0:1], -1
	s_cbranch_scc1 .LBB0_177
	v_readlane_b32 s20, v254, 4
	v_readlane_b32 s22, v254, 6
	v_readlane_b32 s23, v254, 7
	s_brev_b32 s0, 15
	s_mov_b32 s1, -1
	v_lshl_add_u64 v[64:65], v[126:127], 2, s[22:23]
	v_lshl_add_u64 v[64:65], v[64:65], 0, s[0:1]
	s_mov_b64 s[0:1], 0
	v_readlane_b32 s21, v254, 5

; template <int EPI, int TS, bool VT>
; DEVI void gemm_epilogue(const Params& p, char* smem, f32x4 (&acc)[2][2][4][2], int m0, int n0, float scale, const float* ssin,
;                         float* ssout, u16* xbout, int wid, int lane, int wr, int wc, int fr, int fq) {
;     ...
;           for (int u = 0; u < 8; ++u) {
;             const size_t ro = (size_t)(g0 + i0 + u) * 1024 + n0 + 4 * lane;
;             const int gr = g0 + i0 + u;
;             const float* xs = p.x + ro;
;             if (scale < 0.f)
;               xs = (gr < MP ? p.x_prompt + ro : p.x_sample + (ro - (size_t)MP * 1024));
;             { const f32x4 t_ = __builtin_nontemporal_load((const f32x4*)xs); xo[u] = make_float4(t_[0], t_[1], t_[2], t_[3]); }
.LBB0_179:
	global_load_dwordx4 v[88:91], v[64:65], off
	s_or_b32 s64, s18, 2
	s_ashr_i32 s65, s64, 31
	s_lshl_b64 s[0:1], s[64:65], 10
	v_lshl_add_u64 v[120:121], s[0:1], 0, v[128:129]
	v_lshl_add_u64 v[118:119], v[120:121], 2, s[38:39]
	s_and_b64 vcc, exec, s[4:5]
	v_mov_b64_e32 v[64:65], v[118:119]
	s_cbranch_vccnz .LBB0_184
	s_cmp_lt_i32 s18, 0xfffe
	s_mov_b64 s[0:1], -1
	s_cbranch_scc1 .LBB0_182
	v_readlane_b32 s20, v254, 4
	v_readlane_b32 s22, v254, 6
	v_readlane_b32 s23, v254, 7
	s_brev_b32 s0, 15
	s_mov_b32 s1, -1
	v_lshl_add_u64 v[64:65], v[120:121], 2, s[22:23]
	v_lshl_add_u64 v[64:65], v[64:65], 0, s[0:1]
	s_mov_b64 s[0:1], 0
	v_readlane_b32 s21, v254, 5

; template <int EPI, int TS, bool VT>
; DEVI void gemm_epilogue(const Params& p, char* smem, f32x4 (&acc)[2][2][4][2], int m0, int n0, float scale, const float* ssin,
;                         float* ssout, u16* xbout, int wid, int lane, int wr, int wc, int fr, int fq) {
;     ...
;           for (int u = 0; u < 8; ++u) {
;             const size_t ro = (size_t)(g0 + i0 + u) * 1024 + n0 + 4 * lane;
;             const int gr = g0 + i0 + u;
;             const float* xs = p.x + ro;
;             if (scale < 0.f)
;               xs = (gr < MP ? p.x_prompt + ro : p.x_sample + (ro - (size_t)MP * 1024));
;             { const f32x4 t_ = __builtin_nontemporal_load((const f32x4*)xs); xo[u] = make_float4(t_[0], t_[1], t_[2], t_[3]); }
.LBB0_184:
	global_load_dwordx4 v[84:87], v[64:65], off
	s_or_b32 s62, s18, 3
	s_ashr_i32 s63, s62, 31
	s_lshl_b64 s[0:1], s[62:63], 10
	v_lshl_add_u64 v[116:117], s[0:1], 0, v[128:129]
	v_lshl_add_u64 v[112:113], v[116:117], 2, s[38:39]
	s_and_b64 vcc, exec, s[4:5]
	v_mov_b64_e32 v[64:65], v[112:113]
	s_cbranch_vccnz .LBB0_189
	s_cmp_lt_i32 s18, 0xfffd
	s_mov_b64 s[0:1], -1
	s_cbranch_scc1 .LBB0_187
	v_readlane_b32 s20, v254, 4
	v_readlane_b32 s22, v254, 6
	v_readlane_b32 s23, v254, 7
	s_brev_b32 s0, 15
	s_mov_b32 s1, -1
	v_lshl_add_u64 v[64:65], v[116:117], 2, s[22:23]
	v_lshl_add_u64 v[64:65], v[64:65], 0, s[0:1]
	s_mov_b64 s[0:1], 0
	v_readlane_b32 s21, v254, 5

; template <int EPI, int TS, bool VT>
; DEVI void gemm_epilogue(const Params& p, char* smem, f32x4 (&acc)[2][2][4][2], int m0, int n0, float scale, const float* ssin,
;                         float* ssout, u16* xbout, int wid, int lane, int wr, int wc, int fr, int fq) {
;     ...
;           for (int u = 0; u < 8; ++u) {
;             const size_t ro = (size_t)(g0 + i0 + u) * 1024 + n0 + 4 * lane;
;             const int gr = g0 + i0 + u;
;             const float* xs = p.x + ro;
;             if (scale < 0.f)
;               xs = (gr < MP ? p.x_prompt + ro : p.x_sample + (ro - (size_t)MP * 1024));
;             { const f32x4 t_ = __builtin_nontemporal_load((const f32x4*)xs); xo[u] = make_float4(t_[0], t_[1], t_[2], t_[3]); }
.LBB0_189:
	global_load_dwordx4 v[80:83], v[64:65], off
	s_or_b32 s34, s18, 4
	s_ashr_i32 s35, s34, 31
	s_lshl_b64 s[0:1], s[34:35], 10
	v_lshl_add_u64 v[110:111], s[0:1], 0, v[128:129]
	v_lshl_add_u64 v[108:109], v[110:111], 2, s[38:39]
	s_and_b64 vcc, exec, s[4:5]
	v_mov_b64_e32 v[64:65], v[108:109]
	s_cbranch_vccnz .LBB0_194
	s_cmp_lt_i32 s18, 0xfffc
	s_mov_b64 s[0:1], -1
	s_cbranch_scc1 .LBB0_192
	v_readlane_b32 s20, v254, 4
	v_readlane_b32 s22, v254, 6
	v_readlane_b32 s23, v254, 7
	s_brev_b32 s0, 15
	s_mov_b32 s1, -1
	v_lshl_add_u64 v[64:65], v[110:111], 2, s[22:23]
	v_lshl_add_u64 v[64:65], v[64:65], 0, s[0:1]
	s_mov_b64 s[0:1], 0
	v_readlane_b32 s21, v254, 5

; template <int EPI, int TS, bool VT>
; DEVI void gemm_epilogue(const Params& p, char* smem, f32x4 (&acc)[2][2][4][2], int m0, int n0, float scale, const float* ssin,
;                         float* ssout, u16* xbout, int wid, int lane, int wr, int wc, int fr, int fq) {
;     ...
;           for (int u = 0; u < 8; ++u) {
;             const size_t ro = (size_t)(g0 + i0 + u) * 1024 + n0 + 4 * lane;
;             const int gr = g0 + i0 + u;
;             const float* xs = p.x + ro;
;             if (scale < 0.f)
;               xs = (gr < MP ? p.x_prompt + ro : p.x_sample + (ro - (size_t)MP * 1024));
;             { const f32x4 t_ = __builtin_nontemporal_load((const f32x4*)xs); xo[u] = make_float4(t_[0], t_[1], t_[2], t_[3]); }
.LBB0_194:
	global_load_dwordx4 v[76:79], v[64:65], off
	s_or_b32 s30, s18, 5
	s_ashr_i32 s31, s30, 31
	s_lshl_b64 s[0:1], s[30:31], 10
	v_lshl_add_u64 v[106:107], s[0:1], 0, v[128:129]
	v_lshl_add_u64 v[104:105], v[106:107], 2, s[38:39]
	s_and_b64 vcc, exec, s[4:5]
	v_mov_b64_e32 v[64:65], v[104:105]
	s_cbranch_vccnz .LBB0_199
	s_cmp_lt_i32 s18, 0xfffb
	s_mov_b64 s[0:1], -1
	s_cbranch_scc1 .LBB0_197
	v_readlane_b32 s20, v254, 4
	v_readlane_b32 s22, v254, 6
	v_readlane_b32 s23, v254, 7
	s_brev_b32 s0, 15
	s_mov_b32 s1, -1
	v_lshl_add_u64 v[64:65], v[106:107], 2, s[22:23]
	v_lshl_add_u64 v[64:65], v[64:65], 0, s[0:1]
	s_mov_b64 s[0:1], 0
	v_readlane_b32 s21, v254, 5

; template <int EPI, int TS, bool VT>
; DEVI void gemm_epilogue(const Params& p, char* smem, f32x4 (&acc)[2][2][4][2], int m0, int n0, float scale, const float* ssin,
;                         float* ssout, u16* xbout, int wid, int lane, int wr, int wc, int fr, int fq) {
;     ...
;           for (int u = 0; u < 8; ++u) {
;             const size_t ro = (size_t)(g0 + i0 + u) * 1024 + n0 + 4 * lane;
;             const int gr = g0 + i0 + u;
;             const float* xs = p.x + ro;
;             if (scale < 0.f)
;               xs = (gr < MP ? p.x_prompt + ro : p.x_sample + (ro - (size_t)MP * 1024));
;             { const f32x4 t_ = __builtin_nontemporal_load((const f32x4*)xs); xo[u] = make_float4(t_[0], t_[1], t_[2], t_[3]); }
.LBB0_199:
	global_load_dwordx4 v[72:75], v[64:65], off
	s_or_b32 s22, s18, 6
	s_ashr_i32 s23, s22, 31
	s_lshl_b64 s[0:1], s[22:23], 10
	v_lshl_add_u64 v[102:103], s[0:1], 0, v[128:129]
	v_lshl_add_u64 v[100:101], v[102:103], 2, s[38:39]
	s_and_b64 vcc, exec, s[4:5]
	v_mov_b64_e32 v[64:65], v[100:101]
	s_cbranch_vccnz .LBB0_204
	s_cmp_lt_i32 s18, 0xfffa
	s_mov_b64 s[0:1], -1
	s_cbranch_scc1 .LBB0_202
	v_readlane_b32 s76, v254, 4
	v_readlane_b32 s78, v254, 6
	v_readlane_b32 s79, v254, 7
	s_brev_b32 s0, 15
	s_mov_b32 s1, -1
	v_lshl_add_u64 v[64:65], v[102:103], 2, s[78:79]
	v_lshl_add_u64 v[64:65], v[64:65], 0, s[0:1]
	s_mov_b64 s[0:1], 0
	v_readlane_b32 s77, v254, 5

; template <int EPI, int TS, bool VT>
; DEVI void gemm_epilogue(const Params& p, char* smem, f32x4 (&acc)[2][2][4][2], int m0, int n0, float scale, const float* ssin,
;                         float* ssout, u16* xbout, int wid, int lane, int wr, int wc, int fr, int fq) {
;     ...
;           for (int u = 0; u < 8; ++u) {
;             const size_t ro = (size_t)(g0 + i0 + u) * 1024 + n0 + 4 * lane;
;             const int gr = g0 + i0 + u;
;             const float* xs = p.x + ro;
;             if (scale < 0.f)
;               xs = (gr < MP ? p.x_prompt + ro : p.x_sample + (ro - (size_t)MP * 1024));
;             { const f32x4 t_ = __builtin_nontemporal_load((const f32x4*)xs); xo[u] = make_float4(t_[0], t_[1], t_[2], t_[3]); }
.LBB0_204:
	global_load_dwordx4 v[68:71], v[64:65], off
	s_or_b32 s20, s18, 7
	s_ashr_i32 s21, s20, 31
	s_lshl_b64 s[0:1], s[20:21], 10
	v_lshl_add_u64 v[98:99], s[0:1], 0, v[128:129]
	v_lshl_add_u64 v[96:97], v[98:99], 2, s[38:39]
	s_and_b64 vcc, exec, s[4:5]
	v_mov_b64_e32 v[64:65], v[96:97]
	s_cbranch_vccnz .LBB0_209
	s_cmp_lt_i32 s18, 0xfff9
	s_mov_b64 s[0:1], -1
	s_cbranch_scc1 .LBB0_207
	v_readlane_b32 s76, v254, 4
	v_readlane_b32 s78, v254, 6
	v_readlane_b32 s79, v254, 7
	s_brev_b32 s0, 15
	s_mov_b32 s1, -1
	v_lshl_add_u64 v[64:65], v[98:99], 2, s[78:79]
	v_lshl_add_u64 v[64:65], v[64:65], 0, s[0:1]
	s_mov_b64 s[0:1], 0
	v_readlane_b32 s77, v254, 5

; DEVI float fsig(float x) { return __builtin_amdgcn_rcpf(1.f + __expf(-x)); }
; DEVI float bflo(unsigned u) { return __uint_as_float(u << 16); }
; DEVI float bfhi(unsigned u) { return __uint_as_float(u & 0xffff0000u); }
; template <int EPI, int TS, bool VT>
; DEVI void gemm_epilogue(const Params& p, char* smem, f32x4 (&acc)[2][2][4][2], int m0, int n0, float scale, const float* ssin,
;                         float* ssout, u16* xbout, int wid, int lane, int wr, int wc, int fr, int fq) {
;     ...
;         for (int u = 0; u < 8; ++u) {
;           const int i = i0 + u;
;           const int grow = g0 + i;
;           const float* Tr = T + (r0 + i) * TS;
;           const float rs = __int_as_float(__builtin_amdgcn_readlane(__float_as_int(rsv), i));
;           if constexpr (EPI == E_RESID || EPI == E_PLEGATE) {
;             const float4 a = *(const float4*)(Tr + 4 * lane);
;             const size_t ro = (size_t)grow * 1024 + n0 + 4 * lane;
;             float4 x4 = xo[u];
;             if constexpr (EPI == E_PLEGATE) {
;               x4.x += bflo(pv[u].x) * fsig(a.x * rs);
;               x4.y += bfhi(pv[u].x) * fsig(a.y * rs);
;               x4.z += bflo(pv[u].y) * fsig(a.z * rs);
;               x4.w += bfhi(pv[u].y) * fsig(a.w * rs);
;             } else {
;               const float sc = fabsf(scale);
;               x4.x += sc * a.x; x4.y += sc * a.y; x4.z += sc * a.z; x4.w += sc * a.w;
;             }
;             st_nt16(p.x + ro, x4);
;             if (xbout) {
;               uint2 o;
;               o.x = pack2(x4.x, x4.y);
;               o.y = pack2(x4.z, x4.w);
;               st_nt8(xbout + ro, o);
;             }
;             if (ssout) {
;               const float ssq = wsum(x4.x * x4.x + x4.y * x4.y + x4.z * x4.z + x4.w * x4.w, lane);
;               if (lane == 0) atomicAdd(ssout + grow, ssq);
;             }
.LBB0_209:
	global_load_dwordx4 v[64:67], v[64:65], off
	v_lshlrev_b32_e32 v130, 2, v130
	s_mulk_i32 s68, 0x4100
	v_add_u32_e32 v130, s68, v130
	ds_read_b128 v[154:157], v130
	v_cmp_eq_u32_e64 s[0:1], 0, v152
	v_lshl_add_u64 v[114:115], v[114:115], 1, s[8:9]
	s_waitcnt vmcnt(7) lgkmcnt(0)
	v_pk_fma_f32 v[92:93], s[12:13], v[154:155], v[92:93]
	v_pk_fma_f32 v[94:95], s[12:13], v[156:157], v[94:95]
	global_store_dwordx4 v[122:123], v[92:95], off
	v_cvt_pk_bf16_f32 v122, v92, v93
	v_cvt_pk_bf16_f32 v123, v94, v95
	v_pk_mul_f32 v[92:93], v[92:93], v[92:93]
	v_pk_mul_f32 v[94:95], v[94:95], v[94:95]
	v_add_f32_e32 v92, v92, v93
	v_add_f32_e32 v92, v92, v94
	v_add_f32_e32 v92, v92, v95
	flat_store_dwordx2 v[114:115], v[122:123]
	s_nop 0
	v_add_f32_dpp v92, v92, v92 row_ror:8 row_mask:0xf bank_mask:0xf bound_ctrl:1
	s_nop 1
	v_add_f32_dpp v92, v92, v92 row_ror:4 row_mask:0xf bank_mask:0xf bound_ctrl:1
	s_nop 1
	v_add_f32_dpp v92, v92, v92 row_ror:2 row_mask:0xf bank_mask:0xf bound_ctrl:1
	s_nop 1
	v_add_f32_dpp v92, v92, v92 row_ror:1 row_mask:0xf bank_mask:0xf bound_ctrl:1
	s_nop 0
	v_readlane_b32 s70, v92, 0
	v_readlane_b32 s76, v92, 16
	v_readlane_b32 s71, v92, 32
	v_readlane_b32 s75, v92, 48
	s_and_saveexec_b64 s[68:69], s[0:1]
	s_cbranch_execz .LBB0_211
	s_lshl_b64 s[78:79], s[18:19], 2
	v_mov_b32_e32 v92, s76
	s_add_u32 s78, s16, s78
	v_add_f32_e32 v92, s70, v92
	s_addc_u32 s79, s17, s79
	v_add_f32_e32 v92, s71, v92
	v_add_f32_e32 v94, s75, v92
	v_mov_b64_e32 v[92:93], s[78:79]
	flat_atomic_add_f32 v[92:93], v94
.LBB0_211:
	s_or_b64 exec, exec, s[68:69]
	ds_read_b128 v[92:95], v130 offset:1040
	v_lshl_add_u64 v[114:115], v[126:127], 1, s[8:9]
	s_waitcnt vmcnt(0) lgkmcnt(0)
	v_pk_fma_f32 v[88:89], s[12:13], v[92:93], v[88:89]
	v_pk_fma_f32 v[90:91], s[12:13], v[94:95], v[90:91]
	global_store_dwordx4 v[124:125], v[88:91], off
	v_cvt_pk_bf16_f32 v92, v88, v89
	v_cvt_pk_bf16_f32 v93, v90, v91
	v_pk_mul_f32 v[88:89], v[88:89], v[88:89]
	v_pk_mul_f32 v[90:91], v[90:91], v[90:91]
	v_add_f32_e32 v88, v88, v89
	v_add_f32_e32 v88, v88, v90
	v_add_f32_e32 v88, v88, v91
	flat_store_dwordx2 v[114:115], v[92:93]
	s_nop 0
	v_add_f32_dpp v88, v88, v88 row_ror:8 row_mask:0xf bank_mask:0xf bound_ctrl:1
	s_nop 1
	v_add_f32_dpp v88, v88, v88 row_ror:4 row_mask:0xf bank_mask:0xf bound_ctrl:1
	s_nop 1
	v_add_f32_dpp v88, v88, v88 row_ror:2 row_mask:0xf bank_mask:0xf bound_ctrl:1
	s_nop 1
	v_add_f32_dpp v88, v88, v88 row_ror:1 row_mask:0xf bank_mask:0xf bound_ctrl:1
	s_nop 0
	v_readlane_b32 s19, v88, 0
	v_readlane_b32 s75, v88, 16
	v_readlane_b32 s70, v88, 32
	v_readlane_b32 s71, v88, 48
	s_and_saveexec_b64 s[68:69], s[0:1]
	s_cbranch_execz .LBB0_213
	s_lshl_b64 s[66:67], s[66:67], 2
	v_mov_b32_e32 v88, s75
	s_add_u32 s66, s16, s66
	v_add_f32_e32 v88, s19, v88
	s_addc_u32 s67, s17, s67
	v_add_f32_e32 v88, s70, v88
	v_add_f32_e32 v90, s71, v88
	v_mov_b64_e32 v[88:89], s[66:67]
	flat_atomic_add_f32 v[88:89], v90
.LBB0_213:
	s_or_b64 exec, exec, s[68:69]
	ds_read_b128 v[88:91], v130 offset:2080
	v_lshl_add_u64 v[92:93], v[120:121], 1, s[8:9]
	s_waitcnt lgkmcnt(0)
	v_pk_fma_f32 v[84:85], s[12:13], v[88:89], v[84:85]
	v_pk_fma_f32 v[86:87], s[12:13], v[90:91], v[86:87]
	global_store_dwordx4 v[118:119], v[84:87], off
	v_cvt_pk_bf16_f32 v88, v84, v85
	v_cvt_pk_bf16_f32 v89, v86, v87
	v_pk_mul_f32 v[84:85], v[84:85], v[84:85]
	v_pk_mul_f32 v[86:87], v[86:87], v[86:87]
	v_add_f32_e32 v84, v84, v85
	v_add_f32_e32 v84, v84, v86
	v_add_f32_e32 v84, v84, v87
	flat_store_dwordx2 v[92:93], v[88:89]
	s_nop 0
	v_add_f32_dpp v84, v84, v84 row_ror:8 row_mask:0xf bank_mask:0xf bound_ctrl:1
	s_nop 1
	v_add_f32_dpp v84, v84, v84 row_ror:4 row_mask:0xf bank_mask:0xf bound_ctrl:1
	s_nop 1
	v_add_f32_dpp v84, v84, v84 row_ror:2 row_mask:0xf bank_mask:0xf bound_ctrl:1
	s_nop 1
	v_add_f32_dpp v84, v84, v84 row_ror:1 row_mask:0xf bank_mask:0xf bound_ctrl:1
	s_nop 0
	v_readlane_b32 s19, v84, 0
	v_readlane_b32 s70, v84, 16
	v_readlane_b32 s68, v84, 32
	v_readlane_b32 s69, v84, 48
	s_and_saveexec_b64 s[66:67], s[0:1]
	s_cbranch_execz .LBB0_215
	s_lshl_b64 s[64:65], s[64:65], 2
	v_mov_b32_e32 v84, s70
	s_add_u32 s64, s16, s64
	v_add_f32_e32 v84, s19, v84
	s_addc_u32 s65, s17, s65
	v_add_f32_e32 v84, s68, v84
	v_add_f32_e32 v86, s69, v84
	v_mov_b64_e32 v[84:85], s[64:65]
	flat_atomic_add_f32 v[84:85], v86
.LBB0_215:
	s_or_b64 exec, exec, s[66:67]
	ds_read_b128 v[84:87], v130 offset:3120
	v_lshl_add_u64 v[88:89], v[116:117], 1, s[8:9]
	s_waitcnt lgkmcnt(0)
	v_pk_fma_f32 v[80:81], s[12:13], v[84:85], v[80:81]
	v_pk_fma_f32 v[82:83], s[12:13], v[86:87], v[82:83]
	global_store_dwordx4 v[112:113], v[80:83], off
	v_cvt_pk_bf16_f32 v84, v80, v81
	v_cvt_pk_bf16_f32 v85, v82, v83
	v_pk_mul_f32 v[80:81], v[80:81], v[80:81]
	v_pk_mul_f32 v[82:83], v[82:83], v[82:83]
	v_add_f32_e32 v80, v80, v81
	v_add_f32_e32 v80, v80, v82
	v_add_f32_e32 v80, v80, v83
	flat_store_dwordx2 v[88:89], v[84:85]
	s_nop 0
	v_add_f32_dpp v80, v80, v80 row_ror:8 row_mask:0xf bank_mask:0xf bound_ctrl:1
	s_nop 1
	v_add_f32_dpp v80, v80, v80 row_ror:4 row_mask:0xf bank_mask:0xf bound_ctrl:1
	s_nop 1
	v_add_f32_dpp v80, v80, v80 row_ror:2 row_mask:0xf bank_mask:0xf bound_ctrl:1
	s_nop 1
	v_add_f32_dpp v80, v80, v80 row_ror:1 row_mask:0xf bank_mask:0xf bound_ctrl:1
	s_nop 0
	v_readlane_b32 s19, v80, 0
	v_readlane_b32 s68, v80, 16
	v_readlane_b32 s66, v80, 32
	v_readlane_b32 s67, v80, 48
	s_and_saveexec_b64 s[64:65], s[0:1]
	s_cbranch_execz .LBB0_217
	s_lshl_b64 s[62:63], s[62:63], 2
	v_mov_b32_e32 v80, s68
	s_add_u32 s62, s16, s62
	v_add_f32_e32 v80, s19, v80
	s_addc_u32 s63, s17, s63
	v_add_f32_e32 v80, s66, v80
	v_add_f32_e32 v82, s67, v80
	v_mov_b64_e32 v[80:81], s[62:63]
	flat_atomic_add_f32 v[80:81], v82
; DEVI float fsig(float x) { return __builtin_amdgcn_rcpf(1.f + __expf(-x)); }
; DEVI float bflo(unsigned u) { return __uint_as_float(u << 16); }
; DEVI float bfhi(unsigned u) { return __uint_as_float(u & 0xffff0000u); }
; template <int EPI, int TS, bool VT>
; DEVI void gemm_epilogue(const Params& p, char* smem, f32x4 (&acc)[2][2][4][2], int m0, int n0, float scale, const float* ssin,
;                         float* ssout, u16* xbout, int wid, int lane, int wr, int wc, int fr, int fq) {
;     ...
;         for (int u = 0; u < 8; ++u) {
;           const int i = i0 + u;
;           const int grow = g0 + i;
;           const float* Tr = T + (r0 + i) * TS;
;           const float rs = __int_as_float(__builtin_amdgcn_readlane(__float_as_int(rsv), i));
;           if constexpr (EPI == E_RESID || EPI == E_PLEGATE) {
;             const float4 a = *(const float4*)(Tr + 4 * lane);
;             const size_t ro = (size_t)grow * 1024 + n0 + 4 * lane;
;             float4 x4 = xo[u];
;             if constexpr (EPI == E_PLEGATE) {
;               x4.x += bflo(pv[u].x) * fsig(a.x * rs);
;               x4.y += bfhi(pv[u].x) * fsig(a.y * rs);
;               x4.z += bflo(pv[u].y) * fsig(a.z * rs);
;               x4.w += bfhi(pv[u].y) * fsig(a.w * rs);
;             } else {
;               const float sc = fabsf(scale);
;               x4.x += sc * a.x; x4.y += sc * a.y; x4.z += sc * a.z; x4.w += sc * a.w;
;             }
;             st_nt16(p.x + ro, x4);
;             if (xbout) {
;               uint2 o;
;               o.x = pack2(x4.x, x4.y);
;               o.y = pack2(x4.z, x4.w);
;               st_nt8(xbout + ro, o);
;             }
;             if (ssout) {
;               const float ssq = wsum(x4.x * x4.x + x4.y * x4.y + x4.z * x4.z + x4.w * x4.w, lane);
;               if (lane == 0) atomicAdd(ssout + grow, ssq);
;             }
.LBB0_217:
	s_or_b64 exec, exec, s[64:65]
	ds_read_b128 v[80:83], v130 offset:4160
	v_lshl_add_u64 v[84:85], v[110:111], 1, s[8:9]
	s_waitcnt lgkmcnt(0)
	v_pk_fma_f32 v[76:77], s[12:13], v[80:81], v[76:77]
	v_pk_fma_f32 v[78:79], s[12:13], v[82:83], v[78:79]
	global_store_dwordx4 v[108:109], v[76:79], off
	v_cvt_pk_bf16_f32 v80, v76, v77
	v_cvt_pk_bf16_f32 v81, v78, v79
	v_pk_mul_f32 v[76:77], v[76:77], v[76:77]
	v_pk_mul_f32 v[78:79], v[78:79], v[78:79]
	v_add_f32_e32 v76, v76, v77
	v_add_f32_e32 v76, v76, v78
	v_add_f32_e32 v76, v76, v79
	flat_store_dwordx2 v[84:85], v[80:81]
	s_nop 0
	v_add_f32_dpp v76, v76, v76 row_ror:8 row_mask:0xf bank_mask:0xf bound_ctrl:1
	s_nop 1
	v_add_f32_dpp v76, v76, v76 row_ror:4 row_mask:0xf bank_mask:0xf bound_ctrl:1
	s_nop 1
	v_add_f32_dpp v76, v76, v76 row_ror:2 row_mask:0xf bank_mask:0xf bound_ctrl:1
	s_nop 1
	v_add_f32_dpp v76, v76, v76 row_ror:1 row_mask:0xf bank_mask:0xf bound_ctrl:1
	s_nop 0
	v_readlane_b32 s19, v76, 0
	v_readlane_b32 s66, v76, 16
	v_readlane_b32 s64, v76, 32
	v_readlane_b32 s65, v76, 48
	s_and_saveexec_b64 s[62:63], s[0:1]
	s_cbranch_execz .LBB0_219
	s_lshl_b64 s[34:35], s[34:35], 2
	v_mov_b32_e32 v76, s66
	s_add_u32 s34, s16, s34
	v_add_f32_e32 v76, s19, v76
	s_addc_u32 s35, s17, s35
	v_add_f32_e32 v76, s64, v76
	v_add_f32_e32 v78, s65, v76
	v_mov_b64_e32 v[76:77], s[34:35]
	flat_atomic_add_f32 v[76:77], v78
.LBB0_219:
	s_or_b64 exec, exec, s[62:63]
	ds_read_b128 v[76:79], v130 offset:5200
	v_lshl_add_u64 v[80:81], v[106:107], 1, s[8:9]
	s_waitcnt lgkmcnt(0)
	v_pk_fma_f32 v[72:73], s[12:13], v[76:77], v[72:73]
	v_pk_fma_f32 v[74:75], s[12:13], v[78:79], v[74:75]
	global_store_dwordx4 v[104:105], v[72:75], off
	v_cvt_pk_bf16_f32 v76, v72, v73
	v_cvt_pk_bf16_f32 v77, v74, v75
	v_pk_mul_f32 v[72:73], v[72:73], v[72:73]
	v_pk_mul_f32 v[74:75], v[74:75], v[74:75]
	v_add_f32_e32 v72, v72, v73
	v_add_f32_e32 v72, v72, v74
	v_add_f32_e32 v72, v72, v75
	flat_store_dwordx2 v[80:81], v[76:77]
	s_nop 0
	v_add_f32_dpp v72, v72, v72 row_ror:8 row_mask:0xf bank_mask:0xf bound_ctrl:1
	s_nop 1
	v_add_f32_dpp v72, v72, v72 row_ror:4 row_mask:0xf bank_mask:0xf bound_ctrl:1
	s_nop 1
	v_add_f32_dpp v72, v72, v72 row_ror:2 row_mask:0xf bank_mask:0xf bound_ctrl:1
	s_nop 1
	v_add_f32_dpp v72, v72, v72 row_ror:1 row_mask:0xf bank_mask:0xf bound_ctrl:1
	s_nop 0
	v_readlane_b32 s19, v72, 0
	v_readlane_b32 s64, v72, 16
	v_readlane_b32 s62, v72, 32
	v_readlane_b32 s63, v72, 48
	s_and_saveexec_b64 s[34:35], s[0:1]
	s_cbranch_execz .LBB0_221
	s_lshl_b64 s[30:31], s[30:31], 2
	v_mov_b32_e32 v72, s64
	s_add_u32 s30, s16, s30
	v_add_f32_e32 v72, s19, v72
	s_addc_u32 s31, s17, s31
	v_add_f32_e32 v72, s62, v72
	v_add_f32_e32 v74, s63, v72
	v_mov_b64_e32 v[72:73], s[30:31]
	flat_atomic_add_f32 v[72:73], v74
.LBB0_221:
	s_or_b64 exec, exec, s[34:35]
	ds_read_b128 v[72:75], v130 offset:6240
	v_lshl_add_u64 v[76:77], v[102:103], 1, s[8:9]
	s_waitcnt lgkmcnt(0)
	v_pk_fma_f32 v[68:69], s[12:13], v[72:73], v[68:69]
	v_pk_fma_f32 v[70:71], s[12:13], v[74:75], v[70:71]
	global_store_dwordx4 v[100:101], v[68:71], off
	v_cvt_pk_bf16_f32 v72, v68, v69
	v_cvt_pk_bf16_f32 v73, v70, v71
	v_pk_mul_f32 v[68:69], v[68:69], v[68:69]
	v_pk_mul_f32 v[70:71], v[70:71], v[70:71]
	v_add_f32_e32 v68, v68, v69
	v_add_f32_e32 v68, v68, v70
	v_add_f32_e32 v68, v68, v71
	flat_store_dwordx2 v[76:77], v[72:73]
	s_nop 0
	v_add_f32_dpp v68, v68, v68 row_ror:8 row_mask:0xf bank_mask:0xf bound_ctrl:1
	s_nop 1
	v_add_f32_dpp v68, v68, v68 row_ror:4 row_mask:0xf bank_mask:0xf bound_ctrl:1
	s_nop 1
	v_add_f32_dpp v68, v68, v68 row_ror:2 row_mask:0xf bank_mask:0xf bound_ctrl:1
	s_nop 1
	v_add_f32_dpp v68, v68, v68 row_ror:1 row_mask:0xf bank_mask:0xf bound_ctrl:1
	s_nop 0
	v_readlane_b32 s19, v68, 0
	v_readlane_b32 s62, v68, 16
	v_readlane_b32 s34, v68, 32
	v_readlane_b32 s35, v68, 48
	s_and_saveexec_b64 s[30:31], s[0:1]
	s_cbranch_execz .LBB0_223
	s_lshl_b64 s[22:23], s[22:23], 2
	v_mov_b32_e32 v68, s62
	s_add_u32 s22, s16, s22
	v_add_f32_e32 v68, s19, v68
	s_addc_u32 s23, s17, s23
	v_add_f32_e32 v68, s34, v68
	v_add_f32_e32 v70, s35, v68
	v_mov_b64_e32 v[68:69], s[22:23]
	flat_atomic_add_f32 v[68:69], v70
.LBB0_223:
	s_or_b64 exec, exec, s[30:31]
	ds_read_b128 v[68:71], v130 offset:7280
	v_lshl_add_u64 v[72:73], v[98:99], 1, s[8:9]
	s_waitcnt lgkmcnt(0)
	v_pk_fma_f32 v[64:65], s[12:13], v[68:69], v[64:65]
	v_pk_fma_f32 v[66:67], s[12:13], v[70:71], v[66:67]
	global_store_dwordx4 v[96:97], v[64:67], off
	v_cvt_pk_bf16_f32 v68, v64, v65
	v_cvt_pk_bf16_f32 v69, v66, v67
	v_pk_mul_f32 v[64:65], v[64:65], v[64:65]
	v_pk_mul_f32 v[66:67], v[66:67], v[66:67]
	v_add_f32_e32 v64, v64, v65
	v_add_f32_e32 v64, v64, v66
	v_add_f32_e32 v64, v64, v67
	flat_store_dwordx2 v[72:73], v[68:69]
	s_nop 0
	v_add_f32_dpp v64, v64, v64 row_ror:8 row_mask:0xf bank_mask:0xf bound_ctrl:1
	s_nop 1
	v_add_f32_dpp v64, v64, v64 row_ror:4 row_mask:0xf bank_mask:0xf bound_ctrl:1
	s_nop 1
	v_add_f32_dpp v64, v64, v64 row_ror:2 row_mask:0xf bank_mask:0xf bound_ctrl:1
	s_nop 1
	v_add_f32_dpp v64, v64, v64 row_ror:1 row_mask:0xf bank_mask:0xf bound_ctrl:1
	s_nop 0
	v_readlane_b32 s19, v64, 0
	v_readlane_b32 s34, v64, 16
	v_readlane_b32 s30, v64, 32
	v_readlane_b32 s31, v64, 48
	s_and_saveexec_b64 s[22:23], s[0:1]
	s_cbranch_execz .LBB0_225
	s_lshl_b64 s[20:21], s[20:21], 2
	v_mov_b32_e32 v64, s34
	s_add_u32 s20, s16, s20
	v_add_f32_e32 v64, s19, v64
	s_addc_u32 s21, s17, s21
	v_add_f32_e32 v64, s30, v64
	v_add_f32_e32 v66, s31, v64
	v_mov_b64_e32 v[64:65], s[20:21]
	flat_atomic_add_f32 v[64:65], v66

; template <int EPI, int TS, bool VT>
; DEVI void gemm_epilogue(const Params& p, char* smem, f32x4 (&acc)[2][2][4][2], int m0, int n0, float scale, const float* ssin,
;                         float* ssout, u16* xbout, int wid, int lane, int wr, int wc, int fr, int fq) {
;     ...
;           for (int u = 0; u < 8; ++u) {
;             const size_t ro = (size_t)(g0 + i0 + u) * 1024 + n0 + 4 * lane;
;             const int gr = g0 + i0 + u;
;             const float* xs = p.x + ro;
;             if (scale < 0.f)
;               xs = (gr < MP ? p.x_prompt + ro : p.x_sample + (ro - (size_t)MP * 1024));
;             { const f32x4 t_ = __builtin_nontemporal_load((const f32x4*)xs); xo[u] = make_float4(t_[0], t_[1], t_[2], t_[3]); }
.LBB0_230:
	global_load_dwordx4 v[92:95], v[64:65], off
	s_or_b32 s66, s18, 9
	s_ashr_i32 s67, s66, 31
	s_lshl_b64 s[20:21], s[66:67], 10
	v_lshl_add_u64 v[124:125], s[20:21], 0, v[128:129]
	v_lshl_add_u64 v[122:123], v[124:125], 2, s[38:39]
	s_and_b64 vcc, exec, s[4:5]
	v_mov_b64_e32 v[64:65], v[122:123]
	s_cbranch_vccnz .LBB0_235
	s_cmp_lt_i32 s18, 0xfff7
	s_mov_b64 s[20:21], -1
	s_cbranch_scc1 .LBB0_233
	v_readlane_b32 s20, v254, 4
	v_readlane_b32 s21, v254, 5
	v_readlane_b32 s22, v254, 6
	v_readlane_b32 s23, v254, 7
	s_brev_b32 s20, 15
	s_mov_b32 s21, -1
	v_lshl_add_u64 v[64:65], v[124:125], 2, s[22:23]
	v_lshl_add_u64 v[64:65], v[64:65], 0, s[20:21]
	s_mov_b64 s[20:21], 0

; template <int EPI, int TS, bool VT>
; DEVI void gemm_epilogue(const Params& p, char* smem, f32x4 (&acc)[2][2][4][2], int m0, int n0, float scale, const float* ssin,
;                         float* ssout, u16* xbout, int wid, int lane, int wr, int wc, int fr, int fq) {
;     ...
;           for (int u = 0; u < 8; ++u) {
;             const size_t ro = (size_t)(g0 + i0 + u) * 1024 + n0 + 4 * lane;
;             const int gr = g0 + i0 + u;
;             const float* xs = p.x + ro;
;             if (scale < 0.f)
;               xs = (gr < MP ? p.x_prompt + ro : p.x_sample + (ro - (size_t)MP * 1024));
;             { const f32x4 t_ = __builtin_nontemporal_load((const f32x4*)xs); xo[u] = make_float4(t_[0], t_[1], t_[2], t_[3]); }
.LBB0_235:
	global_load_dwordx4 v[88:91], v[64:65], off
	s_or_b32 s64, s18, 10
	s_ashr_i32 s65, s64, 31
	s_lshl_b64 s[20:21], s[64:65], 10
	v_lshl_add_u64 v[118:119], s[20:21], 0, v[128:129]
	v_lshl_add_u64 v[116:117], v[118:119], 2, s[38:39]
	s_and_b64 vcc, exec, s[4:5]
	v_mov_b64_e32 v[64:65], v[116:117]
	s_cbranch_vccnz .LBB0_240
	s_cmp_lt_i32 s18, 0xfff6
	s_mov_b64 s[20:21], -1
	s_cbranch_scc1 .LBB0_238
	v_readlane_b32 s20, v254, 4
	v_readlane_b32 s21, v254, 5
	v_readlane_b32 s22, v254, 6
	v_readlane_b32 s23, v254, 7
	s_brev_b32 s20, 15
	s_mov_b32 s21, -1
	v_lshl_add_u64 v[64:65], v[118:119], 2, s[22:23]
	v_lshl_add_u64 v[64:65], v[64:65], 0, s[20:21]
	s_mov_b64 s[20:21], 0

; template <int EPI, int TS, bool VT>
; DEVI void gemm_epilogue(const Params& p, char* smem, f32x4 (&acc)[2][2][4][2], int m0, int n0, float scale, const float* ssin,
;                         float* ssout, u16* xbout, int wid, int lane, int wr, int wc, int fr, int fq) {
;     ...
;           for (int u = 0; u < 8; ++u) {
;             const size_t ro = (size_t)(g0 + i0 + u) * 1024 + n0 + 4 * lane;
;             const int gr = g0 + i0 + u;
;             const float* xs = p.x + ro;
;             if (scale < 0.f)
;               xs = (gr < MP ? p.x_prompt + ro : p.x_sample + (ro - (size_t)MP * 1024));
;             { const f32x4 t_ = __builtin_nontemporal_load((const f32x4*)xs); xo[u] = make_float4(t_[0], t_[1], t_[2], t_[3]); }
.LBB0_240:
	global_load_dwordx4 v[84:87], v[64:65], off
	s_or_b32 s62, s18, 11
	s_ashr_i32 s63, s62, 31
	s_lshl_b64 s[20:21], s[62:63], 10
	v_lshl_add_u64 v[114:115], s[20:21], 0, v[128:129]
	v_lshl_add_u64 v[112:113], v[114:115], 2, s[38:39]
	s_and_b64 vcc, exec, s[4:5]
	v_mov_b64_e32 v[64:65], v[112:113]
	s_cbranch_vccnz .LBB0_245
	s_cmp_lt_i32 s18, 0xfff5
	s_mov_b64 s[20:21], -1
	s_cbranch_scc1 .LBB0_243
	v_readlane_b32 s20, v254, 4
	v_readlane_b32 s21, v254, 5
	v_readlane_b32 s22, v254, 6
	v_readlane_b32 s23, v254, 7
	s_brev_b32 s20, 15
	s_mov_b32 s21, -1
	v_lshl_add_u64 v[64:65], v[114:115], 2, s[22:23]
	v_lshl_add_u64 v[64:65], v[64:65], 0, s[20:21]
	s_mov_b64 s[20:21], 0

; template <int EPI, int TS, bool VT>
; DEVI void gemm_epilogue(const Params& p, char* smem, f32x4 (&acc)[2][2][4][2], int m0, int n0, float scale, const float* ssin,
;                         float* ssout, u16* xbout, int wid, int lane, int wr, int wc, int fr, int fq) {
;     ...
;           for (int u = 0; u < 8; ++u) {
;             const size_t ro = (size_t)(g0 + i0 + u) * 1024 + n0 + 4 * lane;
;             const int gr = g0 + i0 + u;
;             const float* xs = p.x + ro;
;             if (scale < 0.f)
;               xs = (gr < MP ? p.x_prompt + ro : p.x_sample + (ro - (size_t)MP * 1024));
;             { const f32x4 t_ = __builtin_nontemporal_load((const f32x4*)xs); xo[u] = make_float4(t_[0], t_[1], t_[2], t_[3]); }
.LBB0_245:
	global_load_dwordx4 v[80:83], v[64:65], off
	s_or_b32 s34, s18, 12
	s_ashr_i32 s35, s34, 31
	s_lshl_b64 s[20:21], s[34:35], 10
	v_lshl_add_u64 v[110:111], s[20:21], 0, v[128:129]
	v_lshl_add_u64 v[108:109], v[110:111], 2, s[38:39]
	s_and_b64 vcc, exec, s[4:5]
	v_mov_b64_e32 v[64:65], v[108:109]
	s_cbranch_vccnz .LBB0_250
	s_cmp_lt_i32 s18, 0xfff4
	s_mov_b64 s[20:21], -1
	s_cbranch_scc1 .LBB0_248
	v_readlane_b32 s20, v254, 4
	v_readlane_b32 s21, v254, 5
	v_readlane_b32 s22, v254, 6
	v_readlane_b32 s23, v254, 7
	s_brev_b32 s20, 15
	s_mov_b32 s21, -1
	v_lshl_add_u64 v[64:65], v[110:111], 2, s[22:23]
	v_lshl_add_u64 v[64:65], v[64:65], 0, s[20:21]
	s_mov_b64 s[20:21], 0

; template <int EPI, int TS, bool VT>
; DEVI void gemm_epilogue(const Params& p, char* smem, f32x4 (&acc)[2][2][4][2], int m0, int n0, float scale, const float* ssin,
;                         float* ssout, u16* xbout, int wid, int lane, int wr, int wc, int fr, int fq) {
;     ...
;           for (int u = 0; u < 8; ++u) {
;             const size_t ro = (size_t)(g0 + i0 + u) * 1024 + n0 + 4 * lane;
;             const int gr = g0 + i0 + u;
;             const float* xs = p.x + ro;
;             if (scale < 0.f)
;               xs = (gr < MP ? p.x_prompt + ro : p.x_sample + (ro - (size_t)MP * 1024));
;             { const f32x4 t_ = __builtin_nontemporal_load((const f32x4*)xs); xo[u] = make_float4(t_[0], t_[1], t_[2], t_[3]); }
.LBB0_250:
	global_load_dwordx4 v[76:79], v[64:65], off
	s_or_b32 s30, s18, 13
	s_ashr_i32 s31, s30, 31
	s_lshl_b64 s[20:21], s[30:31], 10
	v_lshl_add_u64 v[106:107], s[20:21], 0, v[128:129]
	v_lshl_add_u64 v[104:105], v[106:107], 2, s[38:39]
	s_and_b64 vcc, exec, s[4:5]
	v_mov_b64_e32 v[64:65], v[104:105]
	s_cbranch_vccnz .LBB0_255
	s_cmp_lt_i32 s18, 0xfff3
	s_mov_b64 s[20:21], -1
	s_cbranch_scc1 .LBB0_253
	v_readlane_b32 s20, v254, 4
	v_readlane_b32 s21, v254, 5
	v_readlane_b32 s22, v254, 6
	v_readlane_b32 s23, v254, 7
	s_brev_b32 s20, 15
	s_mov_b32 s21, -1
	v_lshl_add_u64 v[64:65], v[106:107], 2, s[22:23]
	v_lshl_add_u64 v[64:65], v[64:65], 0, s[20:21]
	s_mov_b64 s[20:21], 0

; template <int EPI, int TS, bool VT>
; DEVI void gemm_epilogue(const Params& p, char* smem, f32x4 (&acc)[2][2][4][2], int m0, int n0, float scale, const float* ssin,
;                         float* ssout, u16* xbout, int wid, int lane, int wr, int wc, int fr, int fq) {
;     ...
;           for (int u = 0; u < 8; ++u) {
;             const size_t ro = (size_t)(g0 + i0 + u) * 1024 + n0 + 4 * lane;
;             const int gr = g0 + i0 + u;
;             const float* xs = p.x + ro;
;             if (scale < 0.f)
;               xs = (gr < MP ? p.x_prompt + ro : p.x_sample + (ro - (size_t)MP * 1024));
;             { const f32x4 t_ = __builtin_nontemporal_load((const f32x4*)xs); xo[u] = make_float4(t_[0], t_[1], t_[2], t_[3]); }
.LBB0_255:
	global_load_dwordx4 v[72:75], v[64:65], off
	s_or_b32 s22, s18, 14
	s_ashr_i32 s23, s22, 31
	s_lshl_b64 s[20:21], s[22:23], 10
	v_lshl_add_u64 v[102:103], s[20:21], 0, v[128:129]
	v_lshl_add_u64 v[100:101], v[102:103], 2, s[38:39]
	s_and_b64 vcc, exec, s[4:5]
	v_mov_b64_e32 v[64:65], v[100:101]
	s_cbranch_vccnz .LBB0_260
	s_cmp_lt_i32 s18, 0xfff2
	s_mov_b64 s[20:21], -1
	s_cbranch_scc1 .LBB0_258
	v_readlane_b32 s76, v254, 4
	v_readlane_b32 s78, v254, 6
	v_readlane_b32 s79, v254, 7
	s_brev_b32 s20, 15
	s_mov_b32 s21, -1
	v_lshl_add_u64 v[64:65], v[102:103], 2, s[78:79]
	v_lshl_add_u64 v[64:65], v[64:65], 0, s[20:21]
	s_mov_b64 s[20:21], 0
	v_readlane_b32 s77, v254, 5

; template <int EPI, int TS, bool VT>
; DEVI void gemm_epilogue(const Params& p, char* smem, f32x4 (&acc)[2][2][4][2], int m0, int n0, float scale, const float* ssin,
;                         float* ssout, u16* xbout, int wid, int lane, int wr, int wc, int fr, int fq) {
;     ...
;           for (int u = 0; u < 8; ++u) {
;             const size_t ro = (size_t)(g0 + i0 + u) * 1024 + n0 + 4 * lane;
;             const int gr = g0 + i0 + u;
;             const float* xs = p.x + ro;
;             if (scale < 0.f)
;               xs = (gr < MP ? p.x_prompt + ro : p.x_sample + (ro - (size_t)MP * 1024));
;             { const f32x4 t_ = __builtin_nontemporal_load((const f32x4*)xs); xo[u] = make_float4(t_[0], t_[1], t_[2], t_[3]); }
.LBB0_260:
	global_load_dwordx4 v[68:71], v[64:65], off
	s_or_b32 s20, s18, 15
	s_ashr_i32 s21, s20, 31
	s_lshl_b64 s[70:71], s[20:21], 10
	v_lshl_add_u64 v[98:99], s[70:71], 0, v[128:129]
	v_lshl_add_u64 v[96:97], v[98:99], 2, s[38:39]
	s_and_b64 vcc, exec, s[4:5]
	v_mov_b64_e32 v[64:65], v[96:97]
	s_cbranch_vccnz .LBB0_265
	s_cmp_lt_i32 s18, 0xfff1
	s_mov_b64 s[70:71], -1
	s_cbranch_scc1 .LBB0_263
	v_readlane_b32 s76, v254, 4
	v_readlane_b32 s78, v254, 6
	v_readlane_b32 s79, v254, 7
	s_brev_b32 s70, 15
	s_mov_b32 s71, -1
	v_lshl_add_u64 v[64:65], v[98:99], 2, s[78:79]
	v_lshl_add_u64 v[64:65], v[64:65], 0, s[70:71]
	s_mov_b64 s[70:71], 0
	v_readlane_b32 s77, v254, 5

; DEVI float fsig(float x) { return __builtin_amdgcn_rcpf(1.f + __expf(-x)); }
; DEVI float bflo(unsigned u) { return __uint_as_float(u << 16); }
; DEVI float bfhi(unsigned u) { return __uint_as_float(u & 0xffff0000u); }
; template <int EPI, int TS, bool VT>
; DEVI void gemm_epilogue(const Params& p, char* smem, f32x4 (&acc)[2][2][4][2], int m0, int n0, float scale, const float* ssin,
;                         float* ssout, u16* xbout, int wid, int lane, int wr, int wc, int fr, int fq) {
;     ...
;         for (int u = 0; u < 8; ++u) {
;           const int i = i0 + u;
;           const int grow = g0 + i;
;           const float* Tr = T + (r0 + i) * TS;
;           const float rs = __int_as_float(__builtin_amdgcn_readlane(__float_as_int(rsv), i));
;           if constexpr (EPI == E_RESID || EPI == E_PLEGATE) {
;             const float4 a = *(const float4*)(Tr + 4 * lane);
;             const size_t ro = (size_t)grow * 1024 + n0 + 4 * lane;
;             float4 x4 = xo[u];
;             if constexpr (EPI == E_PLEGATE) {
;               x4.x += bflo(pv[u].x) * fsig(a.x * rs);
;               x4.y += bfhi(pv[u].x) * fsig(a.y * rs);
;               x4.z += bflo(pv[u].y) * fsig(a.z * rs);
;               x4.w += bfhi(pv[u].y) * fsig(a.w * rs);
;             } else {
;               const float sc = fabsf(scale);
;               x4.x += sc * a.x; x4.y += sc * a.y; x4.z += sc * a.z; x4.w += sc * a.w;
;             }
;             st_nt16(p.x + ro, x4);
;             if (xbout) {
;               uint2 o;
;               o.x = pack2(x4.x, x4.y);
;               o.y = pack2(x4.z, x4.w);
;               st_nt8(xbout + ro, o);
;             }
;             if (ssout) {
;               const float ssq = wsum(x4.x * x4.x + x4.y * x4.y + x4.z * x4.z + x4.w * x4.w, lane);
;               if (lane == 0) atomicAdd(ssout + grow, ssq);
;             }
.LBB0_265:
	global_load_dwordx4 v[64:67], v[64:65], off
	ds_read_b128 v[152:155], v130 offset:8320
	v_lshl_add_u64 v[120:121], v[120:121], 1, s[8:9]
	s_waitcnt vmcnt(0) lgkmcnt(0)
	v_pk_fma_f32 v[92:93], s[12:13], v[152:153], v[92:93]
	v_pk_fma_f32 v[94:95], s[12:13], v[154:155], v[94:95]
	global_store_dwordx4 v[126:127], v[92:95], off
	v_cvt_pk_bf16_f32 v126, v92, v93
	v_cvt_pk_bf16_f32 v127, v94, v95
	v_pk_mul_f32 v[92:93], v[92:93], v[92:93]
	v_pk_mul_f32 v[94:95], v[94:95], v[94:95]
	v_add_f32_e32 v92, v92, v93
	v_add_f32_e32 v92, v92, v94
	v_add_f32_e32 v92, v92, v95
	flat_store_dwordx2 v[120:121], v[126:127]
	s_nop 0
	v_add_f32_dpp v92, v92, v92 row_ror:8 row_mask:0xf bank_mask:0xf bound_ctrl:1
	s_nop 1
	v_add_f32_dpp v92, v92, v92 row_ror:4 row_mask:0xf bank_mask:0xf bound_ctrl:1
	s_nop 1
	v_add_f32_dpp v92, v92, v92 row_ror:2 row_mask:0xf bank_mask:0xf bound_ctrl:1
	s_nop 1
	v_add_f32_dpp v92, v92, v92 row_ror:1 row_mask:0xf bank_mask:0xf bound_ctrl:1
	s_nop 0
	v_readlane_b32 s19, v92, 0
	v_readlane_b32 s77, v92, 16
	v_readlane_b32 s75, v92, 32
	v_readlane_b32 s76, v92, 48
	s_and_saveexec_b64 s[70:71], s[0:1]
	s_cbranch_execz .LBB0_267
	s_lshl_b64 s[68:69], s[68:69], 2
	v_mov_b32_e32 v92, s77
	s_add_u32 s68, s16, s68
	v_add_f32_e32 v92, s19, v92
	s_addc_u32 s69, s17, s69
	v_add_f32_e32 v92, s75, v92
	v_add_f32_e32 v94, s76, v92
	v_mov_b64_e32 v[92:93], s[68:69]
	flat_atomic_add_f32 v[92:93], v94
.LBB0_267:
	s_or_b64 exec, exec, s[70:71]
	ds_read_b128 v[92:95], v130 offset:9360
	v_lshl_add_u64 v[120:121], v[124:125], 1, s[8:9]
	s_waitcnt lgkmcnt(0)
	v_pk_fma_f32 v[88:89], s[12:13], v[92:93], v[88:89]
	v_pk_fma_f32 v[90:91], s[12:13], v[94:95], v[90:91]
	global_store_dwordx4 v[122:123], v[88:91], off
	v_cvt_pk_bf16_f32 v92, v88, v89
	v_cvt_pk_bf16_f32 v93, v90, v91
	v_pk_mul_f32 v[88:89], v[88:89], v[88:89]
	v_pk_mul_f32 v[90:91], v[90:91], v[90:91]
	v_add_f32_e32 v88, v88, v89
	v_add_f32_e32 v88, v88, v90
	v_add_f32_e32 v88, v88, v91
	flat_store_dwordx2 v[120:121], v[92:93]
	s_nop 0
	v_add_f32_dpp v88, v88, v88 row_ror:8 row_mask:0xf bank_mask:0xf bound_ctrl:1
	s_nop 1
	v_add_f32_dpp v88, v88, v88 row_ror:4 row_mask:0xf bank_mask:0xf bound_ctrl:1
	s_nop 1
	v_add_f32_dpp v88, v88, v88 row_ror:2 row_mask:0xf bank_mask:0xf bound_ctrl:1
	s_nop 1
	v_add_f32_dpp v88, v88, v88 row_ror:1 row_mask:0xf bank_mask:0xf bound_ctrl:1
	s_nop 0
	v_readlane_b32 s19, v88, 0
	v_readlane_b32 s75, v88, 16
	v_readlane_b32 s70, v88, 32
	v_readlane_b32 s71, v88, 48
	s_and_saveexec_b64 s[68:69], s[0:1]
	s_cbranch_execz .LBB0_269
	s_lshl_b64 s[66:67], s[66:67], 2
	v_mov_b32_e32 v88, s75
	s_add_u32 s66, s16, s66
	v_add_f32_e32 v88, s19, v88
	s_addc_u32 s67, s17, s67
	v_add_f32_e32 v88, s70, v88
	v_add_f32_e32 v90, s71, v88
	v_mov_b64_e32 v[88:89], s[66:67]
	flat_atomic_add_f32 v[88:89], v90
.LBB0_269:
	s_or_b64 exec, exec, s[68:69]
	ds_read_b128 v[88:91], v130 offset:10400
	v_lshl_add_u64 v[92:93], v[118:119], 1, s[8:9]
	s_waitcnt lgkmcnt(0)
	v_pk_fma_f32 v[84:85], s[12:13], v[88:89], v[84:85]
	v_pk_fma_f32 v[86:87], s[12:13], v[90:91], v[86:87]
	global_store_dwordx4 v[116:117], v[84:87], off
	v_cvt_pk_bf16_f32 v88, v84, v85
	v_cvt_pk_bf16_f32 v89, v86, v87
	v_pk_mul_f32 v[84:85], v[84:85], v[84:85]
	v_pk_mul_f32 v[86:87], v[86:87], v[86:87]
	v_add_f32_e32 v84, v84, v85
	v_add_f32_e32 v84, v84, v86
	v_add_f32_e32 v84, v84, v87
	flat_store_dwordx2 v[92:93], v[88:89]
	s_nop 0
	v_add_f32_dpp v84, v84, v84 row_ror:8 row_mask:0xf bank_mask:0xf bound_ctrl:1
	s_nop 1
	v_add_f32_dpp v84, v84, v84 row_ror:4 row_mask:0xf bank_mask:0xf bound_ctrl:1
	s_nop 1
	v_add_f32_dpp v84, v84, v84 row_ror:2 row_mask:0xf bank_mask:0xf bound_ctrl:1
	s_nop 1
	v_add_f32_dpp v84, v84, v84 row_ror:1 row_mask:0xf bank_mask:0xf bound_ctrl:1
	s_nop 0
	v_readlane_b32 s19, v84, 0
	v_readlane_b32 s70, v84, 16
	v_readlane_b32 s68, v84, 32
	v_readlane_b32 s69, v84, 48
	s_and_saveexec_b64 s[66:67], s[0:1]
	s_cbranch_execz .LBB0_271
	s_lshl_b64 s[64:65], s[64:65], 2
	v_mov_b32_e32 v84, s70
	s_add_u32 s64, s16, s64
	v_add_f32_e32 v84, s19, v84
	s_addc_u32 s65, s17, s65
	v_add_f32_e32 v84, s68, v84
	v_add_f32_e32 v86, s69, v84
	v_mov_b64_e32 v[84:85], s[64:65]
	flat_atomic_add_f32 v[84:85], v86
.LBB0_271:
	s_or_b64 exec, exec, s[66:67]
	ds_read_b128 v[84:87], v130 offset:11440
	v_lshl_add_u64 v[88:89], v[114:115], 1, s[8:9]
	s_waitcnt lgkmcnt(0)
	v_pk_fma_f32 v[80:81], s[12:13], v[84:85], v[80:81]
	v_pk_fma_f32 v[82:83], s[12:13], v[86:87], v[82:83]
	global_store_dwordx4 v[112:113], v[80:83], off
	v_cvt_pk_bf16_f32 v84, v80, v81
	v_cvt_pk_bf16_f32 v85, v82, v83
	v_pk_mul_f32 v[80:81], v[80:81], v[80:81]
	v_pk_mul_f32 v[82:83], v[82:83], v[82:83]
	v_add_f32_e32 v80, v80, v81
	v_add_f32_e32 v80, v80, v82
	v_add_f32_e32 v80, v80, v83
	flat_store_dwordx2 v[88:89], v[84:85]
	s_nop 0
	v_add_f32_dpp v80, v80, v80 row_ror:8 row_mask:0xf bank_mask:0xf bound_ctrl:1
	s_nop 1
	v_add_f32_dpp v80, v80, v80 row_ror:4 row_mask:0xf bank_mask:0xf bound_ctrl:1
	s_nop 1
	v_add_f32_dpp v80, v80, v80 row_ror:2 row_mask:0xf bank_mask:0xf bound_ctrl:1
	s_nop 1
	v_add_f32_dpp v80, v80, v80 row_ror:1 row_mask:0xf bank_mask:0xf bound_ctrl:1
	s_nop 0
	v_readlane_b32 s19, v80, 0
	v_readlane_b32 s68, v80, 16
	v_readlane_b32 s66, v80, 32
	v_readlane_b32 s67, v80, 48
	s_and_saveexec_b64 s[64:65], s[0:1]
	s_cbranch_execz .LBB0_273
	s_lshl_b64 s[62:63], s[62:63], 2
	v_mov_b32_e32 v80, s68
	s_add_u32 s62, s16, s62
	v_add_f32_e32 v80, s19, v80
	s_addc_u32 s63, s17, s63
	v_add_f32_e32 v80, s66, v80
	v_add_f32_e32 v82, s67, v80
	v_mov_b64_e32 v[80:81], s[62:63]
	flat_atomic_add_f32 v[80:81], v82
; DEVI float fsig(float x) { return __builtin_amdgcn_rcpf(1.f + __expf(-x)); }
; DEVI float bflo(unsigned u) { return __uint_as_float(u << 16); }
; DEVI float bfhi(unsigned u) { return __uint_as_float(u & 0xffff0000u); }
; template <int EPI, int TS, bool VT>
; DEVI void gemm_epilogue(const Params& p, char* smem, f32x4 (&acc)[2][2][4][2], int m0, int n0, float scale, const float* ssin,
;                         float* ssout, u16* xbout, int wid, int lane, int wr, int wc, int fr, int fq) {
;     ...
;         for (int u = 0; u < 8; ++u) {
;           const int i = i0 + u;
;           const int grow = g0 + i;
;           const float* Tr = T + (r0 + i) * TS;
;           const float rs = __int_as_float(__builtin_amdgcn_readlane(__float_as_int(rsv), i));
;           if constexpr (EPI == E_RESID || EPI == E_PLEGATE) {
;             const float4 a = *(const float4*)(Tr + 4 * lane);
;             const size_t ro = (size_t)grow * 1024 + n0 + 4 * lane;
;             float4 x4 = xo[u];
;             if constexpr (EPI == E_PLEGATE) {
;               x4.x += bflo(pv[u].x) * fsig(a.x * rs);
;               x4.y += bfhi(pv[u].x) * fsig(a.y * rs);
;               x4.z += bflo(pv[u].y) * fsig(a.z * rs);
;               x4.w += bfhi(pv[u].y) * fsig(a.w * rs);
;             } else {
;               const float sc = fabsf(scale);
;               x4.x += sc * a.x; x4.y += sc * a.y; x4.z += sc * a.z; x4.w += sc * a.w;
;             }
;             st_nt16(p.x + ro, x4);
;             if (xbout) {
;               uint2 o;
;               o.x = pack2(x4.x, x4.y);
;               o.y = pack2(x4.z, x4.w);
;               st_nt8(xbout + ro, o);
;             }
;             if (ssout) {
;               const float ssq = wsum(x4.x * x4.x + x4.y * x4.y + x4.z * x4.z + x4.w * x4.w, lane);
;               if (lane == 0) atomicAdd(ssout + grow, ssq);
;             }
.LBB0_273:
	s_or_b64 exec, exec, s[64:65]
	ds_read_b128 v[80:83], v130 offset:12480
	v_lshl_add_u64 v[84:85], v[110:111], 1, s[8:9]
	s_waitcnt lgkmcnt(0)
	v_pk_fma_f32 v[76:77], s[12:13], v[80:81], v[76:77]
	v_pk_fma_f32 v[78:79], s[12:13], v[82:83], v[78:79]
	global_store_dwordx4 v[108:109], v[76:79], off
	v_cvt_pk_bf16_f32 v80, v76, v77
	v_cvt_pk_bf16_f32 v81, v78, v79
	v_pk_mul_f32 v[76:77], v[76:77], v[76:77]
	v_pk_mul_f32 v[78:79], v[78:79], v[78:79]
	v_add_f32_e32 v76, v76, v77
	v_add_f32_e32 v76, v76, v78
	v_add_f32_e32 v76, v76, v79
	flat_store_dwordx2 v[84:85], v[80:81]
	s_nop 0
	v_add_f32_dpp v76, v76, v76 row_ror:8 row_mask:0xf bank_mask:0xf bound_ctrl:1
	s_nop 1
	v_add_f32_dpp v76, v76, v76 row_ror:4 row_mask:0xf bank_mask:0xf bound_ctrl:1
	s_nop 1
	v_add_f32_dpp v76, v76, v76 row_ror:2 row_mask:0xf bank_mask:0xf bound_ctrl:1
	s_nop 1
	v_add_f32_dpp v76, v76, v76 row_ror:1 row_mask:0xf bank_mask:0xf bound_ctrl:1
	s_nop 0
	v_readlane_b32 s19, v76, 0
	v_readlane_b32 s66, v76, 16
	v_readlane_b32 s64, v76, 32
	v_readlane_b32 s65, v76, 48
	s_and_saveexec_b64 s[62:63], s[0:1]
	s_cbranch_execz .LBB0_275
	s_lshl_b64 s[34:35], s[34:35], 2
	v_mov_b32_e32 v76, s66
	s_add_u32 s34, s16, s34
	v_add_f32_e32 v76, s19, v76
	s_addc_u32 s35, s17, s35
	v_add_f32_e32 v76, s64, v76
	v_add_f32_e32 v78, s65, v76
	v_mov_b64_e32 v[76:77], s[34:35]
	flat_atomic_add_f32 v[76:77], v78
.LBB0_275:
	s_or_b64 exec, exec, s[62:63]
	ds_read_b128 v[76:79], v130 offset:13520
	v_lshl_add_u64 v[80:81], v[106:107], 1, s[8:9]
	s_waitcnt lgkmcnt(0)
	v_pk_fma_f32 v[72:73], s[12:13], v[76:77], v[72:73]
	v_pk_fma_f32 v[74:75], s[12:13], v[78:79], v[74:75]
	global_store_dwordx4 v[104:105], v[72:75], off
	v_cvt_pk_bf16_f32 v76, v72, v73
	v_cvt_pk_bf16_f32 v77, v74, v75
	v_pk_mul_f32 v[72:73], v[72:73], v[72:73]
	v_pk_mul_f32 v[74:75], v[74:75], v[74:75]
	v_add_f32_e32 v72, v72, v73
	v_add_f32_e32 v72, v72, v74
	v_add_f32_e32 v72, v72, v75
	flat_store_dwordx2 v[80:81], v[76:77]
	s_nop 0
	v_add_f32_dpp v72, v72, v72 row_ror:8 row_mask:0xf bank_mask:0xf bound_ctrl:1
	s_nop 1
	v_add_f32_dpp v72, v72, v72 row_ror:4 row_mask:0xf bank_mask:0xf bound_ctrl:1
	s_nop 1
	v_add_f32_dpp v72, v72, v72 row_ror:2 row_mask:0xf bank_mask:0xf bound_ctrl:1
	s_nop 1
	v_add_f32_dpp v72, v72, v72 row_ror:1 row_mask:0xf bank_mask:0xf bound_ctrl:1
	s_nop 0
	v_readlane_b32 s19, v72, 0
	v_readlane_b32 s64, v72, 16
	v_readlane_b32 s62, v72, 32
	v_readlane_b32 s63, v72, 48
	s_and_saveexec_b64 s[34:35], s[0:1]
	s_cbranch_execz .LBB0_277
	s_lshl_b64 s[30:31], s[30:31], 2
	v_mov_b32_e32 v72, s64
	s_add_u32 s30, s16, s30
	v_add_f32_e32 v72, s19, v72
	s_addc_u32 s31, s17, s31
	v_add_f32_e32 v72, s62, v72
	v_add_f32_e32 v74, s63, v72
	v_mov_b64_e32 v[72:73], s[30:31]
	flat_atomic_add_f32 v[72:73], v74
.LBB0_277:
	s_or_b64 exec, exec, s[34:35]
	ds_read_b128 v[72:75], v130 offset:14560
	v_lshl_add_u64 v[76:77], v[102:103], 1, s[8:9]
	s_waitcnt lgkmcnt(0)
	v_pk_fma_f32 v[68:69], s[12:13], v[72:73], v[68:69]
	v_pk_fma_f32 v[70:71], s[12:13], v[74:75], v[70:71]
	global_store_dwordx4 v[100:101], v[68:71], off
	v_cvt_pk_bf16_f32 v72, v68, v69
	v_cvt_pk_bf16_f32 v73, v70, v71
	v_pk_mul_f32 v[68:69], v[68:69], v[68:69]
	v_pk_mul_f32 v[70:71], v[70:71], v[70:71]
	v_add_f32_e32 v68, v68, v69
	v_add_f32_e32 v68, v68, v70
	v_add_f32_e32 v68, v68, v71
	flat_store_dwordx2 v[76:77], v[72:73]
	s_nop 0
	v_add_f32_dpp v68, v68, v68 row_ror:8 row_mask:0xf bank_mask:0xf bound_ctrl:1
	s_nop 1
	v_add_f32_dpp v68, v68, v68 row_ror:4 row_mask:0xf bank_mask:0xf bound_ctrl:1
	s_nop 1
	v_add_f32_dpp v68, v68, v68 row_ror:2 row_mask:0xf bank_mask:0xf bound_ctrl:1
	s_nop 1
	v_add_f32_dpp v68, v68, v68 row_ror:1 row_mask:0xf bank_mask:0xf bound_ctrl:1
	s_nop 0
	v_readlane_b32 s19, v68, 0
	v_readlane_b32 s62, v68, 16
	v_readlane_b32 s34, v68, 32
	v_readlane_b32 s35, v68, 48
	s_and_saveexec_b64 s[30:31], s[0:1]
	s_cbranch_execz .LBB0_279
	s_lshl_b64 s[22:23], s[22:23], 2
	v_mov_b32_e32 v68, s62
	s_add_u32 s22, s16, s22
	v_add_f32_e32 v68, s19, v68
	s_addc_u32 s23, s17, s23
	v_add_f32_e32 v68, s34, v68
	v_add_f32_e32 v70, s35, v68
	v_mov_b64_e32 v[68:69], s[22:23]
	flat_atomic_add_f32 v[68:69], v70
.LBB0_279:
	s_or_b64 exec, exec, s[30:31]
	ds_read_b128 v[68:71], v130 offset:15600
	v_lshl_add_u64 v[72:73], v[98:99], 1, s[8:9]
	s_waitcnt lgkmcnt(0)
	v_pk_fma_f32 v[64:65], s[12:13], v[68:69], v[64:65]
	v_pk_fma_f32 v[66:67], s[12:13], v[70:71], v[66:67]
	global_store_dwordx4 v[96:97], v[64:67], off
	v_cvt_pk_bf16_f32 v68, v64, v65
	v_cvt_pk_bf16_f32 v69, v66, v67
	v_pk_mul_f32 v[64:65], v[64:65], v[64:65]
	v_pk_mul_f32 v[66:67], v[66:67], v[66:67]
	v_add_f32_e32 v64, v64, v65
	v_add_f32_e32 v64, v64, v66
	v_add_f32_e32 v64, v64, v67
	flat_store_dwordx2 v[72:73], v[68:69]
	s_nop 0
	v_add_f32_dpp v64, v64, v64 row_ror:8 row_mask:0xf bank_mask:0xf bound_ctrl:1
	s_nop 1
	v_add_f32_dpp v64, v64, v64 row_ror:4 row_mask:0xf bank_mask:0xf bound_ctrl:1
	s_nop 1
	v_add_f32_dpp v64, v64, v64 row_ror:2 row_mask:0xf bank_mask:0xf bound_ctrl:1
	s_nop 1
	v_add_f32_dpp v64, v64, v64 row_ror:1 row_mask:0xf bank_mask:0xf bound_ctrl:1
	s_nop 0
	v_readlane_b32 s19, v64, 0
	v_readlane_b32 s34, v64, 16
	v_readlane_b32 s30, v64, 32
	v_readlane_b32 s31, v64, 48
	s_and_saveexec_b64 s[22:23], s[0:1]
	s_cbranch_execz .LBB0_281
	s_lshl_b64 s[20:21], s[20:21], 2
	v_mov_b32_e32 v64, s34
	s_add_u32 s20, s16, s20
	v_add_f32_e32 v64, s19, v64
	s_addc_u32 s21, s17, s21
	v_add_f32_e32 v64, s30, v64
	v_add_f32_e32 v66, s31, v64
	v_mov_b64_e32 v[64:65], s[20:21]
	flat_atomic_add_f32 v[64:65], v66

; template <int EPI, int TS, bool VT>
; DEVI void gemm_epilogue(const Params& p, char* smem, f32x4 (&acc)[2][2][4][2], int m0, int n0, float scale, const float* ssin,
;                         float* ssout, u16* xbout, int wid, int lane, int wr, int wc, int fr, int fq) {
;     ...
;           for (int u = 0; u < 8; ++u) {
;             const size_t ro = (size_t)(g0 + i0 + u) * 1024 + n0 + 4 * lane;
;             const int gr = g0 + i0 + u;
;             const float* xs = p.x + ro;
;             if (scale < 0.f)
;               xs = (gr < MP ? p.x_prompt + ro : p.x_sample + (ro - (size_t)MP * 1024));
;             { const f32x4 t_ = __builtin_nontemporal_load((const f32x4*)xs); xo[u] = make_float4(t_[0], t_[1], t_[2], t_[3]); }
.LBB0_286:
	global_load_dwordx4 v[28:31], v[0:1], off
	s_add_i32 s66, s18, 0x81
	s_ashr_i32 s67, s66, 31
	s_lshl_b64 s[20:21], s[66:67], 10
	v_lshl_add_u64 v[60:61], s[20:21], 0, v[128:129]
	v_lshl_add_u64 v[58:59], v[60:61], 2, s[38:39]
	s_and_b64 vcc, exec, s[4:5]
	v_mov_b64_e32 v[0:1], v[58:59]
	s_cbranch_vccnz .LBB0_291
	s_cmp_lt_i32 s66, 0x10000
	s_mov_b64 s[20:21], -1
	s_cbranch_scc1 .LBB0_289
	v_readlane_b32 s20, v254, 4
	v_readlane_b32 s21, v254, 5
	v_readlane_b32 s22, v254, 6
	v_readlane_b32 s23, v254, 7
	s_brev_b32 s20, 15
	s_mov_b32 s21, -1
	v_lshl_add_u64 v[0:1], v[60:61], 2, s[22:23]
	v_lshl_add_u64 v[0:1], v[0:1], 0, s[20:21]
	s_mov_b64 s[20:21], 0

; template <int EPI, int TS, bool VT>
; DEVI void gemm_epilogue(const Params& p, char* smem, f32x4 (&acc)[2][2][4][2], int m0, int n0, float scale, const float* ssin,
;                         float* ssout, u16* xbout, int wid, int lane, int wr, int wc, int fr, int fq) {
;     ...
;           for (int u = 0; u < 8; ++u) {
;             const size_t ro = (size_t)(g0 + i0 + u) * 1024 + n0 + 4 * lane;
;             const int gr = g0 + i0 + u;
;             const float* xs = p.x + ro;
;             if (scale < 0.f)
;               xs = (gr < MP ? p.x_prompt + ro : p.x_sample + (ro - (size_t)MP * 1024));
;             { const f32x4 t_ = __builtin_nontemporal_load((const f32x4*)xs); xo[u] = make_float4(t_[0], t_[1], t_[2], t_[3]); }
.LBB0_291:
	global_load_dwordx4 v[24:27], v[0:1], off
	s_add_i32 s64, s18, 0x82
	s_ashr_i32 s65, s64, 31
	s_lshl_b64 s[20:21], s[64:65], 10
	v_lshl_add_u64 v[54:55], s[20:21], 0, v[128:129]
	v_lshl_add_u64 v[52:53], v[54:55], 2, s[38:39]
	s_and_b64 vcc, exec, s[4:5]
	v_mov_b64_e32 v[0:1], v[52:53]
	s_cbranch_vccnz .LBB0_296
	s_cmp_lt_i32 s64, 0x10000
	s_mov_b64 s[20:21], -1
	s_cbranch_scc1 .LBB0_294
	v_readlane_b32 s20, v254, 4
	v_readlane_b32 s21, v254, 5
	v_readlane_b32 s22, v254, 6
	v_readlane_b32 s23, v254, 7
	s_brev_b32 s20, 15
	s_mov_b32 s21, -1
	v_lshl_add_u64 v[0:1], v[54:55], 2, s[22:23]
	v_lshl_add_u64 v[0:1], v[0:1], 0, s[20:21]
	s_mov_b64 s[20:21], 0

; template <int EPI, int TS, bool VT>
; DEVI void gemm_epilogue(const Params& p, char* smem, f32x4 (&acc)[2][2][4][2], int m0, int n0, float scale, const float* ssin,
;                         float* ssout, u16* xbout, int wid, int lane, int wr, int wc, int fr, int fq) {
;     ...
;           for (int u = 0; u < 8; ++u) {
;             const size_t ro = (size_t)(g0 + i0 + u) * 1024 + n0 + 4 * lane;
;             const int gr = g0 + i0 + u;
;             const float* xs = p.x + ro;
;             if (scale < 0.f)
;               xs = (gr < MP ? p.x_prompt + ro : p.x_sample + (ro - (size_t)MP * 1024));
;             { const f32x4 t_ = __builtin_nontemporal_load((const f32x4*)xs); xo[u] = make_float4(t_[0], t_[1], t_[2], t_[3]); }
.LBB0_296:
	global_load_dwordx4 v[20:23], v[0:1], off
	s_add_i32 s62, s18, 0x83
	s_ashr_i32 s63, s62, 31
	s_lshl_b64 s[20:21], s[62:63], 10
	v_lshl_add_u64 v[50:51], s[20:21], 0, v[128:129]
	v_lshl_add_u64 v[48:49], v[50:51], 2, s[38:39]
	s_and_b64 vcc, exec, s[4:5]
	v_mov_b64_e32 v[0:1], v[48:49]
	s_cbranch_vccnz .LBB0_301
	s_cmp_lt_i32 s62, 0x10000
	s_mov_b64 s[20:21], -1
	s_cbranch_scc1 .LBB0_299
	v_readlane_b32 s20, v254, 4
	v_readlane_b32 s21, v254, 5
	v_readlane_b32 s22, v254, 6
	v_readlane_b32 s23, v254, 7
	s_brev_b32 s20, 15
	s_mov_b32 s21, -1
	v_lshl_add_u64 v[0:1], v[50:51], 2, s[22:23]
	v_lshl_add_u64 v[0:1], v[0:1], 0, s[20:21]
	s_mov_b64 s[20:21], 0

; template <int EPI, int TS, bool VT>
; DEVI void gemm_epilogue(const Params& p, char* smem, f32x4 (&acc)[2][2][4][2], int m0, int n0, float scale, const float* ssin,
;                         float* ssout, u16* xbout, int wid, int lane, int wr, int wc, int fr, int fq) {
;     ...
;           for (int u = 0; u < 8; ++u) {
;             const size_t ro = (size_t)(g0 + i0 + u) * 1024 + n0 + 4 * lane;
;             const int gr = g0 + i0 + u;
;             const float* xs = p.x + ro;
;             if (scale < 0.f)
;               xs = (gr < MP ? p.x_prompt + ro : p.x_sample + (ro - (size_t)MP * 1024));
;             { const f32x4 t_ = __builtin_nontemporal_load((const f32x4*)xs); xo[u] = make_float4(t_[0], t_[1], t_[2], t_[3]); }
.LBB0_301:
	global_load_dwordx4 v[16:19], v[0:1], off
	s_add_i32 s34, s18, 0x84
	s_ashr_i32 s35, s34, 31
	s_lshl_b64 s[20:21], s[34:35], 10
	v_lshl_add_u64 v[46:47], s[20:21], 0, v[128:129]
	v_lshl_add_u64 v[44:45], v[46:47], 2, s[38:39]
	s_and_b64 vcc, exec, s[4:5]
	v_mov_b64_e32 v[0:1], v[44:45]
	s_cbranch_vccnz .LBB0_306
	s_cmp_lt_i32 s34, 0x10000
	s_mov_b64 s[20:21], -1
	s_cbranch_scc1 .LBB0_304
	v_readlane_b32 s20, v254, 4
	v_readlane_b32 s21, v254, 5
	v_readlane_b32 s22, v254, 6
	v_readlane_b32 s23, v254, 7
	s_brev_b32 s20, 15
	s_mov_b32 s21, -1
	v_lshl_add_u64 v[0:1], v[46:47], 2, s[22:23]
	v_lshl_add_u64 v[0:1], v[0:1], 0, s[20:21]
	s_mov_b64 s[20:21], 0

; template <int EPI, int TS, bool VT>
; DEVI void gemm_epilogue(const Params& p, char* smem, f32x4 (&acc)[2][2][4][2], int m0, int n0, float scale, const float* ssin,
;                         float* ssout, u16* xbout, int wid, int lane, int wr, int wc, int fr, int fq) {
;     ...
;           for (int u = 0; u < 8; ++u) {
;             const size_t ro = (size_t)(g0 + i0 + u) * 1024 + n0 + 4 * lane;
;             const int gr = g0 + i0 + u;
;             const float* xs = p.x + ro;
;             if (scale < 0.f)
;               xs = (gr < MP ? p.x_prompt + ro : p.x_sample + (ro - (size_t)MP * 1024));
;             { const f32x4 t_ = __builtin_nontemporal_load((const f32x4*)xs); xo[u] = make_float4(t_[0], t_[1], t_[2], t_[3]); }
.LBB0_306:
	global_load_dwordx4 v[12:15], v[0:1], off
	s_add_i32 s30, s18, 0x85
	s_ashr_i32 s31, s30, 31
	s_lshl_b64 s[20:21], s[30:31], 10
	v_lshl_add_u64 v[42:43], s[20:21], 0, v[128:129]
	v_lshl_add_u64 v[40:41], v[42:43], 2, s[38:39]
	s_and_b64 vcc, exec, s[4:5]
	v_mov_b64_e32 v[0:1], v[40:41]
	s_cbranch_vccnz .LBB0_311
	s_cmp_lt_i32 s30, 0x10000
	s_mov_b64 s[20:21], -1
	s_cbranch_scc1 .LBB0_309
	v_readlane_b32 s20, v254, 4
	v_readlane_b32 s21, v254, 5
	v_readlane_b32 s22, v254, 6
	v_readlane_b32 s23, v254, 7
	s_brev_b32 s20, 15
	s_mov_b32 s21, -1
	v_lshl_add_u64 v[0:1], v[42:43], 2, s[22:23]
	v_lshl_add_u64 v[0:1], v[0:1], 0, s[20:21]
	s_mov_b64 s[20:21], 0

; template <int EPI, int TS, bool VT>
; DEVI void gemm_epilogue(const Params& p, char* smem, f32x4 (&acc)[2][2][4][2], int m0, int n0, float scale, const float* ssin,
;                         float* ssout, u16* xbout, int wid, int lane, int wr, int wc, int fr, int fq) {
;     ...
;           for (int u = 0; u < 8; ++u) {
;             const size_t ro = (size_t)(g0 + i0 + u) * 1024 + n0 + 4 * lane;
;             const int gr = g0 + i0 + u;
;             const float* xs = p.x + ro;
;             if (scale < 0.f)
;               xs = (gr < MP ? p.x_prompt + ro : p.x_sample + (ro - (size_t)MP * 1024));
;             { const f32x4 t_ = __builtin_nontemporal_load((const f32x4*)xs); xo[u] = make_float4(t_[0], t_[1], t_[2], t_[3]); }
.LBB0_311:
	global_load_dwordx4 v[8:11], v[0:1], off
	s_add_i32 s22, s18, 0x86
	s_ashr_i32 s23, s22, 31
	s_lshl_b64 s[20:21], s[22:23], 10
	v_lshl_add_u64 v[38:39], s[20:21], 0, v[128:129]
	v_lshl_add_u64 v[36:37], v[38:39], 2, s[38:39]
	s_and_b64 vcc, exec, s[4:5]
	v_mov_b64_e32 v[0:1], v[36:37]
	s_cbranch_vccnz .LBB0_316
	s_cmp_lt_i32 s22, 0x10000
	s_mov_b64 s[20:21], -1
	s_cbranch_scc1 .LBB0_314
	v_readlane_b32 s76, v254, 4
	v_readlane_b32 s78, v254, 6
	v_readlane_b32 s79, v254, 7
	s_brev_b32 s20, 15
	s_mov_b32 s21, -1
	v_lshl_add_u64 v[0:1], v[38:39], 2, s[78:79]
	v_lshl_add_u64 v[0:1], v[0:1], 0, s[20:21]
	s_mov_b64 s[20:21], 0
	v_readlane_b32 s77, v254, 5

; template <int EPI, int TS, bool VT>
; DEVI void gemm_epilogue(const Params& p, char* smem, f32x4 (&acc)[2][2][4][2], int m0, int n0, float scale, const float* ssin,
;                         float* ssout, u16* xbout, int wid, int lane, int wr, int wc, int fr, int fq) {
;     ...
;           for (int u = 0; u < 8; ++u) {
;             const size_t ro = (size_t)(g0 + i0 + u) * 1024 + n0 + 4 * lane;
;             const int gr = g0 + i0 + u;
;             const float* xs = p.x + ro;
;             if (scale < 0.f)
;               xs = (gr < MP ? p.x_prompt + ro : p.x_sample + (ro - (size_t)MP * 1024));
;             { const f32x4 t_ = __builtin_nontemporal_load((const f32x4*)xs); xo[u] = make_float4(t_[0], t_[1], t_[2], t_[3]); }
.LBB0_316:
	global_load_dwordx4 v[4:7], v[0:1], off
	s_add_i32 s20, s18, 0x87
	s_ashr_i32 s21, s20, 31
	s_lshl_b64 s[70:71], s[20:21], 10
	v_lshl_add_u64 v[34:35], s[70:71], 0, v[128:129]
	v_lshl_add_u64 v[32:33], v[34:35], 2, s[38:39]
	s_and_b64 vcc, exec, s[4:5]
	v_mov_b64_e32 v[0:1], v[32:33]
	s_cbranch_vccnz .LBB0_321
	s_cmp_lt_i32 s20, 0x10000
	s_mov_b64 s[70:71], -1
	s_cbranch_scc1 .LBB0_319
	v_readlane_b32 s76, v254, 4
	v_readlane_b32 s78, v254, 6
	v_readlane_b32 s79, v254, 7
	s_brev_b32 s70, 15
	s_mov_b32 s71, -1
	v_lshl_add_u64 v[0:1], v[34:35], 2, s[78:79]
	v_lshl_add_u64 v[0:1], v[0:1], 0, s[70:71]
	s_mov_b64 s[70:71], 0
	v_readlane_b32 s77, v254, 5

; DEVI float fsig(float x) { return __builtin_amdgcn_rcpf(1.f + __expf(-x)); }
; DEVI float bflo(unsigned u) { return __uint_as_float(u << 16); }
; DEVI float bfhi(unsigned u) { return __uint_as_float(u & 0xffff0000u); }
; template <int EPI, int TS, bool VT>
; DEVI void gemm_epilogue(const Params& p, char* smem, f32x4 (&acc)[2][2][4][2], int m0, int n0, float scale, const float* ssin,
;                         float* ssout, u16* xbout, int wid, int lane, int wr, int wc, int fr, int fq) {
;     ...
;         for (int u = 0; u < 8; ++u) {
;           const int i = i0 + u;
;           const int grow = g0 + i;
;           const float* Tr = T + (r0 + i) * TS;
;           const float rs = __int_as_float(__builtin_amdgcn_readlane(__float_as_int(rsv), i));
;           if constexpr (EPI == E_RESID || EPI == E_PLEGATE) {
;             const float4 a = *(const float4*)(Tr + 4 * lane);
;             const size_t ro = (size_t)grow * 1024 + n0 + 4 * lane;
;             float4 x4 = xo[u];
;             if constexpr (EPI == E_PLEGATE) {
;               x4.x += bflo(pv[u].x) * fsig(a.x * rs);
;               x4.y += bfhi(pv[u].x) * fsig(a.y * rs);
;               x4.z += bflo(pv[u].y) * fsig(a.z * rs);
;               x4.w += bfhi(pv[u].y) * fsig(a.w * rs);
;             } else {
;               const float sc = fabsf(scale);
;               x4.x += sc * a.x; x4.y += sc * a.y; x4.z += sc * a.z; x4.w += sc * a.w;
;             }
;             st_nt16(p.x + ro, x4);
;             if (xbout) {
;               uint2 o;
;               o.x = pack2(x4.x, x4.y);
;               o.y = pack2(x4.z, x4.w);
;               st_nt8(xbout + ro, o);
;             }
;             if (ssout) {
;               const float ssq = wsum(x4.x * x4.x + x4.y * x4.y + x4.z * x4.z + x4.w * x4.w, lane);
;               if (lane == 0) atomicAdd(ssout + grow, ssq);
;             }
.LBB0_321:
	global_load_dwordx4 v[0:3], v[0:1], off
	ds_read_b128 v[64:67], v130
	v_lshl_add_u64 v[56:57], v[56:57], 1, s[8:9]
	s_waitcnt vmcnt(0) lgkmcnt(0)
	v_pk_fma_f32 v[28:29], s[12:13], v[64:65], v[28:29]
	v_pk_fma_f32 v[30:31], s[12:13], v[66:67], v[30:31]
	global_store_dwordx4 v[62:63], v[28:31], off
	v_cvt_pk_bf16_f32 v62, v28, v29
	v_cvt_pk_bf16_f32 v63, v30, v31
	v_pk_mul_f32 v[28:29], v[28:29], v[28:29]
	v_pk_mul_f32 v[30:31], v[30:31], v[30:31]
	v_add_f32_e32 v28, v28, v29
	v_add_f32_e32 v28, v28, v30
	v_add_f32_e32 v28, v28, v31
	flat_store_dwordx2 v[56:57], v[62:63]
	s_nop 0
	v_add_f32_dpp v28, v28, v28 row_ror:8 row_mask:0xf bank_mask:0xf bound_ctrl:1
	s_nop 1
	v_add_f32_dpp v28, v28, v28 row_ror:4 row_mask:0xf bank_mask:0xf bound_ctrl:1
	s_nop 1
	v_add_f32_dpp v28, v28, v28 row_ror:2 row_mask:0xf bank_mask:0xf bound_ctrl:1
	s_nop 1
	v_add_f32_dpp v28, v28, v28 row_ror:1 row_mask:0xf bank_mask:0xf bound_ctrl:1
	s_nop 0
	v_readlane_b32 s19, v28, 0
	v_readlane_b32 s77, v28, 16
	v_readlane_b32 s75, v28, 32
	v_readlane_b32 s76, v28, 48
	s_and_saveexec_b64 s[70:71], s[0:1]
	s_cbranch_execz .LBB0_323
	s_lshl_b64 s[68:69], s[68:69], 2
	v_mov_b32_e32 v28, s77
	s_add_u32 s68, s16, s68
	v_add_f32_e32 v28, s19, v28
	s_addc_u32 s69, s17, s69
	v_add_f32_e32 v28, s75, v28
	v_add_f32_e32 v30, s76, v28
	v_mov_b64_e32 v[28:29], s[68:69]
	flat_atomic_add_f32 v[28:29], v30
.LBB0_323:
	s_or_b64 exec, exec, s[70:71]
	ds_read_b128 v[28:31], v130 offset:1040
	v_lshl_add_u64 v[56:57], v[60:61], 1, s[8:9]
	s_waitcnt lgkmcnt(0)
	v_pk_fma_f32 v[24:25], s[12:13], v[28:29], v[24:25]
	v_pk_fma_f32 v[26:27], s[12:13], v[30:31], v[26:27]
	global_store_dwordx4 v[58:59], v[24:27], off
	v_cvt_pk_bf16_f32 v28, v24, v25
	v_cvt_pk_bf16_f32 v29, v26, v27
	v_pk_mul_f32 v[24:25], v[24:25], v[24:25]
	v_pk_mul_f32 v[26:27], v[26:27], v[26:27]
	v_add_f32_e32 v24, v24, v25
	v_add_f32_e32 v24, v24, v26
	v_add_f32_e32 v24, v24, v27
	flat_store_dwordx2 v[56:57], v[28:29]
	s_nop 0
	v_add_f32_dpp v24, v24, v24 row_ror:8 row_mask:0xf bank_mask:0xf bound_ctrl:1
	s_nop 1
	v_add_f32_dpp v24, v24, v24 row_ror:4 row_mask:0xf bank_mask:0xf bound_ctrl:1
	s_nop 1
	v_add_f32_dpp v24, v24, v24 row_ror:2 row_mask:0xf bank_mask:0xf bound_ctrl:1
	s_nop 1
	v_add_f32_dpp v24, v24, v24 row_ror:1 row_mask:0xf bank_mask:0xf bound_ctrl:1
	s_nop 0
	v_readlane_b32 s19, v24, 0
	v_readlane_b32 s75, v24, 16
	v_readlane_b32 s70, v24, 32
	v_readlane_b32 s71, v24, 48
	s_and_saveexec_b64 s[68:69], s[0:1]
	s_cbranch_execz .LBB0_325
	s_lshl_b64 s[66:67], s[66:67], 2
	v_mov_b32_e32 v24, s75
	s_add_u32 s66, s16, s66
	v_add_f32_e32 v24, s19, v24
	s_addc_u32 s67, s17, s67
	v_add_f32_e32 v24, s70, v24
	v_add_f32_e32 v26, s71, v24
	v_mov_b64_e32 v[24:25], s[66:67]
	flat_atomic_add_f32 v[24:25], v26
.LBB0_325:
	s_or_b64 exec, exec, s[68:69]
	ds_read_b128 v[24:27], v130 offset:2080
	v_lshl_add_u64 v[28:29], v[54:55], 1, s[8:9]
	s_waitcnt lgkmcnt(0)
	v_pk_fma_f32 v[20:21], s[12:13], v[24:25], v[20:21]
	v_pk_fma_f32 v[22:23], s[12:13], v[26:27], v[22:23]
	global_store_dwordx4 v[52:53], v[20:23], off
	v_cvt_pk_bf16_f32 v24, v20, v21
	v_cvt_pk_bf16_f32 v25, v22, v23
	v_pk_mul_f32 v[20:21], v[20:21], v[20:21]
	v_pk_mul_f32 v[22:23], v[22:23], v[22:23]
	v_add_f32_e32 v20, v20, v21
	v_add_f32_e32 v20, v20, v22
	v_add_f32_e32 v20, v20, v23
	flat_store_dwordx2 v[28:29], v[24:25]
	s_nop 0
	v_add_f32_dpp v20, v20, v20 row_ror:8 row_mask:0xf bank_mask:0xf bound_ctrl:1
	s_nop 1
	v_add_f32_dpp v20, v20, v20 row_ror:4 row_mask:0xf bank_mask:0xf bound_ctrl:1
	s_nop 1
	v_add_f32_dpp v20, v20, v20 row_ror:2 row_mask:0xf bank_mask:0xf bound_ctrl:1
	s_nop 1
	v_add_f32_dpp v20, v20, v20 row_ror:1 row_mask:0xf bank_mask:0xf bound_ctrl:1
	s_nop 0
	v_readlane_b32 s19, v20, 0
	v_readlane_b32 s70, v20, 16
	v_readlane_b32 s68, v20, 32
	v_readlane_b32 s69, v20, 48
	s_and_saveexec_b64 s[66:67], s[0:1]
	s_cbranch_execz .LBB0_327
	s_lshl_b64 s[64:65], s[64:65], 2
	v_mov_b32_e32 v20, s70
	s_add_u32 s64, s16, s64
	v_add_f32_e32 v20, s19, v20
	s_addc_u32 s65, s17, s65
	v_add_f32_e32 v20, s68, v20
	v_add_f32_e32 v22, s69, v20
	v_mov_b64_e32 v[20:21], s[64:65]
	flat_atomic_add_f32 v[20:21], v22
.LBB0_327:
	s_or_b64 exec, exec, s[66:67]
	ds_read_b128 v[20:23], v130 offset:3120
	v_lshl_add_u64 v[24:25], v[50:51], 1, s[8:9]
	s_waitcnt lgkmcnt(0)
	v_pk_fma_f32 v[16:17], s[12:13], v[20:21], v[16:17]
	v_pk_fma_f32 v[18:19], s[12:13], v[22:23], v[18:19]
	global_store_dwordx4 v[48:49], v[16:19], off
	v_cvt_pk_bf16_f32 v20, v16, v17
	v_cvt_pk_bf16_f32 v21, v18, v19
	v_pk_mul_f32 v[16:17], v[16:17], v[16:17]
	v_pk_mul_f32 v[18:19], v[18:19], v[18:19]
	v_add_f32_e32 v16, v16, v17
	v_add_f32_e32 v16, v16, v18
	v_add_f32_e32 v16, v16, v19
	flat_store_dwordx2 v[24:25], v[20:21]
	s_nop 0
	v_add_f32_dpp v16, v16, v16 row_ror:8 row_mask:0xf bank_mask:0xf bound_ctrl:1
	s_nop 1
	v_add_f32_dpp v16, v16, v16 row_ror:4 row_mask:0xf bank_mask:0xf bound_ctrl:1
	s_nop 1
	v_add_f32_dpp v16, v16, v16 row_ror:2 row_mask:0xf bank_mask:0xf bound_ctrl:1
	s_nop 1
	v_add_f32_dpp v16, v16, v16 row_ror:1 row_mask:0xf bank_mask:0xf bound_ctrl:1
	s_nop 0
	v_readlane_b32 s19, v16, 0
	v_readlane_b32 s68, v16, 16
	v_readlane_b32 s66, v16, 32
	v_readlane_b32 s67, v16, 48
	s_and_saveexec_b64 s[64:65], s[0:1]
	s_cbranch_execz .LBB0_329
	s_lshl_b64 s[62:63], s[62:63], 2
	v_mov_b32_e32 v16, s68
	s_add_u32 s62, s16, s62
	v_add_f32_e32 v16, s19, v16
	s_addc_u32 s63, s17, s63
	v_add_f32_e32 v16, s66, v16
	v_add_f32_e32 v18, s67, v16
	v_mov_b64_e32 v[16:17], s[62:63]
	flat_atomic_add_f32 v[16:17], v18
; DEVI float fsig(float x) { return __builtin_amdgcn_rcpf(1.f + __expf(-x)); }
; DEVI float bflo(unsigned u) { return __uint_as_float(u << 16); }
; DEVI float bfhi(unsigned u) { return __uint_as_float(u & 0xffff0000u); }
; template <int EPI, int TS, bool VT>
; DEVI void gemm_epilogue(const Params& p, char* smem, f32x4 (&acc)[2][2][4][2], int m0, int n0, float scale, const float* ssin,
;                         float* ssout, u16* xbout, int wid, int lane, int wr, int wc, int fr, int fq) {
;     ...
;           if constexpr (EPI == E_RESID || EPI == E_PLEGATE) {
;             const float4 a = *(const float4*)(Tr + 4 * lane);
;             const size_t ro = (size_t)grow * 1024 + n0 + 4 * lane;
;             float4 x4 = xo[u];
;             if constexpr (EPI == E_PLEGATE) {
;               x4.x += bflo(pv[u].x) * fsig(a.x * rs);
;               x4.y += bfhi(pv[u].x) * fsig(a.y * rs);
;               x4.z += bflo(pv[u].y) * fsig(a.z * rs);
;               x4.w += bfhi(pv[u].y) * fsig(a.w * rs);
;             } else {
;               const float sc = fabsf(scale);
;               x4.x += sc * a.x; x4.y += sc * a.y; x4.z += sc * a.z; x4.w += sc * a.w;
;             }
;             st_nt16(p.x + ro, x4);
;             if (xbout) {
;               uint2 o;
;               o.x = pack2(x4.x, x4.y);
;               o.y = pack2(x4.z, x4.w);
;               st_nt8(xbout + ro, o);
;             }
;             if (ssout) {
;               const float ssq = wsum(x4.x * x4.x + x4.y * x4.y + x4.z * x4.z + x4.w * x4.w, lane);
;               if (lane == 0) atomicAdd(ssout + grow, ssq);
;             }
.LBB0_329:
	s_or_b64 exec, exec, s[64:65]
	ds_read_b128 v[16:19], v130 offset:4160
	v_lshl_add_u64 v[20:21], v[46:47], 1, s[8:9]
	s_waitcnt lgkmcnt(0)
	v_pk_fma_f32 v[12:13], s[12:13], v[16:17], v[12:13]
	v_pk_fma_f32 v[14:15], s[12:13], v[18:19], v[14:15]
	global_store_dwordx4 v[44:45], v[12:15], off
	v_cvt_pk_bf16_f32 v16, v12, v13
	v_cvt_pk_bf16_f32 v17, v14, v15
	v_pk_mul_f32 v[12:13], v[12:13], v[12:13]
	v_pk_mul_f32 v[14:15], v[14:15], v[14:15]
	v_add_f32_e32 v12, v12, v13
	v_add_f32_e32 v12, v12, v14
	v_add_f32_e32 v12, v12, v15
	flat_store_dwordx2 v[20:21], v[16:17]
	s_nop 0
	v_add_f32_dpp v12, v12, v12 row_ror:8 row_mask:0xf bank_mask:0xf bound_ctrl:1
	s_nop 1
	v_add_f32_dpp v12, v12, v12 row_ror:4 row_mask:0xf bank_mask:0xf bound_ctrl:1
	s_nop 1
	v_add_f32_dpp v12, v12, v12 row_ror:2 row_mask:0xf bank_mask:0xf bound_ctrl:1
	s_nop 1
	v_add_f32_dpp v12, v12, v12 row_ror:1 row_mask:0xf bank_mask:0xf bound_ctrl:1
	s_nop 0
	v_readlane_b32 s19, v12, 0
	v_readlane_b32 s66, v12, 16
	v_readlane_b32 s64, v12, 32
	v_readlane_b32 s65, v12, 48
	s_and_saveexec_b64 s[62:63], s[0:1]
	s_cbranch_execz .LBB0_331
	s_lshl_b64 s[34:35], s[34:35], 2
	v_mov_b32_e32 v12, s66
	s_add_u32 s34, s16, s34
	v_add_f32_e32 v12, s19, v12
	s_addc_u32 s35, s17, s35
	v_add_f32_e32 v12, s64, v12
	v_add_f32_e32 v14, s65, v12
	v_mov_b64_e32 v[12:13], s[34:35]
	flat_atomic_add_f32 v[12:13], v14
.LBB0_331:
	s_or_b64 exec, exec, s[62:63]
	ds_read_b128 v[12:15], v130 offset:5200
	v_lshl_add_u64 v[16:17], v[42:43], 1, s[8:9]
	s_waitcnt lgkmcnt(0)
	v_pk_fma_f32 v[8:9], s[12:13], v[12:13], v[8:9]
	v_pk_fma_f32 v[10:11], s[12:13], v[14:15], v[10:11]
	global_store_dwordx4 v[40:41], v[8:11], off
	v_cvt_pk_bf16_f32 v12, v8, v9
	v_cvt_pk_bf16_f32 v13, v10, v11
	v_pk_mul_f32 v[8:9], v[8:9], v[8:9]
	v_pk_mul_f32 v[10:11], v[10:11], v[10:11]
	v_add_f32_e32 v8, v8, v9
	v_add_f32_e32 v8, v8, v10
	v_add_f32_e32 v8, v8, v11
	flat_store_dwordx2 v[16:17], v[12:13]
	s_nop 0
	v_add_f32_dpp v8, v8, v8 row_ror:8 row_mask:0xf bank_mask:0xf bound_ctrl:1
	s_nop 1
	v_add_f32_dpp v8, v8, v8 row_ror:4 row_mask:0xf bank_mask:0xf bound_ctrl:1
	s_nop 1
	v_add_f32_dpp v8, v8, v8 row_ror:2 row_mask:0xf bank_mask:0xf bound_ctrl:1
	s_nop 1
	v_add_f32_dpp v8, v8, v8 row_ror:1 row_mask:0xf bank_mask:0xf bound_ctrl:1
	s_nop 0
	v_readlane_b32 s19, v8, 0
	v_readlane_b32 s64, v8, 16
	v_readlane_b32 s62, v8, 32
	v_readlane_b32 s63, v8, 48
	s_and_saveexec_b64 s[34:35], s[0:1]
	s_cbranch_execz .LBB0_333
	s_lshl_b64 s[30:31], s[30:31], 2
	v_mov_b32_e32 v8, s64
	s_add_u32 s30, s16, s30
	v_add_f32_e32 v8, s19, v8
	s_addc_u32 s31, s17, s31
	v_add_f32_e32 v8, s62, v8
	v_add_f32_e32 v10, s63, v8
	v_mov_b64_e32 v[8:9], s[30:31]
	flat_atomic_add_f32 v[8:9], v10
.LBB0_333:
	s_or_b64 exec, exec, s[34:35]
	ds_read_b128 v[8:11], v130 offset:6240
	v_lshl_add_u64 v[12:13], v[38:39], 1, s[8:9]
	s_waitcnt lgkmcnt(0)
	v_pk_fma_f32 v[4:5], s[12:13], v[8:9], v[4:5]
	v_pk_fma_f32 v[6:7], s[12:13], v[10:11], v[6:7]
	global_store_dwordx4 v[36:37], v[4:7], off
	v_cvt_pk_bf16_f32 v8, v4, v5
	v_cvt_pk_bf16_f32 v9, v6, v7
	v_pk_mul_f32 v[4:5], v[4:5], v[4:5]
	v_pk_mul_f32 v[6:7], v[6:7], v[6:7]
	v_add_f32_e32 v4, v4, v5
	v_add_f32_e32 v4, v4, v6
	v_add_f32_e32 v4, v4, v7
	flat_store_dwordx2 v[12:13], v[8:9]
	s_nop 0
	v_add_f32_dpp v4, v4, v4 row_ror:8 row_mask:0xf bank_mask:0xf bound_ctrl:1
	s_nop 1
	v_add_f32_dpp v4, v4, v4 row_ror:4 row_mask:0xf bank_mask:0xf bound_ctrl:1
	s_nop 1
	v_add_f32_dpp v4, v4, v4 row_ror:2 row_mask:0xf bank_mask:0xf bound_ctrl:1
	s_nop 1
	v_add_f32_dpp v4, v4, v4 row_ror:1 row_mask:0xf bank_mask:0xf bound_ctrl:1
	s_nop 0
	v_readlane_b32 s19, v4, 0
	v_readlane_b32 s62, v4, 16
	v_readlane_b32 s34, v4, 32
	v_readlane_b32 s35, v4, 48
	s_and_saveexec_b64 s[30:31], s[0:1]
	s_cbranch_execz .LBB0_335
	s_lshl_b64 s[22:23], s[22:23], 2
	v_mov_b32_e32 v4, s62
	s_add_u32 s22, s16, s22
	v_add_f32_e32 v4, s19, v4
	s_addc_u32 s23, s17, s23
	v_add_f32_e32 v4, s34, v4
	v_add_f32_e32 v6, s35, v4
	v_mov_b64_e32 v[4:5], s[22:23]
	flat_atomic_add_f32 v[4:5], v6
.LBB0_335:
	s_or_b64 exec, exec, s[30:31]
	ds_read_b128 v[4:7], v130 offset:7280
	v_lshl_add_u64 v[8:9], v[34:35], 1, s[8:9]
	s_waitcnt lgkmcnt(0)
	v_pk_fma_f32 v[0:1], s[12:13], v[4:5], v[0:1]
	v_pk_fma_f32 v[2:3], s[12:13], v[6:7], v[2:3]
	global_store_dwordx4 v[32:33], v[0:3], off
	v_cvt_pk_bf16_f32 v4, v0, v1
	v_cvt_pk_bf16_f32 v5, v2, v3
	v_pk_mul_f32 v[0:1], v[0:1], v[0:1]
	v_pk_mul_f32 v[2:3], v[2:3], v[2:3]
	v_add_f32_e32 v0, v0, v1
	v_add_f32_e32 v0, v0, v2
	v_add_f32_e32 v0, v0, v3
	flat_store_dwordx2 v[8:9], v[4:5]
	s_nop 0
	v_add_f32_dpp v0, v0, v0 row_ror:8 row_mask:0xf bank_mask:0xf bound_ctrl:1
	s_nop 1
	v_add_f32_dpp v0, v0, v0 row_ror:4 row_mask:0xf bank_mask:0xf bound_ctrl:1
	s_nop 1
	v_add_f32_dpp v0, v0, v0 row_ror:2 row_mask:0xf bank_mask:0xf bound_ctrl:1
	s_nop 1
	v_add_f32_dpp v0, v0, v0 row_ror:1 row_mask:0xf bank_mask:0xf bound_ctrl:1
	s_nop 0
	v_readlane_b32 s19, v0, 0
	v_readlane_b32 s34, v0, 16
	v_readlane_b32 s30, v0, 32
	v_readlane_b32 s31, v0, 48
	s_and_saveexec_b64 s[22:23], s[0:1]
	s_cbranch_execz .LBB0_337
	s_lshl_b64 s[20:21], s[20:21], 2
	v_mov_b32_e32 v0, s34
	s_add_u32 s20, s16, s20
	v_add_f32_e32 v0, s19, v0
	s_addc_u32 s21, s17, s21
	v_add_f32_e32 v0, s30, v0
	v_add_f32_e32 v2, s31, v0
	v_mov_b64_e32 v[0:1], s[20:21]
	flat_atomic_add_f32 v[0:1], v2

; template <int EPI, int TS, bool VT>
; DEVI void gemm_epilogue(const Params& p, char* smem, f32x4 (&acc)[2][2][4][2], int m0, int n0, float scale, const float* ssin,
;                         float* ssout, u16* xbout, int wid, int lane, int wr, int wc, int fr, int fq) {
;     ...
;           for (int u = 0; u < 8; ++u) {
;             const size_t ro = (size_t)(g0 + i0 + u) * 1024 + n0 + 4 * lane;
;             const int gr = g0 + i0 + u;
;             const float* xs = p.x + ro;
;             if (scale < 0.f)
;               xs = (gr < MP ? p.x_prompt + ro : p.x_sample + (ro - (size_t)MP * 1024));
;             { const f32x4 t_ = __builtin_nontemporal_load((const f32x4*)xs); xo[u] = make_float4(t_[0], t_[1], t_[2], t_[3]); }
.LBB0_342:
	global_load_dwordx4 v[28:31], v[0:1], off
	s_add_i32 s64, s18, 0x89
	s_ashr_i32 s65, s64, 31
	s_lshl_b64 s[20:21], s[64:65], 10
	v_lshl_add_u64 v[60:61], s[20:21], 0, v[128:129]
	v_lshl_add_u64 v[58:59], v[60:61], 2, s[38:39]
	s_and_b64 vcc, exec, s[4:5]
	v_mov_b64_e32 v[0:1], v[58:59]
	s_cbranch_vccnz .LBB0_347
	s_cmp_lt_i32 s64, 0x10000
	s_mov_b64 s[20:21], -1
	s_cbranch_scc1 .LBB0_345
	v_readlane_b32 s20, v254, 4
	v_readlane_b32 s21, v254, 5
	v_readlane_b32 s22, v254, 6
	v_readlane_b32 s23, v254, 7
	s_brev_b32 s20, 15
	s_mov_b32 s21, -1
	v_lshl_add_u64 v[0:1], v[60:61], 2, s[22:23]
	v_lshl_add_u64 v[0:1], v[0:1], 0, s[20:21]
	s_mov_b64 s[20:21], 0

; template <int EPI, int TS, bool VT>
; DEVI void gemm_epilogue(const Params& p, char* smem, f32x4 (&acc)[2][2][4][2], int m0, int n0, float scale, const float* ssin,
;                         float* ssout, u16* xbout, int wid, int lane, int wr, int wc, int fr, int fq) {
;     ...
;           for (int u = 0; u < 8; ++u) {
;             const size_t ro = (size_t)(g0 + i0 + u) * 1024 + n0 + 4 * lane;
;             const int gr = g0 + i0 + u;
;             const float* xs = p.x + ro;
;             if (scale < 0.f)
;               xs = (gr < MP ? p.x_prompt + ro : p.x_sample + (ro - (size_t)MP * 1024));
;             { const f32x4 t_ = __builtin_nontemporal_load((const f32x4*)xs); xo[u] = make_float4(t_[0], t_[1], t_[2], t_[3]); }
.LBB0_347:
	global_load_dwordx4 v[24:27], v[0:1], off
	s_add_i32 s62, s18, 0x8a
	s_ashr_i32 s63, s62, 31
	s_lshl_b64 s[20:21], s[62:63], 10
	v_lshl_add_u64 v[54:55], s[20:21], 0, v[128:129]
	v_lshl_add_u64 v[52:53], v[54:55], 2, s[38:39]
	s_and_b64 vcc, exec, s[4:5]
	v_mov_b64_e32 v[0:1], v[52:53]
	s_cbranch_vccnz .LBB0_352
	s_cmp_lt_i32 s62, 0x10000
	s_mov_b64 s[20:21], -1
	s_cbranch_scc1 .LBB0_350
	v_readlane_b32 s20, v254, 4
	v_readlane_b32 s21, v254, 5
	v_readlane_b32 s22, v254, 6
	v_readlane_b32 s23, v254, 7
	s_brev_b32 s20, 15
	s_mov_b32 s21, -1
	v_lshl_add_u64 v[0:1], v[54:55], 2, s[22:23]
	v_lshl_add_u64 v[0:1], v[0:1], 0, s[20:21]
	s_mov_b64 s[20:21], 0

; template <int EPI, int TS, bool VT>
; DEVI void gemm_epilogue(const Params& p, char* smem, f32x4 (&acc)[2][2][4][2], int m0, int n0, float scale, const float* ssin,
;                         float* ssout, u16* xbout, int wid, int lane, int wr, int wc, int fr, int fq) {
;     ...
;           for (int u = 0; u < 8; ++u) {
;             const size_t ro = (size_t)(g0 + i0 + u) * 1024 + n0 + 4 * lane;
;             const int gr = g0 + i0 + u;
;             const float* xs = p.x + ro;
;             if (scale < 0.f)
;               xs = (gr < MP ? p.x_prompt + ro : p.x_sample + (ro - (size_t)MP * 1024));
;             { const f32x4 t_ = __builtin_nontemporal_load((const f32x4*)xs); xo[u] = make_float4(t_[0], t_[1], t_[2], t_[3]); }
.LBB0_352:
	global_load_dwordx4 v[20:23], v[0:1], off
	s_add_i32 s34, s18, 0x8b
	s_ashr_i32 s35, s34, 31
	s_lshl_b64 s[20:21], s[34:35], 10
	v_lshl_add_u64 v[50:51], s[20:21], 0, v[128:129]
	v_lshl_add_u64 v[48:49], v[50:51], 2, s[38:39]
	s_and_b64 vcc, exec, s[4:5]
	v_mov_b64_e32 v[0:1], v[48:49]
	s_cbranch_vccnz .LBB0_357
	s_cmp_lt_i32 s34, 0x10000
	s_mov_b64 s[20:21], -1
	s_cbranch_scc1 .LBB0_355
	v_readlane_b32 s20, v254, 4
	v_readlane_b32 s21, v254, 5
	v_readlane_b32 s22, v254, 6
	v_readlane_b32 s23, v254, 7
	s_brev_b32 s20, 15
	s_mov_b32 s21, -1
	v_lshl_add_u64 v[0:1], v[50:51], 2, s[22:23]
	v_lshl_add_u64 v[0:1], v[0:1], 0, s[20:21]
	s_mov_b64 s[20:21], 0

; template <int EPI, int TS, bool VT>
; DEVI void gemm_epilogue(const Params& p, char* smem, f32x4 (&acc)[2][2][4][2], int m0, int n0, float scale, const float* ssin,
;                         float* ssout, u16* xbout, int wid, int lane, int wr, int wc, int fr, int fq) {
;     ...
;           for (int u = 0; u < 8; ++u) {
;             const size_t ro = (size_t)(g0 + i0 + u) * 1024 + n0 + 4 * lane;
;             const int gr = g0 + i0 + u;
;             const float* xs = p.x + ro;
;             if (scale < 0.f)
;               xs = (gr < MP ? p.x_prompt + ro : p.x_sample + (ro - (size_t)MP * 1024));
;             { const f32x4 t_ = __builtin_nontemporal_load((const f32x4*)xs); xo[u] = make_float4(t_[0], t_[1], t_[2], t_[3]); }
.LBB0_357:
	global_load_dwordx4 v[16:19], v[0:1], off
	s_add_i32 s30, s18, 0x8c
	s_ashr_i32 s31, s30, 31
	s_lshl_b64 s[20:21], s[30:31], 10
	v_lshl_add_u64 v[46:47], s[20:21], 0, v[128:129]
	v_lshl_add_u64 v[44:45], v[46:47], 2, s[38:39]
	s_and_b64 vcc, exec, s[4:5]
	v_mov_b64_e32 v[0:1], v[44:45]
	s_cbranch_vccnz .LBB0_362
	s_cmp_lt_i32 s30, 0x10000
	s_mov_b64 s[20:21], -1
	s_cbranch_scc1 .LBB0_360
	v_readlane_b32 s20, v254, 4
	v_readlane_b32 s21, v254, 5
	v_readlane_b32 s22, v254, 6
	v_readlane_b32 s23, v254, 7
	s_brev_b32 s20, 15
	s_mov_b32 s21, -1
	v_lshl_add_u64 v[0:1], v[46:47], 2, s[22:23]
	v_lshl_add_u64 v[0:1], v[0:1], 0, s[20:21]
	s_mov_b64 s[20:21], 0

; template <int EPI, int TS, bool VT>
; DEVI void gemm_epilogue(const Params& p, char* smem, f32x4 (&acc)[2][2][4][2], int m0, int n0, float scale, const float* ssin,
;                         float* ssout, u16* xbout, int wid, int lane, int wr, int wc, int fr, int fq) {
;     ...
;           for (int u = 0; u < 8; ++u) {
;             const size_t ro = (size_t)(g0 + i0 + u) * 1024 + n0 + 4 * lane;
;             const int gr = g0 + i0 + u;
;             const float* xs = p.x + ro;
;             if (scale < 0.f)
;               xs = (gr < MP ? p.x_prompt + ro : p.x_sample + (ro - (size_t)MP * 1024));
;             { const f32x4 t_ = __builtin_nontemporal_load((const f32x4*)xs); xo[u] = make_float4(t_[0], t_[1], t_[2], t_[3]); }
.LBB0_362:
	global_load_dwordx4 v[12:15], v[0:1], off
	s_add_i32 s22, s18, 0x8d
	s_ashr_i32 s23, s22, 31
	s_lshl_b64 s[20:21], s[22:23], 10
	v_lshl_add_u64 v[42:43], s[20:21], 0, v[128:129]
	v_lshl_add_u64 v[40:41], v[42:43], 2, s[38:39]
	s_and_b64 vcc, exec, s[4:5]
	v_mov_b64_e32 v[0:1], v[40:41]
	s_cbranch_vccnz .LBB0_367
	s_cmp_lt_i32 s22, 0x10000
	s_mov_b64 s[20:21], -1
	s_cbranch_scc1 .LBB0_365
	v_readlane_b32 s68, v254, 4
	v_readlane_b32 s70, v254, 6
	v_readlane_b32 s71, v254, 7
	s_brev_b32 s20, 15
	s_mov_b32 s21, -1
	v_lshl_add_u64 v[0:1], v[42:43], 2, s[70:71]
	v_lshl_add_u64 v[0:1], v[0:1], 0, s[20:21]
	s_mov_b64 s[20:21], 0
	v_readlane_b32 s69, v254, 5

; template <int EPI, int TS, bool VT>
; DEVI void gemm_epilogue(const Params& p, char* smem, f32x4 (&acc)[2][2][4][2], int m0, int n0, float scale, const float* ssin,
;                         float* ssout, u16* xbout, int wid, int lane, int wr, int wc, int fr, int fq) {
;     ...
;           for (int u = 0; u < 8; ++u) {
;             const size_t ro = (size_t)(g0 + i0 + u) * 1024 + n0 + 4 * lane;
;             const int gr = g0 + i0 + u;
;             const float* xs = p.x + ro;
;             if (scale < 0.f)
;               xs = (gr < MP ? p.x_prompt + ro : p.x_sample + (ro - (size_t)MP * 1024));
;             { const f32x4 t_ = __builtin_nontemporal_load((const f32x4*)xs); xo[u] = make_float4(t_[0], t_[1], t_[2], t_[3]); }
.LBB0_367:
	global_load_dwordx4 v[8:11], v[0:1], off
	s_add_i32 s20, s18, 0x8e
	s_ashr_i32 s21, s20, 31
	s_lshl_b64 s[68:69], s[20:21], 10
	v_lshl_add_u64 v[38:39], s[68:69], 0, v[128:129]
	v_lshl_add_u64 v[36:37], v[38:39], 2, s[38:39]
	s_and_b64 vcc, exec, s[4:5]
	v_mov_b64_e32 v[0:1], v[36:37]
	s_cbranch_vccnz .LBB0_372
	s_cmp_lt_i32 s20, 0x10000
	s_mov_b64 s[68:69], -1
	s_cbranch_scc1 .LBB0_370
	v_readlane_b32 s68, v254, 4
	v_readlane_b32 s69, v254, 5
	v_readlane_b32 s70, v254, 6
	v_readlane_b32 s71, v254, 7
	s_brev_b32 s68, 15
	s_mov_b32 s69, -1
	v_lshl_add_u64 v[0:1], v[38:39], 2, s[70:71]
	v_lshl_add_u64 v[0:1], v[0:1], 0, s[68:69]
	s_mov_b64 s[68:69], 0

; template <int EPI, int TS, bool VT>
; DEVI void gemm_epilogue(const Params& p, char* smem, f32x4 (&acc)[2][2][4][2], int m0, int n0, float scale, const float* ssin,
;                         float* ssout, u16* xbout, int wid, int lane, int wr, int wc, int fr, int fq) {
;     ...
;           for (int u = 0; u < 8; ++u) {
;             const size_t ro = (size_t)(g0 + i0 + u) * 1024 + n0 + 4 * lane;
;             const int gr = g0 + i0 + u;
;             const float* xs = p.x + ro;
;             if (scale < 0.f)
;               xs = (gr < MP ? p.x_prompt + ro : p.x_sample + (ro - (size_t)MP * 1024));
;             { const f32x4 t_ = __builtin_nontemporal_load((const f32x4*)xs); xo[u] = make_float4(t_[0], t_[1], t_[2], t_[3]); }
.LBB0_372:
	global_load_dwordx4 v[4:7], v[0:1], off
	s_addk_i32 s18, 0x8f
	s_ashr_i32 s19, s18, 31
	s_lshl_b64 s[68:69], s[18:19], 10
	v_lshl_add_u64 v[34:35], s[68:69], 0, v[128:129]
	v_lshl_add_u64 v[32:33], v[34:35], 2, s[38:39]
	s_and_b64 vcc, exec, s[4:5]
	v_mov_b64_e32 v[0:1], v[32:33]
	s_cbranch_vccnz .LBB0_377
	s_cmp_lt_i32 s18, 0x10000
	s_mov_b64 s[4:5], -1
	s_cbranch_scc1 .LBB0_375
	v_readlane_b32 s68, v254, 4
	v_readlane_b32 s70, v254, 6
	v_readlane_b32 s71, v254, 7
	s_brev_b32 s4, 15
	s_mov_b32 s5, -1
	v_lshl_add_u64 v[0:1], v[34:35], 2, s[70:71]
	v_lshl_add_u64 v[0:1], v[0:1], 0, s[4:5]
	s_mov_b64 s[4:5], 0
	v_readlane_b32 s69, v254, 5

; DEVI float fsig(float x) { return __builtin_amdgcn_rcpf(1.f + __expf(-x)); }
; DEVI float bflo(unsigned u) { return __uint_as_float(u << 16); }
; DEVI float bfhi(unsigned u) { return __uint_as_float(u & 0xffff0000u); }
; template <int EPI, int TS, bool VT>
; DEVI void gemm_epilogue(const Params& p, char* smem, f32x4 (&acc)[2][2][4][2], int m0, int n0, float scale, const float* ssin,
;                         float* ssout, u16* xbout, int wid, int lane, int wr, int wc, int fr, int fq) {
;     ...
;           for (int u = 0; u < 8; ++u) {
;             const size_t ro = (size_t)(g0 + i0 + u) * 1024 + n0 + 4 * lane;
;             const int gr = g0 + i0 + u;
;             const float* xs = p.x + ro;
;             if (scale < 0.f)
;               xs = (gr < MP ? p.x_prompt + ro : p.x_sample + (ro - (size_t)MP * 1024));
;             { const f32x4 t_ = __builtin_nontemporal_load((const f32x4*)xs); xo[u] = make_float4(t_[0], t_[1], t_[2], t_[3]); }
;     ...
;           if constexpr (EPI == E_RESID || EPI == E_PLEGATE) {
;             const float4 a = *(const float4*)(Tr + 4 * lane);
;             const size_t ro = (size_t)grow * 1024 + n0 + 4 * lane;
;             float4 x4 = xo[u];
;             if constexpr (EPI == E_PLEGATE) {
;               x4.x += bflo(pv[u].x) * fsig(a.x * rs);
;               x4.y += bfhi(pv[u].x) * fsig(a.y * rs);
;               x4.z += bflo(pv[u].y) * fsig(a.z * rs);
;               x4.w += bfhi(pv[u].y) * fsig(a.w * rs);
;             } else {
;               const float sc = fabsf(scale);
;               x4.x += sc * a.x; x4.y += sc * a.y; x4.z += sc * a.z; x4.w += sc * a.w;
;             }
;             st_nt16(p.x + ro, x4);
;             if (xbout) {
;               uint2 o;
;               o.x = pack2(x4.x, x4.y);
;               o.y = pack2(x4.z, x4.w);
;               st_nt8(xbout + ro, o);
;             }
;             if (ssout) {
;               const float ssq = wsum(x4.x * x4.x + x4.y * x4.y + x4.z * x4.z + x4.w * x4.w, lane);
;               if (lane == 0) atomicAdd(ssout + grow, ssq);
;             }
.LBB0_377:
	global_load_dwordx4 v[0:3], v[0:1], off
	ds_read_b128 v[64:67], v130 offset:8320
	v_lshl_add_u64 v[56:57], v[56:57], 1, s[8:9]
	s_waitcnt vmcnt(0) lgkmcnt(0)
	v_pk_fma_f32 v[28:29], s[12:13], v[64:65], v[28:29]
	v_pk_fma_f32 v[30:31], s[12:13], v[66:67], v[30:31]
	global_store_dwordx4 v[62:63], v[28:31], off
	v_cvt_pk_bf16_f32 v62, v28, v29
	v_cvt_pk_bf16_f32 v63, v30, v31
	v_pk_mul_f32 v[28:29], v[28:29], v[28:29]
	v_pk_mul_f32 v[30:31], v[30:31], v[30:31]
	v_add_f32_e32 v28, v28, v29
	v_add_f32_e32 v28, v28, v30
	v_add_f32_e32 v28, v28, v31
	flat_store_dwordx2 v[56:57], v[62:63]
	s_nop 0
	v_add_f32_dpp v28, v28, v28 row_ror:8 row_mask:0xf bank_mask:0xf bound_ctrl:1
	s_nop 1
	v_add_f32_dpp v28, v28, v28 row_ror:4 row_mask:0xf bank_mask:0xf bound_ctrl:1
	s_nop 1
	v_add_f32_dpp v28, v28, v28 row_ror:2 row_mask:0xf bank_mask:0xf bound_ctrl:1
	s_nop 1
	v_add_f32_dpp v28, v28, v28 row_ror:1 row_mask:0xf bank_mask:0xf bound_ctrl:1
	s_nop 0
	v_readlane_b32 s68, v28, 0
	v_readlane_b32 s71, v28, 16
	v_readlane_b32 s69, v28, 32
	v_readlane_b32 s70, v28, 48
	s_and_saveexec_b64 s[4:5], s[0:1]
	s_cbranch_execz .LBB0_379
	s_lshl_b64 s[66:67], s[66:67], 2
	v_mov_b32_e32 v28, s71
	s_add_u32 s66, s16, s66
	v_add_f32_e32 v28, s68, v28
	s_addc_u32 s67, s17, s67
	v_add_f32_e32 v28, s69, v28
	v_add_f32_e32 v30, s70, v28
	v_mov_b64_e32 v[28:29], s[66:67]
	flat_atomic_add_f32 v[28:29], v30
.LBB0_379:
	s_or_b64 exec, exec, s[4:5]
	ds_read_b128 v[28:31], v130 offset:9360
	v_lshl_add_u64 v[56:57], v[60:61], 1, s[8:9]
	s_waitcnt lgkmcnt(0)
	v_pk_fma_f32 v[24:25], s[12:13], v[28:29], v[24:25]
	v_pk_fma_f32 v[26:27], s[12:13], v[30:31], v[26:27]
	global_store_dwordx4 v[58:59], v[24:27], off
	v_cvt_pk_bf16_f32 v28, v24, v25
	v_cvt_pk_bf16_f32 v29, v26, v27
	v_pk_mul_f32 v[24:25], v[24:25], v[24:25]
	v_pk_mul_f32 v[26:27], v[26:27], v[26:27]
	v_add_f32_e32 v24, v24, v25
	v_add_f32_e32 v24, v24, v26
	v_add_f32_e32 v24, v24, v27
	flat_store_dwordx2 v[56:57], v[28:29]
	s_nop 0
	v_add_f32_dpp v24, v24, v24 row_ror:8 row_mask:0xf bank_mask:0xf bound_ctrl:1
	s_nop 1
	v_add_f32_dpp v24, v24, v24 row_ror:4 row_mask:0xf bank_mask:0xf bound_ctrl:1
	s_nop 1
	v_add_f32_dpp v24, v24, v24 row_ror:2 row_mask:0xf bank_mask:0xf bound_ctrl:1
	s_nop 1
	v_add_f32_dpp v24, v24, v24 row_ror:1 row_mask:0xf bank_mask:0xf bound_ctrl:1
	s_nop 0
	v_readlane_b32 s66, v24, 0
	v_readlane_b32 s69, v24, 16
	v_readlane_b32 s67, v24, 32
	v_readlane_b32 s68, v24, 48
	s_and_saveexec_b64 s[4:5], s[0:1]
	s_cbranch_execz .LBB0_381
	s_lshl_b64 s[64:65], s[64:65], 2
	v_mov_b32_e32 v24, s69
	s_add_u32 s64, s16, s64
	v_add_f32_e32 v24, s66, v24
	s_addc_u32 s65, s17, s65
	v_add_f32_e32 v24, s67, v24
	v_add_f32_e32 v26, s68, v24
	v_mov_b64_e32 v[24:25], s[64:65]
	flat_atomic_add_f32 v[24:25], v26
.LBB0_381:
	s_or_b64 exec, exec, s[4:5]
	ds_read_b128 v[24:27], v130 offset:10400
	v_lshl_add_u64 v[28:29], v[54:55], 1, s[8:9]
	s_waitcnt lgkmcnt(0)
	v_pk_fma_f32 v[20:21], s[12:13], v[24:25], v[20:21]
	v_pk_fma_f32 v[22:23], s[12:13], v[26:27], v[22:23]
	global_store_dwordx4 v[52:53], v[20:23], off
	v_cvt_pk_bf16_f32 v24, v20, v21
	v_cvt_pk_bf16_f32 v25, v22, v23
	v_pk_mul_f32 v[20:21], v[20:21], v[20:21]
	v_pk_mul_f32 v[22:23], v[22:23], v[22:23]
	v_add_f32_e32 v20, v20, v21
	v_add_f32_e32 v20, v20, v22
	v_add_f32_e32 v20, v20, v23
	flat_store_dwordx2 v[28:29], v[24:25]
	s_nop 0
	v_add_f32_dpp v20, v20, v20 row_ror:8 row_mask:0xf bank_mask:0xf bound_ctrl:1
	s_nop 1
	v_add_f32_dpp v20, v20, v20 row_ror:4 row_mask:0xf bank_mask:0xf bound_ctrl:1
	s_nop 1
	v_add_f32_dpp v20, v20, v20 row_ror:2 row_mask:0xf bank_mask:0xf bound_ctrl:1
	s_nop 1
	v_add_f32_dpp v20, v20, v20 row_ror:1 row_mask:0xf bank_mask:0xf bound_ctrl:1
	s_nop 0
	v_readlane_b32 s64, v20, 0
	v_readlane_b32 s67, v20, 16
	v_readlane_b32 s65, v20, 32
	v_readlane_b32 s66, v20, 48
	s_and_saveexec_b64 s[4:5], s[0:1]
	s_cbranch_execz .LBB0_383
	s_lshl_b64 s[62:63], s[62:63], 2
	v_mov_b32_e32 v20, s67
	s_add_u32 s62, s16, s62
	v_add_f32_e32 v20, s64, v20
	s_addc_u32 s63, s17, s63
	v_add_f32_e32 v20, s65, v20
	v_add_f32_e32 v22, s66, v20
	v_mov_b64_e32 v[20:21], s[62:63]
	flat_atomic_add_f32 v[20:21], v22
.LBB0_383:
	s_or_b64 exec, exec, s[4:5]
	ds_read_b128 v[20:23], v130 offset:11440
	v_lshl_add_u64 v[24:25], v[50:51], 1, s[8:9]
	s_waitcnt lgkmcnt(0)
	v_pk_fma_f32 v[16:17], s[12:13], v[20:21], v[16:17]
	v_pk_fma_f32 v[18:19], s[12:13], v[22:23], v[18:19]
	global_store_dwordx4 v[48:49], v[16:19], off
	v_cvt_pk_bf16_f32 v20, v16, v17
	v_cvt_pk_bf16_f32 v21, v18, v19
	v_pk_mul_f32 v[16:17], v[16:17], v[16:17]
	v_pk_mul_f32 v[18:19], v[18:19], v[18:19]
	v_add_f32_e32 v16, v16, v17
	v_add_f32_e32 v16, v16, v18
	v_add_f32_e32 v16, v16, v19
	flat_store_dwordx2 v[24:25], v[20:21]
	s_nop 0
	v_add_f32_dpp v16, v16, v16 row_ror:8 row_mask:0xf bank_mask:0xf bound_ctrl:1
	s_nop 1
	v_add_f32_dpp v16, v16, v16 row_ror:4 row_mask:0xf bank_mask:0xf bound_ctrl:1
	s_nop 1
	v_add_f32_dpp v16, v16, v16 row_ror:2 row_mask:0xf bank_mask:0xf bound_ctrl:1
	s_nop 1
	v_add_f32_dpp v16, v16, v16 row_ror:1 row_mask:0xf bank_mask:0xf bound_ctrl:1
	s_nop 0
	v_readlane_b32 s62, v16, 0
	v_readlane_b32 s65, v16, 16
	v_readlane_b32 s63, v16, 32
	v_readlane_b32 s64, v16, 48
	s_and_saveexec_b64 s[4:5], s[0:1]
	s_cbranch_execz .LBB0_385
	s_lshl_b64 s[34:35], s[34:35], 2
	v_mov_b32_e32 v16, s65
	s_add_u32 s34, s16, s34
	v_add_f32_e32 v16, s62, v16
	s_addc_u32 s35, s17, s35
	v_add_f32_e32 v16, s63, v16
	v_add_f32_e32 v18, s64, v16
	v_mov_b64_e32 v[16:17], s[34:35]
	flat_atomic_add_f32 v[16:17], v18
; DEVI float fsig(float x) { return __builtin_amdgcn_rcpf(1.f + __expf(-x)); }
; DEVI float bflo(unsigned u) { return __uint_as_float(u << 16); }
; DEVI float bfhi(unsigned u) { return __uint_as_float(u & 0xffff0000u); }
; template <int EPI, int TS, bool VT>
; DEVI void gemm_epilogue(const Params& p, char* smem, f32x4 (&acc)[2][2][4][2], int m0, int n0, float scale, const float* ssin,
;                         float* ssout, u16* xbout, int wid, int lane, int wr, int wc, int fr, int fq) {
;     ...
;           if constexpr (EPI == E_RESID || EPI == E_PLEGATE) {
;             const float4 a = *(const float4*)(Tr + 4 * lane);
;             const size_t ro = (size_t)grow * 1024 + n0 + 4 * lane;
;             float4 x4 = xo[u];
;             if constexpr (EPI == E_PLEGATE) {
;               x4.x += bflo(pv[u].x) * fsig(a.x * rs);
;               x4.y += bfhi(pv[u].x) * fsig(a.y * rs);
;               x4.z += bflo(pv[u].y) * fsig(a.z * rs);
;               x4.w += bfhi(pv[u].y) * fsig(a.w * rs);
;             } else {
;               const float sc = fabsf(scale);
;               x4.x += sc * a.x; x4.y += sc * a.y; x4.z += sc * a.z; x4.w += sc * a.w;
;             }
;             st_nt16(p.x + ro, x4);
;             if (xbout) {
;               uint2 o;
;               o.x = pack2(x4.x, x4.y);
;               o.y = pack2(x4.z, x4.w);
;               st_nt8(xbout + ro, o);
;             }
;             if (ssout) {
;               const float ssq = wsum(x4.x * x4.x + x4.y * x4.y + x4.z * x4.z + x4.w * x4.w, lane);
;               if (lane == 0) atomicAdd(ssout + grow, ssq);
;             }
.LBB0_385:
	s_or_b64 exec, exec, s[4:5]
	ds_read_b128 v[16:19], v130 offset:12480
	v_lshl_add_u64 v[20:21], v[46:47], 1, s[8:9]
	s_waitcnt lgkmcnt(0)
	v_pk_fma_f32 v[12:13], s[12:13], v[16:17], v[12:13]
	v_pk_fma_f32 v[14:15], s[12:13], v[18:19], v[14:15]
	global_store_dwordx4 v[44:45], v[12:15], off
	v_cvt_pk_bf16_f32 v16, v12, v13
	v_cvt_pk_bf16_f32 v17, v14, v15
	v_pk_mul_f32 v[12:13], v[12:13], v[12:13]
	v_pk_mul_f32 v[14:15], v[14:15], v[14:15]
	v_add_f32_e32 v12, v12, v13
	v_add_f32_e32 v12, v12, v14
	v_add_f32_e32 v12, v12, v15
	flat_store_dwordx2 v[20:21], v[16:17]
	s_nop 0
	v_add_f32_dpp v12, v12, v12 row_ror:8 row_mask:0xf bank_mask:0xf bound_ctrl:1
	s_nop 1
	v_add_f32_dpp v12, v12, v12 row_ror:4 row_mask:0xf bank_mask:0xf bound_ctrl:1
	s_nop 1
	v_add_f32_dpp v12, v12, v12 row_ror:2 row_mask:0xf bank_mask:0xf bound_ctrl:1
	s_nop 1
	v_add_f32_dpp v12, v12, v12 row_ror:1 row_mask:0xf bank_mask:0xf bound_ctrl:1
	s_nop 0
	v_readlane_b32 s34, v12, 0
	v_readlane_b32 s63, v12, 16
	v_readlane_b32 s35, v12, 32
	v_readlane_b32 s62, v12, 48
	s_and_saveexec_b64 s[4:5], s[0:1]
	s_cbranch_execz .LBB0_387
	s_lshl_b64 s[30:31], s[30:31], 2
	v_mov_b32_e32 v12, s63
	s_add_u32 s30, s16, s30
	v_add_f32_e32 v12, s34, v12
	s_addc_u32 s31, s17, s31
	v_add_f32_e32 v12, s35, v12
	v_add_f32_e32 v14, s62, v12
	v_mov_b64_e32 v[12:13], s[30:31]
	flat_atomic_add_f32 v[12:13], v14
.LBB0_387:
	s_or_b64 exec, exec, s[4:5]
	ds_read_b128 v[12:15], v130 offset:13520
	v_lshl_add_u64 v[16:17], v[42:43], 1, s[8:9]
	s_waitcnt lgkmcnt(0)
	v_pk_fma_f32 v[8:9], s[12:13], v[12:13], v[8:9]
	v_pk_fma_f32 v[10:11], s[12:13], v[14:15], v[10:11]
	global_store_dwordx4 v[40:41], v[8:11], off
	v_cvt_pk_bf16_f32 v12, v8, v9
	v_cvt_pk_bf16_f32 v13, v10, v11
	v_pk_mul_f32 v[8:9], v[8:9], v[8:9]
	v_pk_mul_f32 v[10:11], v[10:11], v[10:11]
	v_add_f32_e32 v8, v8, v9
	v_add_f32_e32 v8, v8, v10
	v_add_f32_e32 v8, v8, v11
	flat_store_dwordx2 v[16:17], v[12:13]
	s_nop 0
	v_add_f32_dpp v8, v8, v8 row_ror:8 row_mask:0xf bank_mask:0xf bound_ctrl:1
	s_nop 1
	v_add_f32_dpp v8, v8, v8 row_ror:4 row_mask:0xf bank_mask:0xf bound_ctrl:1
	s_nop 1
	v_add_f32_dpp v8, v8, v8 row_ror:2 row_mask:0xf bank_mask:0xf bound_ctrl:1
	s_nop 1
	v_add_f32_dpp v8, v8, v8 row_ror:1 row_mask:0xf bank_mask:0xf bound_ctrl:1
	s_nop 0
	v_readlane_b32 s30, v8, 0
	v_readlane_b32 s35, v8, 16
	v_readlane_b32 s31, v8, 32
	v_readlane_b32 s34, v8, 48
	s_and_saveexec_b64 s[4:5], s[0:1]
	s_cbranch_execz .LBB0_389
	s_lshl_b64 s[22:23], s[22:23], 2
	v_mov_b32_e32 v8, s35
	s_add_u32 s22, s16, s22
	v_add_f32_e32 v8, s30, v8
	s_addc_u32 s23, s17, s23
	v_add_f32_e32 v8, s31, v8
	v_add_f32_e32 v10, s34, v8
	v_mov_b64_e32 v[8:9], s[22:23]
	flat_atomic_add_f32 v[8:9], v10
.LBB0_389:
	s_or_b64 exec, exec, s[4:5]
	ds_read_b128 v[8:11], v130 offset:14560
	v_lshl_add_u64 v[12:13], v[38:39], 1, s[8:9]
	s_waitcnt lgkmcnt(0)
	v_pk_fma_f32 v[4:5], s[12:13], v[8:9], v[4:5]
	v_pk_fma_f32 v[6:7], s[12:13], v[10:11], v[6:7]
	global_store_dwordx4 v[36:37], v[4:7], off
	v_cvt_pk_bf16_f32 v8, v4, v5
	v_cvt_pk_bf16_f32 v9, v6, v7
	v_pk_mul_f32 v[4:5], v[4:5], v[4:5]
	v_pk_mul_f32 v[6:7], v[6:7], v[6:7]
	v_add_f32_e32 v4, v4, v5
	v_add_f32_e32 v4, v4, v6
	v_add_f32_e32 v4, v4, v7
	flat_store_dwordx2 v[12:13], v[8:9]
	s_nop 0
	v_add_f32_dpp v4, v4, v4 row_ror:8 row_mask:0xf bank_mask:0xf bound_ctrl:1
	s_nop 1
	v_add_f32_dpp v4, v4, v4 row_ror:4 row_mask:0xf bank_mask:0xf bound_ctrl:1
	s_nop 1
	v_add_f32_dpp v4, v4, v4 row_ror:2 row_mask:0xf bank_mask:0xf bound_ctrl:1
	s_nop 1
	v_add_f32_dpp v4, v4, v4 row_ror:1 row_mask:0xf bank_mask:0xf bound_ctrl:1
	s_nop 0
	v_readlane_b32 s22, v4, 0
	v_readlane_b32 s31, v4, 16
	v_readlane_b32 s23, v4, 32
	v_readlane_b32 s30, v4, 48
	s_and_saveexec_b64 s[4:5], s[0:1]
	s_cbranch_execz .LBB0_391
	s_lshl_b64 s[20:21], s[20:21], 2
	v_mov_b32_e32 v4, s31
	s_add_u32 s20, s16, s20
	v_add_f32_e32 v4, s22, v4
	s_addc_u32 s21, s17, s21
	v_add_f32_e32 v4, s23, v4
	v_add_f32_e32 v6, s30, v4
	v_mov_b64_e32 v[4:5], s[20:21]
	flat_atomic_add_f32 v[4:5], v6
.LBB0_391:
	s_or_b64 exec, exec, s[4:5]
	ds_read_b128 v[4:7], v130 offset:15600
	v_lshl_add_u64 v[8:9], v[34:35], 1, s[8:9]
	s_waitcnt lgkmcnt(0)
	v_pk_fma_f32 v[0:1], s[12:13], v[4:5], v[0:1]
	v_pk_fma_f32 v[2:3], s[12:13], v[6:7], v[2:3]
	global_store_dwordx4 v[32:33], v[0:3], off
	v_cvt_pk_bf16_f32 v4, v0, v1
	v_cvt_pk_bf16_f32 v5, v2, v3
	v_pk_mul_f32 v[0:1], v[0:1], v[0:1]
	v_pk_mul_f32 v[2:3], v[2:3], v[2:3]
	v_add_f32_e32 v0, v0, v1
	v_add_f32_e32 v0, v0, v2
	v_add_f32_e32 v0, v0, v3
	flat_store_dwordx2 v[8:9], v[4:5]
	s_nop 0
	v_add_f32_dpp v0, v0, v0 row_ror:8 row_mask:0xf bank_mask:0xf bound_ctrl:1
	s_nop 1
	v_add_f32_dpp v0, v0, v0 row_ror:4 row_mask:0xf bank_mask:0xf bound_ctrl:1
	s_nop 1
	v_add_f32_dpp v0, v0, v0 row_ror:2 row_mask:0xf bank_mask:0xf bound_ctrl:1
	s_nop 1
	v_add_f32_dpp v0, v0, v0 row_ror:1 row_mask:0xf bank_mask:0xf bound_ctrl:1
	s_nop 0
	v_readlane_b32 s20, v0, 0
	v_readlane_b32 s23, v0, 16
	v_readlane_b32 s21, v0, 32
	v_readlane_b32 s22, v0, 48
	s_and_saveexec_b64 s[4:5], s[0:1]
	s_cbranch_execz .LBB0_160
	s_lshl_b64 s[0:1], s[18:19], 2
	v_mov_b32_e32 v0, s23
	s_add_u32 s0, s16, s0
	v_add_f32_e32 v0, s20, v0
	s_addc_u32 s1, s17, s1
	v_add_f32_e32 v0, s21, v0
	v_add_f32_e32 v2, s22, v0
	v_mov_b64_e32 v[0:1], s[0:1]
	flat_atomic_add_f32 v[0:1], v2
	s_branch .LBB0_160

; template <int EPI, int TS, bool VT>
; DEVI void gemm_epilogue(const Params& p, char* smem, f32x4 (&acc)[2][2][4][2], int m0, int n0, float scale, const float* ssin,
;                         float* ssout, u16* xbout, int wid, int lane, int wr, int wc, int fr, int fq) {
;     ...
;       float* tw = T + (wr * 64 + fq * 4) * TS + wc * 32 + fr;
; #pragma unroll
;       for (int m = 0; m < 4; ++m)
; #pragma unroll
;         for (int j = 0; j < 4; ++j)
; #pragma unroll
;           for (int v = 0; v < 4; ++v) tw[(m * 16 + j) * TS + (v >> 1) * 128 + (v & 1) * 16] = acc[ai][v >> 1][m][v & 1][j];
;     }
;     __syncthreads();
;     const int r0 = wid * 16;
;     const int g0 = m0 + ai * 128 + r0;
;     if constexpr (!VT) {
;       float rsv = 1.f;
;       if constexpr (EPI == E_PLEGATE || EPI == E_F32 || EPI == E_SWIGLU || EPI == E_GLAIN)
;         rsv = rsqrtf(ssin[g0 + (lane & 15)] * (1.f / 1024.f) + EPS);
;       if constexpr (EPI == E_QROPE) rsv = rsqrtf(ssin[g0 + (lane & 15)] * (1.f / 384.f) + EPS);
;       if constexpr (EPI == E_KV) rsv = rsqrtf(ssin[g0 + (lane & 15)] * (1.f / 256.f) + EPS);
;     ...
;           } else if constexpr (EPI == E_KV) {
;             const float4 a = *(const float4*)(Tr + 4 * lane);
;             uint2 o;
;             o.x = pack2(a.x * rs, a.y * rs);
;             o.y = pack2(a.z * rs, a.w * rs);
;             st_nt8((u16*)(wsb + OFF_KM) + (size_t)grow * 1024 + n0 + 4 * lane, o);
;           }
.LBB0_911:
	s_lshl_b32 s2, s63, 6
	v_and_b32_e32 v131, 63, v128
	s_lshl_b32 s15, s15, 7
	v_lshrrev_b32_e32 v128, 2, v128
	s_cmp_lt_i32 s44, 4
	v_and_or_b32 v132, v128, 12, s2
	s_mov_b64 s[2:3], -1
	v_lshlrev_b32_e32 v133, 2, v130
	s_cbranch_scc0 .LBB0_913
	v_readlane_b32 s18, v254, 13
	s_movk_i32 s2, 0x410
	v_readlane_b32 s19, v254, 14
	v_mul_lo_u32 v128, v132, s2
	s_lshl_b32 s2, s13, 4
	s_add_i32 s2, s2, s12
	s_lshl_b64 s[20:21], s[0:1], 1
	s_add_u32 s18, s18, s20
	v_or_b32_e32 v156, s2, v130
	v_add3_u32 v135, s15, v128, v133
	s_addc_u32 s19, s19, s21
	v_lshlrev_b32_e32 v148, 3, v131
	v_ashrrev_i32_e32 v157, 31, v156
	v_lshl_add_u64 v[128:129], s[18:19], 0, v[148:149]
	v_add_u32_e32 v136, 0x400, v135
	v_add_u32_e32 v137, 0x800, v135
	v_add_u32_e32 v138, 0xc00, v135
	v_add_u32_e32 v139, 0x4000, v135
	v_add_u32_e32 v140, 0x4400, v135
	v_add_u32_e32 v141, 0x4800, v135
	v_add_u32_e32 v142, 0x4c00, v135
	v_add_u32_e32 v143, 0x8000, v135
	v_add_u32_e32 v144, 0x8400, v135
	v_add_u32_e32 v145, 0x8800, v135
	v_add_u32_e32 v146, 0x8c00, v135
	v_add_u32_e32 v147, 0x9000, v135
	v_add_u32_e32 v148, 0xc000, v135
	v_add_u32_e32 v152, 0xc400, v135
	v_add_u32_e32 v153, 0xc800, v135
	v_add_u32_e32 v154, 0xcc00, v135
	v_add_u32_e32 v155, 0xd000, v135
	v_lshl_add_u64 v[156:157], v[156:157], 2, s[8:9]
	ds_write2_b32 v135, v88, v96 offset1:16
	ds_write2_b32 v135, v120, v124 offset0:128 offset1:144
	ds_write2_b32 v136, v89, v97 offset0:4 offset1:20
	ds_write2_b32 v136, v121, v125 offset0:132 offset1:148
	ds_write2_b32 v137, v90, v98 offset0:8 offset1:24
	ds_write2_b32 v137, v122, v126 offset0:136 offset1:152
	ds_write2_b32 v138, v91, v99 offset0:12 offset1:28
	ds_write2_b32 v138, v123, v127 offset0:140 offset1:156
	ds_write2_b32 v139, v80, v84 offset0:64 offset1:80
	ds_write2_b32 v139, v112, v116 offset0:192 offset1:208
	ds_write2_b32 v140, v81, v85 offset0:68 offset1:84
	ds_write2_b32 v140, v113, v117 offset0:196 offset1:212
	ds_write2_b32 v141, v82, v86 offset0:72 offset1:88
	ds_write2_b32 v141, v114, v118 offset0:200 offset1:216
	ds_write2_b32 v142, v83, v87 offset0:76 offset1:92
	ds_write2_b32 v142, v115, v119 offset0:204 offset1:220
	ds_write2_b32 v143, v72, v76 offset0:128 offset1:144
	ds_write2_b32 v144, v104, v108 offset1:16
	ds_write2_b32 v144, v73, v77 offset0:132 offset1:148
	ds_write2_b32 v145, v105, v109 offset0:4 offset1:20
	ds_write2_b32 v145, v74, v78 offset0:136 offset1:152
	ds_write2_b32 v146, v106, v110 offset0:8 offset1:24
	ds_write2_b32 v146, v75, v79 offset0:140 offset1:156
	ds_write2_b32 v147, v107, v111 offset0:12 offset1:28
	ds_write2_b32 v148, v64, v68 offset0:192 offset1:208
	ds_write2_b32 v152, v92, v100 offset0:64 offset1:80
	ds_write2_b32 v152, v65, v69 offset0:196 offset1:212
	ds_write2_b32 v153, v93, v101 offset0:68 offset1:84
	ds_write2_b32 v153, v66, v70 offset0:200 offset1:216
	ds_write2_b32 v154, v94, v102 offset0:72 offset1:88
	ds_write2_b32 v154, v67, v71 offset0:204 offset1:220
	ds_write2_b32 v155, v95, v103 offset0:76 offset1:92
	s_waitcnt vmcnt(0) lgkmcnt(0)
	s_barrier
	flat_load_dword v134, v[156:157]
	s_mul_i32 s1, s13, 0x4100
	s_mov_b64 s[18:19], 0x29d5ee00
	v_lshl_add_u64 v[128:129], v[128:129], 0, s[18:19]
	s_ashr_i32 s3, s2, 31
	s_waitcnt vmcnt(0) lgkmcnt(0)
	v_fmamk_f32 v134, v134, 0x3b800000, v150
	v_cmp_gt_f32_e32 vcc, s29, v134
	v_mul_f32_e32 v156, 0x4b800000, v134
	s_nop 0
	v_cndmask_b32_e32 v134, v134, v156, vcc
	v_rsq_f32_e32 v134, v134
	s_nop 0
	v_mul_f32_e32 v156, 0x45800000, v134
	v_cndmask_b32_e32 v156, v134, v156, vcc
	v_lshl_add_u32 v134, v131, 4, s1
	ds_read_b128 v[158:161], v134
	v_readlane_b32 s18, v156, 0
	v_readlane_b32 s20, v156, 1
	s_waitcnt lgkmcnt(0)
	v_pk_mul_f32 v[158:159], s[18:19], v[158:159] op_sel_hi:[0,1]
	v_pk_mul_f32 v[160:161], s[18:19], v[160:161] op_sel_hi:[0,1]
	s_lshl_b64 s[18:19], s[2:3], 11
	v_cvt_pk_bf16_f32 v158, v158, v159
	v_cvt_pk_bf16_f32 v159, v160, v161
	v_lshl_add_u64 v[160:161], v[128:129], 0, s[18:19]
	flat_store_dwordx2 v[160:161], v[158:159]
	ds_read_b128 v[158:161], v134 offset:1040
	s_or_b32 s18, s2, 1
	s_ashr_i32 s19, s18, 31
	s_lshl_b64 s[18:19], s[18:19], 11
	s_waitcnt lgkmcnt(0)
	v_pk_mul_f32 v[158:159], s[20:21], v[158:159] op_sel_hi:[0,1]
	v_pk_mul_f32 v[160:161], s[20:21], v[160:161] op_sel_hi:[0,1]
	v_cvt_pk_bf16_f32 v158, v158, v159
	v_cvt_pk_bf16_f32 v159, v160, v161
	v_lshl_add_u64 v[160:161], v[128:129], 0, s[18:19]
	flat_store_dwordx2 v[160:161], v[158:159]
	ds_read_b128 v[158:161], v134 offset:2080
	s_or_b32 s18, s2, 2
	v_readlane_b32 s20, v156, 2
	s_ashr_i32 s19, s18, 31
	s_lshl_b64 s[18:19], s[18:19], 11
	s_waitcnt lgkmcnt(0)
	v_pk_mul_f32 v[158:159], s[20:21], v[158:159] op_sel_hi:[0,1]
	v_pk_mul_f32 v[160:161], s[20:21], v[160:161] op_sel_hi:[0,1]
	v_cvt_pk_bf16_f32 v158, v158, v159
	v_cvt_pk_bf16_f32 v159, v160, v161
	v_lshl_add_u64 v[160:161], v[128:129], 0, s[18:19]
	flat_store_dwordx2 v[160:161], v[158:159]
	ds_read_b128 v[158:161], v134 offset:3120
	s_or_b32 s18, s2, 3
	v_readlane_b32 s20, v156, 3
	s_ashr_i32 s19, s18, 31
	s_lshl_b64 s[18:19], s[18:19], 11
	s_waitcnt lgkmcnt(0)
	v_pk_mul_f32 v[158:159], s[20:21], v[158:159] op_sel_hi:[0,1]
	v_pk_mul_f32 v[160:161], s[20:21], v[160:161] op_sel_hi:[0,1]
	v_cvt_pk_bf16_f32 v158, v158, v159
	v_cvt_pk_bf16_f32 v159, v160, v161
	v_lshl_add_u64 v[160:161], v[128:129], 0, s[18:19]
	flat_store_dwordx2 v[160:161], v[158:159]
	ds_read_b128 v[158:161], v134 offset:4160
	s_or_b32 s18, s2, 4
	v_readlane_b32 s20, v156, 4
	s_ashr_i32 s19, s18, 31
	s_lshl_b64 s[18:19], s[18:19], 11
	s_waitcnt lgkmcnt(0)
; template <int EPI, int TS, bool VT>
; DEVI void gemm_epilogue(const Params& p, char* smem, f32x4 (&acc)[2][2][4][2], int m0, int n0, float scale, const float* ssin,
;                         float* ssout, u16* xbout, int wid, int lane, int wr, int wc, int fr, int fq) {
;     ...
;           } else if constexpr (EPI == E_KV) {
;             const float4 a = *(const float4*)(Tr + 4 * lane);
;             uint2 o;
;             o.x = pack2(a.x * rs, a.y * rs);
;             o.y = pack2(a.z * rs, a.w * rs);
;             st_nt8((u16*)(wsb + OFF_KM) + (size_t)grow * 1024 + n0 + 4 * lane, o);
;           }
	v_pk_mul_f32 v[158:159], s[20:21], v[158:159] op_sel_hi:[0,1]
	v_pk_mul_f32 v[160:161], s[20:21], v[160:161] op_sel_hi:[0,1]
	v_cvt_pk_bf16_f32 v158, v158, v159
	v_cvt_pk_bf16_f32 v159, v160, v161
	v_lshl_add_u64 v[160:161], v[128:129], 0, s[18:19]
	flat_store_dwordx2 v[160:161], v[158:159]
	ds_read_b128 v[158:161], v134 offset:5200
	s_or_b32 s18, s2, 5
	v_readlane_b32 s20, v156, 5
	s_ashr_i32 s19, s18, 31
	s_lshl_b64 s[18:19], s[18:19], 11
	s_waitcnt lgkmcnt(0)
	v_pk_mul_f32 v[158:159], s[20:21], v[158:159] op_sel_hi:[0,1]
	v_pk_mul_f32 v[160:161], s[20:21], v[160:161] op_sel_hi:[0,1]
	v_cvt_pk_bf16_f32 v158, v158, v159
	v_cvt_pk_bf16_f32 v159, v160, v161
	v_lshl_add_u64 v[160:161], v[128:129], 0, s[18:19]
	flat_store_dwordx2 v[160:161], v[158:159]
	ds_read_b128 v[158:161], v134 offset:6240
	s_or_b32 s18, s2, 6
	v_readlane_b32 s20, v156, 6
	s_ashr_i32 s19, s18, 31
	s_lshl_b64 s[18:19], s[18:19], 11
	s_waitcnt lgkmcnt(0)
	v_pk_mul_f32 v[158:159], s[20:21], v[158:159] op_sel_hi:[0,1]
	v_pk_mul_f32 v[160:161], s[20:21], v[160:161] op_sel_hi:[0,1]
	v_cvt_pk_bf16_f32 v158, v158, v159
	v_cvt_pk_bf16_f32 v159, v160, v161
	v_lshl_add_u64 v[160:161], v[128:129], 0, s[18:19]
	flat_store_dwordx2 v[160:161], v[158:159]
	ds_read_b128 v[158:161], v134 offset:7280
	s_or_b32 s18, s2, 7
	v_readlane_b32 s20, v156, 7
	s_ashr_i32 s19, s18, 31
	s_lshl_b64 s[18:19], s[18:19], 11
	s_waitcnt lgkmcnt(0)
	v_pk_mul_f32 v[158:159], s[20:21], v[158:159] op_sel_hi:[0,1]
	v_pk_mul_f32 v[160:161], s[20:21], v[160:161] op_sel_hi:[0,1]
	v_cvt_pk_bf16_f32 v158, v158, v159
	v_cvt_pk_bf16_f32 v159, v160, v161
	v_lshl_add_u64 v[160:161], v[128:129], 0, s[18:19]
	flat_store_dwordx2 v[160:161], v[158:159]
	ds_read_b128 v[158:161], v134 offset:8320
	s_or_b32 s18, s2, 8
	v_readlane_b32 s20, v156, 8
	s_ashr_i32 s19, s18, 31
	s_lshl_b64 s[18:19], s[18:19], 11
	s_waitcnt lgkmcnt(0)
	v_pk_mul_f32 v[158:159], s[20:21], v[158:159] op_sel_hi:[0,1]
	v_pk_mul_f32 v[160:161], s[20:21], v[160:161] op_sel_hi:[0,1]
	v_cvt_pk_bf16_f32 v158, v158, v159
	v_cvt_pk_bf16_f32 v159, v160, v161
	v_lshl_add_u64 v[160:161], v[128:129], 0, s[18:19]
	flat_store_dwordx2 v[160:161], v[158:159]
	ds_read_b128 v[158:161], v134 offset:9360
	s_or_b32 s18, s2, 9
	v_readlane_b32 s20, v156, 9
	s_ashr_i32 s19, s18, 31
	s_lshl_b64 s[18:19], s[18:19], 11
	s_waitcnt lgkmcnt(0)
	v_pk_mul_f32 v[158:159], s[20:21], v[158:159] op_sel_hi:[0,1]
	v_pk_mul_f32 v[160:161], s[20:21], v[160:161] op_sel_hi:[0,1]
	v_cvt_pk_bf16_f32 v158, v158, v159
	v_cvt_pk_bf16_f32 v159, v160, v161
	v_lshl_add_u64 v[160:161], v[128:129], 0, s[18:19]
	flat_store_dwordx2 v[160:161], v[158:159]
	ds_read_b128 v[158:161], v134 offset:10400
	s_or_b32 s18, s2, 10
	v_readlane_b32 s20, v156, 10
	s_ashr_i32 s19, s18, 31
	s_lshl_b64 s[18:19], s[18:19], 11
	s_waitcnt lgkmcnt(0)
	v_pk_mul_f32 v[158:159], s[20:21], v[158:159] op_sel_hi:[0,1]
	v_pk_mul_f32 v[160:161], s[20:21], v[160:161] op_sel_hi:[0,1]
	v_cvt_pk_bf16_f32 v158, v158, v159
	v_cvt_pk_bf16_f32 v159, v160, v161
	v_lshl_add_u64 v[160:161], v[128:129], 0, s[18:19]
	flat_store_dwordx2 v[160:161], v[158:159]
	ds_read_b128 v[158:161], v134 offset:11440
	s_or_b32 s18, s2, 11
	v_readlane_b32 s20, v156, 11
	s_ashr_i32 s19, s18, 31
	s_lshl_b64 s[18:19], s[18:19], 11
	s_waitcnt lgkmcnt(0)
	v_pk_mul_f32 v[158:159], s[20:21], v[158:159] op_sel_hi:[0,1]
	v_pk_mul_f32 v[160:161], s[20:21], v[160:161] op_sel_hi:[0,1]
	v_cvt_pk_bf16_f32 v158, v158, v159
	v_cvt_pk_bf16_f32 v159, v160, v161
	v_lshl_add_u64 v[160:161], v[128:129], 0, s[18:19]
	flat_store_dwordx2 v[160:161], v[158:159]
	ds_read_b128 v[158:161], v134 offset:12480
	s_or_b32 s18, s2, 12
	v_readlane_b32 s20, v156, 12
	s_ashr_i32 s19, s18, 31
	s_lshl_b64 s[18:19], s[18:19], 11
	s_waitcnt lgkmcnt(0)
	v_pk_mul_f32 v[158:159], s[20:21], v[158:159] op_sel_hi:[0,1]
	v_pk_mul_f32 v[160:161], s[20:21], v[160:161] op_sel_hi:[0,1]
	v_cvt_pk_bf16_f32 v158, v158, v159
	v_cvt_pk_bf16_f32 v159, v160, v161
	v_lshl_add_u64 v[160:161], v[128:129], 0, s[18:19]
	flat_store_dwordx2 v[160:161], v[158:159]
	ds_read_b128 v[158:161], v134 offset:13520
	s_or_b32 s18, s2, 13
	v_readlane_b32 s20, v156, 13
	s_ashr_i32 s19, s18, 31
	s_lshl_b64 s[18:19], s[18:19], 11
	s_waitcnt lgkmcnt(0)
	v_pk_mul_f32 v[158:159], s[20:21], v[158:159] op_sel_hi:[0,1]
	v_pk_mul_f32 v[160:161], s[20:21], v[160:161] op_sel_hi:[0,1]
	v_cvt_pk_bf16_f32 v158, v158, v159
	v_cvt_pk_bf16_f32 v159, v160, v161
	v_lshl_add_u64 v[160:161], v[128:129], 0, s[18:19]
	flat_store_dwordx2 v[160:161], v[158:159]
	ds_read_b128 v[158:161], v134 offset:14560
	s_or_b32 s18, s2, 14
	v_readlane_b32 s20, v156, 14
	s_ashr_i32 s19, s18, 31
	s_lshl_b64 s[18:19], s[18:19], 11
	s_waitcnt lgkmcnt(0)
	v_pk_mul_f32 v[158:159], s[20:21], v[158:159] op_sel_hi:[0,1]
	v_pk_mul_f32 v[160:161], s[20:21], v[160:161] op_sel_hi:[0,1]
	v_cvt_pk_bf16_f32 v158, v158, v159
	v_cvt_pk_bf16_f32 v159, v160, v161
	v_lshl_add_u64 v[160:161], v[128:129], 0, s[18:19]
	flat_store_dwordx2 v[160:161], v[158:159]
	v_readlane_b32 s20, v156, 15
	ds_read_b128 v[156:159], v134 offset:15600
	s_or_b32 s18, s2, 15
	s_ashr_i32 s19, s18, 31
	s_lshl_b64 s[18:19], s[18:19], 11
	s_waitcnt lgkmcnt(0)
	v_pk_mul_f32 v[156:157], s[20:21], v[156:157] op_sel_hi:[0,1]
	v_pk_mul_f32 v[158:159], s[20:21], v[158:159] op_sel_hi:[0,1]
	v_cvt_pk_bf16_f32 v156, v156, v157
	v_cvt_pk_bf16_f32 v157, v158, v159
	v_lshl_add_u64 v[158:159], v[128:129], 0, s[18:19]
	s_add_i32 s18, s2, 0x80
	flat_store_dwordx2 v[158:159], v[156:157]
	s_waitcnt lgkmcnt(0)
	s_barrier
; template <int EPI, int TS, bool VT>
; DEVI void gemm_epilogue(const Params& p, char* smem, f32x4 (&acc)[2][2][4][2], int m0, int n0, float scale, const float* ssin,
;                         float* ssout, u16* xbout, int wid, int lane, int wr, int wc, int fr, int fq) {
;     ...
;       float* tw = T + (wr * 64 + fq * 4) * TS + wc * 32 + fr;
; #pragma unroll
;       for (int m = 0; m < 4; ++m)
; #pragma unroll
;         for (int j = 0; j < 4; ++j)
; #pragma unroll
;           for (int v = 0; v < 4; ++v) tw[(m * 16 + j) * TS + (v >> 1) * 128 + (v & 1) * 16] = acc[ai][v >> 1][m][v & 1][j];
;     }
;     __syncthreads();
;     const int r0 = wid * 16;
;     const int g0 = m0 + ai * 128 + r0;
;     if constexpr (!VT) {
;       float rsv = 1.f;
;       if constexpr (EPI == E_PLEGATE || EPI == E_F32 || EPI == E_SWIGLU || EPI == E_GLAIN)
;         rsv = rsqrtf(ssin[g0 + (lane & 15)] * (1.f / 1024.f) + EPS);
;       if constexpr (EPI == E_QROPE) rsv = rsqrtf(ssin[g0 + (lane & 15)] * (1.f / 384.f) + EPS);
;       if constexpr (EPI == E_KV) rsv = rsqrtf(ssin[g0 + (lane & 15)] * (1.f / 256.f) + EPS);
;     ...
;           } else if constexpr (EPI == E_KV) {
;             const float4 a = *(const float4*)(Tr + 4 * lane);
;             uint2 o;
;             o.x = pack2(a.x * rs, a.y * rs);
;             o.y = pack2(a.z * rs, a.w * rs);
;             st_nt8((u16*)(wsb + OFF_KM) + (size_t)grow * 1024 + n0 + 4 * lane, o);
;           }
	ds_write2_b32 v135, v24, v28 offset1:16
	ds_write2_b32 v135, v56, v60 offset0:128 offset1:144
	ds_write2_b32 v136, v25, v29 offset0:4 offset1:20
	ds_write2_b32 v136, v57, v61 offset0:132 offset1:148
	ds_write2_b32 v137, v26, v30 offset0:8 offset1:24
	ds_write2_b32 v137, v58, v62 offset0:136 offset1:152
	ds_write2_b32 v138, v27, v31 offset0:12 offset1:28
	ds_write2_b32 v138, v59, v63 offset0:140 offset1:156
	ds_write2_b32 v139, v16, v20 offset0:64 offset1:80
	ds_write2_b32 v139, v48, v52 offset0:192 offset1:208
	ds_write2_b32 v140, v17, v21 offset0:68 offset1:84
	ds_write2_b32 v140, v49, v53 offset0:196 offset1:212
	ds_write2_b32 v141, v18, v22 offset0:72 offset1:88
	ds_write2_b32 v141, v50, v54 offset0:200 offset1:216
	ds_write2_b32 v142, v19, v23 offset0:76 offset1:92
	ds_write2_b32 v142, v51, v55 offset0:204 offset1:220
	ds_write2_b32 v143, v8, v12 offset0:128 offset1:144
	ds_write2_b32 v144, v40, v44 offset1:16
	ds_write2_b32 v144, v9, v13 offset0:132 offset1:148
	ds_write2_b32 v145, v41, v45 offset0:4 offset1:20
	ds_write2_b32 v145, v10, v14 offset0:136 offset1:152
	ds_write2_b32 v146, v42, v46 offset0:8 offset1:24
	ds_write2_b32 v146, v11, v15 offset0:140 offset1:156
	ds_write2_b32 v147, v43, v47 offset0:12 offset1:28
	ds_write2_b32 v148, v0, v4 offset0:192 offset1:208
	ds_write2_b32 v152, v32, v36 offset0:64 offset1:80
	ds_write2_b32 v152, v1, v5 offset0:196 offset1:212
	ds_write2_b32 v153, v33, v37 offset0:68 offset1:84
	ds_write2_b32 v153, v2, v6 offset0:200 offset1:216
	ds_write2_b32 v154, v34, v38 offset0:72 offset1:88
	ds_write2_b32 v154, v3, v7 offset0:204 offset1:220
	ds_write2_b32 v155, v35, v39 offset0:76 offset1:92
	v_or_b32_e32 v136, s18, v130
	v_ashrrev_i32_e32 v137, 31, v136
	v_lshl_add_u64 v[136:137], v[136:137], 2, s[8:9]
	s_waitcnt lgkmcnt(0)
	s_barrier
	flat_load_dword v130, v[136:137]
	ds_read_b128 v[136:139], v134
	s_ashr_i32 s19, s18, 31
	s_lshl_b64 s[18:19], s[18:19], 11
	s_waitcnt vmcnt(0) lgkmcnt(0)
	v_fmamk_f32 v130, v130, 0x3b800000, v150
	v_cmp_gt_f32_e32 vcc, s29, v130
	v_mul_f32_e32 v135, 0x4b800000, v130
	s_nop 0
	v_cndmask_b32_e32 v130, v130, v135, vcc
	v_rsq_f32_e32 v130, v130
	s_nop 0
	v_mul_f32_e32 v135, 0x45800000, v130
	v_cndmask_b32_e32 v130, v130, v135, vcc
	s_nop 0
	v_readlane_b32 s20, v130, 0
	s_nop 1
	v_pk_mul_f32 v[136:137], s[20:21], v[136:137] op_sel_hi:[0,1]
	v_pk_mul_f32 v[138:139], s[20:21], v[138:139] op_sel_hi:[0,1]
	v_cvt_pk_bf16_f32 v136, v136, v137
	v_cvt_pk_bf16_f32 v137, v138, v139
	v_lshl_add_u64 v[138:139], v[128:129], 0, s[18:19]
	flat_store_dwordx2 v[138:139], v[136:137]
	ds_read_b128 v[136:139], v134 offset:1040
	s_add_i32 s18, s2, 0x81
	v_readlane_b32 s20, v130, 1
	s_ashr_i32 s19, s18, 31
	s_lshl_b64 s[18:19], s[18:19], 11
	s_waitcnt lgkmcnt(0)
	v_pk_mul_f32 v[136:137], s[20:21], v[136:137] op_sel_hi:[0,1]
	v_pk_mul_f32 v[138:139], s[20:21], v[138:139] op_sel_hi:[0,1]
	v_cvt_pk_bf16_f32 v136, v136, v137
	v_cvt_pk_bf16_f32 v137, v138, v139
	v_lshl_add_u64 v[138:139], v[128:129], 0, s[18:19]
	flat_store_dwordx2 v[138:139], v[136:137]
	ds_read_b128 v[136:139], v134 offset:2080
	s_add_i32 s18, s2, 0x82
	v_readlane_b32 s20, v130, 2
	s_ashr_i32 s19, s18, 31
	s_lshl_b64 s[18:19], s[18:19], 11
	s_waitcnt lgkmcnt(0)
	v_pk_mul_f32 v[136:137], s[20:21], v[136:137] op_sel_hi:[0,1]
	v_pk_mul_f32 v[138:139], s[20:21], v[138:139] op_sel_hi:[0,1]
	v_cvt_pk_bf16_f32 v136, v136, v137
	v_cvt_pk_bf16_f32 v137, v138, v139
	v_lshl_add_u64 v[138:139], v[128:129], 0, s[18:19]
	flat_store_dwordx2 v[138:139], v[136:137]
	ds_read_b128 v[136:139], v134 offset:3120
	s_add_i32 s18, s2, 0x83
	v_readlane_b32 s20, v130, 3
	s_ashr_i32 s19, s18, 31
	s_lshl_b64 s[18:19], s[18:19], 11
	s_waitcnt lgkmcnt(0)
	v_pk_mul_f32 v[136:137], s[20:21], v[136:137] op_sel_hi:[0,1]
	v_pk_mul_f32 v[138:139], s[20:21], v[138:139] op_sel_hi:[0,1]
	v_cvt_pk_bf16_f32 v136, v136, v137
	v_cvt_pk_bf16_f32 v137, v138, v139
	v_lshl_add_u64 v[138:139], v[128:129], 0, s[18:19]
	flat_store_dwordx2 v[138:139], v[136:137]
	ds_read_b128 v[136:139], v134 offset:4160
	s_add_i32 s18, s2, 0x84
	v_readlane_b32 s20, v130, 4
	s_ashr_i32 s19, s18, 31
	s_lshl_b64 s[18:19], s[18:19], 11
	s_waitcnt lgkmcnt(0)
	v_pk_mul_f32 v[136:137], s[20:21], v[136:137] op_sel_hi:[0,1]
	v_pk_mul_f32 v[138:139], s[20:21], v[138:139] op_sel_hi:[0,1]
	v_cvt_pk_bf16_f32 v136, v136, v137
	v_cvt_pk_bf16_f32 v137, v138, v139
	v_lshl_add_u64 v[138:139], v[128:129], 0, s[18:19]
	flat_store_dwordx2 v[138:139], v[136:137]
	ds_read_b128 v[136:139], v134 offset:5200
	s_add_i32 s18, s2, 0x85
	v_readlane_b32 s20, v130, 5
	s_ashr_i32 s19, s18, 31
	s_lshl_b64 s[18:19], s[18:19], 11
	s_waitcnt lgkmcnt(0)
; template <int EPI, int TS, bool VT>
; DEVI void gemm_epilogue(const Params& p, char* smem, f32x4 (&acc)[2][2][4][2], int m0, int n0, float scale, const float* ssin,
;                         float* ssout, u16* xbout, int wid, int lane, int wr, int wc, int fr, int fq) {
;     ...
;           } else if constexpr (EPI == E_KV) {
;             const float4 a = *(const float4*)(Tr + 4 * lane);
;             uint2 o;
;             o.x = pack2(a.x * rs, a.y * rs);
;             o.y = pack2(a.z * rs, a.w * rs);
;             st_nt8((u16*)(wsb + OFF_KM) + (size_t)grow * 1024 + n0 + 4 * lane, o);
;           }
	v_pk_mul_f32 v[136:137], s[20:21], v[136:137] op_sel_hi:[0,1]
	v_pk_mul_f32 v[138:139], s[20:21], v[138:139] op_sel_hi:[0,1]
	v_cvt_pk_bf16_f32 v136, v136, v137
	v_cvt_pk_bf16_f32 v137, v138, v139
	v_lshl_add_u64 v[138:139], v[128:129], 0, s[18:19]
	flat_store_dwordx2 v[138:139], v[136:137]
	ds_read_b128 v[136:139], v134 offset:6240
	s_add_i32 s18, s2, 0x86
	v_readlane_b32 s20, v130, 6
	s_ashr_i32 s19, s18, 31
	s_lshl_b64 s[18:19], s[18:19], 11
	s_waitcnt lgkmcnt(0)
	v_pk_mul_f32 v[136:137], s[20:21], v[136:137] op_sel_hi:[0,1]
	v_pk_mul_f32 v[138:139], s[20:21], v[138:139] op_sel_hi:[0,1]
	v_cvt_pk_bf16_f32 v136, v136, v137
	v_cvt_pk_bf16_f32 v137, v138, v139
	v_lshl_add_u64 v[138:139], v[128:129], 0, s[18:19]
	flat_store_dwordx2 v[138:139], v[136:137]
	ds_read_b128 v[136:139], v134 offset:7280
	s_add_i32 s18, s2, 0x87
	v_readlane_b32 s20, v130, 7
	s_ashr_i32 s19, s18, 31
	s_lshl_b64 s[18:19], s[18:19], 11
	s_waitcnt lgkmcnt(0)
	v_pk_mul_f32 v[136:137], s[20:21], v[136:137] op_sel_hi:[0,1]
	v_pk_mul_f32 v[138:139], s[20:21], v[138:139] op_sel_hi:[0,1]
	v_cvt_pk_bf16_f32 v136, v136, v137
	v_cvt_pk_bf16_f32 v137, v138, v139
	v_lshl_add_u64 v[138:139], v[128:129], 0, s[18:19]
	flat_store_dwordx2 v[138:139], v[136:137]
	ds_read_b128 v[136:139], v134 offset:8320
	s_add_i32 s18, s2, 0x88
	v_readlane_b32 s20, v130, 8
	s_ashr_i32 s19, s18, 31
	s_lshl_b64 s[18:19], s[18:19], 11
	s_waitcnt lgkmcnt(0)
	v_pk_mul_f32 v[136:137], s[20:21], v[136:137] op_sel_hi:[0,1]
	v_pk_mul_f32 v[138:139], s[20:21], v[138:139] op_sel_hi:[0,1]
	v_cvt_pk_bf16_f32 v136, v136, v137
	v_cvt_pk_bf16_f32 v137, v138, v139
	v_lshl_add_u64 v[138:139], v[128:129], 0, s[18:19]
	flat_store_dwordx2 v[138:139], v[136:137]
	ds_read_b128 v[136:139], v134 offset:9360
	s_add_i32 s18, s2, 0x89
	v_readlane_b32 s20, v130, 9
	s_ashr_i32 s19, s18, 31
	s_lshl_b64 s[18:19], s[18:19], 11
	s_waitcnt lgkmcnt(0)
	v_pk_mul_f32 v[136:137], s[20:21], v[136:137] op_sel_hi:[0,1]
	v_pk_mul_f32 v[138:139], s[20:21], v[138:139] op_sel_hi:[0,1]
	v_cvt_pk_bf16_f32 v136, v136, v137
	v_cvt_pk_bf16_f32 v137, v138, v139
	v_lshl_add_u64 v[138:139], v[128:129], 0, s[18:19]
	flat_store_dwordx2 v[138:139], v[136:137]
	ds_read_b128 v[136:139], v134 offset:10400
	s_add_i32 s18, s2, 0x8a
	v_readlane_b32 s20, v130, 10
	s_ashr_i32 s19, s18, 31
	s_lshl_b64 s[18:19], s[18:19], 11
	s_waitcnt lgkmcnt(0)
	v_pk_mul_f32 v[136:137], s[20:21], v[136:137] op_sel_hi:[0,1]
	v_pk_mul_f32 v[138:139], s[20:21], v[138:139] op_sel_hi:[0,1]
	v_cvt_pk_bf16_f32 v136, v136, v137
	v_cvt_pk_bf16_f32 v137, v138, v139
	v_lshl_add_u64 v[138:139], v[128:129], 0, s[18:19]
	flat_store_dwordx2 v[138:139], v[136:137]
	ds_read_b128 v[136:139], v134 offset:11440
	s_add_i32 s18, s2, 0x8b
	v_readlane_b32 s20, v130, 11
	s_ashr_i32 s19, s18, 31
	s_lshl_b64 s[18:19], s[18:19], 11
	s_waitcnt lgkmcnt(0)
	v_pk_mul_f32 v[136:137], s[20:21], v[136:137] op_sel_hi:[0,1]
	v_pk_mul_f32 v[138:139], s[20:21], v[138:139] op_sel_hi:[0,1]
	v_cvt_pk_bf16_f32 v136, v136, v137
	v_cvt_pk_bf16_f32 v137, v138, v139
	v_lshl_add_u64 v[138:139], v[128:129], 0, s[18:19]
	flat_store_dwordx2 v[138:139], v[136:137]
	ds_read_b128 v[136:139], v134 offset:12480
	s_add_i32 s18, s2, 0x8c
	v_readlane_b32 s20, v130, 12
	s_ashr_i32 s19, s18, 31
	s_lshl_b64 s[18:19], s[18:19], 11
	s_waitcnt lgkmcnt(0)
	v_pk_mul_f32 v[136:137], s[20:21], v[136:137] op_sel_hi:[0,1]
	v_pk_mul_f32 v[138:139], s[20:21], v[138:139] op_sel_hi:[0,1]
	v_cvt_pk_bf16_f32 v136, v136, v137
	v_cvt_pk_bf16_f32 v137, v138, v139
	v_lshl_add_u64 v[138:139], v[128:129], 0, s[18:19]
	flat_store_dwordx2 v[138:139], v[136:137]
	ds_read_b128 v[136:139], v134 offset:13520
	s_add_i32 s18, s2, 0x8d
	v_readlane_b32 s20, v130, 13
	s_ashr_i32 s19, s18, 31
	s_lshl_b64 s[18:19], s[18:19], 11
	s_waitcnt lgkmcnt(0)
	v_pk_mul_f32 v[136:137], s[20:21], v[136:137] op_sel_hi:[0,1]
	v_pk_mul_f32 v[138:139], s[20:21], v[138:139] op_sel_hi:[0,1]
	v_cvt_pk_bf16_f32 v136, v136, v137
	v_cvt_pk_bf16_f32 v137, v138, v139
	v_lshl_add_u64 v[138:139], v[128:129], 0, s[18:19]
	flat_store_dwordx2 v[138:139], v[136:137]
	ds_read_b128 v[136:139], v134 offset:14560
	s_add_i32 s18, s2, 0x8e
	v_readlane_b32 s20, v130, 14
	s_ashr_i32 s19, s18, 31
	s_lshl_b64 s[18:19], s[18:19], 11
	s_waitcnt lgkmcnt(0)
	v_pk_mul_f32 v[136:137], s[20:21], v[136:137] op_sel_hi:[0,1]
	v_pk_mul_f32 v[138:139], s[20:21], v[138:139] op_sel_hi:[0,1]
	v_cvt_pk_bf16_f32 v136, v136, v137
	v_cvt_pk_bf16_f32 v137, v138, v139
	v_lshl_add_u64 v[138:139], v[128:129], 0, s[18:19]
	flat_store_dwordx2 v[138:139], v[136:137]
	ds_read_b128 v[134:137], v134 offset:15600
	s_addk_i32 s2, 0x8f
	v_readlane_b32 s18, v130, 15
	s_ashr_i32 s3, s2, 31
	s_lshl_b64 s[2:3], s[2:3], 11
	s_waitcnt lgkmcnt(0)
	v_pk_mul_f32 v[134:135], s[18:19], v[134:135] op_sel_hi:[0,1]
	v_pk_mul_f32 v[136:137], s[18:19], v[136:137] op_sel_hi:[0,1]
	v_cvt_pk_bf16_f32 v134, v134, v135
	v_cvt_pk_bf16_f32 v135, v136, v137
	v_lshl_add_u64 v[128:129], v[128:129], 0, s[2:3]
	flat_store_dwordx2 v[128:129], v[134:135]
	s_waitcnt lgkmcnt(0)
	s_barrier
	s_mov_b64 s[2:3], 0

; template <int EPI, int TS, bool VT>
; DEVI void gemm_epilogue(const Params& p, char* smem, f32x4 (&acc)[2][2][4][2], int m0, int n0, float scale, const float* ssin,
;                         float* ssout, u16* xbout, int wid, int lane, int wr, int wc, int fr, int fq) {
;     ...
;       float* tw = T + (wr * 64 + fq * 4) * TS + wc * 32 + fr;
; #pragma unroll
;       for (int m = 0; m < 4; ++m)
; #pragma unroll
;         for (int j = 0; j < 4; ++j)
; #pragma unroll
;           for (int v = 0; v < 4; ++v) tw[(m * 16 + j) * TS + (v >> 1) * 128 + (v & 1) * 16] = acc[ai][v >> 1][m][v & 1][j];
;     }
;     __syncthreads();
;     const int r0 = wid * 16;
;     const int g0 = m0 + ai * 128 + r0;
;     if constexpr (!VT) {
;       float rsv = 1.f;
;       if constexpr (EPI == E_PLEGATE || EPI == E_F32 || EPI == E_SWIGLU || EPI == E_GLAIN)
;         rsv = rsqrtf(ssin[g0 + (lane & 15)] * (1.f / 1024.f) + EPS);
;       if constexpr (EPI == E_QROPE) rsv = rsqrtf(ssin[g0 + (lane & 15)] * (1.f / 384.f) + EPS);
;       if constexpr (EPI == E_KV) rsv = rsqrtf(ssin[g0 + (lane & 15)] * (1.f / 256.f) + EPS);
;       for (int i0 = 0; i0 < 16; i0 += 8) {
;         float4 xo[8];
;         uint2 pv[8];
;         if constexpr (EPI == E_RESID || EPI == E_PLEGATE) {
; #pragma unroll
;           for (int u = 0; u < 8; ++u) {
;             const size_t ro = (size_t)(g0 + i0 + u) * 1024 + n0 + 4 * lane;
;             const int gr = g0 + i0 + u;
;             const float* xs = p.x + ro;
;             if (scale < 0.f)
;               xs = (gr < MP ? p.x_prompt + ro : p.x_sample + (ro - (size_t)MP * 1024));
;             { const f32x4 t_ = __builtin_nontemporal_load((const f32x4*)xs); xo[u] = make_float4(t_[0], t_[1], t_[2], t_[3]); }
;     ...
;           if constexpr (EPI == E_RESID || EPI == E_PLEGATE) {
;             const float4 a = *(const float4*)(Tr + 4 * lane);
;             const size_t ro = (size_t)grow * 1024 + n0 + 4 * lane;
;             float4 x4 = xo[u];
;             if constexpr (EPI == E_PLEGATE) {
;               x4.x += bflo(pv[u].x) * fsig(a.x * rs);
;               x4.y += bfhi(pv[u].x) * fsig(a.y * rs);
;               x4.z += bflo(pv[u].y) * fsig(a.z * rs);
;               x4.w += bfhi(pv[u].y) * fsig(a.w * rs);
;             } else {
;               const float sc = fabsf(scale);
;               x4.x += sc * a.x; x4.y += sc * a.y; x4.z += sc * a.z; x4.w += sc * a.w;
.LBB0_1019:
	v_readlane_b32 s12, v254, 13
	v_readlane_b32 s13, v254, 14
	v_lshrrev_b32_e32 v128, 2, v132
	v_and_or_b32 v128, v128, 12, s62
	s_movk_i32 s12, 0x410
	v_mul_lo_u32 v128, v128, s12
	s_lshl_b32 s9, s9, 7
	v_lshlrev_b32_e32 v129, 2, v133
	v_add3_u32 v130, s9, v128, v129
	s_lshl_b32 s9, s35, 4
	s_add_i32 s8, s9, s8
	v_and_b32_e32 v141, 63, v132
	ds_write2_b32 v130, v92, v100 offset1:16
	ds_write2_b32 v130, v120, v124 offset0:128 offset1:144
	v_add_u32_e32 v124, 0x400, v130
	s_ashr_i32 s9, s8, 31
	v_lshl_or_b32 v128, v141, 2, s10
	v_mov_b32_e32 v129, s11
	ds_write2_b32 v124, v93, v101 offset0:4 offset1:20
	ds_write2_b32 v124, v121, v125 offset0:132 offset1:148
	v_add_u32_e32 v121, 0x800, v130
	s_lshl_b64 s[10:11], s[8:9], 10
	s_or_b32 s30, s8, 1
	ds_write2_b32 v121, v94, v102 offset0:8 offset1:24
	ds_write2_b32 v121, v122, v126 offset0:136 offset1:152
	v_add_u32_e32 v122, 0xc00, v130
	v_lshl_add_u64 v[146:147], s[10:11], 0, v[128:129]
	s_ashr_i32 s31, s30, 31
	s_or_b32 s22, s8, 2
	ds_write2_b32 v122, v95, v103 offset0:12 offset1:28
	ds_write2_b32 v122, v123, v127 offset0:140 offset1:156
	v_add_u32_e32 v123, 0x4000, v130
	v_add_u32_e32 v125, 0x4400, v130
	v_add_u32_e32 v126, 0x4800, v130
	v_add_u32_e32 v127, 0x4c00, v130
	v_add_u32_e32 v131, 0x8000, v130
	v_add_u32_e32 v132, 0x8400, v130
	v_add_u32_e32 v133, 0x8800, v130
	v_add_u32_e32 v134, 0x8c00, v130
	v_add_u32_e32 v135, 0x9000, v130
	v_add_u32_e32 v136, 0xc000, v130
	v_add_u32_e32 v137, 0xc400, v130
	v_add_u32_e32 v138, 0xc800, v130
	v_add_u32_e32 v139, 0xcc00, v130
	v_add_u32_e32 v140, 0xd000, v130
	v_lshl_add_u64 v[156:157], v[146:147], 2, s[38:39]
	s_lshl_b64 s[10:11], s[30:31], 10
	s_ashr_i32 s23, s22, 31
	s_or_b32 s20, s8, 3
	ds_write2_b32 v123, v80, v84 offset0:64 offset1:80
	ds_write2_b32 v123, v112, v116 offset0:192 offset1:208
	ds_write2_b32 v125, v81, v85 offset0:68 offset1:84
	ds_write2_b32 v125, v113, v117 offset0:196 offset1:212
	ds_write2_b32 v126, v82, v86 offset0:72 offset1:88
	ds_write2_b32 v126, v114, v118 offset0:200 offset1:216
	ds_write2_b32 v127, v83, v87 offset0:76 offset1:92
	ds_write2_b32 v127, v115, v119 offset0:204 offset1:220
	ds_write2_b32 v131, v72, v76 offset0:128 offset1:144
	ds_write2_b32 v132, v104, v108 offset1:16
	ds_write2_b32 v132, v73, v77 offset0:132 offset1:148
	ds_write2_b32 v133, v105, v109 offset0:4 offset1:20
	ds_write2_b32 v133, v74, v78 offset0:136 offset1:152
	ds_write2_b32 v134, v106, v110 offset0:8 offset1:24
	ds_write2_b32 v134, v75, v79 offset0:140 offset1:156
	ds_write2_b32 v135, v107, v111 offset0:12 offset1:28
	ds_write2_b32 v136, v64, v68 offset0:192 offset1:208
	ds_write2_b32 v137, v88, v96 offset0:64 offset1:80
	ds_write2_b32 v137, v65, v69 offset0:196 offset1:212
	ds_write2_b32 v138, v89, v97 offset0:68 offset1:84
	ds_write2_b32 v138, v66, v70 offset0:200 offset1:216
	ds_write2_b32 v139, v90, v98 offset0:72 offset1:88
	ds_write2_b32 v139, v67, v71 offset0:204 offset1:220
	ds_write2_b32 v140, v91, v99 offset0:76 offset1:92
	s_waitcnt vmcnt(0) lgkmcnt(0)
	s_barrier
	global_load_dwordx4 v[142:145], v[156:157], off
	v_lshl_add_u64 v[118:119], s[10:11], 0, v[128:129]
	s_lshl_b64 s[10:11], s[22:23], 10
	s_ashr_i32 s21, s20, 31
	s_or_b32 s18, s8, 4
	v_lshl_add_u64 v[114:115], s[10:11], 0, v[128:129]
	s_lshl_b64 s[10:11], s[20:21], 10
	s_ashr_i32 s19, s18, 31
	s_or_b32 s14, s8, 5
	v_lshl_add_u64 v[110:111], s[10:11], 0, v[128:129]
	s_lshl_b64 s[10:11], s[18:19], 10
	s_ashr_i32 s15, s14, 31
	s_or_b32 s12, s8, 6
	v_lshl_add_u64 v[106:107], s[10:11], 0, v[128:129]
	s_lshl_b64 s[10:11], s[14:15], 10
	s_ashr_i32 s13, s12, 31
	v_lshl_add_u64 v[102:103], s[10:11], 0, v[128:129]
	s_lshl_b64 s[10:11], s[12:13], 10
	v_lshl_add_u64 v[98:99], s[10:11], 0, v[128:129]
	s_or_b32 s10, s8, 7
	s_ashr_i32 s11, s10, 31
	s_lshl_b64 s[62:63], s[10:11], 10
	v_lshl_add_u64 v[94:95], s[62:63], 0, v[128:129]
	v_lshl_add_u64 v[116:117], v[118:119], 2, s[38:39]
	v_lshl_add_u64 v[108:109], v[110:111], 2, s[38:39]
	v_lshl_add_u64 v[100:101], v[102:103], 2, s[38:39]
	v_lshl_add_u64 v[92:93], v[94:95], 2, s[38:39]
	v_lshl_add_u64 v[112:113], v[114:115], 2, s[38:39]
	global_load_dwordx4 v[88:91], v[116:117], off
	global_load_dwordx4 v[84:87], v[112:113], off
	v_lshl_add_u64 v[104:105], v[106:107], 2, s[38:39]
	global_load_dwordx4 v[80:83], v[108:109], off
	global_load_dwordx4 v[76:79], v[104:105], off
	v_lshl_add_u64 v[96:97], v[98:99], 2, s[38:39]
	global_load_dwordx4 v[72:75], v[100:101], off
	global_load_dwordx4 v[68:71], v[96:97], off
	global_load_dwordx4 v[64:67], v[92:93], off
	v_lshlrev_b32_e32 v120, 4, v141
	s_mulk_i32 s35, 0x4100
	v_add_u32_e32 v120, s35, v120
	ds_read_b128 v[152:155], v120
	v_cmp_eq_u32_e32 vcc, 0, v141
	v_lshl_add_u64 v[146:147], v[146:147], 1, s[4:5]
	s_waitcnt vmcnt(7) lgkmcnt(0)
	v_pk_add_f32 v[142:143], v[142:143], v[152:153]
	v_pk_add_f32 v[144:145], v[144:145], v[154:155]
	global_store_dwordx4 v[156:157], v[142:145], off
	v_cvt_pk_bf16_f32 v152, v142, v143
	v_cvt_pk_bf16_f32 v153, v144, v145
	v_pk_mul_f32 v[142:143], v[142:143], v[142:143]
	v_pk_mul_f32 v[144:145], v[144:145], v[144:145]
	v_add_f32_e32 v141, v142, v143
	v_add_f32_e32 v141, v141, v144
	v_add_f32_e32 v141, v141, v145
	flat_store_dwordx2 v[146:147], v[152:153]
	s_nop 0
	v_add_f32_dpp v141, v141, v141 row_ror:8 row_mask:0xf bank_mask:0xf bound_ctrl:1
	s_nop 1
	v_add_f32_dpp v141, v141, v141 row_ror:4 row_mask:0xf bank_mask:0xf bound_ctrl:1
	s_nop 1
	v_add_f32_dpp v141, v141, v141 row_ror:2 row_mask:0xf bank_mask:0xf bound_ctrl:1
	s_nop 1
	v_add_f32_dpp v141, v141, v141 row_ror:1 row_mask:0xf bank_mask:0xf bound_ctrl:1
	s_nop 0
	v_readlane_b32 s62, v141, 0
	v_readlane_b32 s70, v141, 16
	v_readlane_b32 s63, v141, 32
	v_readlane_b32 s69, v141, 48
	s_and_saveexec_b64 s[34:35], vcc
	s_cbranch_execz .LBB0_1021
	s_lshl_b64 s[72:73], s[8:9], 2
	v_mov_b32_e32 v141, s70
	s_add_u32 s72, s65, s72
	v_add_f32_e32 v141, s62, v141
	s_addc_u32 s73, s66, s73
	v_add_f32_e32 v141, s63, v141
	v_add_f32_e32 v141, s69, v141
	v_mov_b64_e32 v[142:143], s[72:73]
	flat_atomic_add_f32 v[142:143], v141
; DEVI float fsig(float x) { return __builtin_amdgcn_rcpf(1.f + __expf(-x)); }
; DEVI float bflo(unsigned u) { return __uint_as_float(u << 16); }
; DEVI float bfhi(unsigned u) { return __uint_as_float(u & 0xffff0000u); }
; template <int EPI, int TS, bool VT>
; DEVI void gemm_epilogue(const Params& p, char* smem, f32x4 (&acc)[2][2][4][2], int m0, int n0, float scale, const float* ssin,
;                         float* ssout, u16* xbout, int wid, int lane, int wr, int wc, int fr, int fq) {
;     ...
;           if constexpr (EPI == E_RESID || EPI == E_PLEGATE) {
;             const float4 a = *(const float4*)(Tr + 4 * lane);
;             const size_t ro = (size_t)grow * 1024 + n0 + 4 * lane;
;             float4 x4 = xo[u];
;             if constexpr (EPI == E_PLEGATE) {
;               x4.x += bflo(pv[u].x) * fsig(a.x * rs);
;               x4.y += bfhi(pv[u].x) * fsig(a.y * rs);
;               x4.z += bflo(pv[u].y) * fsig(a.z * rs);
;               x4.w += bfhi(pv[u].y) * fsig(a.w * rs);
;             } else {
;               const float sc = fabsf(scale);
;               x4.x += sc * a.x; x4.y += sc * a.y; x4.z += sc * a.z; x4.w += sc * a.w;
;             }
;             st_nt16(p.x + ro, x4);
;             if (xbout) {
;               uint2 o;
;               o.x = pack2(x4.x, x4.y);
;               o.y = pack2(x4.z, x4.w);
;               st_nt8(xbout + ro, o);
;             }
;             if (ssout) {
;               const float ssq = wsum(x4.x * x4.x + x4.y * x4.y + x4.z * x4.z + x4.w * x4.w, lane);
;               if (lane == 0) atomicAdd(ssout + grow, ssq);
;             }
.LBB0_1021:
	s_or_b64 exec, exec, s[34:35]
	ds_read_b128 v[142:145], v120 offset:1040
	v_lshl_add_u64 v[118:119], v[118:119], 1, s[4:5]
	s_waitcnt vmcnt(0) lgkmcnt(0)
	v_pk_add_f32 v[88:89], v[88:89], v[142:143]
	v_pk_add_f32 v[90:91], v[90:91], v[144:145]
	global_store_dwordx4 v[116:117], v[88:91], off
	v_cvt_pk_bf16_f32 v116, v88, v89
	v_cvt_pk_bf16_f32 v117, v90, v91
	v_pk_mul_f32 v[88:89], v[88:89], v[88:89]
	v_pk_mul_f32 v[90:91], v[90:91], v[90:91]
	v_add_f32_e32 v88, v88, v89
	v_add_f32_e32 v88, v88, v90
	v_add_f32_e32 v88, v88, v91
	flat_store_dwordx2 v[118:119], v[116:117]
	s_nop 0
	v_add_f32_dpp v88, v88, v88 row_ror:8 row_mask:0xf bank_mask:0xf bound_ctrl:1
	s_nop 1
	v_add_f32_dpp v88, v88, v88 row_ror:4 row_mask:0xf bank_mask:0xf bound_ctrl:1
	s_nop 1
	v_add_f32_dpp v88, v88, v88 row_ror:2 row_mask:0xf bank_mask:0xf bound_ctrl:1
	s_nop 1
	v_add_f32_dpp v88, v88, v88 row_ror:1 row_mask:0xf bank_mask:0xf bound_ctrl:1
	s_nop 0
	v_readlane_b32 s9, v88, 0
	v_readlane_b32 s69, v88, 16
	v_readlane_b32 s62, v88, 32
	v_readlane_b32 s63, v88, 48
	s_and_saveexec_b64 s[34:35], vcc
	s_cbranch_execz .LBB0_1023
	s_lshl_b64 s[30:31], s[30:31], 2
	v_mov_b32_e32 v88, s69
	s_add_u32 s30, s65, s30
	v_add_f32_e32 v88, s9, v88
	s_addc_u32 s31, s66, s31
	v_add_f32_e32 v88, s62, v88
	v_add_f32_e32 v90, s63, v88
	v_mov_b64_e32 v[88:89], s[30:31]
	flat_atomic_add_f32 v[88:89], v90
.LBB0_1023:
	s_or_b64 exec, exec, s[34:35]
	ds_read_b128 v[88:91], v120 offset:2080
	v_lshl_add_u64 v[114:115], v[114:115], 1, s[4:5]
	s_waitcnt lgkmcnt(0)
	v_pk_add_f32 v[84:85], v[84:85], v[88:89]
	v_pk_add_f32 v[86:87], v[86:87], v[90:91]
	global_store_dwordx4 v[112:113], v[84:87], off
	v_cvt_pk_bf16_f32 v88, v84, v85
	v_cvt_pk_bf16_f32 v89, v86, v87
	v_pk_mul_f32 v[84:85], v[84:85], v[84:85]
	v_pk_mul_f32 v[86:87], v[86:87], v[86:87]
	v_add_f32_e32 v84, v84, v85
	v_add_f32_e32 v84, v84, v86
	v_add_f32_e32 v84, v84, v87
	flat_store_dwordx2 v[114:115], v[88:89]
	s_nop 0
	v_add_f32_dpp v84, v84, v84 row_ror:8 row_mask:0xf bank_mask:0xf bound_ctrl:1
	s_nop 1
	v_add_f32_dpp v84, v84, v84 row_ror:4 row_mask:0xf bank_mask:0xf bound_ctrl:1
	s_nop 1
	v_add_f32_dpp v84, v84, v84 row_ror:2 row_mask:0xf bank_mask:0xf bound_ctrl:1
	s_nop 1
	v_add_f32_dpp v84, v84, v84 row_ror:1 row_mask:0xf bank_mask:0xf bound_ctrl:1
	s_nop 0
	v_readlane_b32 s9, v84, 0
	v_readlane_b32 s62, v84, 16
	v_readlane_b32 s34, v84, 32
	v_readlane_b32 s35, v84, 48
	s_and_saveexec_b64 s[30:31], vcc
	s_cbranch_execz .LBB0_1025
	s_lshl_b64 s[22:23], s[22:23], 2
	v_mov_b32_e32 v84, s62
	s_add_u32 s22, s65, s22
	v_add_f32_e32 v84, s9, v84
	s_addc_u32 s23, s66, s23
	v_add_f32_e32 v84, s34, v84
	v_add_f32_e32 v86, s35, v84
	v_mov_b64_e32 v[84:85], s[22:23]
	flat_atomic_add_f32 v[84:85], v86
.LBB0_1025:
	s_or_b64 exec, exec, s[30:31]
	ds_read_b128 v[84:87], v120 offset:3120
	v_lshl_add_u64 v[88:89], v[110:111], 1, s[4:5]
	s_waitcnt lgkmcnt(0)
	v_pk_add_f32 v[80:81], v[80:81], v[84:85]
	v_pk_add_f32 v[82:83], v[82:83], v[86:87]
	global_store_dwordx4 v[108:109], v[80:83], off
	v_cvt_pk_bf16_f32 v84, v80, v81
	v_cvt_pk_bf16_f32 v85, v82, v83
	v_pk_mul_f32 v[80:81], v[80:81], v[80:81]
	v_pk_mul_f32 v[82:83], v[82:83], v[82:83]
	v_add_f32_e32 v80, v80, v81
	v_add_f32_e32 v80, v80, v82
	v_add_f32_e32 v80, v80, v83
	flat_store_dwordx2 v[88:89], v[84:85]
	s_nop 0
	v_add_f32_dpp v80, v80, v80 row_ror:8 row_mask:0xf bank_mask:0xf bound_ctrl:1
	s_nop 1
	v_add_f32_dpp v80, v80, v80 row_ror:4 row_mask:0xf bank_mask:0xf bound_ctrl:1
	s_nop 1
	v_add_f32_dpp v80, v80, v80 row_ror:2 row_mask:0xf bank_mask:0xf bound_ctrl:1
	s_nop 1
	v_add_f32_dpp v80, v80, v80 row_ror:1 row_mask:0xf bank_mask:0xf bound_ctrl:1
	s_nop 0
	v_readlane_b32 s9, v80, 0
	v_readlane_b32 s34, v80, 16
	v_readlane_b32 s30, v80, 32
	v_readlane_b32 s31, v80, 48
	s_and_saveexec_b64 s[22:23], vcc
	s_cbranch_execz .LBB0_1027
	s_lshl_b64 s[20:21], s[20:21], 2
	v_mov_b32_e32 v80, s34
	s_add_u32 s20, s65, s20
	v_add_f32_e32 v80, s9, v80
	s_addc_u32 s21, s66, s21
	v_add_f32_e32 v80, s30, v80
	v_add_f32_e32 v82, s31, v80
	v_mov_b64_e32 v[80:81], s[20:21]
	flat_atomic_add_f32 v[80:81], v82
.LBB0_1027:
	s_or_b64 exec, exec, s[22:23]
	ds_read_b128 v[80:83], v120 offset:4160
	v_lshl_add_u64 v[84:85], v[106:107], 1, s[4:5]
	s_waitcnt lgkmcnt(0)
	v_pk_add_f32 v[76:77], v[76:77], v[80:81]
	v_pk_add_f32 v[78:79], v[78:79], v[82:83]
	global_store_dwordx4 v[104:105], v[76:79], off
	v_cvt_pk_bf16_f32 v80, v76, v77
	v_cvt_pk_bf16_f32 v81, v78, v79
	v_pk_mul_f32 v[76:77], v[76:77], v[76:77]
	v_pk_mul_f32 v[78:79], v[78:79], v[78:79]
	v_add_f32_e32 v76, v76, v77
	v_add_f32_e32 v76, v76, v78
	v_add_f32_e32 v76, v76, v79
	flat_store_dwordx2 v[84:85], v[80:81]
	s_nop 0
	v_add_f32_dpp v76, v76, v76 row_ror:8 row_mask:0xf bank_mask:0xf bound_ctrl:1
	s_nop 1
	v_add_f32_dpp v76, v76, v76 row_ror:4 row_mask:0xf bank_mask:0xf bound_ctrl:1
	s_nop 1
	v_add_f32_dpp v76, v76, v76 row_ror:2 row_mask:0xf bank_mask:0xf bound_ctrl:1
	s_nop 1
	v_add_f32_dpp v76, v76, v76 row_ror:1 row_mask:0xf bank_mask:0xf bound_ctrl:1
	s_nop 0
	v_readlane_b32 s9, v76, 0
	v_readlane_b32 s30, v76, 16
	v_readlane_b32 s22, v76, 32
	v_readlane_b32 s23, v76, 48
	s_and_saveexec_b64 s[20:21], vcc
	s_cbranch_execz .LBB0_1029
	s_lshl_b64 s[18:19], s[18:19], 2
	v_mov_b32_e32 v76, s30
	s_add_u32 s18, s65, s18
	v_add_f32_e32 v76, s9, v76
	s_addc_u32 s19, s66, s19
	v_add_f32_e32 v76, s22, v76
	v_add_f32_e32 v78, s23, v76
	v_mov_b64_e32 v[76:77], s[18:19]
	flat_atomic_add_f32 v[76:77], v78
; DEVI float fsig(float x) { return __builtin_amdgcn_rcpf(1.f + __expf(-x)); }
; DEVI float bflo(unsigned u) { return __uint_as_float(u << 16); }
; DEVI float bfhi(unsigned u) { return __uint_as_float(u & 0xffff0000u); }
; template <int EPI, int TS, bool VT>
; DEVI void gemm_epilogue(const Params& p, char* smem, f32x4 (&acc)[2][2][4][2], int m0, int n0, float scale, const float* ssin,
;                         float* ssout, u16* xbout, int wid, int lane, int wr, int wc, int fr, int fq) {
;     ...
;         if constexpr (EPI == E_RESID || EPI == E_PLEGATE) {
; #pragma unroll
;           for (int u = 0; u < 8; ++u) {
;             const size_t ro = (size_t)(g0 + i0 + u) * 1024 + n0 + 4 * lane;
;             const int gr = g0 + i0 + u;
;             const float* xs = p.x + ro;
;             if (scale < 0.f)
;               xs = (gr < MP ? p.x_prompt + ro : p.x_sample + (ro - (size_t)MP * 1024));
;             { const f32x4 t_ = __builtin_nontemporal_load((const f32x4*)xs); xo[u] = make_float4(t_[0], t_[1], t_[2], t_[3]); }
;     ...
;           if constexpr (EPI == E_RESID || EPI == E_PLEGATE) {
;             const float4 a = *(const float4*)(Tr + 4 * lane);
;             const size_t ro = (size_t)grow * 1024 + n0 + 4 * lane;
;             float4 x4 = xo[u];
;             if constexpr (EPI == E_PLEGATE) {
;               x4.x += bflo(pv[u].x) * fsig(a.x * rs);
;               x4.y += bfhi(pv[u].x) * fsig(a.y * rs);
;               x4.z += bflo(pv[u].y) * fsig(a.z * rs);
;               x4.w += bfhi(pv[u].y) * fsig(a.w * rs);
;             } else {
;               const float sc = fabsf(scale);
;               x4.x += sc * a.x; x4.y += sc * a.y; x4.z += sc * a.z; x4.w += sc * a.w;
;             }
;             st_nt16(p.x + ro, x4);
;             if (xbout) {
;               uint2 o;
;               o.x = pack2(x4.x, x4.y);
;               o.y = pack2(x4.z, x4.w);
;               st_nt8(xbout + ro, o);
;             }
;             if (ssout) {
;               const float ssq = wsum(x4.x * x4.x + x4.y * x4.y + x4.z * x4.z + x4.w * x4.w, lane);
;               if (lane == 0) atomicAdd(ssout + grow, ssq);
;             }
.LBB0_1029:
	s_or_b64 exec, exec, s[20:21]
	ds_read_b128 v[76:79], v120 offset:5200
	v_lshl_add_u64 v[80:81], v[102:103], 1, s[4:5]
	s_waitcnt lgkmcnt(0)
	v_pk_add_f32 v[72:73], v[72:73], v[76:77]
	v_pk_add_f32 v[74:75], v[74:75], v[78:79]
	global_store_dwordx4 v[100:101], v[72:75], off
	v_cvt_pk_bf16_f32 v76, v72, v73
	v_cvt_pk_bf16_f32 v77, v74, v75
	v_pk_mul_f32 v[72:73], v[72:73], v[72:73]
	v_pk_mul_f32 v[74:75], v[74:75], v[74:75]
	v_add_f32_e32 v72, v72, v73
	v_add_f32_e32 v72, v72, v74
	v_add_f32_e32 v72, v72, v75
	flat_store_dwordx2 v[80:81], v[76:77]
	s_nop 0
	v_add_f32_dpp v72, v72, v72 row_ror:8 row_mask:0xf bank_mask:0xf bound_ctrl:1
	s_nop 1
	v_add_f32_dpp v72, v72, v72 row_ror:4 row_mask:0xf bank_mask:0xf bound_ctrl:1
	s_nop 1
	v_add_f32_dpp v72, v72, v72 row_ror:2 row_mask:0xf bank_mask:0xf bound_ctrl:1
	s_nop 1
	v_add_f32_dpp v72, v72, v72 row_ror:1 row_mask:0xf bank_mask:0xf bound_ctrl:1
	s_nop 0
	v_readlane_b32 s9, v72, 0
	v_readlane_b32 s22, v72, 16
	v_readlane_b32 s20, v72, 32
	v_readlane_b32 s21, v72, 48
	s_and_saveexec_b64 s[18:19], vcc
	s_cbranch_execz .LBB0_1031
	s_lshl_b64 s[14:15], s[14:15], 2
	v_mov_b32_e32 v72, s22
	s_add_u32 s14, s65, s14
	v_add_f32_e32 v72, s9, v72
	s_addc_u32 s15, s66, s15
	v_add_f32_e32 v72, s20, v72
	v_add_f32_e32 v74, s21, v72
	v_mov_b64_e32 v[72:73], s[14:15]
	flat_atomic_add_f32 v[72:73], v74
.LBB0_1031:
	s_or_b64 exec, exec, s[18:19]
	ds_read_b128 v[72:75], v120 offset:6240
	v_lshl_add_u64 v[76:77], v[98:99], 1, s[4:5]
	s_waitcnt lgkmcnt(0)
	v_pk_add_f32 v[68:69], v[68:69], v[72:73]
	v_pk_add_f32 v[70:71], v[70:71], v[74:75]
	global_store_dwordx4 v[96:97], v[68:71], off
	v_cvt_pk_bf16_f32 v72, v68, v69
	v_cvt_pk_bf16_f32 v73, v70, v71
	v_pk_mul_f32 v[68:69], v[68:69], v[68:69]
	v_pk_mul_f32 v[70:71], v[70:71], v[70:71]
	v_add_f32_e32 v68, v68, v69
	v_add_f32_e32 v68, v68, v70
	v_add_f32_e32 v68, v68, v71
	flat_store_dwordx2 v[76:77], v[72:73]
	s_nop 0
	v_add_f32_dpp v68, v68, v68 row_ror:8 row_mask:0xf bank_mask:0xf bound_ctrl:1
	s_nop 1
	v_add_f32_dpp v68, v68, v68 row_ror:4 row_mask:0xf bank_mask:0xf bound_ctrl:1
	s_nop 1
	v_add_f32_dpp v68, v68, v68 row_ror:2 row_mask:0xf bank_mask:0xf bound_ctrl:1
	s_nop 1
	v_add_f32_dpp v68, v68, v68 row_ror:1 row_mask:0xf bank_mask:0xf bound_ctrl:1
	s_nop 0
	v_readlane_b32 s9, v68, 0
	v_readlane_b32 s20, v68, 16
	v_readlane_b32 s18, v68, 32
	v_readlane_b32 s19, v68, 48
	s_and_saveexec_b64 s[14:15], vcc
	s_cbranch_execz .LBB0_1033
	s_lshl_b64 s[12:13], s[12:13], 2
	v_mov_b32_e32 v68, s20
	s_add_u32 s12, s65, s12
	v_add_f32_e32 v68, s9, v68
	s_addc_u32 s13, s66, s13
	v_add_f32_e32 v68, s18, v68
	v_add_f32_e32 v70, s19, v68
	v_mov_b64_e32 v[68:69], s[12:13]
	flat_atomic_add_f32 v[68:69], v70
.LBB0_1033:
	s_or_b64 exec, exec, s[14:15]
	ds_read_b128 v[68:71], v120 offset:7280
	v_lshl_add_u64 v[72:73], v[94:95], 1, s[4:5]
	s_waitcnt lgkmcnt(0)
	v_pk_add_f32 v[64:65], v[64:65], v[68:69]
	v_pk_add_f32 v[66:67], v[66:67], v[70:71]
	global_store_dwordx4 v[92:93], v[64:67], off
	v_cvt_pk_bf16_f32 v68, v64, v65
	v_cvt_pk_bf16_f32 v69, v66, v67
	v_pk_mul_f32 v[64:65], v[64:65], v[64:65]
	v_pk_mul_f32 v[66:67], v[66:67], v[66:67]
	v_add_f32_e32 v64, v64, v65
	v_add_f32_e32 v64, v64, v66
	v_add_f32_e32 v64, v64, v67
	flat_store_dwordx2 v[72:73], v[68:69]
	s_nop 0
	v_add_f32_dpp v64, v64, v64 row_ror:8 row_mask:0xf bank_mask:0xf bound_ctrl:1
	s_nop 1
	v_add_f32_dpp v64, v64, v64 row_ror:4 row_mask:0xf bank_mask:0xf bound_ctrl:1
	s_nop 1
	v_add_f32_dpp v64, v64, v64 row_ror:2 row_mask:0xf bank_mask:0xf bound_ctrl:1
	s_nop 1
	v_add_f32_dpp v64, v64, v64 row_ror:1 row_mask:0xf bank_mask:0xf bound_ctrl:1
	s_nop 0
	v_readlane_b32 s9, v64, 0
	v_readlane_b32 s18, v64, 16
	v_readlane_b32 s14, v64, 32
	v_readlane_b32 s15, v64, 48
	s_and_saveexec_b64 s[12:13], vcc
	s_cbranch_execz .LBB0_1035
	s_lshl_b64 s[10:11], s[10:11], 2
	v_mov_b32_e32 v64, s18
	s_add_u32 s10, s65, s10
	v_add_f32_e32 v64, s9, v64
	s_addc_u32 s11, s66, s11
	v_add_f32_e32 v64, s14, v64
	v_add_f32_e32 v66, s15, v64
	v_mov_b64_e32 v[64:65], s[10:11]
	flat_atomic_add_f32 v[64:65], v66
.LBB0_1035:
	s_or_b64 exec, exec, s[12:13]
	s_or_b32 s34, s8, 8
	s_ashr_i32 s35, s34, 31
	s_lshl_b64 s[10:11], s[34:35], 10
	s_or_b32 s30, s8, 9
	v_lshl_add_u64 v[146:147], s[10:11], 0, v[128:129]
	s_ashr_i32 s31, s30, 31
	s_or_b32 s22, s8, 10
	v_lshl_add_u64 v[156:157], v[146:147], 2, s[38:39]
	s_lshl_b64 s[10:11], s[30:31], 10
	s_ashr_i32 s23, s22, 31
	s_or_b32 s20, s8, 11
	global_load_dwordx4 v[142:145], v[156:157], off
	v_lshl_add_u64 v[118:119], s[10:11], 0, v[128:129]
	s_lshl_b64 s[10:11], s[22:23], 10
	s_ashr_i32 s21, s20, 31
	s_or_b32 s18, s8, 12
	v_lshl_add_u64 v[114:115], s[10:11], 0, v[128:129]
	s_lshl_b64 s[10:11], s[20:21], 10
	s_ashr_i32 s19, s18, 31
	s_or_b32 s14, s8, 13
	v_lshl_add_u64 v[110:111], s[10:11], 0, v[128:129]
	s_lshl_b64 s[10:11], s[18:19], 10
	s_ashr_i32 s15, s14, 31
	s_or_b32 s12, s8, 14
	v_lshl_add_u64 v[106:107], s[10:11], 0, v[128:129]
	s_lshl_b64 s[10:11], s[14:15], 10
	s_ashr_i32 s13, s12, 31
	v_lshl_add_u64 v[102:103], s[10:11], 0, v[128:129]
	s_lshl_b64 s[10:11], s[12:13], 10
	v_lshl_add_u64 v[98:99], s[10:11], 0, v[128:129]
	s_or_b32 s10, s8, 15
	s_ashr_i32 s11, s10, 31
	s_lshl_b64 s[62:63], s[10:11], 10
	v_lshl_add_u64 v[94:95], s[62:63], 0, v[128:129]
	v_lshl_add_u64 v[116:117], v[118:119], 2, s[38:39]
	v_lshl_add_u64 v[108:109], v[110:111], 2, s[38:39]
	v_lshl_add_u64 v[100:101], v[102:103], 2, s[38:39]
	v_lshl_add_u64 v[92:93], v[94:95], 2, s[38:39]
	v_lshl_add_u64 v[112:113], v[114:115], 2, s[38:39]
	global_load_dwordx4 v[88:91], v[116:117], off
	global_load_dwordx4 v[84:87], v[112:113], off
	v_lshl_add_u64 v[104:105], v[106:107], 2, s[38:39]
	global_load_dwordx4 v[80:83], v[108:109], off
	global_load_dwordx4 v[76:79], v[104:105], off
	v_lshl_add_u64 v[96:97], v[98:99], 2, s[38:39]
	global_load_dwordx4 v[72:75], v[100:101], off
	global_load_dwordx4 v[68:71], v[96:97], off
	global_load_dwordx4 v[64:67], v[92:93], off
	ds_read_b128 v[152:155], v120 offset:8320
	v_lshl_add_u64 v[146:147], v[146:147], 1, s[4:5]
	s_waitcnt vmcnt(0) lgkmcnt(0)
; DEVI float fsig(float x) { return __builtin_amdgcn_rcpf(1.f + __expf(-x)); }
; DEVI float bflo(unsigned u) { return __uint_as_float(u << 16); }
; DEVI float bfhi(unsigned u) { return __uint_as_float(u & 0xffff0000u); }
; template <int EPI, int TS, bool VT>
; DEVI void gemm_epilogue(const Params& p, char* smem, f32x4 (&acc)[2][2][4][2], int m0, int n0, float scale, const float* ssin,
;                         float* ssout, u16* xbout, int wid, int lane, int wr, int wc, int fr, int fq) {
;     ...
;           if constexpr (EPI == E_RESID || EPI == E_PLEGATE) {
;             const float4 a = *(const float4*)(Tr + 4 * lane);
;             const size_t ro = (size_t)grow * 1024 + n0 + 4 * lane;
;             float4 x4 = xo[u];
;             if constexpr (EPI == E_PLEGATE) {
;               x4.x += bflo(pv[u].x) * fsig(a.x * rs);
;               x4.y += bfhi(pv[u].x) * fsig(a.y * rs);
;               x4.z += bflo(pv[u].y) * fsig(a.z * rs);
;               x4.w += bfhi(pv[u].y) * fsig(a.w * rs);
;             } else {
;               const float sc = fabsf(scale);
;               x4.x += sc * a.x; x4.y += sc * a.y; x4.z += sc * a.z; x4.w += sc * a.w;
;             }
;             st_nt16(p.x + ro, x4);
;             if (xbout) {
;               uint2 o;
;               o.x = pack2(x4.x, x4.y);
;               o.y = pack2(x4.z, x4.w);
;               st_nt8(xbout + ro, o);
;             }
;             if (ssout) {
;               const float ssq = wsum(x4.x * x4.x + x4.y * x4.y + x4.z * x4.z + x4.w * x4.w, lane);
;               if (lane == 0) atomicAdd(ssout + grow, ssq);
;             }
	v_pk_add_f32 v[142:143], v[142:143], v[152:153]
	v_pk_add_f32 v[144:145], v[144:145], v[154:155]
	global_store_dwordx4 v[156:157], v[142:145], off
	v_cvt_pk_bf16_f32 v152, v142, v143
	v_cvt_pk_bf16_f32 v153, v144, v145
	v_pk_mul_f32 v[142:143], v[142:143], v[142:143]
	v_pk_mul_f32 v[144:145], v[144:145], v[144:145]
	v_add_f32_e32 v141, v142, v143
	v_add_f32_e32 v141, v141, v144
	v_add_f32_e32 v141, v141, v145
	flat_store_dwordx2 v[146:147], v[152:153]
	s_nop 0
	v_add_f32_dpp v141, v141, v141 row_ror:8 row_mask:0xf bank_mask:0xf bound_ctrl:1
	s_nop 1
	v_add_f32_dpp v141, v141, v141 row_ror:4 row_mask:0xf bank_mask:0xf bound_ctrl:1
	s_nop 1
	v_add_f32_dpp v141, v141, v141 row_ror:2 row_mask:0xf bank_mask:0xf bound_ctrl:1
	s_nop 1
	v_add_f32_dpp v141, v141, v141 row_ror:1 row_mask:0xf bank_mask:0xf bound_ctrl:1
	s_nop 0
	v_readlane_b32 s9, v141, 0
	v_readlane_b32 s71, v141, 16
	v_readlane_b32 s69, v141, 32
	v_readlane_b32 s70, v141, 48
	s_and_saveexec_b64 s[62:63], vcc
	s_cbranch_execz .LBB0_1037
	s_lshl_b64 s[34:35], s[34:35], 2
	v_mov_b32_e32 v141, s71
	s_add_u32 s34, s65, s34
	v_add_f32_e32 v141, s9, v141
	s_addc_u32 s35, s66, s35
	v_add_f32_e32 v141, s69, v141
	v_add_f32_e32 v141, s70, v141
	v_mov_b64_e32 v[142:143], s[34:35]
	flat_atomic_add_f32 v[142:143], v141
.LBB0_1037:
	s_or_b64 exec, exec, s[62:63]
	ds_read_b128 v[142:145], v120 offset:9360
	v_lshl_add_u64 v[118:119], v[118:119], 1, s[4:5]
	s_waitcnt lgkmcnt(0)
	v_pk_add_f32 v[88:89], v[88:89], v[142:143]
	v_pk_add_f32 v[90:91], v[90:91], v[144:145]
	global_store_dwordx4 v[116:117], v[88:91], off
	v_cvt_pk_bf16_f32 v116, v88, v89
	v_cvt_pk_bf16_f32 v117, v90, v91
	v_pk_mul_f32 v[88:89], v[88:89], v[88:89]
	v_pk_mul_f32 v[90:91], v[90:91], v[90:91]
	v_add_f32_e32 v88, v88, v89
	v_add_f32_e32 v88, v88, v90
	v_add_f32_e32 v88, v88, v91
	flat_store_dwordx2 v[118:119], v[116:117]
	s_nop 0
	v_add_f32_dpp v88, v88, v88 row_ror:8 row_mask:0xf bank_mask:0xf bound_ctrl:1
	s_nop 1
	v_add_f32_dpp v88, v88, v88 row_ror:4 row_mask:0xf bank_mask:0xf bound_ctrl:1
	s_nop 1
	v_add_f32_dpp v88, v88, v88 row_ror:2 row_mask:0xf bank_mask:0xf bound_ctrl:1
	s_nop 1
	v_add_f32_dpp v88, v88, v88 row_ror:1 row_mask:0xf bank_mask:0xf bound_ctrl:1
	s_nop 0
	v_readlane_b32 s9, v88, 0
	v_readlane_b32 s69, v88, 16
	v_readlane_b32 s62, v88, 32
	v_readlane_b32 s63, v88, 48
	s_and_saveexec_b64 s[34:35], vcc
	s_cbranch_execz .LBB0_1039
	s_lshl_b64 s[30:31], s[30:31], 2
	v_mov_b32_e32 v88, s69
	s_add_u32 s30, s65, s30
	v_add_f32_e32 v88, s9, v88
	s_addc_u32 s31, s66, s31
	v_add_f32_e32 v88, s62, v88
	v_add_f32_e32 v90, s63, v88
	v_mov_b64_e32 v[88:89], s[30:31]
	flat_atomic_add_f32 v[88:89], v90
.LBB0_1039:
	s_or_b64 exec, exec, s[34:35]
	ds_read_b128 v[88:91], v120 offset:10400
	v_lshl_add_u64 v[114:115], v[114:115], 1, s[4:5]
	s_waitcnt lgkmcnt(0)
	v_pk_add_f32 v[84:85], v[84:85], v[88:89]
	v_pk_add_f32 v[86:87], v[86:87], v[90:91]
	global_store_dwordx4 v[112:113], v[84:87], off
	v_cvt_pk_bf16_f32 v88, v84, v85
	v_cvt_pk_bf16_f32 v89, v86, v87
	v_pk_mul_f32 v[84:85], v[84:85], v[84:85]
	v_pk_mul_f32 v[86:87], v[86:87], v[86:87]
	v_add_f32_e32 v84, v84, v85
	v_add_f32_e32 v84, v84, v86
	v_add_f32_e32 v84, v84, v87
	flat_store_dwordx2 v[114:115], v[88:89]
	s_nop 0
	v_add_f32_dpp v84, v84, v84 row_ror:8 row_mask:0xf bank_mask:0xf bound_ctrl:1
	s_nop 1
	v_add_f32_dpp v84, v84, v84 row_ror:4 row_mask:0xf bank_mask:0xf bound_ctrl:1
	s_nop 1
	v_add_f32_dpp v84, v84, v84 row_ror:2 row_mask:0xf bank_mask:0xf bound_ctrl:1
	s_nop 1
	v_add_f32_dpp v84, v84, v84 row_ror:1 row_mask:0xf bank_mask:0xf bound_ctrl:1
	s_nop 0
	v_readlane_b32 s9, v84, 0
	v_readlane_b32 s62, v84, 16
	v_readlane_b32 s34, v84, 32
	v_readlane_b32 s35, v84, 48
	s_and_saveexec_b64 s[30:31], vcc
	s_cbranch_execz .LBB0_1041
	s_lshl_b64 s[22:23], s[22:23], 2
	v_mov_b32_e32 v84, s62
	s_add_u32 s22, s65, s22
	v_add_f32_e32 v84, s9, v84
	s_addc_u32 s23, s66, s23
	v_add_f32_e32 v84, s34, v84
	v_add_f32_e32 v86, s35, v84
	v_mov_b64_e32 v[84:85], s[22:23]
	flat_atomic_add_f32 v[84:85], v86
.LBB0_1041:
	s_or_b64 exec, exec, s[30:31]
	ds_read_b128 v[84:87], v120 offset:11440
	v_lshl_add_u64 v[88:89], v[110:111], 1, s[4:5]
	s_waitcnt lgkmcnt(0)
	v_pk_add_f32 v[80:81], v[80:81], v[84:85]
	v_pk_add_f32 v[82:83], v[82:83], v[86:87]
	global_store_dwordx4 v[108:109], v[80:83], off
	v_cvt_pk_bf16_f32 v84, v80, v81
	v_cvt_pk_bf16_f32 v85, v82, v83
	v_pk_mul_f32 v[80:81], v[80:81], v[80:81]
	v_pk_mul_f32 v[82:83], v[82:83], v[82:83]
	v_add_f32_e32 v80, v80, v81
	v_add_f32_e32 v80, v80, v82
	v_add_f32_e32 v80, v80, v83
	flat_store_dwordx2 v[88:89], v[84:85]
	s_nop 0
	v_add_f32_dpp v80, v80, v80 row_ror:8 row_mask:0xf bank_mask:0xf bound_ctrl:1
	s_nop 1
	v_add_f32_dpp v80, v80, v80 row_ror:4 row_mask:0xf bank_mask:0xf bound_ctrl:1
	s_nop 1
	v_add_f32_dpp v80, v80, v80 row_ror:2 row_mask:0xf bank_mask:0xf bound_ctrl:1
	s_nop 1
	v_add_f32_dpp v80, v80, v80 row_ror:1 row_mask:0xf bank_mask:0xf bound_ctrl:1
	s_nop 0
	v_readlane_b32 s9, v80, 0
	v_readlane_b32 s34, v80, 16
	v_readlane_b32 s30, v80, 32
	v_readlane_b32 s31, v80, 48
	s_and_saveexec_b64 s[22:23], vcc
	s_cbranch_execz .LBB0_1043
	s_lshl_b64 s[20:21], s[20:21], 2
	v_mov_b32_e32 v80, s34
	s_add_u32 s20, s65, s20
	v_add_f32_e32 v80, s9, v80
	s_addc_u32 s21, s66, s21
	v_add_f32_e32 v80, s30, v80
	v_add_f32_e32 v82, s31, v80
	v_mov_b64_e32 v[80:81], s[20:21]
	flat_atomic_add_f32 v[80:81], v82
; DEVI float fsig(float x) { return __builtin_amdgcn_rcpf(1.f + __expf(-x)); }
; DEVI float bflo(unsigned u) { return __uint_as_float(u << 16); }
; DEVI float bfhi(unsigned u) { return __uint_as_float(u & 0xffff0000u); }
; template <int EPI, int TS, bool VT>
; DEVI void gemm_epilogue(const Params& p, char* smem, f32x4 (&acc)[2][2][4][2], int m0, int n0, float scale, const float* ssin,
;                         float* ssout, u16* xbout, int wid, int lane, int wr, int wc, int fr, int fq) {
;     ...
;           if constexpr (EPI == E_RESID || EPI == E_PLEGATE) {
;             const float4 a = *(const float4*)(Tr + 4 * lane);
;             const size_t ro = (size_t)grow * 1024 + n0 + 4 * lane;
;             float4 x4 = xo[u];
;             if constexpr (EPI == E_PLEGATE) {
;               x4.x += bflo(pv[u].x) * fsig(a.x * rs);
;               x4.y += bfhi(pv[u].x) * fsig(a.y * rs);
;               x4.z += bflo(pv[u].y) * fsig(a.z * rs);
;               x4.w += bfhi(pv[u].y) * fsig(a.w * rs);
;             } else {
;               const float sc = fabsf(scale);
;               x4.x += sc * a.x; x4.y += sc * a.y; x4.z += sc * a.z; x4.w += sc * a.w;
;             }
;             st_nt16(p.x + ro, x4);
;             if (xbout) {
;               uint2 o;
;               o.x = pack2(x4.x, x4.y);
;               o.y = pack2(x4.z, x4.w);
;               st_nt8(xbout + ro, o);
;             }
;             if (ssout) {
;               const float ssq = wsum(x4.x * x4.x + x4.y * x4.y + x4.z * x4.z + x4.w * x4.w, lane);
;               if (lane == 0) atomicAdd(ssout + grow, ssq);
;             }
.LBB0_1043:
	s_or_b64 exec, exec, s[22:23]
	ds_read_b128 v[80:83], v120 offset:12480
	v_lshl_add_u64 v[84:85], v[106:107], 1, s[4:5]
	s_waitcnt lgkmcnt(0)
	v_pk_add_f32 v[76:77], v[76:77], v[80:81]
	v_pk_add_f32 v[78:79], v[78:79], v[82:83]
	global_store_dwordx4 v[104:105], v[76:79], off
	v_cvt_pk_bf16_f32 v80, v76, v77
	v_cvt_pk_bf16_f32 v81, v78, v79
	v_pk_mul_f32 v[76:77], v[76:77], v[76:77]
	v_pk_mul_f32 v[78:79], v[78:79], v[78:79]
	v_add_f32_e32 v76, v76, v77
	v_add_f32_e32 v76, v76, v78
	v_add_f32_e32 v76, v76, v79
	flat_store_dwordx2 v[84:85], v[80:81]
	s_nop 0
	v_add_f32_dpp v76, v76, v76 row_ror:8 row_mask:0xf bank_mask:0xf bound_ctrl:1
	s_nop 1
	v_add_f32_dpp v76, v76, v76 row_ror:4 row_mask:0xf bank_mask:0xf bound_ctrl:1
	s_nop 1
	v_add_f32_dpp v76, v76, v76 row_ror:2 row_mask:0xf bank_mask:0xf bound_ctrl:1
	s_nop 1
	v_add_f32_dpp v76, v76, v76 row_ror:1 row_mask:0xf bank_mask:0xf bound_ctrl:1
	s_nop 0
	v_readlane_b32 s9, v76, 0
	v_readlane_b32 s30, v76, 16
	v_readlane_b32 s22, v76, 32
	v_readlane_b32 s23, v76, 48
	s_and_saveexec_b64 s[20:21], vcc
	s_cbranch_execz .LBB0_1045
	s_lshl_b64 s[18:19], s[18:19], 2
	v_mov_b32_e32 v76, s30
	s_add_u32 s18, s65, s18
	v_add_f32_e32 v76, s9, v76
	s_addc_u32 s19, s66, s19
	v_add_f32_e32 v76, s22, v76
	v_add_f32_e32 v78, s23, v76
	v_mov_b64_e32 v[76:77], s[18:19]
	flat_atomic_add_f32 v[76:77], v78
.LBB0_1045:
	s_or_b64 exec, exec, s[20:21]
	ds_read_b128 v[76:79], v120 offset:13520
	v_lshl_add_u64 v[80:81], v[102:103], 1, s[4:5]
	s_waitcnt lgkmcnt(0)
	v_pk_add_f32 v[72:73], v[72:73], v[76:77]
	v_pk_add_f32 v[74:75], v[74:75], v[78:79]
	global_store_dwordx4 v[100:101], v[72:75], off
	v_cvt_pk_bf16_f32 v76, v72, v73
	v_cvt_pk_bf16_f32 v77, v74, v75
	v_pk_mul_f32 v[72:73], v[72:73], v[72:73]
	v_pk_mul_f32 v[74:75], v[74:75], v[74:75]
	v_add_f32_e32 v72, v72, v73
	v_add_f32_e32 v72, v72, v74
	v_add_f32_e32 v72, v72, v75
	flat_store_dwordx2 v[80:81], v[76:77]
	s_nop 0
	v_add_f32_dpp v72, v72, v72 row_ror:8 row_mask:0xf bank_mask:0xf bound_ctrl:1
	s_nop 1
	v_add_f32_dpp v72, v72, v72 row_ror:4 row_mask:0xf bank_mask:0xf bound_ctrl:1
	s_nop 1
	v_add_f32_dpp v72, v72, v72 row_ror:2 row_mask:0xf bank_mask:0xf bound_ctrl:1
	s_nop 1
	v_add_f32_dpp v72, v72, v72 row_ror:1 row_mask:0xf bank_mask:0xf bound_ctrl:1
	s_nop 0
	v_readlane_b32 s9, v72, 0
	v_readlane_b32 s22, v72, 16
	v_readlane_b32 s20, v72, 32
	v_readlane_b32 s21, v72, 48
	s_and_saveexec_b64 s[18:19], vcc
	s_cbranch_execz .LBB0_1047
	s_lshl_b64 s[14:15], s[14:15], 2
	v_mov_b32_e32 v72, s22
	s_add_u32 s14, s65, s14
	v_add_f32_e32 v72, s9, v72
	s_addc_u32 s15, s66, s15
	v_add_f32_e32 v72, s20, v72
	v_add_f32_e32 v74, s21, v72
	v_mov_b64_e32 v[72:73], s[14:15]
	flat_atomic_add_f32 v[72:73], v74
.LBB0_1047:
	s_or_b64 exec, exec, s[18:19]
	ds_read_b128 v[72:75], v120 offset:14560
	v_lshl_add_u64 v[76:77], v[98:99], 1, s[4:5]
	s_waitcnt lgkmcnt(0)
	v_pk_add_f32 v[68:69], v[68:69], v[72:73]
	v_pk_add_f32 v[70:71], v[70:71], v[74:75]
	global_store_dwordx4 v[96:97], v[68:71], off
	v_cvt_pk_bf16_f32 v72, v68, v69
	v_cvt_pk_bf16_f32 v73, v70, v71
	v_pk_mul_f32 v[68:69], v[68:69], v[68:69]
	v_pk_mul_f32 v[70:71], v[70:71], v[70:71]
	v_add_f32_e32 v68, v68, v69
	v_add_f32_e32 v68, v68, v70
	v_add_f32_e32 v68, v68, v71
	flat_store_dwordx2 v[76:77], v[72:73]
	s_nop 0
	v_add_f32_dpp v68, v68, v68 row_ror:8 row_mask:0xf bank_mask:0xf bound_ctrl:1
	s_nop 1
	v_add_f32_dpp v68, v68, v68 row_ror:4 row_mask:0xf bank_mask:0xf bound_ctrl:1
	s_nop 1
	v_add_f32_dpp v68, v68, v68 row_ror:2 row_mask:0xf bank_mask:0xf bound_ctrl:1
	s_nop 1
	v_add_f32_dpp v68, v68, v68 row_ror:1 row_mask:0xf bank_mask:0xf bound_ctrl:1
	s_nop 0
	v_readlane_b32 s9, v68, 0
	v_readlane_b32 s20, v68, 16
	v_readlane_b32 s18, v68, 32
	v_readlane_b32 s19, v68, 48
	s_and_saveexec_b64 s[14:15], vcc
	s_cbranch_execz .LBB0_1049
	s_lshl_b64 s[12:13], s[12:13], 2
	v_mov_b32_e32 v68, s20
	s_add_u32 s12, s65, s12
	v_add_f32_e32 v68, s9, v68
	s_addc_u32 s13, s66, s13
	v_add_f32_e32 v68, s18, v68
	v_add_f32_e32 v70, s19, v68
	v_mov_b64_e32 v[68:69], s[12:13]
	flat_atomic_add_f32 v[68:69], v70
.LBB0_1049:
	s_or_b64 exec, exec, s[14:15]
	ds_read_b128 v[68:71], v120 offset:15600
	v_lshl_add_u64 v[72:73], v[94:95], 1, s[4:5]
	s_waitcnt lgkmcnt(0)
	v_pk_add_f32 v[64:65], v[64:65], v[68:69]
	v_pk_add_f32 v[66:67], v[66:67], v[70:71]
	global_store_dwordx4 v[92:93], v[64:67], off
	v_cvt_pk_bf16_f32 v68, v64, v65
	v_cvt_pk_bf16_f32 v69, v66, v67
	v_pk_mul_f32 v[64:65], v[64:65], v[64:65]
	v_pk_mul_f32 v[66:67], v[66:67], v[66:67]
	v_add_f32_e32 v64, v64, v65
	v_add_f32_e32 v64, v64, v66
	v_add_f32_e32 v64, v64, v67
	flat_store_dwordx2 v[72:73], v[68:69]
	s_nop 0
	v_add_f32_dpp v64, v64, v64 row_ror:8 row_mask:0xf bank_mask:0xf bound_ctrl:1
	s_nop 1
	v_add_f32_dpp v64, v64, v64 row_ror:4 row_mask:0xf bank_mask:0xf bound_ctrl:1
	s_nop 1
	v_add_f32_dpp v64, v64, v64 row_ror:2 row_mask:0xf bank_mask:0xf bound_ctrl:1
	s_nop 1
	v_add_f32_dpp v64, v64, v64 row_ror:1 row_mask:0xf bank_mask:0xf bound_ctrl:1
	s_nop 0
	v_readlane_b32 s9, v64, 0
	v_readlane_b32 s18, v64, 16
	v_readlane_b32 s14, v64, 32
	v_readlane_b32 s15, v64, 48
	s_and_saveexec_b64 s[12:13], vcc
	s_cbranch_execz .LBB0_1051
	s_lshl_b64 s[10:11], s[10:11], 2
	v_mov_b32_e32 v64, s18
	s_add_u32 s10, s65, s10
	v_add_f32_e32 v64, s9, v64
	s_addc_u32 s11, s66, s11
	v_add_f32_e32 v64, s14, v64
	v_add_f32_e32 v66, s15, v64
	v_mov_b64_e32 v[64:65], s[10:11]
	flat_atomic_add_f32 v[64:65], v66
; template <int EPI, int TS, bool VT>
; DEVI void gemm_epilogue(const Params& p, char* smem, f32x4 (&acc)[2][2][4][2], int m0, int n0, float scale, const float* ssin,
;                         float* ssout, u16* xbout, int wid, int lane, int wr, int wc, int fr, int fq) {
;     ...
;       float* tw = T + (wr * 64 + fq * 4) * TS + wc * 32 + fr;
; #pragma unroll
;       for (int m = 0; m < 4; ++m)
; #pragma unroll
;         for (int j = 0; j < 4; ++j)
; #pragma unroll
;           for (int v = 0; v < 4; ++v) tw[(m * 16 + j) * TS + (v >> 1) * 128 + (v & 1) * 16] = acc[ai][v >> 1][m][v & 1][j];
;     }
;     __syncthreads();
;     const int r0 = wid * 16;
;     const int g0 = m0 + ai * 128 + r0;
;     if constexpr (!VT) {
;       float rsv = 1.f;
;       if constexpr (EPI == E_PLEGATE || EPI == E_F32 || EPI == E_SWIGLU || EPI == E_GLAIN)
;         rsv = rsqrtf(ssin[g0 + (lane & 15)] * (1.f / 1024.f) + EPS);
;       if constexpr (EPI == E_QROPE) rsv = rsqrtf(ssin[g0 + (lane & 15)] * (1.f / 384.f) + EPS);
;       if constexpr (EPI == E_KV) rsv = rsqrtf(ssin[g0 + (lane & 15)] * (1.f / 256.f) + EPS);
;       for (int i0 = 0; i0 < 16; i0 += 8) {
;         float4 xo[8];
;         uint2 pv[8];
;         if constexpr (EPI == E_RESID || EPI == E_PLEGATE) {
; #pragma unroll
;           for (int u = 0; u < 8; ++u) {
;             const size_t ro = (size_t)(g0 + i0 + u) * 1024 + n0 + 4 * lane;
;             const int gr = g0 + i0 + u;
;             const float* xs = p.x + ro;
;             if (scale < 0.f)
;               xs = (gr < MP ? p.x_prompt + ro : p.x_sample + (ro - (size_t)MP * 1024));
;             { const f32x4 t_ = __builtin_nontemporal_load((const f32x4*)xs); xo[u] = make_float4(t_[0], t_[1], t_[2], t_[3]); }
;     ...
;           if constexpr (EPI == E_RESID || EPI == E_PLEGATE) {
;             const float4 a = *(const float4*)(Tr + 4 * lane);
;             const size_t ro = (size_t)grow * 1024 + n0 + 4 * lane;
;             float4 x4 = xo[u];
;             if constexpr (EPI == E_PLEGATE) {
;               x4.x += bflo(pv[u].x) * fsig(a.x * rs);
;               x4.y += bfhi(pv[u].x) * fsig(a.y * rs);
;               x4.z += bflo(pv[u].y) * fsig(a.z * rs);
;               x4.w += bfhi(pv[u].y) * fsig(a.w * rs);
;             } else {
;               const float sc = fabsf(scale);
;               x4.x += sc * a.x; x4.y += sc * a.y; x4.z += sc * a.z; x4.w += sc * a.w;
.LBB0_1051:
	s_or_b64 exec, exec, s[12:13]
	s_add_i32 s34, s8, 0x80
	s_ashr_i32 s35, s34, 31
	s_lshl_b64 s[10:11], s[34:35], 10
	s_add_i32 s30, s8, 0x81
	v_lshl_add_u64 v[64:65], s[10:11], 0, v[128:129]
	s_ashr_i32 s31, s30, 31
	s_add_i32 s22, s8, 0x82
	v_lshl_add_u64 v[66:67], v[64:65], 2, s[38:39]
	s_lshl_b64 s[10:11], s[30:31], 10
	s_ashr_i32 s23, s22, 31
	s_add_i32 s20, s8, 0x83
	s_waitcnt lgkmcnt(0)
	s_barrier
	ds_write2_b32 v130, v24, v28 offset1:16
	ds_write2_b32 v130, v56, v60 offset0:128 offset1:144
	ds_write2_b32 v124, v25, v29 offset0:4 offset1:20
	ds_write2_b32 v124, v57, v61 offset0:132 offset1:148
	ds_write2_b32 v121, v26, v30 offset0:8 offset1:24
	ds_write2_b32 v121, v58, v62 offset0:136 offset1:152
	ds_write2_b32 v122, v27, v31 offset0:12 offset1:28
	ds_write2_b32 v122, v59, v63 offset0:140 offset1:156
	ds_write2_b32 v123, v16, v20 offset0:64 offset1:80
	ds_write2_b32 v123, v48, v52 offset0:192 offset1:208
	ds_write2_b32 v125, v17, v21 offset0:68 offset1:84
	ds_write2_b32 v125, v49, v53 offset0:196 offset1:212
	ds_write2_b32 v126, v18, v22 offset0:72 offset1:88
	ds_write2_b32 v126, v50, v54 offset0:200 offset1:216
	ds_write2_b32 v127, v19, v23 offset0:76 offset1:92
	ds_write2_b32 v127, v51, v55 offset0:204 offset1:220
	ds_write2_b32 v131, v8, v12 offset0:128 offset1:144
	ds_write2_b32 v132, v40, v44 offset1:16
	ds_write2_b32 v132, v9, v13 offset0:132 offset1:148
	ds_write2_b32 v133, v41, v45 offset0:4 offset1:20
	ds_write2_b32 v133, v10, v14 offset0:136 offset1:152
	ds_write2_b32 v134, v42, v46 offset0:8 offset1:24
	ds_write2_b32 v134, v11, v15 offset0:140 offset1:156
	ds_write2_b32 v135, v43, v47 offset0:12 offset1:28
	ds_write2_b32 v136, v0, v4 offset0:192 offset1:208
	ds_write2_b32 v137, v32, v36 offset0:64 offset1:80
	ds_write2_b32 v137, v1, v5 offset0:196 offset1:212
	ds_write2_b32 v138, v33, v37 offset0:68 offset1:84
	ds_write2_b32 v138, v2, v6 offset0:200 offset1:216
	ds_write2_b32 v139, v34, v38 offset0:72 offset1:88
	ds_write2_b32 v139, v3, v7 offset0:204 offset1:220
	ds_write2_b32 v140, v35, v39 offset0:76 offset1:92
	s_waitcnt lgkmcnt(0)
	s_barrier
	global_load_dwordx4 v[56:59], v[66:67], off
	v_lshl_add_u64 v[54:55], s[10:11], 0, v[128:129]
	s_lshl_b64 s[10:11], s[22:23], 10
	s_ashr_i32 s21, s20, 31
	s_add_i32 s18, s8, 0x84
	v_lshl_add_u64 v[50:51], s[10:11], 0, v[128:129]
	s_lshl_b64 s[10:11], s[20:21], 10
	s_ashr_i32 s19, s18, 31
	s_add_i32 s14, s8, 0x85
	v_lshl_add_u64 v[46:47], s[10:11], 0, v[128:129]
	s_lshl_b64 s[10:11], s[18:19], 10
	s_ashr_i32 s15, s14, 31
	s_add_i32 s12, s8, 0x86
	v_lshl_add_u64 v[42:43], s[10:11], 0, v[128:129]
	s_lshl_b64 s[10:11], s[14:15], 10
	s_ashr_i32 s13, s12, 31
	v_lshl_add_u64 v[38:39], s[10:11], 0, v[128:129]
	s_lshl_b64 s[10:11], s[12:13], 10
	v_lshl_add_u64 v[34:35], s[10:11], 0, v[128:129]
	s_add_i32 s10, s8, 0x87
	s_ashr_i32 s11, s10, 31
	s_lshl_b64 s[62:63], s[10:11], 10
	v_lshl_add_u64 v[30:31], s[62:63], 0, v[128:129]
	v_lshl_add_u64 v[52:53], v[54:55], 2, s[38:39]
	v_lshl_add_u64 v[44:45], v[46:47], 2, s[38:39]
	v_lshl_add_u64 v[36:37], v[38:39], 2, s[38:39]
	v_lshl_add_u64 v[28:29], v[30:31], 2, s[38:39]
	v_lshl_add_u64 v[48:49], v[50:51], 2, s[38:39]
	global_load_dwordx4 v[24:27], v[52:53], off
	global_load_dwordx4 v[20:23], v[48:49], off
	v_lshl_add_u64 v[40:41], v[42:43], 2, s[38:39]
	global_load_dwordx4 v[16:19], v[44:45], off
	global_load_dwordx4 v[12:15], v[40:41], off
	v_lshl_add_u64 v[32:33], v[34:35], 2, s[38:39]
	global_load_dwordx4 v[8:11], v[36:37], off
	global_load_dwordx4 v[4:7], v[32:33], off
	global_load_dwordx4 v[0:3], v[28:29], off
	ds_read_b128 v[60:63], v120
	s_waitcnt vmcnt(0) lgkmcnt(0)
	v_pk_add_f32 v[56:57], v[56:57], v[60:61]
	v_pk_add_f32 v[58:59], v[58:59], v[62:63]
	global_store_dwordx4 v[66:67], v[56:59], off
	v_cvt_pk_bf16_f32 v60, v56, v57
	v_cvt_pk_bf16_f32 v61, v58, v59
	v_pk_mul_f32 v[56:57], v[56:57], v[56:57]
	v_pk_mul_f32 v[58:59], v[58:59], v[58:59]
	v_add_f32_e32 v56, v56, v57
	v_add_f32_e32 v56, v56, v58
	v_add_f32_e32 v56, v56, v59
	v_lshl_add_u64 v[62:63], v[64:65], 1, s[4:5]
	flat_store_dwordx2 v[62:63], v[60:61]
	v_add_f32_dpp v56, v56, v56 row_ror:8 row_mask:0xf bank_mask:0xf bound_ctrl:1
	s_nop 1
	v_add_f32_dpp v56, v56, v56 row_ror:4 row_mask:0xf bank_mask:0xf bound_ctrl:1
	s_nop 1
	v_add_f32_dpp v56, v56, v56 row_ror:2 row_mask:0xf bank_mask:0xf bound_ctrl:1
	s_nop 1
	v_add_f32_dpp v56, v56, v56 row_ror:1 row_mask:0xf bank_mask:0xf bound_ctrl:1
	s_nop 0
	v_readlane_b32 s9, v56, 0
	v_readlane_b32 s71, v56, 16
	v_readlane_b32 s69, v56, 32
	v_readlane_b32 s70, v56, 48
	s_and_saveexec_b64 s[62:63], vcc
	s_cbranch_execz .LBB0_1053
	s_lshl_b64 s[34:35], s[34:35], 2
	v_mov_b32_e32 v56, s71
	s_add_u32 s34, s65, s34
	v_add_f32_e32 v56, s9, v56
	s_addc_u32 s35, s66, s35
	v_add_f32_e32 v56, s69, v56
	v_add_f32_e32 v58, s70, v56
	v_mov_b64_e32 v[56:57], s[34:35]
	flat_atomic_add_f32 v[56:57], v58
.LBB0_1053:
	s_or_b64 exec, exec, s[62:63]
	ds_read_b128 v[56:59], v120 offset:1040
	v_lshl_add_u64 v[54:55], v[54:55], 1, s[4:5]
	s_waitcnt lgkmcnt(0)
	v_pk_add_f32 v[24:25], v[24:25], v[56:57]
	v_pk_add_f32 v[26:27], v[26:27], v[58:59]
	global_store_dwordx4 v[52:53], v[24:27], off
	v_cvt_pk_bf16_f32 v52, v24, v25
	v_cvt_pk_bf16_f32 v53, v26, v27
	v_pk_mul_f32 v[24:25], v[24:25], v[24:25]
	v_pk_mul_f32 v[26:27], v[26:27], v[26:27]
	v_add_f32_e32 v24, v24, v25
	v_add_f32_e32 v24, v24, v26
	v_add_f32_e32 v24, v24, v27
	flat_store_dwordx2 v[54:55], v[52:53]
	s_nop 0
	v_add_f32_dpp v24, v24, v24 row_ror:8 row_mask:0xf bank_mask:0xf bound_ctrl:1
	s_nop 1
	v_add_f32_dpp v24, v24, v24 row_ror:4 row_mask:0xf bank_mask:0xf bound_ctrl:1
	s_nop 1
	v_add_f32_dpp v24, v24, v24 row_ror:2 row_mask:0xf bank_mask:0xf bound_ctrl:1
	s_nop 1
	v_add_f32_dpp v24, v24, v24 row_ror:1 row_mask:0xf bank_mask:0xf bound_ctrl:1
	s_nop 0
	v_readlane_b32 s9, v24, 0
	v_readlane_b32 s69, v24, 16
	v_readlane_b32 s62, v24, 32
	v_readlane_b32 s63, v24, 48
	s_and_saveexec_b64 s[34:35], vcc
	s_cbranch_execz .LBB0_1055
	s_lshl_b64 s[30:31], s[30:31], 2
	v_mov_b32_e32 v24, s69
	s_add_u32 s30, s65, s30
	v_add_f32_e32 v24, s9, v24
	s_addc_u32 s31, s66, s31
	v_add_f32_e32 v24, s62, v24
	v_add_f32_e32 v26, s63, v24
	v_mov_b64_e32 v[24:25], s[30:31]
	flat_atomic_add_f32 v[24:25], v26
; DEVI float fsig(float x) { return __builtin_amdgcn_rcpf(1.f + __expf(-x)); }
; DEVI float bflo(unsigned u) { return __uint_as_float(u << 16); }
; DEVI float bfhi(unsigned u) { return __uint_as_float(u & 0xffff0000u); }
; template <int EPI, int TS, bool VT>
; DEVI void gemm_epilogue(const Params& p, char* smem, f32x4 (&acc)[2][2][4][2], int m0, int n0, float scale, const float* ssin,
;                         float* ssout, u16* xbout, int wid, int lane, int wr, int wc, int fr, int fq) {
;     ...
;           if constexpr (EPI == E_RESID || EPI == E_PLEGATE) {
;             const float4 a = *(const float4*)(Tr + 4 * lane);
;             const size_t ro = (size_t)grow * 1024 + n0 + 4 * lane;
;             float4 x4 = xo[u];
;             if constexpr (EPI == E_PLEGATE) {
;               x4.x += bflo(pv[u].x) * fsig(a.x * rs);
;               x4.y += bfhi(pv[u].x) * fsig(a.y * rs);
;               x4.z += bflo(pv[u].y) * fsig(a.z * rs);
;               x4.w += bfhi(pv[u].y) * fsig(a.w * rs);
;             } else {
;               const float sc = fabsf(scale);
;               x4.x += sc * a.x; x4.y += sc * a.y; x4.z += sc * a.z; x4.w += sc * a.w;
;             }
;             st_nt16(p.x + ro, x4);
;             if (xbout) {
;               uint2 o;
;               o.x = pack2(x4.x, x4.y);
;               o.y = pack2(x4.z, x4.w);
;               st_nt8(xbout + ro, o);
;             }
;             if (ssout) {
;               const float ssq = wsum(x4.x * x4.x + x4.y * x4.y + x4.z * x4.z + x4.w * x4.w, lane);
;               if (lane == 0) atomicAdd(ssout + grow, ssq);
;             }
.LBB0_1055:
	s_or_b64 exec, exec, s[34:35]
	ds_read_b128 v[24:27], v120 offset:2080
	v_lshl_add_u64 v[50:51], v[50:51], 1, s[4:5]
	s_waitcnt lgkmcnt(0)
	v_pk_add_f32 v[20:21], v[20:21], v[24:25]
	v_pk_add_f32 v[22:23], v[22:23], v[26:27]
	global_store_dwordx4 v[48:49], v[20:23], off
	v_cvt_pk_bf16_f32 v24, v20, v21
	v_cvt_pk_bf16_f32 v25, v22, v23
	v_pk_mul_f32 v[20:21], v[20:21], v[20:21]
	v_pk_mul_f32 v[22:23], v[22:23], v[22:23]
	v_add_f32_e32 v20, v20, v21
	v_add_f32_e32 v20, v20, v22
	v_add_f32_e32 v20, v20, v23
	flat_store_dwordx2 v[50:51], v[24:25]
	s_nop 0
	v_add_f32_dpp v20, v20, v20 row_ror:8 row_mask:0xf bank_mask:0xf bound_ctrl:1
	s_nop 1
	v_add_f32_dpp v20, v20, v20 row_ror:4 row_mask:0xf bank_mask:0xf bound_ctrl:1
	s_nop 1
	v_add_f32_dpp v20, v20, v20 row_ror:2 row_mask:0xf bank_mask:0xf bound_ctrl:1
	s_nop 1
	v_add_f32_dpp v20, v20, v20 row_ror:1 row_mask:0xf bank_mask:0xf bound_ctrl:1
	s_nop 0
	v_readlane_b32 s9, v20, 0
	v_readlane_b32 s62, v20, 16
	v_readlane_b32 s34, v20, 32
	v_readlane_b32 s35, v20, 48
	s_and_saveexec_b64 s[30:31], vcc
	s_cbranch_execz .LBB0_1057
	s_lshl_b64 s[22:23], s[22:23], 2
	v_mov_b32_e32 v20, s62
	s_add_u32 s22, s65, s22
	v_add_f32_e32 v20, s9, v20
	s_addc_u32 s23, s66, s23
	v_add_f32_e32 v20, s34, v20
	v_add_f32_e32 v22, s35, v20
	v_mov_b64_e32 v[20:21], s[22:23]
	flat_atomic_add_f32 v[20:21], v22
.LBB0_1057:
	s_or_b64 exec, exec, s[30:31]
	ds_read_b128 v[20:23], v120 offset:3120
	v_lshl_add_u64 v[24:25], v[46:47], 1, s[4:5]
	s_waitcnt lgkmcnt(0)
	v_pk_add_f32 v[16:17], v[16:17], v[20:21]
	v_pk_add_f32 v[18:19], v[18:19], v[22:23]
	global_store_dwordx4 v[44:45], v[16:19], off
	v_cvt_pk_bf16_f32 v20, v16, v17
	v_cvt_pk_bf16_f32 v21, v18, v19
	v_pk_mul_f32 v[16:17], v[16:17], v[16:17]
	v_pk_mul_f32 v[18:19], v[18:19], v[18:19]
	v_add_f32_e32 v16, v16, v17
	v_add_f32_e32 v16, v16, v18
	v_add_f32_e32 v16, v16, v19
	flat_store_dwordx2 v[24:25], v[20:21]
	s_nop 0
	v_add_f32_dpp v16, v16, v16 row_ror:8 row_mask:0xf bank_mask:0xf bound_ctrl:1
	s_nop 1
	v_add_f32_dpp v16, v16, v16 row_ror:4 row_mask:0xf bank_mask:0xf bound_ctrl:1
	s_nop 1
	v_add_f32_dpp v16, v16, v16 row_ror:2 row_mask:0xf bank_mask:0xf bound_ctrl:1
	s_nop 1
	v_add_f32_dpp v16, v16, v16 row_ror:1 row_mask:0xf bank_mask:0xf bound_ctrl:1
	s_nop 0
	v_readlane_b32 s9, v16, 0
	v_readlane_b32 s34, v16, 16
	v_readlane_b32 s30, v16, 32
	v_readlane_b32 s31, v16, 48
	s_and_saveexec_b64 s[22:23], vcc
	s_cbranch_execz .LBB0_1059
	s_lshl_b64 s[20:21], s[20:21], 2
	v_mov_b32_e32 v16, s34
	s_add_u32 s20, s65, s20
	v_add_f32_e32 v16, s9, v16
	s_addc_u32 s21, s66, s21
	v_add_f32_e32 v16, s30, v16
	v_add_f32_e32 v18, s31, v16
	v_mov_b64_e32 v[16:17], s[20:21]
	flat_atomic_add_f32 v[16:17], v18
.LBB0_1059:
	s_or_b64 exec, exec, s[22:23]
	ds_read_b128 v[16:19], v120 offset:4160
	v_lshl_add_u64 v[20:21], v[42:43], 1, s[4:5]
	s_waitcnt lgkmcnt(0)
	v_pk_add_f32 v[12:13], v[12:13], v[16:17]
	v_pk_add_f32 v[14:15], v[14:15], v[18:19]
	global_store_dwordx4 v[40:41], v[12:15], off
	v_cvt_pk_bf16_f32 v16, v12, v13
	v_cvt_pk_bf16_f32 v17, v14, v15
	v_pk_mul_f32 v[12:13], v[12:13], v[12:13]
	v_pk_mul_f32 v[14:15], v[14:15], v[14:15]
	v_add_f32_e32 v12, v12, v13
	v_add_f32_e32 v12, v12, v14
	v_add_f32_e32 v12, v12, v15
	flat_store_dwordx2 v[20:21], v[16:17]
	s_nop 0
	v_add_f32_dpp v12, v12, v12 row_ror:8 row_mask:0xf bank_mask:0xf bound_ctrl:1
	s_nop 1
	v_add_f32_dpp v12, v12, v12 row_ror:4 row_mask:0xf bank_mask:0xf bound_ctrl:1
	s_nop 1
	v_add_f32_dpp v12, v12, v12 row_ror:2 row_mask:0xf bank_mask:0xf bound_ctrl:1
	s_nop 1
	v_add_f32_dpp v12, v12, v12 row_ror:1 row_mask:0xf bank_mask:0xf bound_ctrl:1
	s_nop 0
	v_readlane_b32 s9, v12, 0
	v_readlane_b32 s30, v12, 16
	v_readlane_b32 s22, v12, 32
	v_readlane_b32 s23, v12, 48
	s_and_saveexec_b64 s[20:21], vcc
	s_cbranch_execz .LBB0_1061
	s_lshl_b64 s[18:19], s[18:19], 2
	v_mov_b32_e32 v12, s30
	s_add_u32 s18, s65, s18
	v_add_f32_e32 v12, s9, v12
	s_addc_u32 s19, s66, s19
	v_add_f32_e32 v12, s22, v12
	v_add_f32_e32 v14, s23, v12
	v_mov_b64_e32 v[12:13], s[18:19]
	flat_atomic_add_f32 v[12:13], v14
.LBB0_1061:
	s_or_b64 exec, exec, s[20:21]
	ds_read_b128 v[12:15], v120 offset:5200
	v_lshl_add_u64 v[16:17], v[38:39], 1, s[4:5]
	s_waitcnt lgkmcnt(0)
	v_pk_add_f32 v[8:9], v[8:9], v[12:13]
	v_pk_add_f32 v[10:11], v[10:11], v[14:15]
	global_store_dwordx4 v[36:37], v[8:11], off
	v_cvt_pk_bf16_f32 v12, v8, v9
	v_cvt_pk_bf16_f32 v13, v10, v11
	v_pk_mul_f32 v[8:9], v[8:9], v[8:9]
	v_pk_mul_f32 v[10:11], v[10:11], v[10:11]
	v_add_f32_e32 v8, v8, v9
	v_add_f32_e32 v8, v8, v10
	v_add_f32_e32 v8, v8, v11
	flat_store_dwordx2 v[16:17], v[12:13]
	s_nop 0
	v_add_f32_dpp v8, v8, v8 row_ror:8 row_mask:0xf bank_mask:0xf bound_ctrl:1
	s_nop 1
	v_add_f32_dpp v8, v8, v8 row_ror:4 row_mask:0xf bank_mask:0xf bound_ctrl:1
	s_nop 1
	v_add_f32_dpp v8, v8, v8 row_ror:2 row_mask:0xf bank_mask:0xf bound_ctrl:1
	s_nop 1
	v_add_f32_dpp v8, v8, v8 row_ror:1 row_mask:0xf bank_mask:0xf bound_ctrl:1
	s_nop 0
	v_readlane_b32 s9, v8, 0
	v_readlane_b32 s22, v8, 16
	v_readlane_b32 s20, v8, 32
	v_readlane_b32 s21, v8, 48
	s_and_saveexec_b64 s[18:19], vcc
	s_cbranch_execz .LBB0_1063
	s_lshl_b64 s[14:15], s[14:15], 2
	v_mov_b32_e32 v8, s22
	s_add_u32 s14, s65, s14
	v_add_f32_e32 v8, s9, v8
	s_addc_u32 s15, s66, s15
	v_add_f32_e32 v8, s20, v8
	v_add_f32_e32 v10, s21, v8
	v_mov_b64_e32 v[8:9], s[14:15]
	flat_atomic_add_f32 v[8:9], v10
; DEVI float fsig(float x) { return __builtin_amdgcn_rcpf(1.f + __expf(-x)); }
; DEVI float bflo(unsigned u) { return __uint_as_float(u << 16); }
; DEVI float bfhi(unsigned u) { return __uint_as_float(u & 0xffff0000u); }
; template <int EPI, int TS, bool VT>
; DEVI void gemm_epilogue(const Params& p, char* smem, f32x4 (&acc)[2][2][4][2], int m0, int n0, float scale, const float* ssin,
;                         float* ssout, u16* xbout, int wid, int lane, int wr, int wc, int fr, int fq) {
;     ...
;         if constexpr (EPI == E_RESID || EPI == E_PLEGATE) {
; #pragma unroll
;           for (int u = 0; u < 8; ++u) {
;             const size_t ro = (size_t)(g0 + i0 + u) * 1024 + n0 + 4 * lane;
;             const int gr = g0 + i0 + u;
;             const float* xs = p.x + ro;
;             if (scale < 0.f)
;               xs = (gr < MP ? p.x_prompt + ro : p.x_sample + (ro - (size_t)MP * 1024));
;             { const f32x4 t_ = __builtin_nontemporal_load((const f32x4*)xs); xo[u] = make_float4(t_[0], t_[1], t_[2], t_[3]); }
;     ...
;           if constexpr (EPI == E_RESID || EPI == E_PLEGATE) {
;             const float4 a = *(const float4*)(Tr + 4 * lane);
;             const size_t ro = (size_t)grow * 1024 + n0 + 4 * lane;
;             float4 x4 = xo[u];
;             if constexpr (EPI == E_PLEGATE) {
;               x4.x += bflo(pv[u].x) * fsig(a.x * rs);
;               x4.y += bfhi(pv[u].x) * fsig(a.y * rs);
;               x4.z += bflo(pv[u].y) * fsig(a.z * rs);
;               x4.w += bfhi(pv[u].y) * fsig(a.w * rs);
;             } else {
;               const float sc = fabsf(scale);
;               x4.x += sc * a.x; x4.y += sc * a.y; x4.z += sc * a.z; x4.w += sc * a.w;
;             }
;             st_nt16(p.x + ro, x4);
;             if (xbout) {
;               uint2 o;
;               o.x = pack2(x4.x, x4.y);
;               o.y = pack2(x4.z, x4.w);
;               st_nt8(xbout + ro, o);
;             }
;             if (ssout) {
;               const float ssq = wsum(x4.x * x4.x + x4.y * x4.y + x4.z * x4.z + x4.w * x4.w, lane);
;               if (lane == 0) atomicAdd(ssout + grow, ssq);
;             }
.LBB0_1063:
	s_or_b64 exec, exec, s[18:19]
	ds_read_b128 v[8:11], v120 offset:6240
	v_lshl_add_u64 v[12:13], v[34:35], 1, s[4:5]
	s_waitcnt lgkmcnt(0)
	v_pk_add_f32 v[4:5], v[4:5], v[8:9]
	v_pk_add_f32 v[6:7], v[6:7], v[10:11]
	global_store_dwordx4 v[32:33], v[4:7], off
	v_cvt_pk_bf16_f32 v8, v4, v5
	v_cvt_pk_bf16_f32 v9, v6, v7
	v_pk_mul_f32 v[4:5], v[4:5], v[4:5]
	v_pk_mul_f32 v[6:7], v[6:7], v[6:7]
	v_add_f32_e32 v4, v4, v5
	v_add_f32_e32 v4, v4, v6
	v_add_f32_e32 v4, v4, v7
	flat_store_dwordx2 v[12:13], v[8:9]
	s_nop 0
	v_add_f32_dpp v4, v4, v4 row_ror:8 row_mask:0xf bank_mask:0xf bound_ctrl:1
	s_nop 1
	v_add_f32_dpp v4, v4, v4 row_ror:4 row_mask:0xf bank_mask:0xf bound_ctrl:1
	s_nop 1
	v_add_f32_dpp v4, v4, v4 row_ror:2 row_mask:0xf bank_mask:0xf bound_ctrl:1
	s_nop 1
	v_add_f32_dpp v4, v4, v4 row_ror:1 row_mask:0xf bank_mask:0xf bound_ctrl:1
	s_nop 0
	v_readlane_b32 s9, v4, 0
	v_readlane_b32 s20, v4, 16
	v_readlane_b32 s18, v4, 32
	v_readlane_b32 s19, v4, 48
	s_and_saveexec_b64 s[14:15], vcc
	s_cbranch_execz .LBB0_1065
	s_lshl_b64 s[12:13], s[12:13], 2
	v_mov_b32_e32 v4, s20
	s_add_u32 s12, s65, s12
	v_add_f32_e32 v4, s9, v4
	s_addc_u32 s13, s66, s13
	v_add_f32_e32 v4, s18, v4
	v_add_f32_e32 v6, s19, v4
	v_mov_b64_e32 v[4:5], s[12:13]
	flat_atomic_add_f32 v[4:5], v6
.LBB0_1065:
	s_or_b64 exec, exec, s[14:15]
	ds_read_b128 v[4:7], v120 offset:7280
	v_lshl_add_u64 v[8:9], v[30:31], 1, s[4:5]
	s_waitcnt lgkmcnt(0)
	v_pk_add_f32 v[0:1], v[0:1], v[4:5]
	v_pk_add_f32 v[2:3], v[2:3], v[6:7]
	global_store_dwordx4 v[28:29], v[0:3], off
	v_cvt_pk_bf16_f32 v4, v0, v1
	v_cvt_pk_bf16_f32 v5, v2, v3
	v_pk_mul_f32 v[0:1], v[0:1], v[0:1]
	v_pk_mul_f32 v[2:3], v[2:3], v[2:3]
	v_add_f32_e32 v0, v0, v1
	v_add_f32_e32 v0, v0, v2
	v_add_f32_e32 v0, v0, v3
	flat_store_dwordx2 v[8:9], v[4:5]
	s_nop 0
	v_add_f32_dpp v0, v0, v0 row_ror:8 row_mask:0xf bank_mask:0xf bound_ctrl:1
	s_nop 1
	v_add_f32_dpp v0, v0, v0 row_ror:4 row_mask:0xf bank_mask:0xf bound_ctrl:1
	s_nop 1
	v_add_f32_dpp v0, v0, v0 row_ror:2 row_mask:0xf bank_mask:0xf bound_ctrl:1
	s_nop 1
	v_add_f32_dpp v0, v0, v0 row_ror:1 row_mask:0xf bank_mask:0xf bound_ctrl:1
	s_nop 0
	v_readlane_b32 s9, v0, 0
	v_readlane_b32 s18, v0, 16
	v_readlane_b32 s14, v0, 32
	v_readlane_b32 s15, v0, 48
	s_and_saveexec_b64 s[12:13], vcc
	s_cbranch_execz .LBB0_1067
	s_lshl_b64 s[10:11], s[10:11], 2
	v_mov_b32_e32 v0, s18
	s_add_u32 s10, s65, s10
	v_add_f32_e32 v0, s9, v0
	s_addc_u32 s11, s66, s11
	v_add_f32_e32 v0, s14, v0
	v_add_f32_e32 v2, s15, v0
	v_mov_b64_e32 v[0:1], s[10:11]
	flat_atomic_add_f32 v[0:1], v2
.LBB0_1067:
	s_or_b64 exec, exec, s[12:13]
	s_add_i32 s30, s8, 0x88
	s_ashr_i32 s31, s30, 31
	s_lshl_b64 s[10:11], s[30:31], 10
	s_add_i32 s22, s8, 0x89
	v_lshl_add_u64 v[64:65], s[10:11], 0, v[128:129]
	s_ashr_i32 s23, s22, 31
	s_add_i32 s20, s8, 0x8a
	v_lshl_add_u64 v[66:67], v[64:65], 2, s[38:39]
	s_lshl_b64 s[10:11], s[22:23], 10
	s_ashr_i32 s21, s20, 31
	s_add_i32 s18, s8, 0x8b
	global_load_dwordx4 v[56:59], v[66:67], off
	v_lshl_add_u64 v[54:55], s[10:11], 0, v[128:129]
	s_lshl_b64 s[10:11], s[20:21], 10
	s_ashr_i32 s19, s18, 31
	s_add_i32 s14, s8, 0x8c
	v_lshl_add_u64 v[50:51], s[10:11], 0, v[128:129]
	s_lshl_b64 s[10:11], s[18:19], 10
	s_ashr_i32 s15, s14, 31
	s_add_i32 s12, s8, 0x8d
	v_lshl_add_u64 v[46:47], s[10:11], 0, v[128:129]
	s_lshl_b64 s[10:11], s[14:15], 10
	s_ashr_i32 s13, s12, 31
	v_lshl_add_u64 v[42:43], s[10:11], 0, v[128:129]
	s_lshl_b64 s[10:11], s[12:13], 10
	v_lshl_add_u64 v[38:39], s[10:11], 0, v[128:129]
	s_add_i32 s10, s8, 0x8e
	s_ashr_i32 s11, s10, 31
	s_addk_i32 s8, 0x8f
	s_lshl_b64 s[34:35], s[10:11], 10
	s_ashr_i32 s9, s8, 31
	v_lshl_add_u64 v[34:35], s[34:35], 0, v[128:129]
	s_lshl_b64 s[34:35], s[8:9], 10
	v_lshl_add_u64 v[30:31], s[34:35], 0, v[128:129]
	v_lshl_add_u64 v[52:53], v[54:55], 2, s[38:39]
	v_lshl_add_u64 v[44:45], v[46:47], 2, s[38:39]
	v_lshl_add_u64 v[36:37], v[38:39], 2, s[38:39]
	v_lshl_add_u64 v[28:29], v[30:31], 2, s[38:39]
	v_lshl_add_u64 v[48:49], v[50:51], 2, s[38:39]
	global_load_dwordx4 v[24:27], v[52:53], off
	global_load_dwordx4 v[20:23], v[48:49], off
	v_lshl_add_u64 v[40:41], v[42:43], 2, s[38:39]
	global_load_dwordx4 v[16:19], v[44:45], off
	global_load_dwordx4 v[12:15], v[40:41], off
	v_lshl_add_u64 v[32:33], v[34:35], 2, s[38:39]
	global_load_dwordx4 v[8:11], v[36:37], off
	global_load_dwordx4 v[4:7], v[32:33], off
	global_load_dwordx4 v[0:3], v[28:29], off
	ds_read_b128 v[60:63], v120 offset:8320
	v_lshl_add_u64 v[64:65], v[64:65], 1, s[4:5]
	s_waitcnt vmcnt(0) lgkmcnt(0)
	v_pk_add_f32 v[56:57], v[56:57], v[60:61]
	v_pk_add_f32 v[58:59], v[58:59], v[62:63]
	global_store_dwordx4 v[66:67], v[56:59], off
	v_cvt_pk_bf16_f32 v60, v56, v57
	v_cvt_pk_bf16_f32 v61, v58, v59
	v_pk_mul_f32 v[56:57], v[56:57], v[56:57]
	v_pk_mul_f32 v[58:59], v[58:59], v[58:59]
	v_add_f32_e32 v56, v56, v57
	v_add_f32_e32 v56, v56, v58
	v_add_f32_e32 v56, v56, v59
	flat_store_dwordx2 v[64:65], v[60:61]
	s_nop 0
	v_add_f32_dpp v56, v56, v56 row_ror:8 row_mask:0xf bank_mask:0xf bound_ctrl:1
	s_nop 1
	v_add_f32_dpp v56, v56, v56 row_ror:4 row_mask:0xf bank_mask:0xf bound_ctrl:1
	s_nop 1
	v_add_f32_dpp v56, v56, v56 row_ror:2 row_mask:0xf bank_mask:0xf bound_ctrl:1
	s_nop 1
	v_add_f32_dpp v56, v56, v56 row_ror:1 row_mask:0xf bank_mask:0xf bound_ctrl:1
	s_nop 0
	v_readlane_b32 s62, v56, 0
	v_readlane_b32 s70, v56, 16
	v_readlane_b32 s63, v56, 32
	v_readlane_b32 s69, v56, 48
	s_and_saveexec_b64 s[34:35], vcc
	s_cbranch_execz .LBB0_1069
	s_lshl_b64 s[30:31], s[30:31], 2
	v_mov_b32_e32 v56, s70
	s_add_u32 s30, s65, s30
	v_add_f32_e32 v56, s62, v56
	s_addc_u32 s31, s66, s31
	v_add_f32_e32 v56, s63, v56
	v_add_f32_e32 v58, s69, v56
	v_mov_b64_e32 v[56:57], s[30:31]
	flat_atomic_add_f32 v[56:57], v58
; DEVI float fsig(float x) { return __builtin_amdgcn_rcpf(1.f + __expf(-x)); }
; DEVI float bflo(unsigned u) { return __uint_as_float(u << 16); }
; DEVI float bfhi(unsigned u) { return __uint_as_float(u & 0xffff0000u); }
; template <int EPI, int TS, bool VT>
; DEVI void gemm_epilogue(const Params& p, char* smem, f32x4 (&acc)[2][2][4][2], int m0, int n0, float scale, const float* ssin,
;                         float* ssout, u16* xbout, int wid, int lane, int wr, int wc, int fr, int fq) {
;     ...
;           if constexpr (EPI == E_RESID || EPI == E_PLEGATE) {
;             const float4 a = *(const float4*)(Tr + 4 * lane);
;             const size_t ro = (size_t)grow * 1024 + n0 + 4 * lane;
;             float4 x4 = xo[u];
;             if constexpr (EPI == E_PLEGATE) {
;               x4.x += bflo(pv[u].x) * fsig(a.x * rs);
;               x4.y += bfhi(pv[u].x) * fsig(a.y * rs);
;               x4.z += bflo(pv[u].y) * fsig(a.z * rs);
;               x4.w += bfhi(pv[u].y) * fsig(a.w * rs);
;             } else {
;               const float sc = fabsf(scale);
;               x4.x += sc * a.x; x4.y += sc * a.y; x4.z += sc * a.z; x4.w += sc * a.w;
;             }
;             st_nt16(p.x + ro, x4);
;             if (xbout) {
;               uint2 o;
;               o.x = pack2(x4.x, x4.y);
;               o.y = pack2(x4.z, x4.w);
;               st_nt8(xbout + ro, o);
;             }
;             if (ssout) {
;               const float ssq = wsum(x4.x * x4.x + x4.y * x4.y + x4.z * x4.z + x4.w * x4.w, lane);
;               if (lane == 0) atomicAdd(ssout + grow, ssq);
;             }
.LBB0_1069:
	s_or_b64 exec, exec, s[34:35]
	ds_read_b128 v[56:59], v120 offset:9360
	v_lshl_add_u64 v[54:55], v[54:55], 1, s[4:5]
	s_waitcnt lgkmcnt(0)
	v_pk_add_f32 v[24:25], v[24:25], v[56:57]
	v_pk_add_f32 v[26:27], v[26:27], v[58:59]
	global_store_dwordx4 v[52:53], v[24:27], off
	v_cvt_pk_bf16_f32 v52, v24, v25
	v_cvt_pk_bf16_f32 v53, v26, v27
	v_pk_mul_f32 v[24:25], v[24:25], v[24:25]
	v_pk_mul_f32 v[26:27], v[26:27], v[26:27]
	v_add_f32_e32 v24, v24, v25
	v_add_f32_e32 v24, v24, v26
	v_add_f32_e32 v24, v24, v27
	flat_store_dwordx2 v[54:55], v[52:53]
	s_nop 0
	v_add_f32_dpp v24, v24, v24 row_ror:8 row_mask:0xf bank_mask:0xf bound_ctrl:1
	s_nop 1
	v_add_f32_dpp v24, v24, v24 row_ror:4 row_mask:0xf bank_mask:0xf bound_ctrl:1
	s_nop 1
	v_add_f32_dpp v24, v24, v24 row_ror:2 row_mask:0xf bank_mask:0xf bound_ctrl:1
	s_nop 1
	v_add_f32_dpp v24, v24, v24 row_ror:1 row_mask:0xf bank_mask:0xf bound_ctrl:1
	s_nop 0
	v_readlane_b32 s34, v24, 0
	v_readlane_b32 s63, v24, 16
	v_readlane_b32 s35, v24, 32
	v_readlane_b32 s62, v24, 48
	s_and_saveexec_b64 s[30:31], vcc
	s_cbranch_execz .LBB0_1071
	s_lshl_b64 s[22:23], s[22:23], 2
	v_mov_b32_e32 v24, s63
	s_add_u32 s22, s65, s22
	v_add_f32_e32 v24, s34, v24
	s_addc_u32 s23, s66, s23
	v_add_f32_e32 v24, s35, v24
	v_add_f32_e32 v26, s62, v24
	v_mov_b64_e32 v[24:25], s[22:23]
	flat_atomic_add_f32 v[24:25], v26
.LBB0_1071:
	s_or_b64 exec, exec, s[30:31]
	ds_read_b128 v[24:27], v120 offset:10400
	v_lshl_add_u64 v[50:51], v[50:51], 1, s[4:5]
	s_waitcnt lgkmcnt(0)
	v_pk_add_f32 v[20:21], v[20:21], v[24:25]
	v_pk_add_f32 v[22:23], v[22:23], v[26:27]
	global_store_dwordx4 v[48:49], v[20:23], off
	v_cvt_pk_bf16_f32 v24, v20, v21
	v_cvt_pk_bf16_f32 v25, v22, v23
	v_pk_mul_f32 v[20:21], v[20:21], v[20:21]
	v_pk_mul_f32 v[22:23], v[22:23], v[22:23]
	v_add_f32_e32 v20, v20, v21
	v_add_f32_e32 v20, v20, v22
	v_add_f32_e32 v20, v20, v23
	flat_store_dwordx2 v[50:51], v[24:25]
	s_nop 0
	v_add_f32_dpp v20, v20, v20 row_ror:8 row_mask:0xf bank_mask:0xf bound_ctrl:1
	s_nop 1
	v_add_f32_dpp v20, v20, v20 row_ror:4 row_mask:0xf bank_mask:0xf bound_ctrl:1
	s_nop 1
	v_add_f32_dpp v20, v20, v20 row_ror:2 row_mask:0xf bank_mask:0xf bound_ctrl:1
	s_nop 1
	v_add_f32_dpp v20, v20, v20 row_ror:1 row_mask:0xf bank_mask:0xf bound_ctrl:1
	s_nop 0
	v_readlane_b32 s30, v20, 0
	v_readlane_b32 s35, v20, 16
	v_readlane_b32 s31, v20, 32
	v_readlane_b32 s34, v20, 48
	s_and_saveexec_b64 s[22:23], vcc
	s_cbranch_execz .LBB0_1073
	s_lshl_b64 s[20:21], s[20:21], 2
	v_mov_b32_e32 v20, s35
	s_add_u32 s20, s65, s20
	v_add_f32_e32 v20, s30, v20
	s_addc_u32 s21, s66, s21
	v_add_f32_e32 v20, s31, v20
	v_add_f32_e32 v22, s34, v20
	v_mov_b64_e32 v[20:21], s[20:21]
	flat_atomic_add_f32 v[20:21], v22
.LBB0_1073:
	s_or_b64 exec, exec, s[22:23]
	ds_read_b128 v[20:23], v120 offset:11440
	v_lshl_add_u64 v[24:25], v[46:47], 1, s[4:5]
	s_waitcnt lgkmcnt(0)
	v_pk_add_f32 v[16:17], v[16:17], v[20:21]
	v_pk_add_f32 v[18:19], v[18:19], v[22:23]
	global_store_dwordx4 v[44:45], v[16:19], off
	v_cvt_pk_bf16_f32 v20, v16, v17
	v_cvt_pk_bf16_f32 v21, v18, v19
	v_pk_mul_f32 v[16:17], v[16:17], v[16:17]
	v_pk_mul_f32 v[18:19], v[18:19], v[18:19]
	v_add_f32_e32 v16, v16, v17
	v_add_f32_e32 v16, v16, v18
	v_add_f32_e32 v16, v16, v19
	flat_store_dwordx2 v[24:25], v[20:21]
	s_nop 0
	v_add_f32_dpp v16, v16, v16 row_ror:8 row_mask:0xf bank_mask:0xf bound_ctrl:1
	s_nop 1
	v_add_f32_dpp v16, v16, v16 row_ror:4 row_mask:0xf bank_mask:0xf bound_ctrl:1
	s_nop 1
	v_add_f32_dpp v16, v16, v16 row_ror:2 row_mask:0xf bank_mask:0xf bound_ctrl:1
	s_nop 1
	v_add_f32_dpp v16, v16, v16 row_ror:1 row_mask:0xf bank_mask:0xf bound_ctrl:1
	s_nop 0
	v_readlane_b32 s22, v16, 0
	v_readlane_b32 s31, v16, 16
	v_readlane_b32 s23, v16, 32
	v_readlane_b32 s30, v16, 48
	s_and_saveexec_b64 s[20:21], vcc
	s_cbranch_execz .LBB0_1075
	s_lshl_b64 s[18:19], s[18:19], 2
	v_mov_b32_e32 v16, s31
	s_add_u32 s18, s65, s18
	v_add_f32_e32 v16, s22, v16
	s_addc_u32 s19, s66, s19
	v_add_f32_e32 v16, s23, v16
	v_add_f32_e32 v18, s30, v16
	v_mov_b64_e32 v[16:17], s[18:19]
	flat_atomic_add_f32 v[16:17], v18
; DEVI float fsig(float x) { return __builtin_amdgcn_rcpf(1.f + __expf(-x)); }
; DEVI float bflo(unsigned u) { return __uint_as_float(u << 16); }
; DEVI float bfhi(unsigned u) { return __uint_as_float(u & 0xffff0000u); }
; template <int EPI, int TS, bool VT>
; DEVI void gemm_epilogue(const Params& p, char* smem, f32x4 (&acc)[2][2][4][2], int m0, int n0, float scale, const float* ssin,
;                         float* ssout, u16* xbout, int wid, int lane, int wr, int wc, int fr, int fq) {
;     ...
;           if constexpr (EPI == E_RESID || EPI == E_PLEGATE) {
;             const float4 a = *(const float4*)(Tr + 4 * lane);
;             const size_t ro = (size_t)grow * 1024 + n0 + 4 * lane;
;             float4 x4 = xo[u];
;             if constexpr (EPI == E_PLEGATE) {
;               x4.x += bflo(pv[u].x) * fsig(a.x * rs);
;               x4.y += bfhi(pv[u].x) * fsig(a.y * rs);
;               x4.z += bflo(pv[u].y) * fsig(a.z * rs);
;               x4.w += bfhi(pv[u].y) * fsig(a.w * rs);
;             } else {
;               const float sc = fabsf(scale);
;               x4.x += sc * a.x; x4.y += sc * a.y; x4.z += sc * a.z; x4.w += sc * a.w;
;             }
;             st_nt16(p.x + ro, x4);
;             if (xbout) {
;               uint2 o;
;               o.x = pack2(x4.x, x4.y);
;               o.y = pack2(x4.z, x4.w);
;               st_nt8(xbout + ro, o);
;             }
;             if (ssout) {
;               const float ssq = wsum(x4.x * x4.x + x4.y * x4.y + x4.z * x4.z + x4.w * x4.w, lane);
;               if (lane == 0) atomicAdd(ssout + grow, ssq);
;             }
.LBB0_1075:
	s_or_b64 exec, exec, s[20:21]
	ds_read_b128 v[16:19], v120 offset:12480
	v_lshl_add_u64 v[20:21], v[42:43], 1, s[4:5]
	s_waitcnt lgkmcnt(0)
	v_pk_add_f32 v[12:13], v[12:13], v[16:17]
	v_pk_add_f32 v[14:15], v[14:15], v[18:19]
	global_store_dwordx4 v[40:41], v[12:15], off
	v_cvt_pk_bf16_f32 v16, v12, v13
	v_cvt_pk_bf16_f32 v17, v14, v15
	v_pk_mul_f32 v[12:13], v[12:13], v[12:13]
	v_pk_mul_f32 v[14:15], v[14:15], v[14:15]
	v_add_f32_e32 v12, v12, v13
	v_add_f32_e32 v12, v12, v14
	v_add_f32_e32 v12, v12, v15
	flat_store_dwordx2 v[20:21], v[16:17]
	s_nop 0
	v_add_f32_dpp v12, v12, v12 row_ror:8 row_mask:0xf bank_mask:0xf bound_ctrl:1
	s_nop 1
	v_add_f32_dpp v12, v12, v12 row_ror:4 row_mask:0xf bank_mask:0xf bound_ctrl:1
	s_nop 1
	v_add_f32_dpp v12, v12, v12 row_ror:2 row_mask:0xf bank_mask:0xf bound_ctrl:1
	s_nop 1
	v_add_f32_dpp v12, v12, v12 row_ror:1 row_mask:0xf bank_mask:0xf bound_ctrl:1
	s_nop 0
	v_readlane_b32 s20, v12, 0
	v_readlane_b32 s23, v12, 16
	v_readlane_b32 s21, v12, 32
	v_readlane_b32 s22, v12, 48
	s_and_saveexec_b64 s[18:19], vcc
	s_cbranch_execz .LBB0_1077
	s_lshl_b64 s[14:15], s[14:15], 2
	v_mov_b32_e32 v12, s23
	s_add_u32 s14, s65, s14
	v_add_f32_e32 v12, s20, v12
	s_addc_u32 s15, s66, s15
	v_add_f32_e32 v12, s21, v12
	v_add_f32_e32 v14, s22, v12
	v_mov_b64_e32 v[12:13], s[14:15]
	flat_atomic_add_f32 v[12:13], v14
.LBB0_1077:
	s_or_b64 exec, exec, s[18:19]
	ds_read_b128 v[12:15], v120 offset:13520
	v_lshl_add_u64 v[16:17], v[38:39], 1, s[4:5]
	s_waitcnt lgkmcnt(0)
	v_pk_add_f32 v[8:9], v[8:9], v[12:13]
	v_pk_add_f32 v[10:11], v[10:11], v[14:15]
	global_store_dwordx4 v[36:37], v[8:11], off
	v_cvt_pk_bf16_f32 v12, v8, v9
	v_cvt_pk_bf16_f32 v13, v10, v11
	v_pk_mul_f32 v[8:9], v[8:9], v[8:9]
	v_pk_mul_f32 v[10:11], v[10:11], v[10:11]
	v_add_f32_e32 v8, v8, v9
	v_add_f32_e32 v8, v8, v10
	v_add_f32_e32 v8, v8, v11
	flat_store_dwordx2 v[16:17], v[12:13]
	s_nop 0
	v_add_f32_dpp v8, v8, v8 row_ror:8 row_mask:0xf bank_mask:0xf bound_ctrl:1
	s_nop 1
	v_add_f32_dpp v8, v8, v8 row_ror:4 row_mask:0xf bank_mask:0xf bound_ctrl:1
	s_nop 1
	v_add_f32_dpp v8, v8, v8 row_ror:2 row_mask:0xf bank_mask:0xf bound_ctrl:1
	s_nop 1
	v_add_f32_dpp v8, v8, v8 row_ror:1 row_mask:0xf bank_mask:0xf bound_ctrl:1
	s_nop 0
	v_readlane_b32 s18, v8, 0
	v_readlane_b32 s21, v8, 16
	v_readlane_b32 s19, v8, 32
	v_readlane_b32 s20, v8, 48
	s_and_saveexec_b64 s[14:15], vcc
	s_cbranch_execz .LBB0_1079
	s_lshl_b64 s[12:13], s[12:13], 2
	v_mov_b32_e32 v8, s21
	s_add_u32 s12, s65, s12
	v_add_f32_e32 v8, s18, v8
	s_addc_u32 s13, s66, s13
	v_add_f32_e32 v8, s19, v8
	v_add_f32_e32 v10, s20, v8
	v_mov_b64_e32 v[8:9], s[12:13]
	flat_atomic_add_f32 v[8:9], v10
.LBB0_1079:
	s_or_b64 exec, exec, s[14:15]
	ds_read_b128 v[8:11], v120 offset:14560
	v_lshl_add_u64 v[12:13], v[34:35], 1, s[4:5]
	s_waitcnt lgkmcnt(0)
	v_pk_add_f32 v[4:5], v[4:5], v[8:9]
	v_pk_add_f32 v[6:7], v[6:7], v[10:11]
	global_store_dwordx4 v[32:33], v[4:7], off
	v_cvt_pk_bf16_f32 v8, v4, v5
	v_cvt_pk_bf16_f32 v9, v6, v7
	v_pk_mul_f32 v[4:5], v[4:5], v[4:5]
	v_pk_mul_f32 v[6:7], v[6:7], v[6:7]
	v_add_f32_e32 v4, v4, v5
	v_add_f32_e32 v4, v4, v6
	v_add_f32_e32 v4, v4, v7
	flat_store_dwordx2 v[12:13], v[8:9]
	s_nop 0
	v_add_f32_dpp v4, v4, v4 row_ror:8 row_mask:0xf bank_mask:0xf bound_ctrl:1
	s_nop 1
	v_add_f32_dpp v4, v4, v4 row_ror:4 row_mask:0xf bank_mask:0xf bound_ctrl:1
	s_nop 1
	v_add_f32_dpp v4, v4, v4 row_ror:2 row_mask:0xf bank_mask:0xf bound_ctrl:1
	s_nop 1
	v_add_f32_dpp v4, v4, v4 row_ror:1 row_mask:0xf bank_mask:0xf bound_ctrl:1
	s_nop 0
	v_readlane_b32 s14, v4, 0
	v_readlane_b32 s19, v4, 16
	v_readlane_b32 s15, v4, 32
	v_readlane_b32 s18, v4, 48
	s_and_saveexec_b64 s[12:13], vcc
	s_cbranch_execz .LBB0_1081
	s_lshl_b64 s[10:11], s[10:11], 2
	v_mov_b32_e32 v4, s19
	s_add_u32 s10, s65, s10
	v_add_f32_e32 v4, s14, v4
	s_addc_u32 s11, s66, s11
	v_add_f32_e32 v4, s15, v4
	v_add_f32_e32 v6, s18, v4
	v_mov_b64_e32 v[4:5], s[10:11]
	flat_atomic_add_f32 v[4:5], v6
.LBB0_1081:
	s_or_b64 exec, exec, s[12:13]
	ds_read_b128 v[4:7], v120 offset:15600
	v_lshl_add_u64 v[8:9], v[30:31], 1, s[4:5]
	s_waitcnt lgkmcnt(0)
	v_pk_add_f32 v[0:1], v[0:1], v[4:5]
	v_pk_add_f32 v[2:3], v[2:3], v[6:7]
	global_store_dwordx4 v[28:29], v[0:3], off
	v_cvt_pk_bf16_f32 v4, v0, v1
	v_cvt_pk_bf16_f32 v5, v2, v3
	v_pk_mul_f32 v[0:1], v[0:1], v[0:1]
	v_pk_mul_f32 v[2:3], v[2:3], v[2:3]
	v_add_f32_e32 v0, v0, v1
	v_add_f32_e32 v0, v0, v2
	v_add_f32_e32 v0, v0, v3
	flat_store_dwordx2 v[8:9], v[4:5]
	s_nop 0
	v_add_f32_dpp v0, v0, v0 row_ror:8 row_mask:0xf bank_mask:0xf bound_ctrl:1
	s_nop 1
	v_add_f32_dpp v0, v0, v0 row_ror:4 row_mask:0xf bank_mask:0xf bound_ctrl:1
	s_nop 1
	v_add_f32_dpp v0, v0, v0 row_ror:2 row_mask:0xf bank_mask:0xf bound_ctrl:1
	s_nop 1
	v_add_f32_dpp v0, v0, v0 row_ror:1 row_mask:0xf bank_mask:0xf bound_ctrl:1
	s_nop 0
	v_readlane_b32 s12, v0, 0
	v_readlane_b32 s15, v0, 16
	v_readlane_b32 s13, v0, 32
	v_readlane_b32 s14, v0, 48
	s_and_saveexec_b64 s[10:11], vcc
	s_cbranch_execz .LBB0_1010
	s_lshl_b64 s[8:9], s[8:9], 2
	v_mov_b32_e32 v0, s15
	s_add_u32 s8, s65, s8
	v_add_f32_e32 v0, s12, v0
	s_addc_u32 s9, s66, s9
	v_add_f32_e32 v0, s13, v0
	v_add_f32_e32 v2, s14, v0
	v_mov_b64_e32 v[0:1], s[8:9]
	flat_atomic_add_f32 v[0:1], v2
	s_branch .LBB0_1010

; template <int EPI, int TS, bool VT>
; DEVI void gemm_epilogue(const Params& p, char* smem, f32x4 (&acc)[2][2][4][2], int m0, int n0, float scale, const float* ssin,
;                         float* ssout, u16* xbout, int wid, int lane, int wr, int wc, int fr, int fq) {
;     ...
;             if (n0 < 3072) {
;               u16* O = (u16*)(wsb + (n0 < 512 ? OFF_QG : n0 < 1024 ? OFF_KG : OFF_RG));
;               const float f = n0 < 512 ? rs * 0.08838834764831845f : rs;
;               const int ld = n0 < 1024 ? 512 : 1024;
;               const int cc = n0 - (n0 < 512 ? 0 : n0 < 1024 ? 512 : 2048) + 4 * lane;
;               uint2 o;
;               o.x = pack2(a.x * f, a.y * f);
;               o.y = pack2(a.z * f, a.w * f);
;               st_nt8(O + (size_t)grow * ld + cc, o);
.LBB0_1125:
	s_add_i32 s31, s31, s20
	v_lshl_or_b32 v134, v137, 2, s31
	v_ashrrev_i32_e32 v135, 31, v134
	s_andn2_b64 vcc, exec, s[34:35]
	v_lshl_add_u64 v[134:135], v[134:135], 1, s[4:5]
	s_cbranch_vccnz .LBB0_1127
	v_mul_f32_e32 v148, s30, v172
	v_mov_b32_e32 v164, s30
	v_cndmask_b32_e64 v148, v164, v148, s[0:1]
	s_ashr_i32 s23, s22, 31
	s_waitcnt lgkmcnt(0)
	v_pk_mul_f32 v[128:129], v[128:129], v[148:149] op_sel_hi:[1,0]
	v_pk_mul_f32 v[130:131], v[148:149], v[130:131] op_sel_hi:[0,1]
	s_lshl_b64 s[4:5], s[22:23], s21
	v_cvt_pk_bf16_f32 v128, v128, v129
	v_cvt_pk_bf16_f32 v129, v130, v131
	v_lshl_add_u64 v[130:131], s[4:5], 1, v[134:135]
	flat_store_dwordx2 v[130:131], v[128:129]

; template <int EPI, int TS, bool VT>
; DEVI void gemm_epilogue(const Params& p, char* smem, f32x4 (&acc)[2][2][4][2], int m0, int n0, float scale, const float* ssin,
;                         float* ssout, u16* xbout, int wid, int lane, int wr, int wc, int fr, int fq) {
;     ...
;             if (n0 < 3072) {
;               u16* O = (u16*)(wsb + (n0 < 512 ? OFF_QG : n0 < 1024 ? OFF_KG : OFF_RG));
;               const float f = n0 < 512 ? rs * 0.08838834764831845f : rs;
;               const int ld = n0 < 1024 ? 512 : 1024;
;               const int cc = n0 - (n0 < 512 ? 0 : n0 < 1024 ? 512 : 2048) + 4 * lane;
;               uint2 o;
;               o.x = pack2(a.x * f, a.y * f);
;               o.y = pack2(a.z * f, a.w * f);
;               st_nt8(O + (size_t)grow * ld + cc, o);
.LBB0_1131:
	s_andn2_b64 vcc, exec, s[8:9]
	s_cbranch_vccnz .LBB0_1133
	v_mul_f32_e32 v148, s34, v172
	v_mov_b32_e32 v164, s34
	v_cndmask_b32_e64 v148, v164, v148, s[0:1]
	s_ashr_i32 s31, s30, 31
	s_waitcnt lgkmcnt(0)
	v_pk_mul_f32 v[128:129], v[128:129], v[148:149] op_sel_hi:[1,0]
	v_pk_mul_f32 v[130:131], v[148:149], v[130:131] op_sel_hi:[0,1]
	s_lshl_b64 s[8:9], s[30:31], s21
	v_cvt_pk_bf16_f32 v128, v128, v129
	v_cvt_pk_bf16_f32 v129, v130, v131
	v_lshl_add_u64 v[130:131], s[8:9], 1, v[134:135]
	flat_store_dwordx2 v[130:131], v[128:129]

; template <int EPI, int TS, bool VT>
; DEVI void gemm_epilogue(const Params& p, char* smem, f32x4 (&acc)[2][2][4][2], int m0, int n0, float scale, const float* ssin,
;                         float* ssout, u16* xbout, int wid, int lane, int wr, int wc, int fr, int fq) {
;     ...
;             if (n0 < 3072) {
;               u16* O = (u16*)(wsb + (n0 < 512 ? OFF_QG : n0 < 1024 ? OFF_KG : OFF_RG));
;               const float f = n0 < 512 ? rs * 0.08838834764831845f : rs;
;               const int ld = n0 < 1024 ? 512 : 1024;
;               const int cc = n0 - (n0 < 512 ? 0 : n0 < 1024 ? 512 : 2048) + 4 * lane;
;               uint2 o;
;               o.x = pack2(a.x * f, a.y * f);
;               o.y = pack2(a.z * f, a.w * f);
;               st_nt8(O + (size_t)grow * ld + cc, o);
.LBB0_1137:
	s_andn2_b64 vcc, exec, s[34:35]
	s_cbranch_vccnz .LBB0_1139
	v_mul_f32_e32 v148, s30, v172
	v_mov_b32_e32 v164, s30
	v_cndmask_b32_e64 v148, v164, v148, s[0:1]
	s_ashr_i32 s9, s8, 31
	s_waitcnt lgkmcnt(0)
	v_pk_mul_f32 v[128:129], v[128:129], v[148:149] op_sel_hi:[1,0]
	v_pk_mul_f32 v[130:131], v[148:149], v[130:131] op_sel_hi:[0,1]
	s_lshl_b64 s[8:9], s[8:9], s21
	v_cvt_pk_bf16_f32 v128, v128, v129
	v_cvt_pk_bf16_f32 v129, v130, v131
	v_lshl_add_u64 v[130:131], s[8:9], 1, v[134:135]
	flat_store_dwordx2 v[130:131], v[128:129]

; template <int EPI, int TS, bool VT>
; DEVI void gemm_epilogue(const Params& p, char* smem, f32x4 (&acc)[2][2][4][2], int m0, int n0, float scale, const float* ssin,
;                         float* ssout, u16* xbout, int wid, int lane, int wr, int wc, int fr, int fq) {
;     ...
;             if (n0 < 3072) {
;               u16* O = (u16*)(wsb + (n0 < 512 ? OFF_QG : n0 < 1024 ? OFF_KG : OFF_RG));
;               const float f = n0 < 512 ? rs * 0.08838834764831845f : rs;
;               const int ld = n0 < 1024 ? 512 : 1024;
;               const int cc = n0 - (n0 < 512 ? 0 : n0 < 1024 ? 512 : 2048) + 4 * lane;
;               uint2 o;
;               o.x = pack2(a.x * f, a.y * f);
;               o.y = pack2(a.z * f, a.w * f);
;               st_nt8(O + (size_t)grow * ld + cc, o);
.LBB0_1215:
	s_andn2_b64 vcc, exec, s[34:35]
	s_cbranch_vccnz .LBB0_1217
	v_mul_f32_e32 v148, s30, v172
	v_mov_b32_e32 v163, s30
	v_cndmask_b32_e64 v148, v163, v148, s[0:1]
	s_ashr_i32 s9, s8, 31
	s_waitcnt lgkmcnt(0)
	v_pk_mul_f32 v[128:129], v[128:129], v[148:149] op_sel_hi:[1,0]
	v_pk_mul_f32 v[130:131], v[148:149], v[130:131] op_sel_hi:[0,1]
	s_lshl_b64 s[8:9], s[8:9], s21
	v_cvt_pk_bf16_f32 v128, v128, v129
	v_cvt_pk_bf16_f32 v129, v130, v131
	v_lshl_add_u64 v[130:131], s[8:9], 1, v[134:135]
	flat_store_dwordx2 v[130:131], v[128:129]

; template <int EPI, int TS, bool VT>
; DEVI void gemm_epilogue(const Params& p, char* smem, f32x4 (&acc)[2][2][4][2], int m0, int n0, float scale, const float* ssin,
;                         float* ssout, u16* xbout, int wid, int lane, int wr, int wc, int fr, int fq) {
;     ...
;             if (n0 < 3072) {
;               u16* O = (u16*)(wsb + (n0 < 512 ? OFF_QG : n0 < 1024 ? OFF_KG : OFF_RG));
;               const float f = n0 < 512 ? rs * 0.08838834764831845f : rs;
;               const int ld = n0 < 1024 ? 512 : 1024;
;               const int cc = n0 - (n0 < 512 ? 0 : n0 < 1024 ? 512 : 2048) + 4 * lane;
;               uint2 o;
;               o.x = pack2(a.x * f, a.y * f);
;               o.y = pack2(a.z * f, a.w * f);
;               st_nt8(O + (size_t)grow * ld + cc, o);
.LBB0_1221:
	s_andn2_b64 vcc, exec, s[34:35]
	s_cbranch_vccnz .LBB0_1223
	v_mul_f32_e32 v141, s8, v172
	v_mov_b32_e32 v142, s8
	v_cndmask_b32_e64 v142, v142, v141, s[0:1]
	s_ashr_i32 s31, s30, 31
	s_waitcnt lgkmcnt(0)
	v_pk_mul_f32 v[128:129], v[128:129], v[142:143] op_sel_hi:[1,0]
	v_pk_mul_f32 v[130:131], v[142:143], v[130:131] op_sel_hi:[0,1]
	s_lshl_b64 s[8:9], s[30:31], s21
	v_cvt_pk_bf16_f32 v128, v128, v129
	v_cvt_pk_bf16_f32 v129, v130, v131
	v_lshl_add_u64 v[130:131], s[8:9], 1, v[134:135]
	flat_store_dwordx2 v[130:131], v[128:129]

; template <int EPI, int TS, bool VT>
; DEVI void gemm_epilogue(const Params& p, char* smem, f32x4 (&acc)[2][2][4][2], int m0, int n0, float scale, const float* ssin,
;                         float* ssout, u16* xbout, int wid, int lane, int wr, int wc, int fr, int fq) {
;     ...
;             if (n0 < 3072) {
;               u16* O = (u16*)(wsb + (n0 < 512 ? OFF_QG : n0 < 1024 ? OFF_KG : OFF_RG));
;               const float f = n0 < 512 ? rs * 0.08838834764831845f : rs;
;               const int ld = n0 < 1024 ? 512 : 1024;
;               const int cc = n0 - (n0 < 512 ? 0 : n0 < 1024 ? 512 : 2048) + 4 * lane;
;               uint2 o;
;               o.x = pack2(a.x * f, a.y * f);
;               o.y = pack2(a.z * f, a.w * f);
;               st_nt8(O + (size_t)grow * ld + cc, o);
.LBB0_1227:
	s_andn2_b64 vcc, exec, s[34:35]
	s_cbranch_vccnz .LBB0_1229
	v_mul_f32_e32 v141, s30, v172
	v_mov_b32_e32 v142, s30
	v_cndmask_b32_e64 v142, v142, v141, s[0:1]
	s_ashr_i32 s9, s8, 31
	s_waitcnt lgkmcnt(0)
	v_pk_mul_f32 v[128:129], v[128:129], v[142:143] op_sel_hi:[1,0]
	v_pk_mul_f32 v[130:131], v[142:143], v[130:131] op_sel_hi:[0,1]
	s_lshl_b64 s[8:9], s[8:9], s21
	v_cvt_pk_bf16_f32 v128, v128, v129
	v_cvt_pk_bf16_f32 v129, v130, v131
	v_lshl_add_u64 v[130:131], s[8:9], 1, v[134:135]
	flat_store_dwordx2 v[130:131], v[128:129]

; template <int EPI, int TS, bool VT>
; DEVI void gemm_epilogue(const Params& p, char* smem, f32x4 (&acc)[2][2][4][2], int m0, int n0, float scale, const float* ssin,
;                         float* ssout, u16* xbout, int wid, int lane, int wr, int wc, int fr, int fq) {
;     ...
;             if (n0 < 3072) {
;               u16* O = (u16*)(wsb + (n0 < 512 ? OFF_QG : n0 < 1024 ? OFF_KG : OFF_RG));
;               const float f = n0 < 512 ? rs * 0.08838834764831845f : rs;
;               const int ld = n0 < 1024 ? 512 : 1024;
;               const int cc = n0 - (n0 < 512 ? 0 : n0 < 1024 ? 512 : 2048) + 4 * lane;
;               uint2 o;
;               o.x = pack2(a.x * f, a.y * f);
;               o.y = pack2(a.z * f, a.w * f);
;               st_nt8(O + (size_t)grow * ld + cc, o);
.LBB0_1311:
	s_andn2_b64 vcc, exec, s[4:5]
	s_cbranch_vccnz .LBB0_1313
	v_mul_f32_e32 v132, s22, v172
	v_mov_b32_e32 v133, s22
	v_cndmask_b32_e64 v132, v133, v132, s[0:1]
	s_ashr_i32 s9, s8, 31
	s_waitcnt lgkmcnt(0)
	v_pk_mul_f32 v[128:129], v[128:129], v[132:133] op_sel_hi:[1,0]
	v_pk_mul_f32 v[130:131], v[132:133], v[130:131] op_sel_hi:[0,1]
	s_lshl_b64 s[0:1], s[8:9], s21
	v_cvt_pk_bf16_f32 v128, v128, v129
	v_cvt_pk_bf16_f32 v129, v130, v131
	v_lshl_add_u64 v[130:131], s[0:1], 1, v[134:135]
	flat_store_dwordx2 v[130:131], v[128:129]

; template <int EPI, int TS, bool VT>
; DEVI void gemm_epilogue(const Params& p, char* smem, f32x4 (&acc)[2][2][4][2], int m0, int n0, float scale, const float* ssin,
;                         float* ssout, u16* xbout, int wid, int lane, int wr, int wc, int fr, int fq) {
;     ...
;       float* tw = T + (wr * 64 + fq * 4) * TS + wc * 32 + fr;
; #pragma unroll
;       for (int m = 0; m < 4; ++m)
; #pragma unroll
;         for (int j = 0; j < 4; ++j)
; #pragma unroll
;           for (int v = 0; v < 4; ++v) tw[(m * 16 + j) * TS + (v >> 1) * 128 + (v & 1) * 16] = acc[ai][v >> 1][m][v & 1][j];
;     }
;     __syncthreads();
;     const int r0 = wid * 16;
;     const int g0 = m0 + ai * 128 + r0;
;     if constexpr (!VT) {
;       float rsv = 1.f;
;       if constexpr (EPI == E_PLEGATE || EPI == E_F32 || EPI == E_SWIGLU || EPI == E_GLAIN)
;         rsv = rsqrtf(ssin[g0 + (lane & 15)] * (1.f / 1024.f) + EPS);
;       if constexpr (EPI == E_QROPE) rsv = rsqrtf(ssin[g0 + (lane & 15)] * (1.f / 384.f) + EPS);
;       if constexpr (EPI == E_KV) rsv = rsqrtf(ssin[g0 + (lane & 15)] * (1.f / 256.f) + EPS);
;       for (int i0 = 0; i0 < 16; i0 += 8) {
;         float4 xo[8];
;         uint2 pv[8];
;         if constexpr (EPI == E_RESID || EPI == E_PLEGATE) {
; #pragma unroll
;           for (int u = 0; u < 8; ++u) {
;             const size_t ro = (size_t)(g0 + i0 + u) * 1024 + n0 + 4 * lane;
;             const int gr = g0 + i0 + u;
;             const float* xs = p.x + ro;
;             if (scale < 0.f)
;               xs = (gr < MP ? p.x_prompt + ro : p.x_sample + (ro - (size_t)MP * 1024));
;             { const f32x4 t_ = __builtin_nontemporal_load((const f32x4*)xs); xo[u] = make_float4(t_[0], t_[1], t_[2], t_[3]); }
;     ...
;           if constexpr (EPI == E_RESID || EPI == E_PLEGATE) {
;             const float4 a = *(const float4*)(Tr + 4 * lane);
;             const size_t ro = (size_t)grow * 1024 + n0 + 4 * lane;
;             float4 x4 = xo[u];
;             if constexpr (EPI == E_PLEGATE) {
;               x4.x += bflo(pv[u].x) * fsig(a.x * rs);
;               x4.y += bfhi(pv[u].x) * fsig(a.y * rs);
;               x4.z += bflo(pv[u].y) * fsig(a.z * rs);
;               x4.w += bfhi(pv[u].y) * fsig(a.w * rs);
;             } else {
;               const float sc = fabsf(scale);
;               x4.x += sc * a.x; x4.y += sc * a.y; x4.z += sc * a.z; x4.w += sc * a.w;
.LBB0_1669:
	v_readlane_b32 s12, v254, 13
	v_readlane_b32 s13, v254, 14
	v_lshrrev_b32_e32 v128, 2, v132
	v_and_or_b32 v128, v128, 12, s34
	s_movk_i32 s12, 0x410
	v_mul_lo_u32 v128, v128, s12
	s_lshl_b32 s9, s9, 7
	v_lshlrev_b32_e32 v129, 2, v133
	v_add3_u32 v130, s9, v128, v129
	s_lshl_b32 s9, s31, 4
	s_add_i32 s8, s9, s8
	v_and_b32_e32 v141, 63, v132
	ds_write2_b32 v130, v92, v100 offset1:16
	ds_write2_b32 v130, v120, v124 offset0:128 offset1:144
	v_add_u32_e32 v124, 0x400, v130
	s_ashr_i32 s9, s8, 31
	v_lshl_or_b32 v128, v141, 2, s10
	v_mov_b32_e32 v129, s11
	ds_write2_b32 v124, v93, v101 offset0:4 offset1:20
	ds_write2_b32 v124, v121, v125 offset0:132 offset1:148
	v_add_u32_e32 v121, 0x800, v130
	s_lshl_b64 s[10:11], s[8:9], 10
	s_or_b32 s22, s8, 1
	ds_write2_b32 v121, v94, v102 offset0:8 offset1:24
	ds_write2_b32 v121, v122, v126 offset0:136 offset1:152
	v_add_u32_e32 v122, 0xc00, v130
	v_lshl_add_u64 v[146:147], s[10:11], 0, v[128:129]
	s_ashr_i32 s23, s22, 31
	s_or_b32 s20, s8, 2
	ds_write2_b32 v122, v95, v103 offset0:12 offset1:28
	ds_write2_b32 v122, v123, v127 offset0:140 offset1:156
	v_add_u32_e32 v123, 0x4000, v130
	v_add_u32_e32 v125, 0x4400, v130
	v_add_u32_e32 v126, 0x4800, v130
	v_add_u32_e32 v127, 0x4c00, v130
	v_add_u32_e32 v131, 0x8000, v130
	v_add_u32_e32 v132, 0x8400, v130
	v_add_u32_e32 v133, 0x8800, v130
	v_add_u32_e32 v134, 0x8c00, v130
	v_add_u32_e32 v135, 0x9000, v130
	v_add_u32_e32 v136, 0xc000, v130
	v_add_u32_e32 v137, 0xc400, v130
	v_add_u32_e32 v138, 0xc800, v130
	v_add_u32_e32 v139, 0xcc00, v130
	v_add_u32_e32 v140, 0xd000, v130
	v_lshl_add_u64 v[156:157], v[146:147], 2, s[38:39]
	s_lshl_b64 s[10:11], s[22:23], 10
	s_ashr_i32 s21, s20, 31
	s_or_b32 s18, s8, 3
	ds_write2_b32 v123, v80, v84 offset0:64 offset1:80
	ds_write2_b32 v123, v112, v116 offset0:192 offset1:208
	ds_write2_b32 v125, v81, v85 offset0:68 offset1:84
	ds_write2_b32 v125, v113, v117 offset0:196 offset1:212
	ds_write2_b32 v126, v82, v86 offset0:72 offset1:88
	ds_write2_b32 v126, v114, v118 offset0:200 offset1:216
	ds_write2_b32 v127, v83, v87 offset0:76 offset1:92
	ds_write2_b32 v127, v115, v119 offset0:204 offset1:220
	ds_write2_b32 v131, v72, v76 offset0:128 offset1:144
	ds_write2_b32 v132, v104, v108 offset1:16
	ds_write2_b32 v132, v73, v77 offset0:132 offset1:148
	ds_write2_b32 v133, v105, v109 offset0:4 offset1:20
	ds_write2_b32 v133, v74, v78 offset0:136 offset1:152
	ds_write2_b32 v134, v106, v110 offset0:8 offset1:24
	ds_write2_b32 v134, v75, v79 offset0:140 offset1:156
	ds_write2_b32 v135, v107, v111 offset0:12 offset1:28
	ds_write2_b32 v136, v64, v68 offset0:192 offset1:208
	ds_write2_b32 v137, v88, v96 offset0:64 offset1:80
	ds_write2_b32 v137, v65, v69 offset0:196 offset1:212
	ds_write2_b32 v138, v89, v97 offset0:68 offset1:84
	ds_write2_b32 v138, v66, v70 offset0:200 offset1:216
	ds_write2_b32 v139, v90, v98 offset0:72 offset1:88
	ds_write2_b32 v139, v67, v71 offset0:204 offset1:220
	ds_write2_b32 v140, v91, v99 offset0:76 offset1:92
	s_waitcnt vmcnt(0) lgkmcnt(0)
	s_barrier
	global_load_dwordx4 v[142:145], v[156:157], off
	v_lshl_add_u64 v[118:119], s[10:11], 0, v[128:129]
	s_lshl_b64 s[10:11], s[20:21], 10
	s_ashr_i32 s19, s18, 31
	s_or_b32 s16, s8, 4
	v_lshl_add_u64 v[114:115], s[10:11], 0, v[128:129]
	s_lshl_b64 s[10:11], s[18:19], 10
	s_ashr_i32 s17, s16, 31
	s_or_b32 s14, s8, 5
	v_lshl_add_u64 v[110:111], s[10:11], 0, v[128:129]
	s_lshl_b64 s[10:11], s[16:17], 10
	s_ashr_i32 s15, s14, 31
	s_or_b32 s12, s8, 6
	v_lshl_add_u64 v[106:107], s[10:11], 0, v[128:129]
	s_lshl_b64 s[10:11], s[14:15], 10
	s_ashr_i32 s13, s12, 31
	v_lshl_add_u64 v[102:103], s[10:11], 0, v[128:129]
	s_lshl_b64 s[10:11], s[12:13], 10
	v_lshl_add_u64 v[98:99], s[10:11], 0, v[128:129]
	s_or_b32 s10, s8, 7
	s_ashr_i32 s11, s10, 31
	s_lshl_b64 s[34:35], s[10:11], 10
	v_lshl_add_u64 v[94:95], s[34:35], 0, v[128:129]
	v_lshl_add_u64 v[116:117], v[118:119], 2, s[38:39]
	v_lshl_add_u64 v[108:109], v[110:111], 2, s[38:39]
	v_lshl_add_u64 v[100:101], v[102:103], 2, s[38:39]
	v_lshl_add_u64 v[92:93], v[94:95], 2, s[38:39]
	v_lshl_add_u64 v[112:113], v[114:115], 2, s[38:39]
	global_load_dwordx4 v[88:91], v[116:117], off
	global_load_dwordx4 v[84:87], v[112:113], off
	v_lshl_add_u64 v[104:105], v[106:107], 2, s[38:39]
	global_load_dwordx4 v[80:83], v[108:109], off
	global_load_dwordx4 v[76:79], v[104:105], off
	v_lshl_add_u64 v[96:97], v[98:99], 2, s[38:39]
	global_load_dwordx4 v[72:75], v[100:101], off
	global_load_dwordx4 v[68:71], v[96:97], off
	global_load_dwordx4 v[64:67], v[92:93], off
	v_lshlrev_b32_e32 v120, 4, v141
	s_mulk_i32 s31, 0x4100
	v_add_u32_e32 v120, s31, v120
	ds_read_b128 v[152:155], v120
	v_cmp_eq_u32_e32 vcc, 0, v141
	v_lshl_add_u64 v[146:147], v[146:147], 1, s[4:5]
	s_waitcnt vmcnt(7) lgkmcnt(0)
	v_pk_add_f32 v[142:143], v[142:143], v[152:153]
	v_pk_add_f32 v[144:145], v[144:145], v[154:155]
	global_store_dwordx4 v[156:157], v[142:145], off
	v_cvt_pk_bf16_f32 v152, v142, v143
	v_cvt_pk_bf16_f32 v153, v144, v145
	v_pk_mul_f32 v[142:143], v[142:143], v[142:143]
	v_pk_mul_f32 v[144:145], v[144:145], v[144:145]
	v_add_f32_e32 v141, v142, v143
	v_add_f32_e32 v141, v141, v144
	v_add_f32_e32 v141, v141, v145
	flat_store_dwordx2 v[146:147], v[152:153]
	s_nop 0
	v_add_f32_dpp v141, v141, v141 row_ror:8 row_mask:0xf bank_mask:0xf bound_ctrl:1
	s_nop 1
	v_add_f32_dpp v141, v141, v141 row_ror:4 row_mask:0xf bank_mask:0xf bound_ctrl:1
	s_nop 1
	v_add_f32_dpp v141, v141, v141 row_ror:2 row_mask:0xf bank_mask:0xf bound_ctrl:1
	s_nop 1
	v_add_f32_dpp v141, v141, v141 row_ror:1 row_mask:0xf bank_mask:0xf bound_ctrl:1
	s_nop 0
	v_readlane_b32 s34, v141, 0
	v_readlane_b32 s68, v141, 16
	v_readlane_b32 s35, v141, 32
	v_readlane_b32 s67, v141, 48
	s_and_saveexec_b64 s[30:31], vcc
	s_cbranch_execz .LBB0_1671
	s_lshl_b64 s[70:71], s[8:9], 2
	v_mov_b32_e32 v141, s68
	s_add_u32 s70, s63, s70
	v_add_f32_e32 v141, s34, v141
	s_addc_u32 s71, s64, s71
	v_add_f32_e32 v141, s35, v141
	v_add_f32_e32 v141, s67, v141
	v_mov_b64_e32 v[142:143], s[70:71]
	flat_atomic_add_f32 v[142:143], v141
; DEVI float fsig(float x) { return __builtin_amdgcn_rcpf(1.f + __expf(-x)); }
; DEVI float bflo(unsigned u) { return __uint_as_float(u << 16); }
; DEVI float bfhi(unsigned u) { return __uint_as_float(u & 0xffff0000u); }
; template <int EPI, int TS, bool VT>
; DEVI void gemm_epilogue(const Params& p, char* smem, f32x4 (&acc)[2][2][4][2], int m0, int n0, float scale, const float* ssin,
;                         float* ssout, u16* xbout, int wid, int lane, int wr, int wc, int fr, int fq) {
;     ...
;           if constexpr (EPI == E_RESID || EPI == E_PLEGATE) {
;             const float4 a = *(const float4*)(Tr + 4 * lane);
;             const size_t ro = (size_t)grow * 1024 + n0 + 4 * lane;
;             float4 x4 = xo[u];
;             if constexpr (EPI == E_PLEGATE) {
;               x4.x += bflo(pv[u].x) * fsig(a.x * rs);
;               x4.y += bfhi(pv[u].x) * fsig(a.y * rs);
;               x4.z += bflo(pv[u].y) * fsig(a.z * rs);
;               x4.w += bfhi(pv[u].y) * fsig(a.w * rs);
;             } else {
;               const float sc = fabsf(scale);
;               x4.x += sc * a.x; x4.y += sc * a.y; x4.z += sc * a.z; x4.w += sc * a.w;
;             }
;             st_nt16(p.x + ro, x4);
;             if (xbout) {
;               uint2 o;
;               o.x = pack2(x4.x, x4.y);
;               o.y = pack2(x4.z, x4.w);
;               st_nt8(xbout + ro, o);
;             }
;             if (ssout) {
;               const float ssq = wsum(x4.x * x4.x + x4.y * x4.y + x4.z * x4.z + x4.w * x4.w, lane);
;               if (lane == 0) atomicAdd(ssout + grow, ssq);
;             }
.LBB0_1671:
	s_or_b64 exec, exec, s[30:31]
	ds_read_b128 v[142:145], v120 offset:1040
	v_lshl_add_u64 v[118:119], v[118:119], 1, s[4:5]
	s_waitcnt vmcnt(0) lgkmcnt(0)
	v_pk_add_f32 v[88:89], v[88:89], v[142:143]
	v_pk_add_f32 v[90:91], v[90:91], v[144:145]
	global_store_dwordx4 v[116:117], v[88:91], off
	v_cvt_pk_bf16_f32 v116, v88, v89
	v_cvt_pk_bf16_f32 v117, v90, v91
	v_pk_mul_f32 v[88:89], v[88:89], v[88:89]
	v_pk_mul_f32 v[90:91], v[90:91], v[90:91]
	v_add_f32_e32 v88, v88, v89
	v_add_f32_e32 v88, v88, v90
	v_add_f32_e32 v88, v88, v91
	flat_store_dwordx2 v[118:119], v[116:117]
	s_nop 0
	v_add_f32_dpp v88, v88, v88 row_ror:8 row_mask:0xf bank_mask:0xf bound_ctrl:1
	s_nop 1
	v_add_f32_dpp v88, v88, v88 row_ror:4 row_mask:0xf bank_mask:0xf bound_ctrl:1
	s_nop 1
	v_add_f32_dpp v88, v88, v88 row_ror:2 row_mask:0xf bank_mask:0xf bound_ctrl:1
	s_nop 1
	v_add_f32_dpp v88, v88, v88 row_ror:1 row_mask:0xf bank_mask:0xf bound_ctrl:1
	s_nop 0
	v_readlane_b32 s9, v88, 0
	v_readlane_b32 s67, v88, 16
	v_readlane_b32 s34, v88, 32
	v_readlane_b32 s35, v88, 48
	s_and_saveexec_b64 s[30:31], vcc
	s_cbranch_execz .LBB0_1673
	s_lshl_b64 s[22:23], s[22:23], 2
	v_mov_b32_e32 v88, s67
	s_add_u32 s22, s63, s22
	v_add_f32_e32 v88, s9, v88
	s_addc_u32 s23, s64, s23
	v_add_f32_e32 v88, s34, v88
	v_add_f32_e32 v90, s35, v88
	v_mov_b64_e32 v[88:89], s[22:23]
	flat_atomic_add_f32 v[88:89], v90
.LBB0_1673:
	s_or_b64 exec, exec, s[30:31]
	ds_read_b128 v[88:91], v120 offset:2080
	v_lshl_add_u64 v[114:115], v[114:115], 1, s[4:5]
	s_waitcnt lgkmcnt(0)
	v_pk_add_f32 v[84:85], v[84:85], v[88:89]
	v_pk_add_f32 v[86:87], v[86:87], v[90:91]
	global_store_dwordx4 v[112:113], v[84:87], off
	v_cvt_pk_bf16_f32 v88, v84, v85
	v_cvt_pk_bf16_f32 v89, v86, v87
	v_pk_mul_f32 v[84:85], v[84:85], v[84:85]
	v_pk_mul_f32 v[86:87], v[86:87], v[86:87]
	v_add_f32_e32 v84, v84, v85
	v_add_f32_e32 v84, v84, v86
	v_add_f32_e32 v84, v84, v87
	flat_store_dwordx2 v[114:115], v[88:89]
	s_nop 0
	v_add_f32_dpp v84, v84, v84 row_ror:8 row_mask:0xf bank_mask:0xf bound_ctrl:1
	s_nop 1
	v_add_f32_dpp v84, v84, v84 row_ror:4 row_mask:0xf bank_mask:0xf bound_ctrl:1
	s_nop 1
	v_add_f32_dpp v84, v84, v84 row_ror:2 row_mask:0xf bank_mask:0xf bound_ctrl:1
	s_nop 1
	v_add_f32_dpp v84, v84, v84 row_ror:1 row_mask:0xf bank_mask:0xf bound_ctrl:1
	s_nop 0
	v_readlane_b32 s9, v84, 0
	v_readlane_b32 s34, v84, 16
	v_readlane_b32 s30, v84, 32
	v_readlane_b32 s31, v84, 48
	s_and_saveexec_b64 s[22:23], vcc
	s_cbranch_execz .LBB0_1675
	s_lshl_b64 s[20:21], s[20:21], 2
	v_mov_b32_e32 v84, s34
	s_add_u32 s20, s63, s20
	v_add_f32_e32 v84, s9, v84
	s_addc_u32 s21, s64, s21
	v_add_f32_e32 v84, s30, v84
	v_add_f32_e32 v86, s31, v84
	v_mov_b64_e32 v[84:85], s[20:21]
	flat_atomic_add_f32 v[84:85], v86
.LBB0_1675:
	s_or_b64 exec, exec, s[22:23]
	ds_read_b128 v[84:87], v120 offset:3120
	v_lshl_add_u64 v[88:89], v[110:111], 1, s[4:5]
	s_waitcnt lgkmcnt(0)
	v_pk_add_f32 v[80:81], v[80:81], v[84:85]
	v_pk_add_f32 v[82:83], v[82:83], v[86:87]
	global_store_dwordx4 v[108:109], v[80:83], off
	v_cvt_pk_bf16_f32 v84, v80, v81
	v_cvt_pk_bf16_f32 v85, v82, v83
	v_pk_mul_f32 v[80:81], v[80:81], v[80:81]
	v_pk_mul_f32 v[82:83], v[82:83], v[82:83]
	v_add_f32_e32 v80, v80, v81
	v_add_f32_e32 v80, v80, v82
	v_add_f32_e32 v80, v80, v83
	flat_store_dwordx2 v[88:89], v[84:85]
	s_nop 0
	v_add_f32_dpp v80, v80, v80 row_ror:8 row_mask:0xf bank_mask:0xf bound_ctrl:1
	s_nop 1
	v_add_f32_dpp v80, v80, v80 row_ror:4 row_mask:0xf bank_mask:0xf bound_ctrl:1
	s_nop 1
	v_add_f32_dpp v80, v80, v80 row_ror:2 row_mask:0xf bank_mask:0xf bound_ctrl:1
	s_nop 1
	v_add_f32_dpp v80, v80, v80 row_ror:1 row_mask:0xf bank_mask:0xf bound_ctrl:1
	s_nop 0
	v_readlane_b32 s9, v80, 0
	v_readlane_b32 s30, v80, 16
	v_readlane_b32 s22, v80, 32
	v_readlane_b32 s23, v80, 48
	s_and_saveexec_b64 s[20:21], vcc
	s_cbranch_execz .LBB0_1677
	s_lshl_b64 s[18:19], s[18:19], 2
	v_mov_b32_e32 v80, s30
	s_add_u32 s18, s63, s18
	v_add_f32_e32 v80, s9, v80
	s_addc_u32 s19, s64, s19
	v_add_f32_e32 v80, s22, v80
	v_add_f32_e32 v82, s23, v80
	v_mov_b64_e32 v[80:81], s[18:19]
	flat_atomic_add_f32 v[80:81], v82
.LBB0_1677:
	s_or_b64 exec, exec, s[20:21]
	ds_read_b128 v[80:83], v120 offset:4160
	v_lshl_add_u64 v[84:85], v[106:107], 1, s[4:5]
	s_waitcnt lgkmcnt(0)
	v_pk_add_f32 v[76:77], v[76:77], v[80:81]
	v_pk_add_f32 v[78:79], v[78:79], v[82:83]
	global_store_dwordx4 v[104:105], v[76:79], off
	v_cvt_pk_bf16_f32 v80, v76, v77
	v_cvt_pk_bf16_f32 v81, v78, v79
	v_pk_mul_f32 v[76:77], v[76:77], v[76:77]
	v_pk_mul_f32 v[78:79], v[78:79], v[78:79]
	v_add_f32_e32 v76, v76, v77
	v_add_f32_e32 v76, v76, v78
	v_add_f32_e32 v76, v76, v79
	flat_store_dwordx2 v[84:85], v[80:81]
	s_nop 0
	v_add_f32_dpp v76, v76, v76 row_ror:8 row_mask:0xf bank_mask:0xf bound_ctrl:1
	s_nop 1
	v_add_f32_dpp v76, v76, v76 row_ror:4 row_mask:0xf bank_mask:0xf bound_ctrl:1
	s_nop 1
	v_add_f32_dpp v76, v76, v76 row_ror:2 row_mask:0xf bank_mask:0xf bound_ctrl:1
	s_nop 1
	v_add_f32_dpp v76, v76, v76 row_ror:1 row_mask:0xf bank_mask:0xf bound_ctrl:1
	s_nop 0
	v_readlane_b32 s9, v76, 0
	v_readlane_b32 s22, v76, 16
	v_readlane_b32 s20, v76, 32
	v_readlane_b32 s21, v76, 48
	s_and_saveexec_b64 s[18:19], vcc
	s_cbranch_execz .LBB0_1679
	s_lshl_b64 s[16:17], s[16:17], 2
	v_mov_b32_e32 v76, s22
	s_add_u32 s16, s63, s16
	v_add_f32_e32 v76, s9, v76
	s_addc_u32 s17, s64, s17
	v_add_f32_e32 v76, s20, v76
	v_add_f32_e32 v78, s21, v76
	v_mov_b64_e32 v[76:77], s[16:17]
	flat_atomic_add_f32 v[76:77], v78
; DEVI float fsig(float x) { return __builtin_amdgcn_rcpf(1.f + __expf(-x)); }
; template <int EPI, int TS, bool VT>
; DEVI void gemm_epilogue(const Params& p, char* smem, f32x4 (&acc)[2][2][4][2], int m0, int n0, float scale, const float* ssin,
;                         float* ssout, u16* xbout, int wid, int lane, int wr, int wc, int fr, int fq) {
;     ...
;         if constexpr (EPI == E_RESID || EPI == E_PLEGATE) {
; #pragma unroll
;           for (int u = 0; u < 8; ++u) {
;             const size_t ro = (size_t)(g0 + i0 + u) * 1024 + n0 + 4 * lane;
;             const int gr = g0 + i0 + u;
;             const float* xs = p.x + ro;
;             if (scale < 0.f)
;               xs = (gr < MP ? p.x_prompt + ro : p.x_sample + (ro - (size_t)MP * 1024));
;             { const f32x4 t_ = __builtin_nontemporal_load((const f32x4*)xs); xo[u] = make_float4(t_[0], t_[1], t_[2], t_[3]); }
;             if constexpr (EPI == E_PLEGATE) {
;               const unsigned long long t2_ = __builtin_nontemporal_load((const unsigned long long*)((const u16*)(wsb + OFF_PP) + ro));
;               pv[u] = make_uint2((unsigned)t2_, (unsigned)(t2_ >> 32));
;             }
;           }
;         }
; #pragma unroll
;         for (int u = 0; u < 8; ++u) {
;           const int i = i0 + u;
;           const int grow = g0 + i;
;           const float* Tr = T + (r0 + i) * TS;
;           const float rs = __int_as_float(__builtin_amdgcn_readlane(__float_as_int(rsv), i));
;           if constexpr (EPI == E_RESID || EPI == E_PLEGATE) {
;             const float4 a = *(const float4*)(Tr + 4 * lane);
;             const size_t ro = (size_t)grow * 1024 + n0 + 4 * lane;
;             float4 x4 = xo[u];
;             if constexpr (EPI == E_PLEGATE) {
;               x4.x += bflo(pv[u].x) * fsig(a.x * rs);
;               x4.y += bfhi(pv[u].x) * fsig(a.y * rs);
;               x4.z += bflo(pv[u].y) * fsig(a.z * rs);
;               x4.w += bfhi(pv[u].y) * fsig(a.w * rs);
;             } else {
;               const float sc = fabsf(scale);
;               x4.x += sc * a.x; x4.y += sc * a.y; x4.z += sc * a.z; x4.w += sc * a.w;
;             }
;             st_nt16(p.x + ro, x4);
;             if (xbout) {
;               uint2 o;
;               o.x = pack2(x4.x, x4.y);
;               o.y = pack2(x4.z, x4.w);
;               st_nt8(xbout + ro, o);
;             }
;             if (ssout) {
.LBB0_1679:
	s_or_b64 exec, exec, s[18:19]
	ds_read_b128 v[76:79], v120 offset:5200
	v_lshl_add_u64 v[80:81], v[102:103], 1, s[4:5]
	s_waitcnt lgkmcnt(0)
	v_pk_add_f32 v[72:73], v[72:73], v[76:77]
	v_pk_add_f32 v[74:75], v[74:75], v[78:79]
	global_store_dwordx4 v[100:101], v[72:75], off
	v_cvt_pk_bf16_f32 v76, v72, v73
	v_cvt_pk_bf16_f32 v77, v74, v75
	v_pk_mul_f32 v[72:73], v[72:73], v[72:73]
	v_pk_mul_f32 v[74:75], v[74:75], v[74:75]
	v_add_f32_e32 v72, v72, v73
	v_add_f32_e32 v72, v72, v74
	v_add_f32_e32 v72, v72, v75
	flat_store_dwordx2 v[80:81], v[76:77]
	s_nop 0
	v_add_f32_dpp v72, v72, v72 row_ror:8 row_mask:0xf bank_mask:0xf bound_ctrl:1
	s_nop 1
	v_add_f32_dpp v72, v72, v72 row_ror:4 row_mask:0xf bank_mask:0xf bound_ctrl:1
	s_nop 1
	v_add_f32_dpp v72, v72, v72 row_ror:2 row_mask:0xf bank_mask:0xf bound_ctrl:1
	s_nop 1
	v_add_f32_dpp v72, v72, v72 row_ror:1 row_mask:0xf bank_mask:0xf bound_ctrl:1
	s_nop 0
	v_readlane_b32 s9, v72, 0
	v_readlane_b32 s20, v72, 16
	v_readlane_b32 s18, v72, 32
	v_readlane_b32 s19, v72, 48
	s_and_saveexec_b64 s[16:17], vcc
	s_cbranch_execz .LBB0_1681
	s_lshl_b64 s[14:15], s[14:15], 2
	v_mov_b32_e32 v72, s20
	s_add_u32 s14, s63, s14
	v_add_f32_e32 v72, s9, v72
	s_addc_u32 s15, s64, s15
	v_add_f32_e32 v72, s18, v72
	v_add_f32_e32 v74, s19, v72
	v_mov_b64_e32 v[72:73], s[14:15]
	flat_atomic_add_f32 v[72:73], v74
.LBB0_1681:
	s_or_b64 exec, exec, s[16:17]
	ds_read_b128 v[72:75], v120 offset:6240
	v_lshl_add_u64 v[76:77], v[98:99], 1, s[4:5]
	s_waitcnt lgkmcnt(0)
	v_pk_add_f32 v[68:69], v[68:69], v[72:73]
	v_pk_add_f32 v[70:71], v[70:71], v[74:75]
	global_store_dwordx4 v[96:97], v[68:71], off
	v_cvt_pk_bf16_f32 v72, v68, v69
	v_cvt_pk_bf16_f32 v73, v70, v71
	v_pk_mul_f32 v[68:69], v[68:69], v[68:69]
	v_pk_mul_f32 v[70:71], v[70:71], v[70:71]
	v_add_f32_e32 v68, v68, v69
	v_add_f32_e32 v68, v68, v70
	v_add_f32_e32 v68, v68, v71
	flat_store_dwordx2 v[76:77], v[72:73]
	s_nop 0
	v_add_f32_dpp v68, v68, v68 row_ror:8 row_mask:0xf bank_mask:0xf bound_ctrl:1
	s_nop 1
	v_add_f32_dpp v68, v68, v68 row_ror:4 row_mask:0xf bank_mask:0xf bound_ctrl:1
	s_nop 1
	v_add_f32_dpp v68, v68, v68 row_ror:2 row_mask:0xf bank_mask:0xf bound_ctrl:1
	s_nop 1
	v_add_f32_dpp v68, v68, v68 row_ror:1 row_mask:0xf bank_mask:0xf bound_ctrl:1
	s_nop 0
	v_readlane_b32 s9, v68, 0
	v_readlane_b32 s18, v68, 16
	v_readlane_b32 s16, v68, 32
	v_readlane_b32 s17, v68, 48
	s_and_saveexec_b64 s[14:15], vcc
	s_cbranch_execz .LBB0_1683
	s_lshl_b64 s[12:13], s[12:13], 2
	v_mov_b32_e32 v68, s18
	s_add_u32 s12, s63, s12
	v_add_f32_e32 v68, s9, v68
	s_addc_u32 s13, s64, s13
	v_add_f32_e32 v68, s16, v68
	v_add_f32_e32 v70, s17, v68
	v_mov_b64_e32 v[68:69], s[12:13]
	flat_atomic_add_f32 v[68:69], v70
.LBB0_1683:
	s_or_b64 exec, exec, s[14:15]
	ds_read_b128 v[68:71], v120 offset:7280
	v_lshl_add_u64 v[72:73], v[94:95], 1, s[4:5]
	s_waitcnt lgkmcnt(0)
	v_pk_add_f32 v[64:65], v[64:65], v[68:69]
	v_pk_add_f32 v[66:67], v[66:67], v[70:71]
	global_store_dwordx4 v[92:93], v[64:67], off
	v_cvt_pk_bf16_f32 v68, v64, v65
	v_cvt_pk_bf16_f32 v69, v66, v67
	v_pk_mul_f32 v[64:65], v[64:65], v[64:65]
	v_pk_mul_f32 v[66:67], v[66:67], v[66:67]
	v_add_f32_e32 v64, v64, v65
	v_add_f32_e32 v64, v64, v66
	v_add_f32_e32 v64, v64, v67
	flat_store_dwordx2 v[72:73], v[68:69]
	s_nop 0
	v_add_f32_dpp v64, v64, v64 row_ror:8 row_mask:0xf bank_mask:0xf bound_ctrl:1
	s_nop 1
	v_add_f32_dpp v64, v64, v64 row_ror:4 row_mask:0xf bank_mask:0xf bound_ctrl:1
	s_nop 1
	v_add_f32_dpp v64, v64, v64 row_ror:2 row_mask:0xf bank_mask:0xf bound_ctrl:1
	s_nop 1
	v_add_f32_dpp v64, v64, v64 row_ror:1 row_mask:0xf bank_mask:0xf bound_ctrl:1
	s_nop 0
	v_readlane_b32 s9, v64, 0
	v_readlane_b32 s16, v64, 16
	v_readlane_b32 s14, v64, 32
	v_readlane_b32 s15, v64, 48
	s_and_saveexec_b64 s[12:13], vcc
	s_cbranch_execz .LBB0_1685
	s_lshl_b64 s[10:11], s[10:11], 2
	v_mov_b32_e32 v64, s16
	s_add_u32 s10, s63, s10
	v_add_f32_e32 v64, s9, v64
	s_addc_u32 s11, s64, s11
	v_add_f32_e32 v64, s14, v64
	v_add_f32_e32 v66, s15, v64
	v_mov_b64_e32 v[64:65], s[10:11]
	flat_atomic_add_f32 v[64:65], v66
.LBB0_1685:
	s_or_b64 exec, exec, s[12:13]
	s_or_b32 s30, s8, 8
	s_ashr_i32 s31, s30, 31
	s_lshl_b64 s[10:11], s[30:31], 10
	s_or_b32 s22, s8, 9
	v_lshl_add_u64 v[146:147], s[10:11], 0, v[128:129]
	s_ashr_i32 s23, s22, 31
	s_or_b32 s20, s8, 10
	v_lshl_add_u64 v[156:157], v[146:147], 2, s[38:39]
	s_lshl_b64 s[10:11], s[22:23], 10
	s_ashr_i32 s21, s20, 31
	s_or_b32 s18, s8, 11
	global_load_dwordx4 v[142:145], v[156:157], off
	v_lshl_add_u64 v[118:119], s[10:11], 0, v[128:129]
	s_lshl_b64 s[10:11], s[20:21], 10
	s_ashr_i32 s19, s18, 31
	s_or_b32 s16, s8, 12
	v_lshl_add_u64 v[114:115], s[10:11], 0, v[128:129]
	s_lshl_b64 s[10:11], s[18:19], 10
	s_ashr_i32 s17, s16, 31
	s_or_b32 s14, s8, 13
	v_lshl_add_u64 v[110:111], s[10:11], 0, v[128:129]
	s_lshl_b64 s[10:11], s[16:17], 10
	s_ashr_i32 s15, s14, 31
	s_or_b32 s12, s8, 14
	v_lshl_add_u64 v[106:107], s[10:11], 0, v[128:129]
	s_lshl_b64 s[10:11], s[14:15], 10
	s_ashr_i32 s13, s12, 31
	v_lshl_add_u64 v[102:103], s[10:11], 0, v[128:129]
	s_lshl_b64 s[10:11], s[12:13], 10
	v_lshl_add_u64 v[98:99], s[10:11], 0, v[128:129]
	s_or_b32 s10, s8, 15
	s_ashr_i32 s11, s10, 31
	s_lshl_b64 s[34:35], s[10:11], 10
	v_lshl_add_u64 v[94:95], s[34:35], 0, v[128:129]
	v_lshl_add_u64 v[116:117], v[118:119], 2, s[38:39]
	v_lshl_add_u64 v[108:109], v[110:111], 2, s[38:39]
	v_lshl_add_u64 v[100:101], v[102:103], 2, s[38:39]
	v_lshl_add_u64 v[92:93], v[94:95], 2, s[38:39]
	v_lshl_add_u64 v[112:113], v[114:115], 2, s[38:39]
	global_load_dwordx4 v[88:91], v[116:117], off
	global_load_dwordx4 v[84:87], v[112:113], off
	v_lshl_add_u64 v[104:105], v[106:107], 2, s[38:39]
	global_load_dwordx4 v[80:83], v[108:109], off
	global_load_dwordx4 v[76:79], v[104:105], off
	v_lshl_add_u64 v[96:97], v[98:99], 2, s[38:39]
	global_load_dwordx4 v[72:75], v[100:101], off
	global_load_dwordx4 v[68:71], v[96:97], off
	global_load_dwordx4 v[64:67], v[92:93], off
	ds_read_b128 v[152:155], v120 offset:8320
	v_lshl_add_u64 v[146:147], v[146:147], 1, s[4:5]
	s_waitcnt vmcnt(0) lgkmcnt(0)
; DEVI float fsig(float x) { return __builtin_amdgcn_rcpf(1.f + __expf(-x)); }
; DEVI float bflo(unsigned u) { return __uint_as_float(u << 16); }
; DEVI float bfhi(unsigned u) { return __uint_as_float(u & 0xffff0000u); }
; template <int EPI, int TS, bool VT>
; DEVI void gemm_epilogue(const Params& p, char* smem, f32x4 (&acc)[2][2][4][2], int m0, int n0, float scale, const float* ssin,
;                         float* ssout, u16* xbout, int wid, int lane, int wr, int wc, int fr, int fq) {
;     ...
;         for (int u = 0; u < 8; ++u) {
;           const int i = i0 + u;
;           const int grow = g0 + i;
;           const float* Tr = T + (r0 + i) * TS;
;           const float rs = __int_as_float(__builtin_amdgcn_readlane(__float_as_int(rsv), i));
;           if constexpr (EPI == E_RESID || EPI == E_PLEGATE) {
;             const float4 a = *(const float4*)(Tr + 4 * lane);
;             const size_t ro = (size_t)grow * 1024 + n0 + 4 * lane;
;             float4 x4 = xo[u];
;             if constexpr (EPI == E_PLEGATE) {
;               x4.x += bflo(pv[u].x) * fsig(a.x * rs);
;               x4.y += bfhi(pv[u].x) * fsig(a.y * rs);
;               x4.z += bflo(pv[u].y) * fsig(a.z * rs);
;               x4.w += bfhi(pv[u].y) * fsig(a.w * rs);
;             } else {
;               const float sc = fabsf(scale);
;               x4.x += sc * a.x; x4.y += sc * a.y; x4.z += sc * a.z; x4.w += sc * a.w;
;             }
;             st_nt16(p.x + ro, x4);
;             if (xbout) {
;               uint2 o;
;               o.x = pack2(x4.x, x4.y);
;               o.y = pack2(x4.z, x4.w);
;               st_nt8(xbout + ro, o);
;             }
;             if (ssout) {
;               const float ssq = wsum(x4.x * x4.x + x4.y * x4.y + x4.z * x4.z + x4.w * x4.w, lane);
;               if (lane == 0) atomicAdd(ssout + grow, ssq);
;             }
	v_pk_add_f32 v[142:143], v[142:143], v[152:153]
	v_pk_add_f32 v[144:145], v[144:145], v[154:155]
	global_store_dwordx4 v[156:157], v[142:145], off
	v_cvt_pk_bf16_f32 v152, v142, v143
	v_cvt_pk_bf16_f32 v153, v144, v145
	v_pk_mul_f32 v[142:143], v[142:143], v[142:143]
	v_pk_mul_f32 v[144:145], v[144:145], v[144:145]
	v_add_f32_e32 v141, v142, v143
	v_add_f32_e32 v141, v141, v144
	v_add_f32_e32 v141, v141, v145
	flat_store_dwordx2 v[146:147], v[152:153]
	s_nop 0
	v_add_f32_dpp v141, v141, v141 row_ror:8 row_mask:0xf bank_mask:0xf bound_ctrl:1
	s_nop 1
	v_add_f32_dpp v141, v141, v141 row_ror:4 row_mask:0xf bank_mask:0xf bound_ctrl:1
	s_nop 1
	v_add_f32_dpp v141, v141, v141 row_ror:2 row_mask:0xf bank_mask:0xf bound_ctrl:1
	s_nop 1
	v_add_f32_dpp v141, v141, v141 row_ror:1 row_mask:0xf bank_mask:0xf bound_ctrl:1
	s_nop 0
	v_readlane_b32 s9, v141, 0
	v_readlane_b32 s69, v141, 16
	v_readlane_b32 s67, v141, 32
	v_readlane_b32 s68, v141, 48
	s_and_saveexec_b64 s[34:35], vcc
	s_cbranch_execz .LBB0_1687
	s_lshl_b64 s[30:31], s[30:31], 2
	v_mov_b32_e32 v141, s69
	s_add_u32 s30, s63, s30
	v_add_f32_e32 v141, s9, v141
	s_addc_u32 s31, s64, s31
	v_add_f32_e32 v141, s67, v141
	v_add_f32_e32 v141, s68, v141
	v_mov_b64_e32 v[142:143], s[30:31]
	flat_atomic_add_f32 v[142:143], v141
.LBB0_1687:
	s_or_b64 exec, exec, s[34:35]
	ds_read_b128 v[142:145], v120 offset:9360
	v_lshl_add_u64 v[118:119], v[118:119], 1, s[4:5]
	s_waitcnt lgkmcnt(0)
	v_pk_add_f32 v[88:89], v[88:89], v[142:143]
	v_pk_add_f32 v[90:91], v[90:91], v[144:145]
	global_store_dwordx4 v[116:117], v[88:91], off
	v_cvt_pk_bf16_f32 v116, v88, v89
	v_cvt_pk_bf16_f32 v117, v90, v91
	v_pk_mul_f32 v[88:89], v[88:89], v[88:89]
	v_pk_mul_f32 v[90:91], v[90:91], v[90:91]
	v_add_f32_e32 v88, v88, v89
	v_add_f32_e32 v88, v88, v90
	v_add_f32_e32 v88, v88, v91
	flat_store_dwordx2 v[118:119], v[116:117]
	s_nop 0
	v_add_f32_dpp v88, v88, v88 row_ror:8 row_mask:0xf bank_mask:0xf bound_ctrl:1
	s_nop 1
	v_add_f32_dpp v88, v88, v88 row_ror:4 row_mask:0xf bank_mask:0xf bound_ctrl:1
	s_nop 1
	v_add_f32_dpp v88, v88, v88 row_ror:2 row_mask:0xf bank_mask:0xf bound_ctrl:1
	s_nop 1
	v_add_f32_dpp v88, v88, v88 row_ror:1 row_mask:0xf bank_mask:0xf bound_ctrl:1
	s_nop 0
	v_readlane_b32 s9, v88, 0
	v_readlane_b32 s67, v88, 16
	v_readlane_b32 s34, v88, 32
	v_readlane_b32 s35, v88, 48
	s_and_saveexec_b64 s[30:31], vcc
	s_cbranch_execz .LBB0_1689
	s_lshl_b64 s[22:23], s[22:23], 2
	v_mov_b32_e32 v88, s67
	s_add_u32 s22, s63, s22
	v_add_f32_e32 v88, s9, v88
	s_addc_u32 s23, s64, s23
	v_add_f32_e32 v88, s34, v88
	v_add_f32_e32 v90, s35, v88
	v_mov_b64_e32 v[88:89], s[22:23]
	flat_atomic_add_f32 v[88:89], v90
.LBB0_1689:
	s_or_b64 exec, exec, s[30:31]
	ds_read_b128 v[88:91], v120 offset:10400
	v_lshl_add_u64 v[114:115], v[114:115], 1, s[4:5]
	s_waitcnt lgkmcnt(0)
	v_pk_add_f32 v[84:85], v[84:85], v[88:89]
	v_pk_add_f32 v[86:87], v[86:87], v[90:91]
	global_store_dwordx4 v[112:113], v[84:87], off
	v_cvt_pk_bf16_f32 v88, v84, v85
	v_cvt_pk_bf16_f32 v89, v86, v87
	v_pk_mul_f32 v[84:85], v[84:85], v[84:85]
	v_pk_mul_f32 v[86:87], v[86:87], v[86:87]
	v_add_f32_e32 v84, v84, v85
	v_add_f32_e32 v84, v84, v86
	v_add_f32_e32 v84, v84, v87
	flat_store_dwordx2 v[114:115], v[88:89]
	s_nop 0
	v_add_f32_dpp v84, v84, v84 row_ror:8 row_mask:0xf bank_mask:0xf bound_ctrl:1
	s_nop 1
	v_add_f32_dpp v84, v84, v84 row_ror:4 row_mask:0xf bank_mask:0xf bound_ctrl:1
	s_nop 1
	v_add_f32_dpp v84, v84, v84 row_ror:2 row_mask:0xf bank_mask:0xf bound_ctrl:1
	s_nop 1
	v_add_f32_dpp v84, v84, v84 row_ror:1 row_mask:0xf bank_mask:0xf bound_ctrl:1
	s_nop 0
	v_readlane_b32 s9, v84, 0
	v_readlane_b32 s34, v84, 16
	v_readlane_b32 s30, v84, 32
	v_readlane_b32 s31, v84, 48
	s_and_saveexec_b64 s[22:23], vcc
	s_cbranch_execz .LBB0_1691
	s_lshl_b64 s[20:21], s[20:21], 2
	v_mov_b32_e32 v84, s34
	s_add_u32 s20, s63, s20
	v_add_f32_e32 v84, s9, v84
	s_addc_u32 s21, s64, s21
	v_add_f32_e32 v84, s30, v84
	v_add_f32_e32 v86, s31, v84
	v_mov_b64_e32 v[84:85], s[20:21]
	flat_atomic_add_f32 v[84:85], v86
.LBB0_1691:
	s_or_b64 exec, exec, s[22:23]
	ds_read_b128 v[84:87], v120 offset:11440
	v_lshl_add_u64 v[88:89], v[110:111], 1, s[4:5]
	s_waitcnt lgkmcnt(0)
	v_pk_add_f32 v[80:81], v[80:81], v[84:85]
	v_pk_add_f32 v[82:83], v[82:83], v[86:87]
	global_store_dwordx4 v[108:109], v[80:83], off
	v_cvt_pk_bf16_f32 v84, v80, v81
	v_cvt_pk_bf16_f32 v85, v82, v83
	v_pk_mul_f32 v[80:81], v[80:81], v[80:81]
	v_pk_mul_f32 v[82:83], v[82:83], v[82:83]
	v_add_f32_e32 v80, v80, v81
	v_add_f32_e32 v80, v80, v82
	v_add_f32_e32 v80, v80, v83
	flat_store_dwordx2 v[88:89], v[84:85]
	s_nop 0
	v_add_f32_dpp v80, v80, v80 row_ror:8 row_mask:0xf bank_mask:0xf bound_ctrl:1
	s_nop 1
	v_add_f32_dpp v80, v80, v80 row_ror:4 row_mask:0xf bank_mask:0xf bound_ctrl:1
	s_nop 1
	v_add_f32_dpp v80, v80, v80 row_ror:2 row_mask:0xf bank_mask:0xf bound_ctrl:1
	s_nop 1
	v_add_f32_dpp v80, v80, v80 row_ror:1 row_mask:0xf bank_mask:0xf bound_ctrl:1
	s_nop 0
	v_readlane_b32 s9, v80, 0
	v_readlane_b32 s30, v80, 16
	v_readlane_b32 s22, v80, 32
	v_readlane_b32 s23, v80, 48
	s_and_saveexec_b64 s[20:21], vcc
	s_cbranch_execz .LBB0_1693
	s_lshl_b64 s[18:19], s[18:19], 2
	v_mov_b32_e32 v80, s30
	s_add_u32 s18, s63, s18
	v_add_f32_e32 v80, s9, v80
	s_addc_u32 s19, s64, s19
	v_add_f32_e32 v80, s22, v80
	v_add_f32_e32 v82, s23, v80
	v_mov_b64_e32 v[80:81], s[18:19]
	flat_atomic_add_f32 v[80:81], v82
; DEVI float fsig(float x) { return __builtin_amdgcn_rcpf(1.f + __expf(-x)); }
; DEVI float bflo(unsigned u) { return __uint_as_float(u << 16); }
; DEVI float bfhi(unsigned u) { return __uint_as_float(u & 0xffff0000u); }
; template <int EPI, int TS, bool VT>
; DEVI void gemm_epilogue(const Params& p, char* smem, f32x4 (&acc)[2][2][4][2], int m0, int n0, float scale, const float* ssin,
;                         float* ssout, u16* xbout, int wid, int lane, int wr, int wc, int fr, int fq) {
;     ...
;         for (int u = 0; u < 8; ++u) {
;           const int i = i0 + u;
;           const int grow = g0 + i;
;           const float* Tr = T + (r0 + i) * TS;
;           const float rs = __int_as_float(__builtin_amdgcn_readlane(__float_as_int(rsv), i));
;           if constexpr (EPI == E_RESID || EPI == E_PLEGATE) {
;             const float4 a = *(const float4*)(Tr + 4 * lane);
;             const size_t ro = (size_t)grow * 1024 + n0 + 4 * lane;
;             float4 x4 = xo[u];
;             if constexpr (EPI == E_PLEGATE) {
;               x4.x += bflo(pv[u].x) * fsig(a.x * rs);
;               x4.y += bfhi(pv[u].x) * fsig(a.y * rs);
;               x4.z += bflo(pv[u].y) * fsig(a.z * rs);
;               x4.w += bfhi(pv[u].y) * fsig(a.w * rs);
;             } else {
;               const float sc = fabsf(scale);
;               x4.x += sc * a.x; x4.y += sc * a.y; x4.z += sc * a.z; x4.w += sc * a.w;
;             }
;             st_nt16(p.x + ro, x4);
;             if (xbout) {
;               uint2 o;
;               o.x = pack2(x4.x, x4.y);
;               o.y = pack2(x4.z, x4.w);
;               st_nt8(xbout + ro, o);
;             }
;             if (ssout) {
;               const float ssq = wsum(x4.x * x4.x + x4.y * x4.y + x4.z * x4.z + x4.w * x4.w, lane);
;               if (lane == 0) atomicAdd(ssout + grow, ssq);
;             }
.LBB0_1693:
	s_or_b64 exec, exec, s[20:21]
	ds_read_b128 v[80:83], v120 offset:12480
	v_lshl_add_u64 v[84:85], v[106:107], 1, s[4:5]
	s_waitcnt lgkmcnt(0)
	v_pk_add_f32 v[76:77], v[76:77], v[80:81]
	v_pk_add_f32 v[78:79], v[78:79], v[82:83]
	global_store_dwordx4 v[104:105], v[76:79], off
	v_cvt_pk_bf16_f32 v80, v76, v77
	v_cvt_pk_bf16_f32 v81, v78, v79
	v_pk_mul_f32 v[76:77], v[76:77], v[76:77]
	v_pk_mul_f32 v[78:79], v[78:79], v[78:79]
	v_add_f32_e32 v76, v76, v77
	v_add_f32_e32 v76, v76, v78
	v_add_f32_e32 v76, v76, v79
	flat_store_dwordx2 v[84:85], v[80:81]
	s_nop 0
	v_add_f32_dpp v76, v76, v76 row_ror:8 row_mask:0xf bank_mask:0xf bound_ctrl:1
	s_nop 1
	v_add_f32_dpp v76, v76, v76 row_ror:4 row_mask:0xf bank_mask:0xf bound_ctrl:1
	s_nop 1
	v_add_f32_dpp v76, v76, v76 row_ror:2 row_mask:0xf bank_mask:0xf bound_ctrl:1
	s_nop 1
	v_add_f32_dpp v76, v76, v76 row_ror:1 row_mask:0xf bank_mask:0xf bound_ctrl:1
	s_nop 0
	v_readlane_b32 s9, v76, 0
	v_readlane_b32 s22, v76, 16
	v_readlane_b32 s20, v76, 32
	v_readlane_b32 s21, v76, 48
	s_and_saveexec_b64 s[18:19], vcc
	s_cbranch_execz .LBB0_1695
	s_lshl_b64 s[16:17], s[16:17], 2
	v_mov_b32_e32 v76, s22
	s_add_u32 s16, s63, s16
	v_add_f32_e32 v76, s9, v76
	s_addc_u32 s17, s64, s17
	v_add_f32_e32 v76, s20, v76
	v_add_f32_e32 v78, s21, v76
	v_mov_b64_e32 v[76:77], s[16:17]
	flat_atomic_add_f32 v[76:77], v78
.LBB0_1695:
	s_or_b64 exec, exec, s[18:19]
	ds_read_b128 v[76:79], v120 offset:13520
	v_lshl_add_u64 v[80:81], v[102:103], 1, s[4:5]
	s_waitcnt lgkmcnt(0)
	v_pk_add_f32 v[72:73], v[72:73], v[76:77]
	v_pk_add_f32 v[74:75], v[74:75], v[78:79]
	global_store_dwordx4 v[100:101], v[72:75], off
	v_cvt_pk_bf16_f32 v76, v72, v73
	v_cvt_pk_bf16_f32 v77, v74, v75
	v_pk_mul_f32 v[72:73], v[72:73], v[72:73]
	v_pk_mul_f32 v[74:75], v[74:75], v[74:75]
	v_add_f32_e32 v72, v72, v73
	v_add_f32_e32 v72, v72, v74
	v_add_f32_e32 v72, v72, v75
	flat_store_dwordx2 v[80:81], v[76:77]
	s_nop 0
	v_add_f32_dpp v72, v72, v72 row_ror:8 row_mask:0xf bank_mask:0xf bound_ctrl:1
	s_nop 1
	v_add_f32_dpp v72, v72, v72 row_ror:4 row_mask:0xf bank_mask:0xf bound_ctrl:1
	s_nop 1
	v_add_f32_dpp v72, v72, v72 row_ror:2 row_mask:0xf bank_mask:0xf bound_ctrl:1
	s_nop 1
	v_add_f32_dpp v72, v72, v72 row_ror:1 row_mask:0xf bank_mask:0xf bound_ctrl:1
	s_nop 0
	v_readlane_b32 s9, v72, 0
	v_readlane_b32 s20, v72, 16
	v_readlane_b32 s18, v72, 32
	v_readlane_b32 s19, v72, 48
	s_and_saveexec_b64 s[16:17], vcc
	s_cbranch_execz .LBB0_1697
	s_lshl_b64 s[14:15], s[14:15], 2
	v_mov_b32_e32 v72, s20
	s_add_u32 s14, s63, s14
	v_add_f32_e32 v72, s9, v72
	s_addc_u32 s15, s64, s15
	v_add_f32_e32 v72, s18, v72
	v_add_f32_e32 v74, s19, v72
	v_mov_b64_e32 v[72:73], s[14:15]
	flat_atomic_add_f32 v[72:73], v74
.LBB0_1697:
	s_or_b64 exec, exec, s[16:17]
	ds_read_b128 v[72:75], v120 offset:14560
	v_lshl_add_u64 v[76:77], v[98:99], 1, s[4:5]
	s_waitcnt lgkmcnt(0)
	v_pk_add_f32 v[68:69], v[68:69], v[72:73]
	v_pk_add_f32 v[70:71], v[70:71], v[74:75]
	global_store_dwordx4 v[96:97], v[68:71], off
	v_cvt_pk_bf16_f32 v72, v68, v69
	v_cvt_pk_bf16_f32 v73, v70, v71
	v_pk_mul_f32 v[68:69], v[68:69], v[68:69]
	v_pk_mul_f32 v[70:71], v[70:71], v[70:71]
	v_add_f32_e32 v68, v68, v69
	v_add_f32_e32 v68, v68, v70
	v_add_f32_e32 v68, v68, v71
	flat_store_dwordx2 v[76:77], v[72:73]
	s_nop 0
	v_add_f32_dpp v68, v68, v68 row_ror:8 row_mask:0xf bank_mask:0xf bound_ctrl:1
	s_nop 1
	v_add_f32_dpp v68, v68, v68 row_ror:4 row_mask:0xf bank_mask:0xf bound_ctrl:1
	s_nop 1
	v_add_f32_dpp v68, v68, v68 row_ror:2 row_mask:0xf bank_mask:0xf bound_ctrl:1
	s_nop 1
	v_add_f32_dpp v68, v68, v68 row_ror:1 row_mask:0xf bank_mask:0xf bound_ctrl:1
	s_nop 0
	v_readlane_b32 s9, v68, 0
	v_readlane_b32 s18, v68, 16
	v_readlane_b32 s16, v68, 32
	v_readlane_b32 s17, v68, 48
	s_and_saveexec_b64 s[14:15], vcc
	s_cbranch_execz .LBB0_1699
	s_lshl_b64 s[12:13], s[12:13], 2
	v_mov_b32_e32 v68, s18
	s_add_u32 s12, s63, s12
	v_add_f32_e32 v68, s9, v68
	s_addc_u32 s13, s64, s13
	v_add_f32_e32 v68, s16, v68
	v_add_f32_e32 v70, s17, v68
	v_mov_b64_e32 v[68:69], s[12:13]
	flat_atomic_add_f32 v[68:69], v70
.LBB0_1699:
	s_or_b64 exec, exec, s[14:15]
	ds_read_b128 v[68:71], v120 offset:15600
	v_lshl_add_u64 v[72:73], v[94:95], 1, s[4:5]
	s_waitcnt lgkmcnt(0)
	v_pk_add_f32 v[64:65], v[64:65], v[68:69]
	v_pk_add_f32 v[66:67], v[66:67], v[70:71]
	global_store_dwordx4 v[92:93], v[64:67], off
	v_cvt_pk_bf16_f32 v68, v64, v65
	v_cvt_pk_bf16_f32 v69, v66, v67
	v_pk_mul_f32 v[64:65], v[64:65], v[64:65]
	v_pk_mul_f32 v[66:67], v[66:67], v[66:67]
	v_add_f32_e32 v64, v64, v65
	v_add_f32_e32 v64, v64, v66
	v_add_f32_e32 v64, v64, v67
	flat_store_dwordx2 v[72:73], v[68:69]
	s_nop 0
	v_add_f32_dpp v64, v64, v64 row_ror:8 row_mask:0xf bank_mask:0xf bound_ctrl:1
	s_nop 1
	v_add_f32_dpp v64, v64, v64 row_ror:4 row_mask:0xf bank_mask:0xf bound_ctrl:1
	s_nop 1
	v_add_f32_dpp v64, v64, v64 row_ror:2 row_mask:0xf bank_mask:0xf bound_ctrl:1
	s_nop 1
	v_add_f32_dpp v64, v64, v64 row_ror:1 row_mask:0xf bank_mask:0xf bound_ctrl:1
	s_nop 0
	v_readlane_b32 s9, v64, 0
	v_readlane_b32 s16, v64, 16
	v_readlane_b32 s14, v64, 32
	v_readlane_b32 s15, v64, 48
	s_and_saveexec_b64 s[12:13], vcc
	s_cbranch_execz .LBB0_1701
	s_lshl_b64 s[10:11], s[10:11], 2
	v_mov_b32_e32 v64, s16
	s_add_u32 s10, s63, s10
	v_add_f32_e32 v64, s9, v64
	s_addc_u32 s11, s64, s11
	v_add_f32_e32 v64, s14, v64
	v_add_f32_e32 v66, s15, v64
	v_mov_b64_e32 v[64:65], s[10:11]
	flat_atomic_add_f32 v[64:65], v66
; template <int EPI, int TS, bool VT>
; DEVI void gemm_epilogue(const Params& p, char* smem, f32x4 (&acc)[2][2][4][2], int m0, int n0, float scale, const float* ssin,
;                         float* ssout, u16* xbout, int wid, int lane, int wr, int wc, int fr, int fq) {
;     ...
;       float* tw = T + (wr * 64 + fq * 4) * TS + wc * 32 + fr;
; #pragma unroll
;       for (int m = 0; m < 4; ++m)
; #pragma unroll
;         for (int j = 0; j < 4; ++j)
; #pragma unroll
;           for (int v = 0; v < 4; ++v) tw[(m * 16 + j) * TS + (v >> 1) * 128 + (v & 1) * 16] = acc[ai][v >> 1][m][v & 1][j];
;     }
;     __syncthreads();
;     ...
;         if constexpr (EPI == E_RESID || EPI == E_PLEGATE) {
; #pragma unroll
;           for (int u = 0; u < 8; ++u) {
;             const size_t ro = (size_t)(g0 + i0 + u) * 1024 + n0 + 4 * lane;
;             const int gr = g0 + i0 + u;
;             const float* xs = p.x + ro;
;             if (scale < 0.f)
;               xs = (gr < MP ? p.x_prompt + ro : p.x_sample + (ro - (size_t)MP * 1024));
;             { const f32x4 t_ = __builtin_nontemporal_load((const f32x4*)xs); xo[u] = make_float4(t_[0], t_[1], t_[2], t_[3]); }
;             if constexpr (EPI == E_PLEGATE) {
;               const unsigned long long t2_ = __builtin_nontemporal_load((const unsigned long long*)((const u16*)(wsb + OFF_PP) + ro));
;               pv[u] = make_uint2((unsigned)t2_, (unsigned)(t2_ >> 32));
;             }
;           }
;         }
; #pragma unroll
;         for (int u = 0; u < 8; ++u) {
;           const int i = i0 + u;
;           const int grow = g0 + i;
;           const float* Tr = T + (r0 + i) * TS;
;           const float rs = __int_as_float(__builtin_amdgcn_readlane(__float_as_int(rsv), i));
;           if constexpr (EPI == E_RESID || EPI == E_PLEGATE) {
;             const float4 a = *(const float4*)(Tr + 4 * lane);
;             const size_t ro = (size_t)grow * 1024 + n0 + 4 * lane;
;             float4 x4 = xo[u];
;             if constexpr (EPI == E_PLEGATE) {
;               x4.x += bflo(pv[u].x) * fsig(a.x * rs);
;               x4.y += bfhi(pv[u].x) * fsig(a.y * rs);
;               x4.z += bflo(pv[u].y) * fsig(a.z * rs);
;               x4.w += bfhi(pv[u].y) * fsig(a.w * rs);
;             } else {
;               const float sc = fabsf(scale);
;               x4.x += sc * a.x; x4.y += sc * a.y; x4.z += sc * a.z; x4.w += sc * a.w;
.LBB0_1701:
	s_or_b64 exec, exec, s[12:13]
	s_add_i32 s30, s8, 0x80
	s_ashr_i32 s31, s30, 31
	s_lshl_b64 s[10:11], s[30:31], 10
	s_add_i32 s22, s8, 0x81
	v_lshl_add_u64 v[64:65], s[10:11], 0, v[128:129]
	s_ashr_i32 s23, s22, 31
	s_add_i32 s20, s8, 0x82
	v_lshl_add_u64 v[66:67], v[64:65], 2, s[38:39]
	s_lshl_b64 s[10:11], s[22:23], 10
	s_ashr_i32 s21, s20, 31
	s_add_i32 s18, s8, 0x83
	s_waitcnt lgkmcnt(0)
	s_barrier
	ds_write2_b32 v130, v24, v28 offset1:16
	ds_write2_b32 v130, v56, v60 offset0:128 offset1:144
	ds_write2_b32 v124, v25, v29 offset0:4 offset1:20
	ds_write2_b32 v124, v57, v61 offset0:132 offset1:148
	ds_write2_b32 v121, v26, v30 offset0:8 offset1:24
	ds_write2_b32 v121, v58, v62 offset0:136 offset1:152
	ds_write2_b32 v122, v27, v31 offset0:12 offset1:28
	ds_write2_b32 v122, v59, v63 offset0:140 offset1:156
	ds_write2_b32 v123, v16, v20 offset0:64 offset1:80
	ds_write2_b32 v123, v48, v52 offset0:192 offset1:208
	ds_write2_b32 v125, v17, v21 offset0:68 offset1:84
	ds_write2_b32 v125, v49, v53 offset0:196 offset1:212
	ds_write2_b32 v126, v18, v22 offset0:72 offset1:88
	ds_write2_b32 v126, v50, v54 offset0:200 offset1:216
	ds_write2_b32 v127, v19, v23 offset0:76 offset1:92
	ds_write2_b32 v127, v51, v55 offset0:204 offset1:220
	ds_write2_b32 v131, v8, v12 offset0:128 offset1:144
	ds_write2_b32 v132, v40, v44 offset1:16
	ds_write2_b32 v132, v9, v13 offset0:132 offset1:148
	ds_write2_b32 v133, v41, v45 offset0:4 offset1:20
	ds_write2_b32 v133, v10, v14 offset0:136 offset1:152
	ds_write2_b32 v134, v42, v46 offset0:8 offset1:24
	ds_write2_b32 v134, v11, v15 offset0:140 offset1:156
	ds_write2_b32 v135, v43, v47 offset0:12 offset1:28
	ds_write2_b32 v136, v0, v4 offset0:192 offset1:208
	ds_write2_b32 v137, v32, v36 offset0:64 offset1:80
	ds_write2_b32 v137, v1, v5 offset0:196 offset1:212
	ds_write2_b32 v138, v33, v37 offset0:68 offset1:84
	ds_write2_b32 v138, v2, v6 offset0:200 offset1:216
	ds_write2_b32 v139, v34, v38 offset0:72 offset1:88
	ds_write2_b32 v139, v3, v7 offset0:204 offset1:220
	ds_write2_b32 v140, v35, v39 offset0:76 offset1:92
	s_waitcnt lgkmcnt(0)
	s_barrier
	global_load_dwordx4 v[56:59], v[66:67], off
	v_lshl_add_u64 v[54:55], s[10:11], 0, v[128:129]
	s_lshl_b64 s[10:11], s[20:21], 10
	s_ashr_i32 s19, s18, 31
	s_add_i32 s16, s8, 0x84
	v_lshl_add_u64 v[50:51], s[10:11], 0, v[128:129]
	s_lshl_b64 s[10:11], s[18:19], 10
	s_ashr_i32 s17, s16, 31
	s_add_i32 s14, s8, 0x85
	v_lshl_add_u64 v[46:47], s[10:11], 0, v[128:129]
	s_lshl_b64 s[10:11], s[16:17], 10
	s_ashr_i32 s15, s14, 31
	s_add_i32 s12, s8, 0x86
	v_lshl_add_u64 v[42:43], s[10:11], 0, v[128:129]
	s_lshl_b64 s[10:11], s[14:15], 10
	s_ashr_i32 s13, s12, 31
	v_lshl_add_u64 v[38:39], s[10:11], 0, v[128:129]
	s_lshl_b64 s[10:11], s[12:13], 10
	v_lshl_add_u64 v[34:35], s[10:11], 0, v[128:129]
	s_add_i32 s10, s8, 0x87
	s_ashr_i32 s11, s10, 31
	s_lshl_b64 s[34:35], s[10:11], 10
	v_lshl_add_u64 v[30:31], s[34:35], 0, v[128:129]
	v_lshl_add_u64 v[52:53], v[54:55], 2, s[38:39]
	v_lshl_add_u64 v[44:45], v[46:47], 2, s[38:39]
	v_lshl_add_u64 v[36:37], v[38:39], 2, s[38:39]
	v_lshl_add_u64 v[28:29], v[30:31], 2, s[38:39]
	v_lshl_add_u64 v[48:49], v[50:51], 2, s[38:39]
	global_load_dwordx4 v[24:27], v[52:53], off
	global_load_dwordx4 v[20:23], v[48:49], off
	v_lshl_add_u64 v[40:41], v[42:43], 2, s[38:39]
	global_load_dwordx4 v[16:19], v[44:45], off
	global_load_dwordx4 v[12:15], v[40:41], off
	v_lshl_add_u64 v[32:33], v[34:35], 2, s[38:39]
	global_load_dwordx4 v[8:11], v[36:37], off
	global_load_dwordx4 v[4:7], v[32:33], off
	global_load_dwordx4 v[0:3], v[28:29], off
	ds_read_b128 v[60:63], v120
	s_waitcnt vmcnt(0) lgkmcnt(0)
	v_pk_add_f32 v[56:57], v[56:57], v[60:61]
	v_pk_add_f32 v[58:59], v[58:59], v[62:63]
	global_store_dwordx4 v[66:67], v[56:59], off
	v_cvt_pk_bf16_f32 v60, v56, v57
	v_cvt_pk_bf16_f32 v61, v58, v59
	v_pk_mul_f32 v[56:57], v[56:57], v[56:57]
	v_pk_mul_f32 v[58:59], v[58:59], v[58:59]
	v_add_f32_e32 v56, v56, v57
	v_add_f32_e32 v56, v56, v58
	v_add_f32_e32 v56, v56, v59
	v_lshl_add_u64 v[62:63], v[64:65], 1, s[4:5]
	flat_store_dwordx2 v[62:63], v[60:61]
	v_add_f32_dpp v56, v56, v56 row_ror:8 row_mask:0xf bank_mask:0xf bound_ctrl:1
	s_nop 1
	v_add_f32_dpp v56, v56, v56 row_ror:4 row_mask:0xf bank_mask:0xf bound_ctrl:1
	s_nop 1
	v_add_f32_dpp v56, v56, v56 row_ror:2 row_mask:0xf bank_mask:0xf bound_ctrl:1
	s_nop 1
	v_add_f32_dpp v56, v56, v56 row_ror:1 row_mask:0xf bank_mask:0xf bound_ctrl:1
	s_nop 0
	v_readlane_b32 s9, v56, 0
	v_readlane_b32 s69, v56, 16
	v_readlane_b32 s67, v56, 32
	v_readlane_b32 s68, v56, 48
	s_and_saveexec_b64 s[34:35], vcc
	s_cbranch_execz .LBB0_1703
	s_lshl_b64 s[30:31], s[30:31], 2
	v_mov_b32_e32 v56, s69
	s_add_u32 s30, s63, s30
	v_add_f32_e32 v56, s9, v56
	s_addc_u32 s31, s64, s31
	v_add_f32_e32 v56, s67, v56
	v_add_f32_e32 v58, s68, v56
	v_mov_b64_e32 v[56:57], s[30:31]
	flat_atomic_add_f32 v[56:57], v58
.LBB0_1703:
	s_or_b64 exec, exec, s[34:35]
	ds_read_b128 v[56:59], v120 offset:1040
	v_lshl_add_u64 v[54:55], v[54:55], 1, s[4:5]
	s_waitcnt lgkmcnt(0)
	v_pk_add_f32 v[24:25], v[24:25], v[56:57]
	v_pk_add_f32 v[26:27], v[26:27], v[58:59]
	global_store_dwordx4 v[52:53], v[24:27], off
	v_cvt_pk_bf16_f32 v52, v24, v25
	v_cvt_pk_bf16_f32 v53, v26, v27
	v_pk_mul_f32 v[24:25], v[24:25], v[24:25]
	v_pk_mul_f32 v[26:27], v[26:27], v[26:27]
	v_add_f32_e32 v24, v24, v25
	v_add_f32_e32 v24, v24, v26
	v_add_f32_e32 v24, v24, v27
	flat_store_dwordx2 v[54:55], v[52:53]
	s_nop 0
	v_add_f32_dpp v24, v24, v24 row_ror:8 row_mask:0xf bank_mask:0xf bound_ctrl:1
	s_nop 1
	v_add_f32_dpp v24, v24, v24 row_ror:4 row_mask:0xf bank_mask:0xf bound_ctrl:1
	s_nop 1
	v_add_f32_dpp v24, v24, v24 row_ror:2 row_mask:0xf bank_mask:0xf bound_ctrl:1
	s_nop 1
	v_add_f32_dpp v24, v24, v24 row_ror:1 row_mask:0xf bank_mask:0xf bound_ctrl:1
	s_nop 0
	v_readlane_b32 s9, v24, 0
	v_readlane_b32 s67, v24, 16
	v_readlane_b32 s34, v24, 32
	v_readlane_b32 s35, v24, 48
	s_and_saveexec_b64 s[30:31], vcc
	s_cbranch_execz .LBB0_1705
	s_lshl_b64 s[22:23], s[22:23], 2
	v_mov_b32_e32 v24, s67
	s_add_u32 s22, s63, s22
	v_add_f32_e32 v24, s9, v24
	s_addc_u32 s23, s64, s23
	v_add_f32_e32 v24, s34, v24
	v_add_f32_e32 v26, s35, v24
	v_mov_b64_e32 v[24:25], s[22:23]
	flat_atomic_add_f32 v[24:25], v26
; DEVI float fsig(float x) { return __builtin_amdgcn_rcpf(1.f + __expf(-x)); }
; DEVI float bflo(unsigned u) { return __uint_as_float(u << 16); }
; DEVI float bfhi(unsigned u) { return __uint_as_float(u & 0xffff0000u); }
; template <int EPI, int TS, bool VT>
; DEVI void gemm_epilogue(const Params& p, char* smem, f32x4 (&acc)[2][2][4][2], int m0, int n0, float scale, const float* ssin,
;                         float* ssout, u16* xbout, int wid, int lane, int wr, int wc, int fr, int fq) {
;     ...
;         for (int u = 0; u < 8; ++u) {
;           const int i = i0 + u;
;           const int grow = g0 + i;
;           const float* Tr = T + (r0 + i) * TS;
;           const float rs = __int_as_float(__builtin_amdgcn_readlane(__float_as_int(rsv), i));
;           if constexpr (EPI == E_RESID || EPI == E_PLEGATE) {
;             const float4 a = *(const float4*)(Tr + 4 * lane);
;             const size_t ro = (size_t)grow * 1024 + n0 + 4 * lane;
;             float4 x4 = xo[u];
;             if constexpr (EPI == E_PLEGATE) {
;               x4.x += bflo(pv[u].x) * fsig(a.x * rs);
;               x4.y += bfhi(pv[u].x) * fsig(a.y * rs);
;               x4.z += bflo(pv[u].y) * fsig(a.z * rs);
;               x4.w += bfhi(pv[u].y) * fsig(a.w * rs);
;             } else {
;               const float sc = fabsf(scale);
;               x4.x += sc * a.x; x4.y += sc * a.y; x4.z += sc * a.z; x4.w += sc * a.w;
;             }
;             st_nt16(p.x + ro, x4);
;             if (xbout) {
;               uint2 o;
;               o.x = pack2(x4.x, x4.y);
;               o.y = pack2(x4.z, x4.w);
;               st_nt8(xbout + ro, o);
;             }
;             if (ssout) {
;               const float ssq = wsum(x4.x * x4.x + x4.y * x4.y + x4.z * x4.z + x4.w * x4.w, lane);
;               if (lane == 0) atomicAdd(ssout + grow, ssq);
;             }
.LBB0_1705:
	s_or_b64 exec, exec, s[30:31]
	ds_read_b128 v[24:27], v120 offset:2080
	v_lshl_add_u64 v[50:51], v[50:51], 1, s[4:5]
	s_waitcnt lgkmcnt(0)
	v_pk_add_f32 v[20:21], v[20:21], v[24:25]
	v_pk_add_f32 v[22:23], v[22:23], v[26:27]
	global_store_dwordx4 v[48:49], v[20:23], off
	v_cvt_pk_bf16_f32 v24, v20, v21
	v_cvt_pk_bf16_f32 v25, v22, v23
	v_pk_mul_f32 v[20:21], v[20:21], v[20:21]
	v_pk_mul_f32 v[22:23], v[22:23], v[22:23]
	v_add_f32_e32 v20, v20, v21
	v_add_f32_e32 v20, v20, v22
	v_add_f32_e32 v20, v20, v23
	flat_store_dwordx2 v[50:51], v[24:25]
	s_nop 0
	v_add_f32_dpp v20, v20, v20 row_ror:8 row_mask:0xf bank_mask:0xf bound_ctrl:1
	s_nop 1
	v_add_f32_dpp v20, v20, v20 row_ror:4 row_mask:0xf bank_mask:0xf bound_ctrl:1
	s_nop 1
	v_add_f32_dpp v20, v20, v20 row_ror:2 row_mask:0xf bank_mask:0xf bound_ctrl:1
	s_nop 1
	v_add_f32_dpp v20, v20, v20 row_ror:1 row_mask:0xf bank_mask:0xf bound_ctrl:1
	s_nop 0
	v_readlane_b32 s9, v20, 0
	v_readlane_b32 s34, v20, 16
	v_readlane_b32 s30, v20, 32
	v_readlane_b32 s31, v20, 48
	s_and_saveexec_b64 s[22:23], vcc
	s_cbranch_execz .LBB0_1707
	s_lshl_b64 s[20:21], s[20:21], 2
	v_mov_b32_e32 v20, s34
	s_add_u32 s20, s63, s20
	v_add_f32_e32 v20, s9, v20
	s_addc_u32 s21, s64, s21
	v_add_f32_e32 v20, s30, v20
	v_add_f32_e32 v22, s31, v20
	v_mov_b64_e32 v[20:21], s[20:21]
	flat_atomic_add_f32 v[20:21], v22
.LBB0_1707:
	s_or_b64 exec, exec, s[22:23]
	ds_read_b128 v[20:23], v120 offset:3120
	v_lshl_add_u64 v[24:25], v[46:47], 1, s[4:5]
	s_waitcnt lgkmcnt(0)
	v_pk_add_f32 v[16:17], v[16:17], v[20:21]
	v_pk_add_f32 v[18:19], v[18:19], v[22:23]
	global_store_dwordx4 v[44:45], v[16:19], off
	v_cvt_pk_bf16_f32 v20, v16, v17
	v_cvt_pk_bf16_f32 v21, v18, v19
	v_pk_mul_f32 v[16:17], v[16:17], v[16:17]
	v_pk_mul_f32 v[18:19], v[18:19], v[18:19]
	v_add_f32_e32 v16, v16, v17
	v_add_f32_e32 v16, v16, v18
	v_add_f32_e32 v16, v16, v19
	flat_store_dwordx2 v[24:25], v[20:21]
	s_nop 0
	v_add_f32_dpp v16, v16, v16 row_ror:8 row_mask:0xf bank_mask:0xf bound_ctrl:1
	s_nop 1
	v_add_f32_dpp v16, v16, v16 row_ror:4 row_mask:0xf bank_mask:0xf bound_ctrl:1
	s_nop 1
	v_add_f32_dpp v16, v16, v16 row_ror:2 row_mask:0xf bank_mask:0xf bound_ctrl:1
	s_nop 1
	v_add_f32_dpp v16, v16, v16 row_ror:1 row_mask:0xf bank_mask:0xf bound_ctrl:1
	s_nop 0
	v_readlane_b32 s9, v16, 0
	v_readlane_b32 s30, v16, 16
	v_readlane_b32 s22, v16, 32
	v_readlane_b32 s23, v16, 48
	s_and_saveexec_b64 s[20:21], vcc
	s_cbranch_execz .LBB0_1709
	s_lshl_b64 s[18:19], s[18:19], 2
	v_mov_b32_e32 v16, s30
	s_add_u32 s18, s63, s18
	v_add_f32_e32 v16, s9, v16
	s_addc_u32 s19, s64, s19
	v_add_f32_e32 v16, s22, v16
	v_add_f32_e32 v18, s23, v16
	v_mov_b64_e32 v[16:17], s[18:19]
	flat_atomic_add_f32 v[16:17], v18
.LBB0_1709:
	s_or_b64 exec, exec, s[20:21]
	ds_read_b128 v[16:19], v120 offset:4160
	v_lshl_add_u64 v[20:21], v[42:43], 1, s[4:5]
	s_waitcnt lgkmcnt(0)
	v_pk_add_f32 v[12:13], v[12:13], v[16:17]
	v_pk_add_f32 v[14:15], v[14:15], v[18:19]
	global_store_dwordx4 v[40:41], v[12:15], off
	v_cvt_pk_bf16_f32 v16, v12, v13
	v_cvt_pk_bf16_f32 v17, v14, v15
	v_pk_mul_f32 v[12:13], v[12:13], v[12:13]
	v_pk_mul_f32 v[14:15], v[14:15], v[14:15]
	v_add_f32_e32 v12, v12, v13
	v_add_f32_e32 v12, v12, v14
	v_add_f32_e32 v12, v12, v15
	flat_store_dwordx2 v[20:21], v[16:17]
	s_nop 0
	v_add_f32_dpp v12, v12, v12 row_ror:8 row_mask:0xf bank_mask:0xf bound_ctrl:1
	s_nop 1
	v_add_f32_dpp v12, v12, v12 row_ror:4 row_mask:0xf bank_mask:0xf bound_ctrl:1
	s_nop 1
	v_add_f32_dpp v12, v12, v12 row_ror:2 row_mask:0xf bank_mask:0xf bound_ctrl:1
	s_nop 1
	v_add_f32_dpp v12, v12, v12 row_ror:1 row_mask:0xf bank_mask:0xf bound_ctrl:1
	s_nop 0
	v_readlane_b32 s9, v12, 0
	v_readlane_b32 s22, v12, 16
	v_readlane_b32 s20, v12, 32
	v_readlane_b32 s21, v12, 48
	s_and_saveexec_b64 s[18:19], vcc
	s_cbranch_execz .LBB0_1711
	s_lshl_b64 s[16:17], s[16:17], 2
	v_mov_b32_e32 v12, s22
	s_add_u32 s16, s63, s16
	v_add_f32_e32 v12, s9, v12
	s_addc_u32 s17, s64, s17
	v_add_f32_e32 v12, s20, v12
	v_add_f32_e32 v14, s21, v12
	v_mov_b64_e32 v[12:13], s[16:17]
	flat_atomic_add_f32 v[12:13], v14
.LBB0_1711:
	s_or_b64 exec, exec, s[18:19]
	ds_read_b128 v[12:15], v120 offset:5200
	v_lshl_add_u64 v[16:17], v[38:39], 1, s[4:5]
	s_waitcnt lgkmcnt(0)
	v_pk_add_f32 v[8:9], v[8:9], v[12:13]
	v_pk_add_f32 v[10:11], v[10:11], v[14:15]
	global_store_dwordx4 v[36:37], v[8:11], off
	v_cvt_pk_bf16_f32 v12, v8, v9
	v_cvt_pk_bf16_f32 v13, v10, v11
	v_pk_mul_f32 v[8:9], v[8:9], v[8:9]
	v_pk_mul_f32 v[10:11], v[10:11], v[10:11]
	v_add_f32_e32 v8, v8, v9
	v_add_f32_e32 v8, v8, v10
	v_add_f32_e32 v8, v8, v11
	flat_store_dwordx2 v[16:17], v[12:13]
	s_nop 0
	v_add_f32_dpp v8, v8, v8 row_ror:8 row_mask:0xf bank_mask:0xf bound_ctrl:1
	s_nop 1
	v_add_f32_dpp v8, v8, v8 row_ror:4 row_mask:0xf bank_mask:0xf bound_ctrl:1
	s_nop 1
	v_add_f32_dpp v8, v8, v8 row_ror:2 row_mask:0xf bank_mask:0xf bound_ctrl:1
	s_nop 1
	v_add_f32_dpp v8, v8, v8 row_ror:1 row_mask:0xf bank_mask:0xf bound_ctrl:1
	s_nop 0
	v_readlane_b32 s9, v8, 0
	v_readlane_b32 s20, v8, 16
	v_readlane_b32 s18, v8, 32
	v_readlane_b32 s19, v8, 48
	s_and_saveexec_b64 s[16:17], vcc
	s_cbranch_execz .LBB0_1713
	s_lshl_b64 s[14:15], s[14:15], 2
	v_mov_b32_e32 v8, s20
	s_add_u32 s14, s63, s14
	v_add_f32_e32 v8, s9, v8
	s_addc_u32 s15, s64, s15
	v_add_f32_e32 v8, s18, v8
	v_add_f32_e32 v10, s19, v8
	v_mov_b64_e32 v[8:9], s[14:15]
	flat_atomic_add_f32 v[8:9], v10
; template <int EPI, int TS, bool VT>
; DEVI void gemm_epilogue(const Params& p, char* smem, f32x4 (&acc)[2][2][4][2], int m0, int n0, float scale, const float* ssin,
;                         float* ssout, u16* xbout, int wid, int lane, int wr, int wc, int fr, int fq) {
;     ...
;             const size_t ro = (size_t)(g0 + i0 + u) * 1024 + n0 + 4 * lane;
;             const int gr = g0 + i0 + u;
;             const float* xs = p.x + ro;
;             if (scale < 0.f)
;               xs = (gr < MP ? p.x_prompt + ro : p.x_sample + (ro - (size_t)MP * 1024));
;             { const f32x4 t_ = __builtin_nontemporal_load((const f32x4*)xs); xo[u] = make_float4(t_[0], t_[1], t_[2], t_[3]); }
;             if constexpr (EPI == E_PLEGATE) {
;               const unsigned long long t2_ = __builtin_nontemporal_load((const unsigned long long*)((const u16*)(wsb + OFF_PP) + ro));
;               pv[u] = make_uint2((unsigned)t2_, (unsigned)(t2_ >> 32));
;             }
;           }
;         }
; #pragma unroll
;         for (int u = 0; u < 8; ++u) {
;           const int i = i0 + u;
;           const int grow = g0 + i;
;           const float* Tr = T + (r0 + i) * TS;
;           const float rs = __int_as_float(__builtin_amdgcn_readlane(__float_as_int(rsv), i));
;           if constexpr (EPI == E_RESID || EPI == E_PLEGATE) {
;             const float4 a = *(const float4*)(Tr + 4 * lane);
;             const size_t ro = (size_t)grow * 1024 + n0 + 4 * lane;
;             float4 x4 = xo[u];
;             if constexpr (EPI == E_PLEGATE) {
;               x4.x += bflo(pv[u].x) * fsig(a.x * rs);
;               x4.y += bfhi(pv[u].x) * fsig(a.y * rs);
;               x4.z += bflo(pv[u].y) * fsig(a.z * rs);
;               x4.w += bfhi(pv[u].y) * fsig(a.w * rs);
;             } else {
;               const float sc = fabsf(scale);
;               x4.x += sc * a.x; x4.y += sc * a.y; x4.z += sc * a.z; x4.w += sc * a.w;
;             }
;             st_nt16(p.x + ro, x4);
;             if (xbout) {
;               uint2 o;
;               o.x = pack2(x4.x, x4.y);
;               o.y = pack2(x4.z, x4.w);
;               st_nt8(xbout + ro, o);
;             }
;             if (ssout) {
;               const float ssq = wsum(x4.x * x4.x + x4.y * x4.y + x4.z * x4.z + x4.w * x4.w, lane);
;               if (lane == 0) atomicAdd(ssout + grow, ssq);
;             }
.LBB0_1713:
	s_or_b64 exec, exec, s[16:17]
	ds_read_b128 v[8:11], v120 offset:6240
	v_lshl_add_u64 v[12:13], v[34:35], 1, s[4:5]
	s_waitcnt lgkmcnt(0)
	v_pk_add_f32 v[4:5], v[4:5], v[8:9]
	v_pk_add_f32 v[6:7], v[6:7], v[10:11]
	global_store_dwordx4 v[32:33], v[4:7], off
	v_cvt_pk_bf16_f32 v8, v4, v5
	v_cvt_pk_bf16_f32 v9, v6, v7
	v_pk_mul_f32 v[4:5], v[4:5], v[4:5]
	v_pk_mul_f32 v[6:7], v[6:7], v[6:7]
	v_add_f32_e32 v4, v4, v5
	v_add_f32_e32 v4, v4, v6
	v_add_f32_e32 v4, v4, v7
	flat_store_dwordx2 v[12:13], v[8:9]
	s_nop 0
	v_add_f32_dpp v4, v4, v4 row_ror:8 row_mask:0xf bank_mask:0xf bound_ctrl:1
	s_nop 1
	v_add_f32_dpp v4, v4, v4 row_ror:4 row_mask:0xf bank_mask:0xf bound_ctrl:1
	s_nop 1
	v_add_f32_dpp v4, v4, v4 row_ror:2 row_mask:0xf bank_mask:0xf bound_ctrl:1
	s_nop 1
	v_add_f32_dpp v4, v4, v4 row_ror:1 row_mask:0xf bank_mask:0xf bound_ctrl:1
	s_nop 0
	v_readlane_b32 s9, v4, 0
	v_readlane_b32 s18, v4, 16
	v_readlane_b32 s16, v4, 32
	v_readlane_b32 s17, v4, 48
	s_and_saveexec_b64 s[14:15], vcc
	s_cbranch_execz .LBB0_1715
	s_lshl_b64 s[12:13], s[12:13], 2
	v_mov_b32_e32 v4, s18
	s_add_u32 s12, s63, s12
	v_add_f32_e32 v4, s9, v4
	s_addc_u32 s13, s64, s13
	v_add_f32_e32 v4, s16, v4
	v_add_f32_e32 v6, s17, v4
	v_mov_b64_e32 v[4:5], s[12:13]
	flat_atomic_add_f32 v[4:5], v6
.LBB0_1715:
	s_or_b64 exec, exec, s[14:15]
	ds_read_b128 v[4:7], v120 offset:7280
	v_lshl_add_u64 v[8:9], v[30:31], 1, s[4:5]
	s_waitcnt lgkmcnt(0)
	v_pk_add_f32 v[0:1], v[0:1], v[4:5]
	v_pk_add_f32 v[2:3], v[2:3], v[6:7]
	global_store_dwordx4 v[28:29], v[0:3], off
	v_cvt_pk_bf16_f32 v4, v0, v1
	v_cvt_pk_bf16_f32 v5, v2, v3
	v_pk_mul_f32 v[0:1], v[0:1], v[0:1]
	v_pk_mul_f32 v[2:3], v[2:3], v[2:3]
	v_add_f32_e32 v0, v0, v1
	v_add_f32_e32 v0, v0, v2
	v_add_f32_e32 v0, v0, v3
	flat_store_dwordx2 v[8:9], v[4:5]
	s_nop 0
	v_add_f32_dpp v0, v0, v0 row_ror:8 row_mask:0xf bank_mask:0xf bound_ctrl:1
	s_nop 1
	v_add_f32_dpp v0, v0, v0 row_ror:4 row_mask:0xf bank_mask:0xf bound_ctrl:1
	s_nop 1
	v_add_f32_dpp v0, v0, v0 row_ror:2 row_mask:0xf bank_mask:0xf bound_ctrl:1
	s_nop 1
	v_add_f32_dpp v0, v0, v0 row_ror:1 row_mask:0xf bank_mask:0xf bound_ctrl:1
	s_nop 0
	v_readlane_b32 s9, v0, 0
	v_readlane_b32 s16, v0, 16
	v_readlane_b32 s14, v0, 32
	v_readlane_b32 s15, v0, 48
	s_and_saveexec_b64 s[12:13], vcc
	s_cbranch_execz .LBB0_1717
	s_lshl_b64 s[10:11], s[10:11], 2
	v_mov_b32_e32 v0, s16
	s_add_u32 s10, s63, s10
	v_add_f32_e32 v0, s9, v0
	s_addc_u32 s11, s64, s11
	v_add_f32_e32 v0, s14, v0
	v_add_f32_e32 v2, s15, v0
	v_mov_b64_e32 v[0:1], s[10:11]
	flat_atomic_add_f32 v[0:1], v2
.LBB0_1717:
	s_or_b64 exec, exec, s[12:13]
	s_add_i32 s22, s8, 0x88
	s_ashr_i32 s23, s22, 31
	s_lshl_b64 s[10:11], s[22:23], 10
	s_add_i32 s20, s8, 0x89
	v_lshl_add_u64 v[64:65], s[10:11], 0, v[128:129]
	s_ashr_i32 s21, s20, 31
	s_add_i32 s18, s8, 0x8a
	v_lshl_add_u64 v[66:67], v[64:65], 2, s[38:39]
	s_lshl_b64 s[10:11], s[20:21], 10
	s_ashr_i32 s19, s18, 31
	s_add_i32 s16, s8, 0x8b
	global_load_dwordx4 v[56:59], v[66:67], off
	v_lshl_add_u64 v[54:55], s[10:11], 0, v[128:129]
	s_lshl_b64 s[10:11], s[18:19], 10
	s_ashr_i32 s17, s16, 31
	s_add_i32 s14, s8, 0x8c
	v_lshl_add_u64 v[50:51], s[10:11], 0, v[128:129]
	s_lshl_b64 s[10:11], s[16:17], 10
	s_ashr_i32 s15, s14, 31
	s_add_i32 s12, s8, 0x8d
	v_lshl_add_u64 v[46:47], s[10:11], 0, v[128:129]
	s_lshl_b64 s[10:11], s[14:15], 10
	s_ashr_i32 s13, s12, 31
	v_lshl_add_u64 v[42:43], s[10:11], 0, v[128:129]
	s_lshl_b64 s[10:11], s[12:13], 10
	v_lshl_add_u64 v[38:39], s[10:11], 0, v[128:129]
	s_add_i32 s10, s8, 0x8e
	s_ashr_i32 s11, s10, 31
	s_addk_i32 s8, 0x8f
	s_lshl_b64 s[30:31], s[10:11], 10
	s_ashr_i32 s9, s8, 31
	v_lshl_add_u64 v[34:35], s[30:31], 0, v[128:129]
	s_lshl_b64 s[30:31], s[8:9], 10
	v_lshl_add_u64 v[30:31], s[30:31], 0, v[128:129]
	v_lshl_add_u64 v[52:53], v[54:55], 2, s[38:39]
	v_lshl_add_u64 v[44:45], v[46:47], 2, s[38:39]
	v_lshl_add_u64 v[36:37], v[38:39], 2, s[38:39]
	v_lshl_add_u64 v[28:29], v[30:31], 2, s[38:39]
	v_lshl_add_u64 v[48:49], v[50:51], 2, s[38:39]
	global_load_dwordx4 v[24:27], v[52:53], off
	global_load_dwordx4 v[20:23], v[48:49], off
	v_lshl_add_u64 v[40:41], v[42:43], 2, s[38:39]
	global_load_dwordx4 v[16:19], v[44:45], off
	global_load_dwordx4 v[12:15], v[40:41], off
	v_lshl_add_u64 v[32:33], v[34:35], 2, s[38:39]
	global_load_dwordx4 v[8:11], v[36:37], off
	global_load_dwordx4 v[4:7], v[32:33], off
	global_load_dwordx4 v[0:3], v[28:29], off
	ds_read_b128 v[60:63], v120 offset:8320
	v_lshl_add_u64 v[64:65], v[64:65], 1, s[4:5]
	s_waitcnt vmcnt(0) lgkmcnt(0)
	v_pk_add_f32 v[56:57], v[56:57], v[60:61]
	v_pk_add_f32 v[58:59], v[58:59], v[62:63]
	global_store_dwordx4 v[66:67], v[56:59], off
	v_cvt_pk_bf16_f32 v60, v56, v57
	v_cvt_pk_bf16_f32 v61, v58, v59
	v_pk_mul_f32 v[56:57], v[56:57], v[56:57]
	v_pk_mul_f32 v[58:59], v[58:59], v[58:59]
	v_add_f32_e32 v56, v56, v57
	v_add_f32_e32 v56, v56, v58
	v_add_f32_e32 v56, v56, v59
	flat_store_dwordx2 v[64:65], v[60:61]
	s_nop 0
	v_add_f32_dpp v56, v56, v56 row_ror:8 row_mask:0xf bank_mask:0xf bound_ctrl:1
	s_nop 1
	v_add_f32_dpp v56, v56, v56 row_ror:4 row_mask:0xf bank_mask:0xf bound_ctrl:1
	s_nop 1
	v_add_f32_dpp v56, v56, v56 row_ror:2 row_mask:0xf bank_mask:0xf bound_ctrl:1
	s_nop 1
	v_add_f32_dpp v56, v56, v56 row_ror:1 row_mask:0xf bank_mask:0xf bound_ctrl:1
	s_nop 0
	v_readlane_b32 s34, v56, 0
	v_readlane_b32 s68, v56, 16
	v_readlane_b32 s35, v56, 32
	v_readlane_b32 s67, v56, 48
	s_and_saveexec_b64 s[30:31], vcc
	s_cbranch_execz .LBB0_1719
	s_lshl_b64 s[22:23], s[22:23], 2
	v_mov_b32_e32 v56, s68
	s_add_u32 s22, s63, s22
	v_add_f32_e32 v56, s34, v56
	s_addc_u32 s23, s64, s23
	v_add_f32_e32 v56, s35, v56
	v_add_f32_e32 v58, s67, v56
	v_mov_b64_e32 v[56:57], s[22:23]
	flat_atomic_add_f32 v[56:57], v58
; DEVI float fsig(float x) { return __builtin_amdgcn_rcpf(1.f + __expf(-x)); }
; DEVI float bflo(unsigned u) { return __uint_as_float(u << 16); }
; DEVI float bfhi(unsigned u) { return __uint_as_float(u & 0xffff0000u); }
; template <int EPI, int TS, bool VT>
; DEVI void gemm_epilogue(const Params& p, char* smem, f32x4 (&acc)[2][2][4][2], int m0, int n0, float scale, const float* ssin,
;                         float* ssout, u16* xbout, int wid, int lane, int wr, int wc, int fr, int fq) {
;     ...
;         for (int u = 0; u < 8; ++u) {
;           const int i = i0 + u;
;           const int grow = g0 + i;
;           const float* Tr = T + (r0 + i) * TS;
;           const float rs = __int_as_float(__builtin_amdgcn_readlane(__float_as_int(rsv), i));
;           if constexpr (EPI == E_RESID || EPI == E_PLEGATE) {
;             const float4 a = *(const float4*)(Tr + 4 * lane);
;             const size_t ro = (size_t)grow * 1024 + n0 + 4 * lane;
;             float4 x4 = xo[u];
;             if constexpr (EPI == E_PLEGATE) {
;               x4.x += bflo(pv[u].x) * fsig(a.x * rs);
;               x4.y += bfhi(pv[u].x) * fsig(a.y * rs);
;               x4.z += bflo(pv[u].y) * fsig(a.z * rs);
;               x4.w += bfhi(pv[u].y) * fsig(a.w * rs);
;             } else {
;               const float sc = fabsf(scale);
;               x4.x += sc * a.x; x4.y += sc * a.y; x4.z += sc * a.z; x4.w += sc * a.w;
;             }
;             st_nt16(p.x + ro, x4);
;             if (xbout) {
;               uint2 o;
;               o.x = pack2(x4.x, x4.y);
;               o.y = pack2(x4.z, x4.w);
;               st_nt8(xbout + ro, o);
;             }
;             if (ssout) {
;               const float ssq = wsum(x4.x * x4.x + x4.y * x4.y + x4.z * x4.z + x4.w * x4.w, lane);
;               if (lane == 0) atomicAdd(ssout + grow, ssq);
;             }
.LBB0_1719:
	s_or_b64 exec, exec, s[30:31]
	ds_read_b128 v[56:59], v120 offset:9360
	v_lshl_add_u64 v[54:55], v[54:55], 1, s[4:5]
	s_waitcnt lgkmcnt(0)
	v_pk_add_f32 v[24:25], v[24:25], v[56:57]
	v_pk_add_f32 v[26:27], v[26:27], v[58:59]
	global_store_dwordx4 v[52:53], v[24:27], off
	v_cvt_pk_bf16_f32 v52, v24, v25
	v_cvt_pk_bf16_f32 v53, v26, v27
	v_pk_mul_f32 v[24:25], v[24:25], v[24:25]
	v_pk_mul_f32 v[26:27], v[26:27], v[26:27]
	v_add_f32_e32 v24, v24, v25
	v_add_f32_e32 v24, v24, v26
	v_add_f32_e32 v24, v24, v27
	flat_store_dwordx2 v[54:55], v[52:53]
	s_nop 0
	v_add_f32_dpp v24, v24, v24 row_ror:8 row_mask:0xf bank_mask:0xf bound_ctrl:1
	s_nop 1
	v_add_f32_dpp v24, v24, v24 row_ror:4 row_mask:0xf bank_mask:0xf bound_ctrl:1
	s_nop 1
	v_add_f32_dpp v24, v24, v24 row_ror:2 row_mask:0xf bank_mask:0xf bound_ctrl:1
	s_nop 1
	v_add_f32_dpp v24, v24, v24 row_ror:1 row_mask:0xf bank_mask:0xf bound_ctrl:1
	s_nop 0
	v_readlane_b32 s30, v24, 0
	v_readlane_b32 s35, v24, 16
	v_readlane_b32 s31, v24, 32
	v_readlane_b32 s34, v24, 48
	s_and_saveexec_b64 s[22:23], vcc
	s_cbranch_execz .LBB0_1721
	s_lshl_b64 s[20:21], s[20:21], 2
	v_mov_b32_e32 v24, s35
	s_add_u32 s20, s63, s20
	v_add_f32_e32 v24, s30, v24
	s_addc_u32 s21, s64, s21
	v_add_f32_e32 v24, s31, v24
	v_add_f32_e32 v26, s34, v24
	v_mov_b64_e32 v[24:25], s[20:21]
	flat_atomic_add_f32 v[24:25], v26
.LBB0_1721:
	s_or_b64 exec, exec, s[22:23]
	ds_read_b128 v[24:27], v120 offset:10400
	v_lshl_add_u64 v[50:51], v[50:51], 1, s[4:5]
	s_waitcnt lgkmcnt(0)
	v_pk_add_f32 v[20:21], v[20:21], v[24:25]
	v_pk_add_f32 v[22:23], v[22:23], v[26:27]
	global_store_dwordx4 v[48:49], v[20:23], off
	v_cvt_pk_bf16_f32 v24, v20, v21
	v_cvt_pk_bf16_f32 v25, v22, v23
	v_pk_mul_f32 v[20:21], v[20:21], v[20:21]
	v_pk_mul_f32 v[22:23], v[22:23], v[22:23]
	v_add_f32_e32 v20, v20, v21
	v_add_f32_e32 v20, v20, v22
	v_add_f32_e32 v20, v20, v23
	flat_store_dwordx2 v[50:51], v[24:25]
	s_nop 0
	v_add_f32_dpp v20, v20, v20 row_ror:8 row_mask:0xf bank_mask:0xf bound_ctrl:1
	s_nop 1
	v_add_f32_dpp v20, v20, v20 row_ror:4 row_mask:0xf bank_mask:0xf bound_ctrl:1
	s_nop 1
	v_add_f32_dpp v20, v20, v20 row_ror:2 row_mask:0xf bank_mask:0xf bound_ctrl:1
	s_nop 1
	v_add_f32_dpp v20, v20, v20 row_ror:1 row_mask:0xf bank_mask:0xf bound_ctrl:1
	s_nop 0
	v_readlane_b32 s22, v20, 0
	v_readlane_b32 s31, v20, 16
	v_readlane_b32 s23, v20, 32
	v_readlane_b32 s30, v20, 48
	s_and_saveexec_b64 s[20:21], vcc
	s_cbranch_execz .LBB0_1723
	s_lshl_b64 s[18:19], s[18:19], 2
	v_mov_b32_e32 v20, s31
	s_add_u32 s18, s63, s18
	v_add_f32_e32 v20, s22, v20
	s_addc_u32 s19, s64, s19
	v_add_f32_e32 v20, s23, v20
	v_add_f32_e32 v22, s30, v20
	v_mov_b64_e32 v[20:21], s[18:19]
	flat_atomic_add_f32 v[20:21], v22
.LBB0_1723:
	s_or_b64 exec, exec, s[20:21]
	ds_read_b128 v[20:23], v120 offset:11440
	v_lshl_add_u64 v[24:25], v[46:47], 1, s[4:5]
	s_waitcnt lgkmcnt(0)
	v_pk_add_f32 v[16:17], v[16:17], v[20:21]
	v_pk_add_f32 v[18:19], v[18:19], v[22:23]
	global_store_dwordx4 v[44:45], v[16:19], off
	v_cvt_pk_bf16_f32 v20, v16, v17
	v_cvt_pk_bf16_f32 v21, v18, v19
	v_pk_mul_f32 v[16:17], v[16:17], v[16:17]
	v_pk_mul_f32 v[18:19], v[18:19], v[18:19]
	v_add_f32_e32 v16, v16, v17
	v_add_f32_e32 v16, v16, v18
	v_add_f32_e32 v16, v16, v19
	flat_store_dwordx2 v[24:25], v[20:21]
	s_nop 0
	v_add_f32_dpp v16, v16, v16 row_ror:8 row_mask:0xf bank_mask:0xf bound_ctrl:1
	s_nop 1
	v_add_f32_dpp v16, v16, v16 row_ror:4 row_mask:0xf bank_mask:0xf bound_ctrl:1
	s_nop 1
	v_add_f32_dpp v16, v16, v16 row_ror:2 row_mask:0xf bank_mask:0xf bound_ctrl:1
	s_nop 1
	v_add_f32_dpp v16, v16, v16 row_ror:1 row_mask:0xf bank_mask:0xf bound_ctrl:1
	s_nop 0
	v_readlane_b32 s20, v16, 0
	v_readlane_b32 s23, v16, 16
	v_readlane_b32 s21, v16, 32
	v_readlane_b32 s22, v16, 48
	s_and_saveexec_b64 s[18:19], vcc
	s_cbranch_execz .LBB0_1725
	s_lshl_b64 s[16:17], s[16:17], 2
	v_mov_b32_e32 v16, s23
	s_add_u32 s16, s63, s16
	v_add_f32_e32 v16, s20, v16
	s_addc_u32 s17, s64, s17
	v_add_f32_e32 v16, s21, v16
	v_add_f32_e32 v18, s22, v16
	v_mov_b64_e32 v[16:17], s[16:17]
	flat_atomic_add_f32 v[16:17], v18
; DEVI float fsig(float x) { return __builtin_amdgcn_rcpf(1.f + __expf(-x)); }
; DEVI float bflo(unsigned u) { return __uint_as_float(u << 16); }
; DEVI float bfhi(unsigned u) { return __uint_as_float(u & 0xffff0000u); }
; template <int EPI, int TS, bool VT>
; DEVI void gemm_epilogue(const Params& p, char* smem, f32x4 (&acc)[2][2][4][2], int m0, int n0, float scale, const float* ssin,
;                         float* ssout, u16* xbout, int wid, int lane, int wr, int wc, int fr, int fq) {
;     ...
;         for (int u = 0; u < 8; ++u) {
;           const int i = i0 + u;
;           const int grow = g0 + i;
;           const float* Tr = T + (r0 + i) * TS;
;           const float rs = __int_as_float(__builtin_amdgcn_readlane(__float_as_int(rsv), i));
;           if constexpr (EPI == E_RESID || EPI == E_PLEGATE) {
;             const float4 a = *(const float4*)(Tr + 4 * lane);
;             const size_t ro = (size_t)grow * 1024 + n0 + 4 * lane;
;             float4 x4 = xo[u];
;             if constexpr (EPI == E_PLEGATE) {
;               x4.x += bflo(pv[u].x) * fsig(a.x * rs);
;               x4.y += bfhi(pv[u].x) * fsig(a.y * rs);
;               x4.z += bflo(pv[u].y) * fsig(a.z * rs);
;               x4.w += bfhi(pv[u].y) * fsig(a.w * rs);
;             } else {
;               const float sc = fabsf(scale);
;               x4.x += sc * a.x; x4.y += sc * a.y; x4.z += sc * a.z; x4.w += sc * a.w;
;             }
;             st_nt16(p.x + ro, x4);
;             if (xbout) {
;               uint2 o;
;               o.x = pack2(x4.x, x4.y);
;               o.y = pack2(x4.z, x4.w);
;               st_nt8(xbout + ro, o);
;             }
;             if (ssout) {
;               const float ssq = wsum(x4.x * x4.x + x4.y * x4.y + x4.z * x4.z + x4.w * x4.w, lane);
;               if (lane == 0) atomicAdd(ssout + grow, ssq);
;             }
.LBB0_1725:
	s_or_b64 exec, exec, s[18:19]
	ds_read_b128 v[16:19], v120 offset:12480
	v_lshl_add_u64 v[20:21], v[42:43], 1, s[4:5]
	s_waitcnt lgkmcnt(0)
	v_pk_add_f32 v[12:13], v[12:13], v[16:17]
	v_pk_add_f32 v[14:15], v[14:15], v[18:19]
	global_store_dwordx4 v[40:41], v[12:15], off
	v_cvt_pk_bf16_f32 v16, v12, v13
	v_cvt_pk_bf16_f32 v17, v14, v15
	v_pk_mul_f32 v[12:13], v[12:13], v[12:13]
	v_pk_mul_f32 v[14:15], v[14:15], v[14:15]
	v_add_f32_e32 v12, v12, v13
	v_add_f32_e32 v12, v12, v14
	v_add_f32_e32 v12, v12, v15
	flat_store_dwordx2 v[20:21], v[16:17]
	s_nop 0
	v_add_f32_dpp v12, v12, v12 row_ror:8 row_mask:0xf bank_mask:0xf bound_ctrl:1
	s_nop 1
	v_add_f32_dpp v12, v12, v12 row_ror:4 row_mask:0xf bank_mask:0xf bound_ctrl:1
	s_nop 1
	v_add_f32_dpp v12, v12, v12 row_ror:2 row_mask:0xf bank_mask:0xf bound_ctrl:1
	s_nop 1
	v_add_f32_dpp v12, v12, v12 row_ror:1 row_mask:0xf bank_mask:0xf bound_ctrl:1
	s_nop 0
	v_readlane_b32 s18, v12, 0
	v_readlane_b32 s21, v12, 16
	v_readlane_b32 s19, v12, 32
	v_readlane_b32 s20, v12, 48
	s_and_saveexec_b64 s[16:17], vcc
	s_cbranch_execz .LBB0_1727
	s_lshl_b64 s[14:15], s[14:15], 2
	v_mov_b32_e32 v12, s21
	s_add_u32 s14, s63, s14
	v_add_f32_e32 v12, s18, v12
	s_addc_u32 s15, s64, s15
	v_add_f32_e32 v12, s19, v12
	v_add_f32_e32 v14, s20, v12
	v_mov_b64_e32 v[12:13], s[14:15]
	flat_atomic_add_f32 v[12:13], v14
.LBB0_1727:
	s_or_b64 exec, exec, s[16:17]
	ds_read_b128 v[12:15], v120 offset:13520
	v_lshl_add_u64 v[16:17], v[38:39], 1, s[4:5]
	s_waitcnt lgkmcnt(0)
	v_pk_add_f32 v[8:9], v[8:9], v[12:13]
	v_pk_add_f32 v[10:11], v[10:11], v[14:15]
	global_store_dwordx4 v[36:37], v[8:11], off
	v_cvt_pk_bf16_f32 v12, v8, v9
	v_cvt_pk_bf16_f32 v13, v10, v11
	v_pk_mul_f32 v[8:9], v[8:9], v[8:9]
	v_pk_mul_f32 v[10:11], v[10:11], v[10:11]
	v_add_f32_e32 v8, v8, v9
	v_add_f32_e32 v8, v8, v10
	v_add_f32_e32 v8, v8, v11
	flat_store_dwordx2 v[16:17], v[12:13]
	s_nop 0
	v_add_f32_dpp v8, v8, v8 row_ror:8 row_mask:0xf bank_mask:0xf bound_ctrl:1
	s_nop 1
	v_add_f32_dpp v8, v8, v8 row_ror:4 row_mask:0xf bank_mask:0xf bound_ctrl:1
	s_nop 1
	v_add_f32_dpp v8, v8, v8 row_ror:2 row_mask:0xf bank_mask:0xf bound_ctrl:1
	s_nop 1
	v_add_f32_dpp v8, v8, v8 row_ror:1 row_mask:0xf bank_mask:0xf bound_ctrl:1
	s_nop 0
	v_readlane_b32 s16, v8, 0
	v_readlane_b32 s19, v8, 16
	v_readlane_b32 s17, v8, 32
	v_readlane_b32 s18, v8, 48
	s_and_saveexec_b64 s[14:15], vcc
	s_cbranch_execz .LBB0_1729
	s_lshl_b64 s[12:13], s[12:13], 2
	v_mov_b32_e32 v8, s19
	s_add_u32 s12, s63, s12
	v_add_f32_e32 v8, s16, v8
	s_addc_u32 s13, s64, s13
	v_add_f32_e32 v8, s17, v8
	v_add_f32_e32 v10, s18, v8
	v_mov_b64_e32 v[8:9], s[12:13]
	flat_atomic_add_f32 v[8:9], v10
.LBB0_1729:
	s_or_b64 exec, exec, s[14:15]
	ds_read_b128 v[8:11], v120 offset:14560
	v_lshl_add_u64 v[12:13], v[34:35], 1, s[4:5]
	s_waitcnt lgkmcnt(0)
	v_pk_add_f32 v[4:5], v[4:5], v[8:9]
	v_pk_add_f32 v[6:7], v[6:7], v[10:11]
	global_store_dwordx4 v[32:33], v[4:7], off
	v_cvt_pk_bf16_f32 v8, v4, v5
	v_cvt_pk_bf16_f32 v9, v6, v7
	v_pk_mul_f32 v[4:5], v[4:5], v[4:5]
	v_pk_mul_f32 v[6:7], v[6:7], v[6:7]
	v_add_f32_e32 v4, v4, v5
	v_add_f32_e32 v4, v4, v6
	v_add_f32_e32 v4, v4, v7
	flat_store_dwordx2 v[12:13], v[8:9]
	s_nop 0
	v_add_f32_dpp v4, v4, v4 row_ror:8 row_mask:0xf bank_mask:0xf bound_ctrl:1
	s_nop 1
	v_add_f32_dpp v4, v4, v4 row_ror:4 row_mask:0xf bank_mask:0xf bound_ctrl:1
	s_nop 1
	v_add_f32_dpp v4, v4, v4 row_ror:2 row_mask:0xf bank_mask:0xf bound_ctrl:1
	s_nop 1
	v_add_f32_dpp v4, v4, v4 row_ror:1 row_mask:0xf bank_mask:0xf bound_ctrl:1
	s_nop 0
	v_readlane_b32 s14, v4, 0
	v_readlane_b32 s17, v4, 16
	v_readlane_b32 s15, v4, 32
	v_readlane_b32 s16, v4, 48
	s_and_saveexec_b64 s[12:13], vcc
	s_cbranch_execz .LBB0_1731
	s_lshl_b64 s[10:11], s[10:11], 2
	v_mov_b32_e32 v4, s17
	s_add_u32 s10, s63, s10
	v_add_f32_e32 v4, s14, v4
	s_addc_u32 s11, s64, s11
	v_add_f32_e32 v4, s15, v4
	v_add_f32_e32 v6, s16, v4
	v_mov_b64_e32 v[4:5], s[10:11]
	flat_atomic_add_f32 v[4:5], v6
.LBB0_1731:
	s_or_b64 exec, exec, s[12:13]
	ds_read_b128 v[4:7], v120 offset:15600
	v_lshl_add_u64 v[8:9], v[30:31], 1, s[4:5]
	s_waitcnt lgkmcnt(0)
	v_pk_add_f32 v[0:1], v[0:1], v[4:5]
	v_pk_add_f32 v[2:3], v[2:3], v[6:7]
	global_store_dwordx4 v[28:29], v[0:3], off
	v_cvt_pk_bf16_f32 v4, v0, v1
	v_cvt_pk_bf16_f32 v5, v2, v3
	v_pk_mul_f32 v[0:1], v[0:1], v[0:1]
	v_pk_mul_f32 v[2:3], v[2:3], v[2:3]
	v_add_f32_e32 v0, v0, v1
	v_add_f32_e32 v0, v0, v2
	v_add_f32_e32 v0, v0, v3
	flat_store_dwordx2 v[8:9], v[4:5]
	s_nop 0
	v_add_f32_dpp v0, v0, v0 row_ror:8 row_mask:0xf bank_mask:0xf bound_ctrl:1
	s_nop 1
	v_add_f32_dpp v0, v0, v0 row_ror:4 row_mask:0xf bank_mask:0xf bound_ctrl:1
	s_nop 1
	v_add_f32_dpp v0, v0, v0 row_ror:2 row_mask:0xf bank_mask:0xf bound_ctrl:1
	s_nop 1
	v_add_f32_dpp v0, v0, v0 row_ror:1 row_mask:0xf bank_mask:0xf bound_ctrl:1
	s_nop 0
	v_readlane_b32 s12, v0, 0
	v_readlane_b32 s15, v0, 16
	v_readlane_b32 s13, v0, 32
	v_readlane_b32 s14, v0, 48
	s_and_saveexec_b64 s[10:11], vcc
	s_cbranch_execz .LBB0_1660
	s_lshl_b64 s[8:9], s[8:9], 2
	v_mov_b32_e32 v0, s15
	s_add_u32 s8, s63, s8
	v_add_f32_e32 v0, s12, v0
	s_addc_u32 s9, s64, s9
	v_add_f32_e32 v0, s13, v0
	v_add_f32_e32 v2, s14, v0
	v_mov_b64_e32 v[0:1], s[8:9]
	flat_atomic_add_f32 v[0:1], v2
	s_branch .LBB0_1660

; DEVI float fsig(float x) { return __builtin_amdgcn_rcpf(1.f + __expf(-x)); }
; template <int EPI, int TS, bool VT>
; DEVI void gemm_epilogue(const Params& p, char* smem, f32x4 (&acc)[2][2][4][2], int m0, int n0, float scale, const float* ssin,
;                         float* ssout, u16* xbout, int wid, int lane, int wr, int wc, int fr, int fq) {
;     ...
;       float* tw = T + (wr * 64 + fq * 4) * TS + wc * 32 + fr;
; #pragma unroll
;       for (int m = 0; m < 4; ++m)
; #pragma unroll
;         for (int j = 0; j < 4; ++j)
; #pragma unroll
;           for (int v = 0; v < 4; ++v) tw[(m * 16 + j) * TS + (v >> 1) * 128 + (v & 1) * 16] = acc[ai][v >> 1][m][v & 1][j];
;     }
;     __syncthreads();
;     const int r0 = wid * 16;
;     const int g0 = m0 + ai * 128 + r0;
;     if constexpr (!VT) {
;       float rsv = 1.f;
;       if constexpr (EPI == E_PLEGATE || EPI == E_F32 || EPI == E_SWIGLU || EPI == E_GLAIN)
;         rsv = rsqrtf(ssin[g0 + (lane & 15)] * (1.f / 1024.f) + EPS);
;     ...
;           } else if constexpr (EPI == E_SWIGLU) {
;             const int gc = (lane >> 3) * 32 + 2 * (lane & 7);
;             const float2 g2 = *(const float2*)(Tr + gc), u2 = *(const float2*)(Tr + gc + 16);
;             const float ga = g2.x * rs, gb = g2.y * rs;
;             const float ha = ga * fsig(ga) * (u2.x * rs), hb = gb * fsig(gb) * (u2.y * rs);
;             __builtin_nontemporal_store(pack2(ha, hb), (unsigned*)((u16*)(wsb + OFF_HID) + (size_t)grow * 2816 + (n0 >> 1) + 2 * lane));
.LBB0_1748:
	s_lshl_b32 s16, s9, 4
	s_add_i32 s16, s16, s8
	v_or_b32_e32 v176, s16, v132
	v_lshlrev_b32_e32 v176, 2, v176
	s_nop 2
	global_load_dword v178, v176, s[4:5]
	global_load_dword v179, v176, s[4:5] offset:512
	v_lshrrev_b32_e32 v128, 2, v134
	v_and_or_b32 v128, v128, 12, s64
	s_movk_i32 s12, 0x410
	v_readlane_b32 s10, v254, 13
	v_mul_lo_u32 v128, v128, s12
	s_lshl_b32 s12, s63, 7
	v_lshlrev_b32_e32 v129, 2, v132
	v_readlane_b32 s11, v254, 14
	v_add3_u32 v128, s12, v128, v129
	ds_write2_b32 v128, v92, v100 offset1:16
	ds_write2_b32 v128, v120, v124 offset0:128 offset1:144
	v_add_u32_e32 v92, 0x400, v128
	ds_write2_b32 v92, v93, v101 offset0:4 offset1:20
	ds_write2_b32 v92, v121, v125 offset0:132 offset1:148
	v_add_u32_e32 v93, 0x800, v128
	ds_write2_b32 v93, v94, v102 offset0:8 offset1:24
	ds_write2_b32 v93, v122, v126 offset0:136 offset1:152
	v_add_u32_e32 v94, 0xc00, v128
	ds_write2_b32 v94, v95, v103 offset0:12 offset1:28
	ds_write2_b32 v94, v123, v127 offset0:140 offset1:156
	v_add_u32_e32 v95, 0x4000, v128
	ds_write2_b32 v95, v80, v84 offset0:64 offset1:80
	ds_write2_b32 v95, v112, v116 offset0:192 offset1:208
	v_add_u32_e32 v80, 0x4400, v128
	ds_write2_b32 v80, v81, v85 offset0:68 offset1:84
	ds_write2_b32 v80, v113, v117 offset0:196 offset1:212
	v_add_u32_e32 v81, 0x4800, v128
	ds_write2_b32 v81, v82, v86 offset0:72 offset1:88
	ds_write2_b32 v81, v114, v118 offset0:200 offset1:216
	v_add_u32_e32 v82, 0x4c00, v128
	ds_write2_b32 v82, v83, v87 offset0:76 offset1:92
	ds_write2_b32 v82, v115, v119 offset0:204 offset1:220
	v_add_u32_e32 v83, 0x8000, v128
	ds_write2_b32 v83, v72, v76 offset0:128 offset1:144
	v_add_u32_e32 v72, 0x8400, v128
	s_lshl_b32 s12, s9, 4
	ds_write2_b32 v72, v104, v108 offset1:16
	ds_write2_b32 v72, v73, v77 offset0:132 offset1:148
	v_add_u32_e32 v73, 0x8800, v128
	s_add_i32 s8, s12, s8
	ds_write2_b32 v73, v105, v109 offset0:4 offset1:20
	ds_write2_b32 v73, v74, v78 offset0:136 offset1:152
	v_add_u32_e32 v74, 0x8c00, v128
	v_add_u32_e32 v76, 0xc000, v128
	ds_write2_b32 v74, v106, v110 offset0:8 offset1:24
	ds_write2_b32 v74, v75, v79 offset0:140 offset1:156
	v_add_u32_e32 v75, 0x9000, v128
	ds_write2_b32 v76, v64, v68 offset0:192 offset1:208
	v_add_u32_e32 v77, 0xc400, v128
	v_or_b32_e32 v64, s8, v132
	ds_write2_b32 v75, v107, v111 offset0:12 offset1:28
	ds_write2_b32 v77, v88, v96 offset0:64 offset1:80
	ds_write2_b32 v77, v65, v69 offset0:196 offset1:212
	v_add_u32_e32 v78, 0xc800, v128
	v_ashrrev_i32_e32 v65, 31, v64
	ds_write2_b32 v78, v89, v97 offset0:68 offset1:84
	ds_write2_b32 v78, v66, v70 offset0:200 offset1:216
	v_add_u32_e32 v70, 0xcc00, v128
	v_add_u32_e32 v79, 0xd000, v128
	v_lshl_add_u64 v[64:65], v[64:65], 2, s[4:5]
	ds_write2_b32 v70, v90, v98 offset0:72 offset1:88
	ds_write2_b32 v70, v67, v71 offset0:204 offset1:220
	ds_write2_b32 v79, v91, v99 offset0:76 offset1:92
	s_waitcnt vmcnt(0) lgkmcnt(0)
	s_barrier
	v_readlane_b32 s10, v254, 13
	v_readlane_b32 s11, v254, 14
	s_add_u32 s14, s10, 0x1e95ee00
	s_addc_u32 s15, s11, 0
	s_lshl_b32 s16, s35, 8
	s_add_u32 s14, s14, s16
	s_addc_u32 s15, s15, 0
	s_mov_b32 s35, s31
	v_lshlrev_b32_e32 v204, 3, v134
	v_and_b32_e32 v204, 56, v204
	s_movk_i32 s16, 0x380
	v_and_or_b32 v250, v133, s16, v204
	s_mul_i32 s16, s9, 0x4100
	v_add_u32_e32 v250, s16, v250
	v_and_b32_e32 v204, 63, v134
	v_lshlrev_b32_e32 v204, 2, v204
	s_mul_i32 s16, s8, 0x1600
	v_add_u32_e32 v251, s16, v204
	v_add_u32_e32 v253, 0x1600, v251
	v_mov_b32_e32 v246, 0xbfb8aa3b
	v_mov_b32_e32 v247, 0xbfb8aa3b
	v_mov_b32_e32 v248, 1.0
	v_mov_b32_e32 v249, 1.0
	v_fmamk_f32 v204, v178, 0x3a800000, v150
	v_mul_f32_e32 v205, 0x4b800000, v204
	v_cmp_gt_f32_e32 vcc, s29, v204
	s_nop 1
	v_cndmask_b32_e32 v204, v204, v205, vcc
	v_rsq_f32_e32 v204, v204
	s_nop 0
	v_mul_f32_e32 v205, 0x45800000, v204
	v_cndmask_b32_e32 v252, v204, v205, vcc
	ds_read_b64 v[180:181], v250
	ds_read_b64 v[182:183], v250 offset:64
	ds_read_b64 v[184:185], v250 offset:1040
	ds_read_b64 v[186:187], v250 offset:1104
	ds_read_b64 v[188:189], v250 offset:2080
	ds_read_b64 v[190:191], v250 offset:2144
	ds_read_b64 v[192:193], v250 offset:3120
	ds_read_b64 v[194:195], v250 offset:3184
	v_readlane_b32 s10, v252, 0
	v_readlane_b32 s12, v252, 1
	ds_read_b64 v[196:197], v250 offset:4160
	ds_read_b64 v[198:199], v250 offset:4224
	ds_read_b64 v[200:201], v250 offset:5200
	ds_read_b64 v[202:203], v250 offset:5264
	s_waitcnt lgkmcnt(11)
	v_pk_mul_f32 v[180:181], s[10:11], v[180:181] op_sel_hi:[0,1]
	s_waitcnt lgkmcnt(9)
	v_pk_mul_f32 v[184:185], s[12:13], v[184:185] op_sel_hi:[0,1]
	v_pk_mul_f32 v[182:183], s[10:11], v[182:183] op_sel_hi:[0,1]
	s_waitcnt lgkmcnt(8)
	v_pk_mul_f32 v[186:187], s[12:13], v[186:187] op_sel_hi:[0,1]
	v_pk_mul_f32 v[204:205], v[180:181], v[246:247]
	v_pk_mul_f32 v[206:207], v[184:185], v[246:247]
	v_exp_f32_e32 v204, v204
	v_exp_f32_e32 v205, v205
	v_exp_f32_e32 v206, v206
	v_exp_f32_e32 v207, v207
	v_pk_add_f32 v[204:205], v[204:205], v[248:249]
	v_pk_add_f32 v[206:207], v[206:207], v[248:249]
	v_rcp_f32_e32 v204, v204
	v_rcp_f32_e32 v205, v205
	v_rcp_f32_e32 v206, v206
	v_rcp_f32_e32 v207, v207
	v_pk_mul_f32 v[180:181], v[180:181], v[204:205]
	v_pk_mul_f32 v[184:185], v[184:185], v[206:207]
	v_pk_mul_f32 v[180:181], v[182:183], v[180:181]
	v_pk_mul_f32 v[184:185], v[186:187], v[184:185]
	v_cvt_pk_bf16_f32 v212, v180, v181
	v_cvt_pk_bf16_f32 v213, v184, v185
	global_store_dword v251, v212, s[14:15]
	global_store_dword v253, v213, s[14:15]
	v_add_u32_e32 v251, 0x2c00, v251
	v_add_u32_e32 v253, 0x2c00, v253
	v_readlane_b32 s10, v252, 2
	v_readlane_b32 s12, v252, 3
	ds_read_b64 v[180:181], v250 offset:6240
	ds_read_b64 v[182:183], v250 offset:6304
	ds_read_b64 v[184:185], v250 offset:7280
	ds_read_b64 v[186:187], v250 offset:7344
	s_waitcnt lgkmcnt(11)
; DEVI float fsig(float x) { return __builtin_amdgcn_rcpf(1.f + __expf(-x)); }
; template <int EPI, int TS, bool VT>
; DEVI void gemm_epilogue(const Params& p, char* smem, f32x4 (&acc)[2][2][4][2], int m0, int n0, float scale, const float* ssin,
;                         float* ssout, u16* xbout, int wid, int lane, int wr, int wc, int fr, int fq) {
;     ...
;         for (int u = 0; u < 8; ++u) {
;           const int i = i0 + u;
;           const int grow = g0 + i;
;           const float* Tr = T + (r0 + i) * TS;
;           const float rs = __int_as_float(__builtin_amdgcn_readlane(__float_as_int(rsv), i));
;     ...
;           } else if constexpr (EPI == E_SWIGLU) {
;             const int gc = (lane >> 3) * 32 + 2 * (lane & 7);
;             const float2 g2 = *(const float2*)(Tr + gc), u2 = *(const float2*)(Tr + gc + 16);
;             const float ga = g2.x * rs, gb = g2.y * rs;
;             const float ha = ga * fsig(ga) * (u2.x * rs), hb = gb * fsig(gb) * (u2.y * rs);
;             __builtin_nontemporal_store(pack2(ha, hb), (unsigned*)((u16*)(wsb + OFF_HID) + (size_t)grow * 2816 + (n0 >> 1) + 2 * lane));
	v_pk_mul_f32 v[188:189], s[10:11], v[188:189] op_sel_hi:[0,1]
	s_waitcnt lgkmcnt(9)
	v_pk_mul_f32 v[192:193], s[12:13], v[192:193] op_sel_hi:[0,1]
	v_pk_mul_f32 v[190:191], s[10:11], v[190:191] op_sel_hi:[0,1]
	s_waitcnt lgkmcnt(8)
	v_pk_mul_f32 v[194:195], s[12:13], v[194:195] op_sel_hi:[0,1]
	v_pk_mul_f32 v[204:205], v[188:189], v[246:247]
	v_pk_mul_f32 v[206:207], v[192:193], v[246:247]
	v_exp_f32_e32 v204, v204
	v_exp_f32_e32 v205, v205
	v_exp_f32_e32 v206, v206
	v_exp_f32_e32 v207, v207
	v_pk_add_f32 v[204:205], v[204:205], v[248:249]
	v_pk_add_f32 v[206:207], v[206:207], v[248:249]
	v_rcp_f32_e32 v204, v204
	v_rcp_f32_e32 v205, v205
	v_rcp_f32_e32 v206, v206
	v_rcp_f32_e32 v207, v207
	v_pk_mul_f32 v[188:189], v[188:189], v[204:205]
	v_pk_mul_f32 v[192:193], v[192:193], v[206:207]
	v_pk_mul_f32 v[188:189], v[190:191], v[188:189]
	v_pk_mul_f32 v[192:193], v[194:195], v[192:193]
	v_cvt_pk_bf16_f32 v214, v188, v189
	v_cvt_pk_bf16_f32 v215, v192, v193
	global_store_dword v251, v214, s[14:15]
	global_store_dword v253, v215, s[14:15]
	v_add_u32_e32 v251, 0x2c00, v251
	v_add_u32_e32 v253, 0x2c00, v253
	v_readlane_b32 s10, v252, 4
	v_readlane_b32 s12, v252, 5
	ds_read_b64 v[188:189], v250 offset:8320
	ds_read_b64 v[190:191], v250 offset:8384
	ds_read_b64 v[192:193], v250 offset:9360
	ds_read_b64 v[194:195], v250 offset:9424
	s_waitcnt lgkmcnt(11)
	v_pk_mul_f32 v[196:197], s[10:11], v[196:197] op_sel_hi:[0,1]
	s_waitcnt lgkmcnt(9)
	v_pk_mul_f32 v[200:201], s[12:13], v[200:201] op_sel_hi:[0,1]
	v_pk_mul_f32 v[198:199], s[10:11], v[198:199] op_sel_hi:[0,1]
	s_waitcnt lgkmcnt(8)
	v_pk_mul_f32 v[202:203], s[12:13], v[202:203] op_sel_hi:[0,1]
	v_pk_mul_f32 v[204:205], v[196:197], v[246:247]
	v_pk_mul_f32 v[206:207], v[200:201], v[246:247]
	v_exp_f32_e32 v204, v204
	v_exp_f32_e32 v205, v205
	v_exp_f32_e32 v206, v206
	v_exp_f32_e32 v207, v207
	v_pk_add_f32 v[204:205], v[204:205], v[248:249]
	v_pk_add_f32 v[206:207], v[206:207], v[248:249]
	v_rcp_f32_e32 v204, v204
	v_rcp_f32_e32 v205, v205
	v_rcp_f32_e32 v206, v206
	v_rcp_f32_e32 v207, v207
	v_pk_mul_f32 v[196:197], v[196:197], v[204:205]
	v_pk_mul_f32 v[200:201], v[200:201], v[206:207]
	v_pk_mul_f32 v[196:197], v[198:199], v[196:197]
	v_pk_mul_f32 v[200:201], v[202:203], v[200:201]
	v_cvt_pk_bf16_f32 v212, v196, v197
	v_cvt_pk_bf16_f32 v213, v200, v201
	global_store_dword v251, v212, s[14:15]
	global_store_dword v253, v213, s[14:15]
	v_add_u32_e32 v251, 0x2c00, v251
	v_add_u32_e32 v253, 0x2c00, v253
	v_readlane_b32 s10, v252, 6
	v_readlane_b32 s12, v252, 7
	ds_read_b64 v[196:197], v250 offset:10400
	ds_read_b64 v[198:199], v250 offset:10464
	ds_read_b64 v[200:201], v250 offset:11440
	ds_read_b64 v[202:203], v250 offset:11504
	s_waitcnt lgkmcnt(11)
	v_pk_mul_f32 v[180:181], s[10:11], v[180:181] op_sel_hi:[0,1]
	s_waitcnt lgkmcnt(9)
	v_pk_mul_f32 v[184:185], s[12:13], v[184:185] op_sel_hi:[0,1]
	v_pk_mul_f32 v[182:183], s[10:11], v[182:183] op_sel_hi:[0,1]
	s_waitcnt lgkmcnt(8)
	v_pk_mul_f32 v[186:187], s[12:13], v[186:187] op_sel_hi:[0,1]
	v_pk_mul_f32 v[204:205], v[180:181], v[246:247]
	v_pk_mul_f32 v[206:207], v[184:185], v[246:247]
	v_exp_f32_e32 v204, v204
	v_exp_f32_e32 v205, v205
	v_exp_f32_e32 v206, v206
	v_exp_f32_e32 v207, v207
	v_pk_add_f32 v[204:205], v[204:205], v[248:249]
	v_pk_add_f32 v[206:207], v[206:207], v[248:249]
	v_rcp_f32_e32 v204, v204
	v_rcp_f32_e32 v205, v205
	v_rcp_f32_e32 v206, v206
	v_rcp_f32_e32 v207, v207
	v_pk_mul_f32 v[180:181], v[180:181], v[204:205]
	v_pk_mul_f32 v[184:185], v[184:185], v[206:207]
	v_pk_mul_f32 v[180:181], v[182:183], v[180:181]
	v_pk_mul_f32 v[184:185], v[186:187], v[184:185]
	v_cvt_pk_bf16_f32 v214, v180, v181
	v_cvt_pk_bf16_f32 v215, v184, v185
	global_store_dword v251, v214, s[14:15]
	global_store_dword v253, v215, s[14:15]
	v_add_u32_e32 v251, 0x2c00, v251
	v_add_u32_e32 v253, 0x2c00, v253
	v_readlane_b32 s10, v252, 8
	v_readlane_b32 s12, v252, 9
	ds_read_b64 v[180:181], v250 offset:12480
	ds_read_b64 v[182:183], v250 offset:12544
	ds_read_b64 v[184:185], v250 offset:13520
	ds_read_b64 v[186:187], v250 offset:13584
	s_waitcnt lgkmcnt(11)
	v_pk_mul_f32 v[188:189], s[10:11], v[188:189] op_sel_hi:[0,1]
	s_waitcnt lgkmcnt(9)
	v_pk_mul_f32 v[192:193], s[12:13], v[192:193] op_sel_hi:[0,1]
	v_pk_mul_f32 v[190:191], s[10:11], v[190:191] op_sel_hi:[0,1]
	s_waitcnt lgkmcnt(8)
	v_pk_mul_f32 v[194:195], s[12:13], v[194:195] op_sel_hi:[0,1]
	v_pk_mul_f32 v[204:205], v[188:189], v[246:247]
	v_pk_mul_f32 v[206:207], v[192:193], v[246:247]
	v_exp_f32_e32 v204, v204
	v_exp_f32_e32 v205, v205
	v_exp_f32_e32 v206, v206
	v_exp_f32_e32 v207, v207
	v_pk_add_f32 v[204:205], v[204:205], v[248:249]
	v_pk_add_f32 v[206:207], v[206:207], v[248:249]
	v_rcp_f32_e32 v204, v204
	v_rcp_f32_e32 v205, v205
	v_rcp_f32_e32 v206, v206
	v_rcp_f32_e32 v207, v207
	v_pk_mul_f32 v[188:189], v[188:189], v[204:205]
	v_pk_mul_f32 v[192:193], v[192:193], v[206:207]
	v_pk_mul_f32 v[188:189], v[190:191], v[188:189]
	v_pk_mul_f32 v[192:193], v[194:195], v[192:193]
	v_cvt_pk_bf16_f32 v212, v188, v189
	v_cvt_pk_bf16_f32 v213, v192, v193
	global_store_dword v251, v212, s[14:15]
	global_store_dword v253, v213, s[14:15]
	v_add_u32_e32 v251, 0x2c00, v251
	v_add_u32_e32 v253, 0x2c00, v253
	v_readlane_b32 s10, v252, 10
	v_readlane_b32 s12, v252, 11
	ds_read_b64 v[188:189], v250 offset:14560
	ds_read_b64 v[190:191], v250 offset:14624
	ds_read_b64 v[192:193], v250 offset:15600
	ds_read_b64 v[194:195], v250 offset:15664
	s_waitcnt lgkmcnt(11)
	v_pk_mul_f32 v[196:197], s[10:11], v[196:197] op_sel_hi:[0,1]
	s_waitcnt lgkmcnt(9)
; DEVI float fsig(float x) { return __builtin_amdgcn_rcpf(1.f + __expf(-x)); }
; template <int EPI, int TS, bool VT>
; DEVI void gemm_epilogue(const Params& p, char* smem, f32x4 (&acc)[2][2][4][2], int m0, int n0, float scale, const float* ssin,
;                         float* ssout, u16* xbout, int wid, int lane, int wr, int wc, int fr, int fq) {
;     ...
;       float* tw = T + (wr * 64 + fq * 4) * TS + wc * 32 + fr;
; #pragma unroll
;       for (int m = 0; m < 4; ++m)
; #pragma unroll
;         for (int j = 0; j < 4; ++j)
; #pragma unroll
;           for (int v = 0; v < 4; ++v) tw[(m * 16 + j) * TS + (v >> 1) * 128 + (v & 1) * 16] = acc[ai][v >> 1][m][v & 1][j];
;     }
;     __syncthreads();
;     ...
;           } else if constexpr (EPI == E_SWIGLU) {
;             const int gc = (lane >> 3) * 32 + 2 * (lane & 7);
;             const float2 g2 = *(const float2*)(Tr + gc), u2 = *(const float2*)(Tr + gc + 16);
;             const float ga = g2.x * rs, gb = g2.y * rs;
;             const float ha = ga * fsig(ga) * (u2.x * rs), hb = gb * fsig(gb) * (u2.y * rs);
;             __builtin_nontemporal_store(pack2(ha, hb), (unsigned*)((u16*)(wsb + OFF_HID) + (size_t)grow * 2816 + (n0 >> 1) + 2 * lane));
	v_pk_mul_f32 v[200:201], s[12:13], v[200:201] op_sel_hi:[0,1]
	v_pk_mul_f32 v[198:199], s[10:11], v[198:199] op_sel_hi:[0,1]
	s_waitcnt lgkmcnt(8)
	v_pk_mul_f32 v[202:203], s[12:13], v[202:203] op_sel_hi:[0,1]
	v_pk_mul_f32 v[204:205], v[196:197], v[246:247]
	v_pk_mul_f32 v[206:207], v[200:201], v[246:247]
	v_exp_f32_e32 v204, v204
	v_exp_f32_e32 v205, v205
	v_exp_f32_e32 v206, v206
	v_exp_f32_e32 v207, v207
	v_pk_add_f32 v[204:205], v[204:205], v[248:249]
	v_pk_add_f32 v[206:207], v[206:207], v[248:249]
	v_rcp_f32_e32 v204, v204
	v_rcp_f32_e32 v205, v205
	v_rcp_f32_e32 v206, v206
	v_rcp_f32_e32 v207, v207
	v_pk_mul_f32 v[196:197], v[196:197], v[204:205]
	v_pk_mul_f32 v[200:201], v[200:201], v[206:207]
	v_pk_mul_f32 v[196:197], v[198:199], v[196:197]
	v_pk_mul_f32 v[200:201], v[202:203], v[200:201]
	v_cvt_pk_bf16_f32 v214, v196, v197
	v_cvt_pk_bf16_f32 v215, v200, v201
	global_store_dword v251, v214, s[14:15]
	global_store_dword v253, v215, s[14:15]
	v_add_u32_e32 v251, 0x2c00, v251
	v_add_u32_e32 v253, 0x2c00, v253
	v_readlane_b32 s10, v252, 12
	v_readlane_b32 s12, v252, 13
	s_waitcnt lgkmcnt(7)
	v_pk_mul_f32 v[180:181], s[10:11], v[180:181] op_sel_hi:[0,1]
	s_waitcnt lgkmcnt(5)
	v_pk_mul_f32 v[184:185], s[12:13], v[184:185] op_sel_hi:[0,1]
	v_pk_mul_f32 v[182:183], s[10:11], v[182:183] op_sel_hi:[0,1]
	s_waitcnt lgkmcnt(4)
	v_pk_mul_f32 v[186:187], s[12:13], v[186:187] op_sel_hi:[0,1]
	v_pk_mul_f32 v[204:205], v[180:181], v[246:247]
	v_pk_mul_f32 v[206:207], v[184:185], v[246:247]
	v_exp_f32_e32 v204, v204
	v_exp_f32_e32 v205, v205
	v_exp_f32_e32 v206, v206
	v_exp_f32_e32 v207, v207
	v_pk_add_f32 v[204:205], v[204:205], v[248:249]
	v_pk_add_f32 v[206:207], v[206:207], v[248:249]
	v_rcp_f32_e32 v204, v204
	v_rcp_f32_e32 v205, v205
	v_rcp_f32_e32 v206, v206
	v_rcp_f32_e32 v207, v207
	v_pk_mul_f32 v[180:181], v[180:181], v[204:205]
	v_pk_mul_f32 v[184:185], v[184:185], v[206:207]
	v_pk_mul_f32 v[180:181], v[182:183], v[180:181]
	v_pk_mul_f32 v[184:185], v[186:187], v[184:185]
	v_cvt_pk_bf16_f32 v212, v180, v181
	v_cvt_pk_bf16_f32 v213, v184, v185
	global_store_dword v251, v212, s[14:15]
	global_store_dword v253, v213, s[14:15]
	v_add_u32_e32 v251, 0x2c00, v251
	v_add_u32_e32 v253, 0x2c00, v253
	v_readlane_b32 s10, v252, 14
	v_readlane_b32 s12, v252, 15
	s_waitcnt lgkmcnt(3)
	v_pk_mul_f32 v[188:189], s[10:11], v[188:189] op_sel_hi:[0,1]
	s_waitcnt lgkmcnt(1)
	v_pk_mul_f32 v[192:193], s[12:13], v[192:193] op_sel_hi:[0,1]
	v_pk_mul_f32 v[190:191], s[10:11], v[190:191] op_sel_hi:[0,1]
	s_waitcnt lgkmcnt(0)
	v_pk_mul_f32 v[194:195], s[12:13], v[194:195] op_sel_hi:[0,1]
	v_pk_mul_f32 v[204:205], v[188:189], v[246:247]
	v_pk_mul_f32 v[206:207], v[192:193], v[246:247]
	v_exp_f32_e32 v204, v204
	v_exp_f32_e32 v205, v205
	v_exp_f32_e32 v206, v206
	v_exp_f32_e32 v207, v207
	v_pk_add_f32 v[204:205], v[204:205], v[248:249]
	v_pk_add_f32 v[206:207], v[206:207], v[248:249]
	v_rcp_f32_e32 v204, v204
	v_rcp_f32_e32 v205, v205
	v_rcp_f32_e32 v206, v206
	v_rcp_f32_e32 v207, v207
	v_pk_mul_f32 v[188:189], v[188:189], v[204:205]
	v_pk_mul_f32 v[192:193], v[192:193], v[206:207]
	v_pk_mul_f32 v[188:189], v[190:191], v[188:189]
	v_pk_mul_f32 v[192:193], v[194:195], v[192:193]
	v_cvt_pk_bf16_f32 v214, v188, v189
	v_cvt_pk_bf16_f32 v215, v192, v193
	global_store_dword v251, v214, s[14:15]
	global_store_dword v253, v215, s[14:15]
	v_add_u32_e32 v251, 0x2c00, v251
	v_add_u32_e32 v253, 0x2c00, v253
	s_waitcnt lgkmcnt(0)
	s_barrier
	ds_write2_b32 v128, v24, v28 offset1:16
	ds_write2_b32 v128, v56, v60 offset0:128 offset1:144
	ds_write2_b32 v92, v25, v29 offset0:4 offset1:20
	ds_write2_b32 v92, v57, v61 offset0:132 offset1:148
	ds_write2_b32 v93, v26, v30 offset0:8 offset1:24
	ds_write2_b32 v93, v58, v62 offset0:136 offset1:152
	ds_write2_b32 v94, v27, v31 offset0:12 offset1:28
	ds_write2_b32 v94, v59, v63 offset0:140 offset1:156
	ds_write2_b32 v95, v16, v20 offset0:64 offset1:80
	ds_write2_b32 v95, v48, v52 offset0:192 offset1:208
	ds_write2_b32 v80, v17, v21 offset0:68 offset1:84
	ds_write2_b32 v80, v49, v53 offset0:196 offset1:212
	ds_write2_b32 v81, v18, v22 offset0:72 offset1:88
	ds_write2_b32 v81, v50, v54 offset0:200 offset1:216
	ds_write2_b32 v82, v19, v23 offset0:76 offset1:92
	ds_write2_b32 v82, v51, v55 offset0:204 offset1:220
	ds_write2_b32 v83, v8, v12 offset0:128 offset1:144
	ds_write2_b32 v72, v40, v44 offset1:16
	ds_write2_b32 v72, v9, v13 offset0:132 offset1:148
	ds_write2_b32 v73, v41, v45 offset0:4 offset1:20
	ds_write2_b32 v73, v10, v14 offset0:136 offset1:152
	ds_write2_b32 v74, v42, v46 offset0:8 offset1:24
	ds_write2_b32 v74, v11, v15 offset0:140 offset1:156
	ds_write2_b32 v75, v43, v47 offset0:12 offset1:28
	ds_write2_b32 v76, v0, v4 offset0:192 offset1:208
	ds_write2_b32 v77, v32, v36 offset0:64 offset1:80
	ds_write2_b32 v77, v1, v5 offset0:196 offset1:212
	ds_write2_b32 v78, v33, v37 offset0:68 offset1:84
	ds_write2_b32 v78, v2, v6 offset0:200 offset1:216
	ds_write2_b32 v70, v34, v38 offset0:72 offset1:88
	ds_write2_b32 v70, v3, v7 offset0:204 offset1:220
	ds_write2_b32 v79, v35, v39 offset0:76 offset1:92
	s_waitcnt lgkmcnt(0)
	s_barrier
; DEVI float fsig(float x) { return __builtin_amdgcn_rcpf(1.f + __expf(-x)); }
; template <int EPI, int TS, bool VT>
; DEVI void gemm_epilogue(const Params& p, char* smem, f32x4 (&acc)[2][2][4][2], int m0, int n0, float scale, const float* ssin,
;                         float* ssout, u16* xbout, int wid, int lane, int wr, int wc, int fr, int fq) {
;     ...
;       float rsv = 1.f;
;       if constexpr (EPI == E_PLEGATE || EPI == E_F32 || EPI == E_SWIGLU || EPI == E_GLAIN)
;         rsv = rsqrtf(ssin[g0 + (lane & 15)] * (1.f / 1024.f) + EPS);
;     ...
;           } else if constexpr (EPI == E_SWIGLU) {
;             const int gc = (lane >> 3) * 32 + 2 * (lane & 7);
;             const float2 g2 = *(const float2*)(Tr + gc), u2 = *(const float2*)(Tr + gc + 16);
;             const float ga = g2.x * rs, gb = g2.y * rs;
;             const float ha = ga * fsig(ga) * (u2.x * rs), hb = gb * fsig(gb) * (u2.y * rs);
;             __builtin_nontemporal_store(pack2(ha, hb), (unsigned*)((u16*)(wsb + OFF_HID) + (size_t)grow * 2816 + (n0 >> 1) + 2 * lane));
	v_add_u32_e32 v251, 0x9a000, v251
	v_add_u32_e32 v253, 0x9a000, v253
	v_fmamk_f32 v204, v179, 0x3a800000, v150
	v_mul_f32_e32 v205, 0x4b800000, v204
	v_cmp_gt_f32_e32 vcc, s29, v204
	s_nop 1
	v_cndmask_b32_e32 v204, v204, v205, vcc
	v_rsq_f32_e32 v204, v204
	s_nop 0
	v_mul_f32_e32 v205, 0x45800000, v204
	v_cndmask_b32_e32 v252, v204, v205, vcc
	ds_read_b64 v[180:181], v250
	ds_read_b64 v[182:183], v250 offset:64
	ds_read_b64 v[184:185], v250 offset:1040
	ds_read_b64 v[186:187], v250 offset:1104
	ds_read_b64 v[188:189], v250 offset:2080
	ds_read_b64 v[190:191], v250 offset:2144
	ds_read_b64 v[192:193], v250 offset:3120
	ds_read_b64 v[194:195], v250 offset:3184
	v_readlane_b32 s10, v252, 0
	v_readlane_b32 s12, v252, 1
	ds_read_b64 v[196:197], v250 offset:4160
	ds_read_b64 v[198:199], v250 offset:4224
	ds_read_b64 v[200:201], v250 offset:5200
	ds_read_b64 v[202:203], v250 offset:5264
	s_waitcnt lgkmcnt(11)
	v_pk_mul_f32 v[180:181], s[10:11], v[180:181] op_sel_hi:[0,1]
	s_waitcnt lgkmcnt(9)
	v_pk_mul_f32 v[184:185], s[12:13], v[184:185] op_sel_hi:[0,1]
	v_pk_mul_f32 v[182:183], s[10:11], v[182:183] op_sel_hi:[0,1]
	s_waitcnt lgkmcnt(8)
	v_pk_mul_f32 v[186:187], s[12:13], v[186:187] op_sel_hi:[0,1]
	v_pk_mul_f32 v[204:205], v[180:181], v[246:247]
	v_pk_mul_f32 v[206:207], v[184:185], v[246:247]
	v_exp_f32_e32 v204, v204
	v_exp_f32_e32 v205, v205
	v_exp_f32_e32 v206, v206
	v_exp_f32_e32 v207, v207
	v_pk_add_f32 v[204:205], v[204:205], v[248:249]
	v_pk_add_f32 v[206:207], v[206:207], v[248:249]
	v_rcp_f32_e32 v204, v204
	v_rcp_f32_e32 v205, v205
	v_rcp_f32_e32 v206, v206
	v_rcp_f32_e32 v207, v207
	v_pk_mul_f32 v[180:181], v[180:181], v[204:205]
	v_pk_mul_f32 v[184:185], v[184:185], v[206:207]
	v_pk_mul_f32 v[180:181], v[182:183], v[180:181]
	v_pk_mul_f32 v[184:185], v[186:187], v[184:185]
	v_cvt_pk_bf16_f32 v212, v180, v181
	v_cvt_pk_bf16_f32 v213, v184, v185
	global_store_dword v251, v212, s[14:15]
	global_store_dword v253, v213, s[14:15]
	v_add_u32_e32 v251, 0x2c00, v251
	v_add_u32_e32 v253, 0x2c00, v253
	v_readlane_b32 s10, v252, 2
	v_readlane_b32 s12, v252, 3
	ds_read_b64 v[180:181], v250 offset:6240
	ds_read_b64 v[182:183], v250 offset:6304
	ds_read_b64 v[184:185], v250 offset:7280
	ds_read_b64 v[186:187], v250 offset:7344
	s_waitcnt lgkmcnt(11)
	v_pk_mul_f32 v[188:189], s[10:11], v[188:189] op_sel_hi:[0,1]
	s_waitcnt lgkmcnt(9)
	v_pk_mul_f32 v[192:193], s[12:13], v[192:193] op_sel_hi:[0,1]
	v_pk_mul_f32 v[190:191], s[10:11], v[190:191] op_sel_hi:[0,1]
	s_waitcnt lgkmcnt(8)
	v_pk_mul_f32 v[194:195], s[12:13], v[194:195] op_sel_hi:[0,1]
	v_pk_mul_f32 v[204:205], v[188:189], v[246:247]
	v_pk_mul_f32 v[206:207], v[192:193], v[246:247]
	v_exp_f32_e32 v204, v204
	v_exp_f32_e32 v205, v205
	v_exp_f32_e32 v206, v206
	v_exp_f32_e32 v207, v207
	v_pk_add_f32 v[204:205], v[204:205], v[248:249]
	v_pk_add_f32 v[206:207], v[206:207], v[248:249]
	v_rcp_f32_e32 v204, v204
	v_rcp_f32_e32 v205, v205
	v_rcp_f32_e32 v206, v206
	v_rcp_f32_e32 v207, v207
	v_pk_mul_f32 v[188:189], v[188:189], v[204:205]
	v_pk_mul_f32 v[192:193], v[192:193], v[206:207]
	v_pk_mul_f32 v[188:189], v[190:191], v[188:189]
	v_pk_mul_f32 v[192:193], v[194:195], v[192:193]
	v_cvt_pk_bf16_f32 v214, v188, v189
	v_cvt_pk_bf16_f32 v215, v192, v193
	global_store_dword v251, v214, s[14:15]
	global_store_dword v253, v215, s[14:15]
	v_add_u32_e32 v251, 0x2c00, v251
	v_add_u32_e32 v253, 0x2c00, v253
	v_readlane_b32 s10, v252, 4
	v_readlane_b32 s12, v252, 5
	ds_read_b64 v[188:189], v250 offset:8320
	ds_read_b64 v[190:191], v250 offset:8384
	ds_read_b64 v[192:193], v250 offset:9360
	ds_read_b64 v[194:195], v250 offset:9424
	s_waitcnt lgkmcnt(11)
	v_pk_mul_f32 v[196:197], s[10:11], v[196:197] op_sel_hi:[0,1]
	s_waitcnt lgkmcnt(9)
	v_pk_mul_f32 v[200:201], s[12:13], v[200:201] op_sel_hi:[0,1]
	v_pk_mul_f32 v[198:199], s[10:11], v[198:199] op_sel_hi:[0,1]
	s_waitcnt lgkmcnt(8)
	v_pk_mul_f32 v[202:203], s[12:13], v[202:203] op_sel_hi:[0,1]
	v_pk_mul_f32 v[204:205], v[196:197], v[246:247]
	v_pk_mul_f32 v[206:207], v[200:201], v[246:247]
	v_exp_f32_e32 v204, v204
	v_exp_f32_e32 v205, v205
	v_exp_f32_e32 v206, v206
	v_exp_f32_e32 v207, v207
	v_pk_add_f32 v[204:205], v[204:205], v[248:249]
	v_pk_add_f32 v[206:207], v[206:207], v[248:249]
	v_rcp_f32_e32 v204, v204
	v_rcp_f32_e32 v205, v205
	v_rcp_f32_e32 v206, v206
	v_rcp_f32_e32 v207, v207
	v_pk_mul_f32 v[196:197], v[196:197], v[204:205]
	v_pk_mul_f32 v[200:201], v[200:201], v[206:207]
	v_pk_mul_f32 v[196:197], v[198:199], v[196:197]
	v_pk_mul_f32 v[200:201], v[202:203], v[200:201]
	v_cvt_pk_bf16_f32 v212, v196, v197
	v_cvt_pk_bf16_f32 v213, v200, v201
	global_store_dword v251, v212, s[14:15]
	global_store_dword v253, v213, s[14:15]
	v_add_u32_e32 v251, 0x2c00, v251
	v_add_u32_e32 v253, 0x2c00, v253
	v_readlane_b32 s10, v252, 6
	v_readlane_b32 s12, v252, 7
	ds_read_b64 v[196:197], v250 offset:10400
	ds_read_b64 v[198:199], v250 offset:10464
	ds_read_b64 v[200:201], v250 offset:11440
	ds_read_b64 v[202:203], v250 offset:11504
	s_waitcnt lgkmcnt(11)
	v_pk_mul_f32 v[180:181], s[10:11], v[180:181] op_sel_hi:[0,1]
	s_waitcnt lgkmcnt(9)
	v_pk_mul_f32 v[184:185], s[12:13], v[184:185] op_sel_hi:[0,1]
	v_pk_mul_f32 v[182:183], s[10:11], v[182:183] op_sel_hi:[0,1]
	s_waitcnt lgkmcnt(8)
; DEVI float fsig(float x) { return __builtin_amdgcn_rcpf(1.f + __expf(-x)); }
; template <int EPI, int TS, bool VT>
; DEVI void gemm_epilogue(const Params& p, char* smem, f32x4 (&acc)[2][2][4][2], int m0, int n0, float scale, const float* ssin,
;                         float* ssout, u16* xbout, int wid, int lane, int wr, int wc, int fr, int fq) {
;     ...
;           } else if constexpr (EPI == E_SWIGLU) {
;             const int gc = (lane >> 3) * 32 + 2 * (lane & 7);
;             const float2 g2 = *(const float2*)(Tr + gc), u2 = *(const float2*)(Tr + gc + 16);
;             const float ga = g2.x * rs, gb = g2.y * rs;
;             const float ha = ga * fsig(ga) * (u2.x * rs), hb = gb * fsig(gb) * (u2.y * rs);
;             __builtin_nontemporal_store(pack2(ha, hb), (unsigned*)((u16*)(wsb + OFF_HID) + (size_t)grow * 2816 + (n0 >> 1) + 2 * lane));
	v_pk_mul_f32 v[186:187], s[12:13], v[186:187] op_sel_hi:[0,1]
	v_pk_mul_f32 v[204:205], v[180:181], v[246:247]
	v_pk_mul_f32 v[206:207], v[184:185], v[246:247]
	v_exp_f32_e32 v204, v204
	v_exp_f32_e32 v205, v205
	v_exp_f32_e32 v206, v206
	v_exp_f32_e32 v207, v207
	v_pk_add_f32 v[204:205], v[204:205], v[248:249]
	v_pk_add_f32 v[206:207], v[206:207], v[248:249]
	v_rcp_f32_e32 v204, v204
	v_rcp_f32_e32 v205, v205
	v_rcp_f32_e32 v206, v206
	v_rcp_f32_e32 v207, v207
	v_pk_mul_f32 v[180:181], v[180:181], v[204:205]
	v_pk_mul_f32 v[184:185], v[184:185], v[206:207]
	v_pk_mul_f32 v[180:181], v[182:183], v[180:181]
	v_pk_mul_f32 v[184:185], v[186:187], v[184:185]
	v_cvt_pk_bf16_f32 v214, v180, v181
	v_cvt_pk_bf16_f32 v215, v184, v185
	global_store_dword v251, v214, s[14:15]
	global_store_dword v253, v215, s[14:15]
	v_add_u32_e32 v251, 0x2c00, v251
	v_add_u32_e32 v253, 0x2c00, v253
	v_readlane_b32 s10, v252, 8
	v_readlane_b32 s12, v252, 9
	ds_read_b64 v[180:181], v250 offset:12480
	ds_read_b64 v[182:183], v250 offset:12544
	ds_read_b64 v[184:185], v250 offset:13520
	ds_read_b64 v[186:187], v250 offset:13584
	s_waitcnt lgkmcnt(11)
	v_pk_mul_f32 v[188:189], s[10:11], v[188:189] op_sel_hi:[0,1]
	s_waitcnt lgkmcnt(9)
	v_pk_mul_f32 v[192:193], s[12:13], v[192:193] op_sel_hi:[0,1]
	v_pk_mul_f32 v[190:191], s[10:11], v[190:191] op_sel_hi:[0,1]
	s_waitcnt lgkmcnt(8)
	v_pk_mul_f32 v[194:195], s[12:13], v[194:195] op_sel_hi:[0,1]
	v_pk_mul_f32 v[204:205], v[188:189], v[246:247]
	v_pk_mul_f32 v[206:207], v[192:193], v[246:247]
	v_exp_f32_e32 v204, v204
	v_exp_f32_e32 v205, v205
	v_exp_f32_e32 v206, v206
	v_exp_f32_e32 v207, v207
	v_pk_add_f32 v[204:205], v[204:205], v[248:249]
	v_pk_add_f32 v[206:207], v[206:207], v[248:249]
	v_rcp_f32_e32 v204, v204
	v_rcp_f32_e32 v205, v205
	v_rcp_f32_e32 v206, v206
	v_rcp_f32_e32 v207, v207
	v_pk_mul_f32 v[188:189], v[188:189], v[204:205]
	v_pk_mul_f32 v[192:193], v[192:193], v[206:207]
	v_pk_mul_f32 v[188:189], v[190:191], v[188:189]
	v_pk_mul_f32 v[192:193], v[194:195], v[192:193]
	v_cvt_pk_bf16_f32 v212, v188, v189
	v_cvt_pk_bf16_f32 v213, v192, v193
	global_store_dword v251, v212, s[14:15]
	global_store_dword v253, v213, s[14:15]
	v_add_u32_e32 v251, 0x2c00, v251
	v_add_u32_e32 v253, 0x2c00, v253
	v_readlane_b32 s10, v252, 10
	v_readlane_b32 s12, v252, 11
	ds_read_b64 v[188:189], v250 offset:14560
	ds_read_b64 v[190:191], v250 offset:14624
	ds_read_b64 v[192:193], v250 offset:15600
	ds_read_b64 v[194:195], v250 offset:15664
	s_waitcnt lgkmcnt(11)
	v_pk_mul_f32 v[196:197], s[10:11], v[196:197] op_sel_hi:[0,1]
	s_waitcnt lgkmcnt(9)
	v_pk_mul_f32 v[200:201], s[12:13], v[200:201] op_sel_hi:[0,1]
	v_pk_mul_f32 v[198:199], s[10:11], v[198:199] op_sel_hi:[0,1]
	s_waitcnt lgkmcnt(8)
	v_pk_mul_f32 v[202:203], s[12:13], v[202:203] op_sel_hi:[0,1]
	v_pk_mul_f32 v[204:205], v[196:197], v[246:247]
	v_pk_mul_f32 v[206:207], v[200:201], v[246:247]
	v_exp_f32_e32 v204, v204
	v_exp_f32_e32 v205, v205
	v_exp_f32_e32 v206, v206
	v_exp_f32_e32 v207, v207
	v_pk_add_f32 v[204:205], v[204:205], v[248:249]
	v_pk_add_f32 v[206:207], v[206:207], v[248:249]
	v_rcp_f32_e32 v204, v204
	v_rcp_f32_e32 v205, v205
	v_rcp_f32_e32 v206, v206
	v_rcp_f32_e32 v207, v207
	v_pk_mul_f32 v[196:197], v[196:197], v[204:205]
	v_pk_mul_f32 v[200:201], v[200:201], v[206:207]
	v_pk_mul_f32 v[196:197], v[198:199], v[196:197]
	v_pk_mul_f32 v[200:201], v[202:203], v[200:201]
	v_cvt_pk_bf16_f32 v214, v196, v197
	v_cvt_pk_bf16_f32 v215, v200, v201
	global_store_dword v251, v214, s[14:15]
	global_store_dword v253, v215, s[14:15]
	v_add_u32_e32 v251, 0x2c00, v251
	v_add_u32_e32 v253, 0x2c00, v253
	v_readlane_b32 s10, v252, 12
	v_readlane_b32 s12, v252, 13
	s_waitcnt lgkmcnt(7)
	v_pk_mul_f32 v[180:181], s[10:11], v[180:181] op_sel_hi:[0,1]
	s_waitcnt lgkmcnt(5)
	v_pk_mul_f32 v[184:185], s[12:13], v[184:185] op_sel_hi:[0,1]
	v_pk_mul_f32 v[182:183], s[10:11], v[182:183] op_sel_hi:[0,1]
	s_waitcnt lgkmcnt(4)
	v_pk_mul_f32 v[186:187], s[12:13], v[186:187] op_sel_hi:[0,1]
	v_pk_mul_f32 v[204:205], v[180:181], v[246:247]
	v_pk_mul_f32 v[206:207], v[184:185], v[246:247]
	v_exp_f32_e32 v204, v204
	v_exp_f32_e32 v205, v205
	v_exp_f32_e32 v206, v206
	v_exp_f32_e32 v207, v207
	v_pk_add_f32 v[204:205], v[204:205], v[248:249]
	v_pk_add_f32 v[206:207], v[206:207], v[248:249]
	v_rcp_f32_e32 v204, v204
	v_rcp_f32_e32 v205, v205
	v_rcp_f32_e32 v206, v206
	v_rcp_f32_e32 v207, v207
	v_pk_mul_f32 v[180:181], v[180:181], v[204:205]
	v_pk_mul_f32 v[184:185], v[184:185], v[206:207]
	v_pk_mul_f32 v[180:181], v[182:183], v[180:181]
	v_pk_mul_f32 v[184:185], v[186:187], v[184:185]
	v_cvt_pk_bf16_f32 v212, v180, v181
	v_cvt_pk_bf16_f32 v213, v184, v185
	global_store_dword v251, v212, s[14:15]
	global_store_dword v253, v213, s[14:15]
	v_add_u32_e32 v251, 0x2c00, v251
	v_add_u32_e32 v253, 0x2c00, v253
	v_readlane_b32 s10, v252, 14
	v_readlane_b32 s12, v252, 15
	s_waitcnt lgkmcnt(3)
	v_pk_mul_f32 v[188:189], s[10:11], v[188:189] op_sel_hi:[0,1]
	s_waitcnt lgkmcnt(1)
	v_pk_mul_f32 v[192:193], s[12:13], v[192:193] op_sel_hi:[0,1]
	v_pk_mul_f32 v[190:191], s[10:11], v[190:191] op_sel_hi:[0,1]
	s_waitcnt lgkmcnt(0)
	v_pk_mul_f32 v[194:195], s[12:13], v[194:195] op_sel_hi:[0,1]
	v_pk_mul_f32 v[204:205], v[188:189], v[246:247]
	v_pk_mul_f32 v[206:207], v[192:193], v[246:247]
	v_exp_f32_e32 v204, v204
	v_exp_f32_e32 v205, v205
	v_exp_f32_e32 v206, v206
	v_exp_f32_e32 v207, v207
	v_pk_add_f32 v[204:205], v[204:205], v[248:249]
	v_pk_add_f32 v[206:207], v[206:207], v[248:249]
	v_rcp_f32_e32 v204, v204
	v_rcp_f32_e32 v205, v205
	v_rcp_f32_e32 v206, v206
	v_rcp_f32_e32 v207, v207
	v_pk_mul_f32 v[188:189], v[188:189], v[204:205]
	v_pk_mul_f32 v[192:193], v[192:193], v[206:207]
	v_pk_mul_f32 v[188:189], v[190:191], v[188:189]
	v_pk_mul_f32 v[192:193], v[194:195], v[192:193]
	v_cvt_pk_bf16_f32 v214, v188, v189
	v_cvt_pk_bf16_f32 v215, v192, v193
	global_store_dword v251, v214, s[14:15]
	global_store_dword v253, v215, s[14:15]
	v_add_u32_e32 v251, 0x2c00, v251
	v_add_u32_e32 v253, 0x2c00, v253
	s_mov_b32 s9, s34
	s_andn2_b64 vcc, exec, s[6:7]
	s_waitcnt lgkmcnt(0)
	s_barrier
	s_cbranch_vccz .LBB0_1757

; template <int EPI, int TS, bool VT>
; DEVI void gemm_epilogue(const Params& p, char* smem, f32x4 (&acc)[2][2][4][2], int m0, int n0, float scale, const float* ssin,
;                         float* ssout, u16* xbout, int wid, int lane, int wr, int wc, int fr, int fq) {
;     ...
;       float* tw = T + (wr * 64 + fq * 4) * TS + wc * 32 + fr;
; #pragma unroll
;       for (int m = 0; m < 4; ++m)
; #pragma unroll
;         for (int j = 0; j < 4; ++j)
; #pragma unroll
;           for (int v = 0; v < 4; ++v) tw[(m * 16 + j) * TS + (v >> 1) * 128 + (v & 1) * 16] = acc[ai][v >> 1][m][v & 1][j];
;     }
;     __syncthreads();
;     ...
;         if constexpr (EPI == E_RESID || EPI == E_PLEGATE) {
; #pragma unroll
;           for (int u = 0; u < 8; ++u) {
;             const size_t ro = (size_t)(g0 + i0 + u) * 1024 + n0 + 4 * lane;
;             const int gr = g0 + i0 + u;
;             const float* xs = p.x + ro;
;             if (scale < 0.f)
;               xs = (gr < MP ? p.x_prompt + ro : p.x_sample + (ro - (size_t)MP * 1024));
;             { const f32x4 t_ = __builtin_nontemporal_load((const f32x4*)xs); xo[u] = make_float4(t_[0], t_[1], t_[2], t_[3]); }
;             if constexpr (EPI == E_PLEGATE) {
;               const unsigned long long t2_ = __builtin_nontemporal_load((const unsigned long long*)((const u16*)(wsb + OFF_PP) + ro));
;               pv[u] = make_uint2((unsigned)t2_, (unsigned)(t2_ >> 32));
;             }
;           }
;         }
; #pragma unroll
;         for (int u = 0; u < 8; ++u) {
;           const int i = i0 + u;
;           const int grow = g0 + i;
;           const float* Tr = T + (r0 + i) * TS;
;           const float rs = __int_as_float(__builtin_amdgcn_readlane(__float_as_int(rsv), i));
;           if constexpr (EPI == E_RESID || EPI == E_PLEGATE) {
;             const float4 a = *(const float4*)(Tr + 4 * lane);
;             const size_t ro = (size_t)grow * 1024 + n0 + 4 * lane;
;             float4 x4 = xo[u];
;             if constexpr (EPI == E_PLEGATE) {
;               x4.x += bflo(pv[u].x) * fsig(a.x * rs);
;               x4.y += bfhi(pv[u].x) * fsig(a.y * rs);
;               x4.z += bflo(pv[u].y) * fsig(a.z * rs);
;               x4.w += bfhi(pv[u].y) * fsig(a.w * rs);
;             } else {
;               const float sc = fabsf(scale);
;               x4.x += sc * a.x; x4.y += sc * a.y; x4.z += sc * a.z; x4.w += sc * a.w;
.LBB0_1782:
	v_readlane_b32 s10, v254, 13
	v_readlane_b32 s11, v254, 14
	v_lshrrev_b32_e32 v128, 2, v132
	v_and_or_b32 v128, v128, 12, s62
	s_movk_i32 s10, 0x410
	v_mul_lo_u32 v128, v128, s10
	s_lshl_b32 s10, s35, 7
	v_lshlrev_b32_e32 v129, 2, v133
	v_add3_u32 v130, s10, v128, v129
	s_lshl_b32 s10, s34, 4
	s_add_i32 s10, s10, s22
	v_and_b32_e32 v141, 63, v132
	ds_write2_b32 v130, v92, v100 offset1:16
	ds_write2_b32 v130, v120, v124 offset0:128 offset1:144
	v_add_u32_e32 v124, 0x400, v130
	s_ashr_i32 s11, s10, 31
	v_lshl_or_b32 v128, v141, 2, s23
	v_mov_b32_e32 v129, s31
	ds_write2_b32 v124, v93, v101 offset0:4 offset1:20
	ds_write2_b32 v124, v121, v125 offset0:132 offset1:148
	v_add_u32_e32 v121, 0x800, v130
	s_lshl_b64 s[12:13], s[10:11], 10
	s_or_b32 s30, s10, 1
	ds_write2_b32 v121, v94, v102 offset0:8 offset1:24
	ds_write2_b32 v121, v122, v126 offset0:136 offset1:152
	v_add_u32_e32 v122, 0xc00, v130
	v_lshl_add_u64 v[146:147], s[12:13], 0, v[128:129]
	s_ashr_i32 s31, s30, 31
	s_or_b32 s22, s10, 2
	ds_write2_b32 v122, v95, v103 offset0:12 offset1:28
	ds_write2_b32 v122, v123, v127 offset0:140 offset1:156
	v_add_u32_e32 v123, 0x4000, v130
	v_add_u32_e32 v125, 0x4400, v130
	v_add_u32_e32 v126, 0x4800, v130
	v_add_u32_e32 v127, 0x4c00, v130
	v_add_u32_e32 v131, 0x8000, v130
	v_add_u32_e32 v132, 0x8400, v130
	v_add_u32_e32 v133, 0x8800, v130
	v_add_u32_e32 v134, 0x8c00, v130
	v_add_u32_e32 v135, 0x9000, v130
	v_add_u32_e32 v136, 0xc000, v130
	v_add_u32_e32 v137, 0xc400, v130
	v_add_u32_e32 v138, 0xc800, v130
	v_add_u32_e32 v139, 0xcc00, v130
	v_add_u32_e32 v140, 0xd000, v130
	v_lshl_add_u64 v[156:157], v[146:147], 2, s[38:39]
	s_lshl_b64 s[12:13], s[30:31], 10
	s_ashr_i32 s23, s22, 31
	s_or_b32 s20, s10, 3
	ds_write2_b32 v123, v80, v84 offset0:64 offset1:80
	ds_write2_b32 v123, v112, v116 offset0:192 offset1:208
	ds_write2_b32 v125, v81, v85 offset0:68 offset1:84
	ds_write2_b32 v125, v113, v117 offset0:196 offset1:212
	ds_write2_b32 v126, v82, v86 offset0:72 offset1:88
	ds_write2_b32 v126, v114, v118 offset0:200 offset1:216
	ds_write2_b32 v127, v83, v87 offset0:76 offset1:92
	ds_write2_b32 v127, v115, v119 offset0:204 offset1:220
	ds_write2_b32 v131, v72, v76 offset0:128 offset1:144
	ds_write2_b32 v132, v104, v108 offset1:16
	ds_write2_b32 v132, v73, v77 offset0:132 offset1:148
	ds_write2_b32 v133, v105, v109 offset0:4 offset1:20
	ds_write2_b32 v133, v74, v78 offset0:136 offset1:152
	ds_write2_b32 v134, v106, v110 offset0:8 offset1:24
	ds_write2_b32 v134, v75, v79 offset0:140 offset1:156
	ds_write2_b32 v135, v107, v111 offset0:12 offset1:28
	ds_write2_b32 v136, v64, v68 offset0:192 offset1:208
	ds_write2_b32 v137, v88, v96 offset0:64 offset1:80
	ds_write2_b32 v137, v65, v69 offset0:196 offset1:212
	ds_write2_b32 v138, v89, v97 offset0:68 offset1:84
	ds_write2_b32 v138, v66, v70 offset0:200 offset1:216
	ds_write2_b32 v139, v90, v98 offset0:72 offset1:88
	ds_write2_b32 v139, v67, v71 offset0:204 offset1:220
	ds_write2_b32 v140, v91, v99 offset0:76 offset1:92
	s_waitcnt vmcnt(0) lgkmcnt(0)
	s_barrier
	global_load_dwordx4 v[142:145], v[156:157], off
	v_lshl_add_u64 v[118:119], s[12:13], 0, v[128:129]
	s_lshl_b64 s[12:13], s[22:23], 10
	s_ashr_i32 s21, s20, 31
	s_or_b32 s18, s10, 4
	v_lshl_add_u64 v[114:115], s[12:13], 0, v[128:129]
	s_lshl_b64 s[12:13], s[20:21], 10
	s_ashr_i32 s19, s18, 31
	s_or_b32 s16, s10, 5
	v_lshl_add_u64 v[110:111], s[12:13], 0, v[128:129]
	s_lshl_b64 s[12:13], s[18:19], 10
	s_ashr_i32 s17, s16, 31
	s_or_b32 s14, s10, 6
	v_lshl_add_u64 v[106:107], s[12:13], 0, v[128:129]
	s_lshl_b64 s[12:13], s[16:17], 10
	s_ashr_i32 s15, s14, 31
	v_lshl_add_u64 v[102:103], s[12:13], 0, v[128:129]
	s_lshl_b64 s[12:13], s[14:15], 10
	v_lshl_add_u64 v[98:99], s[12:13], 0, v[128:129]
	s_or_b32 s12, s10, 7
	s_ashr_i32 s13, s12, 31
	s_lshl_b64 s[62:63], s[12:13], 10
	v_lshl_add_u64 v[94:95], s[62:63], 0, v[128:129]
	v_lshl_add_u64 v[116:117], v[118:119], 2, s[38:39]
	v_lshl_add_u64 v[108:109], v[110:111], 2, s[38:39]
	v_lshl_add_u64 v[100:101], v[102:103], 2, s[38:39]
	v_lshl_add_u64 v[92:93], v[94:95], 2, s[38:39]
	v_lshl_add_u64 v[112:113], v[114:115], 2, s[38:39]
	global_load_dwordx4 v[88:91], v[116:117], off
	global_load_dwordx4 v[84:87], v[112:113], off
	v_lshl_add_u64 v[104:105], v[106:107], 2, s[38:39]
	global_load_dwordx4 v[80:83], v[108:109], off
	global_load_dwordx4 v[76:79], v[104:105], off
	v_lshl_add_u64 v[96:97], v[98:99], 2, s[38:39]
	global_load_dwordx4 v[72:75], v[100:101], off
	global_load_dwordx4 v[68:71], v[96:97], off
	global_load_dwordx4 v[64:67], v[92:93], off
	v_lshlrev_b32_e32 v120, 4, v141
	s_mulk_i32 s34, 0x4100
	v_add_u32_e32 v120, s34, v120
	ds_read_b128 v[152:155], v120
	v_cmp_eq_u32_e32 vcc, 0, v141
	v_lshl_add_u64 v[146:147], v[146:147], 1, s[6:7]
	s_waitcnt vmcnt(7) lgkmcnt(0)
	v_pk_fma_f32 v[142:143], v[152:153], 0.5, v[142:143] op_sel_hi:[1,0,1]
	v_pk_fma_f32 v[144:145], v[154:155], 0.5, v[144:145] op_sel_hi:[1,0,1]
	global_store_dwordx4 v[156:157], v[142:145], off
	v_cvt_pk_bf16_f32 v152, v142, v143
	v_cvt_pk_bf16_f32 v153, v144, v145
	v_pk_mul_f32 v[142:143], v[142:143], v[142:143]
	v_pk_mul_f32 v[144:145], v[144:145], v[144:145]
	v_add_f32_e32 v141, v142, v143
	v_add_f32_e32 v141, v141, v144
	v_add_f32_e32 v141, v141, v145
	flat_store_dwordx2 v[146:147], v[152:153]
	s_nop 0
	v_add_f32_dpp v141, v141, v141 row_ror:8 row_mask:0xf bank_mask:0xf bound_ctrl:1
	s_nop 1
	v_add_f32_dpp v141, v141, v141 row_ror:4 row_mask:0xf bank_mask:0xf bound_ctrl:1
	s_nop 1
	v_add_f32_dpp v141, v141, v141 row_ror:2 row_mask:0xf bank_mask:0xf bound_ctrl:1
	s_nop 1
	v_add_f32_dpp v141, v141, v141 row_ror:1 row_mask:0xf bank_mask:0xf bound_ctrl:1
	s_nop 0
	v_readlane_b32 s62, v141, 0
	v_readlane_b32 s69, v141, 16
	v_readlane_b32 s63, v141, 32
	v_readlane_b32 s68, v141, 48
	s_and_saveexec_b64 s[34:35], vcc
	s_cbranch_execz .LBB0_1784
	s_lshl_b64 s[70:71], s[10:11], 2
	v_mov_b32_e32 v141, s69
	s_add_u32 s70, s2, s70
	v_add_f32_e32 v141, s62, v141
	s_addc_u32 s71, s3, s71
	v_add_f32_e32 v141, s63, v141
	v_add_f32_e32 v141, s68, v141
	v_mov_b64_e32 v[142:143], s[70:71]
	flat_atomic_add_f32 v[142:143], v141
; DEVI float fsig(float x) { return __builtin_amdgcn_rcpf(1.f + __expf(-x)); }
; DEVI float bflo(unsigned u) { return __uint_as_float(u << 16); }
; DEVI float bfhi(unsigned u) { return __uint_as_float(u & 0xffff0000u); }
; template <int EPI, int TS, bool VT>
; DEVI void gemm_epilogue(const Params& p, char* smem, f32x4 (&acc)[2][2][4][2], int m0, int n0, float scale, const float* ssin,
;                         float* ssout, u16* xbout, int wid, int lane, int wr, int wc, int fr, int fq) {
;     ...
;         for (int u = 0; u < 8; ++u) {
;           const int i = i0 + u;
;           const int grow = g0 + i;
;           const float* Tr = T + (r0 + i) * TS;
;           const float rs = __int_as_float(__builtin_amdgcn_readlane(__float_as_int(rsv), i));
;           if constexpr (EPI == E_RESID || EPI == E_PLEGATE) {
;             const float4 a = *(const float4*)(Tr + 4 * lane);
;             const size_t ro = (size_t)grow * 1024 + n0 + 4 * lane;
;             float4 x4 = xo[u];
;             if constexpr (EPI == E_PLEGATE) {
;               x4.x += bflo(pv[u].x) * fsig(a.x * rs);
;               x4.y += bfhi(pv[u].x) * fsig(a.y * rs);
;               x4.z += bflo(pv[u].y) * fsig(a.z * rs);
;               x4.w += bfhi(pv[u].y) * fsig(a.w * rs);
;             } else {
;               const float sc = fabsf(scale);
;               x4.x += sc * a.x; x4.y += sc * a.y; x4.z += sc * a.z; x4.w += sc * a.w;
;             }
;             st_nt16(p.x + ro, x4);
;             if (xbout) {
;               uint2 o;
;               o.x = pack2(x4.x, x4.y);
;               o.y = pack2(x4.z, x4.w);
;               st_nt8(xbout + ro, o);
;             }
;             if (ssout) {
;               const float ssq = wsum(x4.x * x4.x + x4.y * x4.y + x4.z * x4.z + x4.w * x4.w, lane);
;               if (lane == 0) atomicAdd(ssout + grow, ssq);
;             }
.LBB0_1784:
	s_or_b64 exec, exec, s[34:35]
	ds_read_b128 v[142:145], v120 offset:1040
	v_lshl_add_u64 v[118:119], v[118:119], 1, s[6:7]
	s_waitcnt vmcnt(0) lgkmcnt(0)
	v_pk_fma_f32 v[88:89], v[142:143], 0.5, v[88:89] op_sel_hi:[1,0,1]
	v_pk_fma_f32 v[90:91], v[144:145], 0.5, v[90:91] op_sel_hi:[1,0,1]
	global_store_dwordx4 v[116:117], v[88:91], off
	v_cvt_pk_bf16_f32 v116, v88, v89
	v_cvt_pk_bf16_f32 v117, v90, v91
	v_pk_mul_f32 v[88:89], v[88:89], v[88:89]
	v_pk_mul_f32 v[90:91], v[90:91], v[90:91]
	v_add_f32_e32 v88, v88, v89
	v_add_f32_e32 v88, v88, v90
	v_add_f32_e32 v88, v88, v91
	flat_store_dwordx2 v[118:119], v[116:117]
	s_nop 0
	v_add_f32_dpp v88, v88, v88 row_ror:8 row_mask:0xf bank_mask:0xf bound_ctrl:1
	s_nop 1
	v_add_f32_dpp v88, v88, v88 row_ror:4 row_mask:0xf bank_mask:0xf bound_ctrl:1
	s_nop 1
	v_add_f32_dpp v88, v88, v88 row_ror:2 row_mask:0xf bank_mask:0xf bound_ctrl:1
	s_nop 1
	v_add_f32_dpp v88, v88, v88 row_ror:1 row_mask:0xf bank_mask:0xf bound_ctrl:1
	s_nop 0
	v_readlane_b32 s11, v88, 0
	v_readlane_b32 s68, v88, 16
	v_readlane_b32 s62, v88, 32
	v_readlane_b32 s63, v88, 48
	s_and_saveexec_b64 s[34:35], vcc
	s_cbranch_execz .LBB0_1786
	s_lshl_b64 s[30:31], s[30:31], 2
	v_mov_b32_e32 v88, s68
	s_add_u32 s30, s2, s30
	v_add_f32_e32 v88, s11, v88
	s_addc_u32 s31, s3, s31
	v_add_f32_e32 v88, s62, v88
	v_add_f32_e32 v90, s63, v88
	v_mov_b64_e32 v[88:89], s[30:31]
	flat_atomic_add_f32 v[88:89], v90
.LBB0_1786:
	s_or_b64 exec, exec, s[34:35]
	ds_read_b128 v[88:91], v120 offset:2080
	v_lshl_add_u64 v[114:115], v[114:115], 1, s[6:7]
	s_waitcnt lgkmcnt(0)
	v_pk_fma_f32 v[84:85], v[88:89], 0.5, v[84:85] op_sel_hi:[1,0,1]
	v_pk_fma_f32 v[86:87], v[90:91], 0.5, v[86:87] op_sel_hi:[1,0,1]
	global_store_dwordx4 v[112:113], v[84:87], off
	v_cvt_pk_bf16_f32 v88, v84, v85
	v_cvt_pk_bf16_f32 v89, v86, v87
	v_pk_mul_f32 v[84:85], v[84:85], v[84:85]
	v_pk_mul_f32 v[86:87], v[86:87], v[86:87]
	v_add_f32_e32 v84, v84, v85
	v_add_f32_e32 v84, v84, v86
	v_add_f32_e32 v84, v84, v87
	flat_store_dwordx2 v[114:115], v[88:89]
	s_nop 0
	v_add_f32_dpp v84, v84, v84 row_ror:8 row_mask:0xf bank_mask:0xf bound_ctrl:1
	s_nop 1
	v_add_f32_dpp v84, v84, v84 row_ror:4 row_mask:0xf bank_mask:0xf bound_ctrl:1
	s_nop 1
	v_add_f32_dpp v84, v84, v84 row_ror:2 row_mask:0xf bank_mask:0xf bound_ctrl:1
	s_nop 1
	v_add_f32_dpp v84, v84, v84 row_ror:1 row_mask:0xf bank_mask:0xf bound_ctrl:1
	s_nop 0
	v_readlane_b32 s11, v84, 0
	v_readlane_b32 s62, v84, 16
	v_readlane_b32 s34, v84, 32
	v_readlane_b32 s35, v84, 48
	s_and_saveexec_b64 s[30:31], vcc
	s_cbranch_execz .LBB0_1788
	s_lshl_b64 s[22:23], s[22:23], 2
	v_mov_b32_e32 v84, s62
	s_add_u32 s22, s2, s22
	v_add_f32_e32 v84, s11, v84
	s_addc_u32 s23, s3, s23
	v_add_f32_e32 v84, s34, v84
	v_add_f32_e32 v86, s35, v84
	v_mov_b64_e32 v[84:85], s[22:23]
	flat_atomic_add_f32 v[84:85], v86
.LBB0_1788:
	s_or_b64 exec, exec, s[30:31]
	ds_read_b128 v[84:87], v120 offset:3120
	v_lshl_add_u64 v[88:89], v[110:111], 1, s[6:7]
	s_waitcnt lgkmcnt(0)
	v_pk_fma_f32 v[80:81], v[84:85], 0.5, v[80:81] op_sel_hi:[1,0,1]
	v_pk_fma_f32 v[82:83], v[86:87], 0.5, v[82:83] op_sel_hi:[1,0,1]
	global_store_dwordx4 v[108:109], v[80:83], off
	v_cvt_pk_bf16_f32 v84, v80, v81
	v_cvt_pk_bf16_f32 v85, v82, v83
	v_pk_mul_f32 v[80:81], v[80:81], v[80:81]
	v_pk_mul_f32 v[82:83], v[82:83], v[82:83]
	v_add_f32_e32 v80, v80, v81
	v_add_f32_e32 v80, v80, v82
	v_add_f32_e32 v80, v80, v83
	flat_store_dwordx2 v[88:89], v[84:85]
	s_nop 0
	v_add_f32_dpp v80, v80, v80 row_ror:8 row_mask:0xf bank_mask:0xf bound_ctrl:1
	s_nop 1
	v_add_f32_dpp v80, v80, v80 row_ror:4 row_mask:0xf bank_mask:0xf bound_ctrl:1
	s_nop 1
	v_add_f32_dpp v80, v80, v80 row_ror:2 row_mask:0xf bank_mask:0xf bound_ctrl:1
	s_nop 1
	v_add_f32_dpp v80, v80, v80 row_ror:1 row_mask:0xf bank_mask:0xf bound_ctrl:1
	s_nop 0
	v_readlane_b32 s11, v80, 0
	v_readlane_b32 s34, v80, 16
	v_readlane_b32 s30, v80, 32
	v_readlane_b32 s31, v80, 48
	s_and_saveexec_b64 s[22:23], vcc
	s_cbranch_execz .LBB0_1790
	s_lshl_b64 s[20:21], s[20:21], 2
	v_mov_b32_e32 v80, s34
	s_add_u32 s20, s2, s20
	v_add_f32_e32 v80, s11, v80
	s_addc_u32 s21, s3, s21
	v_add_f32_e32 v80, s30, v80
	v_add_f32_e32 v82, s31, v80
	v_mov_b64_e32 v[80:81], s[20:21]
	flat_atomic_add_f32 v[80:81], v82
.LBB0_1790:
	s_or_b64 exec, exec, s[22:23]
	ds_read_b128 v[80:83], v120 offset:4160
	v_lshl_add_u64 v[84:85], v[106:107], 1, s[6:7]
	s_waitcnt lgkmcnt(0)
	v_pk_fma_f32 v[76:77], v[80:81], 0.5, v[76:77] op_sel_hi:[1,0,1]
	v_pk_fma_f32 v[78:79], v[82:83], 0.5, v[78:79] op_sel_hi:[1,0,1]
	global_store_dwordx4 v[104:105], v[76:79], off
	v_cvt_pk_bf16_f32 v80, v76, v77
	v_cvt_pk_bf16_f32 v81, v78, v79
	v_pk_mul_f32 v[76:77], v[76:77], v[76:77]
	v_pk_mul_f32 v[78:79], v[78:79], v[78:79]
	v_add_f32_e32 v76, v76, v77
	v_add_f32_e32 v76, v76, v78
	v_add_f32_e32 v76, v76, v79
	flat_store_dwordx2 v[84:85], v[80:81]
	s_nop 0
	v_add_f32_dpp v76, v76, v76 row_ror:8 row_mask:0xf bank_mask:0xf bound_ctrl:1
	s_nop 1
	v_add_f32_dpp v76, v76, v76 row_ror:4 row_mask:0xf bank_mask:0xf bound_ctrl:1
	s_nop 1
	v_add_f32_dpp v76, v76, v76 row_ror:2 row_mask:0xf bank_mask:0xf bound_ctrl:1
	s_nop 1
	v_add_f32_dpp v76, v76, v76 row_ror:1 row_mask:0xf bank_mask:0xf bound_ctrl:1
	s_nop 0
	v_readlane_b32 s11, v76, 0
	v_readlane_b32 s30, v76, 16
	v_readlane_b32 s22, v76, 32
	v_readlane_b32 s23, v76, 48
	s_and_saveexec_b64 s[20:21], vcc
	s_cbranch_execz .LBB0_1792
	s_lshl_b64 s[18:19], s[18:19], 2
	v_mov_b32_e32 v76, s30
	s_add_u32 s18, s2, s18
	v_add_f32_e32 v76, s11, v76
	s_addc_u32 s19, s3, s19
	v_add_f32_e32 v76, s22, v76
	v_add_f32_e32 v78, s23, v76
	v_mov_b64_e32 v[76:77], s[18:19]
	flat_atomic_add_f32 v[76:77], v78
; DEVI float fsig(float x) { return __builtin_amdgcn_rcpf(1.f + __expf(-x)); }
; DEVI float bflo(unsigned u) { return __uint_as_float(u << 16); }
; DEVI float bfhi(unsigned u) { return __uint_as_float(u & 0xffff0000u); }
; template <int EPI, int TS, bool VT>
; DEVI void gemm_epilogue(const Params& p, char* smem, f32x4 (&acc)[2][2][4][2], int m0, int n0, float scale, const float* ssin,
;                         float* ssout, u16* xbout, int wid, int lane, int wr, int wc, int fr, int fq) {
;     ...
;         for (int u = 0; u < 8; ++u) {
;           const int i = i0 + u;
;           const int grow = g0 + i;
;           const float* Tr = T + (r0 + i) * TS;
;           const float rs = __int_as_float(__builtin_amdgcn_readlane(__float_as_int(rsv), i));
;           if constexpr (EPI == E_RESID || EPI == E_PLEGATE) {
;             const float4 a = *(const float4*)(Tr + 4 * lane);
;             const size_t ro = (size_t)grow * 1024 + n0 + 4 * lane;
;             float4 x4 = xo[u];
;             if constexpr (EPI == E_PLEGATE) {
;               x4.x += bflo(pv[u].x) * fsig(a.x * rs);
;               x4.y += bfhi(pv[u].x) * fsig(a.y * rs);
;               x4.z += bflo(pv[u].y) * fsig(a.z * rs);
;               x4.w += bfhi(pv[u].y) * fsig(a.w * rs);
;             } else {
;               const float sc = fabsf(scale);
;               x4.x += sc * a.x; x4.y += sc * a.y; x4.z += sc * a.z; x4.w += sc * a.w;
;             }
;             st_nt16(p.x + ro, x4);
;             if (xbout) {
;               uint2 o;
;               o.x = pack2(x4.x, x4.y);
;               o.y = pack2(x4.z, x4.w);
;               st_nt8(xbout + ro, o);
;             }
;             if (ssout) {
;               const float ssq = wsum(x4.x * x4.x + x4.y * x4.y + x4.z * x4.z + x4.w * x4.w, lane);
;               if (lane == 0) atomicAdd(ssout + grow, ssq);
;             }
.LBB0_1792:
	s_or_b64 exec, exec, s[20:21]
	ds_read_b128 v[76:79], v120 offset:5200
	v_lshl_add_u64 v[80:81], v[102:103], 1, s[6:7]
	s_waitcnt lgkmcnt(0)
	v_pk_fma_f32 v[72:73], v[76:77], 0.5, v[72:73] op_sel_hi:[1,0,1]
	v_pk_fma_f32 v[74:75], v[78:79], 0.5, v[74:75] op_sel_hi:[1,0,1]
	global_store_dwordx4 v[100:101], v[72:75], off
	v_cvt_pk_bf16_f32 v76, v72, v73
	v_cvt_pk_bf16_f32 v77, v74, v75
	v_pk_mul_f32 v[72:73], v[72:73], v[72:73]
	v_pk_mul_f32 v[74:75], v[74:75], v[74:75]
	v_add_f32_e32 v72, v72, v73
	v_add_f32_e32 v72, v72, v74
	v_add_f32_e32 v72, v72, v75
	flat_store_dwordx2 v[80:81], v[76:77]
	s_nop 0
	v_add_f32_dpp v72, v72, v72 row_ror:8 row_mask:0xf bank_mask:0xf bound_ctrl:1
	s_nop 1
	v_add_f32_dpp v72, v72, v72 row_ror:4 row_mask:0xf bank_mask:0xf bound_ctrl:1
	s_nop 1
	v_add_f32_dpp v72, v72, v72 row_ror:2 row_mask:0xf bank_mask:0xf bound_ctrl:1
	s_nop 1
	v_add_f32_dpp v72, v72, v72 row_ror:1 row_mask:0xf bank_mask:0xf bound_ctrl:1
	s_nop 0
	v_readlane_b32 s11, v72, 0
	v_readlane_b32 s22, v72, 16
	v_readlane_b32 s20, v72, 32
	v_readlane_b32 s21, v72, 48
	s_and_saveexec_b64 s[18:19], vcc
	s_cbranch_execz .LBB0_1794
	s_lshl_b64 s[16:17], s[16:17], 2
	v_mov_b32_e32 v72, s22
	s_add_u32 s16, s2, s16
	v_add_f32_e32 v72, s11, v72
	s_addc_u32 s17, s3, s17
	v_add_f32_e32 v72, s20, v72
	v_add_f32_e32 v74, s21, v72
	v_mov_b64_e32 v[72:73], s[16:17]
	flat_atomic_add_f32 v[72:73], v74
.LBB0_1794:
	s_or_b64 exec, exec, s[18:19]
	ds_read_b128 v[72:75], v120 offset:6240
	v_lshl_add_u64 v[76:77], v[98:99], 1, s[6:7]
	s_waitcnt lgkmcnt(0)
	v_pk_fma_f32 v[68:69], v[72:73], 0.5, v[68:69] op_sel_hi:[1,0,1]
	v_pk_fma_f32 v[70:71], v[74:75], 0.5, v[70:71] op_sel_hi:[1,0,1]
	global_store_dwordx4 v[96:97], v[68:71], off
	v_cvt_pk_bf16_f32 v72, v68, v69
	v_cvt_pk_bf16_f32 v73, v70, v71
	v_pk_mul_f32 v[68:69], v[68:69], v[68:69]
	v_pk_mul_f32 v[70:71], v[70:71], v[70:71]
	v_add_f32_e32 v68, v68, v69
	v_add_f32_e32 v68, v68, v70
	v_add_f32_e32 v68, v68, v71
	flat_store_dwordx2 v[76:77], v[72:73]
	s_nop 0
	v_add_f32_dpp v68, v68, v68 row_ror:8 row_mask:0xf bank_mask:0xf bound_ctrl:1
	s_nop 1
	v_add_f32_dpp v68, v68, v68 row_ror:4 row_mask:0xf bank_mask:0xf bound_ctrl:1
	s_nop 1
	v_add_f32_dpp v68, v68, v68 row_ror:2 row_mask:0xf bank_mask:0xf bound_ctrl:1
	s_nop 1
	v_add_f32_dpp v68, v68, v68 row_ror:1 row_mask:0xf bank_mask:0xf bound_ctrl:1
	s_nop 0
	v_readlane_b32 s11, v68, 0
	v_readlane_b32 s20, v68, 16
	v_readlane_b32 s18, v68, 32
	v_readlane_b32 s19, v68, 48
	s_and_saveexec_b64 s[16:17], vcc
	s_cbranch_execz .LBB0_1796
	s_lshl_b64 s[14:15], s[14:15], 2
	v_mov_b32_e32 v68, s20
	s_add_u32 s14, s2, s14
	v_add_f32_e32 v68, s11, v68
	s_addc_u32 s15, s3, s15
	v_add_f32_e32 v68, s18, v68
	v_add_f32_e32 v70, s19, v68
	v_mov_b64_e32 v[68:69], s[14:15]
	flat_atomic_add_f32 v[68:69], v70
.LBB0_1796:
	s_or_b64 exec, exec, s[16:17]
	ds_read_b128 v[68:71], v120 offset:7280
	v_lshl_add_u64 v[72:73], v[94:95], 1, s[6:7]
	s_waitcnt lgkmcnt(0)
	v_pk_fma_f32 v[64:65], v[68:69], 0.5, v[64:65] op_sel_hi:[1,0,1]
	v_pk_fma_f32 v[66:67], v[70:71], 0.5, v[66:67] op_sel_hi:[1,0,1]
	global_store_dwordx4 v[92:93], v[64:67], off
	v_cvt_pk_bf16_f32 v68, v64, v65
	v_cvt_pk_bf16_f32 v69, v66, v67
	v_pk_mul_f32 v[64:65], v[64:65], v[64:65]
	v_pk_mul_f32 v[66:67], v[66:67], v[66:67]
	v_add_f32_e32 v64, v64, v65
	v_add_f32_e32 v64, v64, v66
	v_add_f32_e32 v64, v64, v67
	flat_store_dwordx2 v[72:73], v[68:69]
	s_nop 0
	v_add_f32_dpp v64, v64, v64 row_ror:8 row_mask:0xf bank_mask:0xf bound_ctrl:1
	s_nop 1
	v_add_f32_dpp v64, v64, v64 row_ror:4 row_mask:0xf bank_mask:0xf bound_ctrl:1
	s_nop 1
	v_add_f32_dpp v64, v64, v64 row_ror:2 row_mask:0xf bank_mask:0xf bound_ctrl:1
	s_nop 1
	v_add_f32_dpp v64, v64, v64 row_ror:1 row_mask:0xf bank_mask:0xf bound_ctrl:1
	s_nop 0
	v_readlane_b32 s11, v64, 0
	v_readlane_b32 s18, v64, 16
	v_readlane_b32 s16, v64, 32
	v_readlane_b32 s17, v64, 48
	s_and_saveexec_b64 s[14:15], vcc
	s_cbranch_execz .LBB0_1798
	s_lshl_b64 s[12:13], s[12:13], 2
	v_mov_b32_e32 v64, s18
	s_add_u32 s12, s2, s12
	v_add_f32_e32 v64, s11, v64
	s_addc_u32 s13, s3, s13
	v_add_f32_e32 v64, s16, v64
	v_add_f32_e32 v66, s17, v64
	v_mov_b64_e32 v[64:65], s[12:13]
	flat_atomic_add_f32 v[64:65], v66
; template <int EPI, int TS, bool VT>
; DEVI void gemm_epilogue(const Params& p, char* smem, f32x4 (&acc)[2][2][4][2], int m0, int n0, float scale, const float* ssin,
;                         float* ssout, u16* xbout, int wid, int lane, int wr, int wc, int fr, int fq) {
;     ...
;             const size_t ro = (size_t)(g0 + i0 + u) * 1024 + n0 + 4 * lane;
;             const int gr = g0 + i0 + u;
;             const float* xs = p.x + ro;
;             if (scale < 0.f)
;               xs = (gr < MP ? p.x_prompt + ro : p.x_sample + (ro - (size_t)MP * 1024));
;             { const f32x4 t_ = __builtin_nontemporal_load((const f32x4*)xs); xo[u] = make_float4(t_[0], t_[1], t_[2], t_[3]); }
;             if constexpr (EPI == E_PLEGATE) {
;               const unsigned long long t2_ = __builtin_nontemporal_load((const unsigned long long*)((const u16*)(wsb + OFF_PP) + ro));
;               pv[u] = make_uint2((unsigned)t2_, (unsigned)(t2_ >> 32));
;             }
;           }
;         }
; #pragma unroll
;         for (int u = 0; u < 8; ++u) {
;           const int i = i0 + u;
;           const int grow = g0 + i;
;           const float* Tr = T + (r0 + i) * TS;
;           const float rs = __int_as_float(__builtin_amdgcn_readlane(__float_as_int(rsv), i));
;           if constexpr (EPI == E_RESID || EPI == E_PLEGATE) {
;             const float4 a = *(const float4*)(Tr + 4 * lane);
;             const size_t ro = (size_t)grow * 1024 + n0 + 4 * lane;
;             float4 x4 = xo[u];
;             if constexpr (EPI == E_PLEGATE) {
;               x4.x += bflo(pv[u].x) * fsig(a.x * rs);
;               x4.y += bfhi(pv[u].x) * fsig(a.y * rs);
;               x4.z += bflo(pv[u].y) * fsig(a.z * rs);
;               x4.w += bfhi(pv[u].y) * fsig(a.w * rs);
;             } else {
;               const float sc = fabsf(scale);
;               x4.x += sc * a.x; x4.y += sc * a.y; x4.z += sc * a.z; x4.w += sc * a.w;
;             }
;             st_nt16(p.x + ro, x4);
;             if (xbout) {
;               uint2 o;
;               o.x = pack2(x4.x, x4.y);
;               o.y = pack2(x4.z, x4.w);
;               st_nt8(xbout + ro, o);
;             }
;             if (ssout) {
;               const float ssq = wsum(x4.x * x4.x + x4.y * x4.y + x4.z * x4.z + x4.w * x4.w, lane);
;               if (lane == 0) atomicAdd(ssout + grow, ssq);
;             }
.LBB0_1798:
	s_or_b64 exec, exec, s[14:15]
	s_or_b32 s34, s10, 8
	s_ashr_i32 s35, s34, 31
	s_lshl_b64 s[12:13], s[34:35], 10
	s_or_b32 s30, s10, 9
	v_lshl_add_u64 v[146:147], s[12:13], 0, v[128:129]
	s_ashr_i32 s31, s30, 31
	s_or_b32 s22, s10, 10
	v_lshl_add_u64 v[156:157], v[146:147], 2, s[38:39]
	s_lshl_b64 s[12:13], s[30:31], 10
	s_ashr_i32 s23, s22, 31
	s_or_b32 s20, s10, 11
	global_load_dwordx4 v[142:145], v[156:157], off
	v_lshl_add_u64 v[118:119], s[12:13], 0, v[128:129]
	s_lshl_b64 s[12:13], s[22:23], 10
	s_ashr_i32 s21, s20, 31
	s_or_b32 s18, s10, 12
	v_lshl_add_u64 v[114:115], s[12:13], 0, v[128:129]
	s_lshl_b64 s[12:13], s[20:21], 10
	s_ashr_i32 s19, s18, 31
	s_or_b32 s16, s10, 13
	v_lshl_add_u64 v[110:111], s[12:13], 0, v[128:129]
	s_lshl_b64 s[12:13], s[18:19], 10
	s_ashr_i32 s17, s16, 31
	s_or_b32 s14, s10, 14
	v_lshl_add_u64 v[106:107], s[12:13], 0, v[128:129]
	s_lshl_b64 s[12:13], s[16:17], 10
	s_ashr_i32 s15, s14, 31
	v_lshl_add_u64 v[102:103], s[12:13], 0, v[128:129]
	s_lshl_b64 s[12:13], s[14:15], 10
	v_lshl_add_u64 v[98:99], s[12:13], 0, v[128:129]
	s_or_b32 s12, s10, 15
	s_ashr_i32 s13, s12, 31
	s_lshl_b64 s[62:63], s[12:13], 10
	v_lshl_add_u64 v[94:95], s[62:63], 0, v[128:129]
	v_lshl_add_u64 v[116:117], v[118:119], 2, s[38:39]
	v_lshl_add_u64 v[108:109], v[110:111], 2, s[38:39]
	v_lshl_add_u64 v[100:101], v[102:103], 2, s[38:39]
	v_lshl_add_u64 v[92:93], v[94:95], 2, s[38:39]
	v_lshl_add_u64 v[112:113], v[114:115], 2, s[38:39]
	global_load_dwordx4 v[88:91], v[116:117], off
	global_load_dwordx4 v[84:87], v[112:113], off
	v_lshl_add_u64 v[104:105], v[106:107], 2, s[38:39]
	global_load_dwordx4 v[80:83], v[108:109], off
	global_load_dwordx4 v[76:79], v[104:105], off
	v_lshl_add_u64 v[96:97], v[98:99], 2, s[38:39]
	global_load_dwordx4 v[72:75], v[100:101], off
	global_load_dwordx4 v[68:71], v[96:97], off
	global_load_dwordx4 v[64:67], v[92:93], off
	ds_read_b128 v[152:155], v120 offset:8320
	v_lshl_add_u64 v[146:147], v[146:147], 1, s[6:7]
	s_waitcnt vmcnt(0) lgkmcnt(0)
	v_pk_fma_f32 v[142:143], v[152:153], 0.5, v[142:143] op_sel_hi:[1,0,1]
	v_pk_fma_f32 v[144:145], v[154:155], 0.5, v[144:145] op_sel_hi:[1,0,1]
	global_store_dwordx4 v[156:157], v[142:145], off
	v_cvt_pk_bf16_f32 v152, v142, v143
	v_cvt_pk_bf16_f32 v153, v144, v145
	v_pk_mul_f32 v[142:143], v[142:143], v[142:143]
	v_pk_mul_f32 v[144:145], v[144:145], v[144:145]
	v_add_f32_e32 v141, v142, v143
	v_add_f32_e32 v141, v141, v144
	v_add_f32_e32 v141, v141, v145
	flat_store_dwordx2 v[146:147], v[152:153]
	s_nop 0
	v_add_f32_dpp v141, v141, v141 row_ror:8 row_mask:0xf bank_mask:0xf bound_ctrl:1
	s_nop 1
	v_add_f32_dpp v141, v141, v141 row_ror:4 row_mask:0xf bank_mask:0xf bound_ctrl:1
	s_nop 1
	v_add_f32_dpp v141, v141, v141 row_ror:2 row_mask:0xf bank_mask:0xf bound_ctrl:1
	s_nop 1
	v_add_f32_dpp v141, v141, v141 row_ror:1 row_mask:0xf bank_mask:0xf bound_ctrl:1
	s_nop 0
	v_readlane_b32 s11, v141, 0
	v_readlane_b32 s70, v141, 16
	v_readlane_b32 s68, v141, 32
	v_readlane_b32 s69, v141, 48
	s_and_saveexec_b64 s[62:63], vcc
	s_cbranch_execz .LBB0_1800
	s_lshl_b64 s[34:35], s[34:35], 2
	v_mov_b32_e32 v141, s70
	s_add_u32 s34, s2, s34
	v_add_f32_e32 v141, s11, v141
	s_addc_u32 s35, s3, s35
	v_add_f32_e32 v141, s68, v141
	v_add_f32_e32 v141, s69, v141
	v_mov_b64_e32 v[142:143], s[34:35]
	flat_atomic_add_f32 v[142:143], v141
.LBB0_1800:
	s_or_b64 exec, exec, s[62:63]
	ds_read_b128 v[142:145], v120 offset:9360
	v_lshl_add_u64 v[118:119], v[118:119], 1, s[6:7]
	s_waitcnt lgkmcnt(0)
	v_pk_fma_f32 v[88:89], v[142:143], 0.5, v[88:89] op_sel_hi:[1,0,1]
	v_pk_fma_f32 v[90:91], v[144:145], 0.5, v[90:91] op_sel_hi:[1,0,1]
	global_store_dwordx4 v[116:117], v[88:91], off
	v_cvt_pk_bf16_f32 v116, v88, v89
	v_cvt_pk_bf16_f32 v117, v90, v91
	v_pk_mul_f32 v[88:89], v[88:89], v[88:89]
	v_pk_mul_f32 v[90:91], v[90:91], v[90:91]
	v_add_f32_e32 v88, v88, v89
	v_add_f32_e32 v88, v88, v90
	v_add_f32_e32 v88, v88, v91
	flat_store_dwordx2 v[118:119], v[116:117]
	s_nop 0
	v_add_f32_dpp v88, v88, v88 row_ror:8 row_mask:0xf bank_mask:0xf bound_ctrl:1
	s_nop 1
	v_add_f32_dpp v88, v88, v88 row_ror:4 row_mask:0xf bank_mask:0xf bound_ctrl:1
	s_nop 1
	v_add_f32_dpp v88, v88, v88 row_ror:2 row_mask:0xf bank_mask:0xf bound_ctrl:1
	s_nop 1
	v_add_f32_dpp v88, v88, v88 row_ror:1 row_mask:0xf bank_mask:0xf bound_ctrl:1
	s_nop 0
	v_readlane_b32 s11, v88, 0
	v_readlane_b32 s68, v88, 16
	v_readlane_b32 s62, v88, 32
	v_readlane_b32 s63, v88, 48
	s_and_saveexec_b64 s[34:35], vcc
	s_cbranch_execz .LBB0_1802
	s_lshl_b64 s[30:31], s[30:31], 2
	v_mov_b32_e32 v88, s68
	s_add_u32 s30, s2, s30
	v_add_f32_e32 v88, s11, v88
	s_addc_u32 s31, s3, s31
	v_add_f32_e32 v88, s62, v88
	v_add_f32_e32 v90, s63, v88
	v_mov_b64_e32 v[88:89], s[30:31]
	flat_atomic_add_f32 v[88:89], v90
.LBB0_1802:
	s_or_b64 exec, exec, s[34:35]
	ds_read_b128 v[88:91], v120 offset:10400
	v_lshl_add_u64 v[114:115], v[114:115], 1, s[6:7]
	s_waitcnt lgkmcnt(0)
	v_pk_fma_f32 v[84:85], v[88:89], 0.5, v[84:85] op_sel_hi:[1,0,1]
	v_pk_fma_f32 v[86:87], v[90:91], 0.5, v[86:87] op_sel_hi:[1,0,1]
	global_store_dwordx4 v[112:113], v[84:87], off
	v_cvt_pk_bf16_f32 v88, v84, v85
	v_cvt_pk_bf16_f32 v89, v86, v87
	v_pk_mul_f32 v[84:85], v[84:85], v[84:85]
	v_pk_mul_f32 v[86:87], v[86:87], v[86:87]
	v_add_f32_e32 v84, v84, v85
	v_add_f32_e32 v84, v84, v86
	v_add_f32_e32 v84, v84, v87
	flat_store_dwordx2 v[114:115], v[88:89]
	s_nop 0
	v_add_f32_dpp v84, v84, v84 row_ror:8 row_mask:0xf bank_mask:0xf bound_ctrl:1
	s_nop 1
	v_add_f32_dpp v84, v84, v84 row_ror:4 row_mask:0xf bank_mask:0xf bound_ctrl:1
	s_nop 1
	v_add_f32_dpp v84, v84, v84 row_ror:2 row_mask:0xf bank_mask:0xf bound_ctrl:1
	s_nop 1
	v_add_f32_dpp v84, v84, v84 row_ror:1 row_mask:0xf bank_mask:0xf bound_ctrl:1
	s_nop 0
	v_readlane_b32 s11, v84, 0
	v_readlane_b32 s62, v84, 16
	v_readlane_b32 s34, v84, 32
	v_readlane_b32 s35, v84, 48
	s_and_saveexec_b64 s[30:31], vcc
	s_cbranch_execz .LBB0_1804
	s_lshl_b64 s[22:23], s[22:23], 2
	v_mov_b32_e32 v84, s62
	s_add_u32 s22, s2, s22
	v_add_f32_e32 v84, s11, v84
	s_addc_u32 s23, s3, s23
	v_add_f32_e32 v84, s34, v84
	v_add_f32_e32 v86, s35, v84
	v_mov_b64_e32 v[84:85], s[22:23]
	flat_atomic_add_f32 v[84:85], v86
; DEVI float fsig(float x) { return __builtin_amdgcn_rcpf(1.f + __expf(-x)); }
; DEVI float bflo(unsigned u) { return __uint_as_float(u << 16); }
; DEVI float bfhi(unsigned u) { return __uint_as_float(u & 0xffff0000u); }
; template <int EPI, int TS, bool VT>
; DEVI void gemm_epilogue(const Params& p, char* smem, f32x4 (&acc)[2][2][4][2], int m0, int n0, float scale, const float* ssin,
;                         float* ssout, u16* xbout, int wid, int lane, int wr, int wc, int fr, int fq) {
;     ...
;         for (int u = 0; u < 8; ++u) {
;           const int i = i0 + u;
;           const int grow = g0 + i;
;           const float* Tr = T + (r0 + i) * TS;
;           const float rs = __int_as_float(__builtin_amdgcn_readlane(__float_as_int(rsv), i));
;           if constexpr (EPI == E_RESID || EPI == E_PLEGATE) {
;             const float4 a = *(const float4*)(Tr + 4 * lane);
;             const size_t ro = (size_t)grow * 1024 + n0 + 4 * lane;
;             float4 x4 = xo[u];
;             if constexpr (EPI == E_PLEGATE) {
;               x4.x += bflo(pv[u].x) * fsig(a.x * rs);
;               x4.y += bfhi(pv[u].x) * fsig(a.y * rs);
;               x4.z += bflo(pv[u].y) * fsig(a.z * rs);
;               x4.w += bfhi(pv[u].y) * fsig(a.w * rs);
;             } else {
;               const float sc = fabsf(scale);
;               x4.x += sc * a.x; x4.y += sc * a.y; x4.z += sc * a.z; x4.w += sc * a.w;
;             }
;             st_nt16(p.x + ro, x4);
;             if (xbout) {
;               uint2 o;
;               o.x = pack2(x4.x, x4.y);
;               o.y = pack2(x4.z, x4.w);
;               st_nt8(xbout + ro, o);
;             }
;             if (ssout) {
;               const float ssq = wsum(x4.x * x4.x + x4.y * x4.y + x4.z * x4.z + x4.w * x4.w, lane);
;               if (lane == 0) atomicAdd(ssout + grow, ssq);
;             }
.LBB0_1804:
	s_or_b64 exec, exec, s[30:31]
	ds_read_b128 v[84:87], v120 offset:11440
	v_lshl_add_u64 v[88:89], v[110:111], 1, s[6:7]
	s_waitcnt lgkmcnt(0)
	v_pk_fma_f32 v[80:81], v[84:85], 0.5, v[80:81] op_sel_hi:[1,0,1]
	v_pk_fma_f32 v[82:83], v[86:87], 0.5, v[82:83] op_sel_hi:[1,0,1]
	global_store_dwordx4 v[108:109], v[80:83], off
	v_cvt_pk_bf16_f32 v84, v80, v81
	v_cvt_pk_bf16_f32 v85, v82, v83
	v_pk_mul_f32 v[80:81], v[80:81], v[80:81]
	v_pk_mul_f32 v[82:83], v[82:83], v[82:83]
	v_add_f32_e32 v80, v80, v81
	v_add_f32_e32 v80, v80, v82
	v_add_f32_e32 v80, v80, v83
	flat_store_dwordx2 v[88:89], v[84:85]
	s_nop 0
	v_add_f32_dpp v80, v80, v80 row_ror:8 row_mask:0xf bank_mask:0xf bound_ctrl:1
	s_nop 1
	v_add_f32_dpp v80, v80, v80 row_ror:4 row_mask:0xf bank_mask:0xf bound_ctrl:1
	s_nop 1
	v_add_f32_dpp v80, v80, v80 row_ror:2 row_mask:0xf bank_mask:0xf bound_ctrl:1
	s_nop 1
	v_add_f32_dpp v80, v80, v80 row_ror:1 row_mask:0xf bank_mask:0xf bound_ctrl:1
	s_nop 0
	v_readlane_b32 s11, v80, 0
	v_readlane_b32 s34, v80, 16
	v_readlane_b32 s30, v80, 32
	v_readlane_b32 s31, v80, 48
	s_and_saveexec_b64 s[22:23], vcc
	s_cbranch_execz .LBB0_1806
	s_lshl_b64 s[20:21], s[20:21], 2
	v_mov_b32_e32 v80, s34
	s_add_u32 s20, s2, s20
	v_add_f32_e32 v80, s11, v80
	s_addc_u32 s21, s3, s21
	v_add_f32_e32 v80, s30, v80
	v_add_f32_e32 v82, s31, v80
	v_mov_b64_e32 v[80:81], s[20:21]
	flat_atomic_add_f32 v[80:81], v82
.LBB0_1806:
	s_or_b64 exec, exec, s[22:23]
	ds_read_b128 v[80:83], v120 offset:12480
	v_lshl_add_u64 v[84:85], v[106:107], 1, s[6:7]
	s_waitcnt lgkmcnt(0)
	v_pk_fma_f32 v[76:77], v[80:81], 0.5, v[76:77] op_sel_hi:[1,0,1]
	v_pk_fma_f32 v[78:79], v[82:83], 0.5, v[78:79] op_sel_hi:[1,0,1]
	global_store_dwordx4 v[104:105], v[76:79], off
	v_cvt_pk_bf16_f32 v80, v76, v77
	v_cvt_pk_bf16_f32 v81, v78, v79
	v_pk_mul_f32 v[76:77], v[76:77], v[76:77]
	v_pk_mul_f32 v[78:79], v[78:79], v[78:79]
	v_add_f32_e32 v76, v76, v77
	v_add_f32_e32 v76, v76, v78
	v_add_f32_e32 v76, v76, v79
	flat_store_dwordx2 v[84:85], v[80:81]
	s_nop 0
	v_add_f32_dpp v76, v76, v76 row_ror:8 row_mask:0xf bank_mask:0xf bound_ctrl:1
	s_nop 1
	v_add_f32_dpp v76, v76, v76 row_ror:4 row_mask:0xf bank_mask:0xf bound_ctrl:1
	s_nop 1
	v_add_f32_dpp v76, v76, v76 row_ror:2 row_mask:0xf bank_mask:0xf bound_ctrl:1
	s_nop 1
	v_add_f32_dpp v76, v76, v76 row_ror:1 row_mask:0xf bank_mask:0xf bound_ctrl:1
	s_nop 0
	v_readlane_b32 s11, v76, 0
	v_readlane_b32 s30, v76, 16
	v_readlane_b32 s22, v76, 32
	v_readlane_b32 s23, v76, 48
	s_and_saveexec_b64 s[20:21], vcc
	s_cbranch_execz .LBB0_1808
	s_lshl_b64 s[18:19], s[18:19], 2
	v_mov_b32_e32 v76, s30
	s_add_u32 s18, s2, s18
	v_add_f32_e32 v76, s11, v76
	s_addc_u32 s19, s3, s19
	v_add_f32_e32 v76, s22, v76
	v_add_f32_e32 v78, s23, v76
	v_mov_b64_e32 v[76:77], s[18:19]
	flat_atomic_add_f32 v[76:77], v78
.LBB0_1808:
	s_or_b64 exec, exec, s[20:21]
	ds_read_b128 v[76:79], v120 offset:13520
	v_lshl_add_u64 v[80:81], v[102:103], 1, s[6:7]
	s_waitcnt lgkmcnt(0)
	v_pk_fma_f32 v[72:73], v[76:77], 0.5, v[72:73] op_sel_hi:[1,0,1]
	v_pk_fma_f32 v[74:75], v[78:79], 0.5, v[74:75] op_sel_hi:[1,0,1]
	global_store_dwordx4 v[100:101], v[72:75], off
	v_cvt_pk_bf16_f32 v76, v72, v73
	v_cvt_pk_bf16_f32 v77, v74, v75
	v_pk_mul_f32 v[72:73], v[72:73], v[72:73]
	v_pk_mul_f32 v[74:75], v[74:75], v[74:75]
	v_add_f32_e32 v72, v72, v73
	v_add_f32_e32 v72, v72, v74
	v_add_f32_e32 v72, v72, v75
	flat_store_dwordx2 v[80:81], v[76:77]
	s_nop 0
	v_add_f32_dpp v72, v72, v72 row_ror:8 row_mask:0xf bank_mask:0xf bound_ctrl:1
	s_nop 1
	v_add_f32_dpp v72, v72, v72 row_ror:4 row_mask:0xf bank_mask:0xf bound_ctrl:1
	s_nop 1
	v_add_f32_dpp v72, v72, v72 row_ror:2 row_mask:0xf bank_mask:0xf bound_ctrl:1
	s_nop 1
	v_add_f32_dpp v72, v72, v72 row_ror:1 row_mask:0xf bank_mask:0xf bound_ctrl:1
	s_nop 0
	v_readlane_b32 s11, v72, 0
	v_readlane_b32 s22, v72, 16
	v_readlane_b32 s20, v72, 32
	v_readlane_b32 s21, v72, 48
	s_and_saveexec_b64 s[18:19], vcc
	s_cbranch_execz .LBB0_1810
	s_lshl_b64 s[16:17], s[16:17], 2
	v_mov_b32_e32 v72, s22
	s_add_u32 s16, s2, s16
	v_add_f32_e32 v72, s11, v72
	s_addc_u32 s17, s3, s17
	v_add_f32_e32 v72, s20, v72
	v_add_f32_e32 v74, s21, v72
	v_mov_b64_e32 v[72:73], s[16:17]
	flat_atomic_add_f32 v[72:73], v74
.LBB0_1810:
	s_or_b64 exec, exec, s[18:19]
	ds_read_b128 v[72:75], v120 offset:14560
	v_lshl_add_u64 v[76:77], v[98:99], 1, s[6:7]
	s_waitcnt lgkmcnt(0)
	v_pk_fma_f32 v[68:69], v[72:73], 0.5, v[68:69] op_sel_hi:[1,0,1]
	v_pk_fma_f32 v[70:71], v[74:75], 0.5, v[70:71] op_sel_hi:[1,0,1]
	global_store_dwordx4 v[96:97], v[68:71], off
	v_cvt_pk_bf16_f32 v72, v68, v69
	v_cvt_pk_bf16_f32 v73, v70, v71
	v_pk_mul_f32 v[68:69], v[68:69], v[68:69]
	v_pk_mul_f32 v[70:71], v[70:71], v[70:71]
	v_add_f32_e32 v68, v68, v69
	v_add_f32_e32 v68, v68, v70
	v_add_f32_e32 v68, v68, v71
	flat_store_dwordx2 v[76:77], v[72:73]
	s_nop 0
	v_add_f32_dpp v68, v68, v68 row_ror:8 row_mask:0xf bank_mask:0xf bound_ctrl:1
	s_nop 1
	v_add_f32_dpp v68, v68, v68 row_ror:4 row_mask:0xf bank_mask:0xf bound_ctrl:1
	s_nop 1
	v_add_f32_dpp v68, v68, v68 row_ror:2 row_mask:0xf bank_mask:0xf bound_ctrl:1
	s_nop 1
	v_add_f32_dpp v68, v68, v68 row_ror:1 row_mask:0xf bank_mask:0xf bound_ctrl:1
	s_nop 0
	v_readlane_b32 s11, v68, 0
	v_readlane_b32 s20, v68, 16
	v_readlane_b32 s18, v68, 32
	v_readlane_b32 s19, v68, 48
	s_and_saveexec_b64 s[16:17], vcc
	s_cbranch_execz .LBB0_1812
	s_lshl_b64 s[14:15], s[14:15], 2
	v_mov_b32_e32 v68, s20
	s_add_u32 s14, s2, s14
	v_add_f32_e32 v68, s11, v68
	s_addc_u32 s15, s3, s15
	v_add_f32_e32 v68, s18, v68
	v_add_f32_e32 v70, s19, v68
	v_mov_b64_e32 v[68:69], s[14:15]
	flat_atomic_add_f32 v[68:69], v70
; template <int EPI, int TS, bool VT>
; DEVI void gemm_epilogue(const Params& p, char* smem, f32x4 (&acc)[2][2][4][2], int m0, int n0, float scale, const float* ssin,
;                         float* ssout, u16* xbout, int wid, int lane, int wr, int wc, int fr, int fq) {
;     ...
;       float* tw = T + (wr * 64 + fq * 4) * TS + wc * 32 + fr;
; #pragma unroll
;       for (int m = 0; m < 4; ++m)
; #pragma unroll
;         for (int j = 0; j < 4; ++j)
; #pragma unroll
;           for (int v = 0; v < 4; ++v) tw[(m * 16 + j) * TS + (v >> 1) * 128 + (v & 1) * 16] = acc[ai][v >> 1][m][v & 1][j];
;     }
;     __syncthreads();
;     ...
;         if constexpr (EPI == E_RESID || EPI == E_PLEGATE) {
; #pragma unroll
;           for (int u = 0; u < 8; ++u) {
;             const size_t ro = (size_t)(g0 + i0 + u) * 1024 + n0 + 4 * lane;
;             const int gr = g0 + i0 + u;
;             const float* xs = p.x + ro;
;             if (scale < 0.f)
;               xs = (gr < MP ? p.x_prompt + ro : p.x_sample + (ro - (size_t)MP * 1024));
;             { const f32x4 t_ = __builtin_nontemporal_load((const f32x4*)xs); xo[u] = make_float4(t_[0], t_[1], t_[2], t_[3]); }
;             if constexpr (EPI == E_PLEGATE) {
;               const unsigned long long t2_ = __builtin_nontemporal_load((const unsigned long long*)((const u16*)(wsb + OFF_PP) + ro));
;               pv[u] = make_uint2((unsigned)t2_, (unsigned)(t2_ >> 32));
;             }
;           }
;         }
; #pragma unroll
;         for (int u = 0; u < 8; ++u) {
;           const int i = i0 + u;
;           const int grow = g0 + i;
;           const float* Tr = T + (r0 + i) * TS;
;           const float rs = __int_as_float(__builtin_amdgcn_readlane(__float_as_int(rsv), i));
;           if constexpr (EPI == E_RESID || EPI == E_PLEGATE) {
;             const float4 a = *(const float4*)(Tr + 4 * lane);
;             const size_t ro = (size_t)grow * 1024 + n0 + 4 * lane;
;             float4 x4 = xo[u];
;             if constexpr (EPI == E_PLEGATE) {
;               x4.x += bflo(pv[u].x) * fsig(a.x * rs);
;               x4.y += bfhi(pv[u].x) * fsig(a.y * rs);
;               x4.z += bflo(pv[u].y) * fsig(a.z * rs);
;               x4.w += bfhi(pv[u].y) * fsig(a.w * rs);
;             } else {
;               const float sc = fabsf(scale);
;               x4.x += sc * a.x; x4.y += sc * a.y; x4.z += sc * a.z; x4.w += sc * a.w;
.LBB0_1812:
	s_or_b64 exec, exec, s[16:17]
	ds_read_b128 v[68:71], v120 offset:15600
	v_lshl_add_u64 v[72:73], v[94:95], 1, s[6:7]
	s_waitcnt lgkmcnt(0)
	v_pk_fma_f32 v[64:65], v[68:69], 0.5, v[64:65] op_sel_hi:[1,0,1]
	v_pk_fma_f32 v[66:67], v[70:71], 0.5, v[66:67] op_sel_hi:[1,0,1]
	global_store_dwordx4 v[92:93], v[64:67], off
	v_cvt_pk_bf16_f32 v68, v64, v65
	v_cvt_pk_bf16_f32 v69, v66, v67
	v_pk_mul_f32 v[64:65], v[64:65], v[64:65]
	v_pk_mul_f32 v[66:67], v[66:67], v[66:67]
	v_add_f32_e32 v64, v64, v65
	v_add_f32_e32 v64, v64, v66
	v_add_f32_e32 v64, v64, v67
	flat_store_dwordx2 v[72:73], v[68:69]
	s_nop 0
	v_add_f32_dpp v64, v64, v64 row_ror:8 row_mask:0xf bank_mask:0xf bound_ctrl:1
	s_nop 1
	v_add_f32_dpp v64, v64, v64 row_ror:4 row_mask:0xf bank_mask:0xf bound_ctrl:1
	s_nop 1
	v_add_f32_dpp v64, v64, v64 row_ror:2 row_mask:0xf bank_mask:0xf bound_ctrl:1
	s_nop 1
	v_add_f32_dpp v64, v64, v64 row_ror:1 row_mask:0xf bank_mask:0xf bound_ctrl:1
	s_nop 0
	v_readlane_b32 s11, v64, 0
	v_readlane_b32 s18, v64, 16
	v_readlane_b32 s16, v64, 32
	v_readlane_b32 s17, v64, 48
	s_and_saveexec_b64 s[14:15], vcc
	s_cbranch_execz .LBB0_1814
	s_lshl_b64 s[12:13], s[12:13], 2
	v_mov_b32_e32 v64, s18
	s_add_u32 s12, s2, s12
	v_add_f32_e32 v64, s11, v64
	s_addc_u32 s13, s3, s13
	v_add_f32_e32 v64, s16, v64
	v_add_f32_e32 v66, s17, v64
	v_mov_b64_e32 v[64:65], s[12:13]
	flat_atomic_add_f32 v[64:65], v66
.LBB0_1814:
	s_or_b64 exec, exec, s[14:15]
	s_add_i32 s34, s10, 0x80
	s_ashr_i32 s35, s34, 31
	s_lshl_b64 s[12:13], s[34:35], 10
	s_add_i32 s30, s10, 0x81
	v_lshl_add_u64 v[64:65], s[12:13], 0, v[128:129]
	s_ashr_i32 s31, s30, 31
	s_add_i32 s22, s10, 0x82
	v_lshl_add_u64 v[66:67], v[64:65], 2, s[38:39]
	s_lshl_b64 s[12:13], s[30:31], 10
	s_ashr_i32 s23, s22, 31
	s_add_i32 s20, s10, 0x83
	s_waitcnt lgkmcnt(0)
	s_barrier
	ds_write2_b32 v130, v24, v28 offset1:16
	ds_write2_b32 v130, v56, v60 offset0:128 offset1:144
	ds_write2_b32 v124, v25, v29 offset0:4 offset1:20
	ds_write2_b32 v124, v57, v61 offset0:132 offset1:148
	ds_write2_b32 v121, v26, v30 offset0:8 offset1:24
	ds_write2_b32 v121, v58, v62 offset0:136 offset1:152
	ds_write2_b32 v122, v27, v31 offset0:12 offset1:28
	ds_write2_b32 v122, v59, v63 offset0:140 offset1:156
	ds_write2_b32 v123, v16, v20 offset0:64 offset1:80
	ds_write2_b32 v123, v48, v52 offset0:192 offset1:208
	ds_write2_b32 v125, v17, v21 offset0:68 offset1:84
	ds_write2_b32 v125, v49, v53 offset0:196 offset1:212
	ds_write2_b32 v126, v18, v22 offset0:72 offset1:88
	ds_write2_b32 v126, v50, v54 offset0:200 offset1:216
	ds_write2_b32 v127, v19, v23 offset0:76 offset1:92
	ds_write2_b32 v127, v51, v55 offset0:204 offset1:220
	ds_write2_b32 v131, v8, v12 offset0:128 offset1:144
	ds_write2_b32 v132, v40, v44 offset1:16
	ds_write2_b32 v132, v9, v13 offset0:132 offset1:148
	ds_write2_b32 v133, v41, v45 offset0:4 offset1:20
	ds_write2_b32 v133, v10, v14 offset0:136 offset1:152
	ds_write2_b32 v134, v42, v46 offset0:8 offset1:24
	ds_write2_b32 v134, v11, v15 offset0:140 offset1:156
	ds_write2_b32 v135, v43, v47 offset0:12 offset1:28
	ds_write2_b32 v136, v0, v4 offset0:192 offset1:208
	ds_write2_b32 v137, v32, v36 offset0:64 offset1:80
	ds_write2_b32 v137, v1, v5 offset0:196 offset1:212
	ds_write2_b32 v138, v33, v37 offset0:68 offset1:84
	ds_write2_b32 v138, v2, v6 offset0:200 offset1:216
	ds_write2_b32 v139, v34, v38 offset0:72 offset1:88
	ds_write2_b32 v139, v3, v7 offset0:204 offset1:220
	ds_write2_b32 v140, v35, v39 offset0:76 offset1:92
	s_waitcnt lgkmcnt(0)
	s_barrier
	global_load_dwordx4 v[56:59], v[66:67], off
	v_lshl_add_u64 v[54:55], s[12:13], 0, v[128:129]
	s_lshl_b64 s[12:13], s[22:23], 10
	s_ashr_i32 s21, s20, 31
	s_add_i32 s18, s10, 0x84
	v_lshl_add_u64 v[50:51], s[12:13], 0, v[128:129]
	s_lshl_b64 s[12:13], s[20:21], 10
	s_ashr_i32 s19, s18, 31
	s_add_i32 s16, s10, 0x85
	v_lshl_add_u64 v[46:47], s[12:13], 0, v[128:129]
	s_lshl_b64 s[12:13], s[18:19], 10
	s_ashr_i32 s17, s16, 31
	s_add_i32 s14, s10, 0x86
	v_lshl_add_u64 v[42:43], s[12:13], 0, v[128:129]
	s_lshl_b64 s[12:13], s[16:17], 10
	s_ashr_i32 s15, s14, 31
	v_lshl_add_u64 v[38:39], s[12:13], 0, v[128:129]
	s_lshl_b64 s[12:13], s[14:15], 10
	v_lshl_add_u64 v[34:35], s[12:13], 0, v[128:129]
	s_add_i32 s12, s10, 0x87
	s_ashr_i32 s13, s12, 31
	s_lshl_b64 s[62:63], s[12:13], 10
	v_lshl_add_u64 v[30:31], s[62:63], 0, v[128:129]
	v_lshl_add_u64 v[52:53], v[54:55], 2, s[38:39]
	v_lshl_add_u64 v[44:45], v[46:47], 2, s[38:39]
	v_lshl_add_u64 v[36:37], v[38:39], 2, s[38:39]
	v_lshl_add_u64 v[28:29], v[30:31], 2, s[38:39]
	v_lshl_add_u64 v[48:49], v[50:51], 2, s[38:39]
	global_load_dwordx4 v[24:27], v[52:53], off
	global_load_dwordx4 v[20:23], v[48:49], off
	v_lshl_add_u64 v[40:41], v[42:43], 2, s[38:39]
	global_load_dwordx4 v[16:19], v[44:45], off
	global_load_dwordx4 v[12:15], v[40:41], off
	v_lshl_add_u64 v[32:33], v[34:35], 2, s[38:39]
	global_load_dwordx4 v[8:11], v[36:37], off
	global_load_dwordx4 v[4:7], v[32:33], off
	global_load_dwordx4 v[0:3], v[28:29], off
	ds_read_b128 v[60:63], v120
	s_waitcnt vmcnt(0) lgkmcnt(0)
	v_pk_fma_f32 v[56:57], v[60:61], 0.5, v[56:57] op_sel_hi:[1,0,1]
	v_pk_fma_f32 v[58:59], v[62:63], 0.5, v[58:59] op_sel_hi:[1,0,1]
	global_store_dwordx4 v[66:67], v[56:59], off
	v_cvt_pk_bf16_f32 v60, v56, v57
	v_cvt_pk_bf16_f32 v61, v58, v59
	v_pk_mul_f32 v[56:57], v[56:57], v[56:57]
	v_pk_mul_f32 v[58:59], v[58:59], v[58:59]
	v_add_f32_e32 v56, v56, v57
	v_add_f32_e32 v56, v56, v58
	v_add_f32_e32 v56, v56, v59
	v_lshl_add_u64 v[62:63], v[64:65], 1, s[6:7]
	flat_store_dwordx2 v[62:63], v[60:61]
	v_add_f32_dpp v56, v56, v56 row_ror:8 row_mask:0xf bank_mask:0xf bound_ctrl:1
	s_nop 1
	v_add_f32_dpp v56, v56, v56 row_ror:4 row_mask:0xf bank_mask:0xf bound_ctrl:1
	s_nop 1
	v_add_f32_dpp v56, v56, v56 row_ror:2 row_mask:0xf bank_mask:0xf bound_ctrl:1
	s_nop 1
	v_add_f32_dpp v56, v56, v56 row_ror:1 row_mask:0xf bank_mask:0xf bound_ctrl:1
	s_nop 0
	v_readlane_b32 s11, v56, 0
	v_readlane_b32 s70, v56, 16
	v_readlane_b32 s68, v56, 32
	v_readlane_b32 s69, v56, 48
	s_and_saveexec_b64 s[62:63], vcc
	s_cbranch_execz .LBB0_1816
	s_lshl_b64 s[34:35], s[34:35], 2
	v_mov_b32_e32 v56, s70
	s_add_u32 s34, s2, s34
	v_add_f32_e32 v56, s11, v56
	s_addc_u32 s35, s3, s35
	v_add_f32_e32 v56, s68, v56
	v_add_f32_e32 v58, s69, v56
	v_mov_b64_e32 v[56:57], s[34:35]
	flat_atomic_add_f32 v[56:57], v58
; DEVI float fsig(float x) { return __builtin_amdgcn_rcpf(1.f + __expf(-x)); }
; DEVI float bflo(unsigned u) { return __uint_as_float(u << 16); }
; DEVI float bfhi(unsigned u) { return __uint_as_float(u & 0xffff0000u); }
; template <int EPI, int TS, bool VT>
; DEVI void gemm_epilogue(const Params& p, char* smem, f32x4 (&acc)[2][2][4][2], int m0, int n0, float scale, const float* ssin,
;                         float* ssout, u16* xbout, int wid, int lane, int wr, int wc, int fr, int fq) {
;     ...
;         for (int u = 0; u < 8; ++u) {
;           const int i = i0 + u;
;           const int grow = g0 + i;
;           const float* Tr = T + (r0 + i) * TS;
;           const float rs = __int_as_float(__builtin_amdgcn_readlane(__float_as_int(rsv), i));
;           if constexpr (EPI == E_RESID || EPI == E_PLEGATE) {
;             const float4 a = *(const float4*)(Tr + 4 * lane);
;             const size_t ro = (size_t)grow * 1024 + n0 + 4 * lane;
;             float4 x4 = xo[u];
;             if constexpr (EPI == E_PLEGATE) {
;               x4.x += bflo(pv[u].x) * fsig(a.x * rs);
;               x4.y += bfhi(pv[u].x) * fsig(a.y * rs);
;               x4.z += bflo(pv[u].y) * fsig(a.z * rs);
;               x4.w += bfhi(pv[u].y) * fsig(a.w * rs);
;             } else {
;               const float sc = fabsf(scale);
;               x4.x += sc * a.x; x4.y += sc * a.y; x4.z += sc * a.z; x4.w += sc * a.w;
;             }
;             st_nt16(p.x + ro, x4);
;             if (xbout) {
;               uint2 o;
;               o.x = pack2(x4.x, x4.y);
;               o.y = pack2(x4.z, x4.w);
;               st_nt8(xbout + ro, o);
;             }
;             if (ssout) {
;               const float ssq = wsum(x4.x * x4.x + x4.y * x4.y + x4.z * x4.z + x4.w * x4.w, lane);
;               if (lane == 0) atomicAdd(ssout + grow, ssq);
;             }
.LBB0_1816:
	s_or_b64 exec, exec, s[62:63]
	ds_read_b128 v[56:59], v120 offset:1040
	v_lshl_add_u64 v[54:55], v[54:55], 1, s[6:7]
	s_waitcnt lgkmcnt(0)
	v_pk_fma_f32 v[24:25], v[56:57], 0.5, v[24:25] op_sel_hi:[1,0,1]
	v_pk_fma_f32 v[26:27], v[58:59], 0.5, v[26:27] op_sel_hi:[1,0,1]
	global_store_dwordx4 v[52:53], v[24:27], off
	v_cvt_pk_bf16_f32 v52, v24, v25
	v_cvt_pk_bf16_f32 v53, v26, v27
	v_pk_mul_f32 v[24:25], v[24:25], v[24:25]
	v_pk_mul_f32 v[26:27], v[26:27], v[26:27]
	v_add_f32_e32 v24, v24, v25
	v_add_f32_e32 v24, v24, v26
	v_add_f32_e32 v24, v24, v27
	flat_store_dwordx2 v[54:55], v[52:53]
	s_nop 0
	v_add_f32_dpp v24, v24, v24 row_ror:8 row_mask:0xf bank_mask:0xf bound_ctrl:1
	s_nop 1
	v_add_f32_dpp v24, v24, v24 row_ror:4 row_mask:0xf bank_mask:0xf bound_ctrl:1
	s_nop 1
	v_add_f32_dpp v24, v24, v24 row_ror:2 row_mask:0xf bank_mask:0xf bound_ctrl:1
	s_nop 1
	v_add_f32_dpp v24, v24, v24 row_ror:1 row_mask:0xf bank_mask:0xf bound_ctrl:1
	s_nop 0
	v_readlane_b32 s11, v24, 0
	v_readlane_b32 s68, v24, 16
	v_readlane_b32 s62, v24, 32
	v_readlane_b32 s63, v24, 48
	s_and_saveexec_b64 s[34:35], vcc
	s_cbranch_execz .LBB0_1818
	s_lshl_b64 s[30:31], s[30:31], 2
	v_mov_b32_e32 v24, s68
	s_add_u32 s30, s2, s30
	v_add_f32_e32 v24, s11, v24
	s_addc_u32 s31, s3, s31
	v_add_f32_e32 v24, s62, v24
	v_add_f32_e32 v26, s63, v24
	v_mov_b64_e32 v[24:25], s[30:31]
	flat_atomic_add_f32 v[24:25], v26
.LBB0_1818:
	s_or_b64 exec, exec, s[34:35]
	ds_read_b128 v[24:27], v120 offset:2080
	v_lshl_add_u64 v[50:51], v[50:51], 1, s[6:7]
	s_waitcnt lgkmcnt(0)
	v_pk_fma_f32 v[20:21], v[24:25], 0.5, v[20:21] op_sel_hi:[1,0,1]
	v_pk_fma_f32 v[22:23], v[26:27], 0.5, v[22:23] op_sel_hi:[1,0,1]
	global_store_dwordx4 v[48:49], v[20:23], off
	v_cvt_pk_bf16_f32 v24, v20, v21
	v_cvt_pk_bf16_f32 v25, v22, v23
	v_pk_mul_f32 v[20:21], v[20:21], v[20:21]
	v_pk_mul_f32 v[22:23], v[22:23], v[22:23]
	v_add_f32_e32 v20, v20, v21
	v_add_f32_e32 v20, v20, v22
	v_add_f32_e32 v20, v20, v23
	flat_store_dwordx2 v[50:51], v[24:25]
	s_nop 0
	v_add_f32_dpp v20, v20, v20 row_ror:8 row_mask:0xf bank_mask:0xf bound_ctrl:1
	s_nop 1
	v_add_f32_dpp v20, v20, v20 row_ror:4 row_mask:0xf bank_mask:0xf bound_ctrl:1
	s_nop 1
	v_add_f32_dpp v20, v20, v20 row_ror:2 row_mask:0xf bank_mask:0xf bound_ctrl:1
	s_nop 1
	v_add_f32_dpp v20, v20, v20 row_ror:1 row_mask:0xf bank_mask:0xf bound_ctrl:1
	s_nop 0
	v_readlane_b32 s11, v20, 0
	v_readlane_b32 s62, v20, 16
	v_readlane_b32 s34, v20, 32
	v_readlane_b32 s35, v20, 48
	s_and_saveexec_b64 s[30:31], vcc
	s_cbranch_execz .LBB0_1820
	s_lshl_b64 s[22:23], s[22:23], 2
	v_mov_b32_e32 v20, s62
	s_add_u32 s22, s2, s22
	v_add_f32_e32 v20, s11, v20
	s_addc_u32 s23, s3, s23
	v_add_f32_e32 v20, s34, v20
	v_add_f32_e32 v22, s35, v20
	v_mov_b64_e32 v[20:21], s[22:23]
	flat_atomic_add_f32 v[20:21], v22
.LBB0_1820:
	s_or_b64 exec, exec, s[30:31]
	ds_read_b128 v[20:23], v120 offset:3120
	v_lshl_add_u64 v[24:25], v[46:47], 1, s[6:7]
	s_waitcnt lgkmcnt(0)
	v_pk_fma_f32 v[16:17], v[20:21], 0.5, v[16:17] op_sel_hi:[1,0,1]
	v_pk_fma_f32 v[18:19], v[22:23], 0.5, v[18:19] op_sel_hi:[1,0,1]
	global_store_dwordx4 v[44:45], v[16:19], off
	v_cvt_pk_bf16_f32 v20, v16, v17
	v_cvt_pk_bf16_f32 v21, v18, v19
	v_pk_mul_f32 v[16:17], v[16:17], v[16:17]
	v_pk_mul_f32 v[18:19], v[18:19], v[18:19]
	v_add_f32_e32 v16, v16, v17
	v_add_f32_e32 v16, v16, v18
	v_add_f32_e32 v16, v16, v19
	flat_store_dwordx2 v[24:25], v[20:21]
	s_nop 0
	v_add_f32_dpp v16, v16, v16 row_ror:8 row_mask:0xf bank_mask:0xf bound_ctrl:1
	s_nop 1
	v_add_f32_dpp v16, v16, v16 row_ror:4 row_mask:0xf bank_mask:0xf bound_ctrl:1
	s_nop 1
	v_add_f32_dpp v16, v16, v16 row_ror:2 row_mask:0xf bank_mask:0xf bound_ctrl:1
	s_nop 1
	v_add_f32_dpp v16, v16, v16 row_ror:1 row_mask:0xf bank_mask:0xf bound_ctrl:1
	s_nop 0
	v_readlane_b32 s11, v16, 0
	v_readlane_b32 s34, v16, 16
	v_readlane_b32 s30, v16, 32
	v_readlane_b32 s31, v16, 48
	s_and_saveexec_b64 s[22:23], vcc
	s_cbranch_execz .LBB0_1822
	s_lshl_b64 s[20:21], s[20:21], 2
	v_mov_b32_e32 v16, s34
	s_add_u32 s20, s2, s20
	v_add_f32_e32 v16, s11, v16
	s_addc_u32 s21, s3, s21
	v_add_f32_e32 v16, s30, v16
	v_add_f32_e32 v18, s31, v16
	v_mov_b64_e32 v[16:17], s[20:21]
	flat_atomic_add_f32 v[16:17], v18
.LBB0_1822:
	s_or_b64 exec, exec, s[22:23]
	ds_read_b128 v[16:19], v120 offset:4160
	v_lshl_add_u64 v[20:21], v[42:43], 1, s[6:7]
	s_waitcnt lgkmcnt(0)
	v_pk_fma_f32 v[12:13], v[16:17], 0.5, v[12:13] op_sel_hi:[1,0,1]
	v_pk_fma_f32 v[14:15], v[18:19], 0.5, v[14:15] op_sel_hi:[1,0,1]
	global_store_dwordx4 v[40:41], v[12:15], off
	v_cvt_pk_bf16_f32 v16, v12, v13
	v_cvt_pk_bf16_f32 v17, v14, v15
	v_pk_mul_f32 v[12:13], v[12:13], v[12:13]
	v_pk_mul_f32 v[14:15], v[14:15], v[14:15]
	v_add_f32_e32 v12, v12, v13
	v_add_f32_e32 v12, v12, v14
	v_add_f32_e32 v12, v12, v15
	flat_store_dwordx2 v[20:21], v[16:17]
	s_nop 0
	v_add_f32_dpp v12, v12, v12 row_ror:8 row_mask:0xf bank_mask:0xf bound_ctrl:1
	s_nop 1
	v_add_f32_dpp v12, v12, v12 row_ror:4 row_mask:0xf bank_mask:0xf bound_ctrl:1
	s_nop 1
	v_add_f32_dpp v12, v12, v12 row_ror:2 row_mask:0xf bank_mask:0xf bound_ctrl:1
	s_nop 1
	v_add_f32_dpp v12, v12, v12 row_ror:1 row_mask:0xf bank_mask:0xf bound_ctrl:1
	s_nop 0
	v_readlane_b32 s11, v12, 0
	v_readlane_b32 s30, v12, 16
	v_readlane_b32 s22, v12, 32
	v_readlane_b32 s23, v12, 48
	s_and_saveexec_b64 s[20:21], vcc
	s_cbranch_execz .LBB0_1824
	s_lshl_b64 s[18:19], s[18:19], 2
	v_mov_b32_e32 v12, s30
	s_add_u32 s18, s2, s18
	v_add_f32_e32 v12, s11, v12
	s_addc_u32 s19, s3, s19
	v_add_f32_e32 v12, s22, v12
	v_add_f32_e32 v14, s23, v12
	v_mov_b64_e32 v[12:13], s[18:19]
	flat_atomic_add_f32 v[12:13], v14
; template <int EPI, int TS, bool VT>
; DEVI void gemm_epilogue(const Params& p, char* smem, f32x4 (&acc)[2][2][4][2], int m0, int n0, float scale, const float* ssin,
;                         float* ssout, u16* xbout, int wid, int lane, int wr, int wc, int fr, int fq) {
;     ...
;           for (int u = 0; u < 8; ++u) {
;             const size_t ro = (size_t)(g0 + i0 + u) * 1024 + n0 + 4 * lane;
;             const int gr = g0 + i0 + u;
;             const float* xs = p.x + ro;
;             if (scale < 0.f)
;               xs = (gr < MP ? p.x_prompt + ro : p.x_sample + (ro - (size_t)MP * 1024));
;             { const f32x4 t_ = __builtin_nontemporal_load((const f32x4*)xs); xo[u] = make_float4(t_[0], t_[1], t_[2], t_[3]); }
;             if constexpr (EPI == E_PLEGATE) {
;               const unsigned long long t2_ = __builtin_nontemporal_load((const unsigned long long*)((const u16*)(wsb + OFF_PP) + ro));
;               pv[u] = make_uint2((unsigned)t2_, (unsigned)(t2_ >> 32));
;             }
;           }
;         }
; #pragma unroll
;         for (int u = 0; u < 8; ++u) {
;           const int i = i0 + u;
;           const int grow = g0 + i;
;           const float* Tr = T + (r0 + i) * TS;
;           const float rs = __int_as_float(__builtin_amdgcn_readlane(__float_as_int(rsv), i));
;           if constexpr (EPI == E_RESID || EPI == E_PLEGATE) {
;             const float4 a = *(const float4*)(Tr + 4 * lane);
;             const size_t ro = (size_t)grow * 1024 + n0 + 4 * lane;
;             float4 x4 = xo[u];
;             if constexpr (EPI == E_PLEGATE) {
;               x4.x += bflo(pv[u].x) * fsig(a.x * rs);
;               x4.y += bfhi(pv[u].x) * fsig(a.y * rs);
;               x4.z += bflo(pv[u].y) * fsig(a.z * rs);
;               x4.w += bfhi(pv[u].y) * fsig(a.w * rs);
;             } else {
;               const float sc = fabsf(scale);
;               x4.x += sc * a.x; x4.y += sc * a.y; x4.z += sc * a.z; x4.w += sc * a.w;
;             }
;             st_nt16(p.x + ro, x4);
;             if (xbout) {
;               uint2 o;
;               o.x = pack2(x4.x, x4.y);
;               o.y = pack2(x4.z, x4.w);
;               st_nt8(xbout + ro, o);
;             }
;             if (ssout) {
;               const float ssq = wsum(x4.x * x4.x + x4.y * x4.y + x4.z * x4.z + x4.w * x4.w, lane);
;               if (lane == 0) atomicAdd(ssout + grow, ssq);
.LBB0_1824:
	s_or_b64 exec, exec, s[20:21]
	ds_read_b128 v[12:15], v120 offset:5200
	v_lshl_add_u64 v[16:17], v[38:39], 1, s[6:7]
	s_waitcnt lgkmcnt(0)
	v_pk_fma_f32 v[8:9], v[12:13], 0.5, v[8:9] op_sel_hi:[1,0,1]
	v_pk_fma_f32 v[10:11], v[14:15], 0.5, v[10:11] op_sel_hi:[1,0,1]
	global_store_dwordx4 v[36:37], v[8:11], off
	v_cvt_pk_bf16_f32 v12, v8, v9
	v_cvt_pk_bf16_f32 v13, v10, v11
	v_pk_mul_f32 v[8:9], v[8:9], v[8:9]
	v_pk_mul_f32 v[10:11], v[10:11], v[10:11]
	v_add_f32_e32 v8, v8, v9
	v_add_f32_e32 v8, v8, v10
	v_add_f32_e32 v8, v8, v11
	flat_store_dwordx2 v[16:17], v[12:13]
	s_nop 0
	v_add_f32_dpp v8, v8, v8 row_ror:8 row_mask:0xf bank_mask:0xf bound_ctrl:1
	s_nop 1
	v_add_f32_dpp v8, v8, v8 row_ror:4 row_mask:0xf bank_mask:0xf bound_ctrl:1
	s_nop 1
	v_add_f32_dpp v8, v8, v8 row_ror:2 row_mask:0xf bank_mask:0xf bound_ctrl:1
	s_nop 1
	v_add_f32_dpp v8, v8, v8 row_ror:1 row_mask:0xf bank_mask:0xf bound_ctrl:1
	s_nop 0
	v_readlane_b32 s11, v8, 0
	v_readlane_b32 s22, v8, 16
	v_readlane_b32 s20, v8, 32
	v_readlane_b32 s21, v8, 48
	s_and_saveexec_b64 s[18:19], vcc
	s_cbranch_execz .LBB0_1826
	s_lshl_b64 s[16:17], s[16:17], 2
	v_mov_b32_e32 v8, s22
	s_add_u32 s16, s2, s16
	v_add_f32_e32 v8, s11, v8
	s_addc_u32 s17, s3, s17
	v_add_f32_e32 v8, s20, v8
	v_add_f32_e32 v10, s21, v8
	v_mov_b64_e32 v[8:9], s[16:17]
	flat_atomic_add_f32 v[8:9], v10
.LBB0_1826:
	s_or_b64 exec, exec, s[18:19]
	ds_read_b128 v[8:11], v120 offset:6240
	v_lshl_add_u64 v[12:13], v[34:35], 1, s[6:7]
	s_waitcnt lgkmcnt(0)
	v_pk_fma_f32 v[4:5], v[8:9], 0.5, v[4:5] op_sel_hi:[1,0,1]
	v_pk_fma_f32 v[6:7], v[10:11], 0.5, v[6:7] op_sel_hi:[1,0,1]
	global_store_dwordx4 v[32:33], v[4:7], off
	v_cvt_pk_bf16_f32 v8, v4, v5
	v_cvt_pk_bf16_f32 v9, v6, v7
	v_pk_mul_f32 v[4:5], v[4:5], v[4:5]
	v_pk_mul_f32 v[6:7], v[6:7], v[6:7]
	v_add_f32_e32 v4, v4, v5
	v_add_f32_e32 v4, v4, v6
	v_add_f32_e32 v4, v4, v7
	flat_store_dwordx2 v[12:13], v[8:9]
	s_nop 0
	v_add_f32_dpp v4, v4, v4 row_ror:8 row_mask:0xf bank_mask:0xf bound_ctrl:1
	s_nop 1
	v_add_f32_dpp v4, v4, v4 row_ror:4 row_mask:0xf bank_mask:0xf bound_ctrl:1
	s_nop 1
	v_add_f32_dpp v4, v4, v4 row_ror:2 row_mask:0xf bank_mask:0xf bound_ctrl:1
	s_nop 1
	v_add_f32_dpp v4, v4, v4 row_ror:1 row_mask:0xf bank_mask:0xf bound_ctrl:1
	s_nop 0
	v_readlane_b32 s11, v4, 0
	v_readlane_b32 s20, v4, 16
	v_readlane_b32 s18, v4, 32
	v_readlane_b32 s19, v4, 48
	s_and_saveexec_b64 s[16:17], vcc
	s_cbranch_execz .LBB0_1828
	s_lshl_b64 s[14:15], s[14:15], 2
	v_mov_b32_e32 v4, s20
	s_add_u32 s14, s2, s14
	v_add_f32_e32 v4, s11, v4
	s_addc_u32 s15, s3, s15
	v_add_f32_e32 v4, s18, v4
	v_add_f32_e32 v6, s19, v4
	v_mov_b64_e32 v[4:5], s[14:15]
	flat_atomic_add_f32 v[4:5], v6
.LBB0_1828:
	s_or_b64 exec, exec, s[16:17]
	ds_read_b128 v[4:7], v120 offset:7280
	v_lshl_add_u64 v[8:9], v[30:31], 1, s[6:7]
	s_waitcnt lgkmcnt(0)
	v_pk_fma_f32 v[0:1], v[4:5], 0.5, v[0:1] op_sel_hi:[1,0,1]
	v_pk_fma_f32 v[2:3], v[6:7], 0.5, v[2:3] op_sel_hi:[1,0,1]
	global_store_dwordx4 v[28:29], v[0:3], off
	v_cvt_pk_bf16_f32 v4, v0, v1
	v_cvt_pk_bf16_f32 v5, v2, v3
	v_pk_mul_f32 v[0:1], v[0:1], v[0:1]
	v_pk_mul_f32 v[2:3], v[2:3], v[2:3]
	v_add_f32_e32 v0, v0, v1
	v_add_f32_e32 v0, v0, v2
	v_add_f32_e32 v0, v0, v3
	flat_store_dwordx2 v[8:9], v[4:5]
	s_nop 0
	v_add_f32_dpp v0, v0, v0 row_ror:8 row_mask:0xf bank_mask:0xf bound_ctrl:1
	s_nop 1
	v_add_f32_dpp v0, v0, v0 row_ror:4 row_mask:0xf bank_mask:0xf bound_ctrl:1
	s_nop 1
	v_add_f32_dpp v0, v0, v0 row_ror:2 row_mask:0xf bank_mask:0xf bound_ctrl:1
	s_nop 1
	v_add_f32_dpp v0, v0, v0 row_ror:1 row_mask:0xf bank_mask:0xf bound_ctrl:1
	s_nop 0
	v_readlane_b32 s11, v0, 0
	v_readlane_b32 s18, v0, 16
	v_readlane_b32 s16, v0, 32
	v_readlane_b32 s17, v0, 48
	s_and_saveexec_b64 s[14:15], vcc
	s_cbranch_execz .LBB0_1830
	s_lshl_b64 s[12:13], s[12:13], 2
	v_mov_b32_e32 v0, s18
	s_add_u32 s12, s2, s12
	v_add_f32_e32 v0, s11, v0
	s_addc_u32 s13, s3, s13
	v_add_f32_e32 v0, s16, v0
	v_add_f32_e32 v2, s17, v0
	v_mov_b64_e32 v[0:1], s[12:13]
	flat_atomic_add_f32 v[0:1], v2
.LBB0_1830:
	s_or_b64 exec, exec, s[14:15]
	s_add_i32 s30, s10, 0x88
	s_ashr_i32 s31, s30, 31
	s_lshl_b64 s[12:13], s[30:31], 10
	s_add_i32 s22, s10, 0x89
	v_lshl_add_u64 v[64:65], s[12:13], 0, v[128:129]
	s_ashr_i32 s23, s22, 31
	s_add_i32 s20, s10, 0x8a
	v_lshl_add_u64 v[66:67], v[64:65], 2, s[38:39]
	s_lshl_b64 s[12:13], s[22:23], 10
	s_ashr_i32 s21, s20, 31
	s_add_i32 s18, s10, 0x8b
	global_load_dwordx4 v[56:59], v[66:67], off
	v_lshl_add_u64 v[54:55], s[12:13], 0, v[128:129]
	s_lshl_b64 s[12:13], s[20:21], 10
	s_ashr_i32 s19, s18, 31
	s_add_i32 s16, s10, 0x8c
	v_lshl_add_u64 v[50:51], s[12:13], 0, v[128:129]
	s_lshl_b64 s[12:13], s[18:19], 10
	s_ashr_i32 s17, s16, 31
	s_add_i32 s14, s10, 0x8d
	v_lshl_add_u64 v[46:47], s[12:13], 0, v[128:129]
	s_lshl_b64 s[12:13], s[16:17], 10
	s_ashr_i32 s15, s14, 31
	v_lshl_add_u64 v[42:43], s[12:13], 0, v[128:129]
	s_lshl_b64 s[12:13], s[14:15], 10
	v_lshl_add_u64 v[38:39], s[12:13], 0, v[128:129]
	s_add_i32 s12, s10, 0x8e
	s_ashr_i32 s13, s12, 31
	s_addk_i32 s10, 0x8f
	s_lshl_b64 s[34:35], s[12:13], 10
	s_ashr_i32 s11, s10, 31
	v_lshl_add_u64 v[34:35], s[34:35], 0, v[128:129]
	s_lshl_b64 s[34:35], s[10:11], 10
	v_lshl_add_u64 v[30:31], s[34:35], 0, v[128:129]
	v_lshl_add_u64 v[52:53], v[54:55], 2, s[38:39]
	v_lshl_add_u64 v[44:45], v[46:47], 2, s[38:39]
	v_lshl_add_u64 v[36:37], v[38:39], 2, s[38:39]
	v_lshl_add_u64 v[28:29], v[30:31], 2, s[38:39]
	v_lshl_add_u64 v[48:49], v[50:51], 2, s[38:39]
	global_load_dwordx4 v[24:27], v[52:53], off
	global_load_dwordx4 v[20:23], v[48:49], off
	v_lshl_add_u64 v[40:41], v[42:43], 2, s[38:39]
	global_load_dwordx4 v[16:19], v[44:45], off
	global_load_dwordx4 v[12:15], v[40:41], off
	v_lshl_add_u64 v[32:33], v[34:35], 2, s[38:39]
	global_load_dwordx4 v[8:11], v[36:37], off
	global_load_dwordx4 v[4:7], v[32:33], off
	global_load_dwordx4 v[0:3], v[28:29], off
	ds_read_b128 v[60:63], v120 offset:8320
	v_lshl_add_u64 v[64:65], v[64:65], 1, s[6:7]
	s_waitcnt vmcnt(0) lgkmcnt(0)
	v_pk_fma_f32 v[56:57], v[60:61], 0.5, v[56:57] op_sel_hi:[1,0,1]
	v_pk_fma_f32 v[58:59], v[62:63], 0.5, v[58:59] op_sel_hi:[1,0,1]
	global_store_dwordx4 v[66:67], v[56:59], off
	v_cvt_pk_bf16_f32 v60, v56, v57
	v_cvt_pk_bf16_f32 v61, v58, v59
	v_pk_mul_f32 v[56:57], v[56:57], v[56:57]
	v_pk_mul_f32 v[58:59], v[58:59], v[58:59]
	v_add_f32_e32 v56, v56, v57
	v_add_f32_e32 v56, v56, v58
	v_add_f32_e32 v56, v56, v59
	flat_store_dwordx2 v[64:65], v[60:61]
	s_nop 0
	v_add_f32_dpp v56, v56, v56 row_ror:8 row_mask:0xf bank_mask:0xf bound_ctrl:1
	s_nop 1
	v_add_f32_dpp v56, v56, v56 row_ror:4 row_mask:0xf bank_mask:0xf bound_ctrl:1
	s_nop 1
	v_add_f32_dpp v56, v56, v56 row_ror:2 row_mask:0xf bank_mask:0xf bound_ctrl:1
	s_nop 1
	v_add_f32_dpp v56, v56, v56 row_ror:1 row_mask:0xf bank_mask:0xf bound_ctrl:1
	s_nop 0
	v_readlane_b32 s62, v56, 0
	v_readlane_b32 s69, v56, 16
	v_readlane_b32 s63, v56, 32
	v_readlane_b32 s68, v56, 48
	s_and_saveexec_b64 s[34:35], vcc
	s_cbranch_execz .LBB0_1832
; DEVI float fsig(float x) { return __builtin_amdgcn_rcpf(1.f + __expf(-x)); }
; DEVI float bflo(unsigned u) { return __uint_as_float(u << 16); }
; DEVI float bfhi(unsigned u) { return __uint_as_float(u & 0xffff0000u); }
; template <int EPI, int TS, bool VT>
; DEVI void gemm_epilogue(const Params& p, char* smem, f32x4 (&acc)[2][2][4][2], int m0, int n0, float scale, const float* ssin,
;                         float* ssout, u16* xbout, int wid, int lane, int wr, int wc, int fr, int fq) {
;     ...
;           if constexpr (EPI == E_RESID || EPI == E_PLEGATE) {
;             const float4 a = *(const float4*)(Tr + 4 * lane);
;             const size_t ro = (size_t)grow * 1024 + n0 + 4 * lane;
;             float4 x4 = xo[u];
;             if constexpr (EPI == E_PLEGATE) {
;               x4.x += bflo(pv[u].x) * fsig(a.x * rs);
;               x4.y += bfhi(pv[u].x) * fsig(a.y * rs);
;               x4.z += bflo(pv[u].y) * fsig(a.z * rs);
;               x4.w += bfhi(pv[u].y) * fsig(a.w * rs);
;             } else {
;               const float sc = fabsf(scale);
;               x4.x += sc * a.x; x4.y += sc * a.y; x4.z += sc * a.z; x4.w += sc * a.w;
;             }
;             st_nt16(p.x + ro, x4);
;             if (xbout) {
;               uint2 o;
;               o.x = pack2(x4.x, x4.y);
;               o.y = pack2(x4.z, x4.w);
;               st_nt8(xbout + ro, o);
;             }
;             if (ssout) {
;               const float ssq = wsum(x4.x * x4.x + x4.y * x4.y + x4.z * x4.z + x4.w * x4.w, lane);
;               if (lane == 0) atomicAdd(ssout + grow, ssq);
;             }
	s_lshl_b64 s[30:31], s[30:31], 2
	v_mov_b32_e32 v56, s69
	s_add_u32 s30, s2, s30
	v_add_f32_e32 v56, s62, v56
	s_addc_u32 s31, s3, s31
	v_add_f32_e32 v56, s63, v56
	v_add_f32_e32 v58, s68, v56
	v_mov_b64_e32 v[56:57], s[30:31]
	flat_atomic_add_f32 v[56:57], v58
.LBB0_1832:
	s_or_b64 exec, exec, s[34:35]
	ds_read_b128 v[56:59], v120 offset:9360
	v_lshl_add_u64 v[54:55], v[54:55], 1, s[6:7]
	s_waitcnt lgkmcnt(0)
	v_pk_fma_f32 v[24:25], v[56:57], 0.5, v[24:25] op_sel_hi:[1,0,1]
	v_pk_fma_f32 v[26:27], v[58:59], 0.5, v[26:27] op_sel_hi:[1,0,1]
	global_store_dwordx4 v[52:53], v[24:27], off
	v_cvt_pk_bf16_f32 v52, v24, v25
	v_cvt_pk_bf16_f32 v53, v26, v27
	v_pk_mul_f32 v[24:25], v[24:25], v[24:25]
	v_pk_mul_f32 v[26:27], v[26:27], v[26:27]
	v_add_f32_e32 v24, v24, v25
	v_add_f32_e32 v24, v24, v26
	v_add_f32_e32 v24, v24, v27
	flat_store_dwordx2 v[54:55], v[52:53]
	s_nop 0
	v_add_f32_dpp v24, v24, v24 row_ror:8 row_mask:0xf bank_mask:0xf bound_ctrl:1
	s_nop 1
	v_add_f32_dpp v24, v24, v24 row_ror:4 row_mask:0xf bank_mask:0xf bound_ctrl:1
	s_nop 1
	v_add_f32_dpp v24, v24, v24 row_ror:2 row_mask:0xf bank_mask:0xf bound_ctrl:1
	s_nop 1
	v_add_f32_dpp v24, v24, v24 row_ror:1 row_mask:0xf bank_mask:0xf bound_ctrl:1
	s_nop 0
	v_readlane_b32 s34, v24, 0
	v_readlane_b32 s63, v24, 16
	v_readlane_b32 s35, v24, 32
	v_readlane_b32 s62, v24, 48
	s_and_saveexec_b64 s[30:31], vcc
	s_cbranch_execz .LBB0_1834
	s_lshl_b64 s[22:23], s[22:23], 2
	v_mov_b32_e32 v24, s63
	s_add_u32 s22, s2, s22
	v_add_f32_e32 v24, s34, v24
	s_addc_u32 s23, s3, s23
	v_add_f32_e32 v24, s35, v24
	v_add_f32_e32 v26, s62, v24
	v_mov_b64_e32 v[24:25], s[22:23]
	flat_atomic_add_f32 v[24:25], v26
.LBB0_1834:
	s_or_b64 exec, exec, s[30:31]
	ds_read_b128 v[24:27], v120 offset:10400
	v_lshl_add_u64 v[50:51], v[50:51], 1, s[6:7]
	s_waitcnt lgkmcnt(0)
	v_pk_fma_f32 v[20:21], v[24:25], 0.5, v[20:21] op_sel_hi:[1,0,1]
	v_pk_fma_f32 v[22:23], v[26:27], 0.5, v[22:23] op_sel_hi:[1,0,1]
	global_store_dwordx4 v[48:49], v[20:23], off
	v_cvt_pk_bf16_f32 v24, v20, v21
	v_cvt_pk_bf16_f32 v25, v22, v23
	v_pk_mul_f32 v[20:21], v[20:21], v[20:21]
	v_pk_mul_f32 v[22:23], v[22:23], v[22:23]
	v_add_f32_e32 v20, v20, v21
	v_add_f32_e32 v20, v20, v22
	v_add_f32_e32 v20, v20, v23
	flat_store_dwordx2 v[50:51], v[24:25]
	s_nop 0
	v_add_f32_dpp v20, v20, v20 row_ror:8 row_mask:0xf bank_mask:0xf bound_ctrl:1
	s_nop 1
	v_add_f32_dpp v20, v20, v20 row_ror:4 row_mask:0xf bank_mask:0xf bound_ctrl:1
	s_nop 1
	v_add_f32_dpp v20, v20, v20 row_ror:2 row_mask:0xf bank_mask:0xf bound_ctrl:1
	s_nop 1
	v_add_f32_dpp v20, v20, v20 row_ror:1 row_mask:0xf bank_mask:0xf bound_ctrl:1
	s_nop 0
	v_readlane_b32 s30, v20, 0
	v_readlane_b32 s35, v20, 16
	v_readlane_b32 s31, v20, 32
	v_readlane_b32 s34, v20, 48
	s_and_saveexec_b64 s[22:23], vcc
	s_cbranch_execz .LBB0_1836
	s_lshl_b64 s[20:21], s[20:21], 2
	v_mov_b32_e32 v20, s35
	s_add_u32 s20, s2, s20
	v_add_f32_e32 v20, s30, v20
	s_addc_u32 s21, s3, s21
	v_add_f32_e32 v20, s31, v20
	v_add_f32_e32 v22, s34, v20
	v_mov_b64_e32 v[20:21], s[20:21]
	flat_atomic_add_f32 v[20:21], v22
.LBB0_1836:
	s_or_b64 exec, exec, s[22:23]
	ds_read_b128 v[20:23], v120 offset:11440
	v_lshl_add_u64 v[24:25], v[46:47], 1, s[6:7]
	s_waitcnt lgkmcnt(0)
	v_pk_fma_f32 v[16:17], v[20:21], 0.5, v[16:17] op_sel_hi:[1,0,1]
	v_pk_fma_f32 v[18:19], v[22:23], 0.5, v[18:19] op_sel_hi:[1,0,1]
	global_store_dwordx4 v[44:45], v[16:19], off
	v_cvt_pk_bf16_f32 v20, v16, v17
	v_cvt_pk_bf16_f32 v21, v18, v19
	v_pk_mul_f32 v[16:17], v[16:17], v[16:17]
	v_pk_mul_f32 v[18:19], v[18:19], v[18:19]
	v_add_f32_e32 v16, v16, v17
	v_add_f32_e32 v16, v16, v18
	v_add_f32_e32 v16, v16, v19
	flat_store_dwordx2 v[24:25], v[20:21]
	s_nop 0
	v_add_f32_dpp v16, v16, v16 row_ror:8 row_mask:0xf bank_mask:0xf bound_ctrl:1
	s_nop 1
	v_add_f32_dpp v16, v16, v16 row_ror:4 row_mask:0xf bank_mask:0xf bound_ctrl:1
	s_nop 1
	v_add_f32_dpp v16, v16, v16 row_ror:2 row_mask:0xf bank_mask:0xf bound_ctrl:1
	s_nop 1
	v_add_f32_dpp v16, v16, v16 row_ror:1 row_mask:0xf bank_mask:0xf bound_ctrl:1
	s_nop 0
	v_readlane_b32 s22, v16, 0
	v_readlane_b32 s31, v16, 16
	v_readlane_b32 s23, v16, 32
	v_readlane_b32 s30, v16, 48
	s_and_saveexec_b64 s[20:21], vcc
	s_cbranch_execz .LBB0_1838
	s_lshl_b64 s[18:19], s[18:19], 2
	v_mov_b32_e32 v16, s31
	s_add_u32 s18, s2, s18
	v_add_f32_e32 v16, s22, v16
	s_addc_u32 s19, s3, s19
	v_add_f32_e32 v16, s23, v16
	v_add_f32_e32 v18, s30, v16
	v_mov_b64_e32 v[16:17], s[18:19]
	flat_atomic_add_f32 v[16:17], v18
; DEVI float fsig(float x) { return __builtin_amdgcn_rcpf(1.f + __expf(-x)); }
; DEVI float bflo(unsigned u) { return __uint_as_float(u << 16); }
; DEVI float bfhi(unsigned u) { return __uint_as_float(u & 0xffff0000u); }
; template <int EPI, int TS, bool VT>
; DEVI void gemm_epilogue(const Params& p, char* smem, f32x4 (&acc)[2][2][4][2], int m0, int n0, float scale, const float* ssin,
;                         float* ssout, u16* xbout, int wid, int lane, int wr, int wc, int fr, int fq) {
;     ...
;           if constexpr (EPI == E_RESID || EPI == E_PLEGATE) {
;             const float4 a = *(const float4*)(Tr + 4 * lane);
;             const size_t ro = (size_t)grow * 1024 + n0 + 4 * lane;
;             float4 x4 = xo[u];
;             if constexpr (EPI == E_PLEGATE) {
;               x4.x += bflo(pv[u].x) * fsig(a.x * rs);
;               x4.y += bfhi(pv[u].x) * fsig(a.y * rs);
;               x4.z += bflo(pv[u].y) * fsig(a.z * rs);
;               x4.w += bfhi(pv[u].y) * fsig(a.w * rs);
;             } else {
;               const float sc = fabsf(scale);
;               x4.x += sc * a.x; x4.y += sc * a.y; x4.z += sc * a.z; x4.w += sc * a.w;
;             }
;             st_nt16(p.x + ro, x4);
;             if (xbout) {
;               uint2 o;
;               o.x = pack2(x4.x, x4.y);
;               o.y = pack2(x4.z, x4.w);
;               st_nt8(xbout + ro, o);
;             }
;             if (ssout) {
;               const float ssq = wsum(x4.x * x4.x + x4.y * x4.y + x4.z * x4.z + x4.w * x4.w, lane);
;               if (lane == 0) atomicAdd(ssout + grow, ssq);
;             }
.LBB0_1838:
	s_or_b64 exec, exec, s[20:21]
	ds_read_b128 v[16:19], v120 offset:12480
	v_lshl_add_u64 v[20:21], v[42:43], 1, s[6:7]
	s_waitcnt lgkmcnt(0)
	v_pk_fma_f32 v[12:13], v[16:17], 0.5, v[12:13] op_sel_hi:[1,0,1]
	v_pk_fma_f32 v[14:15], v[18:19], 0.5, v[14:15] op_sel_hi:[1,0,1]
	global_store_dwordx4 v[40:41], v[12:15], off
	v_cvt_pk_bf16_f32 v16, v12, v13
	v_cvt_pk_bf16_f32 v17, v14, v15
	v_pk_mul_f32 v[12:13], v[12:13], v[12:13]
	v_pk_mul_f32 v[14:15], v[14:15], v[14:15]
	v_add_f32_e32 v12, v12, v13
	v_add_f32_e32 v12, v12, v14
	v_add_f32_e32 v12, v12, v15
	flat_store_dwordx2 v[20:21], v[16:17]
	s_nop 0
	v_add_f32_dpp v12, v12, v12 row_ror:8 row_mask:0xf bank_mask:0xf bound_ctrl:1
	s_nop 1
	v_add_f32_dpp v12, v12, v12 row_ror:4 row_mask:0xf bank_mask:0xf bound_ctrl:1
	s_nop 1
	v_add_f32_dpp v12, v12, v12 row_ror:2 row_mask:0xf bank_mask:0xf bound_ctrl:1
	s_nop 1
	v_add_f32_dpp v12, v12, v12 row_ror:1 row_mask:0xf bank_mask:0xf bound_ctrl:1
	s_nop 0
	v_readlane_b32 s20, v12, 0
	v_readlane_b32 s23, v12, 16
	v_readlane_b32 s21, v12, 32
	v_readlane_b32 s22, v12, 48
	s_and_saveexec_b64 s[18:19], vcc
	s_cbranch_execz .LBB0_1840
	s_lshl_b64 s[16:17], s[16:17], 2
	v_mov_b32_e32 v12, s23
	s_add_u32 s16, s2, s16
	v_add_f32_e32 v12, s20, v12
	s_addc_u32 s17, s3, s17
	v_add_f32_e32 v12, s21, v12
	v_add_f32_e32 v14, s22, v12
	v_mov_b64_e32 v[12:13], s[16:17]
	flat_atomic_add_f32 v[12:13], v14
.LBB0_1840:
	s_or_b64 exec, exec, s[18:19]
	ds_read_b128 v[12:15], v120 offset:13520
	v_lshl_add_u64 v[16:17], v[38:39], 1, s[6:7]
	s_waitcnt lgkmcnt(0)
	v_pk_fma_f32 v[8:9], v[12:13], 0.5, v[8:9] op_sel_hi:[1,0,1]
	v_pk_fma_f32 v[10:11], v[14:15], 0.5, v[10:11] op_sel_hi:[1,0,1]
	global_store_dwordx4 v[36:37], v[8:11], off
	v_cvt_pk_bf16_f32 v12, v8, v9
	v_cvt_pk_bf16_f32 v13, v10, v11
	v_pk_mul_f32 v[8:9], v[8:9], v[8:9]
	v_pk_mul_f32 v[10:11], v[10:11], v[10:11]
	v_add_f32_e32 v8, v8, v9
	v_add_f32_e32 v8, v8, v10
	v_add_f32_e32 v8, v8, v11
	flat_store_dwordx2 v[16:17], v[12:13]
	s_nop 0
	v_add_f32_dpp v8, v8, v8 row_ror:8 row_mask:0xf bank_mask:0xf bound_ctrl:1
	s_nop 1
	v_add_f32_dpp v8, v8, v8 row_ror:4 row_mask:0xf bank_mask:0xf bound_ctrl:1
	s_nop 1
	v_add_f32_dpp v8, v8, v8 row_ror:2 row_mask:0xf bank_mask:0xf bound_ctrl:1
	s_nop 1
	v_add_f32_dpp v8, v8, v8 row_ror:1 row_mask:0xf bank_mask:0xf bound_ctrl:1
	s_nop 0
	v_readlane_b32 s18, v8, 0
	v_readlane_b32 s21, v8, 16
	v_readlane_b32 s19, v8, 32
	v_readlane_b32 s20, v8, 48
	s_and_saveexec_b64 s[16:17], vcc
	s_cbranch_execz .LBB0_1842
	s_lshl_b64 s[14:15], s[14:15], 2
	v_mov_b32_e32 v8, s21
	s_add_u32 s14, s2, s14
	v_add_f32_e32 v8, s18, v8
	s_addc_u32 s15, s3, s15
	v_add_f32_e32 v8, s19, v8
	v_add_f32_e32 v10, s20, v8
	v_mov_b64_e32 v[8:9], s[14:15]
	flat_atomic_add_f32 v[8:9], v10
.LBB0_1842:
	s_or_b64 exec, exec, s[16:17]
	ds_read_b128 v[8:11], v120 offset:14560
	v_lshl_add_u64 v[12:13], v[34:35], 1, s[6:7]
	s_waitcnt lgkmcnt(0)
	v_pk_fma_f32 v[4:5], v[8:9], 0.5, v[4:5] op_sel_hi:[1,0,1]
	v_pk_fma_f32 v[6:7], v[10:11], 0.5, v[6:7] op_sel_hi:[1,0,1]
	global_store_dwordx4 v[32:33], v[4:7], off
	v_cvt_pk_bf16_f32 v8, v4, v5
	v_cvt_pk_bf16_f32 v9, v6, v7
	v_pk_mul_f32 v[4:5], v[4:5], v[4:5]
	v_pk_mul_f32 v[6:7], v[6:7], v[6:7]
	v_add_f32_e32 v4, v4, v5
	v_add_f32_e32 v4, v4, v6
	v_add_f32_e32 v4, v4, v7
	flat_store_dwordx2 v[12:13], v[8:9]
	s_nop 0
	v_add_f32_dpp v4, v4, v4 row_ror:8 row_mask:0xf bank_mask:0xf bound_ctrl:1
	s_nop 1
	v_add_f32_dpp v4, v4, v4 row_ror:4 row_mask:0xf bank_mask:0xf bound_ctrl:1
	s_nop 1
	v_add_f32_dpp v4, v4, v4 row_ror:2 row_mask:0xf bank_mask:0xf bound_ctrl:1
	s_nop 1
	v_add_f32_dpp v4, v4, v4 row_ror:1 row_mask:0xf bank_mask:0xf bound_ctrl:1
	s_nop 0
	v_readlane_b32 s16, v4, 0
	v_readlane_b32 s19, v4, 16
	v_readlane_b32 s17, v4, 32
	v_readlane_b32 s18, v4, 48
	s_and_saveexec_b64 s[14:15], vcc
	s_cbranch_execz .LBB0_1844
	s_lshl_b64 s[12:13], s[12:13], 2
	v_mov_b32_e32 v4, s19
	s_add_u32 s12, s2, s12
	v_add_f32_e32 v4, s16, v4
	s_addc_u32 s13, s3, s13
	v_add_f32_e32 v4, s17, v4
	v_add_f32_e32 v6, s18, v4
	v_mov_b64_e32 v[4:5], s[12:13]
	flat_atomic_add_f32 v[4:5], v6
.LBB0_1844:
	s_or_b64 exec, exec, s[14:15]
	ds_read_b128 v[4:7], v120 offset:15600
	v_lshl_add_u64 v[8:9], v[30:31], 1, s[6:7]
	s_waitcnt lgkmcnt(0)
	v_pk_fma_f32 v[0:1], v[4:5], 0.5, v[0:1] op_sel_hi:[1,0,1]
	v_pk_fma_f32 v[2:3], v[6:7], 0.5, v[2:3] op_sel_hi:[1,0,1]
	global_store_dwordx4 v[28:29], v[0:3], off
	v_cvt_pk_bf16_f32 v4, v0, v1
	v_cvt_pk_bf16_f32 v5, v2, v3
	v_pk_mul_f32 v[0:1], v[0:1], v[0:1]
	v_pk_mul_f32 v[2:3], v[2:3], v[2:3]
	v_add_f32_e32 v0, v0, v1
	v_add_f32_e32 v0, v0, v2
	v_add_f32_e32 v0, v0, v3
	flat_store_dwordx2 v[8:9], v[4:5]
	s_nop 0
	v_add_f32_dpp v0, v0, v0 row_ror:8 row_mask:0xf bank_mask:0xf bound_ctrl:1
	s_nop 1
	v_add_f32_dpp v0, v0, v0 row_ror:4 row_mask:0xf bank_mask:0xf bound_ctrl:1
	s_nop 1
	v_add_f32_dpp v0, v0, v0 row_ror:2 row_mask:0xf bank_mask:0xf bound_ctrl:1
	s_nop 1
	v_add_f32_dpp v0, v0, v0 row_ror:1 row_mask:0xf bank_mask:0xf bound_ctrl:1
	s_nop 0
	v_readlane_b32 s14, v0, 0
	v_readlane_b32 s17, v0, 16
	v_readlane_b32 s15, v0, 32
	v_readlane_b32 s16, v0, 48
	s_and_saveexec_b64 s[12:13], vcc
	s_cbranch_execz .LBB0_1773
	s_lshl_b64 s[10:11], s[10:11], 2
	v_mov_b32_e32 v0, s17
	s_add_u32 s10, s2, s10
	v_add_f32_e32 v0, s14, v0
	s_addc_u32 s11, s3, s11
	v_add_f32_e32 v0, s15, v0
	v_add_f32_e32 v2, s16, v0
	v_mov_b64_e32 v[0:1], s[10:11]
	flat_atomic_add_f32 v[0:1], v2
	s_branch .LBB0_1773

; template <int EPI, int TS, bool VT>
; DEVI void gemm_epilogue(const Params& p, char* smem, f32x4 (&acc)[2][2][4][2], int m0, int n0, float scale, const float* ssin,
;                         float* ssout, u16* xbout, int wid, int lane, int wr, int wc, int fr, int fq) {
;     ...
;   for (int ai = 0; ai < 2; ++ai) {
;     {
;       float* tw = T + (wr * 64 + fq * 4) * TS + wc * 32 + fr;
; #pragma unroll
;       for (int m = 0; m < 4; ++m)
; #pragma unroll
;         for (int j = 0; j < 4; ++j)
; #pragma unroll
;           for (int v = 0; v < 4; ++v) tw[(m * 16 + j) * TS + (v >> 1) * 128 + (v & 1) * 16] = acc[ai][v >> 1][m][v & 1][j];
;     }
;     __syncthreads();
;     ...
;           } else if constexpr (EPI == E_BF16) {
;             const float4 a = *(const float4*)(Tr + 4 * lane);
;             uint2 o;
;             o.x = pack2(a.x, a.y);
;             o.y = pack2(a.z, a.w);
;             st_nt8((u16*)(wsb + OFF_PP) + (size_t)grow * 1024 + n0 + 4 * lane, o);
.LBB0_1851:
	s_lshl_b32 s14, s30, 6
	v_lshrrev_b32_e32 v128, 2, v128
	v_and_or_b32 v128, v128, 12, s14
	s_movk_i32 s14, 0x410
	v_readlane_b32 s12, v254, 13
	v_mul_lo_u32 v128, v128, s14
	s_lshl_b32 s14, s34, 7
	v_lshlrev_b32_e32 v129, 2, v129
	v_readlane_b32 s13, v254, 14
	v_add3_u32 v128, s14, v128, v129
	ds_write2_b32 v128, v92, v100 offset1:16
	ds_write2_b32 v128, v120, v124 offset0:128 offset1:144
	v_add_u32_e32 v92, 0x400, v128
	ds_write2_b32 v92, v93, v101 offset0:4 offset1:20
	ds_write2_b32 v92, v121, v125 offset0:132 offset1:148
	v_add_u32_e32 v93, 0x800, v128
	ds_write2_b32 v93, v94, v102 offset0:8 offset1:24
	ds_write2_b32 v93, v122, v126 offset0:136 offset1:152
	v_add_u32_e32 v94, 0xc00, v128
	ds_write2_b32 v94, v95, v103 offset0:12 offset1:28
	ds_write2_b32 v94, v123, v127 offset0:140 offset1:156
	v_add_u32_e32 v95, 0x4000, v128
	ds_write2_b32 v95, v80, v84 offset0:64 offset1:80
	ds_write2_b32 v95, v112, v116 offset0:192 offset1:208
	v_add_u32_e32 v80, 0x4400, v128
	ds_write2_b32 v80, v81, v85 offset0:68 offset1:84
	ds_write2_b32 v80, v113, v117 offset0:196 offset1:212
	v_add_u32_e32 v81, 0x4800, v128
	ds_write2_b32 v81, v82, v86 offset0:72 offset1:88
	ds_write2_b32 v81, v114, v118 offset0:200 offset1:216
	v_add_u32_e32 v82, 0x4c00, v128
	ds_write2_b32 v82, v83, v87 offset0:76 offset1:92
	ds_write2_b32 v82, v115, v119 offset0:204 offset1:220
	v_add_u32_e32 v83, 0x8000, v128
	ds_write2_b32 v83, v72, v76 offset0:128 offset1:144
	v_add_u32_e32 v72, 0x8400, v128
	ds_write2_b32 v72, v104, v108 offset1:16
	ds_write2_b32 v72, v73, v77 offset0:132 offset1:148
	v_add_u32_e32 v73, 0x8800, v128
	ds_write2_b32 v73, v105, v109 offset0:4 offset1:20
	ds_write2_b32 v73, v74, v78 offset0:136 offset1:152
	v_add_u32_e32 v74, 0x8c00, v128
	ds_write2_b32 v74, v106, v110 offset0:8 offset1:24
	ds_write2_b32 v74, v75, v79 offset0:140 offset1:156
	v_add_u32_e32 v75, 0x9000, v128
	v_add_u32_e32 v76, 0xc000, v128
	v_add_u32_e32 v77, 0xc400, v128
	v_add_u32_e32 v78, 0xc800, v128
	s_lshl_b32 s14, s11, 4
	v_and_b32_e32 v129, 0xfc, v130
	ds_write2_b32 v75, v107, v111 offset0:12 offset1:28
	ds_write2_b32 v76, v64, v68 offset0:192 offset1:208
	ds_write2_b32 v77, v88, v96 offset0:64 offset1:80
	ds_write2_b32 v77, v65, v69 offset0:196 offset1:212
	ds_write2_b32 v78, v89, v97 offset0:68 offset1:84
	ds_write2_b32 v78, v66, v70 offset0:200 offset1:216
	v_add_u32_e32 v70, 0xcc00, v128
	s_mulk_i32 s11, 0x4100
	ds_write2_b32 v70, v90, v98 offset0:72 offset1:88
	ds_write2_b32 v70, v67, v71 offset0:204 offset1:220
	v_add_u32_e32 v71, 0xd000, v128
	v_lshl_add_u32 v79, v129, 2, s11
	s_add_i32 s10, s14, s10
	s_lshl_b64 s[8:9], s[8:9], 1
	ds_write2_b32 v71, v91, v99 offset0:76 offset1:92
	s_waitcnt vmcnt(0) lgkmcnt(0)
	s_barrier
	ds_read_b128 v[66:69], v79
	s_add_u32 s8, s12, s8
	s_addc_u32 s9, s13, s9
	v_lshlrev_b32_e32 v148, 1, v129
	v_lshl_add_u64 v[64:65], s[8:9], 0, v[148:149]
	s_mov_b64 s[8:9], 0x1495ee00
	s_ashr_i32 s11, s10, 31
	v_lshl_add_u64 v[64:65], v[64:65], 0, s[8:9]
	s_lshl_b64 s[8:9], s[10:11], 11
	s_waitcnt lgkmcnt(0)
	v_cvt_pk_bf16_f32 v66, v66, v67
	v_cvt_pk_bf16_f32 v67, v68, v69
	v_lshl_add_u64 v[68:69], v[64:65], 0, s[8:9]
	flat_store_dwordx2 v[68:69], v[66:67]
	ds_read_b128 v[66:69], v79 offset:1040
	s_or_b32 s8, s10, 1
	s_ashr_i32 s9, s8, 31
	s_lshl_b64 s[8:9], s[8:9], 11
	s_andn2_b64 vcc, exec, s[6:7]
	s_waitcnt lgkmcnt(0)
	v_cvt_pk_bf16_f32 v66, v66, v67
	v_cvt_pk_bf16_f32 v67, v68, v69
	v_lshl_add_u64 v[68:69], v[64:65], 0, s[8:9]
	flat_store_dwordx2 v[68:69], v[66:67]
	ds_read_b128 v[66:69], v79 offset:2080
	s_or_b32 s8, s10, 2
	s_ashr_i32 s9, s8, 31
	s_lshl_b64 s[8:9], s[8:9], 11
	s_waitcnt lgkmcnt(0)
	v_cvt_pk_bf16_f32 v66, v66, v67
	v_cvt_pk_bf16_f32 v67, v68, v69
	v_lshl_add_u64 v[68:69], v[64:65], 0, s[8:9]
	flat_store_dwordx2 v[68:69], v[66:67]
	ds_read_b128 v[66:69], v79 offset:3120
	s_or_b32 s8, s10, 3
	s_ashr_i32 s9, s8, 31
	s_lshl_b64 s[8:9], s[8:9], 11
	s_waitcnt lgkmcnt(0)
	v_cvt_pk_bf16_f32 v66, v66, v67
	v_cvt_pk_bf16_f32 v67, v68, v69
	v_lshl_add_u64 v[68:69], v[64:65], 0, s[8:9]
	flat_store_dwordx2 v[68:69], v[66:67]
	ds_read_b128 v[66:69], v79 offset:4160
	s_or_b32 s8, s10, 4
	s_ashr_i32 s9, s8, 31
	s_lshl_b64 s[8:9], s[8:9], 11
	s_waitcnt lgkmcnt(0)
	v_cvt_pk_bf16_f32 v66, v66, v67
	v_cvt_pk_bf16_f32 v67, v68, v69
	v_lshl_add_u64 v[68:69], v[64:65], 0, s[8:9]
	flat_store_dwordx2 v[68:69], v[66:67]
	ds_read_b128 v[66:69], v79 offset:5200
	s_or_b32 s8, s10, 5
	s_ashr_i32 s9, s8, 31
	s_lshl_b64 s[8:9], s[8:9], 11
	s_waitcnt lgkmcnt(0)
	v_cvt_pk_bf16_f32 v66, v66, v67
	v_cvt_pk_bf16_f32 v67, v68, v69
	v_lshl_add_u64 v[68:69], v[64:65], 0, s[8:9]
	flat_store_dwordx2 v[68:69], v[66:67]
	ds_read_b128 v[66:69], v79 offset:6240
	s_or_b32 s8, s10, 6
	s_ashr_i32 s9, s8, 31
	s_lshl_b64 s[8:9], s[8:9], 11
	s_waitcnt lgkmcnt(0)
	v_cvt_pk_bf16_f32 v66, v66, v67
	v_cvt_pk_bf16_f32 v67, v68, v69
	v_lshl_add_u64 v[68:69], v[64:65], 0, s[8:9]
	flat_store_dwordx2 v[68:69], v[66:67]
	ds_read_b128 v[66:69], v79 offset:7280
	s_or_b32 s8, s10, 7
	s_ashr_i32 s9, s8, 31
	s_lshl_b64 s[8:9], s[8:9], 11
	s_waitcnt lgkmcnt(0)
	v_cvt_pk_bf16_f32 v66, v66, v67
	v_cvt_pk_bf16_f32 v67, v68, v69
	v_lshl_add_u64 v[68:69], v[64:65], 0, s[8:9]
	flat_store_dwordx2 v[68:69], v[66:67]
	ds_read_b128 v[66:69], v79 offset:8320
	s_or_b32 s8, s10, 8
	s_ashr_i32 s9, s8, 31
	s_lshl_b64 s[8:9], s[8:9], 11
	s_waitcnt lgkmcnt(0)
	v_cvt_pk_bf16_f32 v66, v66, v67
	v_cvt_pk_bf16_f32 v67, v68, v69
	v_lshl_add_u64 v[68:69], v[64:65], 0, s[8:9]
	flat_store_dwordx2 v[68:69], v[66:67]
	ds_read_b128 v[66:69], v79 offset:9360
	s_or_b32 s8, s10, 9
	s_ashr_i32 s9, s8, 31
	s_lshl_b64 s[8:9], s[8:9], 11
	s_waitcnt lgkmcnt(0)
; template <int EPI, int TS, bool VT>
; DEVI void gemm_epilogue(const Params& p, char* smem, f32x4 (&acc)[2][2][4][2], int m0, int n0, float scale, const float* ssin,
;                         float* ssout, u16* xbout, int wid, int lane, int wr, int wc, int fr, int fq) {
;     ...
;   for (int ai = 0; ai < 2; ++ai) {
;     {
;       float* tw = T + (wr * 64 + fq * 4) * TS + wc * 32 + fr;
; #pragma unroll
;       for (int m = 0; m < 4; ++m)
; #pragma unroll
;         for (int j = 0; j < 4; ++j)
; #pragma unroll
;           for (int v = 0; v < 4; ++v) tw[(m * 16 + j) * TS + (v >> 1) * 128 + (v & 1) * 16] = acc[ai][v >> 1][m][v & 1][j];
;     }
;     __syncthreads();
;     ...
;           } else if constexpr (EPI == E_BF16) {
;             const float4 a = *(const float4*)(Tr + 4 * lane);
;             uint2 o;
;             o.x = pack2(a.x, a.y);
;             o.y = pack2(a.z, a.w);
;             st_nt8((u16*)(wsb + OFF_PP) + (size_t)grow * 1024 + n0 + 4 * lane, o);
	v_cvt_pk_bf16_f32 v66, v66, v67
	v_cvt_pk_bf16_f32 v67, v68, v69
	v_lshl_add_u64 v[68:69], v[64:65], 0, s[8:9]
	flat_store_dwordx2 v[68:69], v[66:67]
	ds_read_b128 v[66:69], v79 offset:10400
	s_or_b32 s8, s10, 10
	s_ashr_i32 s9, s8, 31
	s_lshl_b64 s[8:9], s[8:9], 11
	s_waitcnt lgkmcnt(0)
	v_cvt_pk_bf16_f32 v66, v66, v67
	v_cvt_pk_bf16_f32 v67, v68, v69
	v_lshl_add_u64 v[68:69], v[64:65], 0, s[8:9]
	flat_store_dwordx2 v[68:69], v[66:67]
	ds_read_b128 v[66:69], v79 offset:11440
	s_or_b32 s8, s10, 11
	s_ashr_i32 s9, s8, 31
	s_lshl_b64 s[8:9], s[8:9], 11
	s_waitcnt lgkmcnt(0)
	v_cvt_pk_bf16_f32 v66, v66, v67
	v_cvt_pk_bf16_f32 v67, v68, v69
	v_lshl_add_u64 v[68:69], v[64:65], 0, s[8:9]
	flat_store_dwordx2 v[68:69], v[66:67]
	ds_read_b128 v[66:69], v79 offset:12480
	s_or_b32 s8, s10, 12
	s_ashr_i32 s9, s8, 31
	s_lshl_b64 s[8:9], s[8:9], 11
	s_waitcnt lgkmcnt(0)
	v_cvt_pk_bf16_f32 v66, v66, v67
	v_cvt_pk_bf16_f32 v67, v68, v69
	v_lshl_add_u64 v[68:69], v[64:65], 0, s[8:9]
	flat_store_dwordx2 v[68:69], v[66:67]
	ds_read_b128 v[66:69], v79 offset:13520
	s_or_b32 s8, s10, 13
	s_ashr_i32 s9, s8, 31
	s_lshl_b64 s[8:9], s[8:9], 11
	s_waitcnt lgkmcnt(0)
	v_cvt_pk_bf16_f32 v66, v66, v67
	v_cvt_pk_bf16_f32 v67, v68, v69
	v_lshl_add_u64 v[68:69], v[64:65], 0, s[8:9]
	flat_store_dwordx2 v[68:69], v[66:67]
	ds_read_b128 v[66:69], v79 offset:14560
	s_or_b32 s8, s10, 14
	s_ashr_i32 s9, s8, 31
	s_lshl_b64 s[8:9], s[8:9], 11
	s_waitcnt lgkmcnt(0)
	v_cvt_pk_bf16_f32 v66, v66, v67
	v_cvt_pk_bf16_f32 v67, v68, v69
	v_lshl_add_u64 v[68:69], v[64:65], 0, s[8:9]
	flat_store_dwordx2 v[68:69], v[66:67]
	ds_read_b128 v[66:69], v79 offset:15600
	s_or_b32 s8, s10, 15
	s_ashr_i32 s9, s8, 31
	s_lshl_b64 s[8:9], s[8:9], 11
	s_waitcnt lgkmcnt(0)
	v_cvt_pk_bf16_f32 v66, v66, v67
	v_cvt_pk_bf16_f32 v67, v68, v69
	v_lshl_add_u64 v[68:69], v[64:65], 0, s[8:9]
	flat_store_dwordx2 v[68:69], v[66:67]
	s_waitcnt lgkmcnt(0)
	s_barrier
	ds_write2_b32 v128, v24, v28 offset1:16
	ds_write2_b32 v128, v56, v60 offset0:128 offset1:144
	ds_write2_b32 v92, v25, v29 offset0:4 offset1:20
	ds_write2_b32 v92, v57, v61 offset0:132 offset1:148
	ds_write2_b32 v93, v26, v30 offset0:8 offset1:24
	ds_write2_b32 v93, v58, v62 offset0:136 offset1:152
	ds_write2_b32 v94, v27, v31 offset0:12 offset1:28
	ds_write2_b32 v94, v59, v63 offset0:140 offset1:156
	ds_write2_b32 v95, v16, v20 offset0:64 offset1:80
	ds_write2_b32 v95, v48, v52 offset0:192 offset1:208
	ds_write2_b32 v80, v17, v21 offset0:68 offset1:84
	ds_write2_b32 v80, v49, v53 offset0:196 offset1:212
	ds_write2_b32 v81, v18, v22 offset0:72 offset1:88
	ds_write2_b32 v81, v50, v54 offset0:200 offset1:216
	ds_write2_b32 v82, v19, v23 offset0:76 offset1:92
	ds_write2_b32 v82, v51, v55 offset0:204 offset1:220
	ds_write2_b32 v83, v8, v12 offset0:128 offset1:144
	ds_write2_b32 v72, v40, v44 offset1:16
	ds_write2_b32 v72, v9, v13 offset0:132 offset1:148
	ds_write2_b32 v73, v41, v45 offset0:4 offset1:20
	ds_write2_b32 v73, v10, v14 offset0:136 offset1:152
	ds_write2_b32 v74, v42, v46 offset0:8 offset1:24
	ds_write2_b32 v74, v11, v15 offset0:140 offset1:156
	ds_write2_b32 v75, v43, v47 offset0:12 offset1:28
	ds_write2_b32 v76, v0, v4 offset0:192 offset1:208
	ds_write2_b32 v77, v32, v36 offset0:64 offset1:80
	ds_write2_b32 v77, v1, v5 offset0:196 offset1:212
	ds_write2_b32 v78, v33, v37 offset0:68 offset1:84
	ds_write2_b32 v78, v2, v6 offset0:200 offset1:216
	ds_write2_b32 v70, v34, v38 offset0:72 offset1:88
	ds_write2_b32 v70, v3, v7 offset0:204 offset1:220
	ds_write2_b32 v71, v35, v39 offset0:76 offset1:92
	s_waitcnt lgkmcnt(0)
	s_barrier
; template <int EPI, int TS, bool VT>
; DEVI void gemm_epilogue(const Params& p, char* smem, f32x4 (&acc)[2][2][4][2], int m0, int n0, float scale, const float* ssin,
;                         float* ssout, u16* xbout, int wid, int lane, int wr, int wc, int fr, int fq) {
;     ...
;           } else if constexpr (EPI == E_BF16) {
;             const float4 a = *(const float4*)(Tr + 4 * lane);
;             uint2 o;
;             o.x = pack2(a.x, a.y);
;             o.y = pack2(a.z, a.w);
;             st_nt8((u16*)(wsb + OFF_PP) + (size_t)grow * 1024 + n0 + 4 * lane, o);
	ds_read_b128 v[0:3], v79
	s_add_i32 s8, s10, 0x80
	s_ashr_i32 s9, s8, 31
	s_lshl_b64 s[8:9], s[8:9], 11
	s_waitcnt lgkmcnt(0)
	v_cvt_pk_bf16_f32 v0, v0, v1
	v_cvt_pk_bf16_f32 v1, v2, v3
	v_lshl_add_u64 v[2:3], v[64:65], 0, s[8:9]
	flat_store_dwordx2 v[2:3], v[0:1]
	ds_read_b128 v[0:3], v79 offset:1040
	s_add_i32 s8, s10, 0x81
	s_ashr_i32 s9, s8, 31
	s_lshl_b64 s[8:9], s[8:9], 11
	s_waitcnt lgkmcnt(0)
	v_cvt_pk_bf16_f32 v0, v0, v1
	v_cvt_pk_bf16_f32 v1, v2, v3
	v_lshl_add_u64 v[2:3], v[64:65], 0, s[8:9]
	flat_store_dwordx2 v[2:3], v[0:1]
	ds_read_b128 v[0:3], v79 offset:2080
	s_add_i32 s8, s10, 0x82
	s_ashr_i32 s9, s8, 31
	s_lshl_b64 s[8:9], s[8:9], 11
	s_waitcnt lgkmcnt(0)
	v_cvt_pk_bf16_f32 v0, v0, v1
	v_cvt_pk_bf16_f32 v1, v2, v3
	v_lshl_add_u64 v[2:3], v[64:65], 0, s[8:9]
	flat_store_dwordx2 v[2:3], v[0:1]
	ds_read_b128 v[0:3], v79 offset:3120
	s_add_i32 s8, s10, 0x83
	s_ashr_i32 s9, s8, 31
	s_lshl_b64 s[8:9], s[8:9], 11
	s_waitcnt lgkmcnt(0)
	v_cvt_pk_bf16_f32 v0, v0, v1
	v_cvt_pk_bf16_f32 v1, v2, v3
	v_lshl_add_u64 v[2:3], v[64:65], 0, s[8:9]
	flat_store_dwordx2 v[2:3], v[0:1]
	ds_read_b128 v[0:3], v79 offset:4160
	s_add_i32 s8, s10, 0x84
	s_ashr_i32 s9, s8, 31
	s_lshl_b64 s[8:9], s[8:9], 11
	s_waitcnt lgkmcnt(0)
	v_cvt_pk_bf16_f32 v0, v0, v1
	v_cvt_pk_bf16_f32 v1, v2, v3
	v_lshl_add_u64 v[2:3], v[64:65], 0, s[8:9]
	flat_store_dwordx2 v[2:3], v[0:1]
	ds_read_b128 v[0:3], v79 offset:5200
	s_add_i32 s8, s10, 0x85
	s_ashr_i32 s9, s8, 31
	s_lshl_b64 s[8:9], s[8:9], 11
	s_waitcnt lgkmcnt(0)
	v_cvt_pk_bf16_f32 v0, v0, v1
	v_cvt_pk_bf16_f32 v1, v2, v3
	v_lshl_add_u64 v[2:3], v[64:65], 0, s[8:9]
	flat_store_dwordx2 v[2:3], v[0:1]
	ds_read_b128 v[0:3], v79 offset:6240
	s_add_i32 s8, s10, 0x86
	s_ashr_i32 s9, s8, 31
	s_lshl_b64 s[8:9], s[8:9], 11
	s_waitcnt lgkmcnt(0)
	v_cvt_pk_bf16_f32 v0, v0, v1
	v_cvt_pk_bf16_f32 v1, v2, v3
	v_lshl_add_u64 v[2:3], v[64:65], 0, s[8:9]
	flat_store_dwordx2 v[2:3], v[0:1]
	ds_read_b128 v[0:3], v79 offset:7280
	s_add_i32 s8, s10, 0x87
	s_ashr_i32 s9, s8, 31
	s_lshl_b64 s[8:9], s[8:9], 11
	s_waitcnt lgkmcnt(0)
	v_cvt_pk_bf16_f32 v0, v0, v1
	v_cvt_pk_bf16_f32 v1, v2, v3
	v_lshl_add_u64 v[2:3], v[64:65], 0, s[8:9]
	flat_store_dwordx2 v[2:3], v[0:1]
	ds_read_b128 v[0:3], v79 offset:8320
	s_add_i32 s8, s10, 0x88
	s_ashr_i32 s9, s8, 31
	s_lshl_b64 s[8:9], s[8:9], 11
	s_waitcnt lgkmcnt(0)
	v_cvt_pk_bf16_f32 v0, v0, v1
	v_cvt_pk_bf16_f32 v1, v2, v3
	v_lshl_add_u64 v[2:3], v[64:65], 0, s[8:9]
	flat_store_dwordx2 v[2:3], v[0:1]
	ds_read_b128 v[0:3], v79 offset:9360
	s_add_i32 s8, s10, 0x89
	s_ashr_i32 s9, s8, 31
	s_lshl_b64 s[8:9], s[8:9], 11
	s_waitcnt lgkmcnt(0)
	v_cvt_pk_bf16_f32 v0, v0, v1
	v_cvt_pk_bf16_f32 v1, v2, v3
	v_lshl_add_u64 v[2:3], v[64:65], 0, s[8:9]
	flat_store_dwordx2 v[2:3], v[0:1]
	ds_read_b128 v[0:3], v79 offset:10400
	s_add_i32 s8, s10, 0x8a
	s_ashr_i32 s9, s8, 31
	s_lshl_b64 s[8:9], s[8:9], 11
	s_waitcnt lgkmcnt(0)
	v_cvt_pk_bf16_f32 v0, v0, v1
	v_cvt_pk_bf16_f32 v1, v2, v3
	v_lshl_add_u64 v[2:3], v[64:65], 0, s[8:9]
	flat_store_dwordx2 v[2:3], v[0:1]
	ds_read_b128 v[0:3], v79 offset:11440
	s_add_i32 s8, s10, 0x8b
	s_ashr_i32 s9, s8, 31
	s_lshl_b64 s[8:9], s[8:9], 11
	s_waitcnt lgkmcnt(0)
	v_cvt_pk_bf16_f32 v0, v0, v1
	v_cvt_pk_bf16_f32 v1, v2, v3
	v_lshl_add_u64 v[2:3], v[64:65], 0, s[8:9]
	flat_store_dwordx2 v[2:3], v[0:1]
	ds_read_b128 v[0:3], v79 offset:12480
	s_add_i32 s8, s10, 0x8c
	s_ashr_i32 s9, s8, 31
	s_lshl_b64 s[8:9], s[8:9], 11
	s_waitcnt lgkmcnt(0)
	v_cvt_pk_bf16_f32 v0, v0, v1
	v_cvt_pk_bf16_f32 v1, v2, v3
	v_lshl_add_u64 v[2:3], v[64:65], 0, s[8:9]
	flat_store_dwordx2 v[2:3], v[0:1]
	ds_read_b128 v[0:3], v79 offset:13520
	s_add_i32 s8, s10, 0x8d
	s_ashr_i32 s9, s8, 31
	s_lshl_b64 s[8:9], s[8:9], 11
	s_waitcnt lgkmcnt(0)
	v_cvt_pk_bf16_f32 v0, v0, v1
	v_cvt_pk_bf16_f32 v1, v2, v3
	v_lshl_add_u64 v[2:3], v[64:65], 0, s[8:9]
	flat_store_dwordx2 v[2:3], v[0:1]
	ds_read_b128 v[0:3], v79 offset:14560
	s_add_i32 s8, s10, 0x8e
	s_ashr_i32 s9, s8, 31
	s_lshl_b64 s[8:9], s[8:9], 11
	s_waitcnt lgkmcnt(0)
	v_cvt_pk_bf16_f32 v0, v0, v1
	v_cvt_pk_bf16_f32 v1, v2, v3
	v_lshl_add_u64 v[2:3], v[64:65], 0, s[8:9]
	flat_store_dwordx2 v[2:3], v[0:1]
	ds_read_b128 v[0:3], v79 offset:15600
	s_add_i32 s8, s10, 0x8f
	s_ashr_i32 s9, s8, 31
	s_lshl_b64 s[8:9], s[8:9], 11
	s_waitcnt lgkmcnt(0)
	v_cvt_pk_bf16_f32 v0, v0, v1
	v_cvt_pk_bf16_f32 v1, v2, v3
	v_lshl_add_u64 v[2:3], v[64:65], 0, s[8:9]
	s_mov_b32 s9, s22
	s_mov_b32 s8, s23
	flat_store_dwordx2 v[2:3], v[0:1]
	s_waitcnt lgkmcnt(0)
	s_barrier
	s_cbranch_vccz .LBB0_1858

; template <int EPI, int TS, bool VT>
; DEVI void gemm_epilogue(const Params& p, char* smem, f32x4 (&acc)[2][2][4][2], int m0, int n0, float scale, const float* ssin,
;                         float* ssout, u16* xbout, int wid, int lane, int wr, int wc, int fr, int fq) {
;     ...
;   for (int ai = 0; ai < 2; ++ai) {
;     {
;       float* tw = T + (wr * 64 + fq * 4) * TS + wc * 32 + fr;
; #pragma unroll
;       for (int m = 0; m < 4; ++m)
; #pragma unroll
;         for (int j = 0; j < 4; ++j)
; #pragma unroll
;           for (int v = 0; v < 4; ++v) tw[(m * 16 + j) * TS + (v >> 1) * 128 + (v & 1) * 16] = acc[ai][v >> 1][m][v & 1][j];
;     }
;     __syncthreads();
;     const int r0 = wid * 16;
;     const int g0 = m0 + ai * 128 + r0;
;     if constexpr (!VT) {
;       float rsv = 1.f;
;       if constexpr (EPI == E_PLEGATE || EPI == E_F32 || EPI == E_SWIGLU || EPI == E_GLAIN)
;         rsv = rsqrtf(ssin[g0 + (lane & 15)] * (1.f / 1024.f) + EPS);
.LBB0_1886:
	v_lshrrev_b32_e32 v128, 2, v132
	v_and_or_b32 v128, v128, 12, s66
	s_movk_i32 s20, 0x410
	v_mul_lo_u32 v128, v128, s20
	s_lshl_b32 s20, s65, 7
	v_lshlrev_b32_e32 v129, 2, v143
	v_readlane_b32 s18, v254, 13
	v_add3_u32 v144, s20, v128, v129
	s_lshl_b32 s20, s5, 4
	v_readlane_b32 s19, v254, 14
	s_add_i32 s20, s20, s4
	v_add_u32_e32 v145, 0x400, v144
	v_add_u32_e32 v146, 0x800, v144
	v_add_u32_e32 v147, 0xc00, v144
	v_add_u32_e32 v148, 0x4000, v144
	v_add_u32_e32 v152, 0x4400, v144
	v_add_u32_e32 v153, 0x4800, v144
	v_add_u32_e32 v154, 0x4c00, v144
	v_add_u32_e32 v155, 0x8000, v144
	v_add_u32_e32 v156, 0x8400, v144
	v_add_u32_e32 v157, 0x8800, v144
	v_add_u32_e32 v158, 0x8c00, v144
	v_add_u32_e32 v160, 0xc000, v144
	ds_write2_b32 v144, v92, v100 offset1:16
	ds_write2_b32 v144, v120, v124 offset0:128 offset1:144
	ds_write2_b32 v145, v93, v101 offset0:4 offset1:20
	ds_write2_b32 v145, v121, v125 offset0:132 offset1:148
	ds_write2_b32 v146, v94, v102 offset0:8 offset1:24
	ds_write2_b32 v146, v122, v126 offset0:136 offset1:152
	ds_write2_b32 v147, v95, v103 offset0:12 offset1:28
	ds_write2_b32 v147, v123, v127 offset0:140 offset1:156
	ds_write2_b32 v148, v80, v84 offset0:64 offset1:80
	ds_write2_b32 v148, v112, v116 offset0:192 offset1:208
	ds_write2_b32 v152, v81, v85 offset0:68 offset1:84
	ds_write2_b32 v152, v113, v117 offset0:196 offset1:212
	ds_write2_b32 v153, v82, v86 offset0:72 offset1:88
	ds_write2_b32 v153, v114, v118 offset0:200 offset1:216
	ds_write2_b32 v154, v83, v87 offset0:76 offset1:92
	ds_write2_b32 v154, v115, v119 offset0:204 offset1:220
	ds_write2_b32 v155, v72, v76 offset0:128 offset1:144
	ds_write2_b32 v156, v104, v108 offset1:16
	ds_write2_b32 v156, v73, v77 offset0:132 offset1:148
	ds_write2_b32 v157, v105, v109 offset0:4 offset1:20
	ds_write2_b32 v157, v74, v78 offset0:136 offset1:152
	ds_write2_b32 v158, v106, v110 offset0:8 offset1:24
	ds_write2_b32 v158, v75, v79 offset0:140 offset1:156
	v_add_u32_e32 v159, 0x9000, v144
	ds_write2_b32 v160, v64, v68 offset0:192 offset1:208
	v_add_u32_e32 v161, 0xc400, v144
	v_or_b32_e32 v64, s20, v143
	ds_write2_b32 v159, v107, v111 offset0:12 offset1:28
	ds_write2_b32 v161, v88, v96 offset0:64 offset1:80
	ds_write2_b32 v161, v65, v69 offset0:196 offset1:212
	v_ashrrev_i32_e32 v65, 31, v64
	v_add_u32_e32 v162, 0xc800, v144
	v_add_u32_e32 v163, 0xcc00, v144
	v_add_u32_e32 v164, 0xd000, v144
	v_lshl_add_u64 v[64:65], v[64:65], 2, s[2:3]
	ds_write2_b32 v162, v89, v97 offset0:68 offset1:84
	ds_write2_b32 v162, v66, v70 offset0:200 offset1:216
	ds_write2_b32 v163, v90, v98 offset0:72 offset1:88
	ds_write2_b32 v163, v67, v71 offset0:204 offset1:220
	ds_write2_b32 v164, v91, v99 offset0:76 offset1:92
	s_waitcnt vmcnt(0) lgkmcnt(0)
	s_barrier
; template <int EPI, int TS, bool VT>
; DEVI void gemm_epilogue(const Params& p, char* smem, f32x4 (&acc)[2][2][4][2], int m0, int n0, float scale, const float* ssin,
;                         float* ssout, u16* xbout, int wid, int lane, int wr, int wc, int fr, int fq) {
;     ...
;         rsv = rsqrtf(ssin[g0 + (lane & 15)] * (1.f / 1024.f) + EPS);
;       if constexpr (EPI == E_QROPE) rsv = rsqrtf(ssin[g0 + (lane & 15)] * (1.f / 384.f) + EPS);
;       if constexpr (EPI == E_KV) rsv = rsqrtf(ssin[g0 + (lane & 15)] * (1.f / 256.f) + EPS);
;       for (int i0 = 0; i0 < 16; i0 += 8) {
;         float4 xo[8];
;         uint2 pv[8];
;         if constexpr (EPI == E_RESID || EPI == E_PLEGATE) {
; #pragma unroll
;           for (int u = 0; u < 8; ++u) {
;             const size_t ro = (size_t)(g0 + i0 + u) * 1024 + n0 + 4 * lane;
;             const int gr = g0 + i0 + u;
;             const float* xs = p.x + ro;
;             if (scale < 0.f)
;               xs = (gr < MP ? p.x_prompt + ro : p.x_sample + (ro - (size_t)MP * 1024));
;             { const f32x4 t_ = __builtin_nontemporal_load((const f32x4*)xs); xo[u] = make_float4(t_[0], t_[1], t_[2], t_[3]); }
;             if constexpr (EPI == E_PLEGATE) {
;               const unsigned long long t2_ = __builtin_nontemporal_load((const unsigned long long*)((const u16*)(wsb + OFF_PP) + ro));
;               pv[u] = make_uint2((unsigned)t2_, (unsigned)(t2_ >> 32));
;             }
;           }
;         }
; #pragma unroll
;         for (int u = 0; u < 8; ++u) {
;           const int i = i0 + u;
;           const int grow = g0 + i;
;           const float* Tr = T + (r0 + i) * TS;
;           const float rs = __int_as_float(__builtin_amdgcn_readlane(__float_as_int(rsv), i));
;           if constexpr (EPI == E_RESID || EPI == E_PLEGATE) {
;             const float4 a = *(const float4*)(Tr + 4 * lane);
;             const size_t ro = (size_t)grow * 1024 + n0 + 4 * lane;
;             float4 x4 = xo[u];
;             if constexpr (EPI == E_PLEGATE) {
;               x4.x += bflo(pv[u].x) * fsig(a.x * rs);
;               x4.y += bfhi(pv[u].x) * fsig(a.y * rs);
;               x4.z += bflo(pv[u].y) * fsig(a.z * rs);
;               x4.w += bfhi(pv[u].y) * fsig(a.w * rs);
;             } else {
;               const float sc = fabsf(scale);
;               x4.x += sc * a.x; x4.y += sc * a.y; x4.z += sc * a.z; x4.w += sc * a.w;
	flat_load_dword v64, v[64:65]
	s_add_u32 s18, s18, 0x1495ee00
	v_and_b32_e32 v166, 63, v132
	s_addc_u32 s19, s19, 0
	s_ashr_i32 s21, s20, 31
	v_lshl_or_b32 v128, v166, 2, s0
	v_mov_b32_e32 v129, s1
	s_lshl_b64 s[0:1], s[20:21], 10
	v_lshl_add_u64 v[140:141], s[0:1], 0, v[128:129]
	v_lshl_add_u64 v[178:179], v[140:141], 2, s[38:39]
	global_load_dwordx4 v[92:95], v[178:179], off
	s_or_b32 s68, s20, 1
	s_ashr_i32 s69, s68, 31
	s_or_b32 s66, s20, 2
	s_lshl_b64 s[0:1], s[68:69], 10
	s_ashr_i32 s67, s66, 31
	s_or_b32 s64, s20, 3
	v_lshl_add_u64 v[134:135], s[0:1], 0, v[128:129]
	s_lshl_b64 s[0:1], s[66:67], 10
	s_ashr_i32 s65, s64, 31
	s_or_b32 s62, s20, 4
	v_lshl_add_u64 v[126:127], s[0:1], 0, v[128:129]
	s_lshl_b64 s[0:1], s[64:65], 10
	s_ashr_i32 s63, s62, 31
	s_or_b32 s34, s20, 5
	v_lshl_add_u64 v[120:121], s[0:1], 0, v[128:129]
	s_lshl_b64 s[0:1], s[62:63], 10
	s_ashr_i32 s35, s34, 31
	s_or_b32 s30, s20, 6
	v_lshl_add_u64 v[114:115], s[0:1], 0, v[128:129]
	s_lshl_b64 s[0:1], s[34:35], 10
	s_ashr_i32 s31, s30, 31
	s_or_b32 s22, s20, 7
	v_lshl_add_u64 v[108:109], s[0:1], 0, v[128:129]
	s_lshl_b64 s[0:1], s[30:31], 10
	s_ashr_i32 s23, s22, 31
	v_lshl_add_u64 v[102:103], s[0:1], 0, v[128:129]
	s_lshl_b64 s[0:1], s[22:23], 10
	v_lshl_add_u64 v[96:97], s[0:1], 0, v[128:129]
	v_lshl_add_u64 v[100:101], v[96:97], 1, s[18:19]
	v_lshl_add_u64 v[136:137], v[134:135], 2, s[38:39]
	v_lshl_add_u64 v[130:131], v[126:127], 2, s[38:39]
	v_lshl_add_u64 v[122:123], v[120:121], 2, s[38:39]
	v_lshl_add_u64 v[116:117], v[114:115], 2, s[38:39]
	flat_load_dwordx2 v[100:101], v[100:101]
	v_lshl_add_u64 v[110:111], v[108:109], 2, s[38:39]
	v_lshl_add_u64 v[104:105], v[102:103], 2, s[38:39]
	v_lshl_add_u64 v[98:99], v[96:97], 2, s[38:39]
	global_load_dwordx4 v[88:91], v[136:137], off
	global_load_dwordx4 v[84:87], v[130:131], off
	global_load_dwordx4 v[80:83], v[122:123], off
	global_load_dwordx4 v[76:79], v[116:117], off
	global_load_dwordx4 v[72:75], v[110:111], off
	global_load_dwordx4 v[68:71], v[104:105], off
	s_mulk_i32 s5, 0x4100
	v_lshl_add_u32 v142, v166, 4, s5
	ds_read_b128 v[174:177], v142
	s_waitcnt vmcnt(0) lgkmcnt(0)
	v_fmamk_f32 v64, v64, 0x3a800000, v150
	v_cmp_gt_f32_e32 vcc, s29, v64
	v_mul_f32_e32 v65, 0x4b800000, v64
	s_nop 0
	v_cndmask_b32_e32 v64, v64, v65, vcc
	v_rsq_f32_e32 v64, v64
	s_nop 0
	v_mul_f32_e32 v65, 0x45800000, v64
	v_cndmask_b32_e32 v165, v64, v65, vcc
	v_lshl_add_u64 v[64:65], v[140:141], 1, s[18:19]
	flat_load_dwordx2 v[180:181], v[64:65]
	v_lshl_add_u64 v[64:65], v[134:135], 1, s[18:19]
	flat_load_dwordx2 v[138:139], v[64:65]
	v_lshl_add_u64 v[64:65], v[126:127], 1, s[18:19]
	flat_load_dwordx2 v[132:133], v[64:65]
	v_lshl_add_u64 v[64:65], v[120:121], 1, s[18:19]
	flat_load_dwordx2 v[124:125], v[64:65]
	v_lshl_add_u64 v[64:65], v[114:115], 1, s[18:19]
	flat_load_dwordx2 v[118:119], v[64:65]
	v_lshl_add_u64 v[64:65], v[108:109], 1, s[18:19]
	flat_load_dwordx2 v[112:113], v[64:65]
	v_lshl_add_u64 v[64:65], v[102:103], 1, s[18:19]
	flat_load_dwordx2 v[106:107], v[64:65]
	v_readlane_b32 s0, v165, 0
	global_load_dwordx4 v[64:67], v[98:99], off
	s_andn2_b64 vcc, exec, s[14:15]
	v_mul_f32_e32 v174, s0, v174
	v_mul_f32_e32 v174, 0xbfb8aa3b, v174
	v_exp_f32_e32 v174, v174
	s_waitcnt vmcnt(0) lgkmcnt(0)
	v_lshlrev_b32_e32 v167, 16, v180
	v_add_f32_e32 v174, 1.0, v174
	v_rcp_f32_e32 v174, v174
	s_nop 0
	v_fma_f32 v92, v174, v167, v92
	v_mul_f32_e32 v174, s0, v175
	v_mul_f32_e32 v174, 0xbfb8aa3b, v174
	v_exp_f32_e32 v174, v174
	v_and_b32_e32 v167, 0xffff0000, v180
	v_add_f32_e32 v174, 1.0, v174
	v_rcp_f32_e32 v174, v174
	s_nop 0
	v_fma_f32 v93, v174, v167, v93
	v_mul_f32_e32 v174, s0, v176
	v_mul_f32_e32 v174, 0xbfb8aa3b, v174
	v_exp_f32_e32 v174, v174
	v_lshlrev_b32_e32 v167, 16, v181
	v_add_f32_e32 v174, 1.0, v174
	v_rcp_f32_e32 v174, v174
	s_nop 0
	v_fma_f32 v94, v174, v167, v94
	v_mul_f32_e32 v174, s0, v177
	v_mul_f32_e32 v174, 0xbfb8aa3b, v174
	v_exp_f32_e32 v174, v174
	v_and_b32_e32 v167, 0xffff0000, v181
	v_add_f32_e32 v174, 1.0, v174
	v_rcp_f32_e32 v174, v174
	s_nop 0
	v_fmac_f32_e32 v95, v174, v167
	v_cndmask_b32_e64 v167, 0, 1, s[14:15]
	v_cmp_ne_u32_e64 s[4:5], 1, v167
	global_store_dwordx4 v[178:179], v[92:95], off
	s_cbranch_vccnz .LBB0_1888
	v_cvt_pk_bf16_f32 v174, v92, v93
	v_cvt_pk_bf16_f32 v175, v94, v95
	v_lshl_add_u64 v[140:141], v[140:141], 1, s[8:9]
	flat_store_dwordx2 v[140:141], v[174:175]

; DEVI float fsig(float x) { return __builtin_amdgcn_rcpf(1.f + __expf(-x)); }
; DEVI float bflo(unsigned u) { return __uint_as_float(u << 16); }
; DEVI float bfhi(unsigned u) { return __uint_as_float(u & 0xffff0000u); }
; template <int EPI, int TS, bool VT>
; DEVI void gemm_epilogue(const Params& p, char* smem, f32x4 (&acc)[2][2][4][2], int m0, int n0, float scale, const float* ssin,
;                         float* ssout, u16* xbout, int wid, int lane, int wr, int wc, int fr, int fq) {
;     ...
;           if constexpr (EPI == E_RESID || EPI == E_PLEGATE) {
;             const float4 a = *(const float4*)(Tr + 4 * lane);
;             const size_t ro = (size_t)grow * 1024 + n0 + 4 * lane;
;             float4 x4 = xo[u];
;             if constexpr (EPI == E_PLEGATE) {
;               x4.x += bflo(pv[u].x) * fsig(a.x * rs);
;               x4.y += bfhi(pv[u].x) * fsig(a.y * rs);
;               x4.z += bflo(pv[u].y) * fsig(a.z * rs);
;               x4.w += bfhi(pv[u].y) * fsig(a.w * rs);
;             } else {
;               const float sc = fabsf(scale);
;               x4.x += sc * a.x; x4.y += sc * a.y; x4.z += sc * a.z; x4.w += sc * a.w;
;             }
;             st_nt16(p.x + ro, x4);
;             if (xbout) {
;               uint2 o;
;               o.x = pack2(x4.x, x4.y);
;               o.y = pack2(x4.z, x4.w);
;               st_nt8(xbout + ro, o);
;             }
.LBB0_1892:
	ds_read_b128 v[92:95], v142 offset:1040
	v_readlane_b32 s21, v165, 1
	s_and_b64 vcc, exec, s[4:5]
	s_waitcnt lgkmcnt(0)
	v_mul_f32_e32 v92, s21, v92
	v_mul_f32_e32 v93, s21, v93
	v_mul_f32_e32 v92, 0xbfb8aa3b, v92
	v_mul_f32_e32 v93, 0xbfb8aa3b, v93
	v_mul_f32_e32 v94, s21, v94
	v_mul_f32_e32 v95, s21, v95
	v_exp_f32_e32 v140, v92
	v_exp_f32_e32 v141, v93
	v_mul_f32_e32 v94, 0xbfb8aa3b, v94
	v_mul_f32_e32 v95, 0xbfb8aa3b, v95
	v_exp_f32_e32 v94, v94
	v_exp_f32_e32 v95, v95
	v_lshlrev_b32_e32 v92, 16, v138
	v_and_b32_e32 v93, 0xffff0000, v138
	v_add_f32_e32 v138, 1.0, v140
	v_add_f32_e32 v141, 1.0, v141
	v_rcp_f32_e32 v140, v138
	v_rcp_f32_e32 v141, v141
	v_add_f32_e32 v94, 1.0, v94
	v_add_f32_e32 v95, 1.0, v95
	v_rcp_f32_e32 v94, v94
	v_rcp_f32_e32 v95, v95
	v_pk_fma_f32 v[88:89], v[140:141], v[92:93], v[88:89]
	v_lshlrev_b32_e32 v92, 16, v139
	v_and_b32_e32 v93, 0xffff0000, v139
	v_pk_fma_f32 v[90:91], v[94:95], v[92:93], v[90:91]
	global_store_dwordx4 v[136:137], v[88:91], off
	s_cbranch_vccnz .LBB0_1894
	v_cvt_pk_bf16_f32 v92, v88, v89
	v_cvt_pk_bf16_f32 v93, v90, v91
	v_lshl_add_u64 v[94:95], v[134:135], 1, s[8:9]
	flat_store_dwordx2 v[94:95], v[92:93]

; DEVI float fsig(float x) { return __builtin_amdgcn_rcpf(1.f + __expf(-x)); }
; DEVI float bflo(unsigned u) { return __uint_as_float(u << 16); }
; DEVI float bfhi(unsigned u) { return __uint_as_float(u & 0xffff0000u); }
; template <int EPI, int TS, bool VT>
; DEVI void gemm_epilogue(const Params& p, char* smem, f32x4 (&acc)[2][2][4][2], int m0, int n0, float scale, const float* ssin,
;                         float* ssout, u16* xbout, int wid, int lane, int wr, int wc, int fr, int fq) {
;     ...
;           if constexpr (EPI == E_RESID || EPI == E_PLEGATE) {
;             const float4 a = *(const float4*)(Tr + 4 * lane);
;             const size_t ro = (size_t)grow * 1024 + n0 + 4 * lane;
;             float4 x4 = xo[u];
;             if constexpr (EPI == E_PLEGATE) {
;               x4.x += bflo(pv[u].x) * fsig(a.x * rs);
;               x4.y += bfhi(pv[u].x) * fsig(a.y * rs);
;               x4.z += bflo(pv[u].y) * fsig(a.z * rs);
;               x4.w += bfhi(pv[u].y) * fsig(a.w * rs);
;             } else {
;               const float sc = fabsf(scale);
;               x4.x += sc * a.x; x4.y += sc * a.y; x4.z += sc * a.z; x4.w += sc * a.w;
;             }
;             st_nt16(p.x + ro, x4);
;             if (xbout) {
;               uint2 o;
;               o.x = pack2(x4.x, x4.y);
;               o.y = pack2(x4.z, x4.w);
;               st_nt8(xbout + ro, o);
;             }
.LBB0_1898:
	ds_read_b128 v[88:91], v142 offset:2080
	v_readlane_b32 s21, v165, 2
	s_and_b64 vcc, exec, s[4:5]
	s_waitcnt lgkmcnt(0)
	v_mul_f32_e32 v88, s21, v88
	v_mul_f32_e32 v89, s21, v89
	v_mul_f32_e32 v88, 0xbfb8aa3b, v88
	v_mul_f32_e32 v89, 0xbfb8aa3b, v89
	v_mul_f32_e32 v90, s21, v90
	v_mul_f32_e32 v91, s21, v91
	v_exp_f32_e32 v92, v88
	v_exp_f32_e32 v93, v89
	v_mul_f32_e32 v90, 0xbfb8aa3b, v90
	v_mul_f32_e32 v91, 0xbfb8aa3b, v91
	v_exp_f32_e32 v90, v90
	v_exp_f32_e32 v91, v91
	v_add_f32_e32 v92, 1.0, v92
	v_add_f32_e32 v93, 1.0, v93
	v_rcp_f32_e32 v92, v92
	v_rcp_f32_e32 v93, v93
	v_add_f32_e32 v90, 1.0, v90
	v_add_f32_e32 v91, 1.0, v91
	v_rcp_f32_e32 v90, v90
	v_rcp_f32_e32 v91, v91
	v_lshlrev_b32_e32 v88, 16, v132
	v_and_b32_e32 v89, 0xffff0000, v132
	v_pk_fma_f32 v[84:85], v[92:93], v[88:89], v[84:85]
	v_lshlrev_b32_e32 v88, 16, v133
	v_and_b32_e32 v89, 0xffff0000, v133
	v_pk_fma_f32 v[86:87], v[90:91], v[88:89], v[86:87]
	global_store_dwordx4 v[130:131], v[84:87], off
	s_cbranch_vccnz .LBB0_1900
	v_cvt_pk_bf16_f32 v88, v84, v85
	v_cvt_pk_bf16_f32 v89, v86, v87
	v_lshl_add_u64 v[90:91], v[126:127], 1, s[8:9]
	flat_store_dwordx2 v[90:91], v[88:89]

; DEVI float fsig(float x) { return __builtin_amdgcn_rcpf(1.f + __expf(-x)); }
; DEVI float bflo(unsigned u) { return __uint_as_float(u << 16); }
; DEVI float bfhi(unsigned u) { return __uint_as_float(u & 0xffff0000u); }
; template <int EPI, int TS, bool VT>
; DEVI void gemm_epilogue(const Params& p, char* smem, f32x4 (&acc)[2][2][4][2], int m0, int n0, float scale, const float* ssin,
;                         float* ssout, u16* xbout, int wid, int lane, int wr, int wc, int fr, int fq) {
;     ...
;           if constexpr (EPI == E_RESID || EPI == E_PLEGATE) {
;             const float4 a = *(const float4*)(Tr + 4 * lane);
;             const size_t ro = (size_t)grow * 1024 + n0 + 4 * lane;
;             float4 x4 = xo[u];
;             if constexpr (EPI == E_PLEGATE) {
;               x4.x += bflo(pv[u].x) * fsig(a.x * rs);
;               x4.y += bfhi(pv[u].x) * fsig(a.y * rs);
;               x4.z += bflo(pv[u].y) * fsig(a.z * rs);
;               x4.w += bfhi(pv[u].y) * fsig(a.w * rs);
;             } else {
;               const float sc = fabsf(scale);
;               x4.x += sc * a.x; x4.y += sc * a.y; x4.z += sc * a.z; x4.w += sc * a.w;
;             }
;             st_nt16(p.x + ro, x4);
;             if (xbout) {
;               uint2 o;
;               o.x = pack2(x4.x, x4.y);
;               o.y = pack2(x4.z, x4.w);
;               st_nt8(xbout + ro, o);
;             }
.LBB0_1904:
	ds_read_b128 v[84:87], v142 offset:3120
	v_readlane_b32 s21, v165, 3
	s_and_b64 vcc, exec, s[4:5]
	s_waitcnt lgkmcnt(0)
	v_mul_f32_e32 v84, s21, v84
	v_mul_f32_e32 v85, s21, v85
	v_mul_f32_e32 v84, 0xbfb8aa3b, v84
	v_mul_f32_e32 v85, 0xbfb8aa3b, v85
	v_mul_f32_e32 v86, s21, v86
	v_mul_f32_e32 v87, s21, v87
	v_exp_f32_e32 v88, v84
	v_exp_f32_e32 v89, v85
	v_mul_f32_e32 v86, 0xbfb8aa3b, v86
	v_mul_f32_e32 v87, 0xbfb8aa3b, v87
	v_exp_f32_e32 v86, v86
	v_exp_f32_e32 v87, v87
	v_add_f32_e32 v88, 1.0, v88
	v_add_f32_e32 v89, 1.0, v89
	v_rcp_f32_e32 v88, v88
	v_rcp_f32_e32 v89, v89
	v_add_f32_e32 v86, 1.0, v86
	v_add_f32_e32 v87, 1.0, v87
	v_rcp_f32_e32 v86, v86
	v_rcp_f32_e32 v87, v87
	v_lshlrev_b32_e32 v84, 16, v124
	v_and_b32_e32 v85, 0xffff0000, v124
	v_pk_fma_f32 v[80:81], v[88:89], v[84:85], v[80:81]
	v_lshlrev_b32_e32 v84, 16, v125
	v_and_b32_e32 v85, 0xffff0000, v125
	v_pk_fma_f32 v[82:83], v[86:87], v[84:85], v[82:83]
	global_store_dwordx4 v[122:123], v[80:83], off
	s_cbranch_vccnz .LBB0_1906
	v_cvt_pk_bf16_f32 v84, v80, v81
	v_cvt_pk_bf16_f32 v85, v82, v83
	v_lshl_add_u64 v[86:87], v[120:121], 1, s[8:9]
	flat_store_dwordx2 v[86:87], v[84:85]

; DEVI float fsig(float x) { return __builtin_amdgcn_rcpf(1.f + __expf(-x)); }
; DEVI float bflo(unsigned u) { return __uint_as_float(u << 16); }
; DEVI float bfhi(unsigned u) { return __uint_as_float(u & 0xffff0000u); }
; template <int EPI, int TS, bool VT>
; DEVI void gemm_epilogue(const Params& p, char* smem, f32x4 (&acc)[2][2][4][2], int m0, int n0, float scale, const float* ssin,
;                         float* ssout, u16* xbout, int wid, int lane, int wr, int wc, int fr, int fq) {
;     ...
;           if constexpr (EPI == E_RESID || EPI == E_PLEGATE) {
;             const float4 a = *(const float4*)(Tr + 4 * lane);
;             const size_t ro = (size_t)grow * 1024 + n0 + 4 * lane;
;             float4 x4 = xo[u];
;             if constexpr (EPI == E_PLEGATE) {
;               x4.x += bflo(pv[u].x) * fsig(a.x * rs);
;               x4.y += bfhi(pv[u].x) * fsig(a.y * rs);
;               x4.z += bflo(pv[u].y) * fsig(a.z * rs);
;               x4.w += bfhi(pv[u].y) * fsig(a.w * rs);
;             } else {
;               const float sc = fabsf(scale);
;               x4.x += sc * a.x; x4.y += sc * a.y; x4.z += sc * a.z; x4.w += sc * a.w;
;             }
;             st_nt16(p.x + ro, x4);
;             if (xbout) {
;               uint2 o;
;               o.x = pack2(x4.x, x4.y);
;               o.y = pack2(x4.z, x4.w);
;               st_nt8(xbout + ro, o);
;             }
.LBB0_1910:
	ds_read_b128 v[80:83], v142 offset:4160
	v_readlane_b32 s21, v165, 4
	s_and_b64 vcc, exec, s[4:5]
	s_waitcnt lgkmcnt(0)
	v_mul_f32_e32 v80, s21, v80
	v_mul_f32_e32 v81, s21, v81
	v_mul_f32_e32 v80, 0xbfb8aa3b, v80
	v_mul_f32_e32 v81, 0xbfb8aa3b, v81
	v_mul_f32_e32 v82, s21, v82
	v_mul_f32_e32 v83, s21, v83
	v_exp_f32_e32 v84, v80
	v_exp_f32_e32 v85, v81
	v_mul_f32_e32 v82, 0xbfb8aa3b, v82
	v_mul_f32_e32 v83, 0xbfb8aa3b, v83
	v_exp_f32_e32 v82, v82
	v_exp_f32_e32 v83, v83
	v_add_f32_e32 v84, 1.0, v84
	v_add_f32_e32 v85, 1.0, v85
	v_rcp_f32_e32 v84, v84
	v_rcp_f32_e32 v85, v85
	v_add_f32_e32 v82, 1.0, v82
	v_add_f32_e32 v83, 1.0, v83
	v_rcp_f32_e32 v82, v82
	v_rcp_f32_e32 v83, v83
	v_lshlrev_b32_e32 v80, 16, v118
	v_and_b32_e32 v81, 0xffff0000, v118
	v_pk_fma_f32 v[76:77], v[84:85], v[80:81], v[76:77]
	v_lshlrev_b32_e32 v80, 16, v119
	v_and_b32_e32 v81, 0xffff0000, v119
	v_pk_fma_f32 v[78:79], v[82:83], v[80:81], v[78:79]
	global_store_dwordx4 v[116:117], v[76:79], off
	s_cbranch_vccnz .LBB0_1912
	v_cvt_pk_bf16_f32 v80, v76, v77
	v_cvt_pk_bf16_f32 v81, v78, v79
	v_lshl_add_u64 v[82:83], v[114:115], 1, s[8:9]
	flat_store_dwordx2 v[82:83], v[80:81]

; DEVI float fsig(float x) { return __builtin_amdgcn_rcpf(1.f + __expf(-x)); }
; DEVI float bflo(unsigned u) { return __uint_as_float(u << 16); }
; DEVI float bfhi(unsigned u) { return __uint_as_float(u & 0xffff0000u); }
; template <int EPI, int TS, bool VT>
; DEVI void gemm_epilogue(const Params& p, char* smem, f32x4 (&acc)[2][2][4][2], int m0, int n0, float scale, const float* ssin,
;                         float* ssout, u16* xbout, int wid, int lane, int wr, int wc, int fr, int fq) {
;     ...
;           if constexpr (EPI == E_RESID || EPI == E_PLEGATE) {
;             const float4 a = *(const float4*)(Tr + 4 * lane);
;             const size_t ro = (size_t)grow * 1024 + n0 + 4 * lane;
;             float4 x4 = xo[u];
;             if constexpr (EPI == E_PLEGATE) {
;               x4.x += bflo(pv[u].x) * fsig(a.x * rs);
;               x4.y += bfhi(pv[u].x) * fsig(a.y * rs);
;               x4.z += bflo(pv[u].y) * fsig(a.z * rs);
;               x4.w += bfhi(pv[u].y) * fsig(a.w * rs);
;             } else {
;               const float sc = fabsf(scale);
;               x4.x += sc * a.x; x4.y += sc * a.y; x4.z += sc * a.z; x4.w += sc * a.w;
;             }
;             st_nt16(p.x + ro, x4);
;             if (xbout) {
;               uint2 o;
;               o.x = pack2(x4.x, x4.y);
;               o.y = pack2(x4.z, x4.w);
;               st_nt8(xbout + ro, o);
;             }
.LBB0_1916:
	ds_read_b128 v[76:79], v142 offset:5200
	v_readlane_b32 s21, v165, 5
	s_and_b64 vcc, exec, s[4:5]
	s_waitcnt lgkmcnt(0)
	v_mul_f32_e32 v76, s21, v76
	v_mul_f32_e32 v77, s21, v77
	v_mul_f32_e32 v76, 0xbfb8aa3b, v76
	v_mul_f32_e32 v77, 0xbfb8aa3b, v77
	v_mul_f32_e32 v78, s21, v78
	v_mul_f32_e32 v79, s21, v79
	v_exp_f32_e32 v80, v76
	v_exp_f32_e32 v81, v77
	v_mul_f32_e32 v78, 0xbfb8aa3b, v78
	v_mul_f32_e32 v79, 0xbfb8aa3b, v79
	v_exp_f32_e32 v78, v78
	v_exp_f32_e32 v79, v79
	v_add_f32_e32 v80, 1.0, v80
	v_add_f32_e32 v81, 1.0, v81
	v_rcp_f32_e32 v80, v80
	v_rcp_f32_e32 v81, v81
	v_add_f32_e32 v78, 1.0, v78
	v_add_f32_e32 v79, 1.0, v79
	v_rcp_f32_e32 v78, v78
	v_rcp_f32_e32 v79, v79
	v_lshlrev_b32_e32 v76, 16, v112
	v_and_b32_e32 v77, 0xffff0000, v112
	v_pk_fma_f32 v[72:73], v[80:81], v[76:77], v[72:73]
	v_lshlrev_b32_e32 v76, 16, v113
	v_and_b32_e32 v77, 0xffff0000, v113
	v_pk_fma_f32 v[74:75], v[78:79], v[76:77], v[74:75]
	global_store_dwordx4 v[110:111], v[72:75], off
	s_cbranch_vccnz .LBB0_1918
	v_cvt_pk_bf16_f32 v76, v72, v73
	v_cvt_pk_bf16_f32 v77, v74, v75
	v_lshl_add_u64 v[78:79], v[108:109], 1, s[8:9]
	flat_store_dwordx2 v[78:79], v[76:77]

; DEVI float fsig(float x) { return __builtin_amdgcn_rcpf(1.f + __expf(-x)); }
; DEVI float bflo(unsigned u) { return __uint_as_float(u << 16); }
; DEVI float bfhi(unsigned u) { return __uint_as_float(u & 0xffff0000u); }
; template <int EPI, int TS, bool VT>
; DEVI void gemm_epilogue(const Params& p, char* smem, f32x4 (&acc)[2][2][4][2], int m0, int n0, float scale, const float* ssin,
;                         float* ssout, u16* xbout, int wid, int lane, int wr, int wc, int fr, int fq) {
;     ...
;           if constexpr (EPI == E_RESID || EPI == E_PLEGATE) {
;             const float4 a = *(const float4*)(Tr + 4 * lane);
;             const size_t ro = (size_t)grow * 1024 + n0 + 4 * lane;
;             float4 x4 = xo[u];
;             if constexpr (EPI == E_PLEGATE) {
;               x4.x += bflo(pv[u].x) * fsig(a.x * rs);
;               x4.y += bfhi(pv[u].x) * fsig(a.y * rs);
;               x4.z += bflo(pv[u].y) * fsig(a.z * rs);
;               x4.w += bfhi(pv[u].y) * fsig(a.w * rs);
;             } else {
;               const float sc = fabsf(scale);
;               x4.x += sc * a.x; x4.y += sc * a.y; x4.z += sc * a.z; x4.w += sc * a.w;
;             }
;             st_nt16(p.x + ro, x4);
;             if (xbout) {
;               uint2 o;
;               o.x = pack2(x4.x, x4.y);
;               o.y = pack2(x4.z, x4.w);
;               st_nt8(xbout + ro, o);
;             }
.LBB0_1922:
	ds_read_b128 v[72:75], v142 offset:6240
	v_readlane_b32 s21, v165, 6
	s_and_b64 vcc, exec, s[4:5]
	s_waitcnt lgkmcnt(0)
	v_mul_f32_e32 v72, s21, v72
	v_mul_f32_e32 v73, s21, v73
	v_mul_f32_e32 v72, 0xbfb8aa3b, v72
	v_mul_f32_e32 v73, 0xbfb8aa3b, v73
	v_mul_f32_e32 v74, s21, v74
	v_mul_f32_e32 v75, s21, v75
	v_exp_f32_e32 v76, v72
	v_exp_f32_e32 v77, v73
	v_mul_f32_e32 v74, 0xbfb8aa3b, v74
	v_mul_f32_e32 v75, 0xbfb8aa3b, v75
	v_exp_f32_e32 v74, v74
	v_exp_f32_e32 v75, v75
	v_add_f32_e32 v76, 1.0, v76
	v_add_f32_e32 v77, 1.0, v77
	v_rcp_f32_e32 v76, v76
	v_rcp_f32_e32 v77, v77
	v_add_f32_e32 v74, 1.0, v74
	v_add_f32_e32 v75, 1.0, v75
	v_rcp_f32_e32 v74, v74
	v_rcp_f32_e32 v75, v75
	v_lshlrev_b32_e32 v72, 16, v106
	v_and_b32_e32 v73, 0xffff0000, v106
	v_pk_fma_f32 v[68:69], v[76:77], v[72:73], v[68:69]
	v_lshlrev_b32_e32 v72, 16, v107
	v_and_b32_e32 v73, 0xffff0000, v107
	v_pk_fma_f32 v[70:71], v[74:75], v[72:73], v[70:71]
	global_store_dwordx4 v[104:105], v[68:71], off
	s_cbranch_vccnz .LBB0_1924
	v_cvt_pk_bf16_f32 v72, v68, v69
	v_cvt_pk_bf16_f32 v73, v70, v71
	v_lshl_add_u64 v[74:75], v[102:103], 1, s[8:9]
	flat_store_dwordx2 v[74:75], v[72:73]

; DEVI float fsig(float x) { return __builtin_amdgcn_rcpf(1.f + __expf(-x)); }
; DEVI float bflo(unsigned u) { return __uint_as_float(u << 16); }
; DEVI float bfhi(unsigned u) { return __uint_as_float(u & 0xffff0000u); }
; template <int EPI, int TS, bool VT>
; DEVI void gemm_epilogue(const Params& p, char* smem, f32x4 (&acc)[2][2][4][2], int m0, int n0, float scale, const float* ssin,
;                         float* ssout, u16* xbout, int wid, int lane, int wr, int wc, int fr, int fq) {
;     ...
;           if constexpr (EPI == E_RESID || EPI == E_PLEGATE) {
;             const float4 a = *(const float4*)(Tr + 4 * lane);
;             const size_t ro = (size_t)grow * 1024 + n0 + 4 * lane;
;             float4 x4 = xo[u];
;             if constexpr (EPI == E_PLEGATE) {
;               x4.x += bflo(pv[u].x) * fsig(a.x * rs);
;               x4.y += bfhi(pv[u].x) * fsig(a.y * rs);
;               x4.z += bflo(pv[u].y) * fsig(a.z * rs);
;               x4.w += bfhi(pv[u].y) * fsig(a.w * rs);
;             } else {
;               const float sc = fabsf(scale);
;               x4.x += sc * a.x; x4.y += sc * a.y; x4.z += sc * a.z; x4.w += sc * a.w;
;             }
;             st_nt16(p.x + ro, x4);
;             if (xbout) {
;               uint2 o;
;               o.x = pack2(x4.x, x4.y);
;               o.y = pack2(x4.z, x4.w);
;               st_nt8(xbout + ro, o);
;             }
.LBB0_1928:
	ds_read_b128 v[68:71], v142 offset:7280
	v_readlane_b32 s21, v165, 7
	s_and_b64 vcc, exec, s[4:5]
	s_waitcnt lgkmcnt(0)
	v_mul_f32_e32 v68, s21, v68
	v_mul_f32_e32 v69, s21, v69
	v_mul_f32_e32 v68, 0xbfb8aa3b, v68
	v_mul_f32_e32 v69, 0xbfb8aa3b, v69
	v_mul_f32_e32 v70, s21, v70
	v_mul_f32_e32 v71, s21, v71
	v_exp_f32_e32 v72, v68
	v_exp_f32_e32 v73, v69
	v_mul_f32_e32 v70, 0xbfb8aa3b, v70
	v_mul_f32_e32 v71, 0xbfb8aa3b, v71
	v_exp_f32_e32 v70, v70
	v_exp_f32_e32 v71, v71
	v_add_f32_e32 v72, 1.0, v72
	v_add_f32_e32 v73, 1.0, v73
	v_rcp_f32_e32 v72, v72
	v_rcp_f32_e32 v73, v73
	v_add_f32_e32 v70, 1.0, v70
	v_add_f32_e32 v71, 1.0, v71
	v_rcp_f32_e32 v70, v70
	v_rcp_f32_e32 v71, v71
	v_lshlrev_b32_e32 v68, 16, v100
	v_and_b32_e32 v69, 0xffff0000, v100
	v_pk_fma_f32 v[64:65], v[72:73], v[68:69], v[64:65]
	v_lshlrev_b32_e32 v68, 16, v101
	v_and_b32_e32 v69, 0xffff0000, v101
	v_pk_fma_f32 v[66:67], v[70:71], v[68:69], v[66:67]
	global_store_dwordx4 v[98:99], v[64:67], off
	s_cbranch_vccnz .LBB0_1930
	v_cvt_pk_bf16_f32 v68, v64, v65
	v_cvt_pk_bf16_f32 v69, v66, v67
	v_lshl_add_u64 v[70:71], v[96:97], 1, s[8:9]
	flat_store_dwordx2 v[70:71], v[68:69]

; DEVI float fsig(float x) { return __builtin_amdgcn_rcpf(1.f + __expf(-x)); }
; DEVI float bflo(unsigned u) { return __uint_as_float(u << 16); }
; template <int EPI, int TS, bool VT>
; DEVI void gemm_epilogue(const Params& p, char* smem, f32x4 (&acc)[2][2][4][2], int m0, int n0, float scale, const float* ssin,
;                         float* ssout, u16* xbout, int wid, int lane, int wr, int wc, int fr, int fq) {
;     ...
; #pragma unroll
;           for (int u = 0; u < 8; ++u) {
;             const size_t ro = (size_t)(g0 + i0 + u) * 1024 + n0 + 4 * lane;
;             const int gr = g0 + i0 + u;
;             const float* xs = p.x + ro;
;             if (scale < 0.f)
;               xs = (gr < MP ? p.x_prompt + ro : p.x_sample + (ro - (size_t)MP * 1024));
;             { const f32x4 t_ = __builtin_nontemporal_load((const f32x4*)xs); xo[u] = make_float4(t_[0], t_[1], t_[2], t_[3]); }
;             if constexpr (EPI == E_PLEGATE) {
;               const unsigned long long t2_ = __builtin_nontemporal_load((const unsigned long long*)((const u16*)(wsb + OFF_PP) + ro));
;               pv[u] = make_uint2((unsigned)t2_, (unsigned)(t2_ >> 32));
;             }
;           }
;         }
; #pragma unroll
;         for (int u = 0; u < 8; ++u) {
;           const int i = i0 + u;
;           const int grow = g0 + i;
;           const float* Tr = T + (r0 + i) * TS;
;           const float rs = __int_as_float(__builtin_amdgcn_readlane(__float_as_int(rsv), i));
;           if constexpr (EPI == E_RESID || EPI == E_PLEGATE) {
;             const float4 a = *(const float4*)(Tr + 4 * lane);
;             const size_t ro = (size_t)grow * 1024 + n0 + 4 * lane;
;             float4 x4 = xo[u];
;             if constexpr (EPI == E_PLEGATE) {
;               x4.x += bflo(pv[u].x) * fsig(a.x * rs);
;               x4.y += bfhi(pv[u].x) * fsig(a.y * rs);
;               x4.z += bflo(pv[u].y) * fsig(a.z * rs);
;               x4.w += bfhi(pv[u].y) * fsig(a.w * rs);
;             } else {
;               const float sc = fabsf(scale);
;               x4.x += sc * a.x; x4.y += sc * a.y; x4.z += sc * a.z; x4.w += sc * a.w;
;             }
;             st_nt16(p.x + ro, x4);
;             if (xbout) {
;               uint2 o;
;               o.x = pack2(x4.x, x4.y);
;               o.y = pack2(x4.z, x4.w);
;               st_nt8(xbout + ro, o);
.LBB0_1934:
	s_or_b32 s70, s20, 8
	s_ashr_i32 s71, s70, 31
	s_or_b32 s68, s20, 9
	s_lshl_b64 s[22:23], s[70:71], 10
	s_ashr_i32 s69, s68, 31
	s_or_b32 s66, s20, 10
	v_lshl_add_u64 v[140:141], s[22:23], 0, v[128:129]
	s_lshl_b64 s[22:23], s[68:69], 10
	s_ashr_i32 s67, s66, 31
	s_or_b32 s64, s20, 11
	v_lshl_add_u64 v[134:135], s[22:23], 0, v[128:129]
	s_lshl_b64 s[22:23], s[66:67], 10
	s_ashr_i32 s65, s64, 31
	s_or_b32 s62, s20, 12
	v_lshl_add_u64 v[126:127], s[22:23], 0, v[128:129]
	s_lshl_b64 s[22:23], s[64:65], 10
	s_ashr_i32 s63, s62, 31
	s_or_b32 s34, s20, 13
	v_lshl_add_u64 v[120:121], s[22:23], 0, v[128:129]
	s_lshl_b64 s[22:23], s[62:63], 10
	s_ashr_i32 s35, s34, 31
	s_or_b32 s30, s20, 14
	v_lshl_add_u64 v[114:115], s[22:23], 0, v[128:129]
	s_lshl_b64 s[22:23], s[34:35], 10
	s_ashr_i32 s31, s30, 31
	v_lshl_add_u64 v[108:109], s[22:23], 0, v[128:129]
	s_lshl_b64 s[22:23], s[30:31], 10
	v_lshl_add_u64 v[166:167], v[140:141], 2, s[38:39]
	v_lshl_add_u64 v[102:103], s[22:23], 0, v[128:129]
	s_or_b32 s22, s20, 15
	global_load_dwordx4 v[92:95], v[166:167], off
	s_ashr_i32 s23, s22, 31
	v_lshl_add_u64 v[64:65], v[140:141], 1, s[18:19]
	v_lshl_add_u64 v[136:137], v[134:135], 2, s[38:39]
	s_lshl_b64 s[72:73], s[22:23], 10
	v_lshl_add_u64 v[66:67], v[134:135], 1, s[18:19]
	v_lshl_add_u64 v[130:131], v[126:127], 2, s[38:39]
	global_load_dwordx4 v[88:91], v[136:137], off
	global_load_dwordx4 v[84:87], v[130:131], off
	v_lshl_add_u64 v[68:69], v[126:127], 1, s[18:19]
	v_lshl_add_u64 v[70:71], v[120:121], 1, s[18:19]
	flat_load_dwordx2 v[178:179], v[64:65]
	flat_load_dwordx2 v[138:139], v[66:67]
	flat_load_dwordx2 v[132:133], v[68:69]
	flat_load_dwordx2 v[124:125], v[70:71]
	v_lshl_add_u64 v[96:97], s[72:73], 0, v[128:129]
	v_lshl_add_u64 v[122:123], v[120:121], 2, s[38:39]
	v_lshl_add_u64 v[100:101], v[114:115], 1, s[18:19]
	v_lshl_add_u64 v[110:111], v[108:109], 2, s[38:39]
	v_lshl_add_u64 v[106:107], v[108:109], 1, s[18:19]
	v_lshl_add_u64 v[98:99], v[96:97], 2, s[38:39]
	v_lshl_add_u64 v[116:117], v[114:115], 2, s[38:39]
	global_load_dwordx4 v[80:83], v[122:123], off
	global_load_dwordx4 v[76:79], v[116:117], off
	v_lshl_add_u64 v[104:105], v[102:103], 2, s[38:39]
	global_load_dwordx4 v[72:75], v[110:111], off
	global_load_dwordx4 v[68:71], v[104:105], off
	v_lshl_add_u64 v[174:175], v[102:103], 1, s[18:19]
	global_load_dwordx4 v[64:67], v[98:99], off
	v_lshl_add_u64 v[176:177], v[96:97], 1, s[18:19]
	flat_load_dwordx2 v[118:119], v[100:101]
	flat_load_dwordx2 v[112:113], v[106:107]
	s_nop 0
	flat_load_dwordx2 v[106:107], v[174:175]
	flat_load_dwordx2 v[100:101], v[176:177]
	ds_read_b128 v[174:177], v142 offset:8320
	v_readlane_b32 s21, v165, 8
	s_and_b64 vcc, exec, s[4:5]
	s_waitcnt vmcnt(0) lgkmcnt(0)
	v_lshlrev_b32_e32 v180, 16, v178
	v_mul_f32_e32 v174, s21, v174
	v_mul_f32_e32 v175, s21, v175
	v_mul_f32_e32 v174, 0xbfb8aa3b, v174
	v_mul_f32_e32 v175, 0xbfb8aa3b, v175
	v_exp_f32_e32 v174, v174
	v_exp_f32_e32 v175, v175
	v_mul_f32_e32 v176, s21, v176
	v_mul_f32_e32 v177, s21, v177
	v_mul_f32_e32 v176, 0xbfb8aa3b, v176
	v_mul_f32_e32 v177, 0xbfb8aa3b, v177
	v_exp_f32_e32 v176, v176
	v_add_f32_e32 v174, 1.0, v174
	v_add_f32_e32 v175, 1.0, v175
	v_exp_f32_e32 v177, v177
	v_rcp_f32_e32 v174, v174
	v_rcp_f32_e32 v175, v175
	v_add_f32_e32 v176, 1.0, v176
	v_and_b32_e32 v178, 0xffff0000, v178
	v_fma_f32 v92, v174, v180, v92
	v_fma_f32 v93, v175, v178, v93
	v_rcp_f32_e32 v174, v176
	v_add_f32_e32 v175, 1.0, v177
	v_rcp_f32_e32 v175, v175
	v_lshlrev_b32_e32 v176, 16, v179
	v_fma_f32 v94, v174, v176, v94
	v_and_b32_e32 v174, 0xffff0000, v179
	v_fmac_f32_e32 v95, v175, v174
	global_store_dwordx4 v[166:167], v[92:95], off
	s_cbranch_vccnz .LBB0_1936
	v_cvt_pk_bf16_f32 v166, v92, v93
	v_cvt_pk_bf16_f32 v167, v94, v95
	v_lshl_add_u64 v[140:141], v[140:141], 1, s[8:9]
	flat_store_dwordx2 v[140:141], v[166:167]

; DEVI float fsig(float x) { return __builtin_amdgcn_rcpf(1.f + __expf(-x)); }
; DEVI float bflo(unsigned u) { return __uint_as_float(u << 16); }
; DEVI float bfhi(unsigned u) { return __uint_as_float(u & 0xffff0000u); }
; template <int EPI, int TS, bool VT>
; DEVI void gemm_epilogue(const Params& p, char* smem, f32x4 (&acc)[2][2][4][2], int m0, int n0, float scale, const float* ssin,
;                         float* ssout, u16* xbout, int wid, int lane, int wr, int wc, int fr, int fq) {
;     ...
;           if constexpr (EPI == E_RESID || EPI == E_PLEGATE) {
;             const float4 a = *(const float4*)(Tr + 4 * lane);
;             const size_t ro = (size_t)grow * 1024 + n0 + 4 * lane;
;             float4 x4 = xo[u];
;             if constexpr (EPI == E_PLEGATE) {
;               x4.x += bflo(pv[u].x) * fsig(a.x * rs);
;               x4.y += bfhi(pv[u].x) * fsig(a.y * rs);
;               x4.z += bflo(pv[u].y) * fsig(a.z * rs);
;               x4.w += bfhi(pv[u].y) * fsig(a.w * rs);
;             } else {
;               const float sc = fabsf(scale);
;               x4.x += sc * a.x; x4.y += sc * a.y; x4.z += sc * a.z; x4.w += sc * a.w;
;             }
;             st_nt16(p.x + ro, x4);
;             if (xbout) {
;               uint2 o;
;               o.x = pack2(x4.x, x4.y);
;               o.y = pack2(x4.z, x4.w);
;               st_nt8(xbout + ro, o);
;             }
.LBB0_1940:
	ds_read_b128 v[92:95], v142 offset:9360
	v_readlane_b32 s21, v165, 9
	s_and_b64 vcc, exec, s[4:5]
	s_waitcnt lgkmcnt(0)
	v_mul_f32_e32 v92, s21, v92
	v_mul_f32_e32 v93, s21, v93
	v_mul_f32_e32 v92, 0xbfb8aa3b, v92
	v_mul_f32_e32 v93, 0xbfb8aa3b, v93
	v_mul_f32_e32 v94, s21, v94
	v_mul_f32_e32 v95, s21, v95
	v_exp_f32_e32 v140, v92
	v_exp_f32_e32 v141, v93
	v_mul_f32_e32 v94, 0xbfb8aa3b, v94
	v_mul_f32_e32 v95, 0xbfb8aa3b, v95
	v_exp_f32_e32 v94, v94
	v_exp_f32_e32 v95, v95
	v_lshlrev_b32_e32 v92, 16, v138
	v_and_b32_e32 v93, 0xffff0000, v138
	v_add_f32_e32 v138, 1.0, v140
	v_add_f32_e32 v141, 1.0, v141
	v_rcp_f32_e32 v140, v138
	v_rcp_f32_e32 v141, v141
	v_add_f32_e32 v94, 1.0, v94
	v_add_f32_e32 v95, 1.0, v95
	v_rcp_f32_e32 v94, v94
	v_rcp_f32_e32 v95, v95
	v_pk_fma_f32 v[88:89], v[140:141], v[92:93], v[88:89]
	v_lshlrev_b32_e32 v92, 16, v139
	v_and_b32_e32 v93, 0xffff0000, v139
	v_pk_fma_f32 v[90:91], v[94:95], v[92:93], v[90:91]
	global_store_dwordx4 v[136:137], v[88:91], off
	s_cbranch_vccnz .LBB0_1942
	v_cvt_pk_bf16_f32 v92, v88, v89
	v_cvt_pk_bf16_f32 v93, v90, v91
	v_lshl_add_u64 v[94:95], v[134:135], 1, s[8:9]
	flat_store_dwordx2 v[94:95], v[92:93]

; DEVI float fsig(float x) { return __builtin_amdgcn_rcpf(1.f + __expf(-x)); }
; DEVI float bflo(unsigned u) { return __uint_as_float(u << 16); }
; DEVI float bfhi(unsigned u) { return __uint_as_float(u & 0xffff0000u); }
; template <int EPI, int TS, bool VT>
; DEVI void gemm_epilogue(const Params& p, char* smem, f32x4 (&acc)[2][2][4][2], int m0, int n0, float scale, const float* ssin,
;                         float* ssout, u16* xbout, int wid, int lane, int wr, int wc, int fr, int fq) {
;     ...
;           if constexpr (EPI == E_RESID || EPI == E_PLEGATE) {
;             const float4 a = *(const float4*)(Tr + 4 * lane);
;             const size_t ro = (size_t)grow * 1024 + n0 + 4 * lane;
;             float4 x4 = xo[u];
;             if constexpr (EPI == E_PLEGATE) {
;               x4.x += bflo(pv[u].x) * fsig(a.x * rs);
;               x4.y += bfhi(pv[u].x) * fsig(a.y * rs);
;               x4.z += bflo(pv[u].y) * fsig(a.z * rs);
;               x4.w += bfhi(pv[u].y) * fsig(a.w * rs);
;             } else {
;               const float sc = fabsf(scale);
;               x4.x += sc * a.x; x4.y += sc * a.y; x4.z += sc * a.z; x4.w += sc * a.w;
;             }
;             st_nt16(p.x + ro, x4);
;             if (xbout) {
;               uint2 o;
;               o.x = pack2(x4.x, x4.y);
;               o.y = pack2(x4.z, x4.w);
;               st_nt8(xbout + ro, o);
;             }
.LBB0_1946:
	ds_read_b128 v[88:91], v142 offset:10400
	v_readlane_b32 s21, v165, 10
	s_and_b64 vcc, exec, s[4:5]
	s_waitcnt lgkmcnt(0)
	v_mul_f32_e32 v88, s21, v88
	v_mul_f32_e32 v89, s21, v89
	v_mul_f32_e32 v88, 0xbfb8aa3b, v88
	v_mul_f32_e32 v89, 0xbfb8aa3b, v89
	v_mul_f32_e32 v90, s21, v90
	v_mul_f32_e32 v91, s21, v91
	v_exp_f32_e32 v92, v88
	v_exp_f32_e32 v93, v89
	v_mul_f32_e32 v90, 0xbfb8aa3b, v90
	v_mul_f32_e32 v91, 0xbfb8aa3b, v91
	v_exp_f32_e32 v90, v90
	v_exp_f32_e32 v91, v91
	v_add_f32_e32 v92, 1.0, v92
	v_add_f32_e32 v93, 1.0, v93
	v_rcp_f32_e32 v92, v92
	v_rcp_f32_e32 v93, v93
	v_add_f32_e32 v90, 1.0, v90
	v_add_f32_e32 v91, 1.0, v91
	v_rcp_f32_e32 v90, v90
	v_rcp_f32_e32 v91, v91
	v_lshlrev_b32_e32 v88, 16, v132
	v_and_b32_e32 v89, 0xffff0000, v132
	v_pk_fma_f32 v[84:85], v[92:93], v[88:89], v[84:85]
	v_lshlrev_b32_e32 v88, 16, v133
	v_and_b32_e32 v89, 0xffff0000, v133
	v_pk_fma_f32 v[86:87], v[90:91], v[88:89], v[86:87]
	global_store_dwordx4 v[130:131], v[84:87], off
	s_cbranch_vccnz .LBB0_1948
	v_cvt_pk_bf16_f32 v88, v84, v85
	v_cvt_pk_bf16_f32 v89, v86, v87
	v_lshl_add_u64 v[90:91], v[126:127], 1, s[8:9]
	flat_store_dwordx2 v[90:91], v[88:89]

; DEVI float fsig(float x) { return __builtin_amdgcn_rcpf(1.f + __expf(-x)); }
; DEVI float bflo(unsigned u) { return __uint_as_float(u << 16); }
; DEVI float bfhi(unsigned u) { return __uint_as_float(u & 0xffff0000u); }
; template <int EPI, int TS, bool VT>
; DEVI void gemm_epilogue(const Params& p, char* smem, f32x4 (&acc)[2][2][4][2], int m0, int n0, float scale, const float* ssin,
;                         float* ssout, u16* xbout, int wid, int lane, int wr, int wc, int fr, int fq) {
;     ...
;           if constexpr (EPI == E_RESID || EPI == E_PLEGATE) {
;             const float4 a = *(const float4*)(Tr + 4 * lane);
;             const size_t ro = (size_t)grow * 1024 + n0 + 4 * lane;
;             float4 x4 = xo[u];
;             if constexpr (EPI == E_PLEGATE) {
;               x4.x += bflo(pv[u].x) * fsig(a.x * rs);
;               x4.y += bfhi(pv[u].x) * fsig(a.y * rs);
;               x4.z += bflo(pv[u].y) * fsig(a.z * rs);
;               x4.w += bfhi(pv[u].y) * fsig(a.w * rs);
;             } else {
;               const float sc = fabsf(scale);
;               x4.x += sc * a.x; x4.y += sc * a.y; x4.z += sc * a.z; x4.w += sc * a.w;
;             }
;             st_nt16(p.x + ro, x4);
;             if (xbout) {
;               uint2 o;
;               o.x = pack2(x4.x, x4.y);
;               o.y = pack2(x4.z, x4.w);
;               st_nt8(xbout + ro, o);
;             }
.LBB0_1952:
	ds_read_b128 v[84:87], v142 offset:11440
	v_readlane_b32 s21, v165, 11
	s_and_b64 vcc, exec, s[4:5]
	s_waitcnt lgkmcnt(0)
	v_mul_f32_e32 v84, s21, v84
	v_mul_f32_e32 v85, s21, v85
	v_mul_f32_e32 v84, 0xbfb8aa3b, v84
	v_mul_f32_e32 v85, 0xbfb8aa3b, v85
	v_mul_f32_e32 v86, s21, v86
	v_mul_f32_e32 v87, s21, v87
	v_exp_f32_e32 v88, v84
	v_exp_f32_e32 v89, v85
	v_mul_f32_e32 v86, 0xbfb8aa3b, v86
	v_mul_f32_e32 v87, 0xbfb8aa3b, v87
	v_exp_f32_e32 v86, v86
	v_exp_f32_e32 v87, v87
	v_add_f32_e32 v88, 1.0, v88
	v_add_f32_e32 v89, 1.0, v89
	v_rcp_f32_e32 v88, v88
	v_rcp_f32_e32 v89, v89
	v_add_f32_e32 v86, 1.0, v86
	v_add_f32_e32 v87, 1.0, v87
	v_rcp_f32_e32 v86, v86
	v_rcp_f32_e32 v87, v87
	v_lshlrev_b32_e32 v84, 16, v124
	v_and_b32_e32 v85, 0xffff0000, v124
	v_pk_fma_f32 v[80:81], v[88:89], v[84:85], v[80:81]
	v_lshlrev_b32_e32 v84, 16, v125
	v_and_b32_e32 v85, 0xffff0000, v125
	v_pk_fma_f32 v[82:83], v[86:87], v[84:85], v[82:83]
	global_store_dwordx4 v[122:123], v[80:83], off
	s_cbranch_vccnz .LBB0_1954
	v_cvt_pk_bf16_f32 v84, v80, v81
	v_cvt_pk_bf16_f32 v85, v82, v83
	v_lshl_add_u64 v[86:87], v[120:121], 1, s[8:9]
	flat_store_dwordx2 v[86:87], v[84:85]

; DEVI float fsig(float x) { return __builtin_amdgcn_rcpf(1.f + __expf(-x)); }
; DEVI float bflo(unsigned u) { return __uint_as_float(u << 16); }
; DEVI float bfhi(unsigned u) { return __uint_as_float(u & 0xffff0000u); }
; template <int EPI, int TS, bool VT>
; DEVI void gemm_epilogue(const Params& p, char* smem, f32x4 (&acc)[2][2][4][2], int m0, int n0, float scale, const float* ssin,
;                         float* ssout, u16* xbout, int wid, int lane, int wr, int wc, int fr, int fq) {
;     ...
;           if constexpr (EPI == E_RESID || EPI == E_PLEGATE) {
;             const float4 a = *(const float4*)(Tr + 4 * lane);
;             const size_t ro = (size_t)grow * 1024 + n0 + 4 * lane;
;             float4 x4 = xo[u];
;             if constexpr (EPI == E_PLEGATE) {
;               x4.x += bflo(pv[u].x) * fsig(a.x * rs);
;               x4.y += bfhi(pv[u].x) * fsig(a.y * rs);
;               x4.z += bflo(pv[u].y) * fsig(a.z * rs);
;               x4.w += bfhi(pv[u].y) * fsig(a.w * rs);
;             } else {
;               const float sc = fabsf(scale);
;               x4.x += sc * a.x; x4.y += sc * a.y; x4.z += sc * a.z; x4.w += sc * a.w;
;             }
;             st_nt16(p.x + ro, x4);
;             if (xbout) {
;               uint2 o;
;               o.x = pack2(x4.x, x4.y);
;               o.y = pack2(x4.z, x4.w);
;               st_nt8(xbout + ro, o);
;             }
.LBB0_1958:
	ds_read_b128 v[80:83], v142 offset:12480
	v_readlane_b32 s21, v165, 12
	s_and_b64 vcc, exec, s[4:5]
	s_waitcnt lgkmcnt(0)
	v_mul_f32_e32 v80, s21, v80
	v_mul_f32_e32 v81, s21, v81
	v_mul_f32_e32 v80, 0xbfb8aa3b, v80
	v_mul_f32_e32 v81, 0xbfb8aa3b, v81
	v_mul_f32_e32 v82, s21, v82
	v_mul_f32_e32 v83, s21, v83
	v_exp_f32_e32 v84, v80
	v_exp_f32_e32 v85, v81
	v_mul_f32_e32 v82, 0xbfb8aa3b, v82
	v_mul_f32_e32 v83, 0xbfb8aa3b, v83
	v_exp_f32_e32 v82, v82
	v_exp_f32_e32 v83, v83
	v_add_f32_e32 v84, 1.0, v84
	v_add_f32_e32 v85, 1.0, v85
	v_rcp_f32_e32 v84, v84
	v_rcp_f32_e32 v85, v85
	v_add_f32_e32 v82, 1.0, v82
	v_add_f32_e32 v83, 1.0, v83
	v_rcp_f32_e32 v82, v82
	v_rcp_f32_e32 v83, v83
	v_lshlrev_b32_e32 v80, 16, v118
	v_and_b32_e32 v81, 0xffff0000, v118
	v_pk_fma_f32 v[76:77], v[84:85], v[80:81], v[76:77]
	v_lshlrev_b32_e32 v80, 16, v119
	v_and_b32_e32 v81, 0xffff0000, v119
	v_pk_fma_f32 v[78:79], v[82:83], v[80:81], v[78:79]
	global_store_dwordx4 v[116:117], v[76:79], off
	s_cbranch_vccnz .LBB0_1960
	v_cvt_pk_bf16_f32 v80, v76, v77
	v_cvt_pk_bf16_f32 v81, v78, v79
	v_lshl_add_u64 v[82:83], v[114:115], 1, s[8:9]
	flat_store_dwordx2 v[82:83], v[80:81]

; DEVI float fsig(float x) { return __builtin_amdgcn_rcpf(1.f + __expf(-x)); }
; DEVI float bflo(unsigned u) { return __uint_as_float(u << 16); }
; DEVI float bfhi(unsigned u) { return __uint_as_float(u & 0xffff0000u); }
; template <int EPI, int TS, bool VT>
; DEVI void gemm_epilogue(const Params& p, char* smem, f32x4 (&acc)[2][2][4][2], int m0, int n0, float scale, const float* ssin,
;                         float* ssout, u16* xbout, int wid, int lane, int wr, int wc, int fr, int fq) {
;     ...
;           if constexpr (EPI == E_RESID || EPI == E_PLEGATE) {
;             const float4 a = *(const float4*)(Tr + 4 * lane);
;             const size_t ro = (size_t)grow * 1024 + n0 + 4 * lane;
;             float4 x4 = xo[u];
;             if constexpr (EPI == E_PLEGATE) {
;               x4.x += bflo(pv[u].x) * fsig(a.x * rs);
;               x4.y += bfhi(pv[u].x) * fsig(a.y * rs);
;               x4.z += bflo(pv[u].y) * fsig(a.z * rs);
;               x4.w += bfhi(pv[u].y) * fsig(a.w * rs);
;             } else {
;               const float sc = fabsf(scale);
;               x4.x += sc * a.x; x4.y += sc * a.y; x4.z += sc * a.z; x4.w += sc * a.w;
;             }
;             st_nt16(p.x + ro, x4);
;             if (xbout) {
;               uint2 o;
;               o.x = pack2(x4.x, x4.y);
;               o.y = pack2(x4.z, x4.w);
;               st_nt8(xbout + ro, o);
;             }
.LBB0_1964:
	ds_read_b128 v[76:79], v142 offset:13520
	v_readlane_b32 s21, v165, 13
	s_and_b64 vcc, exec, s[4:5]
	s_waitcnt lgkmcnt(0)
	v_mul_f32_e32 v76, s21, v76
	v_mul_f32_e32 v77, s21, v77
	v_mul_f32_e32 v76, 0xbfb8aa3b, v76
	v_mul_f32_e32 v77, 0xbfb8aa3b, v77
	v_mul_f32_e32 v78, s21, v78
	v_mul_f32_e32 v79, s21, v79
	v_exp_f32_e32 v80, v76
	v_exp_f32_e32 v81, v77
	v_mul_f32_e32 v78, 0xbfb8aa3b, v78
	v_mul_f32_e32 v79, 0xbfb8aa3b, v79
	v_exp_f32_e32 v78, v78
	v_exp_f32_e32 v79, v79
	v_add_f32_e32 v80, 1.0, v80
	v_add_f32_e32 v81, 1.0, v81
	v_rcp_f32_e32 v80, v80
	v_rcp_f32_e32 v81, v81
	v_add_f32_e32 v78, 1.0, v78
	v_add_f32_e32 v79, 1.0, v79
	v_rcp_f32_e32 v78, v78
	v_rcp_f32_e32 v79, v79
	v_lshlrev_b32_e32 v76, 16, v112
	v_and_b32_e32 v77, 0xffff0000, v112
	v_pk_fma_f32 v[72:73], v[80:81], v[76:77], v[72:73]
	v_lshlrev_b32_e32 v76, 16, v113
	v_and_b32_e32 v77, 0xffff0000, v113
	v_pk_fma_f32 v[74:75], v[78:79], v[76:77], v[74:75]
	global_store_dwordx4 v[110:111], v[72:75], off
	s_cbranch_vccnz .LBB0_1966
	v_cvt_pk_bf16_f32 v76, v72, v73
	v_cvt_pk_bf16_f32 v77, v74, v75
	v_lshl_add_u64 v[78:79], v[108:109], 1, s[8:9]
	flat_store_dwordx2 v[78:79], v[76:77]

; DEVI float fsig(float x) { return __builtin_amdgcn_rcpf(1.f + __expf(-x)); }
; DEVI float bflo(unsigned u) { return __uint_as_float(u << 16); }
; DEVI float bfhi(unsigned u) { return __uint_as_float(u & 0xffff0000u); }
; template <int EPI, int TS, bool VT>
; DEVI void gemm_epilogue(const Params& p, char* smem, f32x4 (&acc)[2][2][4][2], int m0, int n0, float scale, const float* ssin,
;                         float* ssout, u16* xbout, int wid, int lane, int wr, int wc, int fr, int fq) {
;     ...
;           if constexpr (EPI == E_RESID || EPI == E_PLEGATE) {
;             const float4 a = *(const float4*)(Tr + 4 * lane);
;             const size_t ro = (size_t)grow * 1024 + n0 + 4 * lane;
;             float4 x4 = xo[u];
;             if constexpr (EPI == E_PLEGATE) {
;               x4.x += bflo(pv[u].x) * fsig(a.x * rs);
;               x4.y += bfhi(pv[u].x) * fsig(a.y * rs);
;               x4.z += bflo(pv[u].y) * fsig(a.z * rs);
;               x4.w += bfhi(pv[u].y) * fsig(a.w * rs);
;             } else {
;               const float sc = fabsf(scale);
;               x4.x += sc * a.x; x4.y += sc * a.y; x4.z += sc * a.z; x4.w += sc * a.w;
;             }
;             st_nt16(p.x + ro, x4);
;             if (xbout) {
;               uint2 o;
;               o.x = pack2(x4.x, x4.y);
;               o.y = pack2(x4.z, x4.w);
;               st_nt8(xbout + ro, o);
;             }
.LBB0_1970:
	ds_read_b128 v[72:75], v142 offset:14560
	v_readlane_b32 s21, v165, 14
	s_and_b64 vcc, exec, s[4:5]
	s_waitcnt lgkmcnt(0)
	v_mul_f32_e32 v72, s21, v72
	v_mul_f32_e32 v73, s21, v73
	v_mul_f32_e32 v72, 0xbfb8aa3b, v72
	v_mul_f32_e32 v73, 0xbfb8aa3b, v73
	v_mul_f32_e32 v74, s21, v74
	v_mul_f32_e32 v75, s21, v75
	v_exp_f32_e32 v76, v72
	v_exp_f32_e32 v77, v73
	v_mul_f32_e32 v74, 0xbfb8aa3b, v74
	v_mul_f32_e32 v75, 0xbfb8aa3b, v75
	v_exp_f32_e32 v74, v74
	v_exp_f32_e32 v75, v75
	v_add_f32_e32 v76, 1.0, v76
	v_add_f32_e32 v77, 1.0, v77
	v_rcp_f32_e32 v76, v76
	v_rcp_f32_e32 v77, v77
	v_add_f32_e32 v74, 1.0, v74
	v_add_f32_e32 v75, 1.0, v75
	v_rcp_f32_e32 v74, v74
	v_rcp_f32_e32 v75, v75
	v_lshlrev_b32_e32 v72, 16, v106
	v_and_b32_e32 v73, 0xffff0000, v106
	v_pk_fma_f32 v[68:69], v[76:77], v[72:73], v[68:69]
	v_lshlrev_b32_e32 v72, 16, v107
	v_and_b32_e32 v73, 0xffff0000, v107
	v_pk_fma_f32 v[70:71], v[74:75], v[72:73], v[70:71]
	global_store_dwordx4 v[104:105], v[68:71], off
	s_cbranch_vccnz .LBB0_1972
	v_cvt_pk_bf16_f32 v72, v68, v69
	v_cvt_pk_bf16_f32 v73, v70, v71
	v_lshl_add_u64 v[74:75], v[102:103], 1, s[8:9]
	flat_store_dwordx2 v[74:75], v[72:73]

; DEVI float fsig(float x) { return __builtin_amdgcn_rcpf(1.f + __expf(-x)); }
; DEVI float bflo(unsigned u) { return __uint_as_float(u << 16); }
; DEVI float bfhi(unsigned u) { return __uint_as_float(u & 0xffff0000u); }
; template <int EPI, int TS, bool VT>
; DEVI void gemm_epilogue(const Params& p, char* smem, f32x4 (&acc)[2][2][4][2], int m0, int n0, float scale, const float* ssin,
;                         float* ssout, u16* xbout, int wid, int lane, int wr, int wc, int fr, int fq) {
;     ...
;           if constexpr (EPI == E_RESID || EPI == E_PLEGATE) {
;             const float4 a = *(const float4*)(Tr + 4 * lane);
;             const size_t ro = (size_t)grow * 1024 + n0 + 4 * lane;
;             float4 x4 = xo[u];
;             if constexpr (EPI == E_PLEGATE) {
;               x4.x += bflo(pv[u].x) * fsig(a.x * rs);
;               x4.y += bfhi(pv[u].x) * fsig(a.y * rs);
;               x4.z += bflo(pv[u].y) * fsig(a.z * rs);
;               x4.w += bfhi(pv[u].y) * fsig(a.w * rs);
;             } else {
;               const float sc = fabsf(scale);
;               x4.x += sc * a.x; x4.y += sc * a.y; x4.z += sc * a.z; x4.w += sc * a.w;
;             }
;             st_nt16(p.x + ro, x4);
;             if (xbout) {
;               uint2 o;
;               o.x = pack2(x4.x, x4.y);
;               o.y = pack2(x4.z, x4.w);
;               st_nt8(xbout + ro, o);
;             }
.LBB0_1976:
	ds_read_b128 v[68:71], v142 offset:15600
	v_readlane_b32 s21, v165, 15
	s_and_b64 vcc, exec, s[4:5]
	s_waitcnt lgkmcnt(0)
	v_mul_f32_e32 v68, s21, v68
	v_mul_f32_e32 v69, s21, v69
	v_mul_f32_e32 v68, 0xbfb8aa3b, v68
	v_mul_f32_e32 v69, 0xbfb8aa3b, v69
	v_mul_f32_e32 v70, s21, v70
	v_mul_f32_e32 v71, s21, v71
	v_exp_f32_e32 v72, v68
	v_exp_f32_e32 v73, v69
	v_mul_f32_e32 v70, 0xbfb8aa3b, v70
	v_mul_f32_e32 v71, 0xbfb8aa3b, v71
	v_exp_f32_e32 v70, v70
	v_exp_f32_e32 v71, v71
	v_add_f32_e32 v72, 1.0, v72
	v_add_f32_e32 v73, 1.0, v73
	v_rcp_f32_e32 v72, v72
	v_rcp_f32_e32 v73, v73
	v_add_f32_e32 v70, 1.0, v70
	v_add_f32_e32 v71, 1.0, v71
	v_rcp_f32_e32 v70, v70
	v_rcp_f32_e32 v71, v71
	v_lshlrev_b32_e32 v68, 16, v100
	v_and_b32_e32 v69, 0xffff0000, v100
	v_pk_fma_f32 v[64:65], v[72:73], v[68:69], v[64:65]
	v_lshlrev_b32_e32 v68, 16, v101
	v_and_b32_e32 v69, 0xffff0000, v101
	v_pk_fma_f32 v[66:67], v[70:71], v[68:69], v[66:67]
	global_store_dwordx4 v[98:99], v[64:67], off
	s_cbranch_vccnz .LBB0_1978
	v_cvt_pk_bf16_f32 v68, v64, v65
	v_cvt_pk_bf16_f32 v69, v66, v67
	v_lshl_add_u64 v[70:71], v[96:97], 1, s[8:9]
	flat_store_dwordx2 v[70:71], v[68:69]

; template <int EPI, int TS, bool VT>
; DEVI void gemm_epilogue(const Params& p, char* smem, f32x4 (&acc)[2][2][4][2], int m0, int n0, float scale, const float* ssin,
;                         float* ssout, u16* xbout, int wid, int lane, int wr, int wc, int fr, int fq) {
;     ...
;   for (int ai = 0; ai < 2; ++ai) {
;     {
;       float* tw = T + (wr * 64 + fq * 4) * TS + wc * 32 + fr;
; #pragma unroll
;       for (int m = 0; m < 4; ++m)
; #pragma unroll
;         for (int j = 0; j < 4; ++j)
; #pragma unroll
;           for (int v = 0; v < 4; ++v) tw[(m * 16 + j) * TS + (v >> 1) * 128 + (v & 1) * 16] = acc[ai][v >> 1][m][v & 1][j];
;     }
;     __syncthreads();
;     ...
;         rsv = rsqrtf(ssin[g0 + (lane & 15)] * (1.f / 1024.f) + EPS);
;       if constexpr (EPI == E_QROPE) rsv = rsqrtf(ssin[g0 + (lane & 15)] * (1.f / 384.f) + EPS);
;       if constexpr (EPI == E_KV) rsv = rsqrtf(ssin[g0 + (lane & 15)] * (1.f / 256.f) + EPS);
;       for (int i0 = 0; i0 < 16; i0 += 8) {
;         float4 xo[8];
;         uint2 pv[8];
;         if constexpr (EPI == E_RESID || EPI == E_PLEGATE) {
; #pragma unroll
;           for (int u = 0; u < 8; ++u) {
;             const size_t ro = (size_t)(g0 + i0 + u) * 1024 + n0 + 4 * lane;
;             const int gr = g0 + i0 + u;
;             const float* xs = p.x + ro;
;             if (scale < 0.f)
;               xs = (gr < MP ? p.x_prompt + ro : p.x_sample + (ro - (size_t)MP * 1024));
;             { const f32x4 t_ = __builtin_nontemporal_load((const f32x4*)xs); xo[u] = make_float4(t_[0], t_[1], t_[2], t_[3]); }
;             if constexpr (EPI == E_PLEGATE) {
;               const unsigned long long t2_ = __builtin_nontemporal_load((const unsigned long long*)((const u16*)(wsb + OFF_PP) + ro));
;               pv[u] = make_uint2((unsigned)t2_, (unsigned)(t2_ >> 32));
;             }
;           }
;         }
; #pragma unroll
;         for (int u = 0; u < 8; ++u) {
;           const int i = i0 + u;
;           const int grow = g0 + i;
;           const float* Tr = T + (r0 + i) * TS;
;           const float rs = __int_as_float(__builtin_amdgcn_readlane(__float_as_int(rsv), i));
;           if constexpr (EPI == E_RESID || EPI == E_PLEGATE) {
;             const float4 a = *(const float4*)(Tr + 4 * lane);
;             const size_t ro = (size_t)grow * 1024 + n0 + 4 * lane;
;             float4 x4 = xo[u];
.LBB0_1982:
	s_add_i32 s70, s20, 0x80
	s_waitcnt lgkmcnt(0)
	s_barrier
	ds_write2_b32 v144, v24, v28 offset1:16
	ds_write2_b32 v144, v56, v60 offset0:128 offset1:144
	ds_write2_b32 v145, v25, v29 offset0:4 offset1:20
	ds_write2_b32 v145, v57, v61 offset0:132 offset1:148
	ds_write2_b32 v146, v26, v30 offset0:8 offset1:24
	ds_write2_b32 v146, v58, v62 offset0:136 offset1:152
	ds_write2_b32 v147, v27, v31 offset0:12 offset1:28
	ds_write2_b32 v147, v59, v63 offset0:140 offset1:156
	ds_write2_b32 v148, v16, v20 offset0:64 offset1:80
	ds_write2_b32 v148, v48, v52 offset0:192 offset1:208
	ds_write2_b32 v152, v17, v21 offset0:68 offset1:84
	ds_write2_b32 v152, v49, v53 offset0:196 offset1:212
	ds_write2_b32 v153, v18, v22 offset0:72 offset1:88
	ds_write2_b32 v153, v50, v54 offset0:200 offset1:216
	ds_write2_b32 v154, v19, v23 offset0:76 offset1:92
	ds_write2_b32 v154, v51, v55 offset0:204 offset1:220
	ds_write2_b32 v155, v8, v12 offset0:128 offset1:144
	ds_write2_b32 v156, v40, v44 offset1:16
	ds_write2_b32 v156, v9, v13 offset0:132 offset1:148
	ds_write2_b32 v157, v41, v45 offset0:4 offset1:20
	ds_write2_b32 v157, v10, v14 offset0:136 offset1:152
	ds_write2_b32 v158, v42, v46 offset0:8 offset1:24
	ds_write2_b32 v158, v11, v15 offset0:140 offset1:156
	ds_write2_b32 v159, v43, v47 offset0:12 offset1:28
	ds_write2_b32 v160, v0, v4 offset0:192 offset1:208
	ds_write2_b32 v161, v32, v36 offset0:64 offset1:80
	ds_write2_b32 v161, v1, v5 offset0:196 offset1:212
	ds_write2_b32 v162, v33, v37 offset0:68 offset1:84
	ds_write2_b32 v162, v2, v6 offset0:200 offset1:216
	ds_write2_b32 v163, v34, v38 offset0:72 offset1:88
	ds_write2_b32 v163, v3, v7 offset0:204 offset1:220
	ds_write2_b32 v164, v35, v39 offset0:76 offset1:92
	v_or_b32_e32 v0, s70, v143
	v_ashrrev_i32_e32 v1, 31, v0
	v_lshl_add_u64 v[0:1], v[0:1], 2, s[2:3]
	s_waitcnt lgkmcnt(0)
	s_barrier
	flat_load_dword v80, v[0:1]
	s_ashr_i32 s71, s70, 31
	s_add_i32 s68, s20, 0x81
	s_lshl_b64 s[22:23], s[70:71], 10
	s_ashr_i32 s69, s68, 31
	s_add_i32 s66, s20, 0x82
	v_lshl_add_u64 v[74:75], s[22:23], 0, v[128:129]
	s_lshl_b64 s[22:23], s[68:69], 10
	s_ashr_i32 s67, s66, 31
	s_add_i32 s64, s20, 0x83
	v_lshl_add_u64 v[82:83], v[74:75], 2, s[38:39]
	v_lshl_add_u64 v[68:69], s[22:23], 0, v[128:129]
	s_lshl_b64 s[22:23], s[66:67], 10
	s_ashr_i32 s65, s64, 31
	global_load_dwordx4 v[28:31], v[82:83], off
	v_lshl_add_u64 v[62:63], s[22:23], 0, v[128:129]
	s_lshl_b64 s[22:23], s[64:65], 10
	v_lshl_add_u64 v[0:1], v[74:75], 1, s[18:19]
	v_lshl_add_u64 v[70:71], v[68:69], 2, s[38:39]
	v_lshl_add_u64 v[56:57], s[22:23], 0, v[128:129]
	s_add_i32 s62, s20, 0x84
	v_lshl_add_u64 v[2:3], v[68:69], 1, s[18:19]
	v_lshl_add_u64 v[64:65], v[62:63], 2, s[38:39]
	global_load_dwordx4 v[24:27], v[70:71], off
	global_load_dwordx4 v[20:23], v[64:65], off
	v_lshl_add_u64 v[4:5], v[62:63], 1, s[18:19]
	v_lshl_add_u64 v[6:7], v[56:57], 1, s[18:19]
	flat_load_dwordx2 v[84:85], v[0:1]
	flat_load_dwordx2 v[72:73], v[2:3]
	flat_load_dwordx2 v[66:67], v[4:5]
	flat_load_dwordx2 v[60:61], v[6:7]
	s_ashr_i32 s63, s62, 31
	s_add_i32 s34, s20, 0x85
	s_lshl_b64 s[22:23], s[62:63], 10
	s_ashr_i32 s35, s34, 31
	s_add_i32 s30, s20, 0x86
	v_lshl_add_u64 v[50:51], s[22:23], 0, v[128:129]
	s_lshl_b64 s[22:23], s[34:35], 10
	s_ashr_i32 s31, s30, 31
	v_lshl_add_u64 v[44:45], s[22:23], 0, v[128:129]
	s_lshl_b64 s[22:23], s[30:31], 10
	v_lshl_add_u64 v[38:39], s[22:23], 0, v[128:129]
	s_add_i32 s22, s20, 0x87
	s_ashr_i32 s23, s22, 31
	s_lshl_b64 s[72:73], s[22:23], 10
	v_lshl_add_u64 v[32:33], s[72:73], 0, v[128:129]
	v_lshl_add_u64 v[58:59], v[56:57], 2, s[38:39]
	v_lshl_add_u64 v[36:37], v[50:51], 1, s[18:19]
	v_lshl_add_u64 v[46:47], v[44:45], 2, s[38:39]
	v_lshl_add_u64 v[42:43], v[44:45], 1, s[18:19]
	v_lshl_add_u64 v[34:35], v[32:33], 2, s[38:39]
	v_lshl_add_u64 v[52:53], v[50:51], 2, s[38:39]
	global_load_dwordx4 v[16:19], v[58:59], off
	global_load_dwordx4 v[12:15], v[52:53], off
	v_lshl_add_u64 v[40:41], v[38:39], 2, s[38:39]
	global_load_dwordx4 v[8:11], v[46:47], off
	global_load_dwordx4 v[4:7], v[40:41], off
	v_lshl_add_u64 v[76:77], v[38:39], 1, s[18:19]
	global_load_dwordx4 v[0:3], v[34:35], off
	v_lshl_add_u64 v[78:79], v[32:33], 1, s[18:19]
	flat_load_dwordx2 v[54:55], v[36:37]
	flat_load_dwordx2 v[48:49], v[42:43]
	s_nop 0
	flat_load_dwordx2 v[42:43], v[76:77]
	flat_load_dwordx2 v[36:37], v[78:79]
	s_waitcnt vmcnt(0) lgkmcnt(0)
	v_fmamk_f32 v76, v80, 0x3a800000, v150
	v_mul_f32_e32 v77, 0x4b800000, v76
	v_cmp_gt_f32_e32 vcc, s29, v76
	ds_read_b128 v[78:81], v142
	s_nop 0
	v_cndmask_b32_e32 v76, v76, v77, vcc
	v_rsq_f32_e32 v76, v76
	s_nop 0
	v_mul_f32_e32 v77, 0x45800000, v76
	v_cndmask_b32_e32 v76, v76, v77, vcc
	s_and_b64 vcc, exec, s[4:5]
	v_readlane_b32 s21, v76, 0
	s_waitcnt lgkmcnt(0)
	s_nop 0
	v_mul_f32_e32 v77, s21, v78
	v_mul_f32_e32 v77, 0xbfb8aa3b, v77
	v_exp_f32_e32 v77, v77
	v_mul_f32_e32 v78, s21, v79
	v_mul_f32_e32 v78, 0xbfb8aa3b, v78
	v_exp_f32_e32 v78, v78
	v_add_f32_e32 v77, 1.0, v77
	v_rcp_f32_e32 v77, v77
	v_lshlrev_b32_e32 v79, 16, v84
	v_add_f32_e32 v78, 1.0, v78
	v_rcp_f32_e32 v78, v78
	v_fma_f32 v28, v77, v79, v28
	v_mul_f32_e32 v79, s21, v80
	v_mul_f32_e32 v79, 0xbfb8aa3b, v79
	v_mul_f32_e32 v80, s21, v81
	v_exp_f32_e32 v79, v79
	v_mul_f32_e32 v80, 0xbfb8aa3b, v80
	v_exp_f32_e32 v80, v80
	v_and_b32_e32 v77, 0xffff0000, v84
	v_fma_f32 v29, v78, v77, v29
	v_add_f32_e32 v77, 1.0, v79
	v_rcp_f32_e32 v77, v77
	v_add_f32_e32 v78, 1.0, v80
	v_rcp_f32_e32 v78, v78
	v_lshlrev_b32_e32 v79, 16, v85
	v_fma_f32 v30, v77, v79, v30
	v_and_b32_e32 v77, 0xffff0000, v85
	v_fmac_f32_e32 v31, v78, v77
	global_store_dwordx4 v[82:83], v[28:31], off
	s_cbranch_vccnz .LBB0_1984
	v_cvt_pk_bf16_f32 v78, v28, v29
	v_cvt_pk_bf16_f32 v79, v30, v31
	v_lshl_add_u64 v[74:75], v[74:75], 1, s[8:9]
	flat_store_dwordx2 v[74:75], v[78:79]

; DEVI float fsig(float x) { return __builtin_amdgcn_rcpf(1.f + __expf(-x)); }
; DEVI float bflo(unsigned u) { return __uint_as_float(u << 16); }
; DEVI float bfhi(unsigned u) { return __uint_as_float(u & 0xffff0000u); }
; template <int EPI, int TS, bool VT>
; DEVI void gemm_epilogue(const Params& p, char* smem, f32x4 (&acc)[2][2][4][2], int m0, int n0, float scale, const float* ssin,
;                         float* ssout, u16* xbout, int wid, int lane, int wr, int wc, int fr, int fq) {
;     ...
;           if constexpr (EPI == E_RESID || EPI == E_PLEGATE) {
;             const float4 a = *(const float4*)(Tr + 4 * lane);
;             const size_t ro = (size_t)grow * 1024 + n0 + 4 * lane;
;             float4 x4 = xo[u];
;             if constexpr (EPI == E_PLEGATE) {
;               x4.x += bflo(pv[u].x) * fsig(a.x * rs);
;               x4.y += bfhi(pv[u].x) * fsig(a.y * rs);
;               x4.z += bflo(pv[u].y) * fsig(a.z * rs);
;               x4.w += bfhi(pv[u].y) * fsig(a.w * rs);
;             } else {
;               const float sc = fabsf(scale);
;               x4.x += sc * a.x; x4.y += sc * a.y; x4.z += sc * a.z; x4.w += sc * a.w;
;             }
;             st_nt16(p.x + ro, x4);
;             if (xbout) {
;               uint2 o;
;               o.x = pack2(x4.x, x4.y);
;               o.y = pack2(x4.z, x4.w);
;               st_nt8(xbout + ro, o);
;             }
.LBB0_1988:
	ds_read_b128 v[28:31], v142 offset:1040
	v_readlane_b32 s21, v76, 1
	s_and_b64 vcc, exec, s[4:5]
	s_waitcnt lgkmcnt(0)
	v_mul_f32_e32 v28, s21, v28
	v_mul_f32_e32 v29, s21, v29
	v_mul_f32_e32 v28, 0xbfb8aa3b, v28
	v_mul_f32_e32 v29, 0xbfb8aa3b, v29
	v_mul_f32_e32 v30, s21, v30
	v_mul_f32_e32 v31, s21, v31
	v_exp_f32_e32 v74, v28
	v_exp_f32_e32 v75, v29
	v_mul_f32_e32 v30, 0xbfb8aa3b, v30
	v_mul_f32_e32 v31, 0xbfb8aa3b, v31
	v_exp_f32_e32 v30, v30
	v_exp_f32_e32 v31, v31
	v_lshlrev_b32_e32 v28, 16, v72
	v_and_b32_e32 v29, 0xffff0000, v72
	v_add_f32_e32 v72, 1.0, v74
	v_add_f32_e32 v75, 1.0, v75
	v_rcp_f32_e32 v74, v72
	v_rcp_f32_e32 v75, v75
	v_add_f32_e32 v30, 1.0, v30
	v_add_f32_e32 v31, 1.0, v31
	v_rcp_f32_e32 v30, v30
	v_rcp_f32_e32 v31, v31
	v_pk_fma_f32 v[24:25], v[74:75], v[28:29], v[24:25]
	v_lshlrev_b32_e32 v28, 16, v73
	v_and_b32_e32 v29, 0xffff0000, v73
	v_pk_fma_f32 v[26:27], v[30:31], v[28:29], v[26:27]
	global_store_dwordx4 v[70:71], v[24:27], off
	s_cbranch_vccnz .LBB0_1990
	v_cvt_pk_bf16_f32 v28, v24, v25
	v_cvt_pk_bf16_f32 v29, v26, v27
	v_lshl_add_u64 v[30:31], v[68:69], 1, s[8:9]
	flat_store_dwordx2 v[30:31], v[28:29]

; DEVI float fsig(float x) { return __builtin_amdgcn_rcpf(1.f + __expf(-x)); }
; DEVI float bflo(unsigned u) { return __uint_as_float(u << 16); }
; DEVI float bfhi(unsigned u) { return __uint_as_float(u & 0xffff0000u); }
; template <int EPI, int TS, bool VT>
; DEVI void gemm_epilogue(const Params& p, char* smem, f32x4 (&acc)[2][2][4][2], int m0, int n0, float scale, const float* ssin,
;                         float* ssout, u16* xbout, int wid, int lane, int wr, int wc, int fr, int fq) {
;     ...
;           if constexpr (EPI == E_RESID || EPI == E_PLEGATE) {
;             const float4 a = *(const float4*)(Tr + 4 * lane);
;             const size_t ro = (size_t)grow * 1024 + n0 + 4 * lane;
;             float4 x4 = xo[u];
;             if constexpr (EPI == E_PLEGATE) {
;               x4.x += bflo(pv[u].x) * fsig(a.x * rs);
;               x4.y += bfhi(pv[u].x) * fsig(a.y * rs);
;               x4.z += bflo(pv[u].y) * fsig(a.z * rs);
;               x4.w += bfhi(pv[u].y) * fsig(a.w * rs);
;             } else {
;               const float sc = fabsf(scale);
;               x4.x += sc * a.x; x4.y += sc * a.y; x4.z += sc * a.z; x4.w += sc * a.w;
;             }
;             st_nt16(p.x + ro, x4);
;             if (xbout) {
;               uint2 o;
;               o.x = pack2(x4.x, x4.y);
;               o.y = pack2(x4.z, x4.w);
;               st_nt8(xbout + ro, o);
;             }
.LBB0_1994:
	ds_read_b128 v[24:27], v142 offset:2080
	v_readlane_b32 s21, v76, 2
	s_and_b64 vcc, exec, s[4:5]
	s_waitcnt lgkmcnt(0)
	v_mul_f32_e32 v24, s21, v24
	v_mul_f32_e32 v25, s21, v25
	v_mul_f32_e32 v24, 0xbfb8aa3b, v24
	v_mul_f32_e32 v25, 0xbfb8aa3b, v25
	v_mul_f32_e32 v26, s21, v26
	v_mul_f32_e32 v27, s21, v27
	v_exp_f32_e32 v28, v24
	v_exp_f32_e32 v29, v25
	v_mul_f32_e32 v26, 0xbfb8aa3b, v26
	v_mul_f32_e32 v27, 0xbfb8aa3b, v27
	v_exp_f32_e32 v26, v26
	v_exp_f32_e32 v27, v27
	v_add_f32_e32 v28, 1.0, v28
	v_add_f32_e32 v29, 1.0, v29
	v_rcp_f32_e32 v28, v28
	v_rcp_f32_e32 v29, v29
	v_add_f32_e32 v26, 1.0, v26
	v_add_f32_e32 v27, 1.0, v27
	v_rcp_f32_e32 v26, v26
	v_rcp_f32_e32 v27, v27
	v_lshlrev_b32_e32 v24, 16, v66
	v_and_b32_e32 v25, 0xffff0000, v66
	v_pk_fma_f32 v[20:21], v[28:29], v[24:25], v[20:21]
	v_lshlrev_b32_e32 v24, 16, v67
	v_and_b32_e32 v25, 0xffff0000, v67
	v_pk_fma_f32 v[22:23], v[26:27], v[24:25], v[22:23]
	global_store_dwordx4 v[64:65], v[20:23], off
	s_cbranch_vccnz .LBB0_1996
	v_cvt_pk_bf16_f32 v24, v20, v21
	v_cvt_pk_bf16_f32 v25, v22, v23
	v_lshl_add_u64 v[26:27], v[62:63], 1, s[8:9]
	flat_store_dwordx2 v[26:27], v[24:25]

; DEVI float fsig(float x) { return __builtin_amdgcn_rcpf(1.f + __expf(-x)); }
; DEVI float bflo(unsigned u) { return __uint_as_float(u << 16); }
; DEVI float bfhi(unsigned u) { return __uint_as_float(u & 0xffff0000u); }
; template <int EPI, int TS, bool VT>
; DEVI void gemm_epilogue(const Params& p, char* smem, f32x4 (&acc)[2][2][4][2], int m0, int n0, float scale, const float* ssin,
;                         float* ssout, u16* xbout, int wid, int lane, int wr, int wc, int fr, int fq) {
;     ...
;           if constexpr (EPI == E_RESID || EPI == E_PLEGATE) {
;             const float4 a = *(const float4*)(Tr + 4 * lane);
;             const size_t ro = (size_t)grow * 1024 + n0 + 4 * lane;
;             float4 x4 = xo[u];
;             if constexpr (EPI == E_PLEGATE) {
;               x4.x += bflo(pv[u].x) * fsig(a.x * rs);
;               x4.y += bfhi(pv[u].x) * fsig(a.y * rs);
;               x4.z += bflo(pv[u].y) * fsig(a.z * rs);
;               x4.w += bfhi(pv[u].y) * fsig(a.w * rs);
;             } else {
;               const float sc = fabsf(scale);
;               x4.x += sc * a.x; x4.y += sc * a.y; x4.z += sc * a.z; x4.w += sc * a.w;
;             }
;             st_nt16(p.x + ro, x4);
;             if (xbout) {
;               uint2 o;
;               o.x = pack2(x4.x, x4.y);
;               o.y = pack2(x4.z, x4.w);
;               st_nt8(xbout + ro, o);
;             }
.LBB0_2000:
	ds_read_b128 v[20:23], v142 offset:3120
	v_readlane_b32 s21, v76, 3
	s_and_b64 vcc, exec, s[4:5]
	s_waitcnt lgkmcnt(0)
	v_mul_f32_e32 v20, s21, v20
	v_mul_f32_e32 v21, s21, v21
	v_mul_f32_e32 v20, 0xbfb8aa3b, v20
	v_mul_f32_e32 v21, 0xbfb8aa3b, v21
	v_mul_f32_e32 v22, s21, v22
	v_mul_f32_e32 v23, s21, v23
	v_exp_f32_e32 v24, v20
	v_exp_f32_e32 v25, v21
	v_mul_f32_e32 v22, 0xbfb8aa3b, v22
	v_mul_f32_e32 v23, 0xbfb8aa3b, v23
	v_exp_f32_e32 v22, v22
	v_exp_f32_e32 v23, v23
	v_add_f32_e32 v24, 1.0, v24
	v_add_f32_e32 v25, 1.0, v25
	v_rcp_f32_e32 v24, v24
	v_rcp_f32_e32 v25, v25
	v_add_f32_e32 v22, 1.0, v22
	v_add_f32_e32 v23, 1.0, v23
	v_rcp_f32_e32 v22, v22
	v_rcp_f32_e32 v23, v23
	v_lshlrev_b32_e32 v20, 16, v60
	v_and_b32_e32 v21, 0xffff0000, v60
	v_pk_fma_f32 v[16:17], v[24:25], v[20:21], v[16:17]
	v_lshlrev_b32_e32 v20, 16, v61
	v_and_b32_e32 v21, 0xffff0000, v61
	v_pk_fma_f32 v[18:19], v[22:23], v[20:21], v[18:19]
	global_store_dwordx4 v[58:59], v[16:19], off
	s_cbranch_vccnz .LBB0_2002
	v_cvt_pk_bf16_f32 v20, v16, v17
	v_cvt_pk_bf16_f32 v21, v18, v19
	v_lshl_add_u64 v[22:23], v[56:57], 1, s[8:9]
	flat_store_dwordx2 v[22:23], v[20:21]

; DEVI float fsig(float x) { return __builtin_amdgcn_rcpf(1.f + __expf(-x)); }
; DEVI float bflo(unsigned u) { return __uint_as_float(u << 16); }
; DEVI float bfhi(unsigned u) { return __uint_as_float(u & 0xffff0000u); }
; template <int EPI, int TS, bool VT>
; DEVI void gemm_epilogue(const Params& p, char* smem, f32x4 (&acc)[2][2][4][2], int m0, int n0, float scale, const float* ssin,
;                         float* ssout, u16* xbout, int wid, int lane, int wr, int wc, int fr, int fq) {
;     ...
;           if constexpr (EPI == E_RESID || EPI == E_PLEGATE) {
;             const float4 a = *(const float4*)(Tr + 4 * lane);
;             const size_t ro = (size_t)grow * 1024 + n0 + 4 * lane;
;             float4 x4 = xo[u];
;             if constexpr (EPI == E_PLEGATE) {
;               x4.x += bflo(pv[u].x) * fsig(a.x * rs);
;               x4.y += bfhi(pv[u].x) * fsig(a.y * rs);
;               x4.z += bflo(pv[u].y) * fsig(a.z * rs);
;               x4.w += bfhi(pv[u].y) * fsig(a.w * rs);
;             } else {
;               const float sc = fabsf(scale);
;               x4.x += sc * a.x; x4.y += sc * a.y; x4.z += sc * a.z; x4.w += sc * a.w;
;             }
;             st_nt16(p.x + ro, x4);
;             if (xbout) {
;               uint2 o;
;               o.x = pack2(x4.x, x4.y);
;               o.y = pack2(x4.z, x4.w);
;               st_nt8(xbout + ro, o);
;             }
.LBB0_2006:
	ds_read_b128 v[16:19], v142 offset:4160
	v_readlane_b32 s21, v76, 4
	s_and_b64 vcc, exec, s[4:5]
	s_waitcnt lgkmcnt(0)
	v_mul_f32_e32 v16, s21, v16
	v_mul_f32_e32 v17, s21, v17
	v_mul_f32_e32 v16, 0xbfb8aa3b, v16
	v_mul_f32_e32 v17, 0xbfb8aa3b, v17
	v_mul_f32_e32 v18, s21, v18
	v_mul_f32_e32 v19, s21, v19
	v_exp_f32_e32 v20, v16
	v_exp_f32_e32 v21, v17
	v_mul_f32_e32 v18, 0xbfb8aa3b, v18
	v_mul_f32_e32 v19, 0xbfb8aa3b, v19
	v_exp_f32_e32 v18, v18
	v_exp_f32_e32 v19, v19
	v_add_f32_e32 v20, 1.0, v20
	v_add_f32_e32 v21, 1.0, v21
	v_rcp_f32_e32 v20, v20
	v_rcp_f32_e32 v21, v21
	v_add_f32_e32 v18, 1.0, v18
	v_add_f32_e32 v19, 1.0, v19
	v_rcp_f32_e32 v18, v18
	v_rcp_f32_e32 v19, v19
	v_lshlrev_b32_e32 v16, 16, v54
	v_and_b32_e32 v17, 0xffff0000, v54
	v_pk_fma_f32 v[12:13], v[20:21], v[16:17], v[12:13]
	v_lshlrev_b32_e32 v16, 16, v55
	v_and_b32_e32 v17, 0xffff0000, v55
	v_pk_fma_f32 v[14:15], v[18:19], v[16:17], v[14:15]
	global_store_dwordx4 v[52:53], v[12:15], off
	s_cbranch_vccnz .LBB0_2008
	v_cvt_pk_bf16_f32 v16, v12, v13
	v_cvt_pk_bf16_f32 v17, v14, v15
	v_lshl_add_u64 v[18:19], v[50:51], 1, s[8:9]
	flat_store_dwordx2 v[18:19], v[16:17]

; DEVI float fsig(float x) { return __builtin_amdgcn_rcpf(1.f + __expf(-x)); }
; DEVI float bflo(unsigned u) { return __uint_as_float(u << 16); }
; DEVI float bfhi(unsigned u) { return __uint_as_float(u & 0xffff0000u); }
; template <int EPI, int TS, bool VT>
; DEVI void gemm_epilogue(const Params& p, char* smem, f32x4 (&acc)[2][2][4][2], int m0, int n0, float scale, const float* ssin,
;                         float* ssout, u16* xbout, int wid, int lane, int wr, int wc, int fr, int fq) {
;     ...
;           if constexpr (EPI == E_RESID || EPI == E_PLEGATE) {
;             const float4 a = *(const float4*)(Tr + 4 * lane);
;             const size_t ro = (size_t)grow * 1024 + n0 + 4 * lane;
;             float4 x4 = xo[u];
;             if constexpr (EPI == E_PLEGATE) {
;               x4.x += bflo(pv[u].x) * fsig(a.x * rs);
;               x4.y += bfhi(pv[u].x) * fsig(a.y * rs);
;               x4.z += bflo(pv[u].y) * fsig(a.z * rs);
;               x4.w += bfhi(pv[u].y) * fsig(a.w * rs);
;             } else {
;               const float sc = fabsf(scale);
;               x4.x += sc * a.x; x4.y += sc * a.y; x4.z += sc * a.z; x4.w += sc * a.w;
;             }
;             st_nt16(p.x + ro, x4);
;             if (xbout) {
;               uint2 o;
;               o.x = pack2(x4.x, x4.y);
;               o.y = pack2(x4.z, x4.w);
;               st_nt8(xbout + ro, o);
;             }
.LBB0_2012:
	ds_read_b128 v[12:15], v142 offset:5200
	v_readlane_b32 s21, v76, 5
	s_and_b64 vcc, exec, s[4:5]
	s_waitcnt lgkmcnt(0)
	v_mul_f32_e32 v12, s21, v12
	v_mul_f32_e32 v13, s21, v13
	v_mul_f32_e32 v12, 0xbfb8aa3b, v12
	v_mul_f32_e32 v13, 0xbfb8aa3b, v13
	v_mul_f32_e32 v14, s21, v14
	v_mul_f32_e32 v15, s21, v15
	v_exp_f32_e32 v16, v12
	v_exp_f32_e32 v17, v13
	v_mul_f32_e32 v14, 0xbfb8aa3b, v14
	v_mul_f32_e32 v15, 0xbfb8aa3b, v15
	v_exp_f32_e32 v14, v14
	v_exp_f32_e32 v15, v15
	v_add_f32_e32 v16, 1.0, v16
	v_add_f32_e32 v17, 1.0, v17
	v_rcp_f32_e32 v16, v16
	v_rcp_f32_e32 v17, v17
	v_add_f32_e32 v14, 1.0, v14
	v_add_f32_e32 v15, 1.0, v15
	v_rcp_f32_e32 v14, v14
	v_rcp_f32_e32 v15, v15
	v_lshlrev_b32_e32 v12, 16, v48
	v_and_b32_e32 v13, 0xffff0000, v48
	v_pk_fma_f32 v[8:9], v[16:17], v[12:13], v[8:9]
	v_lshlrev_b32_e32 v12, 16, v49
	v_and_b32_e32 v13, 0xffff0000, v49
	v_pk_fma_f32 v[10:11], v[14:15], v[12:13], v[10:11]
	global_store_dwordx4 v[46:47], v[8:11], off
	s_cbranch_vccnz .LBB0_2014
	v_cvt_pk_bf16_f32 v12, v8, v9
	v_cvt_pk_bf16_f32 v13, v10, v11
	v_lshl_add_u64 v[14:15], v[44:45], 1, s[8:9]
	flat_store_dwordx2 v[14:15], v[12:13]

; DEVI float fsig(float x) { return __builtin_amdgcn_rcpf(1.f + __expf(-x)); }
; DEVI float bflo(unsigned u) { return __uint_as_float(u << 16); }
; DEVI float bfhi(unsigned u) { return __uint_as_float(u & 0xffff0000u); }
; template <int EPI, int TS, bool VT>
; DEVI void gemm_epilogue(const Params& p, char* smem, f32x4 (&acc)[2][2][4][2], int m0, int n0, float scale, const float* ssin,
;                         float* ssout, u16* xbout, int wid, int lane, int wr, int wc, int fr, int fq) {
;     ...
;           if constexpr (EPI == E_RESID || EPI == E_PLEGATE) {
;             const float4 a = *(const float4*)(Tr + 4 * lane);
;             const size_t ro = (size_t)grow * 1024 + n0 + 4 * lane;
;             float4 x4 = xo[u];
;             if constexpr (EPI == E_PLEGATE) {
;               x4.x += bflo(pv[u].x) * fsig(a.x * rs);
;               x4.y += bfhi(pv[u].x) * fsig(a.y * rs);
;               x4.z += bflo(pv[u].y) * fsig(a.z * rs);
;               x4.w += bfhi(pv[u].y) * fsig(a.w * rs);
;             } else {
;               const float sc = fabsf(scale);
;               x4.x += sc * a.x; x4.y += sc * a.y; x4.z += sc * a.z; x4.w += sc * a.w;
;             }
;             st_nt16(p.x + ro, x4);
;             if (xbout) {
;               uint2 o;
;               o.x = pack2(x4.x, x4.y);
;               o.y = pack2(x4.z, x4.w);
;               st_nt8(xbout + ro, o);
;             }
.LBB0_2018:
	ds_read_b128 v[8:11], v142 offset:6240
	v_readlane_b32 s21, v76, 6
	s_and_b64 vcc, exec, s[4:5]
	s_waitcnt lgkmcnt(0)
	v_mul_f32_e32 v8, s21, v8
	v_mul_f32_e32 v9, s21, v9
	v_mul_f32_e32 v8, 0xbfb8aa3b, v8
	v_mul_f32_e32 v9, 0xbfb8aa3b, v9
	v_mul_f32_e32 v10, s21, v10
	v_mul_f32_e32 v11, s21, v11
	v_exp_f32_e32 v12, v8
	v_exp_f32_e32 v13, v9
	v_mul_f32_e32 v10, 0xbfb8aa3b, v10
	v_mul_f32_e32 v11, 0xbfb8aa3b, v11
	v_exp_f32_e32 v10, v10
	v_exp_f32_e32 v11, v11
	v_add_f32_e32 v12, 1.0, v12
	v_add_f32_e32 v13, 1.0, v13
	v_rcp_f32_e32 v12, v12
	v_rcp_f32_e32 v13, v13
	v_add_f32_e32 v10, 1.0, v10
	v_add_f32_e32 v11, 1.0, v11
	v_rcp_f32_e32 v10, v10
	v_rcp_f32_e32 v11, v11
	v_lshlrev_b32_e32 v8, 16, v42
	v_and_b32_e32 v9, 0xffff0000, v42
	v_pk_fma_f32 v[4:5], v[12:13], v[8:9], v[4:5]
	v_lshlrev_b32_e32 v8, 16, v43
	v_and_b32_e32 v9, 0xffff0000, v43
	v_pk_fma_f32 v[6:7], v[10:11], v[8:9], v[6:7]
	global_store_dwordx4 v[40:41], v[4:7], off
	s_cbranch_vccnz .LBB0_2020
	v_cvt_pk_bf16_f32 v8, v4, v5
	v_cvt_pk_bf16_f32 v9, v6, v7
	v_lshl_add_u64 v[10:11], v[38:39], 1, s[8:9]
	flat_store_dwordx2 v[10:11], v[8:9]

; DEVI float fsig(float x) { return __builtin_amdgcn_rcpf(1.f + __expf(-x)); }
; DEVI float bflo(unsigned u) { return __uint_as_float(u << 16); }
; DEVI float bfhi(unsigned u) { return __uint_as_float(u & 0xffff0000u); }
; template <int EPI, int TS, bool VT>
; DEVI void gemm_epilogue(const Params& p, char* smem, f32x4 (&acc)[2][2][4][2], int m0, int n0, float scale, const float* ssin,
;                         float* ssout, u16* xbout, int wid, int lane, int wr, int wc, int fr, int fq) {
;     ...
;           if constexpr (EPI == E_RESID || EPI == E_PLEGATE) {
;             const float4 a = *(const float4*)(Tr + 4 * lane);
;             const size_t ro = (size_t)grow * 1024 + n0 + 4 * lane;
;             float4 x4 = xo[u];
;             if constexpr (EPI == E_PLEGATE) {
;               x4.x += bflo(pv[u].x) * fsig(a.x * rs);
;               x4.y += bfhi(pv[u].x) * fsig(a.y * rs);
;               x4.z += bflo(pv[u].y) * fsig(a.z * rs);
;               x4.w += bfhi(pv[u].y) * fsig(a.w * rs);
;             } else {
;               const float sc = fabsf(scale);
;               x4.x += sc * a.x; x4.y += sc * a.y; x4.z += sc * a.z; x4.w += sc * a.w;
;             }
;             st_nt16(p.x + ro, x4);
;             if (xbout) {
;               uint2 o;
;               o.x = pack2(x4.x, x4.y);
;               o.y = pack2(x4.z, x4.w);
;               st_nt8(xbout + ro, o);
;             }
.LBB0_2024:
	ds_read_b128 v[4:7], v142 offset:7280
	v_readlane_b32 s21, v76, 7
	s_and_b64 vcc, exec, s[4:5]
	s_waitcnt lgkmcnt(0)
	v_mul_f32_e32 v4, s21, v4
	v_mul_f32_e32 v5, s21, v5
	v_mul_f32_e32 v4, 0xbfb8aa3b, v4
	v_mul_f32_e32 v5, 0xbfb8aa3b, v5
	v_mul_f32_e32 v6, s21, v6
	v_mul_f32_e32 v7, s21, v7
	v_exp_f32_e32 v8, v4
	v_exp_f32_e32 v9, v5
	v_mul_f32_e32 v6, 0xbfb8aa3b, v6
	v_mul_f32_e32 v7, 0xbfb8aa3b, v7
	v_exp_f32_e32 v6, v6
	v_exp_f32_e32 v7, v7
	v_add_f32_e32 v8, 1.0, v8
	v_add_f32_e32 v9, 1.0, v9
	v_rcp_f32_e32 v8, v8
	v_rcp_f32_e32 v9, v9
	v_add_f32_e32 v6, 1.0, v6
	v_add_f32_e32 v7, 1.0, v7
	v_rcp_f32_e32 v6, v6
	v_rcp_f32_e32 v7, v7
	v_lshlrev_b32_e32 v4, 16, v36
	v_and_b32_e32 v5, 0xffff0000, v36
	v_pk_fma_f32 v[0:1], v[8:9], v[4:5], v[0:1]
	v_lshlrev_b32_e32 v4, 16, v37
	v_and_b32_e32 v5, 0xffff0000, v37
	v_pk_fma_f32 v[2:3], v[6:7], v[4:5], v[2:3]
	global_store_dwordx4 v[34:35], v[0:3], off
	s_cbranch_vccnz .LBB0_2026
	v_cvt_pk_bf16_f32 v4, v0, v1
	v_cvt_pk_bf16_f32 v5, v2, v3
	v_lshl_add_u64 v[6:7], v[32:33], 1, s[8:9]
	flat_store_dwordx2 v[6:7], v[4:5]

; DEVI float fsig(float x) { return __builtin_amdgcn_rcpf(1.f + __expf(-x)); }
; DEVI float bflo(unsigned u) { return __uint_as_float(u << 16); }
; template <int EPI, int TS, bool VT>
; DEVI void gemm_epilogue(const Params& p, char* smem, f32x4 (&acc)[2][2][4][2], int m0, int n0, float scale, const float* ssin,
;                         float* ssout, u16* xbout, int wid, int lane, int wr, int wc, int fr, int fq) {
;     ...
; #pragma unroll
;           for (int u = 0; u < 8; ++u) {
;             const size_t ro = (size_t)(g0 + i0 + u) * 1024 + n0 + 4 * lane;
;             const int gr = g0 + i0 + u;
;             const float* xs = p.x + ro;
;             if (scale < 0.f)
;               xs = (gr < MP ? p.x_prompt + ro : p.x_sample + (ro - (size_t)MP * 1024));
;             { const f32x4 t_ = __builtin_nontemporal_load((const f32x4*)xs); xo[u] = make_float4(t_[0], t_[1], t_[2], t_[3]); }
;             if constexpr (EPI == E_PLEGATE) {
;               const unsigned long long t2_ = __builtin_nontemporal_load((const unsigned long long*)((const u16*)(wsb + OFF_PP) + ro));
;               pv[u] = make_uint2((unsigned)t2_, (unsigned)(t2_ >> 32));
;             }
;           }
;         }
; #pragma unroll
;         for (int u = 0; u < 8; ++u) {
;           const int i = i0 + u;
;           const int grow = g0 + i;
;           const float* Tr = T + (r0 + i) * TS;
;           const float rs = __int_as_float(__builtin_amdgcn_readlane(__float_as_int(rsv), i));
;           if constexpr (EPI == E_RESID || EPI == E_PLEGATE) {
;             const float4 a = *(const float4*)(Tr + 4 * lane);
;             const size_t ro = (size_t)grow * 1024 + n0 + 4 * lane;
;             float4 x4 = xo[u];
;             if constexpr (EPI == E_PLEGATE) {
;               x4.x += bflo(pv[u].x) * fsig(a.x * rs);
;               x4.y += bfhi(pv[u].x) * fsig(a.y * rs);
;               x4.z += bflo(pv[u].y) * fsig(a.z * rs);
;               x4.w += bfhi(pv[u].y) * fsig(a.w * rs);
;             } else {
;               const float sc = fabsf(scale);
;               x4.x += sc * a.x; x4.y += sc * a.y; x4.z += sc * a.z; x4.w += sc * a.w;
;             }
;             st_nt16(p.x + ro, x4);
;             if (xbout) {
;               uint2 o;
;               o.x = pack2(x4.x, x4.y);
;               o.y = pack2(x4.z, x4.w);
;               st_nt8(xbout + ro, o);
.LBB0_2030:
	s_add_i32 s68, s20, 0x88
	s_ashr_i32 s69, s68, 31
	s_add_i32 s66, s20, 0x89
	s_lshl_b64 s[22:23], s[68:69], 10
	s_ashr_i32 s67, s66, 31
	s_add_i32 s64, s20, 0x8a
	v_lshl_add_u64 v[74:75], s[22:23], 0, v[128:129]
	s_lshl_b64 s[22:23], s[66:67], 10
	s_ashr_i32 s65, s64, 31
	s_add_i32 s62, s20, 0x8b
	v_lshl_add_u64 v[68:69], s[22:23], 0, v[128:129]
	s_lshl_b64 s[22:23], s[64:65], 10
	s_ashr_i32 s63, s62, 31
	s_add_i32 s34, s20, 0x8c
	v_lshl_add_u64 v[62:63], s[22:23], 0, v[128:129]
	s_lshl_b64 s[22:23], s[62:63], 10
	s_ashr_i32 s35, s34, 31
	s_add_i32 s30, s20, 0x8d
	v_lshl_add_u64 v[56:57], s[22:23], 0, v[128:129]
	s_lshl_b64 s[22:23], s[34:35], 10
	s_ashr_i32 s31, s30, 31
	v_lshl_add_u64 v[50:51], s[22:23], 0, v[128:129]
	s_lshl_b64 s[22:23], s[30:31], 10
	v_lshl_add_u64 v[44:45], s[22:23], 0, v[128:129]
	s_add_i32 s22, s20, 0x8e
	v_lshl_add_u64 v[82:83], v[74:75], 2, s[38:39]
	s_ashr_i32 s23, s22, 31
	s_addk_i32 s20, 0x8f
	global_load_dwordx4 v[28:31], v[82:83], off
	s_lshl_b64 s[70:71], s[22:23], 10
	s_ashr_i32 s21, s20, 31
	v_lshl_add_u64 v[0:1], v[74:75], 1, s[18:19]
	v_lshl_add_u64 v[70:71], v[68:69], 2, s[38:39]
	v_lshl_add_u64 v[38:39], s[70:71], 0, v[128:129]
	s_lshl_b64 s[70:71], s[20:21], 10
	v_lshl_add_u64 v[2:3], v[68:69], 1, s[18:19]
	v_lshl_add_u64 v[64:65], v[62:63], 2, s[38:39]
	global_load_dwordx4 v[24:27], v[70:71], off
	global_load_dwordx4 v[20:23], v[64:65], off
	v_lshl_add_u64 v[4:5], v[62:63], 1, s[18:19]
	v_lshl_add_u64 v[6:7], v[56:57], 1, s[18:19]
	flat_load_dwordx2 v[84:85], v[0:1]
	flat_load_dwordx2 v[72:73], v[2:3]
	flat_load_dwordx2 v[66:67], v[4:5]
	flat_load_dwordx2 v[60:61], v[6:7]
	v_lshl_add_u64 v[32:33], s[70:71], 0, v[128:129]
	v_lshl_add_u64 v[58:59], v[56:57], 2, s[38:39]
	v_lshl_add_u64 v[36:37], v[50:51], 1, s[18:19]
	v_lshl_add_u64 v[46:47], v[44:45], 2, s[38:39]
	v_lshl_add_u64 v[42:43], v[44:45], 1, s[18:19]
	v_lshl_add_u64 v[34:35], v[32:33], 2, s[38:39]
	v_lshl_add_u64 v[52:53], v[50:51], 2, s[38:39]
	global_load_dwordx4 v[16:19], v[58:59], off
	global_load_dwordx4 v[12:15], v[52:53], off
	v_lshl_add_u64 v[40:41], v[38:39], 2, s[38:39]
	global_load_dwordx4 v[8:11], v[46:47], off
	global_load_dwordx4 v[4:7], v[40:41], off
	v_lshl_add_u64 v[78:79], v[38:39], 1, s[18:19]
	global_load_dwordx4 v[0:3], v[34:35], off
	v_lshl_add_u64 v[80:81], v[32:33], 1, s[18:19]
	flat_load_dwordx2 v[54:55], v[36:37]
	flat_load_dwordx2 v[48:49], v[42:43]
	s_nop 0
	flat_load_dwordx2 v[42:43], v[78:79]
	flat_load_dwordx2 v[36:37], v[80:81]
	ds_read_b128 v[78:81], v142 offset:8320
	v_readlane_b32 s18, v76, 8
	s_and_b64 vcc, exec, s[4:5]
	s_waitcnt lgkmcnt(0)
	v_mul_f32_e32 v77, s18, v78
	v_mul_f32_e32 v78, s18, v79
	v_mul_f32_e32 v77, 0xbfb8aa3b, v77
	v_mul_f32_e32 v78, 0xbfb8aa3b, v78
	v_exp_f32_e32 v77, v77
	v_exp_f32_e32 v78, v78
	v_mul_f32_e32 v79, s18, v80
	v_mul_f32_e32 v80, s18, v81
	v_mul_f32_e32 v79, 0xbfb8aa3b, v79
	v_mul_f32_e32 v80, 0xbfb8aa3b, v80
	v_exp_f32_e32 v79, v79
	v_add_f32_e32 v77, 1.0, v77
	v_add_f32_e32 v78, 1.0, v78
	v_exp_f32_e32 v80, v80
	v_rcp_f32_e32 v77, v77
	v_rcp_f32_e32 v78, v78
	v_add_f32_e32 v79, 1.0, v79
	s_waitcnt vmcnt(0)
	v_lshlrev_b32_e32 v81, 16, v84
	v_and_b32_e32 v84, 0xffff0000, v84
	v_fma_f32 v28, v77, v81, v28
	v_fma_f32 v29, v78, v84, v29
	v_rcp_f32_e32 v77, v79
	v_add_f32_e32 v78, 1.0, v80
	v_rcp_f32_e32 v78, v78
	v_lshlrev_b32_e32 v79, 16, v85
	v_fma_f32 v30, v77, v79, v30
	v_and_b32_e32 v77, 0xffff0000, v85
	v_fmac_f32_e32 v31, v78, v77
	global_store_dwordx4 v[82:83], v[28:31], off
	s_cbranch_vccnz .LBB0_2032
	v_cvt_pk_bf16_f32 v78, v28, v29
	v_cvt_pk_bf16_f32 v79, v30, v31
	v_lshl_add_u64 v[74:75], v[74:75], 1, s[8:9]
	flat_store_dwordx2 v[74:75], v[78:79]

; DEVI float fsig(float x) { return __builtin_amdgcn_rcpf(1.f + __expf(-x)); }
; DEVI float bflo(unsigned u) { return __uint_as_float(u << 16); }
; DEVI float bfhi(unsigned u) { return __uint_as_float(u & 0xffff0000u); }
; template <int EPI, int TS, bool VT>
; DEVI void gemm_epilogue(const Params& p, char* smem, f32x4 (&acc)[2][2][4][2], int m0, int n0, float scale, const float* ssin,
;                         float* ssout, u16* xbout, int wid, int lane, int wr, int wc, int fr, int fq) {
;     ...
;           if constexpr (EPI == E_RESID || EPI == E_PLEGATE) {
;             const float4 a = *(const float4*)(Tr + 4 * lane);
;             const size_t ro = (size_t)grow * 1024 + n0 + 4 * lane;
;             float4 x4 = xo[u];
;             if constexpr (EPI == E_PLEGATE) {
;               x4.x += bflo(pv[u].x) * fsig(a.x * rs);
;               x4.y += bfhi(pv[u].x) * fsig(a.y * rs);
;               x4.z += bflo(pv[u].y) * fsig(a.z * rs);
;               x4.w += bfhi(pv[u].y) * fsig(a.w * rs);
;             } else {
;               const float sc = fabsf(scale);
;               x4.x += sc * a.x; x4.y += sc * a.y; x4.z += sc * a.z; x4.w += sc * a.w;
;             }
;             st_nt16(p.x + ro, x4);
;             if (xbout) {
;               uint2 o;
;               o.x = pack2(x4.x, x4.y);
;               o.y = pack2(x4.z, x4.w);
;               st_nt8(xbout + ro, o);
;             }
.LBB0_2036:
	ds_read_b128 v[28:31], v142 offset:9360
	v_readlane_b32 s18, v76, 9
	s_and_b64 vcc, exec, s[4:5]
	s_waitcnt lgkmcnt(0)
	v_mul_f32_e32 v28, s18, v28
	v_mul_f32_e32 v29, s18, v29
	v_mul_f32_e32 v28, 0xbfb8aa3b, v28
	v_mul_f32_e32 v29, 0xbfb8aa3b, v29
	v_mul_f32_e32 v30, s18, v30
	v_mul_f32_e32 v31, s18, v31
	v_exp_f32_e32 v74, v28
	v_exp_f32_e32 v75, v29
	v_mul_f32_e32 v30, 0xbfb8aa3b, v30
	v_mul_f32_e32 v31, 0xbfb8aa3b, v31
	v_exp_f32_e32 v30, v30
	v_exp_f32_e32 v31, v31
	v_lshlrev_b32_e32 v28, 16, v72
	v_and_b32_e32 v29, 0xffff0000, v72
	v_add_f32_e32 v72, 1.0, v74
	v_add_f32_e32 v75, 1.0, v75
	v_rcp_f32_e32 v74, v72
	v_rcp_f32_e32 v75, v75
	v_add_f32_e32 v30, 1.0, v30
	v_add_f32_e32 v31, 1.0, v31
	v_rcp_f32_e32 v30, v30
	v_rcp_f32_e32 v31, v31
	v_pk_fma_f32 v[24:25], v[74:75], v[28:29], v[24:25]
	v_lshlrev_b32_e32 v28, 16, v73
	v_and_b32_e32 v29, 0xffff0000, v73
	v_pk_fma_f32 v[26:27], v[30:31], v[28:29], v[26:27]
	global_store_dwordx4 v[70:71], v[24:27], off
	s_cbranch_vccnz .LBB0_2038
	v_cvt_pk_bf16_f32 v28, v24, v25
	v_cvt_pk_bf16_f32 v29, v26, v27
	v_lshl_add_u64 v[30:31], v[68:69], 1, s[8:9]
	flat_store_dwordx2 v[30:31], v[28:29]

; DEVI float fsig(float x) { return __builtin_amdgcn_rcpf(1.f + __expf(-x)); }
; DEVI float bflo(unsigned u) { return __uint_as_float(u << 16); }
; DEVI float bfhi(unsigned u) { return __uint_as_float(u & 0xffff0000u); }
; template <int EPI, int TS, bool VT>
; DEVI void gemm_epilogue(const Params& p, char* smem, f32x4 (&acc)[2][2][4][2], int m0, int n0, float scale, const float* ssin,
;                         float* ssout, u16* xbout, int wid, int lane, int wr, int wc, int fr, int fq) {
;     ...
;           if constexpr (EPI == E_RESID || EPI == E_PLEGATE) {
;             const float4 a = *(const float4*)(Tr + 4 * lane);
;             const size_t ro = (size_t)grow * 1024 + n0 + 4 * lane;
;             float4 x4 = xo[u];
;             if constexpr (EPI == E_PLEGATE) {
;               x4.x += bflo(pv[u].x) * fsig(a.x * rs);
;               x4.y += bfhi(pv[u].x) * fsig(a.y * rs);
;               x4.z += bflo(pv[u].y) * fsig(a.z * rs);
;               x4.w += bfhi(pv[u].y) * fsig(a.w * rs);
;             } else {
;               const float sc = fabsf(scale);
;               x4.x += sc * a.x; x4.y += sc * a.y; x4.z += sc * a.z; x4.w += sc * a.w;
;             }
;             st_nt16(p.x + ro, x4);
;             if (xbout) {
;               uint2 o;
;               o.x = pack2(x4.x, x4.y);
;               o.y = pack2(x4.z, x4.w);
;               st_nt8(xbout + ro, o);
;             }
.LBB0_2042:
	ds_read_b128 v[24:27], v142 offset:10400
	v_readlane_b32 s18, v76, 10
	s_and_b64 vcc, exec, s[4:5]
	s_waitcnt lgkmcnt(0)
	v_mul_f32_e32 v24, s18, v24
	v_mul_f32_e32 v25, s18, v25
	v_mul_f32_e32 v24, 0xbfb8aa3b, v24
	v_mul_f32_e32 v25, 0xbfb8aa3b, v25
	v_mul_f32_e32 v26, s18, v26
	v_mul_f32_e32 v27, s18, v27
	v_exp_f32_e32 v28, v24
	v_exp_f32_e32 v29, v25
	v_mul_f32_e32 v26, 0xbfb8aa3b, v26
	v_mul_f32_e32 v27, 0xbfb8aa3b, v27
	v_exp_f32_e32 v26, v26
	v_exp_f32_e32 v27, v27
	v_add_f32_e32 v28, 1.0, v28
	v_add_f32_e32 v29, 1.0, v29
	v_rcp_f32_e32 v28, v28
	v_rcp_f32_e32 v29, v29
	v_add_f32_e32 v26, 1.0, v26
	v_add_f32_e32 v27, 1.0, v27
	v_rcp_f32_e32 v26, v26
	v_rcp_f32_e32 v27, v27
	v_lshlrev_b32_e32 v24, 16, v66
	v_and_b32_e32 v25, 0xffff0000, v66
	v_pk_fma_f32 v[20:21], v[28:29], v[24:25], v[20:21]
	v_lshlrev_b32_e32 v24, 16, v67
	v_and_b32_e32 v25, 0xffff0000, v67
	v_pk_fma_f32 v[22:23], v[26:27], v[24:25], v[22:23]
	global_store_dwordx4 v[64:65], v[20:23], off
	s_cbranch_vccnz .LBB0_2044
	v_cvt_pk_bf16_f32 v24, v20, v21
	v_cvt_pk_bf16_f32 v25, v22, v23
	v_lshl_add_u64 v[26:27], v[62:63], 1, s[8:9]
	flat_store_dwordx2 v[26:27], v[24:25]

; DEVI float fsig(float x) { return __builtin_amdgcn_rcpf(1.f + __expf(-x)); }
; DEVI float bflo(unsigned u) { return __uint_as_float(u << 16); }
; DEVI float bfhi(unsigned u) { return __uint_as_float(u & 0xffff0000u); }
; template <int EPI, int TS, bool VT>
; DEVI void gemm_epilogue(const Params& p, char* smem, f32x4 (&acc)[2][2][4][2], int m0, int n0, float scale, const float* ssin,
;                         float* ssout, u16* xbout, int wid, int lane, int wr, int wc, int fr, int fq) {
;     ...
;           if constexpr (EPI == E_RESID || EPI == E_PLEGATE) {
;             const float4 a = *(const float4*)(Tr + 4 * lane);
;             const size_t ro = (size_t)grow * 1024 + n0 + 4 * lane;
;             float4 x4 = xo[u];
;             if constexpr (EPI == E_PLEGATE) {
;               x4.x += bflo(pv[u].x) * fsig(a.x * rs);
;               x4.y += bfhi(pv[u].x) * fsig(a.y * rs);
;               x4.z += bflo(pv[u].y) * fsig(a.z * rs);
;               x4.w += bfhi(pv[u].y) * fsig(a.w * rs);
;             } else {
;               const float sc = fabsf(scale);
;               x4.x += sc * a.x; x4.y += sc * a.y; x4.z += sc * a.z; x4.w += sc * a.w;
;             }
;             st_nt16(p.x + ro, x4);
;             if (xbout) {
;               uint2 o;
;               o.x = pack2(x4.x, x4.y);
;               o.y = pack2(x4.z, x4.w);
;               st_nt8(xbout + ro, o);
;             }
.LBB0_2048:
	ds_read_b128 v[20:23], v142 offset:11440
	v_readlane_b32 s18, v76, 11
	s_and_b64 vcc, exec, s[4:5]
	s_waitcnt lgkmcnt(0)
	v_mul_f32_e32 v20, s18, v20
	v_mul_f32_e32 v21, s18, v21
	v_mul_f32_e32 v20, 0xbfb8aa3b, v20
	v_mul_f32_e32 v21, 0xbfb8aa3b, v21
	v_mul_f32_e32 v22, s18, v22
	v_mul_f32_e32 v23, s18, v23
	v_exp_f32_e32 v24, v20
	v_exp_f32_e32 v25, v21
	v_mul_f32_e32 v22, 0xbfb8aa3b, v22
	v_mul_f32_e32 v23, 0xbfb8aa3b, v23
	v_exp_f32_e32 v22, v22
	v_exp_f32_e32 v23, v23
	v_add_f32_e32 v24, 1.0, v24
	v_add_f32_e32 v25, 1.0, v25
	v_rcp_f32_e32 v24, v24
	v_rcp_f32_e32 v25, v25
	v_add_f32_e32 v22, 1.0, v22
	v_add_f32_e32 v23, 1.0, v23
	v_rcp_f32_e32 v22, v22
	v_rcp_f32_e32 v23, v23
	v_lshlrev_b32_e32 v20, 16, v60
	v_and_b32_e32 v21, 0xffff0000, v60
	v_pk_fma_f32 v[16:17], v[24:25], v[20:21], v[16:17]
	v_lshlrev_b32_e32 v20, 16, v61
	v_and_b32_e32 v21, 0xffff0000, v61
	v_pk_fma_f32 v[18:19], v[22:23], v[20:21], v[18:19]
	global_store_dwordx4 v[58:59], v[16:19], off
	s_cbranch_vccnz .LBB0_2050
	v_cvt_pk_bf16_f32 v20, v16, v17
	v_cvt_pk_bf16_f32 v21, v18, v19
	v_lshl_add_u64 v[22:23], v[56:57], 1, s[8:9]
	flat_store_dwordx2 v[22:23], v[20:21]

; DEVI float fsig(float x) { return __builtin_amdgcn_rcpf(1.f + __expf(-x)); }
; DEVI float bflo(unsigned u) { return __uint_as_float(u << 16); }
; DEVI float bfhi(unsigned u) { return __uint_as_float(u & 0xffff0000u); }
; template <int EPI, int TS, bool VT>
; DEVI void gemm_epilogue(const Params& p, char* smem, f32x4 (&acc)[2][2][4][2], int m0, int n0, float scale, const float* ssin,
;                         float* ssout, u16* xbout, int wid, int lane, int wr, int wc, int fr, int fq) {
;     ...
;           if constexpr (EPI == E_RESID || EPI == E_PLEGATE) {
;             const float4 a = *(const float4*)(Tr + 4 * lane);
;             const size_t ro = (size_t)grow * 1024 + n0 + 4 * lane;
;             float4 x4 = xo[u];
;             if constexpr (EPI == E_PLEGATE) {
;               x4.x += bflo(pv[u].x) * fsig(a.x * rs);
;               x4.y += bfhi(pv[u].x) * fsig(a.y * rs);
;               x4.z += bflo(pv[u].y) * fsig(a.z * rs);
;               x4.w += bfhi(pv[u].y) * fsig(a.w * rs);
;             } else {
;               const float sc = fabsf(scale);
;               x4.x += sc * a.x; x4.y += sc * a.y; x4.z += sc * a.z; x4.w += sc * a.w;
;             }
;             st_nt16(p.x + ro, x4);
;             if (xbout) {
;               uint2 o;
;               o.x = pack2(x4.x, x4.y);
;               o.y = pack2(x4.z, x4.w);
;               st_nt8(xbout + ro, o);
;             }
.LBB0_2054:
	ds_read_b128 v[16:19], v142 offset:12480
	v_readlane_b32 s18, v76, 12
	s_and_b64 vcc, exec, s[4:5]
	s_waitcnt lgkmcnt(0)
	v_mul_f32_e32 v16, s18, v16
	v_mul_f32_e32 v17, s18, v17
	v_mul_f32_e32 v16, 0xbfb8aa3b, v16
	v_mul_f32_e32 v17, 0xbfb8aa3b, v17
	v_mul_f32_e32 v18, s18, v18
	v_mul_f32_e32 v19, s18, v19
	v_exp_f32_e32 v20, v16
	v_exp_f32_e32 v21, v17
	v_mul_f32_e32 v18, 0xbfb8aa3b, v18
	v_mul_f32_e32 v19, 0xbfb8aa3b, v19
	v_exp_f32_e32 v18, v18
	v_exp_f32_e32 v19, v19
	v_add_f32_e32 v20, 1.0, v20
	v_add_f32_e32 v21, 1.0, v21
	v_rcp_f32_e32 v20, v20
	v_rcp_f32_e32 v21, v21
	v_add_f32_e32 v18, 1.0, v18
	v_add_f32_e32 v19, 1.0, v19
	v_rcp_f32_e32 v18, v18
	v_rcp_f32_e32 v19, v19
	v_lshlrev_b32_e32 v16, 16, v54
	v_and_b32_e32 v17, 0xffff0000, v54
	v_pk_fma_f32 v[12:13], v[20:21], v[16:17], v[12:13]
	v_lshlrev_b32_e32 v16, 16, v55
	v_and_b32_e32 v17, 0xffff0000, v55
	v_pk_fma_f32 v[14:15], v[18:19], v[16:17], v[14:15]
	global_store_dwordx4 v[52:53], v[12:15], off
	s_cbranch_vccnz .LBB0_2056
	v_cvt_pk_bf16_f32 v16, v12, v13
	v_cvt_pk_bf16_f32 v17, v14, v15
	v_lshl_add_u64 v[18:19], v[50:51], 1, s[8:9]
	flat_store_dwordx2 v[18:19], v[16:17]

; DEVI float fsig(float x) { return __builtin_amdgcn_rcpf(1.f + __expf(-x)); }
; DEVI float bflo(unsigned u) { return __uint_as_float(u << 16); }
; DEVI float bfhi(unsigned u) { return __uint_as_float(u & 0xffff0000u); }
; template <int EPI, int TS, bool VT>
; DEVI void gemm_epilogue(const Params& p, char* smem, f32x4 (&acc)[2][2][4][2], int m0, int n0, float scale, const float* ssin,
;                         float* ssout, u16* xbout, int wid, int lane, int wr, int wc, int fr, int fq) {
;     ...
;           if constexpr (EPI == E_RESID || EPI == E_PLEGATE) {
;             const float4 a = *(const float4*)(Tr + 4 * lane);
;             const size_t ro = (size_t)grow * 1024 + n0 + 4 * lane;
;             float4 x4 = xo[u];
;             if constexpr (EPI == E_PLEGATE) {
;               x4.x += bflo(pv[u].x) * fsig(a.x * rs);
;               x4.y += bfhi(pv[u].x) * fsig(a.y * rs);
;               x4.z += bflo(pv[u].y) * fsig(a.z * rs);
;               x4.w += bfhi(pv[u].y) * fsig(a.w * rs);
;             } else {
;               const float sc = fabsf(scale);
;               x4.x += sc * a.x; x4.y += sc * a.y; x4.z += sc * a.z; x4.w += sc * a.w;
;             }
;             st_nt16(p.x + ro, x4);
;             if (xbout) {
;               uint2 o;
;               o.x = pack2(x4.x, x4.y);
;               o.y = pack2(x4.z, x4.w);
;               st_nt8(xbout + ro, o);
;             }
.LBB0_2060:
	ds_read_b128 v[12:15], v142 offset:13520
	v_readlane_b32 s18, v76, 13
	s_and_b64 vcc, exec, s[4:5]
	s_waitcnt lgkmcnt(0)
	v_mul_f32_e32 v12, s18, v12
	v_mul_f32_e32 v13, s18, v13
	v_mul_f32_e32 v12, 0xbfb8aa3b, v12
	v_mul_f32_e32 v13, 0xbfb8aa3b, v13
	v_mul_f32_e32 v14, s18, v14
	v_mul_f32_e32 v15, s18, v15
	v_exp_f32_e32 v16, v12
	v_exp_f32_e32 v17, v13
	v_mul_f32_e32 v14, 0xbfb8aa3b, v14
	v_mul_f32_e32 v15, 0xbfb8aa3b, v15
	v_exp_f32_e32 v14, v14
	v_exp_f32_e32 v15, v15
	v_add_f32_e32 v16, 1.0, v16
	v_add_f32_e32 v17, 1.0, v17
	v_rcp_f32_e32 v16, v16
	v_rcp_f32_e32 v17, v17
	v_add_f32_e32 v14, 1.0, v14
	v_add_f32_e32 v15, 1.0, v15
	v_rcp_f32_e32 v14, v14
	v_rcp_f32_e32 v15, v15
	v_lshlrev_b32_e32 v12, 16, v48
	v_and_b32_e32 v13, 0xffff0000, v48
	v_pk_fma_f32 v[8:9], v[16:17], v[12:13], v[8:9]
	v_lshlrev_b32_e32 v12, 16, v49
	v_and_b32_e32 v13, 0xffff0000, v49
	v_pk_fma_f32 v[10:11], v[14:15], v[12:13], v[10:11]
	global_store_dwordx4 v[46:47], v[8:11], off
	s_cbranch_vccnz .LBB0_2062
	v_cvt_pk_bf16_f32 v12, v8, v9
	v_cvt_pk_bf16_f32 v13, v10, v11
	v_lshl_add_u64 v[14:15], v[44:45], 1, s[8:9]
	flat_store_dwordx2 v[14:15], v[12:13]

; DEVI float fsig(float x) { return __builtin_amdgcn_rcpf(1.f + __expf(-x)); }
; DEVI float bflo(unsigned u) { return __uint_as_float(u << 16); }
; DEVI float bfhi(unsigned u) { return __uint_as_float(u & 0xffff0000u); }
; template <int EPI, int TS, bool VT>
; DEVI void gemm_epilogue(const Params& p, char* smem, f32x4 (&acc)[2][2][4][2], int m0, int n0, float scale, const float* ssin,
;                         float* ssout, u16* xbout, int wid, int lane, int wr, int wc, int fr, int fq) {
;     ...
;           if constexpr (EPI == E_RESID || EPI == E_PLEGATE) {
;             const float4 a = *(const float4*)(Tr + 4 * lane);
;             const size_t ro = (size_t)grow * 1024 + n0 + 4 * lane;
;             float4 x4 = xo[u];
;             if constexpr (EPI == E_PLEGATE) {
;               x4.x += bflo(pv[u].x) * fsig(a.x * rs);
;               x4.y += bfhi(pv[u].x) * fsig(a.y * rs);
;               x4.z += bflo(pv[u].y) * fsig(a.z * rs);
;               x4.w += bfhi(pv[u].y) * fsig(a.w * rs);
;             } else {
;               const float sc = fabsf(scale);
;               x4.x += sc * a.x; x4.y += sc * a.y; x4.z += sc * a.z; x4.w += sc * a.w;
;             }
;             st_nt16(p.x + ro, x4);
;             if (xbout) {
;               uint2 o;
;               o.x = pack2(x4.x, x4.y);
;               o.y = pack2(x4.z, x4.w);
;               st_nt8(xbout + ro, o);
;             }
.LBB0_2066:
	ds_read_b128 v[8:11], v142 offset:14560
	v_readlane_b32 s18, v76, 14
	s_and_b64 vcc, exec, s[4:5]
	s_waitcnt lgkmcnt(0)
	v_mul_f32_e32 v8, s18, v8
	v_mul_f32_e32 v9, s18, v9
	v_mul_f32_e32 v8, 0xbfb8aa3b, v8
	v_mul_f32_e32 v9, 0xbfb8aa3b, v9
	v_mul_f32_e32 v10, s18, v10
	v_mul_f32_e32 v11, s18, v11
	v_exp_f32_e32 v12, v8
	v_exp_f32_e32 v13, v9
	v_mul_f32_e32 v10, 0xbfb8aa3b, v10
	v_mul_f32_e32 v11, 0xbfb8aa3b, v11
	v_exp_f32_e32 v10, v10
	v_exp_f32_e32 v11, v11
	v_add_f32_e32 v12, 1.0, v12
	v_add_f32_e32 v13, 1.0, v13
	v_rcp_f32_e32 v12, v12
	v_rcp_f32_e32 v13, v13
	v_add_f32_e32 v10, 1.0, v10
	v_add_f32_e32 v11, 1.0, v11
	v_rcp_f32_e32 v10, v10
	v_rcp_f32_e32 v11, v11
	v_lshlrev_b32_e32 v8, 16, v42
	v_and_b32_e32 v9, 0xffff0000, v42
	v_pk_fma_f32 v[4:5], v[12:13], v[8:9], v[4:5]
	v_lshlrev_b32_e32 v8, 16, v43
	v_and_b32_e32 v9, 0xffff0000, v43
	v_pk_fma_f32 v[6:7], v[10:11], v[8:9], v[6:7]
	global_store_dwordx4 v[40:41], v[4:7], off
	s_cbranch_vccnz .LBB0_2068
	v_cvt_pk_bf16_f32 v8, v4, v5
	v_cvt_pk_bf16_f32 v9, v6, v7
	v_lshl_add_u64 v[10:11], v[38:39], 1, s[8:9]
	flat_store_dwordx2 v[10:11], v[8:9]

; DEVI float fsig(float x) { return __builtin_amdgcn_rcpf(1.f + __expf(-x)); }
; DEVI float bflo(unsigned u) { return __uint_as_float(u << 16); }
; DEVI float bfhi(unsigned u) { return __uint_as_float(u & 0xffff0000u); }
; template <int EPI, int TS, bool VT>
; DEVI void gemm_epilogue(const Params& p, char* smem, f32x4 (&acc)[2][2][4][2], int m0, int n0, float scale, const float* ssin,
;                         float* ssout, u16* xbout, int wid, int lane, int wr, int wc, int fr, int fq) {
;     ...
;           if constexpr (EPI == E_RESID || EPI == E_PLEGATE) {
;             const float4 a = *(const float4*)(Tr + 4 * lane);
;             const size_t ro = (size_t)grow * 1024 + n0 + 4 * lane;
;             float4 x4 = xo[u];
;             if constexpr (EPI == E_PLEGATE) {
;               x4.x += bflo(pv[u].x) * fsig(a.x * rs);
;               x4.y += bfhi(pv[u].x) * fsig(a.y * rs);
;               x4.z += bflo(pv[u].y) * fsig(a.z * rs);
;               x4.w += bfhi(pv[u].y) * fsig(a.w * rs);
;             } else {
;               const float sc = fabsf(scale);
;               x4.x += sc * a.x; x4.y += sc * a.y; x4.z += sc * a.z; x4.w += sc * a.w;
;             }
;             st_nt16(p.x + ro, x4);
;             if (xbout) {
;               uint2 o;
;               o.x = pack2(x4.x, x4.y);
;               o.y = pack2(x4.z, x4.w);
;               st_nt8(xbout + ro, o);
;             }
.LBB0_2072:
	ds_read_b128 v[4:7], v142 offset:15600
	v_readlane_b32 s18, v76, 15
	s_and_b64 vcc, exec, s[4:5]
	s_waitcnt lgkmcnt(0)
	v_mul_f32_e32 v4, s18, v4
	v_mul_f32_e32 v5, s18, v5
	v_mul_f32_e32 v4, 0xbfb8aa3b, v4
	v_mul_f32_e32 v5, 0xbfb8aa3b, v5
	v_mul_f32_e32 v6, s18, v6
	v_mul_f32_e32 v7, s18, v7
	v_exp_f32_e32 v8, v4
	v_exp_f32_e32 v9, v5
	v_mul_f32_e32 v6, 0xbfb8aa3b, v6
	v_mul_f32_e32 v7, 0xbfb8aa3b, v7
	v_exp_f32_e32 v6, v6
	v_exp_f32_e32 v7, v7
	v_add_f32_e32 v8, 1.0, v8
	v_add_f32_e32 v9, 1.0, v9
	v_rcp_f32_e32 v8, v8
	v_rcp_f32_e32 v9, v9
	v_add_f32_e32 v6, 1.0, v6
	v_add_f32_e32 v7, 1.0, v7
	v_rcp_f32_e32 v6, v6
	v_rcp_f32_e32 v7, v7
	v_lshlrev_b32_e32 v4, 16, v36
	v_and_b32_e32 v5, 0xffff0000, v36
	v_pk_fma_f32 v[0:1], v[8:9], v[4:5], v[0:1]
	v_lshlrev_b32_e32 v4, 16, v37
	v_and_b32_e32 v5, 0xffff0000, v37
	v_pk_fma_f32 v[2:3], v[6:7], v[4:5], v[2:3]
	global_store_dwordx4 v[34:35], v[0:3], off
	s_cbranch_vccnz .LBB0_2074
	v_cvt_pk_bf16_f32 v4, v0, v1
	v_cvt_pk_bf16_f32 v5, v2, v3
	v_lshl_add_u64 v[6:7], v[32:33], 1, s[8:9]
	flat_store_dwordx2 v[6:7], v[4:5]
